# speedup vs baseline: 1.0223x; 1.0008x over previous
; #define STAGE(P, RS, SOFF, OFF, kt) do { const int _so = (SOFF) + (kt) * (BK * 2); \
;     _Pragma("unroll") for (int _i = 0; _i < 2; ++_i) { \
;       __builtin_amdgcn_raw_ptr_buffer_load_lds(RS, (__attribute__((address_space(3))) void*)((P) + wave * 1024 + _i * 8192), 16, OFF[_i], _so, 0, 0); } } while (0)
; #define LDA(dst, b, h) _Pragma("unroll") for (int m = 0; m < 4; ++m) _Pragma("unroll") for (int k = 0; k < 2; ++k) \
;     dst[m][k] = *reinterpret_cast<const bf16x8*>(SA(b, h) + lds_byte(wr * 64 + m * 16 + fr, k * 32 + fq * 8))
; #define LDB(dst, b, h) _Pragma("unroll") for (int n = 0; n < 2; ++n) _Pragma("unroll") for (int k = 0; k < 2; ++k) \
;     dst[n][k] = *reinterpret_cast<const bf16x8*>(SB(b, h) + lds_byte(wc * 32 + n * 16 + fr, k * 32 + fq * 8))
; #define WAIT_V(n) asm volatile("s_waitcnt vmcnt(" #n ")" ::: "memory")
; #define WAIT_L(n) asm volatile("s_waitcnt lgkmcnt(" #n ")" ::: "memory")
; #define BAR __builtin_amdgcn_s_barrier()
; #define SCHED __builtin_amdgcn_sched_barrier(0)
;     ...
;     const int tid = opaque_tid(wave);
;     const int wid = tid >> 6, lane = tid & 63, wr = wid >> 2, wc = wid & 3, fr = lane & 15, fq = lane >> 4;
;     int offA[2], offB[2];
;     _Pragma("unroll") for (int i = 0; i < 2; ++i) {
;       int r, c; stage_rc(tid * 16 + i * 8192, r, c);
;       offA[i] = (r * lda + c) * 2; offB[i] = (r * ldb + c) * 2;
;     }
;     const int brow = pm * BM;
;     f32x4 acc[2][2][4][2];
;     _Pragma("unroll") for (int a = 0; a < 2; ++a) _Pragma("unroll") for (int b = 0; b < 2; ++b) _Pragma("unroll") for (int m = 0; m < 4; ++m) _Pragma("unroll") for (int n = 0; n < 2; ++n)
;       acc[a][b][m][n] = f32x4{0.f, 0.f, 0.f, 0.f};
;     bf16x8 At[4][2], B0[2][2], B1[2][2];
;     if (wr == 1) BAR;
;     if (first_tile) { WAIT_V(0); }
;     else if constexpr (mode == MODE_RESID_LN) { WAIT_V(0); }
;     else if constexpr (mode == MODE_SWIGLU) { WAIT_V(6); }
;     else if constexpr (mode == MODE_V) { WAIT_V(24); }
;     else { WAIT_V(12); }
;     first_tile = false;
;     BAR;
;     BAR;
;     for (int t = 0; t < nt - 2; t += 2) {
;       LDB(B0, 0, 0); SCHED; LDA(At, 0, 0); STAGE(SA(1, 1), rsA, sA1, offA, t + 1);
;       WAIT_L(8); BAR; WAIT_L(0); MMA(0, 0, At, B0); BAR; SCHED;
;       LDB(B1, 0, 1); STAGE(SB(0, 0), rsB, sB0, offB, t + 2);
.LBB0_94:
	v_bfe_i32 v4, v130, 27, 1
	v_lshlrev_b32_e32 v2, 4, v130
	v_lshrrev_b32_e32 v4, 22, v4
	v_add_u32_e32 v4, v2, v4
	v_and_b32_e32 v4, 0xfffffc00, v4
	v_sub_u32_e32 v4, v2, v4
	v_lshrrev_b32_e32 v5, 4, v4
	v_bitop3_b32 v4, v5, v4, 32 bitop3:0x6c
	v_ashrrev_i32_e32 v3, 31, v130
	v_ashrrev_i32_e32 v6, 31, v4
	v_lshrrev_b32_e32 v3, 26, v3
	v_lshrrev_b32_e32 v6, 26, v6
	v_add_u32_e32 v3, v130, v3
	v_add_u32_e32 v6, v4, v6
	v_ashrrev_i32_e32 v3, 6, v3
	v_lshrrev_b32_e32 v7, 6, v6
	v_and_b32_e32 v6, 0xc0, v6
	v_lshlrev_b32_e32 v5, 3, v3
	v_lshlrev_b32_e32 v3, 5, v3
	v_sub_u32_e32 v4, v4, v6
	v_and_b32_e32 v5, 0xffff0, v5
	v_and_b32_e32 v3, 32, v3
	v_ashrrev_i16_sdwa v4, v128, sext(v4) dst_sel:DWORD dst_unused:UNUSED_PAD src0_sel:DWORD src1_sel:BYTE_0
	v_add_u32_sdwa v3, v3, sext(v4) dst_sel:DWORD dst_unused:UNUSED_PAD src0_sel:DWORD src1_sel:WORD_0
	v_add_lshl_u32 v4, v7, v5, 12
	v_add_u32_e32 v2, 0x2000, v2
	v_lshl_add_u32 v143, v3, 1, v4
	v_ashrrev_i32_e32 v3, 31, v2
	v_lshrrev_b32_e32 v3, 22, v3
	v_add_u32_e32 v3, v2, v3
	v_ashrrev_i32_e32 v3, 10, v3
	v_mul_i32_i24_e32 v4, 0x400, v3
	v_sub_u32_e32 v2, v2, v4
	v_lshrrev_b32_e32 v4, 4, v2
	v_bitop3_b32 v2, v4, v2, 32 bitop3:0x6c
	v_ashrrev_i32_e32 v5, 31, v2
	v_lshrrev_b32_e32 v5, 26, v5
	v_add_u32_e32 v5, v2, v5
	v_lshrrev_b32_e32 v6, 6, v5
	v_and_b32_e32 v5, 0xc0, v5
	v_lshlrev_b32_e32 v4, 3, v3
	v_lshlrev_b32_e32 v3, 5, v3
	v_sub_u32_e32 v2, v2, v5
	v_and_b32_e32 v4, 0xffff0, v4
	v_and_b32_e32 v3, 32, v3
	v_ashrrev_i16_sdwa v2, v128, sext(v2) dst_sel:DWORD dst_unused:UNUSED_PAD src0_sel:DWORD src1_sel:BYTE_0
	v_add_u32_sdwa v2, v3, sext(v2) dst_sel:DWORD dst_unused:UNUSED_PAD src0_sel:DWORD src1_sel:WORD_0
	v_add_lshl_u32 v3, v6, v4, 12
	v_lshl_add_u32 v144, v2, 1, v3
	v_and_b32_e32 v3, 15, v0
	v_lshlrev_b32_e32 v5, 2, v0
	v_and_b32_e32 v2, 48, v0
	v_lshlrev_b32_e32 v3, 6, v3
	v_and_b32_e32 v5, 32, v5
	v_lshlrev_b32_e32 v0, 6, v0
	v_or_b32_e32 v4, v3, v2
	v_bitop3_b32 v3, v3, v5, v2 bitop3:0x36
	v_lshlrev_b32_e32 v6, 6, v130
	v_lshlrev_b32_e32 v1, 13, v1
	v_and_or_b32 v0, v0, s34, v2
	v_and_or_b32 v3, v6, s33, v3
	v_bitop3_b32 v0, v1, v0, v5 bitop3:0xf6
	v_or_b32_e32 v6, 0x400, v3
	v_or_b32_e32 v7, 0x800, v3
	v_or_b32_e32 v8, 0xc00, v3
	v_or_b32_e32 v134, 0x800, v0
	v_or_b32_e32 v133, 0x1000, v0
	v_or_b32_e32 v132, 0x1800, v0
	v_mov_b32_e32 v0, 0
	v_bitop3_b32 v131, v4, v1, v5 bitop3:0xde
	s_mov_b32 s14, -2
	s_mov_b32 s15, 0
	v_or_b32_e32 v149, 0x10000, v3
	v_or_b32_e32 v150, 0x10000, v6
	v_or_b32_e32 v151, 0x10000, v7
	v_or_b32_e32 v152, 0x10000, v8
	v_or_b32_e32 v145, 0x14000, v3
	v_or_b32_e32 v146, 0x14000, v6
	v_or_b32_e32 v147, 0x14000, v7
	v_or_b32_e32 v148, 0x14000, v8
	v_or_b32_e32 v139, 0x18000, v3
	v_or_b32_e32 v140, 0x18000, v6
	v_or_b32_e32 v141, 0x18000, v7
	v_or_b32_e32 v142, 0x18000, v8
	v_or_b32_e32 v135, 0x1c000, v3
	v_or_b32_e32 v136, 0x1c000, v6
	v_or_b32_e32 v137, 0x1c000, v7
	v_or_b32_e32 v138, 0x1c000, v8
	s_barrier
	s_barrier
	ds_read_b128 v[154:157], v149
	ds_read_b128 v[158:161], v150
	ds_read_b128 v[162:165], v151
	ds_read_b128 v[166:169], v152
	s_add_i32 s43, s37, s15
	s_add_i32 s10, s43, 0x80
	s_mov_b32 m0, s30
	ds_read_b128 v[170:173], v131
	ds_read_b128 v[174:177], v131 offset:1024
	ds_read_b128 v[178:181], v134
	ds_read_b128 v[182:185], v134 offset:1024
	ds_read_b128 v[186:189], v133
	ds_read_b128 v[190:193], v133 offset:1024
	ds_read_b128 v[194:197], v132
	ds_read_b128 v[198:201], v132 offset:1024
	buffer_load_dwordx4 v143, s[4:7], s10 offen lds
	s_mov_b32 m0, s31
	s_nop 0
	buffer_load_dwordx4 v144, s[4:7], s10 offen lds
	s_waitcnt lgkmcnt(8)
	s_barrier
	s_waitcnt lgkmcnt(0)
	v_mfma_f32_16x16x32_bf16 v[124:127], v[154:157], v[170:173], 0
	v_mfma_f32_16x16x32_bf16 v[124:127], v[158:161], v[174:177], v[124:127]
	v_mfma_f32_16x16x32_bf16 v[120:123], v[166:169], v[174:177], 0
	v_mfma_f32_16x16x32_bf16 v[120:123], v[162:165], v[170:173], v[120:123]
	v_mfma_f32_16x16x32_bf16 v[112:115], v[162:165], v[178:181], 0
	v_mfma_f32_16x16x32_bf16 v[112:115], v[166:169], v[182:185], v[112:115]
	v_mfma_f32_16x16x32_bf16 v[116:119], v[158:161], v[182:185], 0
	v_mfma_f32_16x16x32_bf16 v[116:119], v[154:157], v[178:181], v[116:119]
	v_mfma_f32_16x16x32_bf16 v[108:111], v[154:157], v[186:189], 0
	v_mfma_f32_16x16x32_bf16 v[108:111], v[158:161], v[190:193], v[108:111]
	v_mfma_f32_16x16x32_bf16 v[104:107], v[166:169], v[190:193], 0
	v_mfma_f32_16x16x32_bf16 v[104:107], v[162:165], v[186:189], v[104:107]
	v_mfma_f32_16x16x32_bf16 v[96:99], v[162:165], v[194:197], 0
	v_mfma_f32_16x16x32_bf16 v[96:99], v[166:169], v[198:201], v[96:99]
	v_mfma_f32_16x16x32_bf16 v[100:103], v[158:161], v[198:201], 0
	v_mfma_f32_16x16x32_bf16 v[100:103], v[154:157], v[194:197], v[100:103]
	s_barrier
	s_add_i32 s44, s39, s15
	s_add_i32 s45, s44, 0x100
	s_mov_b32 s10, s6
	s_mov_b32 s11, s7
	s_mov_b32 m0, s1
	ds_read_b128 v[202:205], v145
	ds_read_b128 v[206:209], v146
	ds_read_b128 v[210:213], v147
	ds_read_b128 v[214:217], v148
	buffer_load_dwordx4 v143, s[8:11], s45 offen lds
	s_mov_b32 m0, s3
	s_nop 0
	buffer_load_dwordx4 v144, s[8:11], s45 offen lds
	s_barrier
; #define STAGE(P, RS, SOFF, OFF, kt) do { const int _so = (SOFF) + (kt) * (BK * 2); \
;     _Pragma("unroll") for (int _i = 0; _i < 2; ++_i) { \
;       __builtin_amdgcn_raw_ptr_buffer_load_lds(RS, (__attribute__((address_space(3))) void*)((P) + wave * 1024 + _i * 8192), 16, OFF[_i], _so, 0, 0); } } while (0)
; #define LDA(dst, b, h) _Pragma("unroll") for (int m = 0; m < 4; ++m) _Pragma("unroll") for (int k = 0; k < 2; ++k) \
;     dst[m][k] = *reinterpret_cast<const bf16x8*>(SA(b, h) + lds_byte(wr * 64 + m * 16 + fr, k * 32 + fq * 8))
; #define LDB(dst, b, h) _Pragma("unroll") for (int n = 0; n < 2; ++n) _Pragma("unroll") for (int k = 0; k < 2; ++k) \
;     dst[n][k] = *reinterpret_cast<const bf16x8*>(SB(b, h) + lds_byte(wc * 32 + n * 16 + fr, k * 32 + fq * 8))
; #define WAIT_V(n) asm volatile("s_waitcnt vmcnt(" #n ")" ::: "memory")
; #define WAIT_L(n) asm volatile("s_waitcnt lgkmcnt(" #n ")" ::: "memory")
; #define BAR __builtin_amdgcn_s_barrier()
; #define SCHED __builtin_amdgcn_sched_barrier(0)
;     ...
;       BAR; WAIT_L(0); MMA(0, 1, At, B1); BAR;
;       LDA(At, 0, 1); STAGE(SA(0, 0), rsA, sA0, offA, t + 2);
;       BAR; WAIT_L(0); MMA(1, 0, At, B0); BAR; SCHED;
;       STAGE(SB(0, 1), rsB, sB1, offB, t + 2);
;       WAIT_V(6); BAR; MMA(1, 1, At, B1); BAR;
;       LDB(B0, 1, 0); SCHED; LDA(At, 1, 0); STAGE(SA(0, 1), rsA, sA1, offA, t + 2);
;       WAIT_L(8); BAR; WAIT_L(0); MMA(0, 0, At, B0); BAR; SCHED;
	s_waitcnt lgkmcnt(2)
	v_mfma_f32_16x16x32_bf16 v[92:95], v[202:205], v[170:173], 0
	v_mfma_f32_16x16x32_bf16 v[92:95], v[206:209], v[174:177], v[92:95]
	s_waitcnt lgkmcnt(0)
	v_mfma_f32_16x16x32_bf16 v[88:91], v[214:217], v[174:177], 0
	v_mfma_f32_16x16x32_bf16 v[88:91], v[210:213], v[170:173], v[88:91]
	v_mfma_f32_16x16x32_bf16 v[80:83], v[210:213], v[178:181], 0
	v_mfma_f32_16x16x32_bf16 v[80:83], v[214:217], v[182:185], v[80:83]
	v_mfma_f32_16x16x32_bf16 v[84:87], v[206:209], v[182:185], 0
	v_mfma_f32_16x16x32_bf16 v[84:87], v[202:205], v[178:181], v[84:87]
	v_mfma_f32_16x16x32_bf16 v[76:79], v[202:205], v[186:189], 0
	v_mfma_f32_16x16x32_bf16 v[76:79], v[206:209], v[190:193], v[76:79]
	v_mfma_f32_16x16x32_bf16 v[72:75], v[214:217], v[190:193], 0
	v_mfma_f32_16x16x32_bf16 v[72:75], v[210:213], v[186:189], v[72:75]
	v_mfma_f32_16x16x32_bf16 v[64:67], v[210:213], v[194:197], 0
	v_mfma_f32_16x16x32_bf16 v[64:67], v[214:217], v[198:201], v[64:67]
	v_mfma_f32_16x16x32_bf16 v[68:71], v[206:209], v[198:201], 0
	v_mfma_f32_16x16x32_bf16 v[68:71], v[202:205], v[194:197], v[68:71]
	s_barrier
	s_add_i32 s45, s38, s15
	s_add_i32 s46, s45, 0x100
	s_mov_b32 m0, s0
	ds_read_b128 v[170:173], v131 offset:16384
	ds_read_b128 v[174:177], v131 offset:17408
	ds_read_b128 v[178:181], v134 offset:16384
	ds_read_b128 v[182:185], v134 offset:17408
	ds_read_b128 v[186:189], v133 offset:16384
	ds_read_b128 v[190:193], v133 offset:17408
	ds_read_b128 v[194:197], v132 offset:16384
	ds_read_b128 v[198:201], v132 offset:17408
	buffer_load_dwordx4 v143, s[4:7], s46 offen lds
	s_mov_b32 m0, s18
	s_nop 0
	buffer_load_dwordx4 v144, s[4:7], s46 offen lds
	s_barrier
	s_waitcnt lgkmcnt(6)
	v_mfma_f32_16x16x32_bf16 v[60:63], v[154:157], v[170:173], 0
	v_mfma_f32_16x16x32_bf16 v[60:63], v[158:161], v[174:177], v[60:63]
	v_mfma_f32_16x16x32_bf16 v[56:59], v[166:169], v[174:177], 0
	v_mfma_f32_16x16x32_bf16 v[56:59], v[162:165], v[170:173], v[56:59]
	s_waitcnt lgkmcnt(4)
	v_mfma_f32_16x16x32_bf16 v[48:51], v[162:165], v[178:181], 0
	v_mfma_f32_16x16x32_bf16 v[48:51], v[166:169], v[182:185], v[48:51]
	v_mfma_f32_16x16x32_bf16 v[52:55], v[158:161], v[182:185], 0
	v_mfma_f32_16x16x32_bf16 v[52:55], v[154:157], v[178:181], v[52:55]
	s_waitcnt lgkmcnt(2)
	v_mfma_f32_16x16x32_bf16 v[44:47], v[154:157], v[186:189], 0
	v_mfma_f32_16x16x32_bf16 v[44:47], v[158:161], v[190:193], v[44:47]
	v_mfma_f32_16x16x32_bf16 v[40:43], v[166:169], v[190:193], 0
	v_mfma_f32_16x16x32_bf16 v[40:43], v[162:165], v[186:189], v[40:43]
	s_waitcnt lgkmcnt(0)
	v_mfma_f32_16x16x32_bf16 v[32:35], v[162:165], v[194:197], 0
	v_mfma_f32_16x16x32_bf16 v[32:35], v[166:169], v[198:201], v[32:35]
	v_mfma_f32_16x16x32_bf16 v[36:39], v[158:161], v[198:201], 0
	v_mfma_f32_16x16x32_bf16 v[36:39], v[154:157], v[194:197], v[36:39]
	s_barrier
	s_add_i32 s46, s40, s15
	s_add_i32 s47, s46, 0x100
	s_mov_b32 m0, s19
	s_nop 0
	buffer_load_dwordx4 v143, s[8:11], s47 offen lds
	s_mov_b32 m0, s20
	s_nop 0
	buffer_load_dwordx4 v144, s[8:11], s47 offen lds
	s_waitcnt vmcnt(6)
	s_barrier
	v_mfma_f32_16x16x32_bf16 v[28:31], v[202:205], v[170:173], 0
	v_mfma_f32_16x16x32_bf16 v[28:31], v[206:209], v[174:177], v[28:31]
	v_mfma_f32_16x16x32_bf16 v[24:27], v[214:217], v[174:177], 0
	v_mfma_f32_16x16x32_bf16 v[24:27], v[210:213], v[170:173], v[24:27]
	v_mfma_f32_16x16x32_bf16 v[16:19], v[210:213], v[178:181], 0
	v_mfma_f32_16x16x32_bf16 v[16:19], v[214:217], v[182:185], v[16:19]
	v_mfma_f32_16x16x32_bf16 v[20:23], v[206:209], v[182:185], 0
	v_mfma_f32_16x16x32_bf16 v[20:23], v[202:205], v[178:181], v[20:23]
	v_mfma_f32_16x16x32_bf16 v[12:15], v[202:205], v[186:189], 0
	v_mfma_f32_16x16x32_bf16 v[12:15], v[206:209], v[190:193], v[12:15]
	v_mfma_f32_16x16x32_bf16 v[8:11], v[214:217], v[190:193], 0
	v_mfma_f32_16x16x32_bf16 v[8:11], v[210:213], v[186:189], v[8:11]
	v_mfma_f32_16x16x32_bf16 v[0:3], v[210:213], v[194:197], 0
	v_mfma_f32_16x16x32_bf16 v[0:3], v[214:217], v[198:201], v[0:3]
	v_mfma_f32_16x16x32_bf16 v[4:7], v[206:209], v[198:201], 0
	v_mfma_f32_16x16x32_bf16 v[4:7], v[202:205], v[194:197], v[4:7]
	s_barrier
	ds_read_b128 v[154:157], v139
	ds_read_b128 v[158:161], v140
	ds_read_b128 v[162:165], v141
	ds_read_b128 v[166:169], v142
	s_addk_i32 s43, 0x100
	s_mov_b32 m0, s21
	ds_read_b128 v[170:173], v131 offset:32768
	ds_read_b128 v[174:177], v131 offset:33792
	ds_read_b128 v[178:181], v134 offset:32768
	ds_read_b128 v[182:185], v134 offset:33792
	ds_read_b128 v[186:189], v133 offset:32768
	ds_read_b128 v[190:193], v133 offset:33792
	ds_read_b128 v[194:197], v132 offset:32768
	ds_read_b128 v[198:201], v132 offset:33792
	buffer_load_dwordx4 v143, s[4:7], s43 offen lds
	s_mov_b32 m0, s22
	s_nop 0
	buffer_load_dwordx4 v144, s[4:7], s43 offen lds
	s_waitcnt lgkmcnt(8)
	s_barrier
; #define STAGE(P, RS, SOFF, OFF, kt) do { const int _so = (SOFF) + (kt) * (BK * 2); \
;     _Pragma("unroll") for (int _i = 0; _i < 2; ++_i) { \
;       __builtin_amdgcn_raw_ptr_buffer_load_lds(RS, (__attribute__((address_space(3))) void*)((P) + wave * 1024 + _i * 8192), 16, OFF[_i], _so, 0, 0); } } while (0)
; #define LDA(dst, b, h) _Pragma("unroll") for (int m = 0; m < 4; ++m) _Pragma("unroll") for (int k = 0; k < 2; ++k) \
;     dst[m][k] = *reinterpret_cast<const bf16x8*>(SA(b, h) + lds_byte(wr * 64 + m * 16 + fr, k * 32 + fq * 8))
; #define LDB(dst, b, h) _Pragma("unroll") for (int n = 0; n < 2; ++n) _Pragma("unroll") for (int k = 0; k < 2; ++k) \
;     dst[n][k] = *reinterpret_cast<const bf16x8*>(SB(b, h) + lds_byte(wc * 32 + n * 16 + fr, k * 32 + fq * 8))
; #define WAIT_V(n) asm volatile("s_waitcnt vmcnt(" #n ")" ::: "memory")
; #define WAIT_L(n) asm volatile("s_waitcnt lgkmcnt(" #n ")" ::: "memory")
; #define BAR __builtin_amdgcn_s_barrier()
; #define SCHED __builtin_amdgcn_sched_barrier(0)
;     ...
;       WAIT_L(8); BAR; WAIT_L(0); MMA(0, 0, At, B0); BAR; SCHED;
;       LDB(B1, 1, 1); STAGE(SB(1, 0), rsB, sB0, offB, t + 3);
;       BAR; WAIT_L(0); MMA(0, 1, At, B1); BAR;
;       LDA(At, 1, 1); STAGE(SA(1, 0), rsA, sA0, offA, t + 3);
;       BAR; WAIT_L(0); MMA(1, 0, At, B0); BAR; SCHED;
;       STAGE(SB(1, 1), rsB, sB1, offB, t + 3);
;       WAIT_V(6); BAR; MMA(1, 1, At, B1); BAR;
;     }
	s_waitcnt lgkmcnt(6)
	v_mfma_f32_16x16x32_bf16 v[124:127], v[154:157], v[170:173], v[124:127]
	v_mfma_f32_16x16x32_bf16 v[124:127], v[158:161], v[174:177], v[124:127]
	v_mfma_f32_16x16x32_bf16 v[120:123], v[166:169], v[174:177], v[120:123]
	v_mfma_f32_16x16x32_bf16 v[120:123], v[162:165], v[170:173], v[120:123]
	s_waitcnt lgkmcnt(4)
	v_mfma_f32_16x16x32_bf16 v[112:115], v[162:165], v[178:181], v[112:115]
	v_mfma_f32_16x16x32_bf16 v[112:115], v[166:169], v[182:185], v[112:115]
	v_mfma_f32_16x16x32_bf16 v[116:119], v[158:161], v[182:185], v[116:119]
	v_mfma_f32_16x16x32_bf16 v[116:119], v[154:157], v[178:181], v[116:119]
	s_waitcnt lgkmcnt(2)
	v_mfma_f32_16x16x32_bf16 v[108:111], v[154:157], v[186:189], v[108:111]
	v_mfma_f32_16x16x32_bf16 v[108:111], v[158:161], v[190:193], v[108:111]
	v_mfma_f32_16x16x32_bf16 v[104:107], v[166:169], v[190:193], v[104:107]
	v_mfma_f32_16x16x32_bf16 v[104:107], v[162:165], v[186:189], v[104:107]
	s_waitcnt lgkmcnt(0)
	v_mfma_f32_16x16x32_bf16 v[96:99], v[162:165], v[194:197], v[96:99]
	v_mfma_f32_16x16x32_bf16 v[96:99], v[166:169], v[198:201], v[96:99]
	v_mfma_f32_16x16x32_bf16 v[100:103], v[158:161], v[198:201], v[100:103]
	v_mfma_f32_16x16x32_bf16 v[100:103], v[154:157], v[194:197], v[100:103]
	s_barrier
	s_addk_i32 s44, 0x180
	s_mov_b32 m0, s23
	ds_read_b128 v[202:205], v135
	ds_read_b128 v[206:209], v136
	ds_read_b128 v[210:213], v137
	ds_read_b128 v[214:217], v138
	buffer_load_dwordx4 v143, s[8:11], s44 offen lds
	s_mov_b32 m0, s24
	s_nop 0
	buffer_load_dwordx4 v144, s[8:11], s44 offen lds
	s_barrier
	s_waitcnt lgkmcnt(2)
	v_mfma_f32_16x16x32_bf16 v[92:95], v[202:205], v[170:173], v[92:95]
	v_mfma_f32_16x16x32_bf16 v[92:95], v[206:209], v[174:177], v[92:95]
	s_waitcnt lgkmcnt(0)
	v_mfma_f32_16x16x32_bf16 v[88:91], v[214:217], v[174:177], v[88:91]
	v_mfma_f32_16x16x32_bf16 v[88:91], v[210:213], v[170:173], v[88:91]
	v_mfma_f32_16x16x32_bf16 v[80:83], v[210:213], v[178:181], v[80:83]
	v_mfma_f32_16x16x32_bf16 v[80:83], v[214:217], v[182:185], v[80:83]
	v_mfma_f32_16x16x32_bf16 v[84:87], v[206:209], v[182:185], v[84:87]
	v_mfma_f32_16x16x32_bf16 v[84:87], v[202:205], v[178:181], v[84:87]
	v_mfma_f32_16x16x32_bf16 v[76:79], v[202:205], v[186:189], v[76:79]
	v_mfma_f32_16x16x32_bf16 v[76:79], v[206:209], v[190:193], v[76:79]
	v_mfma_f32_16x16x32_bf16 v[72:75], v[214:217], v[190:193], v[72:75]
	v_mfma_f32_16x16x32_bf16 v[72:75], v[210:213], v[186:189], v[72:75]
	v_mfma_f32_16x16x32_bf16 v[64:67], v[210:213], v[194:197], v[64:67]
	v_mfma_f32_16x16x32_bf16 v[64:67], v[214:217], v[198:201], v[64:67]
	v_mfma_f32_16x16x32_bf16 v[68:71], v[206:209], v[198:201], v[68:71]
	v_mfma_f32_16x16x32_bf16 v[68:71], v[202:205], v[194:197], v[68:71]
	s_barrier
	s_addk_i32 s45, 0x180
	s_mov_b32 m0, s25
	ds_read_b128 v[170:173], v131 offset:49152
	ds_read_b128 v[174:177], v131 offset:50176
	ds_read_b128 v[178:181], v134 offset:49152
	ds_read_b128 v[182:185], v134 offset:50176
	ds_read_b128 v[186:189], v133 offset:49152
	ds_read_b128 v[190:193], v133 offset:50176
	ds_read_b128 v[194:197], v132 offset:49152
	ds_read_b128 v[198:201], v132 offset:50176
	buffer_load_dwordx4 v143, s[4:7], s45 offen lds
	s_mov_b32 m0, s26
	s_nop 0
	buffer_load_dwordx4 v144, s[4:7], s45 offen lds
	s_barrier
	s_waitcnt lgkmcnt(6)
	v_mfma_f32_16x16x32_bf16 v[60:63], v[154:157], v[170:173], v[60:63]
	v_mfma_f32_16x16x32_bf16 v[60:63], v[158:161], v[174:177], v[60:63]
	v_mfma_f32_16x16x32_bf16 v[56:59], v[166:169], v[174:177], v[56:59]
	v_mfma_f32_16x16x32_bf16 v[56:59], v[162:165], v[170:173], v[56:59]
	s_waitcnt lgkmcnt(4)
	v_mfma_f32_16x16x32_bf16 v[48:51], v[162:165], v[178:181], v[48:51]
	v_mfma_f32_16x16x32_bf16 v[48:51], v[166:169], v[182:185], v[48:51]
	v_mfma_f32_16x16x32_bf16 v[52:55], v[158:161], v[182:185], v[52:55]
	v_mfma_f32_16x16x32_bf16 v[52:55], v[154:157], v[178:181], v[52:55]
	s_waitcnt lgkmcnt(2)
	v_mfma_f32_16x16x32_bf16 v[44:47], v[154:157], v[186:189], v[44:47]
	v_mfma_f32_16x16x32_bf16 v[44:47], v[158:161], v[190:193], v[44:47]
	v_mfma_f32_16x16x32_bf16 v[40:43], v[166:169], v[190:193], v[40:43]
	v_mfma_f32_16x16x32_bf16 v[40:43], v[162:165], v[186:189], v[40:43]
	s_waitcnt lgkmcnt(0)
	v_mfma_f32_16x16x32_bf16 v[32:35], v[162:165], v[194:197], v[32:35]
	v_mfma_f32_16x16x32_bf16 v[32:35], v[166:169], v[198:201], v[32:35]
	v_mfma_f32_16x16x32_bf16 v[36:39], v[158:161], v[198:201], v[36:39]
	v_mfma_f32_16x16x32_bf16 v[36:39], v[154:157], v[194:197], v[36:39]
	s_barrier
	s_addk_i32 s46, 0x180
	s_mov_b32 m0, s27
	s_nop 0
	buffer_load_dwordx4 v143, s[8:11], s46 offen lds
	s_mov_b32 m0, s28
	s_nop 0
	buffer_load_dwordx4 v144, s[8:11], s46 offen lds
	s_add_i32 s14, s14, 2
	s_addk_i32 s15, 0x100
	s_cmp_gt_u32 s14, 27
	s_cbranch_scc0 .LBB0_95
	s_branch .Lmy_post_95

; #define STAGE(P, RS, SOFF, OFF, kt) do { const int _so = (SOFF) + (kt) * (BK * 2); \
;     _Pragma("unroll") for (int _i = 0; _i < 2; ++_i) { \
;       __builtin_amdgcn_raw_ptr_buffer_load_lds(RS, (__attribute__((address_space(3))) void*)((P) + wave * 1024 + _i * 8192), 16, OFF[_i], _so, 0, 0); } } while (0)
; #define LDA(dst, b, h) _Pragma("unroll") for (int m = 0; m < 4; ++m) _Pragma("unroll") for (int k = 0; k < 2; ++k) \
;     dst[m][k] = *reinterpret_cast<const bf16x8*>(SA(b, h) + lds_byte(wr * 64 + m * 16 + fr, k * 32 + fq * 8))
; #define LDB(dst, b, h) _Pragma("unroll") for (int n = 0; n < 2; ++n) _Pragma("unroll") for (int k = 0; k < 2; ++k) \
;     dst[n][k] = *reinterpret_cast<const bf16x8*>(SB(b, h) + lds_byte(wc * 32 + n * 16 + fr, k * 32 + fq * 8))
; #define WAIT_V(n) asm volatile("s_waitcnt vmcnt(" #n ")" ::: "memory")
; #define WAIT_L(n) asm volatile("s_waitcnt lgkmcnt(" #n ")" ::: "memory")
; #define BAR __builtin_amdgcn_s_barrier()
; #define SCHED __builtin_amdgcn_sched_barrier(0)
;     ...
;     for (int t = 0; t < nt - 2; t += 2) {
;       LDB(B0, 0, 0); SCHED; LDA(At, 0, 0); STAGE(SA(1, 1), rsA, sA1, offA, t + 1);
;       WAIT_L(8); BAR; WAIT_L(0); MMA(0, 0, At, B0); BAR; SCHED;
;       LDB(B1, 0, 1); STAGE(SB(0, 0), rsB, sB0, offB, t + 2);
;       BAR; WAIT_L(0); MMA(0, 1, At, B1); BAR;
;       LDA(At, 0, 1); STAGE(SA(0, 0), rsA, sA0, offA, t + 2);
;       BAR; WAIT_L(0); MMA(1, 0, At, B0); BAR; SCHED;
;       STAGE(SB(0, 1), rsB, sB1, offB, t + 2);
;       WAIT_V(6); BAR; MMA(1, 1, At, B1); BAR;
.Lmy_rot_95:
	ds_read_b128 v[154:157], v149
	ds_read_b128 v[158:161], v150
	ds_read_b128 v[162:165], v151
	ds_read_b128 v[166:169], v152
	s_add_i32 s43, s37, s15
	s_add_i32 s10, s43, 0x80
	s_mov_b32 m0, s30
	ds_read_b128 v[170:173], v131
	ds_read_b128 v[174:177], v131 offset:1024
	ds_read_b128 v[178:181], v134
	ds_read_b128 v[182:185], v134 offset:1024
	ds_read_b128 v[186:189], v133
	ds_read_b128 v[190:193], v133 offset:1024
	ds_read_b128 v[194:197], v132
	ds_read_b128 v[198:201], v132 offset:1024
	buffer_load_dwordx4 v143, s[4:7], s10 offen lds
	s_mov_b32 m0, s31
	s_nop 0
	buffer_load_dwordx4 v144, s[4:7], s10 offen lds
	s_waitcnt lgkmcnt(8)
	s_barrier
	s_waitcnt lgkmcnt(0)
	v_mfma_f32_16x16x32_bf16 v[124:127], v[154:157], v[170:173], v[124:127]
	v_mfma_f32_16x16x32_bf16 v[124:127], v[158:161], v[174:177], v[124:127]
	v_mfma_f32_16x16x32_bf16 v[120:123], v[166:169], v[174:177], v[120:123]
	v_mfma_f32_16x16x32_bf16 v[120:123], v[162:165], v[170:173], v[120:123]
	v_mfma_f32_16x16x32_bf16 v[112:115], v[162:165], v[178:181], v[112:115]
	v_mfma_f32_16x16x32_bf16 v[112:115], v[166:169], v[182:185], v[112:115]
	v_mfma_f32_16x16x32_bf16 v[116:119], v[158:161], v[182:185], v[116:119]
	v_mfma_f32_16x16x32_bf16 v[116:119], v[154:157], v[178:181], v[116:119]
	v_mfma_f32_16x16x32_bf16 v[108:111], v[154:157], v[186:189], v[108:111]
	v_mfma_f32_16x16x32_bf16 v[108:111], v[158:161], v[190:193], v[108:111]
	v_mfma_f32_16x16x32_bf16 v[104:107], v[166:169], v[190:193], v[104:107]
	v_mfma_f32_16x16x32_bf16 v[104:107], v[162:165], v[186:189], v[104:107]
	v_mfma_f32_16x16x32_bf16 v[96:99], v[162:165], v[194:197], v[96:99]
	v_mfma_f32_16x16x32_bf16 v[96:99], v[166:169], v[198:201], v[96:99]
	v_mfma_f32_16x16x32_bf16 v[100:103], v[158:161], v[198:201], v[100:103]
	v_mfma_f32_16x16x32_bf16 v[100:103], v[154:157], v[194:197], v[100:103]
	s_barrier
	s_add_i32 s44, s39, s15
	s_add_i32 s45, s44, 0x100
	s_mov_b32 s10, s6
	s_mov_b32 s11, s7
	s_mov_b32 m0, s1
	ds_read_b128 v[202:205], v145
	ds_read_b128 v[206:209], v146
	ds_read_b128 v[210:213], v147
	ds_read_b128 v[214:217], v148
	buffer_load_dwordx4 v143, s[8:11], s45 offen lds
	s_mov_b32 m0, s3
	s_nop 0
	buffer_load_dwordx4 v144, s[8:11], s45 offen lds
	s_barrier
	s_waitcnt lgkmcnt(2)
	v_mfma_f32_16x16x32_bf16 v[92:95], v[202:205], v[170:173], v[92:95]
	v_mfma_f32_16x16x32_bf16 v[92:95], v[206:209], v[174:177], v[92:95]
	s_waitcnt lgkmcnt(0)
	v_mfma_f32_16x16x32_bf16 v[88:91], v[214:217], v[174:177], v[88:91]
	v_mfma_f32_16x16x32_bf16 v[88:91], v[210:213], v[170:173], v[88:91]
	v_mfma_f32_16x16x32_bf16 v[80:83], v[210:213], v[178:181], v[80:83]
	v_mfma_f32_16x16x32_bf16 v[80:83], v[214:217], v[182:185], v[80:83]
	v_mfma_f32_16x16x32_bf16 v[84:87], v[206:209], v[182:185], v[84:87]
	v_mfma_f32_16x16x32_bf16 v[84:87], v[202:205], v[178:181], v[84:87]
	v_mfma_f32_16x16x32_bf16 v[76:79], v[202:205], v[186:189], v[76:79]
	v_mfma_f32_16x16x32_bf16 v[76:79], v[206:209], v[190:193], v[76:79]
	v_mfma_f32_16x16x32_bf16 v[72:75], v[214:217], v[190:193], v[72:75]
	v_mfma_f32_16x16x32_bf16 v[72:75], v[210:213], v[186:189], v[72:75]
	v_mfma_f32_16x16x32_bf16 v[64:67], v[210:213], v[194:197], v[64:67]
	v_mfma_f32_16x16x32_bf16 v[64:67], v[214:217], v[198:201], v[64:67]
	v_mfma_f32_16x16x32_bf16 v[68:71], v[206:209], v[198:201], v[68:71]
	v_mfma_f32_16x16x32_bf16 v[68:71], v[202:205], v[194:197], v[68:71]
	s_barrier
	s_add_i32 s45, s38, s15
	s_add_i32 s46, s45, 0x100
	s_mov_b32 m0, s0
	ds_read_b128 v[170:173], v131 offset:16384
	ds_read_b128 v[174:177], v131 offset:17408
	ds_read_b128 v[178:181], v134 offset:16384
	ds_read_b128 v[182:185], v134 offset:17408
	ds_read_b128 v[186:189], v133 offset:16384
	ds_read_b128 v[190:193], v133 offset:17408
	ds_read_b128 v[194:197], v132 offset:16384
	ds_read_b128 v[198:201], v132 offset:17408
	buffer_load_dwordx4 v143, s[4:7], s46 offen lds
	s_mov_b32 m0, s18
	s_nop 0
	buffer_load_dwordx4 v144, s[4:7], s46 offen lds
	s_barrier
	s_waitcnt lgkmcnt(6)
	v_mfma_f32_16x16x32_bf16 v[60:63], v[154:157], v[170:173], v[60:63]
	v_mfma_f32_16x16x32_bf16 v[60:63], v[158:161], v[174:177], v[60:63]
	v_mfma_f32_16x16x32_bf16 v[56:59], v[166:169], v[174:177], v[56:59]
	v_mfma_f32_16x16x32_bf16 v[56:59], v[162:165], v[170:173], v[56:59]
	s_waitcnt lgkmcnt(4)
	v_mfma_f32_16x16x32_bf16 v[48:51], v[162:165], v[178:181], v[48:51]
	v_mfma_f32_16x16x32_bf16 v[48:51], v[166:169], v[182:185], v[48:51]
	v_mfma_f32_16x16x32_bf16 v[52:55], v[158:161], v[182:185], v[52:55]
	v_mfma_f32_16x16x32_bf16 v[52:55], v[154:157], v[178:181], v[52:55]
	s_waitcnt lgkmcnt(2)
	v_mfma_f32_16x16x32_bf16 v[44:47], v[154:157], v[186:189], v[44:47]
	v_mfma_f32_16x16x32_bf16 v[44:47], v[158:161], v[190:193], v[44:47]
	v_mfma_f32_16x16x32_bf16 v[40:43], v[166:169], v[190:193], v[40:43]
	v_mfma_f32_16x16x32_bf16 v[40:43], v[162:165], v[186:189], v[40:43]
	s_waitcnt lgkmcnt(0)
	v_mfma_f32_16x16x32_bf16 v[32:35], v[162:165], v[194:197], v[32:35]
	v_mfma_f32_16x16x32_bf16 v[32:35], v[166:169], v[198:201], v[32:35]
	v_mfma_f32_16x16x32_bf16 v[36:39], v[158:161], v[198:201], v[36:39]
	v_mfma_f32_16x16x32_bf16 v[36:39], v[154:157], v[194:197], v[36:39]
	s_barrier
	s_add_i32 s46, s40, s15
	s_add_i32 s47, s46, 0x100
	s_mov_b32 m0, s19
	s_nop 0
	buffer_load_dwordx4 v143, s[8:11], s47 offen lds
	s_mov_b32 m0, s20
	s_nop 0
	buffer_load_dwordx4 v144, s[8:11], s47 offen lds
	s_waitcnt vmcnt(6)
	s_barrier
; #define STAGE(P, RS, SOFF, OFF, kt) do { const int _so = (SOFF) + (kt) * (BK * 2); \
;     _Pragma("unroll") for (int _i = 0; _i < 2; ++_i) { \
;       __builtin_amdgcn_raw_ptr_buffer_load_lds(RS, (__attribute__((address_space(3))) void*)((P) + wave * 1024 + _i * 8192), 16, OFF[_i], _so, 0, 0); } } while (0)
; #define LDA(dst, b, h) _Pragma("unroll") for (int m = 0; m < 4; ++m) _Pragma("unroll") for (int k = 0; k < 2; ++k) \
;     dst[m][k] = *reinterpret_cast<const bf16x8*>(SA(b, h) + lds_byte(wr * 64 + m * 16 + fr, k * 32 + fq * 8))
; #define LDB(dst, b, h) _Pragma("unroll") for (int n = 0; n < 2; ++n) _Pragma("unroll") for (int k = 0; k < 2; ++k) \
;     dst[n][k] = *reinterpret_cast<const bf16x8*>(SB(b, h) + lds_byte(wc * 32 + n * 16 + fr, k * 32 + fq * 8))
; #define WAIT_V(n) asm volatile("s_waitcnt vmcnt(" #n ")" ::: "memory")
; #define WAIT_L(n) asm volatile("s_waitcnt lgkmcnt(" #n ")" ::: "memory")
; #define BAR __builtin_amdgcn_s_barrier()
; #define SCHED __builtin_amdgcn_sched_barrier(0)
;     ...
;       WAIT_V(6); BAR; MMA(1, 1, At, B1); BAR;
;       LDB(B0, 1, 0); SCHED; LDA(At, 1, 0); STAGE(SA(0, 1), rsA, sA1, offA, t + 2);
;       WAIT_L(8); BAR; WAIT_L(0); MMA(0, 0, At, B0); BAR; SCHED;
;       LDB(B1, 1, 1); STAGE(SB(1, 0), rsB, sB0, offB, t + 3);
;       BAR; WAIT_L(0); MMA(0, 1, At, B1); BAR;
;       LDA(At, 1, 1); STAGE(SA(1, 0), rsA, sA0, offA, t + 3);
;       BAR; WAIT_L(0); MMA(1, 0, At, B0); BAR; SCHED;
;       STAGE(SB(1, 1), rsB, sB1, offB, t + 3);
;       WAIT_V(6); BAR; MMA(1, 1, At, B1); BAR;
;     }
	v_mfma_f32_16x16x32_bf16 v[28:31], v[202:205], v[170:173], v[28:31]
	v_mfma_f32_16x16x32_bf16 v[28:31], v[206:209], v[174:177], v[28:31]
	v_mfma_f32_16x16x32_bf16 v[24:27], v[214:217], v[174:177], v[24:27]
	v_mfma_f32_16x16x32_bf16 v[24:27], v[210:213], v[170:173], v[24:27]
	v_mfma_f32_16x16x32_bf16 v[16:19], v[210:213], v[178:181], v[16:19]
	v_mfma_f32_16x16x32_bf16 v[16:19], v[214:217], v[182:185], v[16:19]
	v_mfma_f32_16x16x32_bf16 v[20:23], v[206:209], v[182:185], v[20:23]
	v_mfma_f32_16x16x32_bf16 v[20:23], v[202:205], v[178:181], v[20:23]
	v_mfma_f32_16x16x32_bf16 v[12:15], v[202:205], v[186:189], v[12:15]
	v_mfma_f32_16x16x32_bf16 v[12:15], v[206:209], v[190:193], v[12:15]
	v_mfma_f32_16x16x32_bf16 v[8:11], v[214:217], v[190:193], v[8:11]
	v_mfma_f32_16x16x32_bf16 v[8:11], v[210:213], v[186:189], v[8:11]
	v_mfma_f32_16x16x32_bf16 v[0:3], v[210:213], v[194:197], v[0:3]
	v_mfma_f32_16x16x32_bf16 v[0:3], v[214:217], v[198:201], v[0:3]
	v_mfma_f32_16x16x32_bf16 v[4:7], v[206:209], v[198:201], v[4:7]
	v_mfma_f32_16x16x32_bf16 v[4:7], v[202:205], v[194:197], v[4:7]
	s_barrier
	ds_read_b128 v[154:157], v139
	ds_read_b128 v[158:161], v140
	ds_read_b128 v[162:165], v141
	ds_read_b128 v[166:169], v142
	s_addk_i32 s43, 0x100
	s_mov_b32 m0, s21
	ds_read_b128 v[170:173], v131 offset:32768
	ds_read_b128 v[174:177], v131 offset:33792
	ds_read_b128 v[178:181], v134 offset:32768
	ds_read_b128 v[182:185], v134 offset:33792
	ds_read_b128 v[186:189], v133 offset:32768
	ds_read_b128 v[190:193], v133 offset:33792
	ds_read_b128 v[194:197], v132 offset:32768
	ds_read_b128 v[198:201], v132 offset:33792
	buffer_load_dwordx4 v143, s[4:7], s43 offen lds
	s_mov_b32 m0, s22
	s_nop 0
	buffer_load_dwordx4 v144, s[4:7], s43 offen lds
	s_waitcnt lgkmcnt(8)
	s_barrier
	s_waitcnt lgkmcnt(6)
	v_mfma_f32_16x16x32_bf16 v[124:127], v[154:157], v[170:173], v[124:127]
	v_mfma_f32_16x16x32_bf16 v[124:127], v[158:161], v[174:177], v[124:127]
	v_mfma_f32_16x16x32_bf16 v[120:123], v[166:169], v[174:177], v[120:123]
	v_mfma_f32_16x16x32_bf16 v[120:123], v[162:165], v[170:173], v[120:123]
	s_waitcnt lgkmcnt(4)
	v_mfma_f32_16x16x32_bf16 v[112:115], v[162:165], v[178:181], v[112:115]
	v_mfma_f32_16x16x32_bf16 v[112:115], v[166:169], v[182:185], v[112:115]
	v_mfma_f32_16x16x32_bf16 v[116:119], v[158:161], v[182:185], v[116:119]
	v_mfma_f32_16x16x32_bf16 v[116:119], v[154:157], v[178:181], v[116:119]
	s_waitcnt lgkmcnt(2)
	v_mfma_f32_16x16x32_bf16 v[108:111], v[154:157], v[186:189], v[108:111]
	v_mfma_f32_16x16x32_bf16 v[108:111], v[158:161], v[190:193], v[108:111]
	v_mfma_f32_16x16x32_bf16 v[104:107], v[166:169], v[190:193], v[104:107]
	v_mfma_f32_16x16x32_bf16 v[104:107], v[162:165], v[186:189], v[104:107]
	s_waitcnt lgkmcnt(0)
	v_mfma_f32_16x16x32_bf16 v[96:99], v[162:165], v[194:197], v[96:99]
	v_mfma_f32_16x16x32_bf16 v[96:99], v[166:169], v[198:201], v[96:99]
	v_mfma_f32_16x16x32_bf16 v[100:103], v[158:161], v[198:201], v[100:103]
	v_mfma_f32_16x16x32_bf16 v[100:103], v[154:157], v[194:197], v[100:103]
	s_barrier
	s_addk_i32 s44, 0x180
	s_mov_b32 m0, s23
	ds_read_b128 v[202:205], v135
	ds_read_b128 v[206:209], v136
	ds_read_b128 v[210:213], v137
	ds_read_b128 v[214:217], v138
	buffer_load_dwordx4 v143, s[8:11], s44 offen lds
	s_mov_b32 m0, s24
	s_nop 0
	buffer_load_dwordx4 v144, s[8:11], s44 offen lds
	s_barrier
	s_waitcnt lgkmcnt(2)
	v_mfma_f32_16x16x32_bf16 v[92:95], v[202:205], v[170:173], v[92:95]
	v_mfma_f32_16x16x32_bf16 v[92:95], v[206:209], v[174:177], v[92:95]
	s_waitcnt lgkmcnt(0)
	v_mfma_f32_16x16x32_bf16 v[88:91], v[214:217], v[174:177], v[88:91]
	v_mfma_f32_16x16x32_bf16 v[88:91], v[210:213], v[170:173], v[88:91]
	v_mfma_f32_16x16x32_bf16 v[80:83], v[210:213], v[178:181], v[80:83]
	v_mfma_f32_16x16x32_bf16 v[80:83], v[214:217], v[182:185], v[80:83]
	v_mfma_f32_16x16x32_bf16 v[84:87], v[206:209], v[182:185], v[84:87]
	v_mfma_f32_16x16x32_bf16 v[84:87], v[202:205], v[178:181], v[84:87]
	v_mfma_f32_16x16x32_bf16 v[76:79], v[202:205], v[186:189], v[76:79]
	v_mfma_f32_16x16x32_bf16 v[76:79], v[206:209], v[190:193], v[76:79]
	v_mfma_f32_16x16x32_bf16 v[72:75], v[214:217], v[190:193], v[72:75]
	v_mfma_f32_16x16x32_bf16 v[72:75], v[210:213], v[186:189], v[72:75]
	v_mfma_f32_16x16x32_bf16 v[64:67], v[210:213], v[194:197], v[64:67]
	v_mfma_f32_16x16x32_bf16 v[64:67], v[214:217], v[198:201], v[64:67]
	v_mfma_f32_16x16x32_bf16 v[68:71], v[206:209], v[198:201], v[68:71]
	v_mfma_f32_16x16x32_bf16 v[68:71], v[202:205], v[194:197], v[68:71]
	s_barrier
	s_addk_i32 s45, 0x180
	s_mov_b32 m0, s25
	ds_read_b128 v[170:173], v131 offset:49152
	ds_read_b128 v[174:177], v131 offset:50176
	ds_read_b128 v[178:181], v134 offset:49152
	ds_read_b128 v[182:185], v134 offset:50176
	ds_read_b128 v[186:189], v133 offset:49152
	ds_read_b128 v[190:193], v133 offset:50176
	ds_read_b128 v[194:197], v132 offset:49152
	ds_read_b128 v[198:201], v132 offset:50176
	buffer_load_dwordx4 v143, s[4:7], s45 offen lds
	s_mov_b32 m0, s26
	s_nop 0
	buffer_load_dwordx4 v144, s[4:7], s45 offen lds
	s_barrier
	s_waitcnt lgkmcnt(6)
	v_mfma_f32_16x16x32_bf16 v[60:63], v[154:157], v[170:173], v[60:63]
	v_mfma_f32_16x16x32_bf16 v[60:63], v[158:161], v[174:177], v[60:63]
	v_mfma_f32_16x16x32_bf16 v[56:59], v[166:169], v[174:177], v[56:59]
	v_mfma_f32_16x16x32_bf16 v[56:59], v[162:165], v[170:173], v[56:59]
	s_waitcnt lgkmcnt(4)
	v_mfma_f32_16x16x32_bf16 v[48:51], v[162:165], v[178:181], v[48:51]
	v_mfma_f32_16x16x32_bf16 v[48:51], v[166:169], v[182:185], v[48:51]
	v_mfma_f32_16x16x32_bf16 v[52:55], v[158:161], v[182:185], v[52:55]
	v_mfma_f32_16x16x32_bf16 v[52:55], v[154:157], v[178:181], v[52:55]
	s_waitcnt lgkmcnt(2)
	v_mfma_f32_16x16x32_bf16 v[44:47], v[154:157], v[186:189], v[44:47]
	v_mfma_f32_16x16x32_bf16 v[44:47], v[158:161], v[190:193], v[44:47]
	v_mfma_f32_16x16x32_bf16 v[40:43], v[166:169], v[190:193], v[40:43]
	v_mfma_f32_16x16x32_bf16 v[40:43], v[162:165], v[186:189], v[40:43]
	s_waitcnt lgkmcnt(0)
	v_mfma_f32_16x16x32_bf16 v[32:35], v[162:165], v[194:197], v[32:35]
	v_mfma_f32_16x16x32_bf16 v[32:35], v[166:169], v[198:201], v[32:35]
	v_mfma_f32_16x16x32_bf16 v[36:39], v[158:161], v[198:201], v[36:39]
	v_mfma_f32_16x16x32_bf16 v[36:39], v[154:157], v[194:197], v[36:39]
	s_barrier
	s_addk_i32 s46, 0x180
	s_mov_b32 m0, s27
	s_nop 0
	buffer_load_dwordx4 v143, s[8:11], s46 offen lds
	s_mov_b32 m0, s28
	s_nop 0
	buffer_load_dwordx4 v144, s[8:11], s46 offen lds
	s_add_i32 s14, s14, 2
	s_addk_i32 s15, 0x100
	s_cmp_gt_u32 s14, 27
	s_cbranch_scc0 .LBB0_95
; #define STAGE(P, RS, SOFF, OFF, kt) do { const int _so = (SOFF) + (kt) * (BK * 2); \
;     _Pragma("unroll") for (int _i = 0; _i < 2; ++_i) { \
;       __builtin_amdgcn_raw_ptr_buffer_load_lds(RS, (__attribute__((address_space(3))) void*)((P) + wave * 1024 + _i * 8192), 16, OFF[_i], _so, 0, 0); } } while (0)
; #define LDA(dst, b, h) _Pragma("unroll") for (int m = 0; m < 4; ++m) _Pragma("unroll") for (int k = 0; k < 2; ++k) \
;     dst[m][k] = *reinterpret_cast<const bf16x8*>(SA(b, h) + lds_byte(wr * 64 + m * 16 + fr, k * 32 + fq * 8))
; #define LDB(dst, b, h) _Pragma("unroll") for (int n = 0; n < 2; ++n) _Pragma("unroll") for (int k = 0; k < 2; ++k) \
;     dst[n][k] = *reinterpret_cast<const bf16x8*>(SB(b, h) + lds_byte(wc * 32 + n * 16 + fr, k * 32 + fq * 8))
; #define WAIT_V(n) asm volatile("s_waitcnt vmcnt(" #n ")" ::: "memory")
; #define WAIT_L(n) asm volatile("s_waitcnt lgkmcnt(" #n ")" ::: "memory")
; #define BAR __builtin_amdgcn_s_barrier()
;     ...
;       WAIT_V(6); BAR; MMA(1, 1, At, B1); BAR;
;     }
;     { LDB(B0, 0, 0); LDA(At, 0, 0); STAGE(SA(1, 1), rsA, sA1, offA, nt - 1);
;       BAR; WAIT_L(0); MMA(0, 0, At, B0); BAR;
;       LDB(B1, 0, 1); BAR; WAIT_L(0); MMA(0, 1, At, B1); BAR;
;       LDA(At, 0, 1); WAIT_V(4); BAR; WAIT_L(0); MMA(1, 0, At, B0); MMA(1, 1, At, B1); BAR; }
.Lmy_post_95:
	s_waitcnt vmcnt(6)
	s_barrier
	v_mfma_f32_16x16x32_bf16 v[28:31], v[202:205], v[170:173], v[28:31]
	v_mfma_f32_16x16x32_bf16 v[28:31], v[206:209], v[174:177], v[28:31]
	v_mfma_f32_16x16x32_bf16 v[24:27], v[214:217], v[174:177], v[24:27]
	v_mfma_f32_16x16x32_bf16 v[24:27], v[210:213], v[170:173], v[24:27]
	v_mfma_f32_16x16x32_bf16 v[16:19], v[210:213], v[178:181], v[16:19]
	v_mfma_f32_16x16x32_bf16 v[16:19], v[214:217], v[182:185], v[16:19]
	v_mfma_f32_16x16x32_bf16 v[20:23], v[206:209], v[182:185], v[20:23]
	v_mfma_f32_16x16x32_bf16 v[20:23], v[202:205], v[178:181], v[20:23]
	v_mfma_f32_16x16x32_bf16 v[12:15], v[202:205], v[186:189], v[12:15]
	v_mfma_f32_16x16x32_bf16 v[12:15], v[206:209], v[190:193], v[12:15]
	v_mfma_f32_16x16x32_bf16 v[8:11], v[214:217], v[190:193], v[8:11]
	v_mfma_f32_16x16x32_bf16 v[8:11], v[210:213], v[186:189], v[8:11]
	v_mfma_f32_16x16x32_bf16 v[0:3], v[210:213], v[194:197], v[0:3]
	v_mfma_f32_16x16x32_bf16 v[0:3], v[214:217], v[198:201], v[0:3]
	v_mfma_f32_16x16x32_bf16 v[4:7], v[206:209], v[198:201], v[4:7]
	v_mfma_f32_16x16x32_bf16 v[4:7], v[202:205], v[194:197], v[4:7]
	s_barrier
	s_add_i32 s10, s37, 0xf80
	s_mov_b32 m0, s30
	ds_read_b128 v[154:157], v149
	ds_read_b128 v[158:161], v150
	ds_read_b128 v[162:165], v151
	ds_read_b128 v[150:153], v152
	ds_read_b128 v[166:169], v131
	ds_read_b128 v[170:173], v131 offset:1024
	ds_read_b128 v[174:177], v134
	ds_read_b128 v[178:181], v134 offset:1024
	ds_read_b128 v[182:185], v133
	ds_read_b128 v[186:189], v133 offset:1024
	ds_read_b128 v[190:193], v132
	ds_read_b128 v[194:197], v132 offset:1024
	buffer_load_dwordx4 v143, s[4:7], s10 offen lds
	s_mov_b32 m0, s31
	s_nop 0
	buffer_load_dwordx4 v144, s[4:7], s10 offen lds
	s_barrier
	s_waitcnt lgkmcnt(6)
	v_mfma_f32_16x16x32_bf16 v[124:127], v[154:157], v[166:169], v[124:127]
	v_mfma_f32_16x16x32_bf16 v[124:127], v[158:161], v[170:173], v[124:127]
	v_mfma_f32_16x16x32_bf16 v[120:123], v[150:153], v[170:173], v[120:123]
	v_mfma_f32_16x16x32_bf16 v[120:123], v[162:165], v[166:169], v[120:123]
	s_waitcnt lgkmcnt(4)
	v_mfma_f32_16x16x32_bf16 v[112:115], v[162:165], v[174:177], v[112:115]
	v_mfma_f32_16x16x32_bf16 v[112:115], v[150:153], v[178:181], v[112:115]
	v_mfma_f32_16x16x32_bf16 v[116:119], v[158:161], v[178:181], v[116:119]
	v_mfma_f32_16x16x32_bf16 v[116:119], v[154:157], v[174:177], v[116:119]
	s_waitcnt lgkmcnt(2)
	v_mfma_f32_16x16x32_bf16 v[108:111], v[154:157], v[182:185], v[108:111]
	v_mfma_f32_16x16x32_bf16 v[108:111], v[158:161], v[186:189], v[108:111]
	v_mfma_f32_16x16x32_bf16 v[104:107], v[150:153], v[186:189], v[104:107]
	v_mfma_f32_16x16x32_bf16 v[104:107], v[162:165], v[182:185], v[104:107]
	s_waitcnt lgkmcnt(0)
	v_mfma_f32_16x16x32_bf16 v[96:99], v[162:165], v[190:193], v[96:99]
	v_mfma_f32_16x16x32_bf16 v[96:99], v[150:153], v[194:197], v[96:99]
	v_mfma_f32_16x16x32_bf16 v[100:103], v[158:161], v[194:197], v[100:103]
	v_mfma_f32_16x16x32_bf16 v[100:103], v[154:157], v[190:193], v[100:103]
	s_barrier
	ds_read_b128 v[198:201], v145
	ds_read_b128 v[202:205], v146
	ds_read_b128 v[144:147], v147
	ds_read_b128 v[206:209], v148
	s_barrier
	s_waitcnt lgkmcnt(3)
	v_mfma_f32_16x16x32_bf16 v[92:95], v[198:201], v[166:169], v[92:95]
	v_mfma_f32_16x16x32_bf16 v[84:87], v[198:201], v[174:177], v[84:87]
	v_mfma_f32_16x16x32_bf16 v[76:79], v[198:201], v[182:185], v[76:79]
	v_mfma_f32_16x16x32_bf16 v[68:71], v[198:201], v[190:193], v[68:71]
	s_waitcnt lgkmcnt(1)
	v_mfma_f32_16x16x32_bf16 v[88:91], v[144:147], v[166:169], v[88:91]
	v_mfma_f32_16x16x32_bf16 v[80:83], v[144:147], v[174:177], v[80:83]
	v_mfma_f32_16x16x32_bf16 v[72:75], v[144:147], v[182:185], v[72:75]
	v_mfma_f32_16x16x32_bf16 v[64:67], v[144:147], v[190:193], v[64:67]
	v_mfma_f32_16x16x32_bf16 v[92:95], v[202:205], v[170:173], v[92:95]
	v_mfma_f32_16x16x32_bf16 v[84:87], v[202:205], v[178:181], v[84:87]
	v_mfma_f32_16x16x32_bf16 v[76:79], v[202:205], v[186:189], v[76:79]
	v_mfma_f32_16x16x32_bf16 v[68:71], v[202:205], v[194:197], v[68:71]
	s_waitcnt lgkmcnt(0)
	v_mfma_f32_16x16x32_bf16 v[166:169], v[206:209], v[170:173], v[88:91]
	v_mfma_f32_16x16x32_bf16 v[170:173], v[206:209], v[178:181], v[80:83]
	v_mfma_f32_16x16x32_bf16 v[174:177], v[206:209], v[186:189], v[72:75]
	v_mfma_f32_16x16x32_bf16 v[178:181], v[206:209], v[194:197], v[64:67]
	s_barrier
	s_nop 0
	ds_read_b128 v[64:67], v131 offset:16384
	ds_read_b128 v[72:75], v131 offset:17408
	ds_read_b128 v[80:83], v134 offset:16384
	ds_read_b128 v[88:91], v134 offset:17408
	ds_read_b128 v[182:185], v133 offset:16384
	ds_read_b128 v[186:189], v133 offset:17408
	ds_read_b128 v[190:193], v132 offset:16384
	ds_read_b128 v[194:197], v132 offset:17408
	s_waitcnt vmcnt(4)
	s_barrier
; #define LDA(dst, b, h) _Pragma("unroll") for (int m = 0; m < 4; ++m) _Pragma("unroll") for (int k = 0; k < 2; ++k) \
;     dst[m][k] = *reinterpret_cast<const bf16x8*>(SA(b, h) + lds_byte(wr * 64 + m * 16 + fr, k * 32 + fq * 8))
; #define LDB(dst, b, h) _Pragma("unroll") for (int n = 0; n < 2; ++n) _Pragma("unroll") for (int k = 0; k < 2; ++k) \
;     dst[n][k] = *reinterpret_cast<const bf16x8*>(SB(b, h) + lds_byte(wc * 32 + n * 16 + fr, k * 32 + fq * 8))
; #define WAIT_V(n) asm volatile("s_waitcnt vmcnt(" #n ")" ::: "memory")
; #define WAIT_L(n) asm volatile("s_waitcnt lgkmcnt(" #n ")" ::: "memory")
; #define BAR __builtin_amdgcn_s_barrier()
;     ...
;       LDA(At, 0, 1); WAIT_V(4); BAR; WAIT_L(0); MMA(1, 0, At, B0); MMA(1, 1, At, B1); BAR; }
;     { LDB(B0, 1, 0); LDA(At, 1, 0); WAIT_V(2); BAR; WAIT_L(0); MMA(0, 0, At, B0); BAR;
	s_waitcnt lgkmcnt(0)
	v_mfma_f32_16x16x32_bf16 v[60:63], v[154:157], v[64:67], v[60:63]
	v_mfma_f32_16x16x32_bf16 v[56:59], v[162:165], v[64:67], v[56:59]
	v_mfma_f32_16x16x32_bf16 v[52:55], v[154:157], v[80:83], v[52:55]
	v_mfma_f32_16x16x32_bf16 v[48:51], v[162:165], v[80:83], v[48:51]
	v_mfma_f32_16x16x32_bf16 v[44:47], v[154:157], v[182:185], v[44:47]
	v_mfma_f32_16x16x32_bf16 v[40:43], v[162:165], v[182:185], v[40:43]
	v_mfma_f32_16x16x32_bf16 v[36:39], v[154:157], v[190:193], v[36:39]
	v_mfma_f32_16x16x32_bf16 v[32:35], v[162:165], v[190:193], v[32:35]
	v_mfma_f32_16x16x32_bf16 v[60:63], v[158:161], v[72:75], v[60:63]
	v_mfma_f32_16x16x32_bf16 v[56:59], v[150:153], v[72:75], v[56:59]
	v_mfma_f32_16x16x32_bf16 v[52:55], v[158:161], v[88:91], v[52:55]
	v_mfma_f32_16x16x32_bf16 v[48:51], v[150:153], v[88:91], v[48:51]
	v_mfma_f32_16x16x32_bf16 v[44:47], v[158:161], v[186:189], v[44:47]
	v_mfma_f32_16x16x32_bf16 v[40:43], v[150:153], v[186:189], v[40:43]
	v_mfma_f32_16x16x32_bf16 v[36:39], v[158:161], v[194:197], v[36:39]
	v_mfma_f32_16x16x32_bf16 v[32:35], v[150:153], v[194:197], v[32:35]
	v_mfma_f32_16x16x32_bf16 v[28:31], v[198:201], v[64:67], v[28:31]
	v_mfma_f32_16x16x32_bf16 v[20:23], v[198:201], v[80:83], v[20:23]
	v_mfma_f32_16x16x32_bf16 v[12:15], v[198:201], v[182:185], v[12:15]
	v_mfma_f32_16x16x32_bf16 v[4:7], v[198:201], v[190:193], v[4:7]
	v_mfma_f32_16x16x32_bf16 v[24:27], v[144:147], v[64:67], v[24:27]
	v_mfma_f32_16x16x32_bf16 v[16:19], v[144:147], v[80:83], v[16:19]
	v_mfma_f32_16x16x32_bf16 v[8:11], v[144:147], v[182:185], v[8:11]
	v_mfma_f32_16x16x32_bf16 v[0:3], v[144:147], v[190:193], v[0:3]
	v_mfma_f32_16x16x32_bf16 v[28:31], v[202:205], v[72:75], v[28:31]
	v_mfma_f32_16x16x32_bf16 v[20:23], v[202:205], v[88:91], v[20:23]
	v_mfma_f32_16x16x32_bf16 v[12:15], v[202:205], v[186:189], v[12:15]
	v_mfma_f32_16x16x32_bf16 v[4:7], v[202:205], v[194:197], v[4:7]
	v_mfma_f32_16x16x32_bf16 v[144:147], v[206:209], v[72:75], v[24:27]
	v_mfma_f32_16x16x32_bf16 v[148:151], v[206:209], v[88:91], v[16:19]
	v_mfma_f32_16x16x32_bf16 v[152:155], v[206:209], v[186:189], v[8:11]
	v_mfma_f32_16x16x32_bf16 v[156:159], v[206:209], v[194:197], v[0:3]
	s_barrier
	s_nop 0
	ds_read_b128 v[0:3], v139
	ds_read_b128 v[8:11], v140
	ds_read_b128 v[16:19], v141
	ds_read_b128 v[140:143], v142
	ds_read_b128 v[24:27], v131 offset:32768
	ds_read_b128 v[160:163], v131 offset:33792
	ds_read_b128 v[182:185], v134 offset:32768
	ds_read_b128 v[186:189], v134 offset:33792
	ds_read_b128 v[190:193], v133 offset:32768
	ds_read_b128 v[194:197], v133 offset:33792
	ds_read_b128 v[198:201], v132 offset:32768
	ds_read_b128 v[202:205], v132 offset:33792
	s_waitcnt vmcnt(2)
	s_barrier
	s_waitcnt lgkmcnt(7)
	v_mfma_f32_16x16x32_bf16 v[64:67], v[0:3], v[24:27], v[124:127]
	v_mfma_f32_16x16x32_bf16 v[72:75], v[16:19], v[24:27], v[120:123]
	s_waitcnt lgkmcnt(5)
	v_mfma_f32_16x16x32_bf16 v[80:83], v[0:3], v[182:185], v[116:119]
	v_mfma_f32_16x16x32_bf16 v[88:91], v[16:19], v[182:185], v[112:115]
	s_waitcnt lgkmcnt(3)
	v_mfma_f32_16x16x32_bf16 v[108:111], v[0:3], v[190:193], v[108:111]
	v_mfma_f32_16x16x32_bf16 v[116:119], v[16:19], v[190:193], v[104:107]
	s_waitcnt lgkmcnt(1)
	v_mfma_f32_16x16x32_bf16 v[100:103], v[0:3], v[198:201], v[100:103]
	v_mfma_f32_16x16x32_bf16 v[124:127], v[16:19], v[198:201], v[96:99]
	v_mfma_f32_16x16x32_bf16 v[120:123], v[8:11], v[160:163], v[64:67]
	v_mfma_f32_16x16x32_bf16 v[112:115], v[140:143], v[160:163], v[72:75]
	v_mfma_f32_16x16x32_bf16 v[104:107], v[8:11], v[186:189], v[80:83]
	v_mfma_f32_16x16x32_bf16 v[96:99], v[140:143], v[186:189], v[88:91]
	v_mfma_f32_16x16x32_bf16 v[88:91], v[8:11], v[194:197], v[108:111]
	v_mfma_f32_16x16x32_bf16 v[80:83], v[140:143], v[194:197], v[116:119]
	s_waitcnt lgkmcnt(0)
	v_mfma_f32_16x16x32_bf16 v[72:75], v[8:11], v[202:205], v[100:103]
	v_mfma_f32_16x16x32_bf16 v[64:67], v[140:143], v[202:205], v[124:127]
	s_barrier
; #define LDA(dst, b, h) _Pragma("unroll") for (int m = 0; m < 4; ++m) _Pragma("unroll") for (int k = 0; k < 2; ++k) \
;     dst[m][k] = *reinterpret_cast<const bf16x8*>(SA(b, h) + lds_byte(wr * 64 + m * 16 + fr, k * 32 + fq * 8))
; #define LDB(dst, b, h) _Pragma("unroll") for (int n = 0; n < 2; ++n) _Pragma("unroll") for (int k = 0; k < 2; ++k) \
;     dst[n][k] = *reinterpret_cast<const bf16x8*>(SB(b, h) + lds_byte(wc * 32 + n * 16 + fr, k * 32 + fq * 8))
; #define WAIT_V(n) asm volatile("s_waitcnt vmcnt(" #n ")" ::: "memory")
; #define WAIT_L(n) asm volatile("s_waitcnt lgkmcnt(" #n ")" ::: "memory")
; #define BAR __builtin_amdgcn_s_barrier()
;     ...
;     { LDB(B0, 1, 0); LDA(At, 1, 0); WAIT_V(2); BAR; WAIT_L(0); MMA(0, 0, At, B0); BAR;
;       LDB(B1, 1, 1); WAIT_V(0); BAR; WAIT_L(0); MMA(0, 1, At, B1); BAR;
;       LDA(At, 1, 1); BAR; WAIT_L(0); MMA(1, 0, At, B0); MMA(1, 1, At, B1); BAR; }
;     if (wr == 0) BAR;
	ds_read_b128 v[206:209], v135
	ds_read_b128 v[210:213], v136
	ds_read_b128 v[214:217], v137
	ds_read_b128 v[136:139], v138
	s_waitcnt vmcnt(0)
	s_barrier
	s_waitcnt lgkmcnt(1)
	v_mfma_f32_16x16x32_bf16 v[92:95], v[206:209], v[24:27], v[92:95]
	v_mfma_f32_16x16x32_bf16 v[24:27], v[214:217], v[24:27], v[166:169]
	v_mfma_f32_16x16x32_bf16 v[84:87], v[206:209], v[182:185], v[84:87]
	v_mfma_f32_16x16x32_bf16 v[100:103], v[214:217], v[182:185], v[170:173]
	v_mfma_f32_16x16x32_bf16 v[76:79], v[206:209], v[190:193], v[76:79]
	v_mfma_f32_16x16x32_bf16 v[164:167], v[214:217], v[190:193], v[174:177]
	v_mfma_f32_16x16x32_bf16 v[68:71], v[206:209], v[198:201], v[68:71]
	v_mfma_f32_16x16x32_bf16 v[168:171], v[214:217], v[198:201], v[178:181]
	s_waitcnt lgkmcnt(0)
	v_mfma_f32_16x16x32_bf16 v[124:127], v[210:213], v[160:163], v[92:95]
	v_mfma_f32_16x16x32_bf16 v[116:119], v[136:139], v[160:163], v[24:27]
	v_mfma_f32_16x16x32_bf16 v[108:111], v[210:213], v[186:189], v[84:87]
	v_mfma_f32_16x16x32_bf16 v[100:103], v[136:139], v[186:189], v[100:103]
	v_mfma_f32_16x16x32_bf16 v[92:95], v[210:213], v[194:197], v[76:79]
	v_mfma_f32_16x16x32_bf16 v[84:87], v[136:139], v[194:197], v[164:167]
	v_mfma_f32_16x16x32_bf16 v[76:79], v[210:213], v[202:205], v[68:71]
	v_mfma_f32_16x16x32_bf16 v[68:71], v[136:139], v[202:205], v[168:171]
	s_barrier
	ds_read_b128 v[160:163], v131 offset:49152
	ds_read_b128 v[164:167], v131 offset:50176
	ds_read_b128 v[168:171], v134 offset:49152
	ds_read_b128 v[172:175], v134 offset:50176
	ds_read_b128 v[176:179], v133 offset:49152
	ds_read_b128 v[180:183], v133 offset:50176
	ds_read_b128 v[184:187], v132 offset:49152
	ds_read_b128 v[132:135], v132 offset:50176
	s_barrier
	s_waitcnt lgkmcnt(0)
	v_mfma_f32_16x16x32_bf16 v[24:27], v[0:3], v[160:163], v[60:63]
	v_mfma_f32_16x16x32_bf16 v[60:63], v[16:19], v[160:163], v[56:59]
	v_mfma_f32_16x16x32_bf16 v[52:55], v[0:3], v[168:171], v[52:55]
	v_mfma_f32_16x16x32_bf16 v[188:191], v[16:19], v[168:171], v[48:51]
	v_mfma_f32_16x16x32_bf16 v[44:47], v[0:3], v[176:179], v[44:47]
	v_mfma_f32_16x16x32_bf16 v[192:195], v[16:19], v[176:179], v[40:43]
	v_mfma_f32_16x16x32_bf16 v[0:3], v[0:3], v[184:187], v[36:39]
	v_mfma_f32_16x16x32_bf16 v[36:39], v[16:19], v[184:187], v[32:35]
	v_mfma_f32_16x16x32_bf16 v[56:59], v[8:11], v[164:167], v[24:27]
	v_mfma_f32_16x16x32_bf16 v[48:51], v[140:143], v[164:167], v[60:63]
	v_mfma_f32_16x16x32_bf16 v[40:43], v[8:11], v[172:175], v[52:55]
	v_mfma_f32_16x16x32_bf16 v[32:35], v[140:143], v[172:175], v[188:191]
	v_mfma_f32_16x16x32_bf16 v[24:27], v[8:11], v[180:183], v[44:47]
	v_mfma_f32_16x16x32_bf16 v[16:19], v[140:143], v[180:183], v[192:195]
	v_mfma_f32_16x16x32_bf16 v[8:11], v[8:11], v[132:135], v[0:3]
	v_mfma_f32_16x16x32_bf16 v[0:3], v[140:143], v[132:135], v[36:39]
	v_mfma_f32_16x16x32_bf16 v[28:31], v[206:209], v[160:163], v[28:31]
	v_mfma_f32_16x16x32_bf16 v[36:39], v[214:217], v[160:163], v[144:147]
	v_mfma_f32_16x16x32_bf16 v[20:23], v[206:209], v[168:171], v[20:23]
	v_mfma_f32_16x16x32_bf16 v[140:143], v[214:217], v[168:171], v[148:151]
	v_mfma_f32_16x16x32_bf16 v[12:15], v[206:209], v[176:179], v[12:15]
	v_mfma_f32_16x16x32_bf16 v[144:147], v[214:217], v[176:179], v[152:155]
	v_mfma_f32_16x16x32_bf16 v[4:7], v[206:209], v[184:187], v[4:7]
	v_mfma_f32_16x16x32_bf16 v[148:151], v[214:217], v[184:187], v[156:159]
	v_mfma_f32_16x16x32_bf16 v[60:63], v[210:213], v[164:167], v[28:31]
	v_mfma_f32_16x16x32_bf16 v[52:55], v[136:139], v[164:167], v[36:39]
	v_mfma_f32_16x16x32_bf16 v[44:47], v[210:213], v[172:175], v[20:23]
	v_mfma_f32_16x16x32_bf16 v[36:39], v[136:139], v[172:175], v[140:143]
	v_mfma_f32_16x16x32_bf16 v[28:31], v[210:213], v[180:183], v[12:15]
	v_mfma_f32_16x16x32_bf16 v[20:23], v[136:139], v[180:183], v[144:147]
	v_mfma_f32_16x16x32_bf16 v[12:15], v[210:213], v[132:135], v[4:7]
	v_mfma_f32_16x16x32_bf16 v[4:7], v[136:139], v[132:135], v[148:151]
	v_cmp_gt_u32_e32 vcc, s35, v130
	s_barrier
	s_and_saveexec_b64 s[10:11], vcc
	s_cbranch_execz .LBB0_98
	s_barrier

; #define STAGE(P, RS, SOFF, OFF, kt) do { const int _so = (SOFF) + (kt) * (BK * 2); \
;     _Pragma("unroll") for (int _i = 0; _i < 2; ++_i) { \
;       __builtin_amdgcn_raw_ptr_buffer_load_lds(RS, (__attribute__((address_space(3))) void*)((P) + wave * 1024 + _i * 8192), 16, OFF[_i], _so, 0, 0); } } while (0)
; #define LDA(dst, b, h) _Pragma("unroll") for (int m = 0; m < 4; ++m) _Pragma("unroll") for (int k = 0; k < 2; ++k) \
;     dst[m][k] = *reinterpret_cast<const bf16x8*>(SA(b, h) + lds_byte(wr * 64 + m * 16 + fr, k * 32 + fq * 8))
; #define LDB(dst, b, h) _Pragma("unroll") for (int n = 0; n < 2; ++n) _Pragma("unroll") for (int k = 0; k < 2; ++k) \
;     dst[n][k] = *reinterpret_cast<const bf16x8*>(SB(b, h) + lds_byte(wc * 32 + n * 16 + fr, k * 32 + fq * 8))
; #define WAIT_V(n) asm volatile("s_waitcnt vmcnt(" #n ")" ::: "memory")
; #define WAIT_L(n) asm volatile("s_waitcnt lgkmcnt(" #n ")" ::: "memory")
; #define BAR __builtin_amdgcn_s_barrier()
; #define SCHED __builtin_amdgcn_sched_barrier(0)
;     ...
;     const int tid = opaque_tid(wave);
;     const int wid = tid >> 6, lane = tid & 63, wr = wid >> 2, wc = wid & 3, fr = lane & 15, fq = lane >> 4;
;     int offA[2], offB[2];
;     _Pragma("unroll") for (int i = 0; i < 2; ++i) {
;       int r, c; stage_rc(tid * 16 + i * 8192, r, c);
;       offA[i] = (r * lda + c) * 2; offB[i] = (r * ldb + c) * 2;
;     }
;     const int brow = pm * BM;
;     f32x4 acc[2][2][4][2];
;     _Pragma("unroll") for (int a = 0; a < 2; ++a) _Pragma("unroll") for (int b = 0; b < 2; ++b) _Pragma("unroll") for (int m = 0; m < 4; ++m) _Pragma("unroll") for (int n = 0; n < 2; ++n)
;       acc[a][b][m][n] = f32x4{0.f, 0.f, 0.f, 0.f};
;     bf16x8 At[4][2], B0[2][2], B1[2][2];
;     if (wr == 1) BAR;
;     if (first_tile) { WAIT_V(0); }
;     else if constexpr (mode == MODE_RESID_LN) { WAIT_V(0); }
;     else if constexpr (mode == MODE_SWIGLU) { WAIT_V(6); }
;     else if constexpr (mode == MODE_V) { WAIT_V(24); }
;     else { WAIT_V(12); }
;     first_tile = false;
;     BAR;
;     BAR;
;     for (int t = 0; t < nt - 2; t += 2) {
;       LDB(B0, 0, 0); SCHED; LDA(At, 0, 0); STAGE(SA(1, 1), rsA, sA1, offA, t + 1);
;       WAIT_L(8); BAR; WAIT_L(0); MMA(0, 0, At, B0); BAR; SCHED;
;       LDB(B1, 0, 1); STAGE(SB(0, 0), rsB, sB0, offB, t + 2);
.LBB0_109:
	v_bfe_i32 v4, v136, 27, 1
	v_lshlrev_b32_e32 v2, 4, v136
	v_lshrrev_b32_e32 v4, 22, v4
	v_add_u32_e32 v4, v2, v4
	v_and_b32_e32 v4, 0xfffffc00, v4
	v_sub_u32_e32 v4, v2, v4
	v_lshrrev_b32_e32 v5, 4, v4
	v_ashrrev_i32_e32 v3, 31, v136
	v_bitop3_b32 v4, v5, v4, 32 bitop3:0x6c
	v_lshrrev_b32_e32 v3, 26, v3
	v_ashrrev_i32_e32 v6, 31, v4
	v_add_u32_e32 v3, v136, v3
	v_lshrrev_b32_e32 v6, 26, v6
	v_ashrrev_i32_e32 v3, 6, v3
	v_add_u32_e32 v6, v4, v6
	v_lshlrev_b32_e32 v5, 3, v3
	v_ashrrev_i32_e32 v7, 6, v6
	v_and_b32_e32 v6, 0xc0, v6
	v_and_b32_e32 v5, -16, v5
	v_lshlrev_b32_e32 v3, 5, v3
	v_sub_u32_e32 v4, v4, v6
	v_add_u32_e32 v5, v7, v5
	v_and_b32_e32 v3, 32, v3
	v_ashrrev_i16_sdwa v4, v129, sext(v4) dst_sel:DWORD dst_unused:UNUSED_PAD src0_sel:DWORD src1_sel:BYTE_0
	v_add_u32_sdwa v3, v3, sext(v4) dst_sel:DWORD dst_unused:UNUSED_PAD src0_sel:DWORD src1_sel:WORD_0
	v_lshlrev_b32_e32 v4, 10, v5
	v_add_u32_e32 v2, 0x2000, v2
	v_lshl_add_u32 v128, v3, 1, v4
	v_ashrrev_i32_e32 v3, 31, v2
	v_lshrrev_b32_e32 v3, 22, v3
	v_add_u32_e32 v3, v2, v3
	v_ashrrev_i32_e32 v3, 10, v3
	v_mul_i32_i24_e32 v4, 0x400, v3
	v_sub_u32_e32 v2, v2, v4
	v_lshrrev_b32_e32 v4, 4, v2
	v_bitop3_b32 v2, v4, v2, 32 bitop3:0x6c
	v_mad_u64_u32 v[130:131], s[10:11], v5, s1, v[128:129]
	v_ashrrev_i32_e32 v5, 31, v2
	v_lshrrev_b32_e32 v5, 26, v5
	v_add_u32_e32 v5, v2, v5
	v_lshlrev_b32_e32 v4, 3, v3
	v_ashrrev_i32_e32 v6, 6, v5
	v_and_b32_e32 v5, 0xc0, v5
	v_and_b32_e32 v4, -16, v4
	v_lshlrev_b32_e32 v3, 5, v3
	v_sub_u32_e32 v2, v2, v5
	v_add_u32_e32 v4, v6, v4
	v_and_b32_e32 v3, 32, v3
	v_ashrrev_i16_sdwa v2, v129, sext(v2) dst_sel:DWORD dst_unused:UNUSED_PAD src0_sel:DWORD src1_sel:BYTE_0
	v_add_u32_sdwa v2, v3, sext(v2) dst_sel:DWORD dst_unused:UNUSED_PAD src0_sel:DWORD src1_sel:WORD_0
	v_lshlrev_b32_e32 v3, 10, v4
	v_lshl_add_u32 v132, v2, 1, v3
	v_and_b32_e32 v3, 15, v0
	v_lshlrev_b32_e32 v5, 2, v0
	v_and_b32_e32 v2, 48, v0
	v_lshlrev_b32_e32 v3, 6, v3
	v_and_b32_e32 v5, 32, v5
	v_lshlrev_b32_e32 v0, 6, v0
	v_mad_u64_u32 v[134:135], s[10:11], v4, s1, v[132:133]
	v_or_b32_e32 v4, v3, v2
	v_bitop3_b32 v3, v3, v5, v2 bitop3:0x36
	v_lshlrev_b32_e32 v6, 6, v136
	v_lshlrev_b32_e32 v1, 13, v1
	v_and_or_b32 v0, v0, s35, v2
	v_and_or_b32 v3, v6, s34, v3
	v_bitop3_b32 v0, v1, v0, v5 bitop3:0xf6
	v_or_b32_e32 v6, 0x400, v3
	v_or_b32_e32 v7, 0x800, v3
	v_or_b32_e32 v8, 0xc00, v3
	v_or_b32_e32 v138, 0x800, v0
	v_or_b32_e32 v137, 0x1000, v0
	v_or_b32_e32 v135, 0x1800, v0
	v_mov_b32_e32 v0, 0
	v_bitop3_b32 v131, v4, v1, v5 bitop3:0xde
	s_mov_b32 s16, -2
	s_mov_b32 s17, 0
	v_or_b32_e32 v151, 0x10000, v3
	v_or_b32_e32 v152, 0x10000, v6
	v_or_b32_e32 v153, 0x10000, v7
	v_or_b32_e32 v154, 0x10000, v8
	v_or_b32_e32 v147, 0x14000, v3
	v_or_b32_e32 v148, 0x14000, v6
	v_or_b32_e32 v149, 0x14000, v7
	v_or_b32_e32 v150, 0x14000, v8
	v_or_b32_e32 v143, 0x18000, v3
	v_or_b32_e32 v144, 0x18000, v6
	v_or_b32_e32 v145, 0x18000, v7
	v_or_b32_e32 v146, 0x18000, v8
	v_or_b32_e32 v139, 0x1c000, v3
	v_or_b32_e32 v140, 0x1c000, v6
	v_or_b32_e32 v141, 0x1c000, v7
	v_or_b32_e32 v142, 0x1c000, v8
	s_barrier
	s_barrier
	ds_read_b128 v[156:159], v151
	ds_read_b128 v[160:163], v152
	ds_read_b128 v[164:167], v153
	ds_read_b128 v[168:171], v154
	s_add_i32 s44, s38, s17
	s_add_i32 s10, s44, 0x80
	s_mov_b32 m0, s31
	ds_read_b128 v[172:175], v131
	ds_read_b128 v[176:179], v131 offset:1024
	ds_read_b128 v[180:183], v138
	ds_read_b128 v[184:187], v138 offset:1024
	ds_read_b128 v[188:191], v137
	ds_read_b128 v[192:195], v137 offset:1024
	ds_read_b128 v[196:199], v135
	ds_read_b128 v[200:203], v135 offset:1024
	buffer_load_dwordx4 v128, s[4:7], s10 offen lds
	s_mov_b32 m0, s33
	s_nop 0
	buffer_load_dwordx4 v132, s[4:7], s10 offen lds
	s_waitcnt lgkmcnt(8)
	s_barrier
	s_waitcnt lgkmcnt(0)
	v_mfma_f32_16x16x32_bf16 v[124:127], v[156:159], v[172:175], 0
	v_mfma_f32_16x16x32_bf16 v[124:127], v[160:163], v[176:179], v[124:127]
	v_mfma_f32_16x16x32_bf16 v[120:123], v[168:171], v[176:179], 0
	v_mfma_f32_16x16x32_bf16 v[120:123], v[164:167], v[172:175], v[120:123]
	v_mfma_f32_16x16x32_bf16 v[112:115], v[164:167], v[180:183], 0
	v_mfma_f32_16x16x32_bf16 v[112:115], v[168:171], v[184:187], v[112:115]
	v_mfma_f32_16x16x32_bf16 v[116:119], v[160:163], v[184:187], 0
	v_mfma_f32_16x16x32_bf16 v[116:119], v[156:159], v[180:183], v[116:119]
	v_mfma_f32_16x16x32_bf16 v[108:111], v[156:159], v[188:191], 0
	v_mfma_f32_16x16x32_bf16 v[108:111], v[160:163], v[192:195], v[108:111]
	v_mfma_f32_16x16x32_bf16 v[104:107], v[168:171], v[192:195], 0
	v_mfma_f32_16x16x32_bf16 v[104:107], v[164:167], v[188:191], v[104:107]
	v_mfma_f32_16x16x32_bf16 v[96:99], v[164:167], v[196:199], 0
	v_mfma_f32_16x16x32_bf16 v[96:99], v[168:171], v[200:203], v[96:99]
	v_mfma_f32_16x16x32_bf16 v[100:103], v[160:163], v[200:203], 0
	v_mfma_f32_16x16x32_bf16 v[100:103], v[156:159], v[196:199], v[100:103]
	s_barrier
	s_add_i32 s45, s40, s17
	s_add_i32 s46, s45, 0x100
	s_mov_b32 s10, s6
	s_mov_b32 s11, s7
	s_mov_b32 m0, s3
	ds_read_b128 v[204:207], v147
	ds_read_b128 v[208:211], v148
	ds_read_b128 v[212:215], v149
	ds_read_b128 v[216:219], v150
	buffer_load_dwordx4 v130, s[8:11], s46 offen lds
	s_mov_b32 m0, s18
	s_nop 0
	buffer_load_dwordx4 v134, s[8:11], s46 offen lds
	s_barrier
; #define STAGE(P, RS, SOFF, OFF, kt) do { const int _so = (SOFF) + (kt) * (BK * 2); \
;     _Pragma("unroll") for (int _i = 0; _i < 2; ++_i) { \
;       __builtin_amdgcn_raw_ptr_buffer_load_lds(RS, (__attribute__((address_space(3))) void*)((P) + wave * 1024 + _i * 8192), 16, OFF[_i], _so, 0, 0); } } while (0)
; #define LDA(dst, b, h) _Pragma("unroll") for (int m = 0; m < 4; ++m) _Pragma("unroll") for (int k = 0; k < 2; ++k) \
;     dst[m][k] = *reinterpret_cast<const bf16x8*>(SA(b, h) + lds_byte(wr * 64 + m * 16 + fr, k * 32 + fq * 8))
; #define LDB(dst, b, h) _Pragma("unroll") for (int n = 0; n < 2; ++n) _Pragma("unroll") for (int k = 0; k < 2; ++k) \
;     dst[n][k] = *reinterpret_cast<const bf16x8*>(SB(b, h) + lds_byte(wc * 32 + n * 16 + fr, k * 32 + fq * 8))
; #define WAIT_V(n) asm volatile("s_waitcnt vmcnt(" #n ")" ::: "memory")
; #define WAIT_L(n) asm volatile("s_waitcnt lgkmcnt(" #n ")" ::: "memory")
; #define BAR __builtin_amdgcn_s_barrier()
; #define SCHED __builtin_amdgcn_sched_barrier(0)
;     ...
;       BAR; WAIT_L(0); MMA(0, 1, At, B1); BAR;
;       LDA(At, 0, 1); STAGE(SA(0, 0), rsA, sA0, offA, t + 2);
;       BAR; WAIT_L(0); MMA(1, 0, At, B0); BAR; SCHED;
;       STAGE(SB(0, 1), rsB, sB1, offB, t + 2);
;       WAIT_V(6); BAR; MMA(1, 1, At, B1); BAR;
;       LDB(B0, 1, 0); SCHED; LDA(At, 1, 0); STAGE(SA(0, 1), rsA, sA1, offA, t + 2);
;       WAIT_L(8); BAR; WAIT_L(0); MMA(0, 0, At, B0); BAR; SCHED;
	s_waitcnt lgkmcnt(2)
	v_mfma_f32_16x16x32_bf16 v[92:95], v[204:207], v[172:175], 0
	v_mfma_f32_16x16x32_bf16 v[92:95], v[208:211], v[176:179], v[92:95]
	s_waitcnt lgkmcnt(0)
	v_mfma_f32_16x16x32_bf16 v[88:91], v[216:219], v[176:179], 0
	v_mfma_f32_16x16x32_bf16 v[88:91], v[212:215], v[172:175], v[88:91]
	v_mfma_f32_16x16x32_bf16 v[80:83], v[212:215], v[180:183], 0
	v_mfma_f32_16x16x32_bf16 v[80:83], v[216:219], v[184:187], v[80:83]
	v_mfma_f32_16x16x32_bf16 v[84:87], v[208:211], v[184:187], 0
	v_mfma_f32_16x16x32_bf16 v[84:87], v[204:207], v[180:183], v[84:87]
	v_mfma_f32_16x16x32_bf16 v[76:79], v[204:207], v[188:191], 0
	v_mfma_f32_16x16x32_bf16 v[76:79], v[208:211], v[192:195], v[76:79]
	v_mfma_f32_16x16x32_bf16 v[72:75], v[216:219], v[192:195], 0
	v_mfma_f32_16x16x32_bf16 v[72:75], v[212:215], v[188:191], v[72:75]
	v_mfma_f32_16x16x32_bf16 v[64:67], v[212:215], v[196:199], 0
	v_mfma_f32_16x16x32_bf16 v[64:67], v[216:219], v[200:203], v[64:67]
	v_mfma_f32_16x16x32_bf16 v[68:71], v[208:211], v[200:203], 0
	v_mfma_f32_16x16x32_bf16 v[68:71], v[204:207], v[196:199], v[68:71]
	s_barrier
	s_add_i32 s46, s39, s17
	s_add_i32 s47, s46, 0x100
	s_mov_b32 m0, s0
	ds_read_b128 v[172:175], v131 offset:16384
	ds_read_b128 v[176:179], v131 offset:17408
	ds_read_b128 v[180:183], v138 offset:16384
	ds_read_b128 v[184:187], v138 offset:17408
	ds_read_b128 v[188:191], v137 offset:16384
	ds_read_b128 v[192:195], v137 offset:17408
	ds_read_b128 v[196:199], v135 offset:16384
	ds_read_b128 v[200:203], v135 offset:17408
	buffer_load_dwordx4 v128, s[4:7], s47 offen lds
	s_mov_b32 m0, s19
	s_nop 0
	buffer_load_dwordx4 v132, s[4:7], s47 offen lds
	s_barrier
	s_waitcnt lgkmcnt(6)
	v_mfma_f32_16x16x32_bf16 v[60:63], v[156:159], v[172:175], 0
	v_mfma_f32_16x16x32_bf16 v[60:63], v[160:163], v[176:179], v[60:63]
	v_mfma_f32_16x16x32_bf16 v[56:59], v[168:171], v[176:179], 0
	v_mfma_f32_16x16x32_bf16 v[56:59], v[164:167], v[172:175], v[56:59]
	s_waitcnt lgkmcnt(4)
	v_mfma_f32_16x16x32_bf16 v[48:51], v[164:167], v[180:183], 0
	v_mfma_f32_16x16x32_bf16 v[48:51], v[168:171], v[184:187], v[48:51]
	v_mfma_f32_16x16x32_bf16 v[52:55], v[160:163], v[184:187], 0
	v_mfma_f32_16x16x32_bf16 v[52:55], v[156:159], v[180:183], v[52:55]
	s_waitcnt lgkmcnt(2)
	v_mfma_f32_16x16x32_bf16 v[44:47], v[156:159], v[188:191], 0
	v_mfma_f32_16x16x32_bf16 v[44:47], v[160:163], v[192:195], v[44:47]
	v_mfma_f32_16x16x32_bf16 v[40:43], v[168:171], v[192:195], 0
	v_mfma_f32_16x16x32_bf16 v[40:43], v[164:167], v[188:191], v[40:43]
	s_waitcnt lgkmcnt(0)
	v_mfma_f32_16x16x32_bf16 v[32:35], v[164:167], v[196:199], 0
	v_mfma_f32_16x16x32_bf16 v[32:35], v[168:171], v[200:203], v[32:35]
	v_mfma_f32_16x16x32_bf16 v[36:39], v[160:163], v[200:203], 0
	v_mfma_f32_16x16x32_bf16 v[36:39], v[156:159], v[196:199], v[36:39]
	s_barrier
	s_add_i32 s47, s41, s17
	s_add_i32 s48, s47, 0x100
	s_mov_b32 m0, s20
	s_nop 0
	buffer_load_dwordx4 v130, s[8:11], s48 offen lds
	s_mov_b32 m0, s21
	s_nop 0
	buffer_load_dwordx4 v134, s[8:11], s48 offen lds
	s_waitcnt vmcnt(6)
	s_barrier
	v_mfma_f32_16x16x32_bf16 v[28:31], v[204:207], v[172:175], 0
	v_mfma_f32_16x16x32_bf16 v[28:31], v[208:211], v[176:179], v[28:31]
	v_mfma_f32_16x16x32_bf16 v[24:27], v[216:219], v[176:179], 0
	v_mfma_f32_16x16x32_bf16 v[24:27], v[212:215], v[172:175], v[24:27]
	v_mfma_f32_16x16x32_bf16 v[16:19], v[212:215], v[180:183], 0
	v_mfma_f32_16x16x32_bf16 v[16:19], v[216:219], v[184:187], v[16:19]
	v_mfma_f32_16x16x32_bf16 v[20:23], v[208:211], v[184:187], 0
	v_mfma_f32_16x16x32_bf16 v[20:23], v[204:207], v[180:183], v[20:23]
	v_mfma_f32_16x16x32_bf16 v[12:15], v[204:207], v[188:191], 0
	v_mfma_f32_16x16x32_bf16 v[12:15], v[208:211], v[192:195], v[12:15]
	v_mfma_f32_16x16x32_bf16 v[8:11], v[216:219], v[192:195], 0
	v_mfma_f32_16x16x32_bf16 v[8:11], v[212:215], v[188:191], v[8:11]
	v_mfma_f32_16x16x32_bf16 v[0:3], v[212:215], v[196:199], 0
	v_mfma_f32_16x16x32_bf16 v[0:3], v[216:219], v[200:203], v[0:3]
	v_mfma_f32_16x16x32_bf16 v[4:7], v[208:211], v[200:203], 0
	v_mfma_f32_16x16x32_bf16 v[4:7], v[204:207], v[196:199], v[4:7]
	s_barrier
	ds_read_b128 v[156:159], v143
	ds_read_b128 v[160:163], v144
	ds_read_b128 v[164:167], v145
	ds_read_b128 v[168:171], v146
	s_addk_i32 s44, 0x100
	s_mov_b32 m0, s22
	ds_read_b128 v[172:175], v131 offset:32768
	ds_read_b128 v[176:179], v131 offset:33792
	ds_read_b128 v[180:183], v138 offset:32768
	ds_read_b128 v[184:187], v138 offset:33792
	ds_read_b128 v[188:191], v137 offset:32768
	ds_read_b128 v[192:195], v137 offset:33792
	ds_read_b128 v[196:199], v135 offset:32768
	ds_read_b128 v[200:203], v135 offset:33792
	buffer_load_dwordx4 v128, s[4:7], s44 offen lds
	s_mov_b32 m0, s23
	s_nop 0
	buffer_load_dwordx4 v132, s[4:7], s44 offen lds
	s_waitcnt lgkmcnt(8)
	s_barrier
; #define STAGE(P, RS, SOFF, OFF, kt) do { const int _so = (SOFF) + (kt) * (BK * 2); \
;     _Pragma("unroll") for (int _i = 0; _i < 2; ++_i) { \
;       __builtin_amdgcn_raw_ptr_buffer_load_lds(RS, (__attribute__((address_space(3))) void*)((P) + wave * 1024 + _i * 8192), 16, OFF[_i], _so, 0, 0); } } while (0)
; #define LDA(dst, b, h) _Pragma("unroll") for (int m = 0; m < 4; ++m) _Pragma("unroll") for (int k = 0; k < 2; ++k) \
;     dst[m][k] = *reinterpret_cast<const bf16x8*>(SA(b, h) + lds_byte(wr * 64 + m * 16 + fr, k * 32 + fq * 8))
; #define LDB(dst, b, h) _Pragma("unroll") for (int n = 0; n < 2; ++n) _Pragma("unroll") for (int k = 0; k < 2; ++k) \
;     dst[n][k] = *reinterpret_cast<const bf16x8*>(SB(b, h) + lds_byte(wc * 32 + n * 16 + fr, k * 32 + fq * 8))
; #define WAIT_V(n) asm volatile("s_waitcnt vmcnt(" #n ")" ::: "memory")
; #define WAIT_L(n) asm volatile("s_waitcnt lgkmcnt(" #n ")" ::: "memory")
; #define BAR __builtin_amdgcn_s_barrier()
; #define SCHED __builtin_amdgcn_sched_barrier(0)
;     ...
;       WAIT_L(8); BAR; WAIT_L(0); MMA(0, 0, At, B0); BAR; SCHED;
;       LDB(B1, 1, 1); STAGE(SB(1, 0), rsB, sB0, offB, t + 3);
;       BAR; WAIT_L(0); MMA(0, 1, At, B1); BAR;
;       LDA(At, 1, 1); STAGE(SA(1, 0), rsA, sA0, offA, t + 3);
;       BAR; WAIT_L(0); MMA(1, 0, At, B0); BAR; SCHED;
;       STAGE(SB(1, 1), rsB, sB1, offB, t + 3);
;       WAIT_V(6); BAR; MMA(1, 1, At, B1); BAR;
	s_waitcnt lgkmcnt(6)
	v_mfma_f32_16x16x32_bf16 v[124:127], v[156:159], v[172:175], v[124:127]
	v_mfma_f32_16x16x32_bf16 v[124:127], v[160:163], v[176:179], v[124:127]
	v_mfma_f32_16x16x32_bf16 v[120:123], v[168:171], v[176:179], v[120:123]
	v_mfma_f32_16x16x32_bf16 v[120:123], v[164:167], v[172:175], v[120:123]
	s_waitcnt lgkmcnt(4)
	v_mfma_f32_16x16x32_bf16 v[112:115], v[164:167], v[180:183], v[112:115]
	v_mfma_f32_16x16x32_bf16 v[112:115], v[168:171], v[184:187], v[112:115]
	v_mfma_f32_16x16x32_bf16 v[116:119], v[160:163], v[184:187], v[116:119]
	v_mfma_f32_16x16x32_bf16 v[116:119], v[156:159], v[180:183], v[116:119]
	s_waitcnt lgkmcnt(2)
	v_mfma_f32_16x16x32_bf16 v[108:111], v[156:159], v[188:191], v[108:111]
	v_mfma_f32_16x16x32_bf16 v[108:111], v[160:163], v[192:195], v[108:111]
	v_mfma_f32_16x16x32_bf16 v[104:107], v[168:171], v[192:195], v[104:107]
	v_mfma_f32_16x16x32_bf16 v[104:107], v[164:167], v[188:191], v[104:107]
	s_waitcnt lgkmcnt(0)
	v_mfma_f32_16x16x32_bf16 v[96:99], v[164:167], v[196:199], v[96:99]
	v_mfma_f32_16x16x32_bf16 v[96:99], v[168:171], v[200:203], v[96:99]
	v_mfma_f32_16x16x32_bf16 v[100:103], v[160:163], v[200:203], v[100:103]
	v_mfma_f32_16x16x32_bf16 v[100:103], v[156:159], v[196:199], v[100:103]
	s_barrier
	s_addk_i32 s45, 0x180
	s_mov_b32 m0, s24
	ds_read_b128 v[204:207], v139
	ds_read_b128 v[208:211], v140
	ds_read_b128 v[212:215], v141
	ds_read_b128 v[216:219], v142
	buffer_load_dwordx4 v130, s[8:11], s45 offen lds
	s_mov_b32 m0, s25
	s_nop 0
	buffer_load_dwordx4 v134, s[8:11], s45 offen lds
	s_barrier
	s_waitcnt lgkmcnt(2)
	v_mfma_f32_16x16x32_bf16 v[92:95], v[204:207], v[172:175], v[92:95]
	v_mfma_f32_16x16x32_bf16 v[92:95], v[208:211], v[176:179], v[92:95]
	s_waitcnt lgkmcnt(0)
	v_mfma_f32_16x16x32_bf16 v[88:91], v[216:219], v[176:179], v[88:91]
	v_mfma_f32_16x16x32_bf16 v[88:91], v[212:215], v[172:175], v[88:91]
	v_mfma_f32_16x16x32_bf16 v[80:83], v[212:215], v[180:183], v[80:83]
	v_mfma_f32_16x16x32_bf16 v[80:83], v[216:219], v[184:187], v[80:83]
	v_mfma_f32_16x16x32_bf16 v[84:87], v[208:211], v[184:187], v[84:87]
	v_mfma_f32_16x16x32_bf16 v[84:87], v[204:207], v[180:183], v[84:87]
	v_mfma_f32_16x16x32_bf16 v[76:79], v[204:207], v[188:191], v[76:79]
	v_mfma_f32_16x16x32_bf16 v[76:79], v[208:211], v[192:195], v[76:79]
	v_mfma_f32_16x16x32_bf16 v[72:75], v[216:219], v[192:195], v[72:75]
	v_mfma_f32_16x16x32_bf16 v[72:75], v[212:215], v[188:191], v[72:75]
	v_mfma_f32_16x16x32_bf16 v[64:67], v[212:215], v[196:199], v[64:67]
	v_mfma_f32_16x16x32_bf16 v[64:67], v[216:219], v[200:203], v[64:67]
	v_mfma_f32_16x16x32_bf16 v[68:71], v[208:211], v[200:203], v[68:71]
	v_mfma_f32_16x16x32_bf16 v[68:71], v[204:207], v[196:199], v[68:71]
	s_barrier
	s_addk_i32 s46, 0x180
	s_mov_b32 m0, s26
	ds_read_b128 v[172:175], v131 offset:49152
	ds_read_b128 v[176:179], v131 offset:50176
	ds_read_b128 v[180:183], v138 offset:49152
	ds_read_b128 v[184:187], v138 offset:50176
	ds_read_b128 v[188:191], v137 offset:49152
	ds_read_b128 v[192:195], v137 offset:50176
	ds_read_b128 v[196:199], v135 offset:49152
	ds_read_b128 v[200:203], v135 offset:50176
	buffer_load_dwordx4 v128, s[4:7], s46 offen lds
	s_mov_b32 m0, s27
	s_nop 0
	buffer_load_dwordx4 v132, s[4:7], s46 offen lds
	s_barrier
	s_waitcnt lgkmcnt(6)
	v_mfma_f32_16x16x32_bf16 v[60:63], v[156:159], v[172:175], v[60:63]
	v_mfma_f32_16x16x32_bf16 v[60:63], v[160:163], v[176:179], v[60:63]
	v_mfma_f32_16x16x32_bf16 v[56:59], v[168:171], v[176:179], v[56:59]
	v_mfma_f32_16x16x32_bf16 v[56:59], v[164:167], v[172:175], v[56:59]
	s_waitcnt lgkmcnt(4)
	v_mfma_f32_16x16x32_bf16 v[48:51], v[164:167], v[180:183], v[48:51]
	v_mfma_f32_16x16x32_bf16 v[48:51], v[168:171], v[184:187], v[48:51]
	v_mfma_f32_16x16x32_bf16 v[52:55], v[160:163], v[184:187], v[52:55]
	v_mfma_f32_16x16x32_bf16 v[52:55], v[156:159], v[180:183], v[52:55]
	s_waitcnt lgkmcnt(2)
	v_mfma_f32_16x16x32_bf16 v[44:47], v[156:159], v[188:191], v[44:47]
	v_mfma_f32_16x16x32_bf16 v[44:47], v[160:163], v[192:195], v[44:47]
	v_mfma_f32_16x16x32_bf16 v[40:43], v[168:171], v[192:195], v[40:43]
	v_mfma_f32_16x16x32_bf16 v[40:43], v[164:167], v[188:191], v[40:43]
	s_waitcnt lgkmcnt(0)
	v_mfma_f32_16x16x32_bf16 v[32:35], v[164:167], v[196:199], v[32:35]
	v_mfma_f32_16x16x32_bf16 v[32:35], v[168:171], v[200:203], v[32:35]
	v_mfma_f32_16x16x32_bf16 v[36:39], v[160:163], v[200:203], v[36:39]
	v_mfma_f32_16x16x32_bf16 v[36:39], v[156:159], v[196:199], v[36:39]
	s_barrier
	s_addk_i32 s47, 0x180
	s_mov_b32 m0, s28
	s_nop 0
	buffer_load_dwordx4 v130, s[8:11], s47 offen lds
	s_mov_b32 m0, s29
	s_nop 0
	buffer_load_dwordx4 v134, s[8:11], s47 offen lds
	s_add_i32 s16, s16, 2
	s_addk_i32 s17, 0x100
	s_cmp_gt_u32 s16, 3
	s_cbranch_scc0 .LBB0_110
	s_branch .Lmy_post_110

; #define STAGE(P, RS, SOFF, OFF, kt) do { const int _so = (SOFF) + (kt) * (BK * 2); \
;     _Pragma("unroll") for (int _i = 0; _i < 2; ++_i) { \
;       __builtin_amdgcn_raw_ptr_buffer_load_lds(RS, (__attribute__((address_space(3))) void*)((P) + wave * 1024 + _i * 8192), 16, OFF[_i], _so, 0, 0); } } while (0)
; #define LDA(dst, b, h) _Pragma("unroll") for (int m = 0; m < 4; ++m) _Pragma("unroll") for (int k = 0; k < 2; ++k) \
;     dst[m][k] = *reinterpret_cast<const bf16x8*>(SA(b, h) + lds_byte(wr * 64 + m * 16 + fr, k * 32 + fq * 8))
; #define LDB(dst, b, h) _Pragma("unroll") for (int n = 0; n < 2; ++n) _Pragma("unroll") for (int k = 0; k < 2; ++k) \
;     dst[n][k] = *reinterpret_cast<const bf16x8*>(SB(b, h) + lds_byte(wc * 32 + n * 16 + fr, k * 32 + fq * 8))
; #define WAIT_V(n) asm volatile("s_waitcnt vmcnt(" #n ")" ::: "memory")
; #define WAIT_L(n) asm volatile("s_waitcnt lgkmcnt(" #n ")" ::: "memory")
; #define BAR __builtin_amdgcn_s_barrier()
; #define SCHED __builtin_amdgcn_sched_barrier(0)
;     ...
;       LDB(B0, 0, 0); SCHED; LDA(At, 0, 0); STAGE(SA(1, 1), rsA, sA1, offA, t + 1);
;       WAIT_L(8); BAR; WAIT_L(0); MMA(0, 0, At, B0); BAR; SCHED;
;       LDB(B1, 0, 1); STAGE(SB(0, 0), rsB, sB0, offB, t + 2);
;       BAR; WAIT_L(0); MMA(0, 1, At, B1); BAR;
;       LDA(At, 0, 1); STAGE(SA(0, 0), rsA, sA0, offA, t + 2);
;       BAR; WAIT_L(0); MMA(1, 0, At, B0); BAR; SCHED;
;       STAGE(SB(0, 1), rsB, sB1, offB, t + 2);
;       WAIT_V(6); BAR; MMA(1, 1, At, B1); BAR;
.Lmy_rot_110:
	ds_read_b128 v[156:159], v151
	ds_read_b128 v[160:163], v152
	ds_read_b128 v[164:167], v153
	ds_read_b128 v[168:171], v154
	s_add_i32 s44, s38, s17
	s_add_i32 s10, s44, 0x80
	s_mov_b32 m0, s31
	ds_read_b128 v[172:175], v131
	ds_read_b128 v[176:179], v131 offset:1024
	ds_read_b128 v[180:183], v138
	ds_read_b128 v[184:187], v138 offset:1024
	ds_read_b128 v[188:191], v137
	ds_read_b128 v[192:195], v137 offset:1024
	ds_read_b128 v[196:199], v135
	ds_read_b128 v[200:203], v135 offset:1024
	buffer_load_dwordx4 v128, s[4:7], s10 offen lds
	s_mov_b32 m0, s33
	s_nop 0
	buffer_load_dwordx4 v132, s[4:7], s10 offen lds
	s_waitcnt lgkmcnt(8)
	s_barrier
	s_waitcnt lgkmcnt(0)
	v_mfma_f32_16x16x32_bf16 v[124:127], v[156:159], v[172:175], v[124:127]
	v_mfma_f32_16x16x32_bf16 v[124:127], v[160:163], v[176:179], v[124:127]
	v_mfma_f32_16x16x32_bf16 v[120:123], v[168:171], v[176:179], v[120:123]
	v_mfma_f32_16x16x32_bf16 v[120:123], v[164:167], v[172:175], v[120:123]
	v_mfma_f32_16x16x32_bf16 v[112:115], v[164:167], v[180:183], v[112:115]
	v_mfma_f32_16x16x32_bf16 v[112:115], v[168:171], v[184:187], v[112:115]
	v_mfma_f32_16x16x32_bf16 v[116:119], v[160:163], v[184:187], v[116:119]
	v_mfma_f32_16x16x32_bf16 v[116:119], v[156:159], v[180:183], v[116:119]
	v_mfma_f32_16x16x32_bf16 v[108:111], v[156:159], v[188:191], v[108:111]
	v_mfma_f32_16x16x32_bf16 v[108:111], v[160:163], v[192:195], v[108:111]
	v_mfma_f32_16x16x32_bf16 v[104:107], v[168:171], v[192:195], v[104:107]
	v_mfma_f32_16x16x32_bf16 v[104:107], v[164:167], v[188:191], v[104:107]
	v_mfma_f32_16x16x32_bf16 v[96:99], v[164:167], v[196:199], v[96:99]
	v_mfma_f32_16x16x32_bf16 v[96:99], v[168:171], v[200:203], v[96:99]
	v_mfma_f32_16x16x32_bf16 v[100:103], v[160:163], v[200:203], v[100:103]
	v_mfma_f32_16x16x32_bf16 v[100:103], v[156:159], v[196:199], v[100:103]
	s_barrier
	s_add_i32 s45, s40, s17
	s_add_i32 s46, s45, 0x100
	s_mov_b32 s10, s6
	s_mov_b32 s11, s7
	s_mov_b32 m0, s3
	ds_read_b128 v[204:207], v147
	ds_read_b128 v[208:211], v148
	ds_read_b128 v[212:215], v149
	ds_read_b128 v[216:219], v150
	buffer_load_dwordx4 v130, s[8:11], s46 offen lds
	s_mov_b32 m0, s18
	s_nop 0
	buffer_load_dwordx4 v134, s[8:11], s46 offen lds
	s_barrier
	s_waitcnt lgkmcnt(2)
	v_mfma_f32_16x16x32_bf16 v[92:95], v[204:207], v[172:175], v[92:95]
	v_mfma_f32_16x16x32_bf16 v[92:95], v[208:211], v[176:179], v[92:95]
	s_waitcnt lgkmcnt(0)
	v_mfma_f32_16x16x32_bf16 v[88:91], v[216:219], v[176:179], v[88:91]
	v_mfma_f32_16x16x32_bf16 v[88:91], v[212:215], v[172:175], v[88:91]
	v_mfma_f32_16x16x32_bf16 v[80:83], v[212:215], v[180:183], v[80:83]
	v_mfma_f32_16x16x32_bf16 v[80:83], v[216:219], v[184:187], v[80:83]
	v_mfma_f32_16x16x32_bf16 v[84:87], v[208:211], v[184:187], v[84:87]
	v_mfma_f32_16x16x32_bf16 v[84:87], v[204:207], v[180:183], v[84:87]
	v_mfma_f32_16x16x32_bf16 v[76:79], v[204:207], v[188:191], v[76:79]
	v_mfma_f32_16x16x32_bf16 v[76:79], v[208:211], v[192:195], v[76:79]
	v_mfma_f32_16x16x32_bf16 v[72:75], v[216:219], v[192:195], v[72:75]
	v_mfma_f32_16x16x32_bf16 v[72:75], v[212:215], v[188:191], v[72:75]
	v_mfma_f32_16x16x32_bf16 v[64:67], v[212:215], v[196:199], v[64:67]
	v_mfma_f32_16x16x32_bf16 v[64:67], v[216:219], v[200:203], v[64:67]
	v_mfma_f32_16x16x32_bf16 v[68:71], v[208:211], v[200:203], v[68:71]
	v_mfma_f32_16x16x32_bf16 v[68:71], v[204:207], v[196:199], v[68:71]
	s_barrier
	s_add_i32 s46, s39, s17
	s_add_i32 s47, s46, 0x100
	s_mov_b32 m0, s0
	ds_read_b128 v[172:175], v131 offset:16384
	ds_read_b128 v[176:179], v131 offset:17408
	ds_read_b128 v[180:183], v138 offset:16384
	ds_read_b128 v[184:187], v138 offset:17408
	ds_read_b128 v[188:191], v137 offset:16384
	ds_read_b128 v[192:195], v137 offset:17408
	ds_read_b128 v[196:199], v135 offset:16384
	ds_read_b128 v[200:203], v135 offset:17408
	buffer_load_dwordx4 v128, s[4:7], s47 offen lds
	s_mov_b32 m0, s19
	s_nop 0
	buffer_load_dwordx4 v132, s[4:7], s47 offen lds
	s_barrier
	s_waitcnt lgkmcnt(6)
	v_mfma_f32_16x16x32_bf16 v[60:63], v[156:159], v[172:175], v[60:63]
	v_mfma_f32_16x16x32_bf16 v[60:63], v[160:163], v[176:179], v[60:63]
	v_mfma_f32_16x16x32_bf16 v[56:59], v[168:171], v[176:179], v[56:59]
	v_mfma_f32_16x16x32_bf16 v[56:59], v[164:167], v[172:175], v[56:59]
	s_waitcnt lgkmcnt(4)
	v_mfma_f32_16x16x32_bf16 v[48:51], v[164:167], v[180:183], v[48:51]
	v_mfma_f32_16x16x32_bf16 v[48:51], v[168:171], v[184:187], v[48:51]
	v_mfma_f32_16x16x32_bf16 v[52:55], v[160:163], v[184:187], v[52:55]
	v_mfma_f32_16x16x32_bf16 v[52:55], v[156:159], v[180:183], v[52:55]
	s_waitcnt lgkmcnt(2)
	v_mfma_f32_16x16x32_bf16 v[44:47], v[156:159], v[188:191], v[44:47]
	v_mfma_f32_16x16x32_bf16 v[44:47], v[160:163], v[192:195], v[44:47]
	v_mfma_f32_16x16x32_bf16 v[40:43], v[168:171], v[192:195], v[40:43]
	v_mfma_f32_16x16x32_bf16 v[40:43], v[164:167], v[188:191], v[40:43]
	s_waitcnt lgkmcnt(0)
	v_mfma_f32_16x16x32_bf16 v[32:35], v[164:167], v[196:199], v[32:35]
	v_mfma_f32_16x16x32_bf16 v[32:35], v[168:171], v[200:203], v[32:35]
	v_mfma_f32_16x16x32_bf16 v[36:39], v[160:163], v[200:203], v[36:39]
	v_mfma_f32_16x16x32_bf16 v[36:39], v[156:159], v[196:199], v[36:39]
	s_barrier
	s_add_i32 s47, s41, s17
	s_add_i32 s48, s47, 0x100
	s_mov_b32 m0, s20
	s_nop 0
	buffer_load_dwordx4 v130, s[8:11], s48 offen lds
	s_mov_b32 m0, s21
	s_nop 0
	buffer_load_dwordx4 v134, s[8:11], s48 offen lds
	s_waitcnt vmcnt(6)
	s_barrier
; #define STAGE(P, RS, SOFF, OFF, kt) do { const int _so = (SOFF) + (kt) * (BK * 2); \
;     _Pragma("unroll") for (int _i = 0; _i < 2; ++_i) { \
;       __builtin_amdgcn_raw_ptr_buffer_load_lds(RS, (__attribute__((address_space(3))) void*)((P) + wave * 1024 + _i * 8192), 16, OFF[_i], _so, 0, 0); } } while (0)
; #define LDA(dst, b, h) _Pragma("unroll") for (int m = 0; m < 4; ++m) _Pragma("unroll") for (int k = 0; k < 2; ++k) \
;     dst[m][k] = *reinterpret_cast<const bf16x8*>(SA(b, h) + lds_byte(wr * 64 + m * 16 + fr, k * 32 + fq * 8))
; #define LDB(dst, b, h) _Pragma("unroll") for (int n = 0; n < 2; ++n) _Pragma("unroll") for (int k = 0; k < 2; ++k) \
;     dst[n][k] = *reinterpret_cast<const bf16x8*>(SB(b, h) + lds_byte(wc * 32 + n * 16 + fr, k * 32 + fq * 8))
; #define WAIT_V(n) asm volatile("s_waitcnt vmcnt(" #n ")" ::: "memory")
; #define WAIT_L(n) asm volatile("s_waitcnt lgkmcnt(" #n ")" ::: "memory")
; #define BAR __builtin_amdgcn_s_barrier()
; #define SCHED __builtin_amdgcn_sched_barrier(0)
;     ...
;       WAIT_V(6); BAR; MMA(1, 1, At, B1); BAR;
;       LDB(B0, 1, 0); SCHED; LDA(At, 1, 0); STAGE(SA(0, 1), rsA, sA1, offA, t + 2);
;       WAIT_L(8); BAR; WAIT_L(0); MMA(0, 0, At, B0); BAR; SCHED;
;       LDB(B1, 1, 1); STAGE(SB(1, 0), rsB, sB0, offB, t + 3);
;       BAR; WAIT_L(0); MMA(0, 1, At, B1); BAR;
;       LDA(At, 1, 1); STAGE(SA(1, 0), rsA, sA0, offA, t + 3);
;       BAR; WAIT_L(0); MMA(1, 0, At, B0); BAR; SCHED;
;       STAGE(SB(1, 1), rsB, sB1, offB, t + 3);
;       WAIT_V(6); BAR; MMA(1, 1, At, B1); BAR;
	v_mfma_f32_16x16x32_bf16 v[28:31], v[204:207], v[172:175], v[28:31]
	v_mfma_f32_16x16x32_bf16 v[28:31], v[208:211], v[176:179], v[28:31]
	v_mfma_f32_16x16x32_bf16 v[24:27], v[216:219], v[176:179], v[24:27]
	v_mfma_f32_16x16x32_bf16 v[24:27], v[212:215], v[172:175], v[24:27]
	v_mfma_f32_16x16x32_bf16 v[16:19], v[212:215], v[180:183], v[16:19]
	v_mfma_f32_16x16x32_bf16 v[16:19], v[216:219], v[184:187], v[16:19]
	v_mfma_f32_16x16x32_bf16 v[20:23], v[208:211], v[184:187], v[20:23]
	v_mfma_f32_16x16x32_bf16 v[20:23], v[204:207], v[180:183], v[20:23]
	v_mfma_f32_16x16x32_bf16 v[12:15], v[204:207], v[188:191], v[12:15]
	v_mfma_f32_16x16x32_bf16 v[12:15], v[208:211], v[192:195], v[12:15]
	v_mfma_f32_16x16x32_bf16 v[8:11], v[216:219], v[192:195], v[8:11]
	v_mfma_f32_16x16x32_bf16 v[8:11], v[212:215], v[188:191], v[8:11]
	v_mfma_f32_16x16x32_bf16 v[0:3], v[212:215], v[196:199], v[0:3]
	v_mfma_f32_16x16x32_bf16 v[0:3], v[216:219], v[200:203], v[0:3]
	v_mfma_f32_16x16x32_bf16 v[4:7], v[208:211], v[200:203], v[4:7]
	v_mfma_f32_16x16x32_bf16 v[4:7], v[204:207], v[196:199], v[4:7]
	s_barrier
	ds_read_b128 v[156:159], v143
	ds_read_b128 v[160:163], v144
	ds_read_b128 v[164:167], v145
	ds_read_b128 v[168:171], v146
	s_addk_i32 s44, 0x100
	s_mov_b32 m0, s22
	ds_read_b128 v[172:175], v131 offset:32768
	ds_read_b128 v[176:179], v131 offset:33792
	ds_read_b128 v[180:183], v138 offset:32768
	ds_read_b128 v[184:187], v138 offset:33792
	ds_read_b128 v[188:191], v137 offset:32768
	ds_read_b128 v[192:195], v137 offset:33792
	ds_read_b128 v[196:199], v135 offset:32768
	ds_read_b128 v[200:203], v135 offset:33792
	buffer_load_dwordx4 v128, s[4:7], s44 offen lds
	s_mov_b32 m0, s23
	s_nop 0
	buffer_load_dwordx4 v132, s[4:7], s44 offen lds
	s_waitcnt lgkmcnt(8)
	s_barrier
	s_waitcnt lgkmcnt(6)
	v_mfma_f32_16x16x32_bf16 v[124:127], v[156:159], v[172:175], v[124:127]
	v_mfma_f32_16x16x32_bf16 v[124:127], v[160:163], v[176:179], v[124:127]
	v_mfma_f32_16x16x32_bf16 v[120:123], v[168:171], v[176:179], v[120:123]
	v_mfma_f32_16x16x32_bf16 v[120:123], v[164:167], v[172:175], v[120:123]
	s_waitcnt lgkmcnt(4)
	v_mfma_f32_16x16x32_bf16 v[112:115], v[164:167], v[180:183], v[112:115]
	v_mfma_f32_16x16x32_bf16 v[112:115], v[168:171], v[184:187], v[112:115]
	v_mfma_f32_16x16x32_bf16 v[116:119], v[160:163], v[184:187], v[116:119]
	v_mfma_f32_16x16x32_bf16 v[116:119], v[156:159], v[180:183], v[116:119]
	s_waitcnt lgkmcnt(2)
	v_mfma_f32_16x16x32_bf16 v[108:111], v[156:159], v[188:191], v[108:111]
	v_mfma_f32_16x16x32_bf16 v[108:111], v[160:163], v[192:195], v[108:111]
	v_mfma_f32_16x16x32_bf16 v[104:107], v[168:171], v[192:195], v[104:107]
	v_mfma_f32_16x16x32_bf16 v[104:107], v[164:167], v[188:191], v[104:107]
	s_waitcnt lgkmcnt(0)
	v_mfma_f32_16x16x32_bf16 v[96:99], v[164:167], v[196:199], v[96:99]
	v_mfma_f32_16x16x32_bf16 v[96:99], v[168:171], v[200:203], v[96:99]
	v_mfma_f32_16x16x32_bf16 v[100:103], v[160:163], v[200:203], v[100:103]
	v_mfma_f32_16x16x32_bf16 v[100:103], v[156:159], v[196:199], v[100:103]
	s_barrier
	s_addk_i32 s45, 0x180
	s_mov_b32 m0, s24
	ds_read_b128 v[204:207], v139
	ds_read_b128 v[208:211], v140
	ds_read_b128 v[212:215], v141
	ds_read_b128 v[216:219], v142
	buffer_load_dwordx4 v130, s[8:11], s45 offen lds
	s_mov_b32 m0, s25
	s_nop 0
	buffer_load_dwordx4 v134, s[8:11], s45 offen lds
	s_barrier
	s_waitcnt lgkmcnt(2)
	v_mfma_f32_16x16x32_bf16 v[92:95], v[204:207], v[172:175], v[92:95]
	v_mfma_f32_16x16x32_bf16 v[92:95], v[208:211], v[176:179], v[92:95]
	s_waitcnt lgkmcnt(0)
	v_mfma_f32_16x16x32_bf16 v[88:91], v[216:219], v[176:179], v[88:91]
	v_mfma_f32_16x16x32_bf16 v[88:91], v[212:215], v[172:175], v[88:91]
	v_mfma_f32_16x16x32_bf16 v[80:83], v[212:215], v[180:183], v[80:83]
	v_mfma_f32_16x16x32_bf16 v[80:83], v[216:219], v[184:187], v[80:83]
	v_mfma_f32_16x16x32_bf16 v[84:87], v[208:211], v[184:187], v[84:87]
	v_mfma_f32_16x16x32_bf16 v[84:87], v[204:207], v[180:183], v[84:87]
	v_mfma_f32_16x16x32_bf16 v[76:79], v[204:207], v[188:191], v[76:79]
	v_mfma_f32_16x16x32_bf16 v[76:79], v[208:211], v[192:195], v[76:79]
	v_mfma_f32_16x16x32_bf16 v[72:75], v[216:219], v[192:195], v[72:75]
	v_mfma_f32_16x16x32_bf16 v[72:75], v[212:215], v[188:191], v[72:75]
	v_mfma_f32_16x16x32_bf16 v[64:67], v[212:215], v[196:199], v[64:67]
	v_mfma_f32_16x16x32_bf16 v[64:67], v[216:219], v[200:203], v[64:67]
	v_mfma_f32_16x16x32_bf16 v[68:71], v[208:211], v[200:203], v[68:71]
	v_mfma_f32_16x16x32_bf16 v[68:71], v[204:207], v[196:199], v[68:71]
	s_barrier
	s_addk_i32 s46, 0x180
	s_mov_b32 m0, s26
	ds_read_b128 v[172:175], v131 offset:49152
	ds_read_b128 v[176:179], v131 offset:50176
	ds_read_b128 v[180:183], v138 offset:49152
	ds_read_b128 v[184:187], v138 offset:50176
	ds_read_b128 v[188:191], v137 offset:49152
	ds_read_b128 v[192:195], v137 offset:50176
	ds_read_b128 v[196:199], v135 offset:49152
	ds_read_b128 v[200:203], v135 offset:50176
	buffer_load_dwordx4 v128, s[4:7], s46 offen lds
	s_mov_b32 m0, s27
	s_nop 0
	buffer_load_dwordx4 v132, s[4:7], s46 offen lds
	s_barrier
	s_waitcnt lgkmcnt(6)
	v_mfma_f32_16x16x32_bf16 v[60:63], v[156:159], v[172:175], v[60:63]
	v_mfma_f32_16x16x32_bf16 v[60:63], v[160:163], v[176:179], v[60:63]
	v_mfma_f32_16x16x32_bf16 v[56:59], v[168:171], v[176:179], v[56:59]
	v_mfma_f32_16x16x32_bf16 v[56:59], v[164:167], v[172:175], v[56:59]
	s_waitcnt lgkmcnt(4)
	v_mfma_f32_16x16x32_bf16 v[48:51], v[164:167], v[180:183], v[48:51]
	v_mfma_f32_16x16x32_bf16 v[48:51], v[168:171], v[184:187], v[48:51]
	v_mfma_f32_16x16x32_bf16 v[52:55], v[160:163], v[184:187], v[52:55]
	v_mfma_f32_16x16x32_bf16 v[52:55], v[156:159], v[180:183], v[52:55]
	s_waitcnt lgkmcnt(2)
	v_mfma_f32_16x16x32_bf16 v[44:47], v[156:159], v[188:191], v[44:47]
	v_mfma_f32_16x16x32_bf16 v[44:47], v[160:163], v[192:195], v[44:47]
	v_mfma_f32_16x16x32_bf16 v[40:43], v[168:171], v[192:195], v[40:43]
	v_mfma_f32_16x16x32_bf16 v[40:43], v[164:167], v[188:191], v[40:43]
	s_waitcnt lgkmcnt(0)
	v_mfma_f32_16x16x32_bf16 v[32:35], v[164:167], v[196:199], v[32:35]
	v_mfma_f32_16x16x32_bf16 v[32:35], v[168:171], v[200:203], v[32:35]
	v_mfma_f32_16x16x32_bf16 v[36:39], v[160:163], v[200:203], v[36:39]
	v_mfma_f32_16x16x32_bf16 v[36:39], v[156:159], v[196:199], v[36:39]
	s_barrier
	s_addk_i32 s47, 0x180
	s_mov_b32 m0, s28
	s_nop 0
	buffer_load_dwordx4 v130, s[8:11], s47 offen lds
	s_mov_b32 m0, s29
	s_nop 0
	buffer_load_dwordx4 v134, s[8:11], s47 offen lds
	s_add_i32 s16, s16, 2
	s_addk_i32 s17, 0x100
	s_cmp_gt_u32 s16, 3
	s_cbranch_scc0 .LBB0_110
; #define STAGE(P, RS, SOFF, OFF, kt) do { const int _so = (SOFF) + (kt) * (BK * 2); \
;     _Pragma("unroll") for (int _i = 0; _i < 2; ++_i) { \
;       __builtin_amdgcn_raw_ptr_buffer_load_lds(RS, (__attribute__((address_space(3))) void*)((P) + wave * 1024 + _i * 8192), 16, OFF[_i], _so, 0, 0); } } while (0)
; #define LDA(dst, b, h) _Pragma("unroll") for (int m = 0; m < 4; ++m) _Pragma("unroll") for (int k = 0; k < 2; ++k) \
;     dst[m][k] = *reinterpret_cast<const bf16x8*>(SA(b, h) + lds_byte(wr * 64 + m * 16 + fr, k * 32 + fq * 8))
; #define LDB(dst, b, h) _Pragma("unroll") for (int n = 0; n < 2; ++n) _Pragma("unroll") for (int k = 0; k < 2; ++k) \
;     dst[n][k] = *reinterpret_cast<const bf16x8*>(SB(b, h) + lds_byte(wc * 32 + n * 16 + fr, k * 32 + fq * 8))
; #define WAIT_V(n) asm volatile("s_waitcnt vmcnt(" #n ")" ::: "memory")
; #define WAIT_L(n) asm volatile("s_waitcnt lgkmcnt(" #n ")" ::: "memory")
; #define BAR __builtin_amdgcn_s_barrier()
;     ...
;       WAIT_V(6); BAR; MMA(1, 1, At, B1); BAR;
;     }
;     { LDB(B0, 0, 0); LDA(At, 0, 0); STAGE(SA(1, 1), rsA, sA1, offA, nt - 1);
;       BAR; WAIT_L(0); MMA(0, 0, At, B0); BAR;
;       LDB(B1, 0, 1); BAR; WAIT_L(0); MMA(0, 1, At, B1); BAR;
;       LDA(At, 0, 1); WAIT_V(4); BAR; WAIT_L(0); MMA(1, 0, At, B0); MMA(1, 1, At, B1); BAR; }
.Lmy_post_110:
	s_waitcnt vmcnt(6)
	s_barrier
	v_mfma_f32_16x16x32_bf16 v[28:31], v[204:207], v[172:175], v[28:31]
	v_mfma_f32_16x16x32_bf16 v[28:31], v[208:211], v[176:179], v[28:31]
	v_mfma_f32_16x16x32_bf16 v[24:27], v[216:219], v[176:179], v[24:27]
	v_mfma_f32_16x16x32_bf16 v[24:27], v[212:215], v[172:175], v[24:27]
	v_mfma_f32_16x16x32_bf16 v[16:19], v[212:215], v[180:183], v[16:19]
	v_mfma_f32_16x16x32_bf16 v[16:19], v[216:219], v[184:187], v[16:19]
	v_mfma_f32_16x16x32_bf16 v[20:23], v[208:211], v[184:187], v[20:23]
	v_mfma_f32_16x16x32_bf16 v[20:23], v[204:207], v[180:183], v[20:23]
	v_mfma_f32_16x16x32_bf16 v[12:15], v[204:207], v[188:191], v[12:15]
	v_mfma_f32_16x16x32_bf16 v[12:15], v[208:211], v[192:195], v[12:15]
	v_mfma_f32_16x16x32_bf16 v[8:11], v[216:219], v[192:195], v[8:11]
	v_mfma_f32_16x16x32_bf16 v[8:11], v[212:215], v[188:191], v[8:11]
	v_mfma_f32_16x16x32_bf16 v[0:3], v[212:215], v[196:199], v[0:3]
	v_mfma_f32_16x16x32_bf16 v[0:3], v[216:219], v[200:203], v[0:3]
	v_mfma_f32_16x16x32_bf16 v[4:7], v[208:211], v[200:203], v[4:7]
	v_mfma_f32_16x16x32_bf16 v[4:7], v[204:207], v[196:199], v[4:7]
	s_barrier
	s_add_i32 s10, s38, 0x380
	s_mov_b32 m0, s31
	ds_read_b128 v[156:159], v151
	ds_read_b128 v[160:163], v152
	ds_read_b128 v[164:167], v153
	ds_read_b128 v[152:155], v154
	ds_read_b128 v[168:171], v131
	ds_read_b128 v[172:175], v131 offset:1024
	ds_read_b128 v[176:179], v138
	ds_read_b128 v[180:183], v138 offset:1024
	ds_read_b128 v[184:187], v137
	ds_read_b128 v[188:191], v137 offset:1024
	ds_read_b128 v[192:195], v135
	ds_read_b128 v[196:199], v135 offset:1024
	buffer_load_dwordx4 v128, s[4:7], s10 offen lds
	s_mov_b32 m0, s33
	s_nop 0
	buffer_load_dwordx4 v132, s[4:7], s10 offen lds
	s_barrier
	s_waitcnt lgkmcnt(6)
	v_mfma_f32_16x16x32_bf16 v[124:127], v[156:159], v[168:171], v[124:127]
	v_mfma_f32_16x16x32_bf16 v[124:127], v[160:163], v[172:175], v[124:127]
	v_mfma_f32_16x16x32_bf16 v[120:123], v[152:155], v[172:175], v[120:123]
	v_mfma_f32_16x16x32_bf16 v[120:123], v[164:167], v[168:171], v[120:123]
	s_waitcnt lgkmcnt(4)
	v_mfma_f32_16x16x32_bf16 v[112:115], v[164:167], v[176:179], v[112:115]
	v_mfma_f32_16x16x32_bf16 v[112:115], v[152:155], v[180:183], v[112:115]
	v_mfma_f32_16x16x32_bf16 v[116:119], v[160:163], v[180:183], v[116:119]
	v_mfma_f32_16x16x32_bf16 v[116:119], v[156:159], v[176:179], v[116:119]
	s_waitcnt lgkmcnt(2)
	v_mfma_f32_16x16x32_bf16 v[108:111], v[156:159], v[184:187], v[108:111]
	v_mfma_f32_16x16x32_bf16 v[108:111], v[160:163], v[188:191], v[108:111]
	v_mfma_f32_16x16x32_bf16 v[104:107], v[152:155], v[188:191], v[104:107]
	v_mfma_f32_16x16x32_bf16 v[104:107], v[164:167], v[184:187], v[104:107]
	s_waitcnt lgkmcnt(0)
	v_mfma_f32_16x16x32_bf16 v[96:99], v[164:167], v[192:195], v[96:99]
	v_mfma_f32_16x16x32_bf16 v[96:99], v[152:155], v[196:199], v[96:99]
	v_mfma_f32_16x16x32_bf16 v[100:103], v[160:163], v[196:199], v[100:103]
	v_mfma_f32_16x16x32_bf16 v[100:103], v[156:159], v[192:195], v[100:103]
	s_barrier
	ds_read_b128 v[200:203], v147
	ds_read_b128 v[204:207], v148
	ds_read_b128 v[208:211], v149
	ds_read_b128 v[148:151], v150
	s_barrier
	s_waitcnt lgkmcnt(2)
	v_mfma_f32_16x16x32_bf16 v[92:95], v[200:203], v[168:171], v[92:95]
	v_mfma_f32_16x16x32_bf16 v[92:95], v[204:207], v[172:175], v[92:95]
	s_waitcnt lgkmcnt(0)
	v_mfma_f32_16x16x32_bf16 v[88:91], v[148:151], v[172:175], v[88:91]
	v_mfma_f32_16x16x32_bf16 v[88:91], v[208:211], v[168:171], v[88:91]
	v_mfma_f32_16x16x32_bf16 v[80:83], v[208:211], v[176:179], v[80:83]
	v_mfma_f32_16x16x32_bf16 v[80:83], v[148:151], v[180:183], v[80:83]
	v_mfma_f32_16x16x32_bf16 v[84:87], v[204:207], v[180:183], v[84:87]
	v_mfma_f32_16x16x32_bf16 v[84:87], v[200:203], v[176:179], v[84:87]
	v_mfma_f32_16x16x32_bf16 v[76:79], v[200:203], v[184:187], v[76:79]
	v_mfma_f32_16x16x32_bf16 v[76:79], v[204:207], v[188:191], v[76:79]
	v_mfma_f32_16x16x32_bf16 v[72:75], v[148:151], v[188:191], v[72:75]
	v_mfma_f32_16x16x32_bf16 v[72:75], v[208:211], v[184:187], v[72:75]
	v_mfma_f32_16x16x32_bf16 v[64:67], v[208:211], v[192:195], v[64:67]
	v_mfma_f32_16x16x32_bf16 v[64:67], v[148:151], v[196:199], v[64:67]
	v_mfma_f32_16x16x32_bf16 v[68:71], v[204:207], v[196:199], v[68:71]
	v_mfma_f32_16x16x32_bf16 v[68:71], v[200:203], v[192:195], v[68:71]
	s_barrier
	ds_read_b128 v[168:171], v131 offset:16384
	ds_read_b128 v[172:175], v131 offset:17408
	ds_read_b128 v[176:179], v138 offset:16384
	ds_read_b128 v[180:183], v138 offset:17408
	ds_read_b128 v[184:187], v137 offset:16384
	ds_read_b128 v[188:191], v137 offset:17408
	ds_read_b128 v[192:195], v135 offset:16384
	ds_read_b128 v[196:199], v135 offset:17408
	s_waitcnt vmcnt(4)
	s_barrier
; #define LDA(dst, b, h) _Pragma("unroll") for (int m = 0; m < 4; ++m) _Pragma("unroll") for (int k = 0; k < 2; ++k) \
;     dst[m][k] = *reinterpret_cast<const bf16x8*>(SA(b, h) + lds_byte(wr * 64 + m * 16 + fr, k * 32 + fq * 8))
; #define LDB(dst, b, h) _Pragma("unroll") for (int n = 0; n < 2; ++n) _Pragma("unroll") for (int k = 0; k < 2; ++k) \
;     dst[n][k] = *reinterpret_cast<const bf16x8*>(SB(b, h) + lds_byte(wc * 32 + n * 16 + fr, k * 32 + fq * 8))
; #define WAIT_V(n) asm volatile("s_waitcnt vmcnt(" #n ")" ::: "memory")
; #define WAIT_L(n) asm volatile("s_waitcnt lgkmcnt(" #n ")" ::: "memory")
; #define BAR __builtin_amdgcn_s_barrier()
;     ...
;       LDA(At, 0, 1); WAIT_V(4); BAR; WAIT_L(0); MMA(1, 0, At, B0); MMA(1, 1, At, B1); BAR; }
;     { LDB(B0, 1, 0); LDA(At, 1, 0); WAIT_V(2); BAR; WAIT_L(0); MMA(0, 0, At, B0); BAR;
	s_waitcnt lgkmcnt(0)
	v_mfma_f32_16x16x32_bf16 v[60:63], v[156:159], v[168:171], v[60:63]
	v_mfma_f32_16x16x32_bf16 v[60:63], v[160:163], v[172:175], v[60:63]
	v_mfma_f32_16x16x32_bf16 v[56:59], v[152:155], v[172:175], v[56:59]
	v_mfma_f32_16x16x32_bf16 v[56:59], v[164:167], v[168:171], v[56:59]
	v_mfma_f32_16x16x32_bf16 v[48:51], v[164:167], v[176:179], v[48:51]
	v_mfma_f32_16x16x32_bf16 v[48:51], v[152:155], v[180:183], v[48:51]
	v_mfma_f32_16x16x32_bf16 v[52:55], v[160:163], v[180:183], v[52:55]
	v_mfma_f32_16x16x32_bf16 v[52:55], v[156:159], v[176:179], v[52:55]
	v_mfma_f32_16x16x32_bf16 v[44:47], v[156:159], v[184:187], v[44:47]
	v_mfma_f32_16x16x32_bf16 v[44:47], v[160:163], v[188:191], v[44:47]
	v_mfma_f32_16x16x32_bf16 v[40:43], v[152:155], v[188:191], v[40:43]
	v_mfma_f32_16x16x32_bf16 v[40:43], v[164:167], v[184:187], v[40:43]
	v_mfma_f32_16x16x32_bf16 v[32:35], v[164:167], v[192:195], v[32:35]
	v_mfma_f32_16x16x32_bf16 v[32:35], v[152:155], v[196:199], v[32:35]
	v_mfma_f32_16x16x32_bf16 v[36:39], v[160:163], v[196:199], v[36:39]
	v_mfma_f32_16x16x32_bf16 v[36:39], v[156:159], v[192:195], v[36:39]
	v_mfma_f32_16x16x32_bf16 v[4:7], v[200:203], v[192:195], v[4:7]
	v_mfma_f32_16x16x32_bf16 v[4:7], v[204:207], v[196:199], v[4:7]
	v_mfma_f32_16x16x32_bf16 v[28:31], v[204:207], v[172:175], v[28:31]
	v_mfma_f32_16x16x32_bf16 v[28:31], v[200:203], v[168:171], v[28:31]
	v_mfma_f32_16x16x32_bf16 v[24:27], v[208:211], v[168:171], v[24:27]
	v_mfma_f32_16x16x32_bf16 v[24:27], v[148:151], v[172:175], v[24:27]
	v_mfma_f32_16x16x32_bf16 v[16:19], v[148:151], v[180:183], v[16:19]
	v_mfma_f32_16x16x32_bf16 v[16:19], v[208:211], v[176:179], v[16:19]
	v_mfma_f32_16x16x32_bf16 v[20:23], v[200:203], v[176:179], v[20:23]
	v_mfma_f32_16x16x32_bf16 v[20:23], v[204:207], v[180:183], v[20:23]
	v_mfma_f32_16x16x32_bf16 v[12:15], v[204:207], v[188:191], v[12:15]
	v_mfma_f32_16x16x32_bf16 v[12:15], v[200:203], v[184:187], v[12:15]
	v_mfma_f32_16x16x32_bf16 v[8:11], v[208:211], v[184:187], v[8:11]
	v_mfma_f32_16x16x32_bf16 v[8:11], v[148:151], v[188:191], v[8:11]
	v_mfma_f32_16x16x32_bf16 v[0:3], v[148:151], v[196:199], v[0:3]
	v_mfma_f32_16x16x32_bf16 v[0:3], v[208:211], v[192:195], v[0:3]
	s_barrier
	ds_read_b128 v[148:151], v143
	ds_read_b128 v[152:155], v144
	ds_read_b128 v[156:159], v145
	ds_read_b128 v[144:147], v146
	ds_read_b128 v[160:163], v131 offset:32768
	ds_read_b128 v[164:167], v131 offset:33792
	ds_read_b128 v[168:171], v138 offset:32768
	ds_read_b128 v[172:175], v138 offset:33792
	ds_read_b128 v[176:179], v137 offset:32768
	ds_read_b128 v[180:183], v137 offset:33792
	ds_read_b128 v[184:187], v135 offset:32768
	ds_read_b128 v[188:191], v135 offset:33792
	s_waitcnt vmcnt(2)
	s_barrier
	s_waitcnt lgkmcnt(6)
	v_mfma_f32_16x16x32_bf16 v[124:127], v[148:151], v[160:163], v[124:127]
	v_mfma_f32_16x16x32_bf16 v[124:127], v[152:155], v[164:167], v[124:127]
	v_mfma_f32_16x16x32_bf16 v[120:123], v[144:147], v[164:167], v[120:123]
	v_mfma_f32_16x16x32_bf16 v[120:123], v[156:159], v[160:163], v[120:123]
	s_waitcnt lgkmcnt(4)
	v_mfma_f32_16x16x32_bf16 v[112:115], v[156:159], v[168:171], v[112:115]
	v_mfma_f32_16x16x32_bf16 v[112:115], v[144:147], v[172:175], v[112:115]
	v_mfma_f32_16x16x32_bf16 v[116:119], v[152:155], v[172:175], v[116:119]
	v_mfma_f32_16x16x32_bf16 v[116:119], v[148:151], v[168:171], v[116:119]
	s_waitcnt lgkmcnt(2)
	v_mfma_f32_16x16x32_bf16 v[108:111], v[148:151], v[176:179], v[108:111]
	v_mfma_f32_16x16x32_bf16 v[108:111], v[152:155], v[180:183], v[108:111]
	v_mfma_f32_16x16x32_bf16 v[104:107], v[144:147], v[180:183], v[104:107]
	v_mfma_f32_16x16x32_bf16 v[104:107], v[156:159], v[176:179], v[104:107]
	s_waitcnt lgkmcnt(0)
	v_mfma_f32_16x16x32_bf16 v[96:99], v[156:159], v[184:187], v[96:99]
	v_mfma_f32_16x16x32_bf16 v[96:99], v[144:147], v[188:191], v[96:99]
	v_mfma_f32_16x16x32_bf16 v[100:103], v[152:155], v[188:191], v[100:103]
	v_mfma_f32_16x16x32_bf16 v[100:103], v[148:151], v[184:187], v[100:103]
	s_barrier
; #define LDA(dst, b, h) _Pragma("unroll") for (int m = 0; m < 4; ++m) _Pragma("unroll") for (int k = 0; k < 2; ++k) \
;     dst[m][k] = *reinterpret_cast<const bf16x8*>(SA(b, h) + lds_byte(wr * 64 + m * 16 + fr, k * 32 + fq * 8))
; #define LDB(dst, b, h) _Pragma("unroll") for (int n = 0; n < 2; ++n) _Pragma("unroll") for (int k = 0; k < 2; ++k) \
;     dst[n][k] = *reinterpret_cast<const bf16x8*>(SB(b, h) + lds_byte(wc * 32 + n * 16 + fr, k * 32 + fq * 8))
; #define WAIT_V(n) asm volatile("s_waitcnt vmcnt(" #n ")" ::: "memory")
; #define WAIT_L(n) asm volatile("s_waitcnt lgkmcnt(" #n ")" ::: "memory")
; #define BAR __builtin_amdgcn_s_barrier()
;     ...
;       LDB(B1, 1, 1); WAIT_V(0); BAR; WAIT_L(0); MMA(0, 1, At, B1); BAR;
;       LDA(At, 1, 1); BAR; WAIT_L(0); MMA(1, 0, At, B0); MMA(1, 1, At, B1); BAR; }
;     if (wr == 0) BAR;
	ds_read_b128 v[192:195], v139
	ds_read_b128 v[196:199], v140
	ds_read_b128 v[200:203], v141
	ds_read_b128 v[140:143], v142
	s_waitcnt vmcnt(0)
	s_barrier
	s_waitcnt lgkmcnt(2)
	v_mfma_f32_16x16x32_bf16 v[92:95], v[192:195], v[160:163], v[92:95]
	v_mfma_f32_16x16x32_bf16 v[92:95], v[196:199], v[164:167], v[92:95]
	s_waitcnt lgkmcnt(0)
	v_mfma_f32_16x16x32_bf16 v[88:91], v[140:143], v[164:167], v[88:91]
	v_mfma_f32_16x16x32_bf16 v[88:91], v[200:203], v[160:163], v[88:91]
	v_mfma_f32_16x16x32_bf16 v[80:83], v[200:203], v[168:171], v[80:83]
	v_mfma_f32_16x16x32_bf16 v[80:83], v[140:143], v[172:175], v[80:83]
	v_mfma_f32_16x16x32_bf16 v[84:87], v[196:199], v[172:175], v[84:87]
	v_mfma_f32_16x16x32_bf16 v[84:87], v[192:195], v[168:171], v[84:87]
	v_mfma_f32_16x16x32_bf16 v[76:79], v[192:195], v[176:179], v[76:79]
	v_mfma_f32_16x16x32_bf16 v[76:79], v[196:199], v[180:183], v[76:79]
	v_mfma_f32_16x16x32_bf16 v[72:75], v[140:143], v[180:183], v[72:75]
	v_mfma_f32_16x16x32_bf16 v[72:75], v[200:203], v[176:179], v[72:75]
	v_mfma_f32_16x16x32_bf16 v[64:67], v[200:203], v[184:187], v[64:67]
	v_mfma_f32_16x16x32_bf16 v[64:67], v[140:143], v[188:191], v[64:67]
	v_mfma_f32_16x16x32_bf16 v[68:71], v[196:199], v[188:191], v[68:71]
	v_mfma_f32_16x16x32_bf16 v[68:71], v[192:195], v[184:187], v[68:71]
	s_barrier
	ds_read_b128 v[160:163], v131 offset:49152
	ds_read_b128 v[164:167], v131 offset:50176
	ds_read_b128 v[168:171], v138 offset:49152
	ds_read_b128 v[172:175], v138 offset:50176
	ds_read_b128 v[176:179], v137 offset:49152
	ds_read_b128 v[180:183], v137 offset:50176
	ds_read_b128 v[184:187], v135 offset:49152
	ds_read_b128 v[188:191], v135 offset:50176
	s_barrier
	s_waitcnt lgkmcnt(0)
	v_mfma_f32_16x16x32_bf16 v[60:63], v[148:151], v[160:163], v[60:63]
	v_mfma_f32_16x16x32_bf16 v[60:63], v[152:155], v[164:167], v[60:63]
	v_mfma_f32_16x16x32_bf16 v[56:59], v[144:147], v[164:167], v[56:59]
	v_mfma_f32_16x16x32_bf16 v[56:59], v[156:159], v[160:163], v[56:59]
	v_mfma_f32_16x16x32_bf16 v[48:51], v[156:159], v[168:171], v[48:51]
	v_mfma_f32_16x16x32_bf16 v[48:51], v[144:147], v[172:175], v[48:51]
	v_mfma_f32_16x16x32_bf16 v[52:55], v[152:155], v[172:175], v[52:55]
	v_mfma_f32_16x16x32_bf16 v[52:55], v[148:151], v[168:171], v[52:55]
	v_mfma_f32_16x16x32_bf16 v[44:47], v[148:151], v[176:179], v[44:47]
	v_mfma_f32_16x16x32_bf16 v[44:47], v[152:155], v[180:183], v[44:47]
	v_mfma_f32_16x16x32_bf16 v[40:43], v[144:147], v[180:183], v[40:43]
	v_mfma_f32_16x16x32_bf16 v[40:43], v[156:159], v[176:179], v[40:43]
	v_mfma_f32_16x16x32_bf16 v[32:35], v[156:159], v[184:187], v[32:35]
	v_mfma_f32_16x16x32_bf16 v[32:35], v[144:147], v[188:191], v[32:35]
	v_mfma_f32_16x16x32_bf16 v[36:39], v[152:155], v[188:191], v[36:39]
	v_mfma_f32_16x16x32_bf16 v[36:39], v[148:151], v[184:187], v[36:39]
	v_mfma_f32_16x16x32_bf16 v[4:7], v[192:195], v[184:187], v[4:7]
	v_mfma_f32_16x16x32_bf16 v[4:7], v[196:199], v[188:191], v[4:7]
	v_mfma_f32_16x16x32_bf16 v[28:31], v[196:199], v[164:167], v[28:31]
	v_mfma_f32_16x16x32_bf16 v[28:31], v[192:195], v[160:163], v[28:31]
	v_mfma_f32_16x16x32_bf16 v[24:27], v[200:203], v[160:163], v[24:27]
	v_mfma_f32_16x16x32_bf16 v[24:27], v[140:143], v[164:167], v[24:27]
	v_mfma_f32_16x16x32_bf16 v[16:19], v[140:143], v[172:175], v[16:19]
	v_mfma_f32_16x16x32_bf16 v[16:19], v[200:203], v[168:171], v[16:19]
	v_mfma_f32_16x16x32_bf16 v[20:23], v[192:195], v[168:171], v[20:23]
	v_mfma_f32_16x16x32_bf16 v[20:23], v[196:199], v[172:175], v[20:23]
	v_mfma_f32_16x16x32_bf16 v[12:15], v[196:199], v[180:183], v[12:15]
	v_mfma_f32_16x16x32_bf16 v[12:15], v[192:195], v[176:179], v[12:15]
	v_mfma_f32_16x16x32_bf16 v[8:11], v[200:203], v[176:179], v[8:11]
	v_mfma_f32_16x16x32_bf16 v[8:11], v[140:143], v[180:183], v[8:11]
	v_mfma_f32_16x16x32_bf16 v[0:3], v[140:143], v[188:191], v[0:3]
	v_mfma_f32_16x16x32_bf16 v[0:3], v[200:203], v[184:187], v[0:3]
	v_cmp_gt_u32_e32 vcc, s36, v136
	s_barrier
	s_and_saveexec_b64 s[10:11], vcc
	s_cbranch_execz .LBB0_113
	s_barrier

; #define STAGE(P, RS, SOFF, OFF, kt) do { const int _so = (SOFF) + (kt) * (BK * 2); \
;     _Pragma("unroll") for (int _i = 0; _i < 2; ++_i) { \
;       __builtin_amdgcn_raw_ptr_buffer_load_lds(RS, (__attribute__((address_space(3))) void*)((P) + wave * 1024 + _i * 8192), 16, OFF[_i], _so, 0, 0); } } while (0)
; #define LDA(dst, b, h) _Pragma("unroll") for (int m = 0; m < 4; ++m) _Pragma("unroll") for (int k = 0; k < 2; ++k) \
;     dst[m][k] = *reinterpret_cast<const bf16x8*>(SA(b, h) + lds_byte(wr * 64 + m * 16 + fr, k * 32 + fq * 8))
; #define LDB(dst, b, h) _Pragma("unroll") for (int n = 0; n < 2; ++n) _Pragma("unroll") for (int k = 0; k < 2; ++k) \
;     dst[n][k] = *reinterpret_cast<const bf16x8*>(SB(b, h) + lds_byte(wc * 32 + n * 16 + fr, k * 32 + fq * 8))
; #define WAIT_V(n) asm volatile("s_waitcnt vmcnt(" #n ")" ::: "memory")
; #define WAIT_L(n) asm volatile("s_waitcnt lgkmcnt(" #n ")" ::: "memory")
; #define BAR __builtin_amdgcn_s_barrier()
; #define SCHED __builtin_amdgcn_sched_barrier(0)
;     ...
;     const int tid = opaque_tid(wave);
;     const int wid = tid >> 6, lane = tid & 63, wr = wid >> 2, wc = wid & 3, fr = lane & 15, fq = lane >> 4;
;     int offA[2], offB[2];
;     _Pragma("unroll") for (int i = 0; i < 2; ++i) {
;       int r, c; stage_rc(tid * 16 + i * 8192, r, c);
;       offA[i] = (r * lda + c) * 2; offB[i] = (r * ldb + c) * 2;
;     }
;     const int brow = pm * BM;
;     f32x4 acc[2][2][4][2];
;     _Pragma("unroll") for (int a = 0; a < 2; ++a) _Pragma("unroll") for (int b = 0; b < 2; ++b) _Pragma("unroll") for (int m = 0; m < 4; ++m) _Pragma("unroll") for (int n = 0; n < 2; ++n)
;       acc[a][b][m][n] = f32x4{0.f, 0.f, 0.f, 0.f};
;     bf16x8 At[4][2], B0[2][2], B1[2][2];
;     if (wr == 1) BAR;
;     if (first_tile) { WAIT_V(0); }
;     else if constexpr (mode == MODE_RESID_LN) { WAIT_V(0); }
;     else if constexpr (mode == MODE_SWIGLU) { WAIT_V(6); }
;     else if constexpr (mode == MODE_V) { WAIT_V(24); }
;     else { WAIT_V(12); }
;     first_tile = false;
;     BAR;
;     BAR;
;     for (int t = 0; t < nt - 2; t += 2) {
;       LDB(B0, 0, 0); SCHED; LDA(At, 0, 0); STAGE(SA(1, 1), rsA, sA1, offA, t + 1);
;       WAIT_L(8); BAR; WAIT_L(0); MMA(0, 0, At, B0); BAR; SCHED;
;       LDB(B1, 0, 1); STAGE(SB(0, 0), rsB, sB0, offB, t + 2);
.LBB0_147:
	v_bfe_i32 v4, v128, 27, 1
	v_lshlrev_b32_e32 v2, 4, v128
	v_lshrrev_b32_e32 v4, 22, v4
	v_add_u32_e32 v4, v2, v4
	v_and_b32_e32 v4, 0xfffffc00, v4
	v_sub_u32_e32 v4, v2, v4
	v_lshrrev_b32_e32 v5, 4, v4
	v_bitop3_b32 v4, v5, v4, 32 bitop3:0x6c
	v_ashrrev_i32_e32 v3, 31, v128
	v_ashrrev_i32_e32 v6, 31, v4
	v_lshrrev_b32_e32 v3, 26, v3
	v_lshrrev_b32_e32 v6, 26, v6
	v_add_u32_e32 v3, v128, v3
	v_add_u32_e32 v6, v4, v6
	v_ashrrev_i32_e32 v3, 6, v3
	v_lshrrev_b32_e32 v7, 6, v6
	v_and_b32_e32 v6, 0xc0, v6
	v_lshlrev_b32_e32 v5, 3, v3
	v_lshlrev_b32_e32 v3, 5, v3
	v_sub_u32_e32 v4, v4, v6
	v_and_b32_e32 v5, 0x7fff0, v5
	v_and_b32_e32 v3, 32, v3
	v_ashrrev_i16_sdwa v4, v244, sext(v4) dst_sel:DWORD dst_unused:UNUSED_PAD src0_sel:DWORD src1_sel:BYTE_0
	v_add_u32_sdwa v3, v3, sext(v4) dst_sel:DWORD dst_unused:UNUSED_PAD src0_sel:DWORD src1_sel:WORD_0
	v_add_lshl_u32 v4, v7, v5, 13
	v_add_u32_e32 v2, 0x2000, v2
	v_lshl_add_u32 v141, v3, 1, v4
	v_ashrrev_i32_e32 v3, 31, v2
	v_lshrrev_b32_e32 v3, 22, v3
	v_add_u32_e32 v3, v2, v3
	v_ashrrev_i32_e32 v3, 10, v3
	v_mul_i32_i24_e32 v4, 0x400, v3
	v_sub_u32_e32 v2, v2, v4
	v_lshrrev_b32_e32 v4, 4, v2
	v_bitop3_b32 v2, v4, v2, 32 bitop3:0x6c
	v_ashrrev_i32_e32 v5, 31, v2
	v_lshrrev_b32_e32 v5, 26, v5
	v_add_u32_e32 v5, v2, v5
	v_lshrrev_b32_e32 v6, 6, v5
	v_and_b32_e32 v5, 0xc0, v5
	v_lshlrev_b32_e32 v4, 3, v3
	v_lshlrev_b32_e32 v3, 5, v3
	v_sub_u32_e32 v2, v2, v5
	v_and_b32_e32 v4, 0x7fff0, v4
	v_and_b32_e32 v3, 32, v3
	v_ashrrev_i16_sdwa v2, v244, sext(v2) dst_sel:DWORD dst_unused:UNUSED_PAD src0_sel:DWORD src1_sel:BYTE_0
	v_add_u32_sdwa v2, v3, sext(v2) dst_sel:DWORD dst_unused:UNUSED_PAD src0_sel:DWORD src1_sel:WORD_0
	v_add_lshl_u32 v3, v6, v4, 13
	v_lshl_add_u32 v142, v2, 1, v3
	v_and_b32_e32 v3, 15, v0
	v_lshlrev_b32_e32 v5, 2, v0
	v_and_b32_e32 v2, 48, v0
	v_lshlrev_b32_e32 v3, 6, v3
	v_and_b32_e32 v5, 32, v5
	v_or_b32_e32 v4, v3, v2
	v_bitop3_b32 v3, v3, v5, v2 bitop3:0x36
	v_lshlrev_b32_e32 v6, 6, v128
	s_movk_i32 s1, 0x3000
	v_and_or_b32 v3, v6, s1, v3
	v_lshlrev_b32_e32 v0, 6, v0
	s_movk_i32 s1, 0x3c0
	v_lshlrev_b32_e32 v1, 13, v1
	v_and_or_b32 v0, v0, s1, v2
	v_bitop3_b32 v0, v1, v0, v5 bitop3:0xf6
	v_or_b32_e32 v6, 0x400, v3
	v_or_b32_e32 v7, 0x800, v3
	v_or_b32_e32 v8, 0xc00, v3
	v_or_b32_e32 v132, 0x800, v0
	v_or_b32_e32 v131, 0x1000, v0
	v_or_b32_e32 v130, 0x1800, v0
	v_mov_b32_e32 v0, 0
	v_bitop3_b32 v129, v4, v1, v5 bitop3:0xde
	s_mov_b32 s1, -2
	s_mov_b32 s3, 0
	v_or_b32_e32 v147, 0x10000, v3
	v_or_b32_e32 v148, 0x10000, v6
	v_or_b32_e32 v149, 0x10000, v7
	v_or_b32_e32 v150, 0x10000, v8
	v_or_b32_e32 v143, 0x14000, v3
	v_or_b32_e32 v144, 0x14000, v6
	v_or_b32_e32 v145, 0x14000, v7
	v_or_b32_e32 v146, 0x14000, v8
	v_or_b32_e32 v137, 0x18000, v3
	v_or_b32_e32 v138, 0x18000, v6
	v_or_b32_e32 v139, 0x18000, v7
	v_or_b32_e32 v140, 0x18000, v8
	v_or_b32_e32 v133, 0x1c000, v3
	v_or_b32_e32 v134, 0x1c000, v6
	v_or_b32_e32 v135, 0x1c000, v7
	v_or_b32_e32 v136, 0x1c000, v8
	s_barrier
	s_barrier
	ds_read_b128 v[152:155], v147
	ds_read_b128 v[156:159], v148
	ds_read_b128 v[160:163], v149
	ds_read_b128 v[164:167], v150
	s_add_i32 s4, s82, s3
	s_add_i32 s5, s4, 0x80
	s_mov_b32 m0, s31
	ds_read_b128 v[168:171], v129
	ds_read_b128 v[172:175], v129 offset:1024
	ds_read_b128 v[176:179], v132
	ds_read_b128 v[180:183], v132 offset:1024
	ds_read_b128 v[184:187], v131
	ds_read_b128 v[188:191], v131 offset:1024
	ds_read_b128 v[192:195], v130
	ds_read_b128 v[196:199], v130 offset:1024
	buffer_load_dwordx4 v141, s[8:11], s5 offen lds
	s_mov_b32 m0, s58
	s_nop 0
	buffer_load_dwordx4 v142, s[8:11], s5 offen lds
	s_waitcnt lgkmcnt(8)
	s_barrier
	s_waitcnt lgkmcnt(0)
	v_mfma_f32_16x16x32_bf16 v[124:127], v[152:155], v[168:171], 0
	v_mfma_f32_16x16x32_bf16 v[124:127], v[156:159], v[172:175], v[124:127]
	v_mfma_f32_16x16x32_bf16 v[120:123], v[164:167], v[172:175], 0
	v_mfma_f32_16x16x32_bf16 v[120:123], v[160:163], v[168:171], v[120:123]
	v_mfma_f32_16x16x32_bf16 v[112:115], v[160:163], v[176:179], 0
	v_mfma_f32_16x16x32_bf16 v[112:115], v[164:167], v[180:183], v[112:115]
	v_mfma_f32_16x16x32_bf16 v[116:119], v[156:159], v[180:183], 0
	v_mfma_f32_16x16x32_bf16 v[116:119], v[152:155], v[176:179], v[116:119]
	v_mfma_f32_16x16x32_bf16 v[108:111], v[152:155], v[184:187], 0
	v_mfma_f32_16x16x32_bf16 v[108:111], v[156:159], v[188:191], v[108:111]
	v_mfma_f32_16x16x32_bf16 v[104:107], v[164:167], v[188:191], 0
	v_mfma_f32_16x16x32_bf16 v[104:107], v[160:163], v[184:187], v[104:107]
	v_mfma_f32_16x16x32_bf16 v[96:99], v[160:163], v[192:195], 0
	v_mfma_f32_16x16x32_bf16 v[96:99], v[164:167], v[196:199], v[96:99]
	v_mfma_f32_16x16x32_bf16 v[100:103], v[156:159], v[196:199], 0
	v_mfma_f32_16x16x32_bf16 v[100:103], v[152:155], v[192:195], v[100:103]
	s_barrier
	s_add_i32 s5, s84, s3
	s_add_i32 s6, s5, 0x100
	s_mov_b32 s14, s10
	s_mov_b32 s15, s11
	s_mov_b32 m0, s34
	ds_read_b128 v[200:203], v143
	ds_read_b128 v[204:207], v144
	ds_read_b128 v[208:211], v145
	ds_read_b128 v[212:215], v146
	buffer_load_dwordx4 v141, s[12:15], s6 offen lds
	s_mov_b32 m0, s43
	s_nop 0
	buffer_load_dwordx4 v142, s[12:15], s6 offen lds
	s_barrier
; #define STAGE(P, RS, SOFF, OFF, kt) do { const int _so = (SOFF) + (kt) * (BK * 2); \
;     _Pragma("unroll") for (int _i = 0; _i < 2; ++_i) { \
;       __builtin_amdgcn_raw_ptr_buffer_load_lds(RS, (__attribute__((address_space(3))) void*)((P) + wave * 1024 + _i * 8192), 16, OFF[_i], _so, 0, 0); } } while (0)
; #define LDA(dst, b, h) _Pragma("unroll") for (int m = 0; m < 4; ++m) _Pragma("unroll") for (int k = 0; k < 2; ++k) \
;     dst[m][k] = *reinterpret_cast<const bf16x8*>(SA(b, h) + lds_byte(wr * 64 + m * 16 + fr, k * 32 + fq * 8))
; #define LDB(dst, b, h) _Pragma("unroll") for (int n = 0; n < 2; ++n) _Pragma("unroll") for (int k = 0; k < 2; ++k) \
;     dst[n][k] = *reinterpret_cast<const bf16x8*>(SB(b, h) + lds_byte(wc * 32 + n * 16 + fr, k * 32 + fq * 8))
; #define WAIT_V(n) asm volatile("s_waitcnt vmcnt(" #n ")" ::: "memory")
; #define WAIT_L(n) asm volatile("s_waitcnt lgkmcnt(" #n ")" ::: "memory")
; #define BAR __builtin_amdgcn_s_barrier()
; #define SCHED __builtin_amdgcn_sched_barrier(0)
;     ...
;       BAR; WAIT_L(0); MMA(0, 1, At, B1); BAR;
;       LDA(At, 0, 1); STAGE(SA(0, 0), rsA, sA0, offA, t + 2);
;       BAR; WAIT_L(0); MMA(1, 0, At, B0); BAR; SCHED;
;       STAGE(SB(0, 1), rsB, sB1, offB, t + 2);
;       WAIT_V(6); BAR; MMA(1, 1, At, B1); BAR;
;       LDB(B0, 1, 0); SCHED; LDA(At, 1, 0); STAGE(SA(0, 1), rsA, sA1, offA, t + 2);
;       WAIT_L(8); BAR; WAIT_L(0); MMA(0, 0, At, B0); BAR; SCHED;
	s_waitcnt lgkmcnt(2)
	v_mfma_f32_16x16x32_bf16 v[92:95], v[200:203], v[168:171], 0
	v_mfma_f32_16x16x32_bf16 v[92:95], v[204:207], v[172:175], v[92:95]
	s_waitcnt lgkmcnt(0)
	v_mfma_f32_16x16x32_bf16 v[88:91], v[212:215], v[172:175], 0
	v_mfma_f32_16x16x32_bf16 v[88:91], v[208:211], v[168:171], v[88:91]
	v_mfma_f32_16x16x32_bf16 v[68:71], v[208:211], v[176:179], 0
	v_mfma_f32_16x16x32_bf16 v[68:71], v[212:215], v[180:183], v[68:71]
	v_mfma_f32_16x16x32_bf16 v[80:83], v[204:207], v[180:183], 0
	v_mfma_f32_16x16x32_bf16 v[80:83], v[200:203], v[176:179], v[80:83]
	v_mfma_f32_16x16x32_bf16 v[60:63], v[200:203], v[184:187], 0
	v_mfma_f32_16x16x32_bf16 v[60:63], v[204:207], v[188:191], v[60:63]
	v_mfma_f32_16x16x32_bf16 v[56:59], v[212:215], v[188:191], 0
	v_mfma_f32_16x16x32_bf16 v[56:59], v[208:211], v[184:187], v[56:59]
	v_mfma_f32_16x16x32_bf16 v[48:51], v[208:211], v[192:195], 0
	v_mfma_f32_16x16x32_bf16 v[48:51], v[212:215], v[196:199], v[48:51]
	v_mfma_f32_16x16x32_bf16 v[52:55], v[204:207], v[196:199], 0
	v_mfma_f32_16x16x32_bf16 v[52:55], v[200:203], v[192:195], v[52:55]
	s_barrier
	s_add_i32 s6, s83, s3
	s_add_i32 s7, s6, 0x100
	s_mov_b32 m0, s30
	ds_read_b128 v[168:171], v129 offset:16384
	ds_read_b128 v[172:175], v129 offset:17408
	ds_read_b128 v[176:179], v132 offset:16384
	ds_read_b128 v[180:183], v132 offset:17408
	ds_read_b128 v[184:187], v131 offset:16384
	ds_read_b128 v[188:191], v131 offset:17408
	ds_read_b128 v[192:195], v130 offset:16384
	ds_read_b128 v[196:199], v130 offset:17408
	buffer_load_dwordx4 v141, s[8:11], s7 offen lds
	s_mov_b32 m0, s44
	s_nop 0
	buffer_load_dwordx4 v142, s[8:11], s7 offen lds
	s_barrier
	s_waitcnt lgkmcnt(6)
	v_mfma_f32_16x16x32_bf16 v[44:47], v[152:155], v[168:171], 0
	v_mfma_f32_16x16x32_bf16 v[44:47], v[156:159], v[172:175], v[44:47]
	v_mfma_f32_16x16x32_bf16 v[40:43], v[164:167], v[172:175], 0
	v_mfma_f32_16x16x32_bf16 v[40:43], v[160:163], v[168:171], v[40:43]
	s_waitcnt lgkmcnt(4)
	v_mfma_f32_16x16x32_bf16 v[32:35], v[160:163], v[176:179], 0
	v_mfma_f32_16x16x32_bf16 v[32:35], v[164:167], v[180:183], v[32:35]
	v_mfma_f32_16x16x32_bf16 v[36:39], v[156:159], v[180:183], 0
	v_mfma_f32_16x16x32_bf16 v[36:39], v[152:155], v[176:179], v[36:39]
	s_waitcnt lgkmcnt(2)
	v_mfma_f32_16x16x32_bf16 v[28:31], v[152:155], v[184:187], 0
	v_mfma_f32_16x16x32_bf16 v[28:31], v[156:159], v[188:191], v[28:31]
	v_mfma_f32_16x16x32_bf16 v[24:27], v[164:167], v[188:191], 0
	v_mfma_f32_16x16x32_bf16 v[24:27], v[160:163], v[184:187], v[24:27]
	s_waitcnt lgkmcnt(0)
	v_mfma_f32_16x16x32_bf16 v[16:19], v[160:163], v[192:195], 0
	v_mfma_f32_16x16x32_bf16 v[16:19], v[164:167], v[196:199], v[16:19]
	v_mfma_f32_16x16x32_bf16 v[20:23], v[156:159], v[196:199], 0
	v_mfma_f32_16x16x32_bf16 v[20:23], v[152:155], v[192:195], v[20:23]
	s_barrier
	s_add_i32 s7, s85, s3
	s_add_i32 s19, s7, 0x100
	s_mov_b32 m0, s35
	s_nop 0
	buffer_load_dwordx4 v141, s[12:15], s19 offen lds
	s_mov_b32 m0, s45
	s_nop 0
	buffer_load_dwordx4 v142, s[12:15], s19 offen lds
	s_waitcnt vmcnt(6)
	s_barrier
	v_mfma_f32_16x16x32_bf16 v[12:15], v[200:203], v[168:171], 0
	v_mfma_f32_16x16x32_bf16 v[12:15], v[204:207], v[172:175], v[12:15]
	v_mfma_f32_16x16x32_bf16 v[8:11], v[212:215], v[172:175], 0
	v_mfma_f32_16x16x32_bf16 v[8:11], v[208:211], v[168:171], v[8:11]
	v_mfma_f32_16x16x32_bf16 v[0:3], v[208:211], v[176:179], 0
	v_mfma_f32_16x16x32_bf16 v[0:3], v[212:215], v[180:183], v[0:3]
	v_mfma_f32_16x16x32_bf16 v[4:7], v[204:207], v[180:183], 0
	v_mfma_f32_16x16x32_bf16 v[4:7], v[200:203], v[176:179], v[4:7]
	v_mfma_f32_16x16x32_bf16 v[64:67], v[200:203], v[184:187], 0
	v_mfma_f32_16x16x32_bf16 v[64:67], v[204:207], v[188:191], v[64:67]
	v_mfma_f32_16x16x32_bf16 v[72:75], v[212:215], v[188:191], 0
	v_mfma_f32_16x16x32_bf16 v[72:75], v[208:211], v[184:187], v[72:75]
	v_mfma_f32_16x16x32_bf16 v[84:87], v[208:211], v[192:195], 0
	v_mfma_f32_16x16x32_bf16 v[84:87], v[212:215], v[196:199], v[84:87]
	v_mfma_f32_16x16x32_bf16 v[76:79], v[204:207], v[196:199], 0
	v_mfma_f32_16x16x32_bf16 v[76:79], v[200:203], v[192:195], v[76:79]
	s_barrier
	ds_read_b128 v[152:155], v137
	ds_read_b128 v[156:159], v138
	ds_read_b128 v[160:163], v139
	ds_read_b128 v[164:167], v140
	s_addk_i32 s4, 0x100
	s_mov_b32 m0, s36
	ds_read_b128 v[168:171], v129 offset:32768
	ds_read_b128 v[172:175], v129 offset:33792
	ds_read_b128 v[176:179], v132 offset:32768
	ds_read_b128 v[180:183], v132 offset:33792
	ds_read_b128 v[184:187], v131 offset:32768
	ds_read_b128 v[188:191], v131 offset:33792
	ds_read_b128 v[192:195], v130 offset:32768
	ds_read_b128 v[196:199], v130 offset:33792
	buffer_load_dwordx4 v141, s[8:11], s4 offen lds
	s_mov_b32 m0, s48
	s_nop 0
	buffer_load_dwordx4 v142, s[8:11], s4 offen lds
	s_waitcnt lgkmcnt(8)
	s_barrier
; #define STAGE(P, RS, SOFF, OFF, kt) do { const int _so = (SOFF) + (kt) * (BK * 2); \
;     _Pragma("unroll") for (int _i = 0; _i < 2; ++_i) { \
;       __builtin_amdgcn_raw_ptr_buffer_load_lds(RS, (__attribute__((address_space(3))) void*)((P) + wave * 1024 + _i * 8192), 16, OFF[_i], _so, 0, 0); } } while (0)
; #define LDA(dst, b, h) _Pragma("unroll") for (int m = 0; m < 4; ++m) _Pragma("unroll") for (int k = 0; k < 2; ++k) \
;     dst[m][k] = *reinterpret_cast<const bf16x8*>(SA(b, h) + lds_byte(wr * 64 + m * 16 + fr, k * 32 + fq * 8))
; #define LDB(dst, b, h) _Pragma("unroll") for (int n = 0; n < 2; ++n) _Pragma("unroll") for (int k = 0; k < 2; ++k) \
;     dst[n][k] = *reinterpret_cast<const bf16x8*>(SB(b, h) + lds_byte(wc * 32 + n * 16 + fr, k * 32 + fq * 8))
; #define WAIT_V(n) asm volatile("s_waitcnt vmcnt(" #n ")" ::: "memory")
; #define WAIT_L(n) asm volatile("s_waitcnt lgkmcnt(" #n ")" ::: "memory")
; #define BAR __builtin_amdgcn_s_barrier()
; #define SCHED __builtin_amdgcn_sched_barrier(0)
;     ...
;       WAIT_L(8); BAR; WAIT_L(0); MMA(0, 0, At, B0); BAR; SCHED;
;       LDB(B1, 1, 1); STAGE(SB(1, 0), rsB, sB0, offB, t + 3);
;       BAR; WAIT_L(0); MMA(0, 1, At, B1); BAR;
;       LDA(At, 1, 1); STAGE(SA(1, 0), rsA, sA0, offA, t + 3);
;       BAR; WAIT_L(0); MMA(1, 0, At, B0); BAR; SCHED;
;       STAGE(SB(1, 1), rsB, sB1, offB, t + 3);
;       WAIT_V(6); BAR; MMA(1, 1, At, B1); BAR;
	s_waitcnt lgkmcnt(6)
	v_mfma_f32_16x16x32_bf16 v[124:127], v[152:155], v[168:171], v[124:127]
	v_mfma_f32_16x16x32_bf16 v[124:127], v[156:159], v[172:175], v[124:127]
	v_mfma_f32_16x16x32_bf16 v[120:123], v[164:167], v[172:175], v[120:123]
	v_mfma_f32_16x16x32_bf16 v[120:123], v[160:163], v[168:171], v[120:123]
	s_waitcnt lgkmcnt(4)
	v_mfma_f32_16x16x32_bf16 v[112:115], v[160:163], v[176:179], v[112:115]
	v_mfma_f32_16x16x32_bf16 v[112:115], v[164:167], v[180:183], v[112:115]
	v_mfma_f32_16x16x32_bf16 v[116:119], v[156:159], v[180:183], v[116:119]
	v_mfma_f32_16x16x32_bf16 v[116:119], v[152:155], v[176:179], v[116:119]
	s_waitcnt lgkmcnt(2)
	v_mfma_f32_16x16x32_bf16 v[108:111], v[152:155], v[184:187], v[108:111]
	v_mfma_f32_16x16x32_bf16 v[108:111], v[156:159], v[188:191], v[108:111]
	v_mfma_f32_16x16x32_bf16 v[104:107], v[164:167], v[188:191], v[104:107]
	v_mfma_f32_16x16x32_bf16 v[104:107], v[160:163], v[184:187], v[104:107]
	s_waitcnt lgkmcnt(0)
	v_mfma_f32_16x16x32_bf16 v[96:99], v[160:163], v[192:195], v[96:99]
	v_mfma_f32_16x16x32_bf16 v[96:99], v[164:167], v[196:199], v[96:99]
	v_mfma_f32_16x16x32_bf16 v[100:103], v[156:159], v[196:199], v[100:103]
	v_mfma_f32_16x16x32_bf16 v[100:103], v[152:155], v[192:195], v[100:103]
	s_barrier
	s_addk_i32 s5, 0x180
	s_mov_b32 m0, s37
	ds_read_b128 v[200:203], v133
	ds_read_b128 v[204:207], v134
	ds_read_b128 v[208:211], v135
	ds_read_b128 v[212:215], v136
	buffer_load_dwordx4 v141, s[12:15], s5 offen lds
	s_mov_b32 m0, s49
	s_nop 0
	buffer_load_dwordx4 v142, s[12:15], s5 offen lds
	s_barrier
	s_waitcnt lgkmcnt(2)
	v_mfma_f32_16x16x32_bf16 v[92:95], v[200:203], v[168:171], v[92:95]
	v_mfma_f32_16x16x32_bf16 v[92:95], v[204:207], v[172:175], v[92:95]
	s_waitcnt lgkmcnt(0)
	v_mfma_f32_16x16x32_bf16 v[88:91], v[212:215], v[172:175], v[88:91]
	v_mfma_f32_16x16x32_bf16 v[88:91], v[208:211], v[168:171], v[88:91]
	v_mfma_f32_16x16x32_bf16 v[68:71], v[208:211], v[176:179], v[68:71]
	v_mfma_f32_16x16x32_bf16 v[68:71], v[212:215], v[180:183], v[68:71]
	v_mfma_f32_16x16x32_bf16 v[80:83], v[204:207], v[180:183], v[80:83]
	v_mfma_f32_16x16x32_bf16 v[80:83], v[200:203], v[176:179], v[80:83]
	v_mfma_f32_16x16x32_bf16 v[60:63], v[200:203], v[184:187], v[60:63]
	v_mfma_f32_16x16x32_bf16 v[60:63], v[204:207], v[188:191], v[60:63]
	v_mfma_f32_16x16x32_bf16 v[56:59], v[212:215], v[188:191], v[56:59]
	v_mfma_f32_16x16x32_bf16 v[56:59], v[208:211], v[184:187], v[56:59]
	v_mfma_f32_16x16x32_bf16 v[48:51], v[208:211], v[192:195], v[48:51]
	v_mfma_f32_16x16x32_bf16 v[48:51], v[212:215], v[196:199], v[48:51]
	v_mfma_f32_16x16x32_bf16 v[52:55], v[204:207], v[196:199], v[52:55]
	v_mfma_f32_16x16x32_bf16 v[52:55], v[200:203], v[192:195], v[52:55]
	s_barrier
	s_addk_i32 s6, 0x180
	s_mov_b32 m0, s38
	ds_read_b128 v[168:171], v129 offset:49152
	ds_read_b128 v[172:175], v129 offset:50176
	ds_read_b128 v[176:179], v132 offset:49152
	ds_read_b128 v[180:183], v132 offset:50176
	ds_read_b128 v[184:187], v131 offset:49152
	ds_read_b128 v[188:191], v131 offset:50176
	ds_read_b128 v[192:195], v130 offset:49152
	ds_read_b128 v[196:199], v130 offset:50176
	buffer_load_dwordx4 v141, s[8:11], s6 offen lds
	s_mov_b32 m0, s54
	s_nop 0
	buffer_load_dwordx4 v142, s[8:11], s6 offen lds
	s_barrier
	s_waitcnt lgkmcnt(6)
	v_mfma_f32_16x16x32_bf16 v[44:47], v[152:155], v[168:171], v[44:47]
	v_mfma_f32_16x16x32_bf16 v[44:47], v[156:159], v[172:175], v[44:47]
	v_mfma_f32_16x16x32_bf16 v[40:43], v[164:167], v[172:175], v[40:43]
	v_mfma_f32_16x16x32_bf16 v[40:43], v[160:163], v[168:171], v[40:43]
	s_waitcnt lgkmcnt(4)
	v_mfma_f32_16x16x32_bf16 v[32:35], v[160:163], v[176:179], v[32:35]
	v_mfma_f32_16x16x32_bf16 v[32:35], v[164:167], v[180:183], v[32:35]
	v_mfma_f32_16x16x32_bf16 v[36:39], v[156:159], v[180:183], v[36:39]
	v_mfma_f32_16x16x32_bf16 v[36:39], v[152:155], v[176:179], v[36:39]
	s_waitcnt lgkmcnt(2)
	v_mfma_f32_16x16x32_bf16 v[28:31], v[152:155], v[184:187], v[28:31]
	v_mfma_f32_16x16x32_bf16 v[28:31], v[156:159], v[188:191], v[28:31]
	v_mfma_f32_16x16x32_bf16 v[24:27], v[164:167], v[188:191], v[24:27]
	v_mfma_f32_16x16x32_bf16 v[24:27], v[160:163], v[184:187], v[24:27]
	s_waitcnt lgkmcnt(0)
	v_mfma_f32_16x16x32_bf16 v[16:19], v[160:163], v[192:195], v[16:19]
	v_mfma_f32_16x16x32_bf16 v[16:19], v[164:167], v[196:199], v[16:19]
	v_mfma_f32_16x16x32_bf16 v[20:23], v[156:159], v[196:199], v[20:23]
	v_mfma_f32_16x16x32_bf16 v[20:23], v[152:155], v[192:195], v[20:23]
	s_barrier
	s_addk_i32 s7, 0x180
	s_mov_b32 m0, s39
	s_nop 0
	buffer_load_dwordx4 v141, s[12:15], s7 offen lds
	s_mov_b32 m0, s55
	s_nop 0
	buffer_load_dwordx4 v142, s[12:15], s7 offen lds
	s_add_i32 s1, s1, 2
	s_addk_i32 s3, 0x100
	s_cmp_gt_u32 s1, 59
	s_cbranch_scc0 .LBB0_148
	s_branch .Lmy_post_148

; #define STAGE(P, RS, SOFF, OFF, kt) do { const int _so = (SOFF) + (kt) * (BK * 2); \
;     _Pragma("unroll") for (int _i = 0; _i < 2; ++_i) { \
;       __builtin_amdgcn_raw_ptr_buffer_load_lds(RS, (__attribute__((address_space(3))) void*)((P) + wave * 1024 + _i * 8192), 16, OFF[_i], _so, 0, 0); } } while (0)
; #define LDA(dst, b, h) _Pragma("unroll") for (int m = 0; m < 4; ++m) _Pragma("unroll") for (int k = 0; k < 2; ++k) \
;     dst[m][k] = *reinterpret_cast<const bf16x8*>(SA(b, h) + lds_byte(wr * 64 + m * 16 + fr, k * 32 + fq * 8))
; #define LDB(dst, b, h) _Pragma("unroll") for (int n = 0; n < 2; ++n) _Pragma("unroll") for (int k = 0; k < 2; ++k) \
;     dst[n][k] = *reinterpret_cast<const bf16x8*>(SB(b, h) + lds_byte(wc * 32 + n * 16 + fr, k * 32 + fq * 8))
; #define WAIT_V(n) asm volatile("s_waitcnt vmcnt(" #n ")" ::: "memory")
; #define WAIT_L(n) asm volatile("s_waitcnt lgkmcnt(" #n ")" ::: "memory")
; #define BAR __builtin_amdgcn_s_barrier()
; #define SCHED __builtin_amdgcn_sched_barrier(0)
;     ...
;       LDB(B0, 0, 0); SCHED; LDA(At, 0, 0); STAGE(SA(1, 1), rsA, sA1, offA, t + 1);
;       WAIT_L(8); BAR; WAIT_L(0); MMA(0, 0, At, B0); BAR; SCHED;
;       LDB(B1, 0, 1); STAGE(SB(0, 0), rsB, sB0, offB, t + 2);
;       BAR; WAIT_L(0); MMA(0, 1, At, B1); BAR;
;       LDA(At, 0, 1); STAGE(SA(0, 0), rsA, sA0, offA, t + 2);
;       BAR; WAIT_L(0); MMA(1, 0, At, B0); BAR; SCHED;
;       STAGE(SB(0, 1), rsB, sB1, offB, t + 2);
;       WAIT_V(6); BAR; MMA(1, 1, At, B1); BAR;
.Lmy_rot_148:
	ds_read_b128 v[152:155], v147
	ds_read_b128 v[156:159], v148
	ds_read_b128 v[160:163], v149
	ds_read_b128 v[164:167], v150
	s_add_i32 s4, s82, s3
	s_add_i32 s5, s4, 0x80
	s_mov_b32 m0, s31
	ds_read_b128 v[168:171], v129
	ds_read_b128 v[172:175], v129 offset:1024
	ds_read_b128 v[176:179], v132
	ds_read_b128 v[180:183], v132 offset:1024
	ds_read_b128 v[184:187], v131
	ds_read_b128 v[188:191], v131 offset:1024
	ds_read_b128 v[192:195], v130
	ds_read_b128 v[196:199], v130 offset:1024
	buffer_load_dwordx4 v141, s[8:11], s5 offen lds
	s_mov_b32 m0, s58
	s_nop 0
	buffer_load_dwordx4 v142, s[8:11], s5 offen lds
	s_waitcnt lgkmcnt(8)
	s_barrier
	s_waitcnt lgkmcnt(0)
	v_mfma_f32_16x16x32_bf16 v[124:127], v[152:155], v[168:171], v[124:127]
	v_mfma_f32_16x16x32_bf16 v[124:127], v[156:159], v[172:175], v[124:127]
	v_mfma_f32_16x16x32_bf16 v[120:123], v[164:167], v[172:175], v[120:123]
	v_mfma_f32_16x16x32_bf16 v[120:123], v[160:163], v[168:171], v[120:123]
	v_mfma_f32_16x16x32_bf16 v[112:115], v[160:163], v[176:179], v[112:115]
	v_mfma_f32_16x16x32_bf16 v[112:115], v[164:167], v[180:183], v[112:115]
	v_mfma_f32_16x16x32_bf16 v[116:119], v[156:159], v[180:183], v[116:119]
	v_mfma_f32_16x16x32_bf16 v[116:119], v[152:155], v[176:179], v[116:119]
	v_mfma_f32_16x16x32_bf16 v[108:111], v[152:155], v[184:187], v[108:111]
	v_mfma_f32_16x16x32_bf16 v[108:111], v[156:159], v[188:191], v[108:111]
	v_mfma_f32_16x16x32_bf16 v[104:107], v[164:167], v[188:191], v[104:107]
	v_mfma_f32_16x16x32_bf16 v[104:107], v[160:163], v[184:187], v[104:107]
	v_mfma_f32_16x16x32_bf16 v[96:99], v[160:163], v[192:195], v[96:99]
	v_mfma_f32_16x16x32_bf16 v[96:99], v[164:167], v[196:199], v[96:99]
	v_mfma_f32_16x16x32_bf16 v[100:103], v[156:159], v[196:199], v[100:103]
	v_mfma_f32_16x16x32_bf16 v[100:103], v[152:155], v[192:195], v[100:103]
	s_barrier
	s_add_i32 s5, s84, s3
	s_add_i32 s6, s5, 0x100
	s_mov_b32 s14, s10
	s_mov_b32 s15, s11
	s_mov_b32 m0, s34
	ds_read_b128 v[200:203], v143
	ds_read_b128 v[204:207], v144
	ds_read_b128 v[208:211], v145
	ds_read_b128 v[212:215], v146
	buffer_load_dwordx4 v141, s[12:15], s6 offen lds
	s_mov_b32 m0, s43
	s_nop 0
	buffer_load_dwordx4 v142, s[12:15], s6 offen lds
	s_barrier
	s_waitcnt lgkmcnt(2)
	v_mfma_f32_16x16x32_bf16 v[92:95], v[200:203], v[168:171], v[92:95]
	v_mfma_f32_16x16x32_bf16 v[92:95], v[204:207], v[172:175], v[92:95]
	s_waitcnt lgkmcnt(0)
	v_mfma_f32_16x16x32_bf16 v[88:91], v[212:215], v[172:175], v[88:91]
	v_mfma_f32_16x16x32_bf16 v[88:91], v[208:211], v[168:171], v[88:91]
	v_mfma_f32_16x16x32_bf16 v[68:71], v[208:211], v[176:179], v[68:71]
	v_mfma_f32_16x16x32_bf16 v[68:71], v[212:215], v[180:183], v[68:71]
	v_mfma_f32_16x16x32_bf16 v[80:83], v[204:207], v[180:183], v[80:83]
	v_mfma_f32_16x16x32_bf16 v[80:83], v[200:203], v[176:179], v[80:83]
	v_mfma_f32_16x16x32_bf16 v[60:63], v[200:203], v[184:187], v[60:63]
	v_mfma_f32_16x16x32_bf16 v[60:63], v[204:207], v[188:191], v[60:63]
	v_mfma_f32_16x16x32_bf16 v[56:59], v[212:215], v[188:191], v[56:59]
	v_mfma_f32_16x16x32_bf16 v[56:59], v[208:211], v[184:187], v[56:59]
	v_mfma_f32_16x16x32_bf16 v[48:51], v[208:211], v[192:195], v[48:51]
	v_mfma_f32_16x16x32_bf16 v[48:51], v[212:215], v[196:199], v[48:51]
	v_mfma_f32_16x16x32_bf16 v[52:55], v[204:207], v[196:199], v[52:55]
	v_mfma_f32_16x16x32_bf16 v[52:55], v[200:203], v[192:195], v[52:55]
	s_barrier
	s_add_i32 s6, s83, s3
	s_add_i32 s7, s6, 0x100
	s_mov_b32 m0, s30
	ds_read_b128 v[168:171], v129 offset:16384
	ds_read_b128 v[172:175], v129 offset:17408
	ds_read_b128 v[176:179], v132 offset:16384
	ds_read_b128 v[180:183], v132 offset:17408
	ds_read_b128 v[184:187], v131 offset:16384
	ds_read_b128 v[188:191], v131 offset:17408
	ds_read_b128 v[192:195], v130 offset:16384
	ds_read_b128 v[196:199], v130 offset:17408
	buffer_load_dwordx4 v141, s[8:11], s7 offen lds
	s_mov_b32 m0, s44
	s_nop 0
	buffer_load_dwordx4 v142, s[8:11], s7 offen lds
	s_barrier
	s_waitcnt lgkmcnt(6)
	v_mfma_f32_16x16x32_bf16 v[44:47], v[152:155], v[168:171], v[44:47]
	v_mfma_f32_16x16x32_bf16 v[44:47], v[156:159], v[172:175], v[44:47]
	v_mfma_f32_16x16x32_bf16 v[40:43], v[164:167], v[172:175], v[40:43]
	v_mfma_f32_16x16x32_bf16 v[40:43], v[160:163], v[168:171], v[40:43]
	s_waitcnt lgkmcnt(4)
	v_mfma_f32_16x16x32_bf16 v[32:35], v[160:163], v[176:179], v[32:35]
	v_mfma_f32_16x16x32_bf16 v[32:35], v[164:167], v[180:183], v[32:35]
	v_mfma_f32_16x16x32_bf16 v[36:39], v[156:159], v[180:183], v[36:39]
	v_mfma_f32_16x16x32_bf16 v[36:39], v[152:155], v[176:179], v[36:39]
	s_waitcnt lgkmcnt(2)
	v_mfma_f32_16x16x32_bf16 v[28:31], v[152:155], v[184:187], v[28:31]
	v_mfma_f32_16x16x32_bf16 v[28:31], v[156:159], v[188:191], v[28:31]
	v_mfma_f32_16x16x32_bf16 v[24:27], v[164:167], v[188:191], v[24:27]
	v_mfma_f32_16x16x32_bf16 v[24:27], v[160:163], v[184:187], v[24:27]
	s_waitcnt lgkmcnt(0)
	v_mfma_f32_16x16x32_bf16 v[16:19], v[160:163], v[192:195], v[16:19]
	v_mfma_f32_16x16x32_bf16 v[16:19], v[164:167], v[196:199], v[16:19]
	v_mfma_f32_16x16x32_bf16 v[20:23], v[156:159], v[196:199], v[20:23]
	v_mfma_f32_16x16x32_bf16 v[20:23], v[152:155], v[192:195], v[20:23]
	s_barrier
	s_add_i32 s7, s85, s3
	s_add_i32 s19, s7, 0x100
	s_mov_b32 m0, s35
	s_nop 0
	buffer_load_dwordx4 v141, s[12:15], s19 offen lds
	s_mov_b32 m0, s45
	s_nop 0
	buffer_load_dwordx4 v142, s[12:15], s19 offen lds
	s_waitcnt vmcnt(6)
	s_barrier
; #define STAGE(P, RS, SOFF, OFF, kt) do { const int _so = (SOFF) + (kt) * (BK * 2); \
;     _Pragma("unroll") for (int _i = 0; _i < 2; ++_i) { \
;       __builtin_amdgcn_raw_ptr_buffer_load_lds(RS, (__attribute__((address_space(3))) void*)((P) + wave * 1024 + _i * 8192), 16, OFF[_i], _so, 0, 0); } } while (0)
; #define LDA(dst, b, h) _Pragma("unroll") for (int m = 0; m < 4; ++m) _Pragma("unroll") for (int k = 0; k < 2; ++k) \
;     dst[m][k] = *reinterpret_cast<const bf16x8*>(SA(b, h) + lds_byte(wr * 64 + m * 16 + fr, k * 32 + fq * 8))
; #define LDB(dst, b, h) _Pragma("unroll") for (int n = 0; n < 2; ++n) _Pragma("unroll") for (int k = 0; k < 2; ++k) \
;     dst[n][k] = *reinterpret_cast<const bf16x8*>(SB(b, h) + lds_byte(wc * 32 + n * 16 + fr, k * 32 + fq * 8))
; #define WAIT_V(n) asm volatile("s_waitcnt vmcnt(" #n ")" ::: "memory")
; #define WAIT_L(n) asm volatile("s_waitcnt lgkmcnt(" #n ")" ::: "memory")
; #define BAR __builtin_amdgcn_s_barrier()
; #define SCHED __builtin_amdgcn_sched_barrier(0)
;     ...
;       WAIT_V(6); BAR; MMA(1, 1, At, B1); BAR;
;       LDB(B0, 1, 0); SCHED; LDA(At, 1, 0); STAGE(SA(0, 1), rsA, sA1, offA, t + 2);
;       WAIT_L(8); BAR; WAIT_L(0); MMA(0, 0, At, B0); BAR; SCHED;
;       LDB(B1, 1, 1); STAGE(SB(1, 0), rsB, sB0, offB, t + 3);
;       BAR; WAIT_L(0); MMA(0, 1, At, B1); BAR;
;       LDA(At, 1, 1); STAGE(SA(1, 0), rsA, sA0, offA, t + 3);
;       BAR; WAIT_L(0); MMA(1, 0, At, B0); BAR; SCHED;
;       STAGE(SB(1, 1), rsB, sB1, offB, t + 3);
;       WAIT_V(6); BAR; MMA(1, 1, At, B1); BAR;
	v_mfma_f32_16x16x32_bf16 v[12:15], v[200:203], v[168:171], v[12:15]
	v_mfma_f32_16x16x32_bf16 v[12:15], v[204:207], v[172:175], v[12:15]
	v_mfma_f32_16x16x32_bf16 v[8:11], v[212:215], v[172:175], v[8:11]
	v_mfma_f32_16x16x32_bf16 v[8:11], v[208:211], v[168:171], v[8:11]
	v_mfma_f32_16x16x32_bf16 v[0:3], v[208:211], v[176:179], v[0:3]
	v_mfma_f32_16x16x32_bf16 v[0:3], v[212:215], v[180:183], v[0:3]
	v_mfma_f32_16x16x32_bf16 v[4:7], v[204:207], v[180:183], v[4:7]
	v_mfma_f32_16x16x32_bf16 v[4:7], v[200:203], v[176:179], v[4:7]
	v_mfma_f32_16x16x32_bf16 v[64:67], v[200:203], v[184:187], v[64:67]
	v_mfma_f32_16x16x32_bf16 v[64:67], v[204:207], v[188:191], v[64:67]
	v_mfma_f32_16x16x32_bf16 v[72:75], v[212:215], v[188:191], v[72:75]
	v_mfma_f32_16x16x32_bf16 v[72:75], v[208:211], v[184:187], v[72:75]
	v_mfma_f32_16x16x32_bf16 v[84:87], v[208:211], v[192:195], v[84:87]
	v_mfma_f32_16x16x32_bf16 v[84:87], v[212:215], v[196:199], v[84:87]
	v_mfma_f32_16x16x32_bf16 v[76:79], v[204:207], v[196:199], v[76:79]
	v_mfma_f32_16x16x32_bf16 v[76:79], v[200:203], v[192:195], v[76:79]
	s_barrier
	ds_read_b128 v[152:155], v137
	ds_read_b128 v[156:159], v138
	ds_read_b128 v[160:163], v139
	ds_read_b128 v[164:167], v140
	s_addk_i32 s4, 0x100
	s_mov_b32 m0, s36
	ds_read_b128 v[168:171], v129 offset:32768
	ds_read_b128 v[172:175], v129 offset:33792
	ds_read_b128 v[176:179], v132 offset:32768
	ds_read_b128 v[180:183], v132 offset:33792
	ds_read_b128 v[184:187], v131 offset:32768
	ds_read_b128 v[188:191], v131 offset:33792
	ds_read_b128 v[192:195], v130 offset:32768
	ds_read_b128 v[196:199], v130 offset:33792
	buffer_load_dwordx4 v141, s[8:11], s4 offen lds
	s_mov_b32 m0, s48
	s_nop 0
	buffer_load_dwordx4 v142, s[8:11], s4 offen lds
	s_waitcnt lgkmcnt(8)
	s_barrier
	s_waitcnt lgkmcnt(6)
	v_mfma_f32_16x16x32_bf16 v[124:127], v[152:155], v[168:171], v[124:127]
	v_mfma_f32_16x16x32_bf16 v[124:127], v[156:159], v[172:175], v[124:127]
	v_mfma_f32_16x16x32_bf16 v[120:123], v[164:167], v[172:175], v[120:123]
	v_mfma_f32_16x16x32_bf16 v[120:123], v[160:163], v[168:171], v[120:123]
	s_waitcnt lgkmcnt(4)
	v_mfma_f32_16x16x32_bf16 v[112:115], v[160:163], v[176:179], v[112:115]
	v_mfma_f32_16x16x32_bf16 v[112:115], v[164:167], v[180:183], v[112:115]
	v_mfma_f32_16x16x32_bf16 v[116:119], v[156:159], v[180:183], v[116:119]
	v_mfma_f32_16x16x32_bf16 v[116:119], v[152:155], v[176:179], v[116:119]
	s_waitcnt lgkmcnt(2)
	v_mfma_f32_16x16x32_bf16 v[108:111], v[152:155], v[184:187], v[108:111]
	v_mfma_f32_16x16x32_bf16 v[108:111], v[156:159], v[188:191], v[108:111]
	v_mfma_f32_16x16x32_bf16 v[104:107], v[164:167], v[188:191], v[104:107]
	v_mfma_f32_16x16x32_bf16 v[104:107], v[160:163], v[184:187], v[104:107]
	s_waitcnt lgkmcnt(0)
	v_mfma_f32_16x16x32_bf16 v[96:99], v[160:163], v[192:195], v[96:99]
	v_mfma_f32_16x16x32_bf16 v[96:99], v[164:167], v[196:199], v[96:99]
	v_mfma_f32_16x16x32_bf16 v[100:103], v[156:159], v[196:199], v[100:103]
	v_mfma_f32_16x16x32_bf16 v[100:103], v[152:155], v[192:195], v[100:103]
	s_barrier
	s_addk_i32 s5, 0x180
	s_mov_b32 m0, s37
	ds_read_b128 v[200:203], v133
	ds_read_b128 v[204:207], v134
	ds_read_b128 v[208:211], v135
	ds_read_b128 v[212:215], v136
	buffer_load_dwordx4 v141, s[12:15], s5 offen lds
	s_mov_b32 m0, s49
	s_nop 0
	buffer_load_dwordx4 v142, s[12:15], s5 offen lds
	s_barrier
	s_waitcnt lgkmcnt(2)
	v_mfma_f32_16x16x32_bf16 v[92:95], v[200:203], v[168:171], v[92:95]
	v_mfma_f32_16x16x32_bf16 v[92:95], v[204:207], v[172:175], v[92:95]
	s_waitcnt lgkmcnt(0)
	v_mfma_f32_16x16x32_bf16 v[88:91], v[212:215], v[172:175], v[88:91]
	v_mfma_f32_16x16x32_bf16 v[88:91], v[208:211], v[168:171], v[88:91]
	v_mfma_f32_16x16x32_bf16 v[68:71], v[208:211], v[176:179], v[68:71]
	v_mfma_f32_16x16x32_bf16 v[68:71], v[212:215], v[180:183], v[68:71]
	v_mfma_f32_16x16x32_bf16 v[80:83], v[204:207], v[180:183], v[80:83]
	v_mfma_f32_16x16x32_bf16 v[80:83], v[200:203], v[176:179], v[80:83]
	v_mfma_f32_16x16x32_bf16 v[60:63], v[200:203], v[184:187], v[60:63]
	v_mfma_f32_16x16x32_bf16 v[60:63], v[204:207], v[188:191], v[60:63]
	v_mfma_f32_16x16x32_bf16 v[56:59], v[212:215], v[188:191], v[56:59]
	v_mfma_f32_16x16x32_bf16 v[56:59], v[208:211], v[184:187], v[56:59]
	v_mfma_f32_16x16x32_bf16 v[48:51], v[208:211], v[192:195], v[48:51]
	v_mfma_f32_16x16x32_bf16 v[48:51], v[212:215], v[196:199], v[48:51]
	v_mfma_f32_16x16x32_bf16 v[52:55], v[204:207], v[196:199], v[52:55]
	v_mfma_f32_16x16x32_bf16 v[52:55], v[200:203], v[192:195], v[52:55]
	s_barrier
	s_addk_i32 s6, 0x180
	s_mov_b32 m0, s38
	ds_read_b128 v[168:171], v129 offset:49152
	ds_read_b128 v[172:175], v129 offset:50176
	ds_read_b128 v[176:179], v132 offset:49152
	ds_read_b128 v[180:183], v132 offset:50176
	ds_read_b128 v[184:187], v131 offset:49152
	ds_read_b128 v[188:191], v131 offset:50176
	ds_read_b128 v[192:195], v130 offset:49152
	ds_read_b128 v[196:199], v130 offset:50176
	buffer_load_dwordx4 v141, s[8:11], s6 offen lds
	s_mov_b32 m0, s54
	s_nop 0
	buffer_load_dwordx4 v142, s[8:11], s6 offen lds
	s_barrier
	s_waitcnt lgkmcnt(6)
	v_mfma_f32_16x16x32_bf16 v[44:47], v[152:155], v[168:171], v[44:47]
	v_mfma_f32_16x16x32_bf16 v[44:47], v[156:159], v[172:175], v[44:47]
	v_mfma_f32_16x16x32_bf16 v[40:43], v[164:167], v[172:175], v[40:43]
	v_mfma_f32_16x16x32_bf16 v[40:43], v[160:163], v[168:171], v[40:43]
	s_waitcnt lgkmcnt(4)
	v_mfma_f32_16x16x32_bf16 v[32:35], v[160:163], v[176:179], v[32:35]
	v_mfma_f32_16x16x32_bf16 v[32:35], v[164:167], v[180:183], v[32:35]
	v_mfma_f32_16x16x32_bf16 v[36:39], v[156:159], v[180:183], v[36:39]
	v_mfma_f32_16x16x32_bf16 v[36:39], v[152:155], v[176:179], v[36:39]
	s_waitcnt lgkmcnt(2)
	v_mfma_f32_16x16x32_bf16 v[28:31], v[152:155], v[184:187], v[28:31]
	v_mfma_f32_16x16x32_bf16 v[28:31], v[156:159], v[188:191], v[28:31]
	v_mfma_f32_16x16x32_bf16 v[24:27], v[164:167], v[188:191], v[24:27]
	v_mfma_f32_16x16x32_bf16 v[24:27], v[160:163], v[184:187], v[24:27]
	s_waitcnt lgkmcnt(0)
	v_mfma_f32_16x16x32_bf16 v[16:19], v[160:163], v[192:195], v[16:19]
	v_mfma_f32_16x16x32_bf16 v[16:19], v[164:167], v[196:199], v[16:19]
	v_mfma_f32_16x16x32_bf16 v[20:23], v[156:159], v[196:199], v[20:23]
	v_mfma_f32_16x16x32_bf16 v[20:23], v[152:155], v[192:195], v[20:23]
	s_barrier
	s_addk_i32 s7, 0x180
	s_mov_b32 m0, s39
	s_nop 0
	buffer_load_dwordx4 v141, s[12:15], s7 offen lds
	s_mov_b32 m0, s55
	s_nop 0
	buffer_load_dwordx4 v142, s[12:15], s7 offen lds
	s_add_i32 s1, s1, 2
	s_addk_i32 s3, 0x100
	s_cmp_gt_u32 s1, 59
	s_cbranch_scc0 .LBB0_148
; #define STAGE(P, RS, SOFF, OFF, kt) do { const int _so = (SOFF) + (kt) * (BK * 2); \
;     _Pragma("unroll") for (int _i = 0; _i < 2; ++_i) { \
;       __builtin_amdgcn_raw_ptr_buffer_load_lds(RS, (__attribute__((address_space(3))) void*)((P) + wave * 1024 + _i * 8192), 16, OFF[_i], _so, 0, 0); } } while (0)
; #define LDA(dst, b, h) _Pragma("unroll") for (int m = 0; m < 4; ++m) _Pragma("unroll") for (int k = 0; k < 2; ++k) \
;     dst[m][k] = *reinterpret_cast<const bf16x8*>(SA(b, h) + lds_byte(wr * 64 + m * 16 + fr, k * 32 + fq * 8))
; #define LDB(dst, b, h) _Pragma("unroll") for (int n = 0; n < 2; ++n) _Pragma("unroll") for (int k = 0; k < 2; ++k) \
;     dst[n][k] = *reinterpret_cast<const bf16x8*>(SB(b, h) + lds_byte(wc * 32 + n * 16 + fr, k * 32 + fq * 8))
; #define WAIT_V(n) asm volatile("s_waitcnt vmcnt(" #n ")" ::: "memory")
; #define WAIT_L(n) asm volatile("s_waitcnt lgkmcnt(" #n ")" ::: "memory")
; #define BAR __builtin_amdgcn_s_barrier()
;     ...
;       WAIT_V(6); BAR; MMA(1, 1, At, B1); BAR;
;     }
;     { LDB(B0, 0, 0); LDA(At, 0, 0); STAGE(SA(1, 1), rsA, sA1, offA, nt - 1);
;       BAR; WAIT_L(0); MMA(0, 0, At, B0); BAR;
;       LDB(B1, 0, 1); BAR; WAIT_L(0); MMA(0, 1, At, B1); BAR;
;       LDA(At, 0, 1); WAIT_V(4); BAR; WAIT_L(0); MMA(1, 0, At, B0); MMA(1, 1, At, B1); BAR; }
.Lmy_post_148:
	s_waitcnt vmcnt(6)
	s_barrier
	v_mfma_f32_16x16x32_bf16 v[12:15], v[200:203], v[168:171], v[12:15]
	v_mfma_f32_16x16x32_bf16 v[12:15], v[204:207], v[172:175], v[12:15]
	v_mfma_f32_16x16x32_bf16 v[8:11], v[212:215], v[172:175], v[8:11]
	v_mfma_f32_16x16x32_bf16 v[8:11], v[208:211], v[168:171], v[8:11]
	v_mfma_f32_16x16x32_bf16 v[0:3], v[208:211], v[176:179], v[0:3]
	v_mfma_f32_16x16x32_bf16 v[0:3], v[212:215], v[180:183], v[0:3]
	v_mfma_f32_16x16x32_bf16 v[4:7], v[204:207], v[180:183], v[4:7]
	v_mfma_f32_16x16x32_bf16 v[4:7], v[200:203], v[176:179], v[4:7]
	v_mfma_f32_16x16x32_bf16 v[64:67], v[200:203], v[184:187], v[64:67]
	v_mfma_f32_16x16x32_bf16 v[64:67], v[204:207], v[188:191], v[64:67]
	v_mfma_f32_16x16x32_bf16 v[72:75], v[212:215], v[188:191], v[72:75]
	v_mfma_f32_16x16x32_bf16 v[72:75], v[208:211], v[184:187], v[72:75]
	v_mfma_f32_16x16x32_bf16 v[84:87], v[208:211], v[192:195], v[84:87]
	v_mfma_f32_16x16x32_bf16 v[84:87], v[212:215], v[196:199], v[84:87]
	v_mfma_f32_16x16x32_bf16 v[76:79], v[204:207], v[196:199], v[76:79]
	v_mfma_f32_16x16x32_bf16 v[76:79], v[200:203], v[192:195], v[76:79]
	s_barrier
	s_add_i32 s1, s82, 0x1f80
	s_mov_b32 m0, s31
	ds_read_b128 v[152:155], v147
	ds_read_b128 v[156:159], v148
	ds_read_b128 v[160:163], v149
	ds_read_b128 v[148:151], v150
	ds_read_b128 v[164:167], v129
	ds_read_b128 v[168:171], v129 offset:1024
	ds_read_b128 v[172:175], v132
	ds_read_b128 v[176:179], v132 offset:1024
	ds_read_b128 v[180:183], v131
	ds_read_b128 v[184:187], v131 offset:1024
	ds_read_b128 v[188:191], v130
	ds_read_b128 v[192:195], v130 offset:1024
	buffer_load_dwordx4 v141, s[8:11], s1 offen lds
	s_mov_b32 m0, s58
	s_nop 0
	buffer_load_dwordx4 v142, s[8:11], s1 offen lds
	s_barrier
	s_waitcnt lgkmcnt(6)
	v_mfma_f32_16x16x32_bf16 v[124:127], v[152:155], v[164:167], v[124:127]
	v_mfma_f32_16x16x32_bf16 v[124:127], v[156:159], v[168:171], v[124:127]
	v_mfma_f32_16x16x32_bf16 v[120:123], v[148:151], v[168:171], v[120:123]
	v_mfma_f32_16x16x32_bf16 v[120:123], v[160:163], v[164:167], v[120:123]
	s_waitcnt lgkmcnt(4)
	v_mfma_f32_16x16x32_bf16 v[112:115], v[160:163], v[172:175], v[112:115]
	v_mfma_f32_16x16x32_bf16 v[112:115], v[148:151], v[176:179], v[112:115]
	v_mfma_f32_16x16x32_bf16 v[116:119], v[156:159], v[176:179], v[116:119]
	v_mfma_f32_16x16x32_bf16 v[116:119], v[152:155], v[172:175], v[116:119]
	s_waitcnt lgkmcnt(2)
	v_mfma_f32_16x16x32_bf16 v[108:111], v[152:155], v[180:183], v[108:111]
	v_mfma_f32_16x16x32_bf16 v[108:111], v[156:159], v[184:187], v[108:111]
	v_mfma_f32_16x16x32_bf16 v[104:107], v[148:151], v[184:187], v[104:107]
	v_mfma_f32_16x16x32_bf16 v[104:107], v[160:163], v[180:183], v[104:107]
	s_waitcnt lgkmcnt(0)
	v_mfma_f32_16x16x32_bf16 v[96:99], v[160:163], v[188:191], v[96:99]
	v_mfma_f32_16x16x32_bf16 v[96:99], v[148:151], v[192:195], v[96:99]
	v_mfma_f32_16x16x32_bf16 v[100:103], v[156:159], v[192:195], v[100:103]
	v_mfma_f32_16x16x32_bf16 v[100:103], v[152:155], v[188:191], v[100:103]
	s_barrier
	ds_read_b128 v[196:199], v143
	ds_read_b128 v[200:203], v144
	ds_read_b128 v[142:145], v145
	ds_read_b128 v[204:207], v146
	s_barrier
	s_waitcnt lgkmcnt(1)
	v_mfma_f32_16x16x32_bf16 v[88:91], v[142:145], v[164:167], v[88:91]
	v_mfma_f32_16x16x32_bf16 v[80:83], v[196:199], v[172:175], v[80:83]
	v_mfma_f32_16x16x32_bf16 v[60:63], v[196:199], v[180:183], v[60:63]
	v_mfma_f32_16x16x32_bf16 v[56:59], v[142:145], v[180:183], v[56:59]
	v_mfma_f32_16x16x32_bf16 v[52:55], v[196:199], v[188:191], v[52:55]
	v_mfma_f32_16x16x32_bf16 v[48:51], v[142:145], v[188:191], v[48:51]
	v_mfma_f32_16x16x32_bf16 v[92:95], v[196:199], v[164:167], v[92:95]
	v_mfma_f32_16x16x32_bf16 v[68:71], v[142:145], v[172:175], v[68:71]
	s_waitcnt lgkmcnt(0)
	v_mfma_f32_16x16x32_bf16 v[88:91], v[204:207], v[168:171], v[88:91]
	v_mfma_f32_16x16x32_bf16 v[80:83], v[200:203], v[176:179], v[80:83]
	v_mfma_f32_16x16x32_bf16 v[60:63], v[200:203], v[184:187], v[60:63]
	v_mfma_f32_16x16x32_bf16 v[56:59], v[204:207], v[184:187], v[56:59]
	v_mfma_f32_16x16x32_bf16 v[52:55], v[200:203], v[192:195], v[52:55]
	v_mfma_f32_16x16x32_bf16 v[48:51], v[204:207], v[192:195], v[48:51]
	v_mfma_f32_16x16x32_bf16 v[164:167], v[200:203], v[168:171], v[92:95]
	v_mfma_f32_16x16x32_bf16 v[168:171], v[204:207], v[176:179], v[68:71]
	s_barrier
	s_nop 0
	ds_read_b128 v[68:71], v129 offset:16384
	ds_read_b128 v[92:95], v129 offset:17408
	ds_read_b128 v[172:175], v132 offset:16384
	ds_read_b128 v[176:179], v132 offset:17408
	ds_read_b128 v[180:183], v131 offset:16384
	ds_read_b128 v[184:187], v131 offset:17408
	ds_read_b128 v[188:191], v130 offset:16384
	ds_read_b128 v[192:195], v130 offset:17408
	s_waitcnt vmcnt(4)
	s_barrier
; #define LDA(dst, b, h) _Pragma("unroll") for (int m = 0; m < 4; ++m) _Pragma("unroll") for (int k = 0; k < 2; ++k) \
;     dst[m][k] = *reinterpret_cast<const bf16x8*>(SA(b, h) + lds_byte(wr * 64 + m * 16 + fr, k * 32 + fq * 8))
; #define LDB(dst, b, h) _Pragma("unroll") for (int n = 0; n < 2; ++n) _Pragma("unroll") for (int k = 0; k < 2; ++k) \
;     dst[n][k] = *reinterpret_cast<const bf16x8*>(SB(b, h) + lds_byte(wc * 32 + n * 16 + fr, k * 32 + fq * 8))
; #define WAIT_V(n) asm volatile("s_waitcnt vmcnt(" #n ")" ::: "memory")
; #define WAIT_L(n) asm volatile("s_waitcnt lgkmcnt(" #n ")" ::: "memory")
; #define BAR __builtin_amdgcn_s_barrier()
;     ...
;       LDA(At, 0, 1); WAIT_V(4); BAR; WAIT_L(0); MMA(1, 0, At, B0); MMA(1, 1, At, B1); BAR; }
;     { LDB(B0, 1, 0); LDA(At, 1, 0); WAIT_V(2); BAR; WAIT_L(0); MMA(0, 0, At, B0); BAR;
	s_waitcnt lgkmcnt(0)
	v_mfma_f32_16x16x32_bf16 v[44:47], v[152:155], v[68:71], v[44:47]
	v_mfma_f32_16x16x32_bf16 v[40:43], v[160:163], v[68:71], v[40:43]
	v_mfma_f32_16x16x32_bf16 v[36:39], v[152:155], v[172:175], v[36:39]
	v_mfma_f32_16x16x32_bf16 v[32:35], v[160:163], v[172:175], v[32:35]
	v_mfma_f32_16x16x32_bf16 v[28:31], v[152:155], v[180:183], v[28:31]
	v_mfma_f32_16x16x32_bf16 v[24:27], v[160:163], v[180:183], v[24:27]
	v_mfma_f32_16x16x32_bf16 v[20:23], v[152:155], v[188:191], v[20:23]
	v_mfma_f32_16x16x32_bf16 v[16:19], v[160:163], v[188:191], v[16:19]
	v_mfma_f32_16x16x32_bf16 v[44:47], v[156:159], v[92:95], v[44:47]
	v_mfma_f32_16x16x32_bf16 v[40:43], v[148:151], v[92:95], v[40:43]
	v_mfma_f32_16x16x32_bf16 v[36:39], v[156:159], v[176:179], v[36:39]
	v_mfma_f32_16x16x32_bf16 v[32:35], v[148:151], v[176:179], v[32:35]
	v_mfma_f32_16x16x32_bf16 v[28:31], v[156:159], v[184:187], v[28:31]
	v_mfma_f32_16x16x32_bf16 v[24:27], v[148:151], v[184:187], v[24:27]
	v_mfma_f32_16x16x32_bf16 v[20:23], v[156:159], v[192:195], v[20:23]
	v_mfma_f32_16x16x32_bf16 v[16:19], v[148:151], v[192:195], v[16:19]
	v_mfma_f32_16x16x32_bf16 v[8:11], v[142:145], v[68:71], v[8:11]
	v_mfma_f32_16x16x32_bf16 v[0:3], v[142:145], v[172:175], v[0:3]
	v_mfma_f32_16x16x32_bf16 v[12:15], v[196:199], v[68:71], v[12:15]
	v_mfma_f32_16x16x32_bf16 v[4:7], v[196:199], v[172:175], v[4:7]
	v_mfma_f32_16x16x32_bf16 v[64:67], v[196:199], v[180:183], v[64:67]
	v_mfma_f32_16x16x32_bf16 v[68:71], v[142:145], v[180:183], v[72:75]
	v_mfma_f32_16x16x32_bf16 v[72:75], v[196:199], v[188:191], v[76:79]
	v_mfma_f32_16x16x32_bf16 v[76:79], v[142:145], v[188:191], v[84:87]
	v_mfma_f32_16x16x32_bf16 v[8:11], v[204:207], v[92:95], v[8:11]
	v_mfma_f32_16x16x32_bf16 v[0:3], v[204:207], v[176:179], v[0:3]
	v_mfma_f32_16x16x32_bf16 v[160:163], v[200:203], v[92:95], v[12:15]
	v_mfma_f32_16x16x32_bf16 v[172:175], v[200:203], v[176:179], v[4:7]
	v_mfma_f32_16x16x32_bf16 v[176:179], v[200:203], v[184:187], v[64:67]
	v_mfma_f32_16x16x32_bf16 v[180:183], v[204:207], v[184:187], v[68:71]
	v_mfma_f32_16x16x32_bf16 v[184:187], v[200:203], v[192:195], v[72:75]
	v_mfma_f32_16x16x32_bf16 v[188:191], v[204:207], v[192:195], v[76:79]
	s_barrier
	ds_read_b128 v[4:7], v137
	ds_read_b128 v[12:15], v138
	ds_read_b128 v[192:195], v139
	ds_read_b128 v[138:141], v140
	ds_read_b128 v[72:75], v129 offset:32768
	ds_read_b128 v[142:145], v129 offset:33792
	ds_read_b128 v[76:79], v132 offset:32768
	ds_read_b128 v[196:199], v132 offset:33792
	ds_read_b128 v[152:155], v131 offset:32768
	ds_read_b128 v[200:203], v131 offset:33792
	ds_read_b128 v[204:207], v130 offset:32768
	ds_read_b128 v[208:211], v130 offset:33792
	s_waitcnt vmcnt(2)
	s_barrier
	s_waitcnt lgkmcnt(7)
	v_mfma_f32_16x16x32_bf16 v[64:67], v[4:7], v[72:75], v[124:127]
	v_mfma_f32_16x16x32_bf16 v[84:87], v[192:195], v[72:75], v[120:123]
	s_waitcnt lgkmcnt(5)
	v_mfma_f32_16x16x32_bf16 v[92:95], v[4:7], v[76:79], v[116:119]
	v_mfma_f32_16x16x32_bf16 v[112:115], v[192:195], v[76:79], v[112:115]
	s_waitcnt lgkmcnt(3)
	v_mfma_f32_16x16x32_bf16 v[108:111], v[4:7], v[152:155], v[108:111]
	v_mfma_f32_16x16x32_bf16 v[104:107], v[192:195], v[152:155], v[104:107]
	s_waitcnt lgkmcnt(1)
	v_mfma_f32_16x16x32_bf16 v[100:103], v[4:7], v[204:207], v[100:103]
	v_mfma_f32_16x16x32_bf16 v[96:99], v[192:195], v[204:207], v[96:99]
	v_mfma_f32_16x16x32_bf16 v[68:71], v[12:15], v[142:145], v[64:67]
	v_mfma_f32_16x16x32_bf16 v[64:67], v[138:141], v[142:145], v[84:87]
	v_mfma_f32_16x16x32_bf16 v[156:159], v[12:15], v[196:199], v[92:95]
	v_mfma_f32_16x16x32_bf16 v[148:151], v[138:141], v[196:199], v[112:115]
	v_mfma_f32_16x16x32_bf16 v[124:127], v[12:15], v[200:203], v[108:111]
	v_mfma_f32_16x16x32_bf16 v[116:119], v[138:141], v[200:203], v[104:107]
	s_waitcnt lgkmcnt(0)
	v_mfma_f32_16x16x32_bf16 v[92:95], v[12:15], v[208:211], v[100:103]
	v_mfma_f32_16x16x32_bf16 v[84:87], v[138:141], v[208:211], v[96:99]
	s_barrier
; #define LDA(dst, b, h) _Pragma("unroll") for (int m = 0; m < 4; ++m) _Pragma("unroll") for (int k = 0; k < 2; ++k) \
;     dst[m][k] = *reinterpret_cast<const bf16x8*>(SA(b, h) + lds_byte(wr * 64 + m * 16 + fr, k * 32 + fq * 8))
; #define LDB(dst, b, h) _Pragma("unroll") for (int n = 0; n < 2; ++n) _Pragma("unroll") for (int k = 0; k < 2; ++k) \
;     dst[n][k] = *reinterpret_cast<const bf16x8*>(SB(b, h) + lds_byte(wc * 32 + n * 16 + fr, k * 32 + fq * 8))
; #define WAIT_V(n) asm volatile("s_waitcnt vmcnt(" #n ")" ::: "memory")
; #define WAIT_L(n) asm volatile("s_waitcnt lgkmcnt(" #n ")" ::: "memory")
; #define BAR __builtin_amdgcn_s_barrier()
;     ...
;       LDB(B1, 1, 1); WAIT_V(0); BAR; WAIT_L(0); MMA(0, 1, At, B1); BAR;
;       LDA(At, 1, 1); BAR; WAIT_L(0); MMA(1, 0, At, B0); MMA(1, 1, At, B1); BAR; }
;     if (wr == 0) BAR;
	s_nop 0
	ds_read_b128 v[96:99], v133
	ds_read_b128 v[100:103], v134
	ds_read_b128 v[104:107], v135
	ds_read_b128 v[108:111], v136
	s_waitcnt vmcnt(0)
	s_barrier
	s_waitcnt lgkmcnt(1)
	v_mfma_f32_16x16x32_bf16 v[112:115], v[96:99], v[72:75], v[164:167]
	v_mfma_f32_16x16x32_bf16 v[72:75], v[104:107], v[72:75], v[88:91]
	v_mfma_f32_16x16x32_bf16 v[80:83], v[96:99], v[76:79], v[80:83]
	v_mfma_f32_16x16x32_bf16 v[88:91], v[104:107], v[76:79], v[168:171]
	v_mfma_f32_16x16x32_bf16 v[60:63], v[96:99], v[152:155], v[60:63]
	v_mfma_f32_16x16x32_bf16 v[56:59], v[104:107], v[152:155], v[56:59]
	v_mfma_f32_16x16x32_bf16 v[52:55], v[96:99], v[204:207], v[52:55]
	v_mfma_f32_16x16x32_bf16 v[48:51], v[104:107], v[204:207], v[48:51]
	s_waitcnt lgkmcnt(0)
	v_mfma_f32_16x16x32_bf16 v[76:79], v[100:103], v[142:145], v[112:115]
	v_mfma_f32_16x16x32_bf16 v[72:75], v[108:111], v[142:145], v[72:75]
	v_mfma_f32_16x16x32_bf16 v[152:155], v[100:103], v[196:199], v[80:83]
	v_mfma_f32_16x16x32_bf16 v[144:147], v[108:111], v[196:199], v[88:91]
	v_mfma_f32_16x16x32_bf16 v[120:123], v[100:103], v[200:203], v[60:63]
	v_mfma_f32_16x16x32_bf16 v[112:115], v[108:111], v[200:203], v[56:59]
	v_mfma_f32_16x16x32_bf16 v[88:91], v[100:103], v[208:211], v[52:55]
	v_mfma_f32_16x16x32_bf16 v[80:83], v[108:111], v[208:211], v[48:51]
	s_barrier
	s_nop 0
	ds_read_b128 v[48:51], v129 offset:49152
	ds_read_b128 v[134:137], v129 offset:50176
	ds_read_b128 v[56:59], v132 offset:49152
	ds_read_b128 v[164:167], v132 offset:50176
	ds_read_b128 v[168:171], v131 offset:49152
	ds_read_b128 v[196:199], v131 offset:50176
	ds_read_b128 v[200:203], v130 offset:49152
	ds_read_b128 v[130:133], v130 offset:50176
	s_barrier
	s_waitcnt lgkmcnt(0)
	v_mfma_f32_16x16x32_bf16 v[44:47], v[4:7], v[48:51], v[44:47]
	v_mfma_f32_16x16x32_bf16 v[40:43], v[192:195], v[48:51], v[40:43]
	v_mfma_f32_16x16x32_bf16 v[36:39], v[4:7], v[56:59], v[36:39]
	v_mfma_f32_16x16x32_bf16 v[32:35], v[192:195], v[56:59], v[32:35]
	v_mfma_f32_16x16x32_bf16 v[28:31], v[4:7], v[168:171], v[28:31]
	v_mfma_f32_16x16x32_bf16 v[24:27], v[192:195], v[168:171], v[24:27]
	v_mfma_f32_16x16x32_bf16 v[4:7], v[4:7], v[200:203], v[20:23]
	v_mfma_f32_16x16x32_bf16 v[16:19], v[192:195], v[200:203], v[16:19]
	v_mfma_f32_16x16x32_bf16 v[60:63], v[12:15], v[134:137], v[44:47]
	v_mfma_f32_16x16x32_bf16 v[52:55], v[138:141], v[134:137], v[40:43]
	v_mfma_f32_16x16x32_bf16 v[44:47], v[12:15], v[164:167], v[36:39]
	v_mfma_f32_16x16x32_bf16 v[36:39], v[138:141], v[164:167], v[32:35]
	v_mfma_f32_16x16x32_bf16 v[28:31], v[12:15], v[196:199], v[28:31]
	v_mfma_f32_16x16x32_bf16 v[20:23], v[138:141], v[196:199], v[24:27]
	v_mfma_f32_16x16x32_bf16 v[12:15], v[12:15], v[130:133], v[4:7]
	v_mfma_f32_16x16x32_bf16 v[4:7], v[138:141], v[130:133], v[16:19]
	v_mfma_f32_16x16x32_bf16 v[16:19], v[96:99], v[48:51], v[160:163]
	v_mfma_f32_16x16x32_bf16 v[8:11], v[104:107], v[48:51], v[8:11]
	v_mfma_f32_16x16x32_bf16 v[24:27], v[96:99], v[56:59], v[172:175]
	v_mfma_f32_16x16x32_bf16 v[0:3], v[104:107], v[56:59], v[0:3]
	v_mfma_f32_16x16x32_bf16 v[138:141], v[96:99], v[168:171], v[176:179]
	v_mfma_f32_16x16x32_bf16 v[160:163], v[104:107], v[168:171], v[180:183]
	v_mfma_f32_16x16x32_bf16 v[96:99], v[96:99], v[200:203], v[184:187]
	v_mfma_f32_16x16x32_bf16 v[104:107], v[104:107], v[200:203], v[188:191]
	v_mfma_f32_16x16x32_bf16 v[56:59], v[100:103], v[134:137], v[16:19]
	v_mfma_f32_16x16x32_bf16 v[48:51], v[108:111], v[134:137], v[8:11]
	v_mfma_f32_16x16x32_bf16 v[40:43], v[100:103], v[164:167], v[24:27]
	v_mfma_f32_16x16x32_bf16 v[32:35], v[108:111], v[164:167], v[0:3]
	v_mfma_f32_16x16x32_bf16 v[24:27], v[100:103], v[196:199], v[138:141]
	v_mfma_f32_16x16x32_bf16 v[16:19], v[108:111], v[196:199], v[160:163]
	v_mfma_f32_16x16x32_bf16 v[8:11], v[100:103], v[130:133], v[96:99]
	v_mfma_f32_16x16x32_bf16 v[0:3], v[108:111], v[130:133], v[104:107]
	v_cmp_gt_u32_e32 vcc, s60, v128
	s_barrier
	s_and_saveexec_b64 s[4:5], vcc
	s_cbranch_execz .LBB0_151
	s_barrier

; #define STAGE(P, RS, SOFF, OFF, kt) do { const int _so = (SOFF) + (kt) * (BK * 2); \
;     _Pragma("unroll") for (int _i = 0; _i < 2; ++_i) { \
;       __builtin_amdgcn_raw_ptr_buffer_load_lds(RS, (__attribute__((address_space(3))) void*)((P) + wave * 1024 + _i * 8192), 16, OFF[_i], _so, 0, 0); } } while (0)
; #define LDA(dst, b, h) _Pragma("unroll") for (int m = 0; m < 4; ++m) _Pragma("unroll") for (int k = 0; k < 2; ++k) \
;     dst[m][k] = *reinterpret_cast<const bf16x8*>(SA(b, h) + lds_byte(wr * 64 + m * 16 + fr, k * 32 + fq * 8))
; #define LDB(dst, b, h) _Pragma("unroll") for (int n = 0; n < 2; ++n) _Pragma("unroll") for (int k = 0; k < 2; ++k) \
;     dst[n][k] = *reinterpret_cast<const bf16x8*>(SB(b, h) + lds_byte(wc * 32 + n * 16 + fr, k * 32 + fq * 8))
; #define WAIT_V(n) asm volatile("s_waitcnt vmcnt(" #n ")" ::: "memory")
; #define WAIT_L(n) asm volatile("s_waitcnt lgkmcnt(" #n ")" ::: "memory")
; #define BAR __builtin_amdgcn_s_barrier()
; #define SCHED __builtin_amdgcn_sched_barrier(0)
;     ...
;     const int tid = opaque_tid(wave);
;     const int wid = tid >> 6, lane = tid & 63, wr = wid >> 2, wc = wid & 3, fr = lane & 15, fq = lane >> 4;
;     int offA[2], offB[2];
;     _Pragma("unroll") for (int i = 0; i < 2; ++i) {
;       int r, c; stage_rc(tid * 16 + i * 8192, r, c);
;       offA[i] = (r * lda + c) * 2; offB[i] = (r * ldb + c) * 2;
;     }
;     const int brow = pm * BM;
;     f32x4 acc[2][2][4][2];
;     _Pragma("unroll") for (int a = 0; a < 2; ++a) _Pragma("unroll") for (int b = 0; b < 2; ++b) _Pragma("unroll") for (int m = 0; m < 4; ++m) _Pragma("unroll") for (int n = 0; n < 2; ++n)
;       acc[a][b][m][n] = f32x4{0.f, 0.f, 0.f, 0.f};
;     bf16x8 At[4][2], B0[2][2], B1[2][2];
;     if (wr == 1) BAR;
;     if (first_tile) { WAIT_V(0); }
;     else if constexpr (mode == MODE_RESID_LN) { WAIT_V(0); }
;     else if constexpr (mode == MODE_SWIGLU) { WAIT_V(6); }
;     else if constexpr (mode == MODE_V) { WAIT_V(24); }
;     else { WAIT_V(12); }
;     first_tile = false;
;     BAR;
;     BAR;
;     for (int t = 0; t < nt - 2; t += 2) {
;       LDB(B0, 0, 0); SCHED; LDA(At, 0, 0); STAGE(SA(1, 1), rsA, sA1, offA, t + 1);
;       WAIT_L(8); BAR; WAIT_L(0); MMA(0, 0, At, B0); BAR; SCHED;
;       LDB(B1, 0, 1); STAGE(SB(0, 0), rsB, sB0, offB, t + 2);
.LBB0_209:
	v_bfe_i32 v4, v130, 27, 1
	v_lshlrev_b32_e32 v2, 4, v130
	v_lshrrev_b32_e32 v4, 22, v4
	v_add_u32_e32 v4, v2, v4
	v_and_b32_e32 v4, 0xfffffc00, v4
	v_sub_u32_e32 v4, v2, v4
	v_lshrrev_b32_e32 v5, 4, v4
	v_bitop3_b32 v4, v5, v4, 32 bitop3:0x6c
	v_ashrrev_i32_e32 v3, 31, v130
	v_ashrrev_i32_e32 v6, 31, v4
	v_lshrrev_b32_e32 v3, 26, v3
	v_lshrrev_b32_e32 v6, 26, v6
	v_add_u32_e32 v3, v130, v3
	v_add_u32_e32 v6, v4, v6
	v_ashrrev_i32_e32 v3, 6, v3
	v_lshrrev_b32_e32 v7, 6, v6
	v_and_b32_e32 v6, 0xc0, v6
	v_lshlrev_b32_e32 v5, 3, v3
	v_lshlrev_b32_e32 v3, 5, v3
	v_sub_u32_e32 v4, v4, v6
	v_and_b32_e32 v5, 0xffff0, v5
	v_and_b32_e32 v3, 32, v3
	v_ashrrev_i16_sdwa v4, v128, sext(v4) dst_sel:DWORD dst_unused:UNUSED_PAD src0_sel:DWORD src1_sel:BYTE_0
	v_add_u32_sdwa v3, v3, sext(v4) dst_sel:DWORD dst_unused:UNUSED_PAD src0_sel:DWORD src1_sel:WORD_0
	v_add_lshl_u32 v4, v7, v5, 12
	v_add_u32_e32 v2, 0x2000, v2
	v_lshl_add_u32 v143, v3, 1, v4
	v_ashrrev_i32_e32 v3, 31, v2
	v_lshrrev_b32_e32 v3, 22, v3
	v_add_u32_e32 v3, v2, v3
	v_ashrrev_i32_e32 v3, 10, v3
	v_mul_i32_i24_e32 v4, 0x400, v3
	v_sub_u32_e32 v2, v2, v4
	v_lshrrev_b32_e32 v4, 4, v2
	v_bitop3_b32 v2, v4, v2, 32 bitop3:0x6c
	v_ashrrev_i32_e32 v5, 31, v2
	v_lshrrev_b32_e32 v5, 26, v5
	v_add_u32_e32 v5, v2, v5
	v_lshrrev_b32_e32 v6, 6, v5
	v_and_b32_e32 v5, 0xc0, v5
	v_lshlrev_b32_e32 v4, 3, v3
	v_lshlrev_b32_e32 v3, 5, v3
	v_sub_u32_e32 v2, v2, v5
	v_and_b32_e32 v4, 0xffff0, v4
	v_and_b32_e32 v3, 32, v3
	v_ashrrev_i16_sdwa v2, v128, sext(v2) dst_sel:DWORD dst_unused:UNUSED_PAD src0_sel:DWORD src1_sel:BYTE_0
	v_add_u32_sdwa v2, v3, sext(v2) dst_sel:DWORD dst_unused:UNUSED_PAD src0_sel:DWORD src1_sel:WORD_0
	v_add_lshl_u32 v3, v6, v4, 12
	v_lshl_add_u32 v144, v2, 1, v3
	v_and_b32_e32 v3, 15, v0
	v_lshlrev_b32_e32 v5, 2, v0
	v_and_b32_e32 v2, 48, v0
	v_lshlrev_b32_e32 v3, 6, v3
	v_and_b32_e32 v5, 32, v5
	v_lshlrev_b32_e32 v0, 6, v0
	v_or_b32_e32 v4, v3, v2
	v_bitop3_b32 v3, v3, v5, v2 bitop3:0x36
	v_lshlrev_b32_e32 v6, 6, v130
	v_lshlrev_b32_e32 v1, 13, v1
	v_and_or_b32 v0, v0, s34, v2
	v_and_or_b32 v3, v6, s33, v3
	v_bitop3_b32 v0, v1, v0, v5 bitop3:0xf6
	v_or_b32_e32 v6, 0x400, v3
	v_or_b32_e32 v7, 0x800, v3
	v_or_b32_e32 v8, 0xc00, v3
	v_or_b32_e32 v134, 0x800, v0
	v_or_b32_e32 v133, 0x1000, v0
	v_or_b32_e32 v132, 0x1800, v0
	v_mov_b32_e32 v0, 0
	v_bitop3_b32 v131, v4, v1, v5 bitop3:0xde
	s_mov_b32 s16, -2
	s_mov_b32 s17, 0
	v_or_b32_e32 v149, 0x10000, v3
	v_or_b32_e32 v150, 0x10000, v6
	v_or_b32_e32 v151, 0x10000, v7
	v_or_b32_e32 v152, 0x10000, v8
	v_or_b32_e32 v145, 0x14000, v3
	v_or_b32_e32 v146, 0x14000, v6
	v_or_b32_e32 v147, 0x14000, v7
	v_or_b32_e32 v148, 0x14000, v8
	v_or_b32_e32 v139, 0x18000, v3
	v_or_b32_e32 v140, 0x18000, v6
	v_or_b32_e32 v141, 0x18000, v7
	v_or_b32_e32 v142, 0x18000, v8
	v_or_b32_e32 v135, 0x1c000, v3
	v_or_b32_e32 v136, 0x1c000, v6
	v_or_b32_e32 v137, 0x1c000, v7
	v_or_b32_e32 v138, 0x1c000, v8
	s_barrier
	s_barrier
	ds_read_b128 v[154:157], v149
	ds_read_b128 v[158:161], v150
	ds_read_b128 v[162:165], v151
	ds_read_b128 v[166:169], v152
	s_add_i32 s44, s38, s17
	s_add_i32 s10, s44, 0x80
	s_mov_b32 m0, s30
	ds_read_b128 v[170:173], v131
	ds_read_b128 v[174:177], v131 offset:1024
	ds_read_b128 v[178:181], v134
	ds_read_b128 v[182:185], v134 offset:1024
	ds_read_b128 v[186:189], v133
	ds_read_b128 v[190:193], v133 offset:1024
	ds_read_b128 v[194:197], v132
	ds_read_b128 v[198:201], v132 offset:1024
	buffer_load_dwordx4 v143, s[4:7], s10 offen lds
	s_mov_b32 m0, s31
	s_nop 0
	buffer_load_dwordx4 v144, s[4:7], s10 offen lds
	s_waitcnt lgkmcnt(8)
	s_barrier
	s_waitcnt lgkmcnt(0)
	v_mfma_f32_16x16x32_bf16 v[124:127], v[154:157], v[170:173], 0
	v_mfma_f32_16x16x32_bf16 v[124:127], v[158:161], v[174:177], v[124:127]
	v_mfma_f32_16x16x32_bf16 v[120:123], v[166:169], v[174:177], 0
	v_mfma_f32_16x16x32_bf16 v[120:123], v[162:165], v[170:173], v[120:123]
	v_mfma_f32_16x16x32_bf16 v[112:115], v[162:165], v[178:181], 0
	v_mfma_f32_16x16x32_bf16 v[112:115], v[166:169], v[182:185], v[112:115]
	v_mfma_f32_16x16x32_bf16 v[116:119], v[158:161], v[182:185], 0
	v_mfma_f32_16x16x32_bf16 v[116:119], v[154:157], v[178:181], v[116:119]
	v_mfma_f32_16x16x32_bf16 v[108:111], v[154:157], v[186:189], 0
	v_mfma_f32_16x16x32_bf16 v[108:111], v[158:161], v[190:193], v[108:111]
	v_mfma_f32_16x16x32_bf16 v[104:107], v[166:169], v[190:193], 0
	v_mfma_f32_16x16x32_bf16 v[104:107], v[162:165], v[186:189], v[104:107]
	v_mfma_f32_16x16x32_bf16 v[96:99], v[162:165], v[194:197], 0
	v_mfma_f32_16x16x32_bf16 v[96:99], v[166:169], v[198:201], v[96:99]
	v_mfma_f32_16x16x32_bf16 v[100:103], v[158:161], v[198:201], 0
	v_mfma_f32_16x16x32_bf16 v[100:103], v[154:157], v[194:197], v[100:103]
	s_barrier
	s_add_i32 s45, s40, s17
	s_add_i32 s46, s45, 0x100
	s_mov_b32 s10, s6
	s_mov_b32 s11, s7
	s_mov_b32 m0, s1
	ds_read_b128 v[202:205], v145
	ds_read_b128 v[206:209], v146
	ds_read_b128 v[210:213], v147
	ds_read_b128 v[214:217], v148
	buffer_load_dwordx4 v143, s[8:11], s46 offen lds
	s_mov_b32 m0, s3
	s_nop 0
	buffer_load_dwordx4 v144, s[8:11], s46 offen lds
	s_barrier
; #define STAGE(P, RS, SOFF, OFF, kt) do { const int _so = (SOFF) + (kt) * (BK * 2); \
;     _Pragma("unroll") for (int _i = 0; _i < 2; ++_i) { \
;       __builtin_amdgcn_raw_ptr_buffer_load_lds(RS, (__attribute__((address_space(3))) void*)((P) + wave * 1024 + _i * 8192), 16, OFF[_i], _so, 0, 0); } } while (0)
; #define LDA(dst, b, h) _Pragma("unroll") for (int m = 0; m < 4; ++m) _Pragma("unroll") for (int k = 0; k < 2; ++k) \
;     dst[m][k] = *reinterpret_cast<const bf16x8*>(SA(b, h) + lds_byte(wr * 64 + m * 16 + fr, k * 32 + fq * 8))
; #define LDB(dst, b, h) _Pragma("unroll") for (int n = 0; n < 2; ++n) _Pragma("unroll") for (int k = 0; k < 2; ++k) \
;     dst[n][k] = *reinterpret_cast<const bf16x8*>(SB(b, h) + lds_byte(wc * 32 + n * 16 + fr, k * 32 + fq * 8))
; #define WAIT_V(n) asm volatile("s_waitcnt vmcnt(" #n ")" ::: "memory")
; #define WAIT_L(n) asm volatile("s_waitcnt lgkmcnt(" #n ")" ::: "memory")
; #define BAR __builtin_amdgcn_s_barrier()
; #define SCHED __builtin_amdgcn_sched_barrier(0)
;     ...
;       BAR; WAIT_L(0); MMA(0, 1, At, B1); BAR;
;       LDA(At, 0, 1); STAGE(SA(0, 0), rsA, sA0, offA, t + 2);
;       BAR; WAIT_L(0); MMA(1, 0, At, B0); BAR; SCHED;
;       STAGE(SB(0, 1), rsB, sB1, offB, t + 2);
;       WAIT_V(6); BAR; MMA(1, 1, At, B1); BAR;
;       LDB(B0, 1, 0); SCHED; LDA(At, 1, 0); STAGE(SA(0, 1), rsA, sA1, offA, t + 2);
;       WAIT_L(8); BAR; WAIT_L(0); MMA(0, 0, At, B0); BAR; SCHED;
	s_waitcnt lgkmcnt(2)
	v_mfma_f32_16x16x32_bf16 v[92:95], v[202:205], v[170:173], 0
	v_mfma_f32_16x16x32_bf16 v[92:95], v[206:209], v[174:177], v[92:95]
	s_waitcnt lgkmcnt(0)
	v_mfma_f32_16x16x32_bf16 v[88:91], v[214:217], v[174:177], 0
	v_mfma_f32_16x16x32_bf16 v[88:91], v[210:213], v[170:173], v[88:91]
	v_mfma_f32_16x16x32_bf16 v[80:83], v[210:213], v[178:181], 0
	v_mfma_f32_16x16x32_bf16 v[80:83], v[214:217], v[182:185], v[80:83]
	v_mfma_f32_16x16x32_bf16 v[84:87], v[206:209], v[182:185], 0
	v_mfma_f32_16x16x32_bf16 v[84:87], v[202:205], v[178:181], v[84:87]
	v_mfma_f32_16x16x32_bf16 v[76:79], v[202:205], v[186:189], 0
	v_mfma_f32_16x16x32_bf16 v[76:79], v[206:209], v[190:193], v[76:79]
	v_mfma_f32_16x16x32_bf16 v[72:75], v[214:217], v[190:193], 0
	v_mfma_f32_16x16x32_bf16 v[72:75], v[210:213], v[186:189], v[72:75]
	v_mfma_f32_16x16x32_bf16 v[64:67], v[210:213], v[194:197], 0
	v_mfma_f32_16x16x32_bf16 v[64:67], v[214:217], v[198:201], v[64:67]
	v_mfma_f32_16x16x32_bf16 v[68:71], v[206:209], v[198:201], 0
	v_mfma_f32_16x16x32_bf16 v[68:71], v[202:205], v[194:197], v[68:71]
	s_barrier
	s_add_i32 s46, s39, s17
	s_add_i32 s47, s46, 0x100
	s_mov_b32 m0, s0
	ds_read_b128 v[170:173], v131 offset:16384
	ds_read_b128 v[174:177], v131 offset:17408
	ds_read_b128 v[178:181], v134 offset:16384
	ds_read_b128 v[182:185], v134 offset:17408
	ds_read_b128 v[186:189], v133 offset:16384
	ds_read_b128 v[190:193], v133 offset:17408
	ds_read_b128 v[194:197], v132 offset:16384
	ds_read_b128 v[198:201], v132 offset:17408
	buffer_load_dwordx4 v143, s[4:7], s47 offen lds
	s_mov_b32 m0, s18
	s_nop 0
	buffer_load_dwordx4 v144, s[4:7], s47 offen lds
	s_barrier
	s_waitcnt lgkmcnt(6)
	v_mfma_f32_16x16x32_bf16 v[60:63], v[154:157], v[170:173], 0
	v_mfma_f32_16x16x32_bf16 v[60:63], v[158:161], v[174:177], v[60:63]
	v_mfma_f32_16x16x32_bf16 v[56:59], v[166:169], v[174:177], 0
	v_mfma_f32_16x16x32_bf16 v[56:59], v[162:165], v[170:173], v[56:59]
	s_waitcnt lgkmcnt(4)
	v_mfma_f32_16x16x32_bf16 v[48:51], v[162:165], v[178:181], 0
	v_mfma_f32_16x16x32_bf16 v[48:51], v[166:169], v[182:185], v[48:51]
	v_mfma_f32_16x16x32_bf16 v[52:55], v[158:161], v[182:185], 0
	v_mfma_f32_16x16x32_bf16 v[52:55], v[154:157], v[178:181], v[52:55]
	s_waitcnt lgkmcnt(2)
	v_mfma_f32_16x16x32_bf16 v[44:47], v[154:157], v[186:189], 0
	v_mfma_f32_16x16x32_bf16 v[44:47], v[158:161], v[190:193], v[44:47]
	v_mfma_f32_16x16x32_bf16 v[40:43], v[166:169], v[190:193], 0
	v_mfma_f32_16x16x32_bf16 v[40:43], v[162:165], v[186:189], v[40:43]
	s_waitcnt lgkmcnt(0)
	v_mfma_f32_16x16x32_bf16 v[32:35], v[162:165], v[194:197], 0
	v_mfma_f32_16x16x32_bf16 v[32:35], v[166:169], v[198:201], v[32:35]
	v_mfma_f32_16x16x32_bf16 v[36:39], v[158:161], v[198:201], 0
	v_mfma_f32_16x16x32_bf16 v[36:39], v[154:157], v[194:197], v[36:39]
	s_barrier
	s_add_i32 s47, s41, s17
	s_add_i32 s48, s47, 0x100
	s_mov_b32 m0, s19
	s_nop 0
	buffer_load_dwordx4 v143, s[8:11], s48 offen lds
	s_mov_b32 m0, s20
	s_nop 0
	buffer_load_dwordx4 v144, s[8:11], s48 offen lds
	s_waitcnt vmcnt(6)
	s_barrier
	v_mfma_f32_16x16x32_bf16 v[28:31], v[202:205], v[170:173], 0
	v_mfma_f32_16x16x32_bf16 v[28:31], v[206:209], v[174:177], v[28:31]
	v_mfma_f32_16x16x32_bf16 v[24:27], v[214:217], v[174:177], 0
	v_mfma_f32_16x16x32_bf16 v[24:27], v[210:213], v[170:173], v[24:27]
	v_mfma_f32_16x16x32_bf16 v[16:19], v[210:213], v[178:181], 0
	v_mfma_f32_16x16x32_bf16 v[16:19], v[214:217], v[182:185], v[16:19]
	v_mfma_f32_16x16x32_bf16 v[20:23], v[206:209], v[182:185], 0
	v_mfma_f32_16x16x32_bf16 v[20:23], v[202:205], v[178:181], v[20:23]
	v_mfma_f32_16x16x32_bf16 v[12:15], v[202:205], v[186:189], 0
	v_mfma_f32_16x16x32_bf16 v[12:15], v[206:209], v[190:193], v[12:15]
	v_mfma_f32_16x16x32_bf16 v[8:11], v[214:217], v[190:193], 0
	v_mfma_f32_16x16x32_bf16 v[8:11], v[210:213], v[186:189], v[8:11]
	v_mfma_f32_16x16x32_bf16 v[0:3], v[210:213], v[194:197], 0
	v_mfma_f32_16x16x32_bf16 v[0:3], v[214:217], v[198:201], v[0:3]
	v_mfma_f32_16x16x32_bf16 v[4:7], v[206:209], v[198:201], 0
	v_mfma_f32_16x16x32_bf16 v[4:7], v[202:205], v[194:197], v[4:7]
	s_barrier
	ds_read_b128 v[154:157], v139
	ds_read_b128 v[158:161], v140
	ds_read_b128 v[162:165], v141
	ds_read_b128 v[166:169], v142
	s_addk_i32 s44, 0x100
	s_mov_b32 m0, s21
	ds_read_b128 v[170:173], v131 offset:32768
	ds_read_b128 v[174:177], v131 offset:33792
	ds_read_b128 v[178:181], v134 offset:32768
	ds_read_b128 v[182:185], v134 offset:33792
	ds_read_b128 v[186:189], v133 offset:32768
	ds_read_b128 v[190:193], v133 offset:33792
	ds_read_b128 v[194:197], v132 offset:32768
	ds_read_b128 v[198:201], v132 offset:33792
	buffer_load_dwordx4 v143, s[4:7], s44 offen lds
	s_mov_b32 m0, s22
	s_nop 0
	buffer_load_dwordx4 v144, s[4:7], s44 offen lds
	s_waitcnt lgkmcnt(8)
	s_barrier
; #define STAGE(P, RS, SOFF, OFF, kt) do { const int _so = (SOFF) + (kt) * (BK * 2); \
;     _Pragma("unroll") for (int _i = 0; _i < 2; ++_i) { \
;       __builtin_amdgcn_raw_ptr_buffer_load_lds(RS, (__attribute__((address_space(3))) void*)((P) + wave * 1024 + _i * 8192), 16, OFF[_i], _so, 0, 0); } } while (0)
; #define LDA(dst, b, h) _Pragma("unroll") for (int m = 0; m < 4; ++m) _Pragma("unroll") for (int k = 0; k < 2; ++k) \
;     dst[m][k] = *reinterpret_cast<const bf16x8*>(SA(b, h) + lds_byte(wr * 64 + m * 16 + fr, k * 32 + fq * 8))
; #define LDB(dst, b, h) _Pragma("unroll") for (int n = 0; n < 2; ++n) _Pragma("unroll") for (int k = 0; k < 2; ++k) \
;     dst[n][k] = *reinterpret_cast<const bf16x8*>(SB(b, h) + lds_byte(wc * 32 + n * 16 + fr, k * 32 + fq * 8))
; #define WAIT_V(n) asm volatile("s_waitcnt vmcnt(" #n ")" ::: "memory")
; #define WAIT_L(n) asm volatile("s_waitcnt lgkmcnt(" #n ")" ::: "memory")
; #define BAR __builtin_amdgcn_s_barrier()
; #define SCHED __builtin_amdgcn_sched_barrier(0)
;     ...
;       WAIT_L(8); BAR; WAIT_L(0); MMA(0, 0, At, B0); BAR; SCHED;
;       LDB(B1, 1, 1); STAGE(SB(1, 0), rsB, sB0, offB, t + 3);
;       BAR; WAIT_L(0); MMA(0, 1, At, B1); BAR;
;       LDA(At, 1, 1); STAGE(SA(1, 0), rsA, sA0, offA, t + 3);
;       BAR; WAIT_L(0); MMA(1, 0, At, B0); BAR; SCHED;
;       STAGE(SB(1, 1), rsB, sB1, offB, t + 3);
;       WAIT_V(6); BAR; MMA(1, 1, At, B1); BAR;
	s_waitcnt lgkmcnt(6)
	v_mfma_f32_16x16x32_bf16 v[124:127], v[154:157], v[170:173], v[124:127]
	v_mfma_f32_16x16x32_bf16 v[124:127], v[158:161], v[174:177], v[124:127]
	v_mfma_f32_16x16x32_bf16 v[120:123], v[166:169], v[174:177], v[120:123]
	v_mfma_f32_16x16x32_bf16 v[120:123], v[162:165], v[170:173], v[120:123]
	s_waitcnt lgkmcnt(4)
	v_mfma_f32_16x16x32_bf16 v[112:115], v[162:165], v[178:181], v[112:115]
	v_mfma_f32_16x16x32_bf16 v[112:115], v[166:169], v[182:185], v[112:115]
	v_mfma_f32_16x16x32_bf16 v[116:119], v[158:161], v[182:185], v[116:119]
	v_mfma_f32_16x16x32_bf16 v[116:119], v[154:157], v[178:181], v[116:119]
	s_waitcnt lgkmcnt(2)
	v_mfma_f32_16x16x32_bf16 v[108:111], v[154:157], v[186:189], v[108:111]
	v_mfma_f32_16x16x32_bf16 v[108:111], v[158:161], v[190:193], v[108:111]
	v_mfma_f32_16x16x32_bf16 v[104:107], v[166:169], v[190:193], v[104:107]
	v_mfma_f32_16x16x32_bf16 v[104:107], v[162:165], v[186:189], v[104:107]
	s_waitcnt lgkmcnt(0)
	v_mfma_f32_16x16x32_bf16 v[96:99], v[162:165], v[194:197], v[96:99]
	v_mfma_f32_16x16x32_bf16 v[96:99], v[166:169], v[198:201], v[96:99]
	v_mfma_f32_16x16x32_bf16 v[100:103], v[158:161], v[198:201], v[100:103]
	v_mfma_f32_16x16x32_bf16 v[100:103], v[154:157], v[194:197], v[100:103]
	s_barrier
	s_addk_i32 s45, 0x180
	s_mov_b32 m0, s23
	ds_read_b128 v[202:205], v135
	ds_read_b128 v[206:209], v136
	ds_read_b128 v[210:213], v137
	ds_read_b128 v[214:217], v138
	buffer_load_dwordx4 v143, s[8:11], s45 offen lds
	s_mov_b32 m0, s24
	s_nop 0
	buffer_load_dwordx4 v144, s[8:11], s45 offen lds
	s_barrier
	s_waitcnt lgkmcnt(2)
	v_mfma_f32_16x16x32_bf16 v[92:95], v[202:205], v[170:173], v[92:95]
	v_mfma_f32_16x16x32_bf16 v[92:95], v[206:209], v[174:177], v[92:95]
	s_waitcnt lgkmcnt(0)
	v_mfma_f32_16x16x32_bf16 v[88:91], v[214:217], v[174:177], v[88:91]
	v_mfma_f32_16x16x32_bf16 v[88:91], v[210:213], v[170:173], v[88:91]
	v_mfma_f32_16x16x32_bf16 v[80:83], v[210:213], v[178:181], v[80:83]
	v_mfma_f32_16x16x32_bf16 v[80:83], v[214:217], v[182:185], v[80:83]
	v_mfma_f32_16x16x32_bf16 v[84:87], v[206:209], v[182:185], v[84:87]
	v_mfma_f32_16x16x32_bf16 v[84:87], v[202:205], v[178:181], v[84:87]
	v_mfma_f32_16x16x32_bf16 v[76:79], v[202:205], v[186:189], v[76:79]
	v_mfma_f32_16x16x32_bf16 v[76:79], v[206:209], v[190:193], v[76:79]
	v_mfma_f32_16x16x32_bf16 v[72:75], v[214:217], v[190:193], v[72:75]
	v_mfma_f32_16x16x32_bf16 v[72:75], v[210:213], v[186:189], v[72:75]
	v_mfma_f32_16x16x32_bf16 v[64:67], v[210:213], v[194:197], v[64:67]
	v_mfma_f32_16x16x32_bf16 v[64:67], v[214:217], v[198:201], v[64:67]
	v_mfma_f32_16x16x32_bf16 v[68:71], v[206:209], v[198:201], v[68:71]
	v_mfma_f32_16x16x32_bf16 v[68:71], v[202:205], v[194:197], v[68:71]
	s_barrier
	s_addk_i32 s46, 0x180
	s_mov_b32 m0, s25
	ds_read_b128 v[170:173], v131 offset:49152
	ds_read_b128 v[174:177], v131 offset:50176
	ds_read_b128 v[178:181], v134 offset:49152
	ds_read_b128 v[182:185], v134 offset:50176
	ds_read_b128 v[186:189], v133 offset:49152
	ds_read_b128 v[190:193], v133 offset:50176
	ds_read_b128 v[194:197], v132 offset:49152
	ds_read_b128 v[198:201], v132 offset:50176
	buffer_load_dwordx4 v143, s[4:7], s46 offen lds
	s_mov_b32 m0, s26
	s_nop 0
	buffer_load_dwordx4 v144, s[4:7], s46 offen lds
	s_barrier
	s_waitcnt lgkmcnt(6)
	v_mfma_f32_16x16x32_bf16 v[60:63], v[154:157], v[170:173], v[60:63]
	v_mfma_f32_16x16x32_bf16 v[60:63], v[158:161], v[174:177], v[60:63]
	v_mfma_f32_16x16x32_bf16 v[56:59], v[166:169], v[174:177], v[56:59]
	v_mfma_f32_16x16x32_bf16 v[56:59], v[162:165], v[170:173], v[56:59]
	s_waitcnt lgkmcnt(4)
	v_mfma_f32_16x16x32_bf16 v[48:51], v[162:165], v[178:181], v[48:51]
	v_mfma_f32_16x16x32_bf16 v[48:51], v[166:169], v[182:185], v[48:51]
	v_mfma_f32_16x16x32_bf16 v[52:55], v[158:161], v[182:185], v[52:55]
	v_mfma_f32_16x16x32_bf16 v[52:55], v[154:157], v[178:181], v[52:55]
	s_waitcnt lgkmcnt(2)
	v_mfma_f32_16x16x32_bf16 v[44:47], v[154:157], v[186:189], v[44:47]
	v_mfma_f32_16x16x32_bf16 v[44:47], v[158:161], v[190:193], v[44:47]
	v_mfma_f32_16x16x32_bf16 v[40:43], v[166:169], v[190:193], v[40:43]
	v_mfma_f32_16x16x32_bf16 v[40:43], v[162:165], v[186:189], v[40:43]
	s_waitcnt lgkmcnt(0)
	v_mfma_f32_16x16x32_bf16 v[32:35], v[162:165], v[194:197], v[32:35]
	v_mfma_f32_16x16x32_bf16 v[32:35], v[166:169], v[198:201], v[32:35]
	v_mfma_f32_16x16x32_bf16 v[36:39], v[158:161], v[198:201], v[36:39]
	v_mfma_f32_16x16x32_bf16 v[36:39], v[154:157], v[194:197], v[36:39]
	s_barrier
	s_addk_i32 s47, 0x180
	s_mov_b32 m0, s27
	s_nop 0
	buffer_load_dwordx4 v143, s[8:11], s47 offen lds
	s_mov_b32 m0, s28
	s_nop 0
	buffer_load_dwordx4 v144, s[8:11], s47 offen lds
	s_add_i32 s16, s16, 2
	s_addk_i32 s17, 0x100
	s_cmp_gt_u32 s16, 27
	s_cbranch_scc0 .LBB0_210
	s_branch .Lmy_post_210

; #define STAGE(P, RS, SOFF, OFF, kt) do { const int _so = (SOFF) + (kt) * (BK * 2); \
;     _Pragma("unroll") for (int _i = 0; _i < 2; ++_i) { \
;       __builtin_amdgcn_raw_ptr_buffer_load_lds(RS, (__attribute__((address_space(3))) void*)((P) + wave * 1024 + _i * 8192), 16, OFF[_i], _so, 0, 0); } } while (0)
; #define LDA(dst, b, h) _Pragma("unroll") for (int m = 0; m < 4; ++m) _Pragma("unroll") for (int k = 0; k < 2; ++k) \
;     dst[m][k] = *reinterpret_cast<const bf16x8*>(SA(b, h) + lds_byte(wr * 64 + m * 16 + fr, k * 32 + fq * 8))
; #define LDB(dst, b, h) _Pragma("unroll") for (int n = 0; n < 2; ++n) _Pragma("unroll") for (int k = 0; k < 2; ++k) \
;     dst[n][k] = *reinterpret_cast<const bf16x8*>(SB(b, h) + lds_byte(wc * 32 + n * 16 + fr, k * 32 + fq * 8))
; #define WAIT_V(n) asm volatile("s_waitcnt vmcnt(" #n ")" ::: "memory")
; #define WAIT_L(n) asm volatile("s_waitcnt lgkmcnt(" #n ")" ::: "memory")
; #define BAR __builtin_amdgcn_s_barrier()
; #define SCHED __builtin_amdgcn_sched_barrier(0)
;     ...
;       LDB(B0, 0, 0); SCHED; LDA(At, 0, 0); STAGE(SA(1, 1), rsA, sA1, offA, t + 1);
;       WAIT_L(8); BAR; WAIT_L(0); MMA(0, 0, At, B0); BAR; SCHED;
;       LDB(B1, 0, 1); STAGE(SB(0, 0), rsB, sB0, offB, t + 2);
;       BAR; WAIT_L(0); MMA(0, 1, At, B1); BAR;
;       LDA(At, 0, 1); STAGE(SA(0, 0), rsA, sA0, offA, t + 2);
;       BAR; WAIT_L(0); MMA(1, 0, At, B0); BAR; SCHED;
;       STAGE(SB(0, 1), rsB, sB1, offB, t + 2);
;       WAIT_V(6); BAR; MMA(1, 1, At, B1); BAR;
.Lmy_rot_210:
	ds_read_b128 v[154:157], v149
	ds_read_b128 v[158:161], v150
	ds_read_b128 v[162:165], v151
	ds_read_b128 v[166:169], v152
	s_add_i32 s44, s38, s17
	s_add_i32 s10, s44, 0x80
	s_mov_b32 m0, s30
	ds_read_b128 v[170:173], v131
	ds_read_b128 v[174:177], v131 offset:1024
	ds_read_b128 v[178:181], v134
	ds_read_b128 v[182:185], v134 offset:1024
	ds_read_b128 v[186:189], v133
	ds_read_b128 v[190:193], v133 offset:1024
	ds_read_b128 v[194:197], v132
	ds_read_b128 v[198:201], v132 offset:1024
	buffer_load_dwordx4 v143, s[4:7], s10 offen lds
	s_mov_b32 m0, s31
	s_nop 0
	buffer_load_dwordx4 v144, s[4:7], s10 offen lds
	s_waitcnt lgkmcnt(8)
	s_barrier
	s_waitcnt lgkmcnt(0)
	v_mfma_f32_16x16x32_bf16 v[124:127], v[154:157], v[170:173], v[124:127]
	v_mfma_f32_16x16x32_bf16 v[124:127], v[158:161], v[174:177], v[124:127]
	v_mfma_f32_16x16x32_bf16 v[120:123], v[166:169], v[174:177], v[120:123]
	v_mfma_f32_16x16x32_bf16 v[120:123], v[162:165], v[170:173], v[120:123]
	v_mfma_f32_16x16x32_bf16 v[112:115], v[162:165], v[178:181], v[112:115]
	v_mfma_f32_16x16x32_bf16 v[112:115], v[166:169], v[182:185], v[112:115]
	v_mfma_f32_16x16x32_bf16 v[116:119], v[158:161], v[182:185], v[116:119]
	v_mfma_f32_16x16x32_bf16 v[116:119], v[154:157], v[178:181], v[116:119]
	v_mfma_f32_16x16x32_bf16 v[108:111], v[154:157], v[186:189], v[108:111]
	v_mfma_f32_16x16x32_bf16 v[108:111], v[158:161], v[190:193], v[108:111]
	v_mfma_f32_16x16x32_bf16 v[104:107], v[166:169], v[190:193], v[104:107]
	v_mfma_f32_16x16x32_bf16 v[104:107], v[162:165], v[186:189], v[104:107]
	v_mfma_f32_16x16x32_bf16 v[96:99], v[162:165], v[194:197], v[96:99]
	v_mfma_f32_16x16x32_bf16 v[96:99], v[166:169], v[198:201], v[96:99]
	v_mfma_f32_16x16x32_bf16 v[100:103], v[158:161], v[198:201], v[100:103]
	v_mfma_f32_16x16x32_bf16 v[100:103], v[154:157], v[194:197], v[100:103]
	s_barrier
	s_add_i32 s45, s40, s17
	s_add_i32 s46, s45, 0x100
	s_mov_b32 s10, s6
	s_mov_b32 s11, s7
	s_mov_b32 m0, s1
	ds_read_b128 v[202:205], v145
	ds_read_b128 v[206:209], v146
	ds_read_b128 v[210:213], v147
	ds_read_b128 v[214:217], v148
	buffer_load_dwordx4 v143, s[8:11], s46 offen lds
	s_mov_b32 m0, s3
	s_nop 0
	buffer_load_dwordx4 v144, s[8:11], s46 offen lds
	s_barrier
	s_waitcnt lgkmcnt(2)
	v_mfma_f32_16x16x32_bf16 v[92:95], v[202:205], v[170:173], v[92:95]
	v_mfma_f32_16x16x32_bf16 v[92:95], v[206:209], v[174:177], v[92:95]
	s_waitcnt lgkmcnt(0)
	v_mfma_f32_16x16x32_bf16 v[88:91], v[214:217], v[174:177], v[88:91]
	v_mfma_f32_16x16x32_bf16 v[88:91], v[210:213], v[170:173], v[88:91]
	v_mfma_f32_16x16x32_bf16 v[80:83], v[210:213], v[178:181], v[80:83]
	v_mfma_f32_16x16x32_bf16 v[80:83], v[214:217], v[182:185], v[80:83]
	v_mfma_f32_16x16x32_bf16 v[84:87], v[206:209], v[182:185], v[84:87]
	v_mfma_f32_16x16x32_bf16 v[84:87], v[202:205], v[178:181], v[84:87]
	v_mfma_f32_16x16x32_bf16 v[76:79], v[202:205], v[186:189], v[76:79]
	v_mfma_f32_16x16x32_bf16 v[76:79], v[206:209], v[190:193], v[76:79]
	v_mfma_f32_16x16x32_bf16 v[72:75], v[214:217], v[190:193], v[72:75]
	v_mfma_f32_16x16x32_bf16 v[72:75], v[210:213], v[186:189], v[72:75]
	v_mfma_f32_16x16x32_bf16 v[64:67], v[210:213], v[194:197], v[64:67]
	v_mfma_f32_16x16x32_bf16 v[64:67], v[214:217], v[198:201], v[64:67]
	v_mfma_f32_16x16x32_bf16 v[68:71], v[206:209], v[198:201], v[68:71]
	v_mfma_f32_16x16x32_bf16 v[68:71], v[202:205], v[194:197], v[68:71]
	s_barrier
	s_add_i32 s46, s39, s17
	s_add_i32 s47, s46, 0x100
	s_mov_b32 m0, s0
	ds_read_b128 v[170:173], v131 offset:16384
	ds_read_b128 v[174:177], v131 offset:17408
	ds_read_b128 v[178:181], v134 offset:16384
	ds_read_b128 v[182:185], v134 offset:17408
	ds_read_b128 v[186:189], v133 offset:16384
	ds_read_b128 v[190:193], v133 offset:17408
	ds_read_b128 v[194:197], v132 offset:16384
	ds_read_b128 v[198:201], v132 offset:17408
	buffer_load_dwordx4 v143, s[4:7], s47 offen lds
	s_mov_b32 m0, s18
	s_nop 0
	buffer_load_dwordx4 v144, s[4:7], s47 offen lds
	s_barrier
	s_waitcnt lgkmcnt(6)
	v_mfma_f32_16x16x32_bf16 v[60:63], v[154:157], v[170:173], v[60:63]
	v_mfma_f32_16x16x32_bf16 v[60:63], v[158:161], v[174:177], v[60:63]
	v_mfma_f32_16x16x32_bf16 v[56:59], v[166:169], v[174:177], v[56:59]
	v_mfma_f32_16x16x32_bf16 v[56:59], v[162:165], v[170:173], v[56:59]
	s_waitcnt lgkmcnt(4)
	v_mfma_f32_16x16x32_bf16 v[48:51], v[162:165], v[178:181], v[48:51]
	v_mfma_f32_16x16x32_bf16 v[48:51], v[166:169], v[182:185], v[48:51]
	v_mfma_f32_16x16x32_bf16 v[52:55], v[158:161], v[182:185], v[52:55]
	v_mfma_f32_16x16x32_bf16 v[52:55], v[154:157], v[178:181], v[52:55]
	s_waitcnt lgkmcnt(2)
	v_mfma_f32_16x16x32_bf16 v[44:47], v[154:157], v[186:189], v[44:47]
	v_mfma_f32_16x16x32_bf16 v[44:47], v[158:161], v[190:193], v[44:47]
	v_mfma_f32_16x16x32_bf16 v[40:43], v[166:169], v[190:193], v[40:43]
	v_mfma_f32_16x16x32_bf16 v[40:43], v[162:165], v[186:189], v[40:43]
	s_waitcnt lgkmcnt(0)
	v_mfma_f32_16x16x32_bf16 v[32:35], v[162:165], v[194:197], v[32:35]
	v_mfma_f32_16x16x32_bf16 v[32:35], v[166:169], v[198:201], v[32:35]
	v_mfma_f32_16x16x32_bf16 v[36:39], v[158:161], v[198:201], v[36:39]
	v_mfma_f32_16x16x32_bf16 v[36:39], v[154:157], v[194:197], v[36:39]
	s_barrier
	s_add_i32 s47, s41, s17
	s_add_i32 s48, s47, 0x100
	s_mov_b32 m0, s19
	s_nop 0
	buffer_load_dwordx4 v143, s[8:11], s48 offen lds
	s_mov_b32 m0, s20
	s_nop 0
	buffer_load_dwordx4 v144, s[8:11], s48 offen lds
	s_waitcnt vmcnt(6)
	s_barrier
; #define STAGE(P, RS, SOFF, OFF, kt) do { const int _so = (SOFF) + (kt) * (BK * 2); \
;     _Pragma("unroll") for (int _i = 0; _i < 2; ++_i) { \
;       __builtin_amdgcn_raw_ptr_buffer_load_lds(RS, (__attribute__((address_space(3))) void*)((P) + wave * 1024 + _i * 8192), 16, OFF[_i], _so, 0, 0); } } while (0)
; #define LDA(dst, b, h) _Pragma("unroll") for (int m = 0; m < 4; ++m) _Pragma("unroll") for (int k = 0; k < 2; ++k) \
;     dst[m][k] = *reinterpret_cast<const bf16x8*>(SA(b, h) + lds_byte(wr * 64 + m * 16 + fr, k * 32 + fq * 8))
; #define LDB(dst, b, h) _Pragma("unroll") for (int n = 0; n < 2; ++n) _Pragma("unroll") for (int k = 0; k < 2; ++k) \
;     dst[n][k] = *reinterpret_cast<const bf16x8*>(SB(b, h) + lds_byte(wc * 32 + n * 16 + fr, k * 32 + fq * 8))
; #define WAIT_V(n) asm volatile("s_waitcnt vmcnt(" #n ")" ::: "memory")
; #define WAIT_L(n) asm volatile("s_waitcnt lgkmcnt(" #n ")" ::: "memory")
; #define BAR __builtin_amdgcn_s_barrier()
; #define SCHED __builtin_amdgcn_sched_barrier(0)
;     ...
;       WAIT_V(6); BAR; MMA(1, 1, At, B1); BAR;
;       LDB(B0, 1, 0); SCHED; LDA(At, 1, 0); STAGE(SA(0, 1), rsA, sA1, offA, t + 2);
;       WAIT_L(8); BAR; WAIT_L(0); MMA(0, 0, At, B0); BAR; SCHED;
;       LDB(B1, 1, 1); STAGE(SB(1, 0), rsB, sB0, offB, t + 3);
;       BAR; WAIT_L(0); MMA(0, 1, At, B1); BAR;
;       LDA(At, 1, 1); STAGE(SA(1, 0), rsA, sA0, offA, t + 3);
;       BAR; WAIT_L(0); MMA(1, 0, At, B0); BAR; SCHED;
;       STAGE(SB(1, 1), rsB, sB1, offB, t + 3);
;       WAIT_V(6); BAR; MMA(1, 1, At, B1); BAR;
	v_mfma_f32_16x16x32_bf16 v[28:31], v[202:205], v[170:173], v[28:31]
	v_mfma_f32_16x16x32_bf16 v[28:31], v[206:209], v[174:177], v[28:31]
	v_mfma_f32_16x16x32_bf16 v[24:27], v[214:217], v[174:177], v[24:27]
	v_mfma_f32_16x16x32_bf16 v[24:27], v[210:213], v[170:173], v[24:27]
	v_mfma_f32_16x16x32_bf16 v[16:19], v[210:213], v[178:181], v[16:19]
	v_mfma_f32_16x16x32_bf16 v[16:19], v[214:217], v[182:185], v[16:19]
	v_mfma_f32_16x16x32_bf16 v[20:23], v[206:209], v[182:185], v[20:23]
	v_mfma_f32_16x16x32_bf16 v[20:23], v[202:205], v[178:181], v[20:23]
	v_mfma_f32_16x16x32_bf16 v[12:15], v[202:205], v[186:189], v[12:15]
	v_mfma_f32_16x16x32_bf16 v[12:15], v[206:209], v[190:193], v[12:15]
	v_mfma_f32_16x16x32_bf16 v[8:11], v[214:217], v[190:193], v[8:11]
	v_mfma_f32_16x16x32_bf16 v[8:11], v[210:213], v[186:189], v[8:11]
	v_mfma_f32_16x16x32_bf16 v[0:3], v[210:213], v[194:197], v[0:3]
	v_mfma_f32_16x16x32_bf16 v[0:3], v[214:217], v[198:201], v[0:3]
	v_mfma_f32_16x16x32_bf16 v[4:7], v[206:209], v[198:201], v[4:7]
	v_mfma_f32_16x16x32_bf16 v[4:7], v[202:205], v[194:197], v[4:7]
	s_barrier
	ds_read_b128 v[154:157], v139
	ds_read_b128 v[158:161], v140
	ds_read_b128 v[162:165], v141
	ds_read_b128 v[166:169], v142
	s_addk_i32 s44, 0x100
	s_mov_b32 m0, s21
	ds_read_b128 v[170:173], v131 offset:32768
	ds_read_b128 v[174:177], v131 offset:33792
	ds_read_b128 v[178:181], v134 offset:32768
	ds_read_b128 v[182:185], v134 offset:33792
	ds_read_b128 v[186:189], v133 offset:32768
	ds_read_b128 v[190:193], v133 offset:33792
	ds_read_b128 v[194:197], v132 offset:32768
	ds_read_b128 v[198:201], v132 offset:33792
	buffer_load_dwordx4 v143, s[4:7], s44 offen lds
	s_mov_b32 m0, s22
	s_nop 0
	buffer_load_dwordx4 v144, s[4:7], s44 offen lds
	s_waitcnt lgkmcnt(8)
	s_barrier
	s_waitcnt lgkmcnt(6)
	v_mfma_f32_16x16x32_bf16 v[124:127], v[154:157], v[170:173], v[124:127]
	v_mfma_f32_16x16x32_bf16 v[124:127], v[158:161], v[174:177], v[124:127]
	v_mfma_f32_16x16x32_bf16 v[120:123], v[166:169], v[174:177], v[120:123]
	v_mfma_f32_16x16x32_bf16 v[120:123], v[162:165], v[170:173], v[120:123]
	s_waitcnt lgkmcnt(4)
	v_mfma_f32_16x16x32_bf16 v[112:115], v[162:165], v[178:181], v[112:115]
	v_mfma_f32_16x16x32_bf16 v[112:115], v[166:169], v[182:185], v[112:115]
	v_mfma_f32_16x16x32_bf16 v[116:119], v[158:161], v[182:185], v[116:119]
	v_mfma_f32_16x16x32_bf16 v[116:119], v[154:157], v[178:181], v[116:119]
	s_waitcnt lgkmcnt(2)
	v_mfma_f32_16x16x32_bf16 v[108:111], v[154:157], v[186:189], v[108:111]
	v_mfma_f32_16x16x32_bf16 v[108:111], v[158:161], v[190:193], v[108:111]
	v_mfma_f32_16x16x32_bf16 v[104:107], v[166:169], v[190:193], v[104:107]
	v_mfma_f32_16x16x32_bf16 v[104:107], v[162:165], v[186:189], v[104:107]
	s_waitcnt lgkmcnt(0)
	v_mfma_f32_16x16x32_bf16 v[96:99], v[162:165], v[194:197], v[96:99]
	v_mfma_f32_16x16x32_bf16 v[96:99], v[166:169], v[198:201], v[96:99]
	v_mfma_f32_16x16x32_bf16 v[100:103], v[158:161], v[198:201], v[100:103]
	v_mfma_f32_16x16x32_bf16 v[100:103], v[154:157], v[194:197], v[100:103]
	s_barrier
	s_addk_i32 s45, 0x180
	s_mov_b32 m0, s23
	ds_read_b128 v[202:205], v135
	ds_read_b128 v[206:209], v136
	ds_read_b128 v[210:213], v137
	ds_read_b128 v[214:217], v138
	buffer_load_dwordx4 v143, s[8:11], s45 offen lds
	s_mov_b32 m0, s24
	s_nop 0
	buffer_load_dwordx4 v144, s[8:11], s45 offen lds
	s_barrier
	s_waitcnt lgkmcnt(2)
	v_mfma_f32_16x16x32_bf16 v[92:95], v[202:205], v[170:173], v[92:95]
	v_mfma_f32_16x16x32_bf16 v[92:95], v[206:209], v[174:177], v[92:95]
	s_waitcnt lgkmcnt(0)
	v_mfma_f32_16x16x32_bf16 v[88:91], v[214:217], v[174:177], v[88:91]
	v_mfma_f32_16x16x32_bf16 v[88:91], v[210:213], v[170:173], v[88:91]
	v_mfma_f32_16x16x32_bf16 v[80:83], v[210:213], v[178:181], v[80:83]
	v_mfma_f32_16x16x32_bf16 v[80:83], v[214:217], v[182:185], v[80:83]
	v_mfma_f32_16x16x32_bf16 v[84:87], v[206:209], v[182:185], v[84:87]
	v_mfma_f32_16x16x32_bf16 v[84:87], v[202:205], v[178:181], v[84:87]
	v_mfma_f32_16x16x32_bf16 v[76:79], v[202:205], v[186:189], v[76:79]
	v_mfma_f32_16x16x32_bf16 v[76:79], v[206:209], v[190:193], v[76:79]
	v_mfma_f32_16x16x32_bf16 v[72:75], v[214:217], v[190:193], v[72:75]
	v_mfma_f32_16x16x32_bf16 v[72:75], v[210:213], v[186:189], v[72:75]
	v_mfma_f32_16x16x32_bf16 v[64:67], v[210:213], v[194:197], v[64:67]
	v_mfma_f32_16x16x32_bf16 v[64:67], v[214:217], v[198:201], v[64:67]
	v_mfma_f32_16x16x32_bf16 v[68:71], v[206:209], v[198:201], v[68:71]
	v_mfma_f32_16x16x32_bf16 v[68:71], v[202:205], v[194:197], v[68:71]
	s_barrier
	s_addk_i32 s46, 0x180
	s_mov_b32 m0, s25
	ds_read_b128 v[170:173], v131 offset:49152
	ds_read_b128 v[174:177], v131 offset:50176
	ds_read_b128 v[178:181], v134 offset:49152
	ds_read_b128 v[182:185], v134 offset:50176
	ds_read_b128 v[186:189], v133 offset:49152
	ds_read_b128 v[190:193], v133 offset:50176
	ds_read_b128 v[194:197], v132 offset:49152
	ds_read_b128 v[198:201], v132 offset:50176
	buffer_load_dwordx4 v143, s[4:7], s46 offen lds
	s_mov_b32 m0, s26
	s_nop 0
	buffer_load_dwordx4 v144, s[4:7], s46 offen lds
	s_barrier
	s_waitcnt lgkmcnt(6)
	v_mfma_f32_16x16x32_bf16 v[60:63], v[154:157], v[170:173], v[60:63]
	v_mfma_f32_16x16x32_bf16 v[60:63], v[158:161], v[174:177], v[60:63]
	v_mfma_f32_16x16x32_bf16 v[56:59], v[166:169], v[174:177], v[56:59]
	v_mfma_f32_16x16x32_bf16 v[56:59], v[162:165], v[170:173], v[56:59]
	s_waitcnt lgkmcnt(4)
	v_mfma_f32_16x16x32_bf16 v[48:51], v[162:165], v[178:181], v[48:51]
	v_mfma_f32_16x16x32_bf16 v[48:51], v[166:169], v[182:185], v[48:51]
	v_mfma_f32_16x16x32_bf16 v[52:55], v[158:161], v[182:185], v[52:55]
	v_mfma_f32_16x16x32_bf16 v[52:55], v[154:157], v[178:181], v[52:55]
	s_waitcnt lgkmcnt(2)
	v_mfma_f32_16x16x32_bf16 v[44:47], v[154:157], v[186:189], v[44:47]
	v_mfma_f32_16x16x32_bf16 v[44:47], v[158:161], v[190:193], v[44:47]
	v_mfma_f32_16x16x32_bf16 v[40:43], v[166:169], v[190:193], v[40:43]
	v_mfma_f32_16x16x32_bf16 v[40:43], v[162:165], v[186:189], v[40:43]
	s_waitcnt lgkmcnt(0)
	v_mfma_f32_16x16x32_bf16 v[32:35], v[162:165], v[194:197], v[32:35]
	v_mfma_f32_16x16x32_bf16 v[32:35], v[166:169], v[198:201], v[32:35]
	v_mfma_f32_16x16x32_bf16 v[36:39], v[158:161], v[198:201], v[36:39]
	v_mfma_f32_16x16x32_bf16 v[36:39], v[154:157], v[194:197], v[36:39]
	s_barrier
	s_addk_i32 s47, 0x180
	s_mov_b32 m0, s27
	s_nop 0
	buffer_load_dwordx4 v143, s[8:11], s47 offen lds
	s_mov_b32 m0, s28
	s_nop 0
	buffer_load_dwordx4 v144, s[8:11], s47 offen lds
	s_add_i32 s16, s16, 2
	s_addk_i32 s17, 0x100
	s_cmp_gt_u32 s16, 27
	s_cbranch_scc0 .LBB0_210
; #define STAGE(P, RS, SOFF, OFF, kt) do { const int _so = (SOFF) + (kt) * (BK * 2); \
;     _Pragma("unroll") for (int _i = 0; _i < 2; ++_i) { \
;       __builtin_amdgcn_raw_ptr_buffer_load_lds(RS, (__attribute__((address_space(3))) void*)((P) + wave * 1024 + _i * 8192), 16, OFF[_i], _so, 0, 0); } } while (0)
; #define LDA(dst, b, h) _Pragma("unroll") for (int m = 0; m < 4; ++m) _Pragma("unroll") for (int k = 0; k < 2; ++k) \
;     dst[m][k] = *reinterpret_cast<const bf16x8*>(SA(b, h) + lds_byte(wr * 64 + m * 16 + fr, k * 32 + fq * 8))
; #define LDB(dst, b, h) _Pragma("unroll") for (int n = 0; n < 2; ++n) _Pragma("unroll") for (int k = 0; k < 2; ++k) \
;     dst[n][k] = *reinterpret_cast<const bf16x8*>(SB(b, h) + lds_byte(wc * 32 + n * 16 + fr, k * 32 + fq * 8))
; #define WAIT_V(n) asm volatile("s_waitcnt vmcnt(" #n ")" ::: "memory")
; #define WAIT_L(n) asm volatile("s_waitcnt lgkmcnt(" #n ")" ::: "memory")
; #define BAR __builtin_amdgcn_s_barrier()
;     ...
;       WAIT_V(6); BAR; MMA(1, 1, At, B1); BAR;
;     }
;     { LDB(B0, 0, 0); LDA(At, 0, 0); STAGE(SA(1, 1), rsA, sA1, offA, nt - 1);
;       BAR; WAIT_L(0); MMA(0, 0, At, B0); BAR;
;       LDB(B1, 0, 1); BAR; WAIT_L(0); MMA(0, 1, At, B1); BAR;
;       LDA(At, 0, 1); WAIT_V(4); BAR; WAIT_L(0); MMA(1, 0, At, B0); MMA(1, 1, At, B1); BAR; }
.Lmy_post_210:
	s_waitcnt vmcnt(6)
	s_barrier
	v_mfma_f32_16x16x32_bf16 v[28:31], v[202:205], v[170:173], v[28:31]
	v_mfma_f32_16x16x32_bf16 v[28:31], v[206:209], v[174:177], v[28:31]
	v_mfma_f32_16x16x32_bf16 v[24:27], v[214:217], v[174:177], v[24:27]
	v_mfma_f32_16x16x32_bf16 v[24:27], v[210:213], v[170:173], v[24:27]
	v_mfma_f32_16x16x32_bf16 v[16:19], v[210:213], v[178:181], v[16:19]
	v_mfma_f32_16x16x32_bf16 v[16:19], v[214:217], v[182:185], v[16:19]
	v_mfma_f32_16x16x32_bf16 v[20:23], v[206:209], v[182:185], v[20:23]
	v_mfma_f32_16x16x32_bf16 v[20:23], v[202:205], v[178:181], v[20:23]
	v_mfma_f32_16x16x32_bf16 v[12:15], v[202:205], v[186:189], v[12:15]
	v_mfma_f32_16x16x32_bf16 v[12:15], v[206:209], v[190:193], v[12:15]
	v_mfma_f32_16x16x32_bf16 v[8:11], v[214:217], v[190:193], v[8:11]
	v_mfma_f32_16x16x32_bf16 v[8:11], v[210:213], v[186:189], v[8:11]
	v_mfma_f32_16x16x32_bf16 v[0:3], v[210:213], v[194:197], v[0:3]
	v_mfma_f32_16x16x32_bf16 v[0:3], v[214:217], v[198:201], v[0:3]
	v_mfma_f32_16x16x32_bf16 v[4:7], v[206:209], v[198:201], v[4:7]
	v_mfma_f32_16x16x32_bf16 v[4:7], v[202:205], v[194:197], v[4:7]
	s_barrier
	s_add_i32 s10, s38, 0xf80
	s_mov_b32 m0, s30
	ds_read_b128 v[154:157], v149
	ds_read_b128 v[158:161], v150
	ds_read_b128 v[162:165], v151
	ds_read_b128 v[150:153], v152
	ds_read_b128 v[166:169], v131
	ds_read_b128 v[170:173], v131 offset:1024
	ds_read_b128 v[174:177], v134
	ds_read_b128 v[178:181], v134 offset:1024
	ds_read_b128 v[182:185], v133
	ds_read_b128 v[186:189], v133 offset:1024
	ds_read_b128 v[190:193], v132
	ds_read_b128 v[194:197], v132 offset:1024
	buffer_load_dwordx4 v143, s[4:7], s10 offen lds
	s_mov_b32 m0, s31
	s_nop 0
	buffer_load_dwordx4 v144, s[4:7], s10 offen lds
	s_barrier
	s_waitcnt lgkmcnt(6)
	v_mfma_f32_16x16x32_bf16 v[124:127], v[154:157], v[166:169], v[124:127]
	v_mfma_f32_16x16x32_bf16 v[124:127], v[158:161], v[170:173], v[124:127]
	v_mfma_f32_16x16x32_bf16 v[120:123], v[150:153], v[170:173], v[120:123]
	v_mfma_f32_16x16x32_bf16 v[120:123], v[162:165], v[166:169], v[120:123]
	s_waitcnt lgkmcnt(4)
	v_mfma_f32_16x16x32_bf16 v[112:115], v[162:165], v[174:177], v[112:115]
	v_mfma_f32_16x16x32_bf16 v[112:115], v[150:153], v[178:181], v[112:115]
	v_mfma_f32_16x16x32_bf16 v[116:119], v[158:161], v[178:181], v[116:119]
	v_mfma_f32_16x16x32_bf16 v[116:119], v[154:157], v[174:177], v[116:119]
	s_waitcnt lgkmcnt(2)
	v_mfma_f32_16x16x32_bf16 v[108:111], v[154:157], v[182:185], v[108:111]
	v_mfma_f32_16x16x32_bf16 v[108:111], v[158:161], v[186:189], v[108:111]
	v_mfma_f32_16x16x32_bf16 v[104:107], v[150:153], v[186:189], v[104:107]
	v_mfma_f32_16x16x32_bf16 v[104:107], v[162:165], v[182:185], v[104:107]
	s_waitcnt lgkmcnt(0)
	v_mfma_f32_16x16x32_bf16 v[96:99], v[162:165], v[190:193], v[96:99]
	v_mfma_f32_16x16x32_bf16 v[96:99], v[150:153], v[194:197], v[96:99]
	v_mfma_f32_16x16x32_bf16 v[100:103], v[158:161], v[194:197], v[100:103]
	v_mfma_f32_16x16x32_bf16 v[100:103], v[154:157], v[190:193], v[100:103]
	s_barrier
	ds_read_b128 v[198:201], v145
	ds_read_b128 v[202:205], v146
	ds_read_b128 v[144:147], v147
	ds_read_b128 v[206:209], v148
	s_barrier
	s_waitcnt lgkmcnt(2)
	v_mfma_f32_16x16x32_bf16 v[92:95], v[198:201], v[166:169], v[92:95]
	v_mfma_f32_16x16x32_bf16 v[92:95], v[202:205], v[170:173], v[92:95]
	s_waitcnt lgkmcnt(0)
	v_mfma_f32_16x16x32_bf16 v[88:91], v[206:209], v[170:173], v[88:91]
	v_mfma_f32_16x16x32_bf16 v[88:91], v[144:147], v[166:169], v[88:91]
	v_mfma_f32_16x16x32_bf16 v[80:83], v[144:147], v[174:177], v[80:83]
	v_mfma_f32_16x16x32_bf16 v[80:83], v[206:209], v[178:181], v[80:83]
	v_mfma_f32_16x16x32_bf16 v[84:87], v[202:205], v[178:181], v[84:87]
	v_mfma_f32_16x16x32_bf16 v[84:87], v[198:201], v[174:177], v[84:87]
	v_mfma_f32_16x16x32_bf16 v[76:79], v[198:201], v[182:185], v[76:79]
	v_mfma_f32_16x16x32_bf16 v[76:79], v[202:205], v[186:189], v[76:79]
	v_mfma_f32_16x16x32_bf16 v[72:75], v[206:209], v[186:189], v[72:75]
	v_mfma_f32_16x16x32_bf16 v[72:75], v[144:147], v[182:185], v[72:75]
	v_mfma_f32_16x16x32_bf16 v[64:67], v[144:147], v[190:193], v[64:67]
	v_mfma_f32_16x16x32_bf16 v[64:67], v[206:209], v[194:197], v[64:67]
	v_mfma_f32_16x16x32_bf16 v[68:71], v[202:205], v[194:197], v[68:71]
	v_mfma_f32_16x16x32_bf16 v[68:71], v[198:201], v[190:193], v[68:71]
	s_barrier
	ds_read_b128 v[166:169], v131 offset:16384
	ds_read_b128 v[170:173], v131 offset:17408
	ds_read_b128 v[174:177], v134 offset:16384
	ds_read_b128 v[178:181], v134 offset:17408
	ds_read_b128 v[182:185], v133 offset:16384
	ds_read_b128 v[186:189], v133 offset:17408
	ds_read_b128 v[190:193], v132 offset:16384
	ds_read_b128 v[194:197], v132 offset:17408
	s_waitcnt vmcnt(4)
	s_barrier
; #define LDA(dst, b, h) _Pragma("unroll") for (int m = 0; m < 4; ++m) _Pragma("unroll") for (int k = 0; k < 2; ++k) \
;     dst[m][k] = *reinterpret_cast<const bf16x8*>(SA(b, h) + lds_byte(wr * 64 + m * 16 + fr, k * 32 + fq * 8))
; #define LDB(dst, b, h) _Pragma("unroll") for (int n = 0; n < 2; ++n) _Pragma("unroll") for (int k = 0; k < 2; ++k) \
;     dst[n][k] = *reinterpret_cast<const bf16x8*>(SB(b, h) + lds_byte(wc * 32 + n * 16 + fr, k * 32 + fq * 8))
; #define WAIT_V(n) asm volatile("s_waitcnt vmcnt(" #n ")" ::: "memory")
; #define WAIT_L(n) asm volatile("s_waitcnt lgkmcnt(" #n ")" ::: "memory")
; #define BAR __builtin_amdgcn_s_barrier()
;     ...
;       LDA(At, 0, 1); WAIT_V(4); BAR; WAIT_L(0); MMA(1, 0, At, B0); MMA(1, 1, At, B1); BAR; }
;     { LDB(B0, 1, 0); LDA(At, 1, 0); WAIT_V(2); BAR; WAIT_L(0); MMA(0, 0, At, B0); BAR;
	s_waitcnt lgkmcnt(0)
	v_mfma_f32_16x16x32_bf16 v[60:63], v[154:157], v[166:169], v[60:63]
	v_mfma_f32_16x16x32_bf16 v[60:63], v[158:161], v[170:173], v[60:63]
	v_mfma_f32_16x16x32_bf16 v[56:59], v[150:153], v[170:173], v[56:59]
	v_mfma_f32_16x16x32_bf16 v[56:59], v[162:165], v[166:169], v[56:59]
	v_mfma_f32_16x16x32_bf16 v[48:51], v[162:165], v[174:177], v[48:51]
	v_mfma_f32_16x16x32_bf16 v[48:51], v[150:153], v[178:181], v[48:51]
	v_mfma_f32_16x16x32_bf16 v[52:55], v[158:161], v[178:181], v[52:55]
	v_mfma_f32_16x16x32_bf16 v[52:55], v[154:157], v[174:177], v[52:55]
	v_mfma_f32_16x16x32_bf16 v[44:47], v[154:157], v[182:185], v[44:47]
	v_mfma_f32_16x16x32_bf16 v[44:47], v[158:161], v[186:189], v[44:47]
	v_mfma_f32_16x16x32_bf16 v[40:43], v[150:153], v[186:189], v[40:43]
	v_mfma_f32_16x16x32_bf16 v[40:43], v[162:165], v[182:185], v[40:43]
	v_mfma_f32_16x16x32_bf16 v[32:35], v[162:165], v[190:193], v[32:35]
	v_mfma_f32_16x16x32_bf16 v[32:35], v[150:153], v[194:197], v[32:35]
	v_mfma_f32_16x16x32_bf16 v[36:39], v[158:161], v[194:197], v[36:39]
	v_mfma_f32_16x16x32_bf16 v[36:39], v[154:157], v[190:193], v[36:39]
	v_mfma_f32_16x16x32_bf16 v[4:7], v[198:201], v[190:193], v[4:7]
	v_mfma_f32_16x16x32_bf16 v[4:7], v[202:205], v[194:197], v[4:7]
	v_mfma_f32_16x16x32_bf16 v[28:31], v[202:205], v[170:173], v[28:31]
	v_mfma_f32_16x16x32_bf16 v[28:31], v[198:201], v[166:169], v[28:31]
	v_mfma_f32_16x16x32_bf16 v[24:27], v[144:147], v[166:169], v[24:27]
	v_mfma_f32_16x16x32_bf16 v[24:27], v[206:209], v[170:173], v[24:27]
	v_mfma_f32_16x16x32_bf16 v[16:19], v[206:209], v[178:181], v[16:19]
	v_mfma_f32_16x16x32_bf16 v[16:19], v[144:147], v[174:177], v[16:19]
	v_mfma_f32_16x16x32_bf16 v[20:23], v[198:201], v[174:177], v[20:23]
	v_mfma_f32_16x16x32_bf16 v[20:23], v[202:205], v[178:181], v[20:23]
	v_mfma_f32_16x16x32_bf16 v[12:15], v[202:205], v[186:189], v[12:15]
	v_mfma_f32_16x16x32_bf16 v[12:15], v[198:201], v[182:185], v[12:15]
	v_mfma_f32_16x16x32_bf16 v[8:11], v[144:147], v[182:185], v[8:11]
	v_mfma_f32_16x16x32_bf16 v[8:11], v[206:209], v[186:189], v[8:11]
	v_mfma_f32_16x16x32_bf16 v[0:3], v[206:209], v[194:197], v[0:3]
	v_mfma_f32_16x16x32_bf16 v[0:3], v[144:147], v[190:193], v[0:3]
	s_barrier
	ds_read_b128 v[144:147], v139
	ds_read_b128 v[148:151], v140
	ds_read_b128 v[152:155], v141
	ds_read_b128 v[140:143], v142
	ds_read_b128 v[156:159], v131 offset:32768
	ds_read_b128 v[160:163], v131 offset:33792
	ds_read_b128 v[164:167], v134 offset:32768
	ds_read_b128 v[168:171], v134 offset:33792
	ds_read_b128 v[172:175], v133 offset:32768
	ds_read_b128 v[176:179], v133 offset:33792
	ds_read_b128 v[180:183], v132 offset:32768
	ds_read_b128 v[184:187], v132 offset:33792
	s_waitcnt vmcnt(2)
	s_barrier
	s_waitcnt lgkmcnt(6)
	v_mfma_f32_16x16x32_bf16 v[124:127], v[144:147], v[156:159], v[124:127]
	v_mfma_f32_16x16x32_bf16 v[124:127], v[148:151], v[160:163], v[124:127]
	v_mfma_f32_16x16x32_bf16 v[120:123], v[140:143], v[160:163], v[120:123]
	v_mfma_f32_16x16x32_bf16 v[120:123], v[152:155], v[156:159], v[120:123]
	s_waitcnt lgkmcnt(4)
	v_mfma_f32_16x16x32_bf16 v[112:115], v[152:155], v[164:167], v[112:115]
	v_mfma_f32_16x16x32_bf16 v[112:115], v[140:143], v[168:171], v[112:115]
	v_mfma_f32_16x16x32_bf16 v[116:119], v[148:151], v[168:171], v[116:119]
	v_mfma_f32_16x16x32_bf16 v[116:119], v[144:147], v[164:167], v[116:119]
	s_waitcnt lgkmcnt(2)
	v_mfma_f32_16x16x32_bf16 v[108:111], v[144:147], v[172:175], v[108:111]
	v_mfma_f32_16x16x32_bf16 v[108:111], v[148:151], v[176:179], v[108:111]
	v_mfma_f32_16x16x32_bf16 v[104:107], v[140:143], v[176:179], v[104:107]
	v_mfma_f32_16x16x32_bf16 v[104:107], v[152:155], v[172:175], v[104:107]
	s_waitcnt lgkmcnt(0)
	v_mfma_f32_16x16x32_bf16 v[96:99], v[152:155], v[180:183], v[96:99]
	v_mfma_f32_16x16x32_bf16 v[96:99], v[140:143], v[184:187], v[96:99]
	v_mfma_f32_16x16x32_bf16 v[100:103], v[148:151], v[184:187], v[100:103]
	v_mfma_f32_16x16x32_bf16 v[100:103], v[144:147], v[180:183], v[100:103]
	s_barrier
; #define LDA(dst, b, h) _Pragma("unroll") for (int m = 0; m < 4; ++m) _Pragma("unroll") for (int k = 0; k < 2; ++k) \
;     dst[m][k] = *reinterpret_cast<const bf16x8*>(SA(b, h) + lds_byte(wr * 64 + m * 16 + fr, k * 32 + fq * 8))
; #define LDB(dst, b, h) _Pragma("unroll") for (int n = 0; n < 2; ++n) _Pragma("unroll") for (int k = 0; k < 2; ++k) \
;     dst[n][k] = *reinterpret_cast<const bf16x8*>(SB(b, h) + lds_byte(wc * 32 + n * 16 + fr, k * 32 + fq * 8))
; #define WAIT_V(n) asm volatile("s_waitcnt vmcnt(" #n ")" ::: "memory")
; #define WAIT_L(n) asm volatile("s_waitcnt lgkmcnt(" #n ")" ::: "memory")
; #define BAR __builtin_amdgcn_s_barrier()
;     ...
;       LDB(B1, 1, 1); WAIT_V(0); BAR; WAIT_L(0); MMA(0, 1, At, B1); BAR;
;       LDA(At, 1, 1); BAR; WAIT_L(0); MMA(1, 0, At, B0); MMA(1, 1, At, B1); BAR; }
;     if (wr == 0) BAR;
	ds_read_b128 v[188:191], v135
	ds_read_b128 v[192:195], v136
	ds_read_b128 v[196:199], v137
	ds_read_b128 v[136:139], v138
	s_waitcnt vmcnt(0)
	s_barrier
	s_waitcnt lgkmcnt(2)
	v_mfma_f32_16x16x32_bf16 v[92:95], v[188:191], v[156:159], v[92:95]
	v_mfma_f32_16x16x32_bf16 v[92:95], v[192:195], v[160:163], v[92:95]
	s_waitcnt lgkmcnt(0)
	v_mfma_f32_16x16x32_bf16 v[88:91], v[136:139], v[160:163], v[88:91]
	v_mfma_f32_16x16x32_bf16 v[88:91], v[196:199], v[156:159], v[88:91]
	v_mfma_f32_16x16x32_bf16 v[80:83], v[196:199], v[164:167], v[80:83]
	v_mfma_f32_16x16x32_bf16 v[80:83], v[136:139], v[168:171], v[80:83]
	v_mfma_f32_16x16x32_bf16 v[84:87], v[192:195], v[168:171], v[84:87]
	v_mfma_f32_16x16x32_bf16 v[84:87], v[188:191], v[164:167], v[84:87]
	v_mfma_f32_16x16x32_bf16 v[76:79], v[188:191], v[172:175], v[76:79]
	v_mfma_f32_16x16x32_bf16 v[76:79], v[192:195], v[176:179], v[76:79]
	v_mfma_f32_16x16x32_bf16 v[72:75], v[136:139], v[176:179], v[72:75]
	v_mfma_f32_16x16x32_bf16 v[72:75], v[196:199], v[172:175], v[72:75]
	v_mfma_f32_16x16x32_bf16 v[64:67], v[196:199], v[180:183], v[64:67]
	v_mfma_f32_16x16x32_bf16 v[64:67], v[136:139], v[184:187], v[64:67]
	v_mfma_f32_16x16x32_bf16 v[68:71], v[192:195], v[184:187], v[68:71]
	v_mfma_f32_16x16x32_bf16 v[68:71], v[188:191], v[180:183], v[68:71]
	s_barrier
	ds_read_b128 v[156:159], v131 offset:49152
	ds_read_b128 v[160:163], v131 offset:50176
	ds_read_b128 v[164:167], v134 offset:49152
	ds_read_b128 v[168:171], v134 offset:50176
	ds_read_b128 v[172:175], v133 offset:49152
	ds_read_b128 v[176:179], v133 offset:50176
	ds_read_b128 v[180:183], v132 offset:49152
	ds_read_b128 v[132:135], v132 offset:50176
	s_barrier
	s_waitcnt lgkmcnt(0)
	v_mfma_f32_16x16x32_bf16 v[60:63], v[144:147], v[156:159], v[60:63]
	v_mfma_f32_16x16x32_bf16 v[60:63], v[148:151], v[160:163], v[60:63]
	v_mfma_f32_16x16x32_bf16 v[56:59], v[140:143], v[160:163], v[56:59]
	v_mfma_f32_16x16x32_bf16 v[56:59], v[152:155], v[156:159], v[56:59]
	v_mfma_f32_16x16x32_bf16 v[48:51], v[152:155], v[164:167], v[48:51]
	v_mfma_f32_16x16x32_bf16 v[48:51], v[140:143], v[168:171], v[48:51]
	v_mfma_f32_16x16x32_bf16 v[52:55], v[148:151], v[168:171], v[52:55]
	v_mfma_f32_16x16x32_bf16 v[52:55], v[144:147], v[164:167], v[52:55]
	v_mfma_f32_16x16x32_bf16 v[44:47], v[144:147], v[172:175], v[44:47]
	v_mfma_f32_16x16x32_bf16 v[44:47], v[148:151], v[176:179], v[44:47]
	v_mfma_f32_16x16x32_bf16 v[40:43], v[140:143], v[176:179], v[40:43]
	v_mfma_f32_16x16x32_bf16 v[40:43], v[152:155], v[172:175], v[40:43]
	v_mfma_f32_16x16x32_bf16 v[32:35], v[152:155], v[180:183], v[32:35]
	v_mfma_f32_16x16x32_bf16 v[32:35], v[140:143], v[132:135], v[32:35]
	v_mfma_f32_16x16x32_bf16 v[36:39], v[148:151], v[132:135], v[36:39]
	v_mfma_f32_16x16x32_bf16 v[36:39], v[144:147], v[180:183], v[36:39]
	v_mfma_f32_16x16x32_bf16 v[4:7], v[188:191], v[180:183], v[4:7]
	v_mfma_f32_16x16x32_bf16 v[4:7], v[192:195], v[132:135], v[4:7]
	v_mfma_f32_16x16x32_bf16 v[28:31], v[192:195], v[160:163], v[28:31]
	v_mfma_f32_16x16x32_bf16 v[28:31], v[188:191], v[156:159], v[28:31]
	v_mfma_f32_16x16x32_bf16 v[24:27], v[196:199], v[156:159], v[24:27]
	v_mfma_f32_16x16x32_bf16 v[24:27], v[136:139], v[160:163], v[24:27]
	v_mfma_f32_16x16x32_bf16 v[16:19], v[136:139], v[168:171], v[16:19]
	v_mfma_f32_16x16x32_bf16 v[16:19], v[196:199], v[164:167], v[16:19]
	v_mfma_f32_16x16x32_bf16 v[20:23], v[188:191], v[164:167], v[20:23]
	v_mfma_f32_16x16x32_bf16 v[20:23], v[192:195], v[168:171], v[20:23]
	v_mfma_f32_16x16x32_bf16 v[12:15], v[192:195], v[176:179], v[12:15]
	v_mfma_f32_16x16x32_bf16 v[12:15], v[188:191], v[172:175], v[12:15]
	v_mfma_f32_16x16x32_bf16 v[8:11], v[196:199], v[172:175], v[8:11]
	v_mfma_f32_16x16x32_bf16 v[8:11], v[136:139], v[176:179], v[8:11]
	v_mfma_f32_16x16x32_bf16 v[0:3], v[136:139], v[132:135], v[0:3]
	v_mfma_f32_16x16x32_bf16 v[0:3], v[196:199], v[180:183], v[0:3]
	v_cmp_gt_u32_e32 vcc, s35, v130
	s_barrier
	s_and_saveexec_b64 s[10:11], vcc
	s_cbranch_execz .LBB0_213
	s_barrier

; #define STAGE(P, RS, SOFF, OFF, kt) do { const int _so = (SOFF) + (kt) * (BK * 2); \
;     _Pragma("unroll") for (int _i = 0; _i < 2; ++_i) { \
;       __builtin_amdgcn_raw_ptr_buffer_load_lds(RS, (__attribute__((address_space(3))) void*)((P) + wave * 1024 + _i * 8192), 16, OFF[_i], _so, 0, 0); } } while (0)
; #define LDA(dst, b, h) _Pragma("unroll") for (int m = 0; m < 4; ++m) _Pragma("unroll") for (int k = 0; k < 2; ++k) \
;     dst[m][k] = *reinterpret_cast<const bf16x8*>(SA(b, h) + lds_byte(wr * 64 + m * 16 + fr, k * 32 + fq * 8))
; #define LDB(dst, b, h) _Pragma("unroll") for (int n = 0; n < 2; ++n) _Pragma("unroll") for (int k = 0; k < 2; ++k) \
;     dst[n][k] = *reinterpret_cast<const bf16x8*>(SB(b, h) + lds_byte(wc * 32 + n * 16 + fr, k * 32 + fq * 8))
; #define WAIT_V(n) asm volatile("s_waitcnt vmcnt(" #n ")" ::: "memory")
; #define WAIT_L(n) asm volatile("s_waitcnt lgkmcnt(" #n ")" ::: "memory")
; #define BAR __builtin_amdgcn_s_barrier()
; #define SCHED __builtin_amdgcn_sched_barrier(0)
;     ...
;     const int tid = opaque_tid(wave);
;     const int wid = tid >> 6, lane = tid & 63, wr = wid >> 2, wc = wid & 3, fr = lane & 15, fq = lane >> 4;
;     int offA[2], offB[2];
;     _Pragma("unroll") for (int i = 0; i < 2; ++i) {
;       int r, c; stage_rc(tid * 16 + i * 8192, r, c);
;       offA[i] = (r * lda + c) * 2; offB[i] = (r * ldb + c) * 2;
;     }
;     const int brow = pm * BM;
;     f32x4 acc[2][2][4][2];
;     _Pragma("unroll") for (int a = 0; a < 2; ++a) _Pragma("unroll") for (int b = 0; b < 2; ++b) _Pragma("unroll") for (int m = 0; m < 4; ++m) _Pragma("unroll") for (int n = 0; n < 2; ++n)
;       acc[a][b][m][n] = f32x4{0.f, 0.f, 0.f, 0.f};
;     bf16x8 At[4][2], B0[2][2], B1[2][2];
;     if (wr == 1) BAR;
;     if (first_tile) { WAIT_V(0); }
;     else if constexpr (mode == MODE_RESID_LN) { WAIT_V(0); }
;     else if constexpr (mode == MODE_SWIGLU) { WAIT_V(6); }
;     else if constexpr (mode == MODE_V) { WAIT_V(24); }
;     else { WAIT_V(12); }
;     first_tile = false;
;     BAR;
;     BAR;
;     for (int t = 0; t < nt - 2; t += 2) {
;       LDB(B0, 0, 0); SCHED; LDA(At, 0, 0); STAGE(SA(1, 1), rsA, sA1, offA, t + 1);
;       WAIT_L(8); BAR; WAIT_L(0); MMA(0, 0, At, B0); BAR; SCHED;
;       LDB(B1, 0, 1); STAGE(SB(0, 0), rsB, sB0, offB, t + 2);
;       BAR; WAIT_L(0); MMA(0, 1, At, B1); BAR;
.LBB0_224:
	v_bfe_i32 v4, v129, 27, 1
	v_lshlrev_b32_e32 v2, 4, v129
	v_lshrrev_b32_e32 v4, 22, v4
	v_add_u32_e32 v4, v2, v4
	v_and_b32_e32 v4, 0xfffffc00, v4
	v_sub_u32_e32 v4, v2, v4
	v_lshrrev_b32_e32 v5, 4, v4
	v_bitop3_b32 v4, v5, v4, 32 bitop3:0x6c
	v_ashrrev_i32_e32 v3, 31, v129
	v_ashrrev_i32_e32 v6, 31, v4
	v_lshrrev_b32_e32 v3, 26, v3
	v_lshrrev_b32_e32 v6, 26, v6
	v_add_u32_e32 v3, v129, v3
	v_add_u32_e32 v6, v4, v6
	v_ashrrev_i32_e32 v3, 6, v3
	v_lshrrev_b32_e32 v7, 6, v6
	v_and_b32_e32 v6, 0xc0, v6
	v_lshlrev_b32_e32 v5, 3, v3
	v_lshlrev_b32_e32 v3, 5, v3
	v_sub_u32_e32 v4, v4, v6
	v_and_b32_e32 v5, 0xffff0, v5
	v_and_b32_e32 v3, 32, v3
	v_ashrrev_i16_sdwa v4, v128, sext(v4) dst_sel:DWORD dst_unused:UNUSED_PAD src0_sel:DWORD src1_sel:BYTE_0
	v_add_u32_sdwa v3, v3, sext(v4) dst_sel:DWORD dst_unused:UNUSED_PAD src0_sel:DWORD src1_sel:WORD_0
	v_add_lshl_u32 v4, v7, v5, 12
	v_add_u32_e32 v2, 0x2000, v2
	v_lshl_add_u32 v142, v3, 1, v4
	v_ashrrev_i32_e32 v3, 31, v2
	v_lshrrev_b32_e32 v3, 22, v3
	v_add_u32_e32 v3, v2, v3
	v_ashrrev_i32_e32 v3, 10, v3
	v_mul_i32_i24_e32 v4, 0x400, v3
	v_sub_u32_e32 v2, v2, v4
	v_lshrrev_b32_e32 v4, 4, v2
	v_bitop3_b32 v2, v4, v2, 32 bitop3:0x6c
	v_ashrrev_i32_e32 v5, 31, v2
	v_lshrrev_b32_e32 v5, 26, v5
	v_add_u32_e32 v5, v2, v5
	v_lshrrev_b32_e32 v6, 6, v5
	v_and_b32_e32 v5, 0xc0, v5
	v_lshlrev_b32_e32 v4, 3, v3
	v_lshlrev_b32_e32 v3, 5, v3
	v_sub_u32_e32 v2, v2, v5
	v_and_b32_e32 v4, 0xffff0, v4
	v_and_b32_e32 v3, 32, v3
	v_ashrrev_i16_sdwa v2, v128, sext(v2) dst_sel:DWORD dst_unused:UNUSED_PAD src0_sel:DWORD src1_sel:BYTE_0
	v_add_u32_sdwa v2, v3, sext(v2) dst_sel:DWORD dst_unused:UNUSED_PAD src0_sel:DWORD src1_sel:WORD_0
	v_add_lshl_u32 v3, v6, v4, 12
	v_lshl_add_u32 v143, v2, 1, v3
	v_and_b32_e32 v3, 15, v0
	v_lshlrev_b32_e32 v5, 2, v0
	v_and_b32_e32 v2, 48, v0
	v_lshlrev_b32_e32 v3, 6, v3
	v_and_b32_e32 v5, 32, v5
	v_lshlrev_b32_e32 v0, 6, v0
	v_or_b32_e32 v4, v3, v2
	v_bitop3_b32 v3, v3, v5, v2 bitop3:0x36
	v_lshlrev_b32_e32 v6, 6, v129
	v_lshlrev_b32_e32 v1, 13, v1
	v_and_or_b32 v0, v0, s36, v2
	v_and_or_b32 v3, v6, s35, v3
	v_bitop3_b32 v0, v1, v0, v5 bitop3:0xf6
	v_or_b32_e32 v6, 0x400, v3
	v_or_b32_e32 v7, 0x800, v3
	v_or_b32_e32 v8, 0xc00, v3
	v_or_b32_e32 v133, 0x800, v0
	v_or_b32_e32 v132, 0x1000, v0
	v_or_b32_e32 v131, 0x1800, v0
	v_mov_b32_e32 v0, 0
	v_bitop3_b32 v130, v4, v1, v5 bitop3:0xde
	s_mov_b32 s16, -2
	s_mov_b32 s17, 0
	v_or_b32_e32 v148, 0x10000, v3
	v_or_b32_e32 v149, 0x10000, v6
	v_or_b32_e32 v150, 0x10000, v7
	v_or_b32_e32 v151, 0x10000, v8
	v_or_b32_e32 v144, 0x14000, v3
	v_or_b32_e32 v145, 0x14000, v6
	v_or_b32_e32 v146, 0x14000, v7
	v_or_b32_e32 v147, 0x14000, v8
	v_or_b32_e32 v138, 0x18000, v3
	v_or_b32_e32 v139, 0x18000, v6
	v_or_b32_e32 v140, 0x18000, v7
	v_or_b32_e32 v141, 0x18000, v8
	v_or_b32_e32 v134, 0x1c000, v3
	v_or_b32_e32 v135, 0x1c000, v6
	v_or_b32_e32 v136, 0x1c000, v7
	v_or_b32_e32 v137, 0x1c000, v8
	s_barrier
	s_barrier
	ds_read_b128 v[152:155], v148
	ds_read_b128 v[156:159], v149
	ds_read_b128 v[160:163], v150
	ds_read_b128 v[164:167], v151
	s_add_i32 s18, s41, s17
	s_add_i32 s19, s18, 0x80
	s_mov_b32 m0, s33
	ds_read_b128 v[168:171], v130
	ds_read_b128 v[172:175], v130 offset:1024
	ds_read_b128 v[176:179], v133
	ds_read_b128 v[180:183], v133 offset:1024
	ds_read_b128 v[184:187], v132
	ds_read_b128 v[188:191], v132 offset:1024
	ds_read_b128 v[192:195], v131
	ds_read_b128 v[196:199], v131 offset:1024
	buffer_load_dwordx4 v142, s[4:7], s19 offen lds
	s_mov_b32 m0, s34
	s_nop 0
	buffer_load_dwordx4 v143, s[4:7], s19 offen lds
	s_waitcnt lgkmcnt(8)
	s_barrier
	s_waitcnt lgkmcnt(0)
	v_mfma_f32_16x16x32_bf16 v[124:127], v[168:171], v[152:155], 0
	v_mfma_f32_16x16x32_bf16 v[124:127], v[172:175], v[156:159], v[124:127]
	v_mfma_f32_16x16x32_bf16 v[120:123], v[172:175], v[164:167], 0
	v_mfma_f32_16x16x32_bf16 v[120:123], v[168:171], v[160:163], v[120:123]
	v_mfma_f32_16x16x32_bf16 v[112:115], v[176:179], v[160:163], 0
	v_mfma_f32_16x16x32_bf16 v[112:115], v[180:183], v[164:167], v[112:115]
	v_mfma_f32_16x16x32_bf16 v[116:119], v[180:183], v[156:159], 0
	v_mfma_f32_16x16x32_bf16 v[116:119], v[176:179], v[152:155], v[116:119]
	v_mfma_f32_16x16x32_bf16 v[108:111], v[184:187], v[152:155], 0
	v_mfma_f32_16x16x32_bf16 v[108:111], v[188:191], v[156:159], v[108:111]
	v_mfma_f32_16x16x32_bf16 v[104:107], v[188:191], v[164:167], 0
	v_mfma_f32_16x16x32_bf16 v[104:107], v[184:187], v[160:163], v[104:107]
	v_mfma_f32_16x16x32_bf16 v[96:99], v[192:195], v[160:163], 0
	v_mfma_f32_16x16x32_bf16 v[96:99], v[196:199], v[164:167], v[96:99]
	v_mfma_f32_16x16x32_bf16 v[100:103], v[196:199], v[156:159], 0
	v_mfma_f32_16x16x32_bf16 v[100:103], v[192:195], v[152:155], v[100:103]
	s_barrier
	s_add_i32 s19, s43, s17
	s_add_i32 s47, s19, 0x100
	s_mov_b32 m0, s1
	ds_read_b128 v[200:203], v144
	ds_read_b128 v[204:207], v145
	ds_read_b128 v[208:211], v146
	ds_read_b128 v[212:215], v147
	buffer_load_dwordx4 v142, s[8:11], s47 offen lds
	s_mov_b32 m0, s3
	s_nop 0
	buffer_load_dwordx4 v143, s[8:11], s47 offen lds
	s_barrier
	s_waitcnt lgkmcnt(2)
	v_mfma_f32_16x16x32_bf16 v[92:95], v[168:171], v[200:203], 0
	v_mfma_f32_16x16x32_bf16 v[92:95], v[172:175], v[204:207], v[92:95]
	s_waitcnt lgkmcnt(0)
	v_mfma_f32_16x16x32_bf16 v[88:91], v[172:175], v[212:215], 0
	v_mfma_f32_16x16x32_bf16 v[88:91], v[168:171], v[208:211], v[88:91]
	v_mfma_f32_16x16x32_bf16 v[80:83], v[176:179], v[208:211], 0
	v_mfma_f32_16x16x32_bf16 v[80:83], v[180:183], v[212:215], v[80:83]
	v_mfma_f32_16x16x32_bf16 v[84:87], v[180:183], v[204:207], 0
	v_mfma_f32_16x16x32_bf16 v[84:87], v[176:179], v[200:203], v[84:87]
	v_mfma_f32_16x16x32_bf16 v[76:79], v[184:187], v[200:203], 0
	v_mfma_f32_16x16x32_bf16 v[76:79], v[188:191], v[204:207], v[76:79]
	v_mfma_f32_16x16x32_bf16 v[72:75], v[188:191], v[212:215], 0
	v_mfma_f32_16x16x32_bf16 v[72:75], v[184:187], v[208:211], v[72:75]
	v_mfma_f32_16x16x32_bf16 v[64:67], v[192:195], v[208:211], 0
	v_mfma_f32_16x16x32_bf16 v[64:67], v[196:199], v[212:215], v[64:67]
	v_mfma_f32_16x16x32_bf16 v[68:71], v[196:199], v[204:207], 0
	v_mfma_f32_16x16x32_bf16 v[68:71], v[192:195], v[200:203], v[68:71]
	s_barrier
; #define STAGE(P, RS, SOFF, OFF, kt) do { const int _so = (SOFF) + (kt) * (BK * 2); \
;     _Pragma("unroll") for (int _i = 0; _i < 2; ++_i) { \
;       __builtin_amdgcn_raw_ptr_buffer_load_lds(RS, (__attribute__((address_space(3))) void*)((P) + wave * 1024 + _i * 8192), 16, OFF[_i], _so, 0, 0); } } while (0)
; #define LDA(dst, b, h) _Pragma("unroll") for (int m = 0; m < 4; ++m) _Pragma("unroll") for (int k = 0; k < 2; ++k) \
;     dst[m][k] = *reinterpret_cast<const bf16x8*>(SA(b, h) + lds_byte(wr * 64 + m * 16 + fr, k * 32 + fq * 8))
; #define LDB(dst, b, h) _Pragma("unroll") for (int n = 0; n < 2; ++n) _Pragma("unroll") for (int k = 0; k < 2; ++k) \
;     dst[n][k] = *reinterpret_cast<const bf16x8*>(SB(b, h) + lds_byte(wc * 32 + n * 16 + fr, k * 32 + fq * 8))
; #define WAIT_V(n) asm volatile("s_waitcnt vmcnt(" #n ")" ::: "memory")
; #define WAIT_L(n) asm volatile("s_waitcnt lgkmcnt(" #n ")" ::: "memory")
; #define BAR __builtin_amdgcn_s_barrier()
; #define SCHED __builtin_amdgcn_sched_barrier(0)
;     ...
;       LDA(At, 0, 1); STAGE(SA(0, 0), rsA, sA0, offA, t + 2);
;       BAR; WAIT_L(0); MMA(1, 0, At, B0); BAR; SCHED;
;       STAGE(SB(0, 1), rsB, sB1, offB, t + 2);
;       WAIT_V(6); BAR; MMA(1, 1, At, B1); BAR;
;       LDB(B0, 1, 0); SCHED; LDA(At, 1, 0); STAGE(SA(0, 1), rsA, sA1, offA, t + 2);
;       WAIT_L(8); BAR; WAIT_L(0); MMA(0, 0, At, B0); BAR; SCHED;
	s_add_i32 s47, s42, s17
	s_add_i32 s48, s47, 0x100
	s_mov_b32 m0, s0
	ds_read_b128 v[168:171], v130 offset:16384
	ds_read_b128 v[172:175], v130 offset:17408
	ds_read_b128 v[176:179], v133 offset:16384
	ds_read_b128 v[180:183], v133 offset:17408
	ds_read_b128 v[184:187], v132 offset:16384
	ds_read_b128 v[188:191], v132 offset:17408
	ds_read_b128 v[192:195], v131 offset:16384
	ds_read_b128 v[196:199], v131 offset:17408
	buffer_load_dwordx4 v142, s[4:7], s48 offen lds
	s_mov_b32 m0, s20
	s_nop 0
	buffer_load_dwordx4 v143, s[4:7], s48 offen lds
	s_barrier
	s_waitcnt lgkmcnt(6)
	v_mfma_f32_16x16x32_bf16 v[60:63], v[168:171], v[152:155], 0
	v_mfma_f32_16x16x32_bf16 v[60:63], v[172:175], v[156:159], v[60:63]
	v_mfma_f32_16x16x32_bf16 v[56:59], v[172:175], v[164:167], 0
	v_mfma_f32_16x16x32_bf16 v[56:59], v[168:171], v[160:163], v[56:59]
	s_waitcnt lgkmcnt(4)
	v_mfma_f32_16x16x32_bf16 v[48:51], v[176:179], v[160:163], 0
	v_mfma_f32_16x16x32_bf16 v[48:51], v[180:183], v[164:167], v[48:51]
	v_mfma_f32_16x16x32_bf16 v[52:55], v[180:183], v[156:159], 0
	v_mfma_f32_16x16x32_bf16 v[52:55], v[176:179], v[152:155], v[52:55]
	s_waitcnt lgkmcnt(2)
	v_mfma_f32_16x16x32_bf16 v[44:47], v[184:187], v[152:155], 0
	v_mfma_f32_16x16x32_bf16 v[44:47], v[188:191], v[156:159], v[44:47]
	v_mfma_f32_16x16x32_bf16 v[40:43], v[188:191], v[164:167], 0
	v_mfma_f32_16x16x32_bf16 v[40:43], v[184:187], v[160:163], v[40:43]
	s_waitcnt lgkmcnt(0)
	v_mfma_f32_16x16x32_bf16 v[32:35], v[192:195], v[160:163], 0
	v_mfma_f32_16x16x32_bf16 v[32:35], v[196:199], v[164:167], v[32:35]
	v_mfma_f32_16x16x32_bf16 v[36:39], v[196:199], v[156:159], 0
	v_mfma_f32_16x16x32_bf16 v[36:39], v[192:195], v[152:155], v[36:39]
	s_barrier
	s_add_i32 s48, s44, s17
	s_add_i32 s49, s48, 0x100
	s_mov_b32 m0, s21
	s_nop 0
	buffer_load_dwordx4 v142, s[8:11], s49 offen lds
	s_mov_b32 m0, s22
	s_nop 0
	buffer_load_dwordx4 v143, s[8:11], s49 offen lds
	s_waitcnt vmcnt(6)
	s_barrier
	v_mfma_f32_16x16x32_bf16 v[28:31], v[168:171], v[200:203], 0
	v_mfma_f32_16x16x32_bf16 v[28:31], v[172:175], v[204:207], v[28:31]
	v_mfma_f32_16x16x32_bf16 v[24:27], v[172:175], v[212:215], 0
	v_mfma_f32_16x16x32_bf16 v[24:27], v[168:171], v[208:211], v[24:27]
	v_mfma_f32_16x16x32_bf16 v[16:19], v[176:179], v[208:211], 0
	v_mfma_f32_16x16x32_bf16 v[16:19], v[180:183], v[212:215], v[16:19]
	v_mfma_f32_16x16x32_bf16 v[20:23], v[180:183], v[204:207], 0
	v_mfma_f32_16x16x32_bf16 v[20:23], v[176:179], v[200:203], v[20:23]
	v_mfma_f32_16x16x32_bf16 v[12:15], v[184:187], v[200:203], 0
	v_mfma_f32_16x16x32_bf16 v[12:15], v[188:191], v[204:207], v[12:15]
	v_mfma_f32_16x16x32_bf16 v[8:11], v[188:191], v[212:215], 0
	v_mfma_f32_16x16x32_bf16 v[8:11], v[184:187], v[208:211], v[8:11]
	v_mfma_f32_16x16x32_bf16 v[0:3], v[192:195], v[208:211], 0
	v_mfma_f32_16x16x32_bf16 v[0:3], v[196:199], v[212:215], v[0:3]
	v_mfma_f32_16x16x32_bf16 v[4:7], v[196:199], v[204:207], 0
	v_mfma_f32_16x16x32_bf16 v[4:7], v[192:195], v[200:203], v[4:7]
	s_barrier
	ds_read_b128 v[152:155], v138
	ds_read_b128 v[156:159], v139
	ds_read_b128 v[160:163], v140
	ds_read_b128 v[164:167], v141
	s_addk_i32 s18, 0x100
	s_mov_b32 m0, s23
	ds_read_b128 v[168:171], v130 offset:32768
	ds_read_b128 v[172:175], v130 offset:33792
	ds_read_b128 v[176:179], v133 offset:32768
	ds_read_b128 v[180:183], v133 offset:33792
	ds_read_b128 v[184:187], v132 offset:32768
	ds_read_b128 v[188:191], v132 offset:33792
	ds_read_b128 v[192:195], v131 offset:32768
	ds_read_b128 v[196:199], v131 offset:33792
	buffer_load_dwordx4 v142, s[4:7], s18 offen lds
	s_mov_b32 m0, s24
	s_nop 0
	buffer_load_dwordx4 v143, s[4:7], s18 offen lds
	s_waitcnt lgkmcnt(8)
	s_barrier
; #define STAGE(P, RS, SOFF, OFF, kt) do { const int _so = (SOFF) + (kt) * (BK * 2); \
;     _Pragma("unroll") for (int _i = 0; _i < 2; ++_i) { \
;       __builtin_amdgcn_raw_ptr_buffer_load_lds(RS, (__attribute__((address_space(3))) void*)((P) + wave * 1024 + _i * 8192), 16, OFF[_i], _so, 0, 0); } } while (0)
; #define LDA(dst, b, h) _Pragma("unroll") for (int m = 0; m < 4; ++m) _Pragma("unroll") for (int k = 0; k < 2; ++k) \
;     dst[m][k] = *reinterpret_cast<const bf16x8*>(SA(b, h) + lds_byte(wr * 64 + m * 16 + fr, k * 32 + fq * 8))
; #define LDB(dst, b, h) _Pragma("unroll") for (int n = 0; n < 2; ++n) _Pragma("unroll") for (int k = 0; k < 2; ++k) \
;     dst[n][k] = *reinterpret_cast<const bf16x8*>(SB(b, h) + lds_byte(wc * 32 + n * 16 + fr, k * 32 + fq * 8))
; #define WAIT_V(n) asm volatile("s_waitcnt vmcnt(" #n ")" ::: "memory")
; #define WAIT_L(n) asm volatile("s_waitcnt lgkmcnt(" #n ")" ::: "memory")
; #define BAR __builtin_amdgcn_s_barrier()
; #define SCHED __builtin_amdgcn_sched_barrier(0)
;     ...
;       WAIT_L(8); BAR; WAIT_L(0); MMA(0, 0, At, B0); BAR; SCHED;
;       LDB(B1, 1, 1); STAGE(SB(1, 0), rsB, sB0, offB, t + 3);
;       BAR; WAIT_L(0); MMA(0, 1, At, B1); BAR;
;       LDA(At, 1, 1); STAGE(SA(1, 0), rsA, sA0, offA, t + 3);
;       BAR; WAIT_L(0); MMA(1, 0, At, B0); BAR; SCHED;
;       STAGE(SB(1, 1), rsB, sB1, offB, t + 3);
;       WAIT_V(6); BAR; MMA(1, 1, At, B1); BAR;
	s_waitcnt lgkmcnt(6)
	v_mfma_f32_16x16x32_bf16 v[124:127], v[168:171], v[152:155], v[124:127]
	v_mfma_f32_16x16x32_bf16 v[124:127], v[172:175], v[156:159], v[124:127]
	v_mfma_f32_16x16x32_bf16 v[120:123], v[172:175], v[164:167], v[120:123]
	v_mfma_f32_16x16x32_bf16 v[120:123], v[168:171], v[160:163], v[120:123]
	s_waitcnt lgkmcnt(4)
	v_mfma_f32_16x16x32_bf16 v[112:115], v[176:179], v[160:163], v[112:115]
	v_mfma_f32_16x16x32_bf16 v[112:115], v[180:183], v[164:167], v[112:115]
	v_mfma_f32_16x16x32_bf16 v[116:119], v[180:183], v[156:159], v[116:119]
	v_mfma_f32_16x16x32_bf16 v[116:119], v[176:179], v[152:155], v[116:119]
	s_waitcnt lgkmcnt(2)
	v_mfma_f32_16x16x32_bf16 v[108:111], v[184:187], v[152:155], v[108:111]
	v_mfma_f32_16x16x32_bf16 v[108:111], v[188:191], v[156:159], v[108:111]
	v_mfma_f32_16x16x32_bf16 v[104:107], v[188:191], v[164:167], v[104:107]
	v_mfma_f32_16x16x32_bf16 v[104:107], v[184:187], v[160:163], v[104:107]
	s_waitcnt lgkmcnt(0)
	v_mfma_f32_16x16x32_bf16 v[96:99], v[192:195], v[160:163], v[96:99]
	v_mfma_f32_16x16x32_bf16 v[96:99], v[196:199], v[164:167], v[96:99]
	v_mfma_f32_16x16x32_bf16 v[100:103], v[196:199], v[156:159], v[100:103]
	v_mfma_f32_16x16x32_bf16 v[100:103], v[192:195], v[152:155], v[100:103]
	s_barrier
	s_addk_i32 s19, 0x180
	s_mov_b32 m0, s25
	ds_read_b128 v[200:203], v134
	ds_read_b128 v[204:207], v135
	ds_read_b128 v[208:211], v136
	ds_read_b128 v[212:215], v137
	buffer_load_dwordx4 v142, s[8:11], s19 offen lds
	s_mov_b32 m0, s26
	s_nop 0
	buffer_load_dwordx4 v143, s[8:11], s19 offen lds
	s_barrier
	s_waitcnt lgkmcnt(2)
	v_mfma_f32_16x16x32_bf16 v[92:95], v[168:171], v[200:203], v[92:95]
	v_mfma_f32_16x16x32_bf16 v[92:95], v[172:175], v[204:207], v[92:95]
	s_waitcnt lgkmcnt(0)
	v_mfma_f32_16x16x32_bf16 v[88:91], v[172:175], v[212:215], v[88:91]
	v_mfma_f32_16x16x32_bf16 v[88:91], v[168:171], v[208:211], v[88:91]
	v_mfma_f32_16x16x32_bf16 v[80:83], v[176:179], v[208:211], v[80:83]
	v_mfma_f32_16x16x32_bf16 v[80:83], v[180:183], v[212:215], v[80:83]
	v_mfma_f32_16x16x32_bf16 v[84:87], v[180:183], v[204:207], v[84:87]
	v_mfma_f32_16x16x32_bf16 v[84:87], v[176:179], v[200:203], v[84:87]
	v_mfma_f32_16x16x32_bf16 v[76:79], v[184:187], v[200:203], v[76:79]
	v_mfma_f32_16x16x32_bf16 v[76:79], v[188:191], v[204:207], v[76:79]
	v_mfma_f32_16x16x32_bf16 v[72:75], v[188:191], v[212:215], v[72:75]
	v_mfma_f32_16x16x32_bf16 v[72:75], v[184:187], v[208:211], v[72:75]
	v_mfma_f32_16x16x32_bf16 v[64:67], v[192:195], v[208:211], v[64:67]
	v_mfma_f32_16x16x32_bf16 v[64:67], v[196:199], v[212:215], v[64:67]
	v_mfma_f32_16x16x32_bf16 v[68:71], v[196:199], v[204:207], v[68:71]
	v_mfma_f32_16x16x32_bf16 v[68:71], v[192:195], v[200:203], v[68:71]
	s_barrier
	s_addk_i32 s47, 0x180
	s_mov_b32 m0, s27
	ds_read_b128 v[168:171], v130 offset:49152
	ds_read_b128 v[172:175], v130 offset:50176
	ds_read_b128 v[176:179], v133 offset:49152
	ds_read_b128 v[180:183], v133 offset:50176
	ds_read_b128 v[184:187], v132 offset:49152
	ds_read_b128 v[188:191], v132 offset:50176
	ds_read_b128 v[192:195], v131 offset:49152
	ds_read_b128 v[196:199], v131 offset:50176
	buffer_load_dwordx4 v142, s[4:7], s47 offen lds
	s_mov_b32 m0, s28
	s_nop 0
	buffer_load_dwordx4 v143, s[4:7], s47 offen lds
	s_barrier
	s_waitcnt lgkmcnt(6)
	v_mfma_f32_16x16x32_bf16 v[60:63], v[168:171], v[152:155], v[60:63]
	v_mfma_f32_16x16x32_bf16 v[60:63], v[172:175], v[156:159], v[60:63]
	v_mfma_f32_16x16x32_bf16 v[56:59], v[172:175], v[164:167], v[56:59]
	v_mfma_f32_16x16x32_bf16 v[56:59], v[168:171], v[160:163], v[56:59]
	s_waitcnt lgkmcnt(4)
	v_mfma_f32_16x16x32_bf16 v[48:51], v[176:179], v[160:163], v[48:51]
	v_mfma_f32_16x16x32_bf16 v[48:51], v[180:183], v[164:167], v[48:51]
	v_mfma_f32_16x16x32_bf16 v[52:55], v[180:183], v[156:159], v[52:55]
	v_mfma_f32_16x16x32_bf16 v[52:55], v[176:179], v[152:155], v[52:55]
	s_waitcnt lgkmcnt(2)
	v_mfma_f32_16x16x32_bf16 v[44:47], v[184:187], v[152:155], v[44:47]
	v_mfma_f32_16x16x32_bf16 v[44:47], v[188:191], v[156:159], v[44:47]
	v_mfma_f32_16x16x32_bf16 v[40:43], v[188:191], v[164:167], v[40:43]
	v_mfma_f32_16x16x32_bf16 v[40:43], v[184:187], v[160:163], v[40:43]
	s_waitcnt lgkmcnt(0)
	v_mfma_f32_16x16x32_bf16 v[32:35], v[192:195], v[160:163], v[32:35]
	v_mfma_f32_16x16x32_bf16 v[32:35], v[196:199], v[164:167], v[32:35]
	v_mfma_f32_16x16x32_bf16 v[36:39], v[196:199], v[156:159], v[36:39]
	v_mfma_f32_16x16x32_bf16 v[36:39], v[192:195], v[152:155], v[36:39]
	s_barrier
	s_addk_i32 s48, 0x180
	s_mov_b32 m0, s29
	s_nop 0
	buffer_load_dwordx4 v142, s[8:11], s48 offen lds
	s_mov_b32 m0, s30
	s_nop 0
	buffer_load_dwordx4 v143, s[8:11], s48 offen lds
	s_add_i32 s16, s16, 2
	s_addk_i32 s17, 0x100
	s_cmp_gt_u32 s16, 27
	s_cbranch_scc0 .LBB0_225
	s_branch .Lmy_post_225

; #define STAGE(P, RS, SOFF, OFF, kt) do { const int _so = (SOFF) + (kt) * (BK * 2); \
;     _Pragma("unroll") for (int _i = 0; _i < 2; ++_i) { \
;       __builtin_amdgcn_raw_ptr_buffer_load_lds(RS, (__attribute__((address_space(3))) void*)((P) + wave * 1024 + _i * 8192), 16, OFF[_i], _so, 0, 0); } } while (0)
; #define LDA(dst, b, h) _Pragma("unroll") for (int m = 0; m < 4; ++m) _Pragma("unroll") for (int k = 0; k < 2; ++k) \
;     dst[m][k] = *reinterpret_cast<const bf16x8*>(SA(b, h) + lds_byte(wr * 64 + m * 16 + fr, k * 32 + fq * 8))
; #define LDB(dst, b, h) _Pragma("unroll") for (int n = 0; n < 2; ++n) _Pragma("unroll") for (int k = 0; k < 2; ++k) \
;     dst[n][k] = *reinterpret_cast<const bf16x8*>(SB(b, h) + lds_byte(wc * 32 + n * 16 + fr, k * 32 + fq * 8))
; #define WAIT_V(n) asm volatile("s_waitcnt vmcnt(" #n ")" ::: "memory")
; #define WAIT_L(n) asm volatile("s_waitcnt lgkmcnt(" #n ")" ::: "memory")
; #define BAR __builtin_amdgcn_s_barrier()
; #define SCHED __builtin_amdgcn_sched_barrier(0)
;     ...
;       LDB(B0, 0, 0); SCHED; LDA(At, 0, 0); STAGE(SA(1, 1), rsA, sA1, offA, t + 1);
;       WAIT_L(8); BAR; WAIT_L(0); MMA(0, 0, At, B0); BAR; SCHED;
;       LDB(B1, 0, 1); STAGE(SB(0, 0), rsB, sB0, offB, t + 2);
;       BAR; WAIT_L(0); MMA(0, 1, At, B1); BAR;
;       LDA(At, 0, 1); STAGE(SA(0, 0), rsA, sA0, offA, t + 2);
;       BAR; WAIT_L(0); MMA(1, 0, At, B0); BAR; SCHED;
;       STAGE(SB(0, 1), rsB, sB1, offB, t + 2);
;       WAIT_V(6); BAR; MMA(1, 1, At, B1); BAR;
.Lmy_rot_225:
	ds_read_b128 v[152:155], v148
	ds_read_b128 v[156:159], v149
	ds_read_b128 v[160:163], v150
	ds_read_b128 v[164:167], v151
	s_add_i32 s18, s41, s17
	s_add_i32 s19, s18, 0x80
	s_mov_b32 m0, s33
	ds_read_b128 v[168:171], v130
	ds_read_b128 v[172:175], v130 offset:1024
	ds_read_b128 v[176:179], v133
	ds_read_b128 v[180:183], v133 offset:1024
	ds_read_b128 v[184:187], v132
	ds_read_b128 v[188:191], v132 offset:1024
	ds_read_b128 v[192:195], v131
	ds_read_b128 v[196:199], v131 offset:1024
	buffer_load_dwordx4 v142, s[4:7], s19 offen lds
	s_mov_b32 m0, s34
	s_nop 0
	buffer_load_dwordx4 v143, s[4:7], s19 offen lds
	s_waitcnt lgkmcnt(8)
	s_barrier
	s_waitcnt lgkmcnt(0)
	v_mfma_f32_16x16x32_bf16 v[124:127], v[168:171], v[152:155], v[124:127]
	v_mfma_f32_16x16x32_bf16 v[124:127], v[172:175], v[156:159], v[124:127]
	v_mfma_f32_16x16x32_bf16 v[120:123], v[172:175], v[164:167], v[120:123]
	v_mfma_f32_16x16x32_bf16 v[120:123], v[168:171], v[160:163], v[120:123]
	v_mfma_f32_16x16x32_bf16 v[112:115], v[176:179], v[160:163], v[112:115]
	v_mfma_f32_16x16x32_bf16 v[112:115], v[180:183], v[164:167], v[112:115]
	v_mfma_f32_16x16x32_bf16 v[116:119], v[180:183], v[156:159], v[116:119]
	v_mfma_f32_16x16x32_bf16 v[116:119], v[176:179], v[152:155], v[116:119]
	v_mfma_f32_16x16x32_bf16 v[108:111], v[184:187], v[152:155], v[108:111]
	v_mfma_f32_16x16x32_bf16 v[108:111], v[188:191], v[156:159], v[108:111]
	v_mfma_f32_16x16x32_bf16 v[104:107], v[188:191], v[164:167], v[104:107]
	v_mfma_f32_16x16x32_bf16 v[104:107], v[184:187], v[160:163], v[104:107]
	v_mfma_f32_16x16x32_bf16 v[96:99], v[192:195], v[160:163], v[96:99]
	v_mfma_f32_16x16x32_bf16 v[96:99], v[196:199], v[164:167], v[96:99]
	v_mfma_f32_16x16x32_bf16 v[100:103], v[196:199], v[156:159], v[100:103]
	v_mfma_f32_16x16x32_bf16 v[100:103], v[192:195], v[152:155], v[100:103]
	s_barrier
	s_add_i32 s19, s43, s17
	s_add_i32 s47, s19, 0x100
	s_mov_b32 m0, s1
	ds_read_b128 v[200:203], v144
	ds_read_b128 v[204:207], v145
	ds_read_b128 v[208:211], v146
	ds_read_b128 v[212:215], v147
	buffer_load_dwordx4 v142, s[8:11], s47 offen lds
	s_mov_b32 m0, s3
	s_nop 0
	buffer_load_dwordx4 v143, s[8:11], s47 offen lds
	s_barrier
	s_waitcnt lgkmcnt(2)
	v_mfma_f32_16x16x32_bf16 v[92:95], v[168:171], v[200:203], v[92:95]
	v_mfma_f32_16x16x32_bf16 v[92:95], v[172:175], v[204:207], v[92:95]
	s_waitcnt lgkmcnt(0)
	v_mfma_f32_16x16x32_bf16 v[88:91], v[172:175], v[212:215], v[88:91]
	v_mfma_f32_16x16x32_bf16 v[88:91], v[168:171], v[208:211], v[88:91]
	v_mfma_f32_16x16x32_bf16 v[80:83], v[176:179], v[208:211], v[80:83]
	v_mfma_f32_16x16x32_bf16 v[80:83], v[180:183], v[212:215], v[80:83]
	v_mfma_f32_16x16x32_bf16 v[84:87], v[180:183], v[204:207], v[84:87]
	v_mfma_f32_16x16x32_bf16 v[84:87], v[176:179], v[200:203], v[84:87]
	v_mfma_f32_16x16x32_bf16 v[76:79], v[184:187], v[200:203], v[76:79]
	v_mfma_f32_16x16x32_bf16 v[76:79], v[188:191], v[204:207], v[76:79]
	v_mfma_f32_16x16x32_bf16 v[72:75], v[188:191], v[212:215], v[72:75]
	v_mfma_f32_16x16x32_bf16 v[72:75], v[184:187], v[208:211], v[72:75]
	v_mfma_f32_16x16x32_bf16 v[64:67], v[192:195], v[208:211], v[64:67]
	v_mfma_f32_16x16x32_bf16 v[64:67], v[196:199], v[212:215], v[64:67]
	v_mfma_f32_16x16x32_bf16 v[68:71], v[196:199], v[204:207], v[68:71]
	v_mfma_f32_16x16x32_bf16 v[68:71], v[192:195], v[200:203], v[68:71]
	s_barrier
	s_add_i32 s47, s42, s17
	s_add_i32 s48, s47, 0x100
	s_mov_b32 m0, s0
	ds_read_b128 v[168:171], v130 offset:16384
	ds_read_b128 v[172:175], v130 offset:17408
	ds_read_b128 v[176:179], v133 offset:16384
	ds_read_b128 v[180:183], v133 offset:17408
	ds_read_b128 v[184:187], v132 offset:16384
	ds_read_b128 v[188:191], v132 offset:17408
	ds_read_b128 v[192:195], v131 offset:16384
	ds_read_b128 v[196:199], v131 offset:17408
	buffer_load_dwordx4 v142, s[4:7], s48 offen lds
	s_mov_b32 m0, s20
	s_nop 0
	buffer_load_dwordx4 v143, s[4:7], s48 offen lds
	s_barrier
	s_waitcnt lgkmcnt(6)
	v_mfma_f32_16x16x32_bf16 v[60:63], v[168:171], v[152:155], v[60:63]
	v_mfma_f32_16x16x32_bf16 v[60:63], v[172:175], v[156:159], v[60:63]
	v_mfma_f32_16x16x32_bf16 v[56:59], v[172:175], v[164:167], v[56:59]
	v_mfma_f32_16x16x32_bf16 v[56:59], v[168:171], v[160:163], v[56:59]
	s_waitcnt lgkmcnt(4)
	v_mfma_f32_16x16x32_bf16 v[48:51], v[176:179], v[160:163], v[48:51]
	v_mfma_f32_16x16x32_bf16 v[48:51], v[180:183], v[164:167], v[48:51]
	v_mfma_f32_16x16x32_bf16 v[52:55], v[180:183], v[156:159], v[52:55]
	v_mfma_f32_16x16x32_bf16 v[52:55], v[176:179], v[152:155], v[52:55]
	s_waitcnt lgkmcnt(2)
	v_mfma_f32_16x16x32_bf16 v[44:47], v[184:187], v[152:155], v[44:47]
	v_mfma_f32_16x16x32_bf16 v[44:47], v[188:191], v[156:159], v[44:47]
	v_mfma_f32_16x16x32_bf16 v[40:43], v[188:191], v[164:167], v[40:43]
	v_mfma_f32_16x16x32_bf16 v[40:43], v[184:187], v[160:163], v[40:43]
	s_waitcnt lgkmcnt(0)
	v_mfma_f32_16x16x32_bf16 v[32:35], v[192:195], v[160:163], v[32:35]
	v_mfma_f32_16x16x32_bf16 v[32:35], v[196:199], v[164:167], v[32:35]
	v_mfma_f32_16x16x32_bf16 v[36:39], v[196:199], v[156:159], v[36:39]
	v_mfma_f32_16x16x32_bf16 v[36:39], v[192:195], v[152:155], v[36:39]
	s_barrier
	s_add_i32 s48, s44, s17
	s_add_i32 s49, s48, 0x100
	s_mov_b32 m0, s21
	s_nop 0
	buffer_load_dwordx4 v142, s[8:11], s49 offen lds
	s_mov_b32 m0, s22
	s_nop 0
	buffer_load_dwordx4 v143, s[8:11], s49 offen lds
	s_waitcnt vmcnt(6)
	s_barrier
; #define STAGE(P, RS, SOFF, OFF, kt) do { const int _so = (SOFF) + (kt) * (BK * 2); \
;     _Pragma("unroll") for (int _i = 0; _i < 2; ++_i) { \
;       __builtin_amdgcn_raw_ptr_buffer_load_lds(RS, (__attribute__((address_space(3))) void*)((P) + wave * 1024 + _i * 8192), 16, OFF[_i], _so, 0, 0); } } while (0)
; #define LDA(dst, b, h) _Pragma("unroll") for (int m = 0; m < 4; ++m) _Pragma("unroll") for (int k = 0; k < 2; ++k) \
;     dst[m][k] = *reinterpret_cast<const bf16x8*>(SA(b, h) + lds_byte(wr * 64 + m * 16 + fr, k * 32 + fq * 8))
; #define LDB(dst, b, h) _Pragma("unroll") for (int n = 0; n < 2; ++n) _Pragma("unroll") for (int k = 0; k < 2; ++k) \
;     dst[n][k] = *reinterpret_cast<const bf16x8*>(SB(b, h) + lds_byte(wc * 32 + n * 16 + fr, k * 32 + fq * 8))
; #define WAIT_V(n) asm volatile("s_waitcnt vmcnt(" #n ")" ::: "memory")
; #define WAIT_L(n) asm volatile("s_waitcnt lgkmcnt(" #n ")" ::: "memory")
; #define BAR __builtin_amdgcn_s_barrier()
; #define SCHED __builtin_amdgcn_sched_barrier(0)
;     ...
;       WAIT_V(6); BAR; MMA(1, 1, At, B1); BAR;
;       LDB(B0, 1, 0); SCHED; LDA(At, 1, 0); STAGE(SA(0, 1), rsA, sA1, offA, t + 2);
;       WAIT_L(8); BAR; WAIT_L(0); MMA(0, 0, At, B0); BAR; SCHED;
;       LDB(B1, 1, 1); STAGE(SB(1, 0), rsB, sB0, offB, t + 3);
;       BAR; WAIT_L(0); MMA(0, 1, At, B1); BAR;
;       LDA(At, 1, 1); STAGE(SA(1, 0), rsA, sA0, offA, t + 3);
;       BAR; WAIT_L(0); MMA(1, 0, At, B0); BAR; SCHED;
;       STAGE(SB(1, 1), rsB, sB1, offB, t + 3);
;       WAIT_V(6); BAR; MMA(1, 1, At, B1); BAR;
	v_mfma_f32_16x16x32_bf16 v[28:31], v[168:171], v[200:203], v[28:31]
	v_mfma_f32_16x16x32_bf16 v[28:31], v[172:175], v[204:207], v[28:31]
	v_mfma_f32_16x16x32_bf16 v[24:27], v[172:175], v[212:215], v[24:27]
	v_mfma_f32_16x16x32_bf16 v[24:27], v[168:171], v[208:211], v[24:27]
	v_mfma_f32_16x16x32_bf16 v[16:19], v[176:179], v[208:211], v[16:19]
	v_mfma_f32_16x16x32_bf16 v[16:19], v[180:183], v[212:215], v[16:19]
	v_mfma_f32_16x16x32_bf16 v[20:23], v[180:183], v[204:207], v[20:23]
	v_mfma_f32_16x16x32_bf16 v[20:23], v[176:179], v[200:203], v[20:23]
	v_mfma_f32_16x16x32_bf16 v[12:15], v[184:187], v[200:203], v[12:15]
	v_mfma_f32_16x16x32_bf16 v[12:15], v[188:191], v[204:207], v[12:15]
	v_mfma_f32_16x16x32_bf16 v[8:11], v[188:191], v[212:215], v[8:11]
	v_mfma_f32_16x16x32_bf16 v[8:11], v[184:187], v[208:211], v[8:11]
	v_mfma_f32_16x16x32_bf16 v[0:3], v[192:195], v[208:211], v[0:3]
	v_mfma_f32_16x16x32_bf16 v[0:3], v[196:199], v[212:215], v[0:3]
	v_mfma_f32_16x16x32_bf16 v[4:7], v[196:199], v[204:207], v[4:7]
	v_mfma_f32_16x16x32_bf16 v[4:7], v[192:195], v[200:203], v[4:7]
	s_barrier
	ds_read_b128 v[152:155], v138
	ds_read_b128 v[156:159], v139
	ds_read_b128 v[160:163], v140
	ds_read_b128 v[164:167], v141
	s_addk_i32 s18, 0x100
	s_mov_b32 m0, s23
	ds_read_b128 v[168:171], v130 offset:32768
	ds_read_b128 v[172:175], v130 offset:33792
	ds_read_b128 v[176:179], v133 offset:32768
	ds_read_b128 v[180:183], v133 offset:33792
	ds_read_b128 v[184:187], v132 offset:32768
	ds_read_b128 v[188:191], v132 offset:33792
	ds_read_b128 v[192:195], v131 offset:32768
	ds_read_b128 v[196:199], v131 offset:33792
	buffer_load_dwordx4 v142, s[4:7], s18 offen lds
	s_mov_b32 m0, s24
	s_nop 0
	buffer_load_dwordx4 v143, s[4:7], s18 offen lds
	s_waitcnt lgkmcnt(8)
	s_barrier
	s_waitcnt lgkmcnt(6)
	v_mfma_f32_16x16x32_bf16 v[124:127], v[168:171], v[152:155], v[124:127]
	v_mfma_f32_16x16x32_bf16 v[124:127], v[172:175], v[156:159], v[124:127]
	v_mfma_f32_16x16x32_bf16 v[120:123], v[172:175], v[164:167], v[120:123]
	v_mfma_f32_16x16x32_bf16 v[120:123], v[168:171], v[160:163], v[120:123]
	s_waitcnt lgkmcnt(4)
	v_mfma_f32_16x16x32_bf16 v[112:115], v[176:179], v[160:163], v[112:115]
	v_mfma_f32_16x16x32_bf16 v[112:115], v[180:183], v[164:167], v[112:115]
	v_mfma_f32_16x16x32_bf16 v[116:119], v[180:183], v[156:159], v[116:119]
	v_mfma_f32_16x16x32_bf16 v[116:119], v[176:179], v[152:155], v[116:119]
	s_waitcnt lgkmcnt(2)
	v_mfma_f32_16x16x32_bf16 v[108:111], v[184:187], v[152:155], v[108:111]
	v_mfma_f32_16x16x32_bf16 v[108:111], v[188:191], v[156:159], v[108:111]
	v_mfma_f32_16x16x32_bf16 v[104:107], v[188:191], v[164:167], v[104:107]
	v_mfma_f32_16x16x32_bf16 v[104:107], v[184:187], v[160:163], v[104:107]
	s_waitcnt lgkmcnt(0)
	v_mfma_f32_16x16x32_bf16 v[96:99], v[192:195], v[160:163], v[96:99]
	v_mfma_f32_16x16x32_bf16 v[96:99], v[196:199], v[164:167], v[96:99]
	v_mfma_f32_16x16x32_bf16 v[100:103], v[196:199], v[156:159], v[100:103]
	v_mfma_f32_16x16x32_bf16 v[100:103], v[192:195], v[152:155], v[100:103]
	s_barrier
	s_addk_i32 s19, 0x180
	s_mov_b32 m0, s25
	ds_read_b128 v[200:203], v134
	ds_read_b128 v[204:207], v135
	ds_read_b128 v[208:211], v136
	ds_read_b128 v[212:215], v137
	buffer_load_dwordx4 v142, s[8:11], s19 offen lds
	s_mov_b32 m0, s26
	s_nop 0
	buffer_load_dwordx4 v143, s[8:11], s19 offen lds
	s_barrier
	s_waitcnt lgkmcnt(2)
	v_mfma_f32_16x16x32_bf16 v[92:95], v[168:171], v[200:203], v[92:95]
	v_mfma_f32_16x16x32_bf16 v[92:95], v[172:175], v[204:207], v[92:95]
	s_waitcnt lgkmcnt(0)
	v_mfma_f32_16x16x32_bf16 v[88:91], v[172:175], v[212:215], v[88:91]
	v_mfma_f32_16x16x32_bf16 v[88:91], v[168:171], v[208:211], v[88:91]
	v_mfma_f32_16x16x32_bf16 v[80:83], v[176:179], v[208:211], v[80:83]
	v_mfma_f32_16x16x32_bf16 v[80:83], v[180:183], v[212:215], v[80:83]
	v_mfma_f32_16x16x32_bf16 v[84:87], v[180:183], v[204:207], v[84:87]
	v_mfma_f32_16x16x32_bf16 v[84:87], v[176:179], v[200:203], v[84:87]
	v_mfma_f32_16x16x32_bf16 v[76:79], v[184:187], v[200:203], v[76:79]
	v_mfma_f32_16x16x32_bf16 v[76:79], v[188:191], v[204:207], v[76:79]
	v_mfma_f32_16x16x32_bf16 v[72:75], v[188:191], v[212:215], v[72:75]
	v_mfma_f32_16x16x32_bf16 v[72:75], v[184:187], v[208:211], v[72:75]
	v_mfma_f32_16x16x32_bf16 v[64:67], v[192:195], v[208:211], v[64:67]
	v_mfma_f32_16x16x32_bf16 v[64:67], v[196:199], v[212:215], v[64:67]
	v_mfma_f32_16x16x32_bf16 v[68:71], v[196:199], v[204:207], v[68:71]
	v_mfma_f32_16x16x32_bf16 v[68:71], v[192:195], v[200:203], v[68:71]
	s_barrier
	s_addk_i32 s47, 0x180
	s_mov_b32 m0, s27
	ds_read_b128 v[168:171], v130 offset:49152
	ds_read_b128 v[172:175], v130 offset:50176
	ds_read_b128 v[176:179], v133 offset:49152
	ds_read_b128 v[180:183], v133 offset:50176
	ds_read_b128 v[184:187], v132 offset:49152
	ds_read_b128 v[188:191], v132 offset:50176
	ds_read_b128 v[192:195], v131 offset:49152
	ds_read_b128 v[196:199], v131 offset:50176
	buffer_load_dwordx4 v142, s[4:7], s47 offen lds
	s_mov_b32 m0, s28
	s_nop 0
	buffer_load_dwordx4 v143, s[4:7], s47 offen lds
	s_barrier
	s_waitcnt lgkmcnt(6)
	v_mfma_f32_16x16x32_bf16 v[60:63], v[168:171], v[152:155], v[60:63]
	v_mfma_f32_16x16x32_bf16 v[60:63], v[172:175], v[156:159], v[60:63]
	v_mfma_f32_16x16x32_bf16 v[56:59], v[172:175], v[164:167], v[56:59]
	v_mfma_f32_16x16x32_bf16 v[56:59], v[168:171], v[160:163], v[56:59]
	s_waitcnt lgkmcnt(4)
	v_mfma_f32_16x16x32_bf16 v[48:51], v[176:179], v[160:163], v[48:51]
	v_mfma_f32_16x16x32_bf16 v[48:51], v[180:183], v[164:167], v[48:51]
	v_mfma_f32_16x16x32_bf16 v[52:55], v[180:183], v[156:159], v[52:55]
	v_mfma_f32_16x16x32_bf16 v[52:55], v[176:179], v[152:155], v[52:55]
	s_waitcnt lgkmcnt(2)
	v_mfma_f32_16x16x32_bf16 v[44:47], v[184:187], v[152:155], v[44:47]
	v_mfma_f32_16x16x32_bf16 v[44:47], v[188:191], v[156:159], v[44:47]
	v_mfma_f32_16x16x32_bf16 v[40:43], v[188:191], v[164:167], v[40:43]
	v_mfma_f32_16x16x32_bf16 v[40:43], v[184:187], v[160:163], v[40:43]
	s_waitcnt lgkmcnt(0)
	v_mfma_f32_16x16x32_bf16 v[32:35], v[192:195], v[160:163], v[32:35]
	v_mfma_f32_16x16x32_bf16 v[32:35], v[196:199], v[164:167], v[32:35]
	v_mfma_f32_16x16x32_bf16 v[36:39], v[196:199], v[156:159], v[36:39]
	v_mfma_f32_16x16x32_bf16 v[36:39], v[192:195], v[152:155], v[36:39]
	s_barrier
	s_addk_i32 s48, 0x180
	s_mov_b32 m0, s29
	s_nop 0
	buffer_load_dwordx4 v142, s[8:11], s48 offen lds
	s_mov_b32 m0, s30
	s_nop 0
	buffer_load_dwordx4 v143, s[8:11], s48 offen lds
	s_add_i32 s16, s16, 2
	s_addk_i32 s17, 0x100
	s_cmp_gt_u32 s16, 27
	s_cbranch_scc0 .LBB0_225
; #define STAGE(P, RS, SOFF, OFF, kt) do { const int _so = (SOFF) + (kt) * (BK * 2); \
;     _Pragma("unroll") for (int _i = 0; _i < 2; ++_i) { \
;       __builtin_amdgcn_raw_ptr_buffer_load_lds(RS, (__attribute__((address_space(3))) void*)((P) + wave * 1024 + _i * 8192), 16, OFF[_i], _so, 0, 0); } } while (0)
; #define LDA(dst, b, h) _Pragma("unroll") for (int m = 0; m < 4; ++m) _Pragma("unroll") for (int k = 0; k < 2; ++k) \
;     dst[m][k] = *reinterpret_cast<const bf16x8*>(SA(b, h) + lds_byte(wr * 64 + m * 16 + fr, k * 32 + fq * 8))
; #define LDB(dst, b, h) _Pragma("unroll") for (int n = 0; n < 2; ++n) _Pragma("unroll") for (int k = 0; k < 2; ++k) \
;     dst[n][k] = *reinterpret_cast<const bf16x8*>(SB(b, h) + lds_byte(wc * 32 + n * 16 + fr, k * 32 + fq * 8))
; #define WAIT_V(n) asm volatile("s_waitcnt vmcnt(" #n ")" ::: "memory")
; #define WAIT_L(n) asm volatile("s_waitcnt lgkmcnt(" #n ")" ::: "memory")
; #define BAR __builtin_amdgcn_s_barrier()
;     ...
;       WAIT_V(6); BAR; MMA(1, 1, At, B1); BAR;
;     }
;     { LDB(B0, 0, 0); LDA(At, 0, 0); STAGE(SA(1, 1), rsA, sA1, offA, nt - 1);
;       BAR; WAIT_L(0); MMA(0, 0, At, B0); BAR;
;       LDB(B1, 0, 1); BAR; WAIT_L(0); MMA(0, 1, At, B1); BAR;
;       LDA(At, 0, 1); WAIT_V(4); BAR; WAIT_L(0); MMA(1, 0, At, B0); MMA(1, 1, At, B1); BAR; }
.Lmy_post_225:
	s_waitcnt vmcnt(6)
	s_barrier
	v_mfma_f32_16x16x32_bf16 v[28:31], v[168:171], v[200:203], v[28:31]
	v_mfma_f32_16x16x32_bf16 v[28:31], v[172:175], v[204:207], v[28:31]
	v_mfma_f32_16x16x32_bf16 v[24:27], v[172:175], v[212:215], v[24:27]
	v_mfma_f32_16x16x32_bf16 v[24:27], v[168:171], v[208:211], v[24:27]
	v_mfma_f32_16x16x32_bf16 v[16:19], v[176:179], v[208:211], v[16:19]
	v_mfma_f32_16x16x32_bf16 v[16:19], v[180:183], v[212:215], v[16:19]
	v_mfma_f32_16x16x32_bf16 v[20:23], v[180:183], v[204:207], v[20:23]
	v_mfma_f32_16x16x32_bf16 v[20:23], v[176:179], v[200:203], v[20:23]
	v_mfma_f32_16x16x32_bf16 v[12:15], v[184:187], v[200:203], v[12:15]
	v_mfma_f32_16x16x32_bf16 v[12:15], v[188:191], v[204:207], v[12:15]
	v_mfma_f32_16x16x32_bf16 v[8:11], v[188:191], v[212:215], v[8:11]
	v_mfma_f32_16x16x32_bf16 v[8:11], v[184:187], v[208:211], v[8:11]
	v_mfma_f32_16x16x32_bf16 v[0:3], v[192:195], v[208:211], v[0:3]
	v_mfma_f32_16x16x32_bf16 v[0:3], v[196:199], v[212:215], v[0:3]
	v_mfma_f32_16x16x32_bf16 v[4:7], v[196:199], v[204:207], v[4:7]
	v_mfma_f32_16x16x32_bf16 v[4:7], v[192:195], v[200:203], v[4:7]
	s_barrier
	s_add_i32 s16, s41, 0xf80
	s_mov_b32 m0, s33
	ds_read_b128 v[152:155], v148
	ds_read_b128 v[156:159], v149
	ds_read_b128 v[160:163], v150
	ds_read_b128 v[148:151], v151
	ds_read_b128 v[164:167], v130
	ds_read_b128 v[168:171], v130 offset:1024
	ds_read_b128 v[172:175], v133
	ds_read_b128 v[176:179], v133 offset:1024
	ds_read_b128 v[180:183], v132
	ds_read_b128 v[184:187], v132 offset:1024
	ds_read_b128 v[188:191], v131
	ds_read_b128 v[192:195], v131 offset:1024
	buffer_load_dwordx4 v142, s[4:7], s16 offen lds
	s_mov_b32 m0, s34
	s_nop 0
	buffer_load_dwordx4 v143, s[4:7], s16 offen lds
	s_barrier
	s_waitcnt lgkmcnt(6)
	v_mfma_f32_16x16x32_bf16 v[124:127], v[164:167], v[152:155], v[124:127]
	v_mfma_f32_16x16x32_bf16 v[124:127], v[168:171], v[156:159], v[124:127]
	v_mfma_f32_16x16x32_bf16 v[120:123], v[168:171], v[148:151], v[120:123]
	v_mfma_f32_16x16x32_bf16 v[120:123], v[164:167], v[160:163], v[120:123]
	s_waitcnt lgkmcnt(4)
	v_mfma_f32_16x16x32_bf16 v[112:115], v[172:175], v[160:163], v[112:115]
	v_mfma_f32_16x16x32_bf16 v[112:115], v[176:179], v[148:151], v[112:115]
	v_mfma_f32_16x16x32_bf16 v[116:119], v[176:179], v[156:159], v[116:119]
	v_mfma_f32_16x16x32_bf16 v[116:119], v[172:175], v[152:155], v[116:119]
	s_waitcnt lgkmcnt(2)
	v_mfma_f32_16x16x32_bf16 v[108:111], v[180:183], v[152:155], v[108:111]
	v_mfma_f32_16x16x32_bf16 v[108:111], v[184:187], v[156:159], v[108:111]
	v_mfma_f32_16x16x32_bf16 v[104:107], v[184:187], v[148:151], v[104:107]
	v_mfma_f32_16x16x32_bf16 v[104:107], v[180:183], v[160:163], v[104:107]
	s_waitcnt lgkmcnt(0)
	v_mfma_f32_16x16x32_bf16 v[96:99], v[188:191], v[160:163], v[96:99]
	v_mfma_f32_16x16x32_bf16 v[96:99], v[192:195], v[148:151], v[96:99]
	v_mfma_f32_16x16x32_bf16 v[100:103], v[192:195], v[156:159], v[100:103]
	v_mfma_f32_16x16x32_bf16 v[100:103], v[188:191], v[152:155], v[100:103]
	s_barrier
	ds_read_b128 v[196:199], v144
	ds_read_b128 v[142:145], v145
	ds_read_b128 v[200:203], v146
	ds_read_b128 v[204:207], v147
	s_barrier
	s_waitcnt lgkmcnt(1)
	v_mfma_f32_16x16x32_bf16 v[88:91], v[164:167], v[200:203], v[88:91]
	v_mfma_f32_16x16x32_bf16 v[84:87], v[172:175], v[196:199], v[84:87]
	v_mfma_f32_16x16x32_bf16 v[80:83], v[172:175], v[200:203], v[80:83]
	v_mfma_f32_16x16x32_bf16 v[76:79], v[180:183], v[196:199], v[76:79]
	v_mfma_f32_16x16x32_bf16 v[72:75], v[180:183], v[200:203], v[72:75]
	v_mfma_f32_16x16x32_bf16 v[68:71], v[188:191], v[196:199], v[68:71]
	v_mfma_f32_16x16x32_bf16 v[64:67], v[188:191], v[200:203], v[64:67]
	v_mfma_f32_16x16x32_bf16 v[92:95], v[164:167], v[196:199], v[92:95]
	s_waitcnt lgkmcnt(0)
	v_mfma_f32_16x16x32_bf16 v[88:91], v[168:171], v[204:207], v[88:91]
	v_mfma_f32_16x16x32_bf16 v[84:87], v[176:179], v[142:145], v[84:87]
	v_mfma_f32_16x16x32_bf16 v[80:83], v[176:179], v[204:207], v[80:83]
	v_mfma_f32_16x16x32_bf16 v[76:79], v[184:187], v[142:145], v[76:79]
	v_mfma_f32_16x16x32_bf16 v[72:75], v[184:187], v[204:207], v[72:75]
	v_mfma_f32_16x16x32_bf16 v[68:71], v[192:195], v[142:145], v[68:71]
	v_mfma_f32_16x16x32_bf16 v[64:67], v[192:195], v[204:207], v[64:67]
	v_mfma_f32_16x16x32_bf16 v[164:167], v[168:171], v[142:145], v[92:95]
	s_barrier
	s_nop 0
	ds_read_b128 v[92:95], v130 offset:16384
	ds_read_b128 v[168:171], v130 offset:17408
	ds_read_b128 v[172:175], v133 offset:16384
	ds_read_b128 v[176:179], v133 offset:17408
	ds_read_b128 v[180:183], v132 offset:16384
	ds_read_b128 v[184:187], v132 offset:17408
	ds_read_b128 v[188:191], v131 offset:16384
	ds_read_b128 v[192:195], v131 offset:17408
	s_waitcnt vmcnt(4)
	s_barrier
; #define LDA(dst, b, h) _Pragma("unroll") for (int m = 0; m < 4; ++m) _Pragma("unroll") for (int k = 0; k < 2; ++k) \
;     dst[m][k] = *reinterpret_cast<const bf16x8*>(SA(b, h) + lds_byte(wr * 64 + m * 16 + fr, k * 32 + fq * 8))
; #define LDB(dst, b, h) _Pragma("unroll") for (int n = 0; n < 2; ++n) _Pragma("unroll") for (int k = 0; k < 2; ++k) \
;     dst[n][k] = *reinterpret_cast<const bf16x8*>(SB(b, h) + lds_byte(wc * 32 + n * 16 + fr, k * 32 + fq * 8))
; #define WAIT_V(n) asm volatile("s_waitcnt vmcnt(" #n ")" ::: "memory")
; #define WAIT_L(n) asm volatile("s_waitcnt lgkmcnt(" #n ")" ::: "memory")
; #define BAR __builtin_amdgcn_s_barrier()
;     ...
;       LDA(At, 0, 1); WAIT_V(4); BAR; WAIT_L(0); MMA(1, 0, At, B0); MMA(1, 1, At, B1); BAR; }
;     { LDB(B0, 1, 0); LDA(At, 1, 0); WAIT_V(2); BAR; WAIT_L(0); MMA(0, 0, At, B0); BAR;
	s_waitcnt lgkmcnt(0)
	v_mfma_f32_16x16x32_bf16 v[60:63], v[92:95], v[152:155], v[60:63]
	v_mfma_f32_16x16x32_bf16 v[60:63], v[168:171], v[156:159], v[60:63]
	v_mfma_f32_16x16x32_bf16 v[56:59], v[168:171], v[148:151], v[56:59]
	v_mfma_f32_16x16x32_bf16 v[56:59], v[92:95], v[160:163], v[56:59]
	v_mfma_f32_16x16x32_bf16 v[48:51], v[172:175], v[160:163], v[48:51]
	v_mfma_f32_16x16x32_bf16 v[48:51], v[176:179], v[148:151], v[48:51]
	v_mfma_f32_16x16x32_bf16 v[52:55], v[176:179], v[156:159], v[52:55]
	v_mfma_f32_16x16x32_bf16 v[52:55], v[172:175], v[152:155], v[52:55]
	v_mfma_f32_16x16x32_bf16 v[44:47], v[180:183], v[152:155], v[44:47]
	v_mfma_f32_16x16x32_bf16 v[44:47], v[184:187], v[156:159], v[44:47]
	v_mfma_f32_16x16x32_bf16 v[40:43], v[184:187], v[148:151], v[40:43]
	v_mfma_f32_16x16x32_bf16 v[40:43], v[180:183], v[160:163], v[40:43]
	v_mfma_f32_16x16x32_bf16 v[32:35], v[188:191], v[160:163], v[32:35]
	v_mfma_f32_16x16x32_bf16 v[32:35], v[192:195], v[148:151], v[32:35]
	v_mfma_f32_16x16x32_bf16 v[36:39], v[192:195], v[156:159], v[36:39]
	v_mfma_f32_16x16x32_bf16 v[36:39], v[188:191], v[152:155], v[36:39]
	v_mfma_f32_16x16x32_bf16 v[4:7], v[188:191], v[196:199], v[4:7]
	v_mfma_f32_16x16x32_bf16 v[4:7], v[192:195], v[142:145], v[4:7]
	v_mfma_f32_16x16x32_bf16 v[28:31], v[168:171], v[142:145], v[28:31]
	v_mfma_f32_16x16x32_bf16 v[28:31], v[92:95], v[196:199], v[28:31]
	v_mfma_f32_16x16x32_bf16 v[24:27], v[92:95], v[200:203], v[24:27]
	v_mfma_f32_16x16x32_bf16 v[24:27], v[168:171], v[204:207], v[24:27]
	v_mfma_f32_16x16x32_bf16 v[16:19], v[176:179], v[204:207], v[16:19]
	v_mfma_f32_16x16x32_bf16 v[16:19], v[172:175], v[200:203], v[16:19]
	v_mfma_f32_16x16x32_bf16 v[20:23], v[172:175], v[196:199], v[20:23]
	v_mfma_f32_16x16x32_bf16 v[20:23], v[176:179], v[142:145], v[20:23]
	v_mfma_f32_16x16x32_bf16 v[12:15], v[184:187], v[142:145], v[12:15]
	v_mfma_f32_16x16x32_bf16 v[12:15], v[180:183], v[196:199], v[12:15]
	v_mfma_f32_16x16x32_bf16 v[8:11], v[180:183], v[200:203], v[8:11]
	v_mfma_f32_16x16x32_bf16 v[8:11], v[184:187], v[204:207], v[8:11]
	v_mfma_f32_16x16x32_bf16 v[0:3], v[192:195], v[204:207], v[0:3]
	v_mfma_f32_16x16x32_bf16 v[0:3], v[188:191], v[200:203], v[0:3]
	s_barrier
	ds_read_b128 v[142:145], v138
	ds_read_b128 v[146:149], v139
	ds_read_b128 v[150:153], v140
	ds_read_b128 v[138:141], v141
	ds_read_b128 v[154:157], v130 offset:32768
	ds_read_b128 v[158:161], v130 offset:33792
	ds_read_b128 v[168:171], v133 offset:32768
	ds_read_b128 v[172:175], v133 offset:33792
	ds_read_b128 v[176:179], v132 offset:32768
	ds_read_b128 v[180:183], v132 offset:33792
	ds_read_b128 v[184:187], v131 offset:32768
	ds_read_b128 v[188:191], v131 offset:33792
	s_waitcnt vmcnt(2)
	s_barrier
	s_waitcnt lgkmcnt(7)
	v_mfma_f32_16x16x32_bf16 v[92:95], v[154:157], v[142:145], v[124:127]
	v_mfma_f32_16x16x32_bf16 v[120:123], v[154:157], v[150:153], v[120:123]
	s_waitcnt lgkmcnt(5)
	v_mfma_f32_16x16x32_bf16 v[116:119], v[168:171], v[142:145], v[116:119]
	v_mfma_f32_16x16x32_bf16 v[112:115], v[168:171], v[150:153], v[112:115]
	s_waitcnt lgkmcnt(3)
	v_mfma_f32_16x16x32_bf16 v[108:111], v[176:179], v[142:145], v[108:111]
	v_mfma_f32_16x16x32_bf16 v[104:107], v[176:179], v[150:153], v[104:107]
	s_waitcnt lgkmcnt(1)
	v_mfma_f32_16x16x32_bf16 v[100:103], v[184:187], v[142:145], v[100:103]
	v_mfma_f32_16x16x32_bf16 v[96:99], v[184:187], v[150:153], v[96:99]
	v_mfma_f32_16x16x32_bf16 v[124:127], v[158:161], v[146:149], v[92:95]
	v_mfma_f32_16x16x32_bf16 v[120:123], v[158:161], v[138:141], v[120:123]
	v_mfma_f32_16x16x32_bf16 v[116:119], v[172:175], v[146:149], v[116:119]
	v_mfma_f32_16x16x32_bf16 v[112:115], v[172:175], v[138:141], v[112:115]
	v_mfma_f32_16x16x32_bf16 v[108:111], v[180:183], v[146:149], v[108:111]
	v_mfma_f32_16x16x32_bf16 v[104:107], v[180:183], v[138:141], v[104:107]
	s_waitcnt lgkmcnt(0)
	v_mfma_f32_16x16x32_bf16 v[100:103], v[188:191], v[146:149], v[100:103]
	v_mfma_f32_16x16x32_bf16 v[92:95], v[188:191], v[138:141], v[96:99]
	s_barrier
; #define LDA(dst, b, h) _Pragma("unroll") for (int m = 0; m < 4; ++m) _Pragma("unroll") for (int k = 0; k < 2; ++k) \
;     dst[m][k] = *reinterpret_cast<const bf16x8*>(SA(b, h) + lds_byte(wr * 64 + m * 16 + fr, k * 32 + fq * 8))
; #define LDB(dst, b, h) _Pragma("unroll") for (int n = 0; n < 2; ++n) _Pragma("unroll") for (int k = 0; k < 2; ++k) \
;     dst[n][k] = *reinterpret_cast<const bf16x8*>(SB(b, h) + lds_byte(wc * 32 + n * 16 + fr, k * 32 + fq * 8))
; #define WAIT_V(n) asm volatile("s_waitcnt vmcnt(" #n ")" ::: "memory")
; #define WAIT_L(n) asm volatile("s_waitcnt lgkmcnt(" #n ")" ::: "memory")
; #define BAR __builtin_amdgcn_s_barrier()
;     ...
;     { LDB(B0, 1, 0); LDA(At, 1, 0); WAIT_V(2); BAR; WAIT_L(0); MMA(0, 0, At, B0); BAR;
;       LDB(B1, 1, 1); WAIT_V(0); BAR; WAIT_L(0); MMA(0, 1, At, B1); BAR;
;       LDA(At, 1, 1); BAR; WAIT_L(0); MMA(1, 0, At, B0); MMA(1, 1, At, B1); BAR; }
;     if (wr == 0) BAR;
	ds_read_b128 v[192:195], v134
	ds_read_b128 v[196:199], v135
	ds_read_b128 v[200:203], v136
	ds_read_b128 v[134:137], v137
	s_waitcnt vmcnt(0)
	s_barrier
	s_waitcnt lgkmcnt(1)
	v_mfma_f32_16x16x32_bf16 v[96:99], v[154:157], v[192:195], v[164:167]
	v_mfma_f32_16x16x32_bf16 v[88:91], v[154:157], v[200:203], v[88:91]
	v_mfma_f32_16x16x32_bf16 v[84:87], v[168:171], v[192:195], v[84:87]
	v_mfma_f32_16x16x32_bf16 v[80:83], v[168:171], v[200:203], v[80:83]
	v_mfma_f32_16x16x32_bf16 v[76:79], v[176:179], v[192:195], v[76:79]
	v_mfma_f32_16x16x32_bf16 v[72:75], v[176:179], v[200:203], v[72:75]
	v_mfma_f32_16x16x32_bf16 v[68:71], v[184:187], v[192:195], v[68:71]
	v_mfma_f32_16x16x32_bf16 v[64:67], v[184:187], v[200:203], v[64:67]
	s_waitcnt lgkmcnt(0)
	v_mfma_f32_16x16x32_bf16 v[96:99], v[158:161], v[196:199], v[96:99]
	v_mfma_f32_16x16x32_bf16 v[88:91], v[158:161], v[134:137], v[88:91]
	v_mfma_f32_16x16x32_bf16 v[84:87], v[172:175], v[196:199], v[84:87]
	v_mfma_f32_16x16x32_bf16 v[80:83], v[172:175], v[134:137], v[80:83]
	v_mfma_f32_16x16x32_bf16 v[76:79], v[180:183], v[196:199], v[76:79]
	v_mfma_f32_16x16x32_bf16 v[72:75], v[180:183], v[134:137], v[72:75]
	v_mfma_f32_16x16x32_bf16 v[68:71], v[188:191], v[196:199], v[68:71]
	v_mfma_f32_16x16x32_bf16 v[64:67], v[188:191], v[134:137], v[64:67]
	s_barrier
	ds_read_b128 v[154:157], v130 offset:49152
	ds_read_b128 v[158:161], v130 offset:50176
	ds_read_b128 v[162:165], v133 offset:49152
	ds_read_b128 v[166:169], v133 offset:50176
	ds_read_b128 v[170:173], v132 offset:49152
	ds_read_b128 v[174:177], v132 offset:50176
	ds_read_b128 v[178:181], v131 offset:49152
	ds_read_b128 v[130:133], v131 offset:50176
	s_barrier
	s_waitcnt lgkmcnt(0)
	v_mfma_f32_16x16x32_bf16 v[60:63], v[154:157], v[142:145], v[60:63]
	v_mfma_f32_16x16x32_bf16 v[60:63], v[158:161], v[146:149], v[60:63]
	v_mfma_f32_16x16x32_bf16 v[56:59], v[158:161], v[138:141], v[56:59]
	v_mfma_f32_16x16x32_bf16 v[56:59], v[154:157], v[150:153], v[56:59]
	v_mfma_f32_16x16x32_bf16 v[48:51], v[162:165], v[150:153], v[48:51]
	v_mfma_f32_16x16x32_bf16 v[48:51], v[166:169], v[138:141], v[48:51]
	v_mfma_f32_16x16x32_bf16 v[52:55], v[166:169], v[146:149], v[52:55]
	v_mfma_f32_16x16x32_bf16 v[52:55], v[162:165], v[142:145], v[52:55]
	v_mfma_f32_16x16x32_bf16 v[44:47], v[170:173], v[142:145], v[44:47]
	v_mfma_f32_16x16x32_bf16 v[44:47], v[174:177], v[146:149], v[44:47]
	v_mfma_f32_16x16x32_bf16 v[40:43], v[174:177], v[138:141], v[40:43]
	v_mfma_f32_16x16x32_bf16 v[40:43], v[170:173], v[150:153], v[40:43]
	v_mfma_f32_16x16x32_bf16 v[32:35], v[178:181], v[150:153], v[32:35]
	v_mfma_f32_16x16x32_bf16 v[32:35], v[130:133], v[138:141], v[32:35]
	v_mfma_f32_16x16x32_bf16 v[36:39], v[130:133], v[146:149], v[36:39]
	v_mfma_f32_16x16x32_bf16 v[36:39], v[178:181], v[142:145], v[36:39]
	v_mfma_f32_16x16x32_bf16 v[4:7], v[178:181], v[192:195], v[4:7]
	v_mfma_f32_16x16x32_bf16 v[4:7], v[130:133], v[196:199], v[4:7]
	v_mfma_f32_16x16x32_bf16 v[28:31], v[158:161], v[196:199], v[28:31]
	v_mfma_f32_16x16x32_bf16 v[28:31], v[154:157], v[192:195], v[28:31]
	v_mfma_f32_16x16x32_bf16 v[24:27], v[154:157], v[200:203], v[24:27]
	v_mfma_f32_16x16x32_bf16 v[24:27], v[158:161], v[134:137], v[24:27]
	v_mfma_f32_16x16x32_bf16 v[16:19], v[166:169], v[134:137], v[16:19]
	v_mfma_f32_16x16x32_bf16 v[16:19], v[162:165], v[200:203], v[16:19]
	v_mfma_f32_16x16x32_bf16 v[20:23], v[162:165], v[192:195], v[20:23]
	v_mfma_f32_16x16x32_bf16 v[20:23], v[166:169], v[196:199], v[20:23]
	v_mfma_f32_16x16x32_bf16 v[12:15], v[174:177], v[196:199], v[12:15]
	v_mfma_f32_16x16x32_bf16 v[12:15], v[170:173], v[192:195], v[12:15]
	v_mfma_f32_16x16x32_bf16 v[8:11], v[170:173], v[200:203], v[8:11]
	v_mfma_f32_16x16x32_bf16 v[8:11], v[174:177], v[134:137], v[8:11]
	v_mfma_f32_16x16x32_bf16 v[0:3], v[130:133], v[134:137], v[0:3]
	v_mfma_f32_16x16x32_bf16 v[0:3], v[178:181], v[200:203], v[0:3]
	v_cmp_gt_u32_e32 vcc, s37, v129
	s_barrier
	s_and_saveexec_b64 s[16:17], vcc
	s_cbranch_execz .LBB0_228
	s_barrier

; #define STAGE(P, RS, SOFF, OFF, kt) do { const int _so = (SOFF) + (kt) * (BK * 2); \
;     _Pragma("unroll") for (int _i = 0; _i < 2; ++_i) { \
;       __builtin_amdgcn_raw_ptr_buffer_load_lds(RS, (__attribute__((address_space(3))) void*)((P) + wave * 1024 + _i * 8192), 16, OFF[_i], _so, 0, 0); } } while (0)
; #define LDA(dst, b, h) _Pragma("unroll") for (int m = 0; m < 4; ++m) _Pragma("unroll") for (int k = 0; k < 2; ++k) \
;     dst[m][k] = *reinterpret_cast<const bf16x8*>(SA(b, h) + lds_byte(wr * 64 + m * 16 + fr, k * 32 + fq * 8))
; #define LDB(dst, b, h) _Pragma("unroll") for (int n = 0; n < 2; ++n) _Pragma("unroll") for (int k = 0; k < 2; ++k) \
;     dst[n][k] = *reinterpret_cast<const bf16x8*>(SB(b, h) + lds_byte(wc * 32 + n * 16 + fr, k * 32 + fq * 8))
; #define WAIT_V(n) asm volatile("s_waitcnt vmcnt(" #n ")" ::: "memory")
; #define WAIT_L(n) asm volatile("s_waitcnt lgkmcnt(" #n ")" ::: "memory")
; #define BAR __builtin_amdgcn_s_barrier()
; #define SCHED __builtin_amdgcn_sched_barrier(0)
;     ...
;     const int tid = opaque_tid(wave);
;     const int wid = tid >> 6, lane = tid & 63, wr = wid >> 2, wc = wid & 3, fr = lane & 15, fq = lane >> 4;
;     int offA[2], offB[2];
;     _Pragma("unroll") for (int i = 0; i < 2; ++i) {
;       int r, c; stage_rc(tid * 16 + i * 8192, r, c);
;       offA[i] = (r * lda + c) * 2; offB[i] = (r * ldb + c) * 2;
;     }
;     const int brow = pm * BM;
;     f32x4 acc[2][2][4][2];
;     _Pragma("unroll") for (int a = 0; a < 2; ++a) _Pragma("unroll") for (int b = 0; b < 2; ++b) _Pragma("unroll") for (int m = 0; m < 4; ++m) _Pragma("unroll") for (int n = 0; n < 2; ++n)
;       acc[a][b][m][n] = f32x4{0.f, 0.f, 0.f, 0.f};
;     bf16x8 At[4][2], B0[2][2], B1[2][2];
;     if (wr == 1) BAR;
;     if (first_tile) { WAIT_V(0); }
;     else if constexpr (mode == MODE_RESID_LN) { WAIT_V(0); }
;     else if constexpr (mode == MODE_SWIGLU) { WAIT_V(6); }
;     else if constexpr (mode == MODE_V) { WAIT_V(24); }
;     else { WAIT_V(12); }
;     first_tile = false;
;     BAR;
;     BAR;
;     for (int t = 0; t < nt - 2; t += 2) {
;       LDB(B0, 0, 0); SCHED; LDA(At, 0, 0); STAGE(SA(1, 1), rsA, sA1, offA, t + 1);
;       WAIT_L(8); BAR; WAIT_L(0); MMA(0, 0, At, B0); BAR; SCHED;
;       LDB(B1, 0, 1); STAGE(SB(0, 0), rsB, sB0, offB, t + 2);
.LBB0_290:
	v_bfe_i32 v4, v128, 27, 1
	v_lshlrev_b32_e32 v2, 4, v128
	v_lshrrev_b32_e32 v4, 22, v4
	v_add_u32_e32 v4, v2, v4
	v_and_b32_e32 v4, 0xfffffc00, v4
	v_sub_u32_e32 v4, v2, v4
	v_lshrrev_b32_e32 v5, 4, v4
	v_bitop3_b32 v4, v5, v4, 32 bitop3:0x6c
	v_ashrrev_i32_e32 v3, 31, v128
	v_ashrrev_i32_e32 v6, 31, v4
	v_lshrrev_b32_e32 v3, 26, v3
	v_lshrrev_b32_e32 v6, 26, v6
	v_add_u32_e32 v3, v128, v3
	v_add_u32_e32 v6, v4, v6
	v_ashrrev_i32_e32 v3, 6, v3
	v_lshrrev_b32_e32 v7, 6, v6
	v_and_b32_e32 v6, 0xc0, v6
	v_lshlrev_b32_e32 v5, 3, v3
	v_lshlrev_b32_e32 v3, 5, v3
	v_sub_u32_e32 v4, v4, v6
	v_and_b32_e32 v5, 0x1ffff0, v5
	v_and_b32_e32 v3, 32, v3
	v_ashrrev_i16_sdwa v4, v216, sext(v4) dst_sel:DWORD dst_unused:UNUSED_PAD src0_sel:DWORD src1_sel:BYTE_0
	v_add_u32_sdwa v3, v3, sext(v4) dst_sel:DWORD dst_unused:UNUSED_PAD src0_sel:DWORD src1_sel:WORD_0
	v_add_lshl_u32 v4, v7, v5, 11
	v_add_u32_e32 v2, 0x2000, v2
	v_lshl_add_u32 v141, v3, 1, v4
	v_ashrrev_i32_e32 v3, 31, v2
	v_lshrrev_b32_e32 v3, 22, v3
	v_add_u32_e32 v3, v2, v3
	v_ashrrev_i32_e32 v3, 10, v3
	v_mul_i32_i24_e32 v4, 0x400, v3
	v_sub_u32_e32 v2, v2, v4
	v_lshrrev_b32_e32 v4, 4, v2
	v_bitop3_b32 v2, v4, v2, 32 bitop3:0x6c
	v_ashrrev_i32_e32 v5, 31, v2
	v_lshrrev_b32_e32 v5, 26, v5
	v_add_u32_e32 v5, v2, v5
	v_lshrrev_b32_e32 v6, 6, v5
	v_and_b32_e32 v5, 0xc0, v5
	v_lshlrev_b32_e32 v4, 3, v3
	v_lshlrev_b32_e32 v3, 5, v3
	v_sub_u32_e32 v2, v2, v5
	v_and_b32_e32 v4, 0x1ffff0, v4
	v_and_b32_e32 v3, 32, v3
	v_ashrrev_i16_sdwa v2, v216, sext(v2) dst_sel:DWORD dst_unused:UNUSED_PAD src0_sel:DWORD src1_sel:BYTE_0
	v_add_u32_sdwa v2, v3, sext(v2) dst_sel:DWORD dst_unused:UNUSED_PAD src0_sel:DWORD src1_sel:WORD_0
	v_add_lshl_u32 v3, v6, v4, 11
	v_lshl_add_u32 v142, v2, 1, v3
	v_and_b32_e32 v3, 15, v0
	v_lshlrev_b32_e32 v5, 2, v0
	v_and_b32_e32 v2, 48, v0
	v_lshlrev_b32_e32 v3, 6, v3
	v_and_b32_e32 v5, 32, v5
	v_or_b32_e32 v4, v3, v2
	v_bitop3_b32 v3, v3, v5, v2 bitop3:0x36
	v_lshlrev_b32_e32 v6, 6, v128
	s_movk_i32 s1, 0x3000
	v_and_or_b32 v3, v6, s1, v3
	v_lshlrev_b32_e32 v0, 6, v0
	s_movk_i32 s1, 0x3c0
	v_lshlrev_b32_e32 v1, 13, v1
	v_and_or_b32 v0, v0, s1, v2
	v_bitop3_b32 v0, v1, v0, v5 bitop3:0xf6
	v_or_b32_e32 v6, 0x400, v3
	v_or_b32_e32 v7, 0x800, v3
	v_or_b32_e32 v8, 0xc00, v3
	v_or_b32_e32 v132, 0x800, v0
	v_or_b32_e32 v131, 0x1000, v0
	v_or_b32_e32 v130, 0x1800, v0
	v_mov_b32_e32 v0, 0
	v_bitop3_b32 v129, v4, v1, v5 bitop3:0xde
	s_mov_b32 s1, -2
	s_mov_b32 s3, 0
	v_or_b32_e32 v147, 0x10000, v3
	v_or_b32_e32 v148, 0x10000, v6
	v_or_b32_e32 v149, 0x10000, v7
	v_or_b32_e32 v150, 0x10000, v8
	v_or_b32_e32 v143, 0x14000, v3
	v_or_b32_e32 v144, 0x14000, v6
	v_or_b32_e32 v145, 0x14000, v7
	v_or_b32_e32 v146, 0x14000, v8
	v_or_b32_e32 v137, 0x18000, v3
	v_or_b32_e32 v138, 0x18000, v6
	v_or_b32_e32 v139, 0x18000, v7
	v_or_b32_e32 v140, 0x18000, v8
	v_or_b32_e32 v133, 0x1c000, v3
	v_or_b32_e32 v134, 0x1c000, v6
	v_or_b32_e32 v135, 0x1c000, v7
	v_or_b32_e32 v136, 0x1c000, v8
	s_barrier
	s_barrier
	ds_read_b128 v[152:155], v147
	ds_read_b128 v[156:159], v148
	ds_read_b128 v[160:163], v149
	ds_read_b128 v[164:167], v150
	s_add_i32 s5, s94, s3
	s_add_i32 s6, s5, 0x80
	s_mov_b32 m0, s36
	ds_read_b128 v[168:171], v129
	ds_read_b128 v[172:175], v129 offset:1024
	ds_read_b128 v[176:179], v132
	ds_read_b128 v[180:183], v132 offset:1024
	ds_read_b128 v[184:187], v131
	ds_read_b128 v[188:191], v131 offset:1024
	ds_read_b128 v[192:195], v130
	ds_read_b128 v[196:199], v130 offset:1024
	buffer_load_dwordx4 v141, s[8:11], s6 offen lds
	s_mov_b32 m0, s61
	s_nop 0
	buffer_load_dwordx4 v142, s[8:11], s6 offen lds
	s_waitcnt lgkmcnt(8)
	s_barrier
	s_waitcnt lgkmcnt(0)
	v_mfma_f32_16x16x32_bf16 v[124:127], v[152:155], v[168:171], 0
	v_mfma_f32_16x16x32_bf16 v[124:127], v[156:159], v[172:175], v[124:127]
	v_mfma_f32_16x16x32_bf16 v[120:123], v[164:167], v[172:175], 0
	v_mfma_f32_16x16x32_bf16 v[120:123], v[160:163], v[168:171], v[120:123]
	v_mfma_f32_16x16x32_bf16 v[112:115], v[160:163], v[176:179], 0
	v_mfma_f32_16x16x32_bf16 v[112:115], v[164:167], v[180:183], v[112:115]
	v_mfma_f32_16x16x32_bf16 v[116:119], v[156:159], v[180:183], 0
	v_mfma_f32_16x16x32_bf16 v[116:119], v[152:155], v[176:179], v[116:119]
	v_mfma_f32_16x16x32_bf16 v[108:111], v[152:155], v[184:187], 0
	v_mfma_f32_16x16x32_bf16 v[108:111], v[156:159], v[188:191], v[108:111]
	v_mfma_f32_16x16x32_bf16 v[104:107], v[164:167], v[188:191], 0
	v_mfma_f32_16x16x32_bf16 v[104:107], v[160:163], v[184:187], v[104:107]
	v_mfma_f32_16x16x32_bf16 v[96:99], v[160:163], v[192:195], 0
	v_mfma_f32_16x16x32_bf16 v[96:99], v[164:167], v[196:199], v[96:99]
	v_mfma_f32_16x16x32_bf16 v[100:103], v[156:159], v[196:199], 0
	v_mfma_f32_16x16x32_bf16 v[100:103], v[152:155], v[192:195], v[100:103]
	s_barrier
	s_add_i32 s6, s96, s3
	s_add_i32 s7, s6, 0x100
	s_mov_b32 s14, s10
	s_mov_b32 s15, s11
	s_mov_b32 m0, s37
	ds_read_b128 v[200:203], v143
	ds_read_b128 v[204:207], v144
	ds_read_b128 v[208:211], v145
	ds_read_b128 v[212:215], v146
	buffer_load_dwordx4 v141, s[12:15], s7 offen lds
	s_mov_b32 m0, s48
	s_nop 0
	buffer_load_dwordx4 v142, s[12:15], s7 offen lds
	s_barrier
; #define STAGE(P, RS, SOFF, OFF, kt) do { const int _so = (SOFF) + (kt) * (BK * 2); \
;     _Pragma("unroll") for (int _i = 0; _i < 2; ++_i) { \
;       __builtin_amdgcn_raw_ptr_buffer_load_lds(RS, (__attribute__((address_space(3))) void*)((P) + wave * 1024 + _i * 8192), 16, OFF[_i], _so, 0, 0); } } while (0)
; #define LDA(dst, b, h) _Pragma("unroll") for (int m = 0; m < 4; ++m) _Pragma("unroll") for (int k = 0; k < 2; ++k) \
;     dst[m][k] = *reinterpret_cast<const bf16x8*>(SA(b, h) + lds_byte(wr * 64 + m * 16 + fr, k * 32 + fq * 8))
; #define LDB(dst, b, h) _Pragma("unroll") for (int n = 0; n < 2; ++n) _Pragma("unroll") for (int k = 0; k < 2; ++k) \
;     dst[n][k] = *reinterpret_cast<const bf16x8*>(SB(b, h) + lds_byte(wc * 32 + n * 16 + fr, k * 32 + fq * 8))
; #define WAIT_V(n) asm volatile("s_waitcnt vmcnt(" #n ")" ::: "memory")
; #define WAIT_L(n) asm volatile("s_waitcnt lgkmcnt(" #n ")" ::: "memory")
; #define BAR __builtin_amdgcn_s_barrier()
; #define SCHED __builtin_amdgcn_sched_barrier(0)
;     ...
;       LDB(B1, 0, 1); STAGE(SB(0, 0), rsB, sB0, offB, t + 2);
;       BAR; WAIT_L(0); MMA(0, 1, At, B1); BAR;
;       LDA(At, 0, 1); STAGE(SA(0, 0), rsA, sA0, offA, t + 2);
;       BAR; WAIT_L(0); MMA(1, 0, At, B0); BAR; SCHED;
;       STAGE(SB(0, 1), rsB, sB1, offB, t + 2);
;       WAIT_V(6); BAR; MMA(1, 1, At, B1); BAR;
;       LDB(B0, 1, 0); SCHED; LDA(At, 1, 0); STAGE(SA(0, 1), rsA, sA1, offA, t + 2);
;       WAIT_L(8); BAR; WAIT_L(0); MMA(0, 0, At, B0); BAR; SCHED;
	s_waitcnt lgkmcnt(2)
	v_mfma_f32_16x16x32_bf16 v[92:95], v[200:203], v[168:171], 0
	v_mfma_f32_16x16x32_bf16 v[92:95], v[204:207], v[172:175], v[92:95]
	s_waitcnt lgkmcnt(0)
	v_mfma_f32_16x16x32_bf16 v[88:91], v[212:215], v[172:175], 0
	v_mfma_f32_16x16x32_bf16 v[88:91], v[208:211], v[168:171], v[88:91]
	v_mfma_f32_16x16x32_bf16 v[68:71], v[208:211], v[176:179], 0
	v_mfma_f32_16x16x32_bf16 v[68:71], v[212:215], v[180:183], v[68:71]
	v_mfma_f32_16x16x32_bf16 v[80:83], v[204:207], v[180:183], 0
	v_mfma_f32_16x16x32_bf16 v[80:83], v[200:203], v[176:179], v[80:83]
	v_mfma_f32_16x16x32_bf16 v[60:63], v[200:203], v[184:187], 0
	v_mfma_f32_16x16x32_bf16 v[60:63], v[204:207], v[188:191], v[60:63]
	v_mfma_f32_16x16x32_bf16 v[56:59], v[212:215], v[188:191], 0
	v_mfma_f32_16x16x32_bf16 v[56:59], v[208:211], v[184:187], v[56:59]
	v_mfma_f32_16x16x32_bf16 v[48:51], v[208:211], v[192:195], 0
	v_mfma_f32_16x16x32_bf16 v[48:51], v[212:215], v[196:199], v[48:51]
	v_mfma_f32_16x16x32_bf16 v[52:55], v[204:207], v[196:199], 0
	v_mfma_f32_16x16x32_bf16 v[52:55], v[200:203], v[192:195], v[52:55]
	s_barrier
	s_add_i32 s7, s95, s3
	s_add_i32 s22, s7, 0x100
	s_mov_b32 m0, s35
	ds_read_b128 v[168:171], v129 offset:16384
	ds_read_b128 v[172:175], v129 offset:17408
	ds_read_b128 v[176:179], v132 offset:16384
	ds_read_b128 v[180:183], v132 offset:17408
	ds_read_b128 v[184:187], v131 offset:16384
	ds_read_b128 v[188:191], v131 offset:17408
	ds_read_b128 v[192:195], v130 offset:16384
	ds_read_b128 v[196:199], v130 offset:17408
	buffer_load_dwordx4 v141, s[8:11], s22 offen lds
	s_mov_b32 m0, s49
	s_nop 0
	buffer_load_dwordx4 v142, s[8:11], s22 offen lds
	s_barrier
	s_waitcnt lgkmcnt(6)
	v_mfma_f32_16x16x32_bf16 v[44:47], v[152:155], v[168:171], 0
	v_mfma_f32_16x16x32_bf16 v[44:47], v[156:159], v[172:175], v[44:47]
	v_mfma_f32_16x16x32_bf16 v[40:43], v[164:167], v[172:175], 0
	v_mfma_f32_16x16x32_bf16 v[40:43], v[160:163], v[168:171], v[40:43]
	s_waitcnt lgkmcnt(4)
	v_mfma_f32_16x16x32_bf16 v[32:35], v[160:163], v[176:179], 0
	v_mfma_f32_16x16x32_bf16 v[32:35], v[164:167], v[180:183], v[32:35]
	v_mfma_f32_16x16x32_bf16 v[36:39], v[156:159], v[180:183], 0
	v_mfma_f32_16x16x32_bf16 v[36:39], v[152:155], v[176:179], v[36:39]
	s_waitcnt lgkmcnt(2)
	v_mfma_f32_16x16x32_bf16 v[28:31], v[152:155], v[184:187], 0
	v_mfma_f32_16x16x32_bf16 v[28:31], v[156:159], v[188:191], v[28:31]
	v_mfma_f32_16x16x32_bf16 v[24:27], v[164:167], v[188:191], 0
	v_mfma_f32_16x16x32_bf16 v[24:27], v[160:163], v[184:187], v[24:27]
	s_waitcnt lgkmcnt(0)
	v_mfma_f32_16x16x32_bf16 v[16:19], v[160:163], v[192:195], 0
	v_mfma_f32_16x16x32_bf16 v[16:19], v[164:167], v[196:199], v[16:19]
	v_mfma_f32_16x16x32_bf16 v[20:23], v[156:159], v[196:199], 0
	v_mfma_f32_16x16x32_bf16 v[20:23], v[152:155], v[192:195], v[20:23]
	s_barrier
	s_add_i32 s22, s97, s3
	s_add_i32 s23, s22, 0x100
	s_mov_b32 m0, s38
	s_nop 0
	buffer_load_dwordx4 v141, s[12:15], s23 offen lds
	s_mov_b32 m0, s54
	s_nop 0
	buffer_load_dwordx4 v142, s[12:15], s23 offen lds
	s_waitcnt vmcnt(6)
	s_barrier
	v_mfma_f32_16x16x32_bf16 v[12:15], v[200:203], v[168:171], 0
	v_mfma_f32_16x16x32_bf16 v[12:15], v[204:207], v[172:175], v[12:15]
	v_mfma_f32_16x16x32_bf16 v[8:11], v[212:215], v[172:175], 0
	v_mfma_f32_16x16x32_bf16 v[8:11], v[208:211], v[168:171], v[8:11]
	v_mfma_f32_16x16x32_bf16 v[0:3], v[208:211], v[176:179], 0
	v_mfma_f32_16x16x32_bf16 v[0:3], v[212:215], v[180:183], v[0:3]
	v_mfma_f32_16x16x32_bf16 v[4:7], v[204:207], v[180:183], 0
	v_mfma_f32_16x16x32_bf16 v[4:7], v[200:203], v[176:179], v[4:7]
	v_mfma_f32_16x16x32_bf16 v[64:67], v[200:203], v[184:187], 0
	v_mfma_f32_16x16x32_bf16 v[64:67], v[204:207], v[188:191], v[64:67]
	v_mfma_f32_16x16x32_bf16 v[72:75], v[212:215], v[188:191], 0
	v_mfma_f32_16x16x32_bf16 v[72:75], v[208:211], v[184:187], v[72:75]
	v_mfma_f32_16x16x32_bf16 v[84:87], v[208:211], v[192:195], 0
	v_mfma_f32_16x16x32_bf16 v[84:87], v[212:215], v[196:199], v[84:87]
	v_mfma_f32_16x16x32_bf16 v[76:79], v[204:207], v[196:199], 0
	v_mfma_f32_16x16x32_bf16 v[76:79], v[200:203], v[192:195], v[76:79]
	s_barrier
	ds_read_b128 v[152:155], v137
	ds_read_b128 v[156:159], v138
	ds_read_b128 v[160:163], v139
	ds_read_b128 v[164:167], v140
	s_addk_i32 s5, 0x100
	s_mov_b32 m0, s39
	ds_read_b128 v[168:171], v129 offset:32768
	ds_read_b128 v[172:175], v129 offset:33792
	ds_read_b128 v[176:179], v132 offset:32768
	ds_read_b128 v[180:183], v132 offset:33792
	ds_read_b128 v[184:187], v131 offset:32768
	ds_read_b128 v[188:191], v131 offset:33792
	ds_read_b128 v[192:195], v130 offset:32768
	ds_read_b128 v[196:199], v130 offset:33792
	buffer_load_dwordx4 v141, s[8:11], s5 offen lds
	s_mov_b32 m0, s55
	s_nop 0
	buffer_load_dwordx4 v142, s[8:11], s5 offen lds
	s_waitcnt lgkmcnt(8)
	s_barrier
; #define STAGE(P, RS, SOFF, OFF, kt) do { const int _so = (SOFF) + (kt) * (BK * 2); \
;     _Pragma("unroll") for (int _i = 0; _i < 2; ++_i) { \
;       __builtin_amdgcn_raw_ptr_buffer_load_lds(RS, (__attribute__((address_space(3))) void*)((P) + wave * 1024 + _i * 8192), 16, OFF[_i], _so, 0, 0); } } while (0)
; #define LDA(dst, b, h) _Pragma("unroll") for (int m = 0; m < 4; ++m) _Pragma("unroll") for (int k = 0; k < 2; ++k) \
;     dst[m][k] = *reinterpret_cast<const bf16x8*>(SA(b, h) + lds_byte(wr * 64 + m * 16 + fr, k * 32 + fq * 8))
; #define LDB(dst, b, h) _Pragma("unroll") for (int n = 0; n < 2; ++n) _Pragma("unroll") for (int k = 0; k < 2; ++k) \
;     dst[n][k] = *reinterpret_cast<const bf16x8*>(SB(b, h) + lds_byte(wc * 32 + n * 16 + fr, k * 32 + fq * 8))
; #define WAIT_V(n) asm volatile("s_waitcnt vmcnt(" #n ")" ::: "memory")
; #define WAIT_L(n) asm volatile("s_waitcnt lgkmcnt(" #n ")" ::: "memory")
; #define BAR __builtin_amdgcn_s_barrier()
; #define SCHED __builtin_amdgcn_sched_barrier(0)
;     ...
;       WAIT_L(8); BAR; WAIT_L(0); MMA(0, 0, At, B0); BAR; SCHED;
;       LDB(B1, 1, 1); STAGE(SB(1, 0), rsB, sB0, offB, t + 3);
;       BAR; WAIT_L(0); MMA(0, 1, At, B1); BAR;
;       LDA(At, 1, 1); STAGE(SA(1, 0), rsA, sA0, offA, t + 3);
;       BAR; WAIT_L(0); MMA(1, 0, At, B0); BAR; SCHED;
;       STAGE(SB(1, 1), rsB, sB1, offB, t + 3);
;       WAIT_V(6); BAR; MMA(1, 1, At, B1); BAR;
	s_waitcnt lgkmcnt(6)
	v_mfma_f32_16x16x32_bf16 v[124:127], v[152:155], v[168:171], v[124:127]
	v_mfma_f32_16x16x32_bf16 v[124:127], v[156:159], v[172:175], v[124:127]
	v_mfma_f32_16x16x32_bf16 v[120:123], v[164:167], v[172:175], v[120:123]
	v_mfma_f32_16x16x32_bf16 v[120:123], v[160:163], v[168:171], v[120:123]
	s_waitcnt lgkmcnt(4)
	v_mfma_f32_16x16x32_bf16 v[112:115], v[160:163], v[176:179], v[112:115]
	v_mfma_f32_16x16x32_bf16 v[112:115], v[164:167], v[180:183], v[112:115]
	v_mfma_f32_16x16x32_bf16 v[116:119], v[156:159], v[180:183], v[116:119]
	v_mfma_f32_16x16x32_bf16 v[116:119], v[152:155], v[176:179], v[116:119]
	s_waitcnt lgkmcnt(2)
	v_mfma_f32_16x16x32_bf16 v[108:111], v[152:155], v[184:187], v[108:111]
	v_mfma_f32_16x16x32_bf16 v[108:111], v[156:159], v[188:191], v[108:111]
	v_mfma_f32_16x16x32_bf16 v[104:107], v[164:167], v[188:191], v[104:107]
	v_mfma_f32_16x16x32_bf16 v[104:107], v[160:163], v[184:187], v[104:107]
	s_waitcnt lgkmcnt(0)
	v_mfma_f32_16x16x32_bf16 v[96:99], v[160:163], v[192:195], v[96:99]
	v_mfma_f32_16x16x32_bf16 v[96:99], v[164:167], v[196:199], v[96:99]
	v_mfma_f32_16x16x32_bf16 v[100:103], v[156:159], v[196:199], v[100:103]
	v_mfma_f32_16x16x32_bf16 v[100:103], v[152:155], v[192:195], v[100:103]
	s_barrier
	s_addk_i32 s6, 0x180
	s_mov_b32 m0, s42
	ds_read_b128 v[200:203], v133
	ds_read_b128 v[204:207], v134
	ds_read_b128 v[208:211], v135
	ds_read_b128 v[212:215], v136
	buffer_load_dwordx4 v141, s[12:15], s6 offen lds
	s_mov_b32 m0, s58
	s_nop 0
	buffer_load_dwordx4 v142, s[12:15], s6 offen lds
	s_barrier
	s_waitcnt lgkmcnt(2)
	v_mfma_f32_16x16x32_bf16 v[92:95], v[200:203], v[168:171], v[92:95]
	v_mfma_f32_16x16x32_bf16 v[92:95], v[204:207], v[172:175], v[92:95]
	s_waitcnt lgkmcnt(0)
	v_mfma_f32_16x16x32_bf16 v[88:91], v[212:215], v[172:175], v[88:91]
	v_mfma_f32_16x16x32_bf16 v[88:91], v[208:211], v[168:171], v[88:91]
	v_mfma_f32_16x16x32_bf16 v[68:71], v[208:211], v[176:179], v[68:71]
	v_mfma_f32_16x16x32_bf16 v[68:71], v[212:215], v[180:183], v[68:71]
	v_mfma_f32_16x16x32_bf16 v[80:83], v[204:207], v[180:183], v[80:83]
	v_mfma_f32_16x16x32_bf16 v[80:83], v[200:203], v[176:179], v[80:83]
	v_mfma_f32_16x16x32_bf16 v[60:63], v[200:203], v[184:187], v[60:63]
	v_mfma_f32_16x16x32_bf16 v[60:63], v[204:207], v[188:191], v[60:63]
	v_mfma_f32_16x16x32_bf16 v[56:59], v[212:215], v[188:191], v[56:59]
	v_mfma_f32_16x16x32_bf16 v[56:59], v[208:211], v[184:187], v[56:59]
	v_mfma_f32_16x16x32_bf16 v[48:51], v[208:211], v[192:195], v[48:51]
	v_mfma_f32_16x16x32_bf16 v[48:51], v[212:215], v[196:199], v[48:51]
	v_mfma_f32_16x16x32_bf16 v[52:55], v[204:207], v[196:199], v[52:55]
	v_mfma_f32_16x16x32_bf16 v[52:55], v[200:203], v[192:195], v[52:55]
	s_barrier
	s_addk_i32 s7, 0x180
	s_mov_b32 m0, s43
	ds_read_b128 v[168:171], v129 offset:49152
	ds_read_b128 v[172:175], v129 offset:50176
	ds_read_b128 v[176:179], v132 offset:49152
	ds_read_b128 v[180:183], v132 offset:50176
	ds_read_b128 v[184:187], v131 offset:49152
	ds_read_b128 v[188:191], v131 offset:50176
	ds_read_b128 v[192:195], v130 offset:49152
	ds_read_b128 v[196:199], v130 offset:50176
	buffer_load_dwordx4 v141, s[8:11], s7 offen lds
	s_mov_b32 m0, s59
	s_nop 0
	buffer_load_dwordx4 v142, s[8:11], s7 offen lds
	s_barrier
	s_waitcnt lgkmcnt(6)
	v_mfma_f32_16x16x32_bf16 v[44:47], v[152:155], v[168:171], v[44:47]
	v_mfma_f32_16x16x32_bf16 v[44:47], v[156:159], v[172:175], v[44:47]
	v_mfma_f32_16x16x32_bf16 v[40:43], v[164:167], v[172:175], v[40:43]
	v_mfma_f32_16x16x32_bf16 v[40:43], v[160:163], v[168:171], v[40:43]
	s_waitcnt lgkmcnt(4)
	v_mfma_f32_16x16x32_bf16 v[32:35], v[160:163], v[176:179], v[32:35]
	v_mfma_f32_16x16x32_bf16 v[32:35], v[164:167], v[180:183], v[32:35]
	v_mfma_f32_16x16x32_bf16 v[36:39], v[156:159], v[180:183], v[36:39]
	v_mfma_f32_16x16x32_bf16 v[36:39], v[152:155], v[176:179], v[36:39]
	s_waitcnt lgkmcnt(2)
	v_mfma_f32_16x16x32_bf16 v[28:31], v[152:155], v[184:187], v[28:31]
	v_mfma_f32_16x16x32_bf16 v[28:31], v[156:159], v[188:191], v[28:31]
	v_mfma_f32_16x16x32_bf16 v[24:27], v[164:167], v[188:191], v[24:27]
	v_mfma_f32_16x16x32_bf16 v[24:27], v[160:163], v[184:187], v[24:27]
	s_waitcnt lgkmcnt(0)
	v_mfma_f32_16x16x32_bf16 v[16:19], v[160:163], v[192:195], v[16:19]
	v_mfma_f32_16x16x32_bf16 v[16:19], v[164:167], v[196:199], v[16:19]
	v_mfma_f32_16x16x32_bf16 v[20:23], v[156:159], v[196:199], v[20:23]
	v_mfma_f32_16x16x32_bf16 v[20:23], v[152:155], v[192:195], v[20:23]
	s_barrier
	s_addk_i32 s22, 0x180
	s_mov_b32 m0, s44
	s_nop 0
	buffer_load_dwordx4 v141, s[12:15], s22 offen lds
	s_mov_b32 m0, s60
	s_nop 0
	buffer_load_dwordx4 v142, s[12:15], s22 offen lds
	s_add_i32 s1, s1, 2
	s_addk_i32 s3, 0x100
	s_cmp_gt_u32 s1, 11
	s_cbranch_scc0 .LBB0_291
	s_branch .Lmy_post_291

; #define STAGE(P, RS, SOFF, OFF, kt) do { const int _so = (SOFF) + (kt) * (BK * 2); \
;     _Pragma("unroll") for (int _i = 0; _i < 2; ++_i) { \
;       __builtin_amdgcn_raw_ptr_buffer_load_lds(RS, (__attribute__((address_space(3))) void*)((P) + wave * 1024 + _i * 8192), 16, OFF[_i], _so, 0, 0); } } while (0)
; #define LDA(dst, b, h) _Pragma("unroll") for (int m = 0; m < 4; ++m) _Pragma("unroll") for (int k = 0; k < 2; ++k) \
;     dst[m][k] = *reinterpret_cast<const bf16x8*>(SA(b, h) + lds_byte(wr * 64 + m * 16 + fr, k * 32 + fq * 8))
; #define LDB(dst, b, h) _Pragma("unroll") for (int n = 0; n < 2; ++n) _Pragma("unroll") for (int k = 0; k < 2; ++k) \
;     dst[n][k] = *reinterpret_cast<const bf16x8*>(SB(b, h) + lds_byte(wc * 32 + n * 16 + fr, k * 32 + fq * 8))
; #define WAIT_V(n) asm volatile("s_waitcnt vmcnt(" #n ")" ::: "memory")
; #define WAIT_L(n) asm volatile("s_waitcnt lgkmcnt(" #n ")" ::: "memory")
; #define BAR __builtin_amdgcn_s_barrier()
; #define SCHED __builtin_amdgcn_sched_barrier(0)
;     ...
;       LDB(B0, 0, 0); SCHED; LDA(At, 0, 0); STAGE(SA(1, 1), rsA, sA1, offA, t + 1);
;       WAIT_L(8); BAR; WAIT_L(0); MMA(0, 0, At, B0); BAR; SCHED;
;       LDB(B1, 0, 1); STAGE(SB(0, 0), rsB, sB0, offB, t + 2);
;       BAR; WAIT_L(0); MMA(0, 1, At, B1); BAR;
;       LDA(At, 0, 1); STAGE(SA(0, 0), rsA, sA0, offA, t + 2);
;       BAR; WAIT_L(0); MMA(1, 0, At, B0); BAR; SCHED;
;       STAGE(SB(0, 1), rsB, sB1, offB, t + 2);
;       WAIT_V(6); BAR; MMA(1, 1, At, B1); BAR;
.Lmy_rot_291:
	ds_read_b128 v[152:155], v147
	ds_read_b128 v[156:159], v148
	ds_read_b128 v[160:163], v149
	ds_read_b128 v[164:167], v150
	s_add_i32 s5, s94, s3
	s_add_i32 s6, s5, 0x80
	s_mov_b32 m0, s36
	ds_read_b128 v[168:171], v129
	ds_read_b128 v[172:175], v129 offset:1024
	ds_read_b128 v[176:179], v132
	ds_read_b128 v[180:183], v132 offset:1024
	ds_read_b128 v[184:187], v131
	ds_read_b128 v[188:191], v131 offset:1024
	ds_read_b128 v[192:195], v130
	ds_read_b128 v[196:199], v130 offset:1024
	buffer_load_dwordx4 v141, s[8:11], s6 offen lds
	s_mov_b32 m0, s61
	s_nop 0
	buffer_load_dwordx4 v142, s[8:11], s6 offen lds
	s_waitcnt lgkmcnt(8)
	s_barrier
	s_waitcnt lgkmcnt(0)
	v_mfma_f32_16x16x32_bf16 v[124:127], v[152:155], v[168:171], v[124:127]
	v_mfma_f32_16x16x32_bf16 v[124:127], v[156:159], v[172:175], v[124:127]
	v_mfma_f32_16x16x32_bf16 v[120:123], v[164:167], v[172:175], v[120:123]
	v_mfma_f32_16x16x32_bf16 v[120:123], v[160:163], v[168:171], v[120:123]
	v_mfma_f32_16x16x32_bf16 v[112:115], v[160:163], v[176:179], v[112:115]
	v_mfma_f32_16x16x32_bf16 v[112:115], v[164:167], v[180:183], v[112:115]
	v_mfma_f32_16x16x32_bf16 v[116:119], v[156:159], v[180:183], v[116:119]
	v_mfma_f32_16x16x32_bf16 v[116:119], v[152:155], v[176:179], v[116:119]
	v_mfma_f32_16x16x32_bf16 v[108:111], v[152:155], v[184:187], v[108:111]
	v_mfma_f32_16x16x32_bf16 v[108:111], v[156:159], v[188:191], v[108:111]
	v_mfma_f32_16x16x32_bf16 v[104:107], v[164:167], v[188:191], v[104:107]
	v_mfma_f32_16x16x32_bf16 v[104:107], v[160:163], v[184:187], v[104:107]
	v_mfma_f32_16x16x32_bf16 v[96:99], v[160:163], v[192:195], v[96:99]
	v_mfma_f32_16x16x32_bf16 v[96:99], v[164:167], v[196:199], v[96:99]
	v_mfma_f32_16x16x32_bf16 v[100:103], v[156:159], v[196:199], v[100:103]
	v_mfma_f32_16x16x32_bf16 v[100:103], v[152:155], v[192:195], v[100:103]
	s_barrier
	s_add_i32 s6, s96, s3
	s_add_i32 s7, s6, 0x100
	s_mov_b32 s14, s10
	s_mov_b32 s15, s11
	s_mov_b32 m0, s37
	ds_read_b128 v[200:203], v143
	ds_read_b128 v[204:207], v144
	ds_read_b128 v[208:211], v145
	ds_read_b128 v[212:215], v146
	buffer_load_dwordx4 v141, s[12:15], s7 offen lds
	s_mov_b32 m0, s48
	s_nop 0
	buffer_load_dwordx4 v142, s[12:15], s7 offen lds
	s_barrier
	s_waitcnt lgkmcnt(2)
	v_mfma_f32_16x16x32_bf16 v[92:95], v[200:203], v[168:171], v[92:95]
	v_mfma_f32_16x16x32_bf16 v[92:95], v[204:207], v[172:175], v[92:95]
	s_waitcnt lgkmcnt(0)
	v_mfma_f32_16x16x32_bf16 v[88:91], v[212:215], v[172:175], v[88:91]
	v_mfma_f32_16x16x32_bf16 v[88:91], v[208:211], v[168:171], v[88:91]
	v_mfma_f32_16x16x32_bf16 v[68:71], v[208:211], v[176:179], v[68:71]
	v_mfma_f32_16x16x32_bf16 v[68:71], v[212:215], v[180:183], v[68:71]
	v_mfma_f32_16x16x32_bf16 v[80:83], v[204:207], v[180:183], v[80:83]
	v_mfma_f32_16x16x32_bf16 v[80:83], v[200:203], v[176:179], v[80:83]
	v_mfma_f32_16x16x32_bf16 v[60:63], v[200:203], v[184:187], v[60:63]
	v_mfma_f32_16x16x32_bf16 v[60:63], v[204:207], v[188:191], v[60:63]
	v_mfma_f32_16x16x32_bf16 v[56:59], v[212:215], v[188:191], v[56:59]
	v_mfma_f32_16x16x32_bf16 v[56:59], v[208:211], v[184:187], v[56:59]
	v_mfma_f32_16x16x32_bf16 v[48:51], v[208:211], v[192:195], v[48:51]
	v_mfma_f32_16x16x32_bf16 v[48:51], v[212:215], v[196:199], v[48:51]
	v_mfma_f32_16x16x32_bf16 v[52:55], v[204:207], v[196:199], v[52:55]
	v_mfma_f32_16x16x32_bf16 v[52:55], v[200:203], v[192:195], v[52:55]
	s_barrier
	s_add_i32 s7, s95, s3
	s_add_i32 s22, s7, 0x100
	s_mov_b32 m0, s35
	ds_read_b128 v[168:171], v129 offset:16384
	ds_read_b128 v[172:175], v129 offset:17408
	ds_read_b128 v[176:179], v132 offset:16384
	ds_read_b128 v[180:183], v132 offset:17408
	ds_read_b128 v[184:187], v131 offset:16384
	ds_read_b128 v[188:191], v131 offset:17408
	ds_read_b128 v[192:195], v130 offset:16384
	ds_read_b128 v[196:199], v130 offset:17408
	buffer_load_dwordx4 v141, s[8:11], s22 offen lds
	s_mov_b32 m0, s49
	s_nop 0
	buffer_load_dwordx4 v142, s[8:11], s22 offen lds
	s_barrier
	s_waitcnt lgkmcnt(6)
	v_mfma_f32_16x16x32_bf16 v[44:47], v[152:155], v[168:171], v[44:47]
	v_mfma_f32_16x16x32_bf16 v[44:47], v[156:159], v[172:175], v[44:47]
	v_mfma_f32_16x16x32_bf16 v[40:43], v[164:167], v[172:175], v[40:43]
	v_mfma_f32_16x16x32_bf16 v[40:43], v[160:163], v[168:171], v[40:43]
	s_waitcnt lgkmcnt(4)
	v_mfma_f32_16x16x32_bf16 v[32:35], v[160:163], v[176:179], v[32:35]
	v_mfma_f32_16x16x32_bf16 v[32:35], v[164:167], v[180:183], v[32:35]
	v_mfma_f32_16x16x32_bf16 v[36:39], v[156:159], v[180:183], v[36:39]
	v_mfma_f32_16x16x32_bf16 v[36:39], v[152:155], v[176:179], v[36:39]
	s_waitcnt lgkmcnt(2)
	v_mfma_f32_16x16x32_bf16 v[28:31], v[152:155], v[184:187], v[28:31]
	v_mfma_f32_16x16x32_bf16 v[28:31], v[156:159], v[188:191], v[28:31]
	v_mfma_f32_16x16x32_bf16 v[24:27], v[164:167], v[188:191], v[24:27]
	v_mfma_f32_16x16x32_bf16 v[24:27], v[160:163], v[184:187], v[24:27]
	s_waitcnt lgkmcnt(0)
	v_mfma_f32_16x16x32_bf16 v[16:19], v[160:163], v[192:195], v[16:19]
	v_mfma_f32_16x16x32_bf16 v[16:19], v[164:167], v[196:199], v[16:19]
	v_mfma_f32_16x16x32_bf16 v[20:23], v[156:159], v[196:199], v[20:23]
	v_mfma_f32_16x16x32_bf16 v[20:23], v[152:155], v[192:195], v[20:23]
	s_barrier
	s_add_i32 s22, s97, s3
	s_add_i32 s23, s22, 0x100
	s_mov_b32 m0, s38
	s_nop 0
	buffer_load_dwordx4 v141, s[12:15], s23 offen lds
	s_mov_b32 m0, s54
	s_nop 0
	buffer_load_dwordx4 v142, s[12:15], s23 offen lds
	s_waitcnt vmcnt(6)
	s_barrier
; #define STAGE(P, RS, SOFF, OFF, kt) do { const int _so = (SOFF) + (kt) * (BK * 2); \
;     _Pragma("unroll") for (int _i = 0; _i < 2; ++_i) { \
;       __builtin_amdgcn_raw_ptr_buffer_load_lds(RS, (__attribute__((address_space(3))) void*)((P) + wave * 1024 + _i * 8192), 16, OFF[_i], _so, 0, 0); } } while (0)
; #define LDA(dst, b, h) _Pragma("unroll") for (int m = 0; m < 4; ++m) _Pragma("unroll") for (int k = 0; k < 2; ++k) \
;     dst[m][k] = *reinterpret_cast<const bf16x8*>(SA(b, h) + lds_byte(wr * 64 + m * 16 + fr, k * 32 + fq * 8))
; #define LDB(dst, b, h) _Pragma("unroll") for (int n = 0; n < 2; ++n) _Pragma("unroll") for (int k = 0; k < 2; ++k) \
;     dst[n][k] = *reinterpret_cast<const bf16x8*>(SB(b, h) + lds_byte(wc * 32 + n * 16 + fr, k * 32 + fq * 8))
; #define WAIT_V(n) asm volatile("s_waitcnt vmcnt(" #n ")" ::: "memory")
; #define WAIT_L(n) asm volatile("s_waitcnt lgkmcnt(" #n ")" ::: "memory")
; #define BAR __builtin_amdgcn_s_barrier()
; #define SCHED __builtin_amdgcn_sched_barrier(0)
;     ...
;       WAIT_V(6); BAR; MMA(1, 1, At, B1); BAR;
;       LDB(B0, 1, 0); SCHED; LDA(At, 1, 0); STAGE(SA(0, 1), rsA, sA1, offA, t + 2);
;       WAIT_L(8); BAR; WAIT_L(0); MMA(0, 0, At, B0); BAR; SCHED;
;       LDB(B1, 1, 1); STAGE(SB(1, 0), rsB, sB0, offB, t + 3);
;       BAR; WAIT_L(0); MMA(0, 1, At, B1); BAR;
;       LDA(At, 1, 1); STAGE(SA(1, 0), rsA, sA0, offA, t + 3);
;       BAR; WAIT_L(0); MMA(1, 0, At, B0); BAR; SCHED;
;       STAGE(SB(1, 1), rsB, sB1, offB, t + 3);
;       WAIT_V(6); BAR; MMA(1, 1, At, B1); BAR;
	v_mfma_f32_16x16x32_bf16 v[12:15], v[200:203], v[168:171], v[12:15]
	v_mfma_f32_16x16x32_bf16 v[12:15], v[204:207], v[172:175], v[12:15]
	v_mfma_f32_16x16x32_bf16 v[8:11], v[212:215], v[172:175], v[8:11]
	v_mfma_f32_16x16x32_bf16 v[8:11], v[208:211], v[168:171], v[8:11]
	v_mfma_f32_16x16x32_bf16 v[0:3], v[208:211], v[176:179], v[0:3]
	v_mfma_f32_16x16x32_bf16 v[0:3], v[212:215], v[180:183], v[0:3]
	v_mfma_f32_16x16x32_bf16 v[4:7], v[204:207], v[180:183], v[4:7]
	v_mfma_f32_16x16x32_bf16 v[4:7], v[200:203], v[176:179], v[4:7]
	v_mfma_f32_16x16x32_bf16 v[64:67], v[200:203], v[184:187], v[64:67]
	v_mfma_f32_16x16x32_bf16 v[64:67], v[204:207], v[188:191], v[64:67]
	v_mfma_f32_16x16x32_bf16 v[72:75], v[212:215], v[188:191], v[72:75]
	v_mfma_f32_16x16x32_bf16 v[72:75], v[208:211], v[184:187], v[72:75]
	v_mfma_f32_16x16x32_bf16 v[84:87], v[208:211], v[192:195], v[84:87]
	v_mfma_f32_16x16x32_bf16 v[84:87], v[212:215], v[196:199], v[84:87]
	v_mfma_f32_16x16x32_bf16 v[76:79], v[204:207], v[196:199], v[76:79]
	v_mfma_f32_16x16x32_bf16 v[76:79], v[200:203], v[192:195], v[76:79]
	s_barrier
	ds_read_b128 v[152:155], v137
	ds_read_b128 v[156:159], v138
	ds_read_b128 v[160:163], v139
	ds_read_b128 v[164:167], v140
	s_addk_i32 s5, 0x100
	s_mov_b32 m0, s39
	ds_read_b128 v[168:171], v129 offset:32768
	ds_read_b128 v[172:175], v129 offset:33792
	ds_read_b128 v[176:179], v132 offset:32768
	ds_read_b128 v[180:183], v132 offset:33792
	ds_read_b128 v[184:187], v131 offset:32768
	ds_read_b128 v[188:191], v131 offset:33792
	ds_read_b128 v[192:195], v130 offset:32768
	ds_read_b128 v[196:199], v130 offset:33792
	buffer_load_dwordx4 v141, s[8:11], s5 offen lds
	s_mov_b32 m0, s55
	s_nop 0
	buffer_load_dwordx4 v142, s[8:11], s5 offen lds
	s_waitcnt lgkmcnt(8)
	s_barrier
	s_waitcnt lgkmcnt(6)
	v_mfma_f32_16x16x32_bf16 v[124:127], v[152:155], v[168:171], v[124:127]
	v_mfma_f32_16x16x32_bf16 v[124:127], v[156:159], v[172:175], v[124:127]
	v_mfma_f32_16x16x32_bf16 v[120:123], v[164:167], v[172:175], v[120:123]
	v_mfma_f32_16x16x32_bf16 v[120:123], v[160:163], v[168:171], v[120:123]
	s_waitcnt lgkmcnt(4)
	v_mfma_f32_16x16x32_bf16 v[112:115], v[160:163], v[176:179], v[112:115]
	v_mfma_f32_16x16x32_bf16 v[112:115], v[164:167], v[180:183], v[112:115]
	v_mfma_f32_16x16x32_bf16 v[116:119], v[156:159], v[180:183], v[116:119]
	v_mfma_f32_16x16x32_bf16 v[116:119], v[152:155], v[176:179], v[116:119]
	s_waitcnt lgkmcnt(2)
	v_mfma_f32_16x16x32_bf16 v[108:111], v[152:155], v[184:187], v[108:111]
	v_mfma_f32_16x16x32_bf16 v[108:111], v[156:159], v[188:191], v[108:111]
	v_mfma_f32_16x16x32_bf16 v[104:107], v[164:167], v[188:191], v[104:107]
	v_mfma_f32_16x16x32_bf16 v[104:107], v[160:163], v[184:187], v[104:107]
	s_waitcnt lgkmcnt(0)
	v_mfma_f32_16x16x32_bf16 v[96:99], v[160:163], v[192:195], v[96:99]
	v_mfma_f32_16x16x32_bf16 v[96:99], v[164:167], v[196:199], v[96:99]
	v_mfma_f32_16x16x32_bf16 v[100:103], v[156:159], v[196:199], v[100:103]
	v_mfma_f32_16x16x32_bf16 v[100:103], v[152:155], v[192:195], v[100:103]
	s_barrier
	s_addk_i32 s6, 0x180
	s_mov_b32 m0, s42
	ds_read_b128 v[200:203], v133
	ds_read_b128 v[204:207], v134
	ds_read_b128 v[208:211], v135
	ds_read_b128 v[212:215], v136
	buffer_load_dwordx4 v141, s[12:15], s6 offen lds
	s_mov_b32 m0, s58
	s_nop 0
	buffer_load_dwordx4 v142, s[12:15], s6 offen lds
	s_barrier
	s_waitcnt lgkmcnt(2)
	v_mfma_f32_16x16x32_bf16 v[92:95], v[200:203], v[168:171], v[92:95]
	v_mfma_f32_16x16x32_bf16 v[92:95], v[204:207], v[172:175], v[92:95]
	s_waitcnt lgkmcnt(0)
	v_mfma_f32_16x16x32_bf16 v[88:91], v[212:215], v[172:175], v[88:91]
	v_mfma_f32_16x16x32_bf16 v[88:91], v[208:211], v[168:171], v[88:91]
	v_mfma_f32_16x16x32_bf16 v[68:71], v[208:211], v[176:179], v[68:71]
	v_mfma_f32_16x16x32_bf16 v[68:71], v[212:215], v[180:183], v[68:71]
	v_mfma_f32_16x16x32_bf16 v[80:83], v[204:207], v[180:183], v[80:83]
	v_mfma_f32_16x16x32_bf16 v[80:83], v[200:203], v[176:179], v[80:83]
	v_mfma_f32_16x16x32_bf16 v[60:63], v[200:203], v[184:187], v[60:63]
	v_mfma_f32_16x16x32_bf16 v[60:63], v[204:207], v[188:191], v[60:63]
	v_mfma_f32_16x16x32_bf16 v[56:59], v[212:215], v[188:191], v[56:59]
	v_mfma_f32_16x16x32_bf16 v[56:59], v[208:211], v[184:187], v[56:59]
	v_mfma_f32_16x16x32_bf16 v[48:51], v[208:211], v[192:195], v[48:51]
	v_mfma_f32_16x16x32_bf16 v[48:51], v[212:215], v[196:199], v[48:51]
	v_mfma_f32_16x16x32_bf16 v[52:55], v[204:207], v[196:199], v[52:55]
	v_mfma_f32_16x16x32_bf16 v[52:55], v[200:203], v[192:195], v[52:55]
	s_barrier
	s_addk_i32 s7, 0x180
	s_mov_b32 m0, s43
	ds_read_b128 v[168:171], v129 offset:49152
	ds_read_b128 v[172:175], v129 offset:50176
	ds_read_b128 v[176:179], v132 offset:49152
	ds_read_b128 v[180:183], v132 offset:50176
	ds_read_b128 v[184:187], v131 offset:49152
	ds_read_b128 v[188:191], v131 offset:50176
	ds_read_b128 v[192:195], v130 offset:49152
	ds_read_b128 v[196:199], v130 offset:50176
	buffer_load_dwordx4 v141, s[8:11], s7 offen lds
	s_mov_b32 m0, s59
	s_nop 0
	buffer_load_dwordx4 v142, s[8:11], s7 offen lds
	s_barrier
	s_waitcnt lgkmcnt(6)
	v_mfma_f32_16x16x32_bf16 v[44:47], v[152:155], v[168:171], v[44:47]
	v_mfma_f32_16x16x32_bf16 v[44:47], v[156:159], v[172:175], v[44:47]
	v_mfma_f32_16x16x32_bf16 v[40:43], v[164:167], v[172:175], v[40:43]
	v_mfma_f32_16x16x32_bf16 v[40:43], v[160:163], v[168:171], v[40:43]
	s_waitcnt lgkmcnt(4)
	v_mfma_f32_16x16x32_bf16 v[32:35], v[160:163], v[176:179], v[32:35]
	v_mfma_f32_16x16x32_bf16 v[32:35], v[164:167], v[180:183], v[32:35]
	v_mfma_f32_16x16x32_bf16 v[36:39], v[156:159], v[180:183], v[36:39]
	v_mfma_f32_16x16x32_bf16 v[36:39], v[152:155], v[176:179], v[36:39]
	s_waitcnt lgkmcnt(2)
	v_mfma_f32_16x16x32_bf16 v[28:31], v[152:155], v[184:187], v[28:31]
	v_mfma_f32_16x16x32_bf16 v[28:31], v[156:159], v[188:191], v[28:31]
	v_mfma_f32_16x16x32_bf16 v[24:27], v[164:167], v[188:191], v[24:27]
	v_mfma_f32_16x16x32_bf16 v[24:27], v[160:163], v[184:187], v[24:27]
	s_waitcnt lgkmcnt(0)
	v_mfma_f32_16x16x32_bf16 v[16:19], v[160:163], v[192:195], v[16:19]
	v_mfma_f32_16x16x32_bf16 v[16:19], v[164:167], v[196:199], v[16:19]
	v_mfma_f32_16x16x32_bf16 v[20:23], v[156:159], v[196:199], v[20:23]
	v_mfma_f32_16x16x32_bf16 v[20:23], v[152:155], v[192:195], v[20:23]
	s_barrier
	s_addk_i32 s22, 0x180
	s_mov_b32 m0, s44
	s_nop 0
	buffer_load_dwordx4 v141, s[12:15], s22 offen lds
	s_mov_b32 m0, s60
	s_nop 0
	buffer_load_dwordx4 v142, s[12:15], s22 offen lds
	s_add_i32 s1, s1, 2
	s_addk_i32 s3, 0x100
	s_cmp_gt_u32 s1, 11
	s_cbranch_scc0 .LBB0_291
; #define STAGE(P, RS, SOFF, OFF, kt) do { const int _so = (SOFF) + (kt) * (BK * 2); \
;     _Pragma("unroll") for (int _i = 0; _i < 2; ++_i) { \
;       __builtin_amdgcn_raw_ptr_buffer_load_lds(RS, (__attribute__((address_space(3))) void*)((P) + wave * 1024 + _i * 8192), 16, OFF[_i], _so, 0, 0); } } while (0)
; #define LDA(dst, b, h) _Pragma("unroll") for (int m = 0; m < 4; ++m) _Pragma("unroll") for (int k = 0; k < 2; ++k) \
;     dst[m][k] = *reinterpret_cast<const bf16x8*>(SA(b, h) + lds_byte(wr * 64 + m * 16 + fr, k * 32 + fq * 8))
; #define LDB(dst, b, h) _Pragma("unroll") for (int n = 0; n < 2; ++n) _Pragma("unroll") for (int k = 0; k < 2; ++k) \
;     dst[n][k] = *reinterpret_cast<const bf16x8*>(SB(b, h) + lds_byte(wc * 32 + n * 16 + fr, k * 32 + fq * 8))
; #define WAIT_V(n) asm volatile("s_waitcnt vmcnt(" #n ")" ::: "memory")
; #define WAIT_L(n) asm volatile("s_waitcnt lgkmcnt(" #n ")" ::: "memory")
; #define BAR __builtin_amdgcn_s_barrier()
;     ...
;       WAIT_V(6); BAR; MMA(1, 1, At, B1); BAR;
;     }
;     { LDB(B0, 0, 0); LDA(At, 0, 0); STAGE(SA(1, 1), rsA, sA1, offA, nt - 1);
;       BAR; WAIT_L(0); MMA(0, 0, At, B0); BAR;
;       LDB(B1, 0, 1); BAR; WAIT_L(0); MMA(0, 1, At, B1); BAR;
;       LDA(At, 0, 1); WAIT_V(4); BAR; WAIT_L(0); MMA(1, 0, At, B0); MMA(1, 1, At, B1); BAR; }
.Lmy_post_291:
	s_waitcnt vmcnt(6)
	s_barrier
	v_mfma_f32_16x16x32_bf16 v[12:15], v[200:203], v[168:171], v[12:15]
	v_mfma_f32_16x16x32_bf16 v[12:15], v[204:207], v[172:175], v[12:15]
	v_mfma_f32_16x16x32_bf16 v[8:11], v[212:215], v[172:175], v[8:11]
	v_mfma_f32_16x16x32_bf16 v[8:11], v[208:211], v[168:171], v[8:11]
	v_mfma_f32_16x16x32_bf16 v[0:3], v[208:211], v[176:179], v[0:3]
	v_mfma_f32_16x16x32_bf16 v[0:3], v[212:215], v[180:183], v[0:3]
	v_mfma_f32_16x16x32_bf16 v[4:7], v[204:207], v[180:183], v[4:7]
	v_mfma_f32_16x16x32_bf16 v[4:7], v[200:203], v[176:179], v[4:7]
	v_mfma_f32_16x16x32_bf16 v[64:67], v[200:203], v[184:187], v[64:67]
	v_mfma_f32_16x16x32_bf16 v[64:67], v[204:207], v[188:191], v[64:67]
	v_mfma_f32_16x16x32_bf16 v[72:75], v[212:215], v[188:191], v[72:75]
	v_mfma_f32_16x16x32_bf16 v[72:75], v[208:211], v[184:187], v[72:75]
	v_mfma_f32_16x16x32_bf16 v[84:87], v[208:211], v[192:195], v[84:87]
	v_mfma_f32_16x16x32_bf16 v[84:87], v[212:215], v[196:199], v[84:87]
	v_mfma_f32_16x16x32_bf16 v[76:79], v[204:207], v[196:199], v[76:79]
	v_mfma_f32_16x16x32_bf16 v[76:79], v[200:203], v[192:195], v[76:79]
	s_barrier
	s_add_i32 s1, s94, 0x780
	s_mov_b32 m0, s36
	ds_read_b128 v[152:155], v147
	ds_read_b128 v[156:159], v148
	ds_read_b128 v[160:163], v149
	ds_read_b128 v[148:151], v150
	ds_read_b128 v[164:167], v129
	ds_read_b128 v[168:171], v129 offset:1024
	ds_read_b128 v[172:175], v132
	ds_read_b128 v[176:179], v132 offset:1024
	ds_read_b128 v[180:183], v131
	ds_read_b128 v[184:187], v131 offset:1024
	ds_read_b128 v[188:191], v130
	ds_read_b128 v[192:195], v130 offset:1024
	buffer_load_dwordx4 v141, s[8:11], s1 offen lds
	s_mov_b32 m0, s61
	s_nop 0
	buffer_load_dwordx4 v142, s[8:11], s1 offen lds
	s_barrier
	s_waitcnt lgkmcnt(6)
	v_mfma_f32_16x16x32_bf16 v[124:127], v[152:155], v[164:167], v[124:127]
	v_mfma_f32_16x16x32_bf16 v[124:127], v[156:159], v[168:171], v[124:127]
	v_mfma_f32_16x16x32_bf16 v[120:123], v[148:151], v[168:171], v[120:123]
	v_mfma_f32_16x16x32_bf16 v[120:123], v[160:163], v[164:167], v[120:123]
	s_waitcnt lgkmcnt(4)
	v_mfma_f32_16x16x32_bf16 v[112:115], v[160:163], v[172:175], v[112:115]
	v_mfma_f32_16x16x32_bf16 v[112:115], v[148:151], v[176:179], v[112:115]
	v_mfma_f32_16x16x32_bf16 v[116:119], v[156:159], v[176:179], v[116:119]
	v_mfma_f32_16x16x32_bf16 v[116:119], v[152:155], v[172:175], v[116:119]
	s_waitcnt lgkmcnt(2)
	v_mfma_f32_16x16x32_bf16 v[108:111], v[152:155], v[180:183], v[108:111]
	v_mfma_f32_16x16x32_bf16 v[108:111], v[156:159], v[184:187], v[108:111]
	v_mfma_f32_16x16x32_bf16 v[104:107], v[148:151], v[184:187], v[104:107]
	v_mfma_f32_16x16x32_bf16 v[104:107], v[160:163], v[180:183], v[104:107]
	s_waitcnt lgkmcnt(0)
	v_mfma_f32_16x16x32_bf16 v[96:99], v[160:163], v[188:191], v[96:99]
	v_mfma_f32_16x16x32_bf16 v[96:99], v[148:151], v[192:195], v[96:99]
	v_mfma_f32_16x16x32_bf16 v[100:103], v[156:159], v[192:195], v[100:103]
	v_mfma_f32_16x16x32_bf16 v[100:103], v[152:155], v[188:191], v[100:103]
	s_barrier
	ds_read_b128 v[196:199], v143
	ds_read_b128 v[200:203], v144
	ds_read_b128 v[142:145], v145
	ds_read_b128 v[204:207], v146
	s_barrier
	s_waitcnt lgkmcnt(1)
	v_mfma_f32_16x16x32_bf16 v[88:91], v[142:145], v[164:167], v[88:91]
	v_mfma_f32_16x16x32_bf16 v[80:83], v[196:199], v[172:175], v[80:83]
	v_mfma_f32_16x16x32_bf16 v[60:63], v[196:199], v[180:183], v[60:63]
	v_mfma_f32_16x16x32_bf16 v[56:59], v[142:145], v[180:183], v[56:59]
	v_mfma_f32_16x16x32_bf16 v[52:55], v[196:199], v[188:191], v[52:55]
	v_mfma_f32_16x16x32_bf16 v[48:51], v[142:145], v[188:191], v[48:51]
	v_mfma_f32_16x16x32_bf16 v[92:95], v[196:199], v[164:167], v[92:95]
	v_mfma_f32_16x16x32_bf16 v[68:71], v[142:145], v[172:175], v[68:71]
	s_waitcnt lgkmcnt(0)
	v_mfma_f32_16x16x32_bf16 v[88:91], v[204:207], v[168:171], v[88:91]
	v_mfma_f32_16x16x32_bf16 v[80:83], v[200:203], v[176:179], v[80:83]
	v_mfma_f32_16x16x32_bf16 v[60:63], v[200:203], v[184:187], v[60:63]
	v_mfma_f32_16x16x32_bf16 v[56:59], v[204:207], v[184:187], v[56:59]
	v_mfma_f32_16x16x32_bf16 v[52:55], v[200:203], v[192:195], v[52:55]
	v_mfma_f32_16x16x32_bf16 v[48:51], v[204:207], v[192:195], v[48:51]
	v_mfma_f32_16x16x32_bf16 v[164:167], v[200:203], v[168:171], v[92:95]
	v_mfma_f32_16x16x32_bf16 v[168:171], v[204:207], v[176:179], v[68:71]
	s_barrier
	s_nop 0
	ds_read_b128 v[68:71], v129 offset:16384
	ds_read_b128 v[92:95], v129 offset:17408
	ds_read_b128 v[172:175], v132 offset:16384
	ds_read_b128 v[176:179], v132 offset:17408
	ds_read_b128 v[180:183], v131 offset:16384
	ds_read_b128 v[184:187], v131 offset:17408
	ds_read_b128 v[188:191], v130 offset:16384
	ds_read_b128 v[192:195], v130 offset:17408
	s_waitcnt vmcnt(4)
	s_barrier
; #define LDA(dst, b, h) _Pragma("unroll") for (int m = 0; m < 4; ++m) _Pragma("unroll") for (int k = 0; k < 2; ++k) \
;     dst[m][k] = *reinterpret_cast<const bf16x8*>(SA(b, h) + lds_byte(wr * 64 + m * 16 + fr, k * 32 + fq * 8))
; #define LDB(dst, b, h) _Pragma("unroll") for (int n = 0; n < 2; ++n) _Pragma("unroll") for (int k = 0; k < 2; ++k) \
;     dst[n][k] = *reinterpret_cast<const bf16x8*>(SB(b, h) + lds_byte(wc * 32 + n * 16 + fr, k * 32 + fq * 8))
; #define WAIT_V(n) asm volatile("s_waitcnt vmcnt(" #n ")" ::: "memory")
; #define WAIT_L(n) asm volatile("s_waitcnt lgkmcnt(" #n ")" ::: "memory")
; #define BAR __builtin_amdgcn_s_barrier()
;     ...
;       LDA(At, 0, 1); WAIT_V(4); BAR; WAIT_L(0); MMA(1, 0, At, B0); MMA(1, 1, At, B1); BAR; }
;     { LDB(B0, 1, 0); LDA(At, 1, 0); WAIT_V(2); BAR; WAIT_L(0); MMA(0, 0, At, B0); BAR;
	s_waitcnt lgkmcnt(0)
	v_mfma_f32_16x16x32_bf16 v[44:47], v[152:155], v[68:71], v[44:47]
	v_mfma_f32_16x16x32_bf16 v[40:43], v[160:163], v[68:71], v[40:43]
	v_mfma_f32_16x16x32_bf16 v[36:39], v[152:155], v[172:175], v[36:39]
	v_mfma_f32_16x16x32_bf16 v[32:35], v[160:163], v[172:175], v[32:35]
	v_mfma_f32_16x16x32_bf16 v[28:31], v[152:155], v[180:183], v[28:31]
	v_mfma_f32_16x16x32_bf16 v[24:27], v[160:163], v[180:183], v[24:27]
	v_mfma_f32_16x16x32_bf16 v[20:23], v[152:155], v[188:191], v[20:23]
	v_mfma_f32_16x16x32_bf16 v[16:19], v[160:163], v[188:191], v[16:19]
	v_mfma_f32_16x16x32_bf16 v[44:47], v[156:159], v[92:95], v[44:47]
	v_mfma_f32_16x16x32_bf16 v[40:43], v[148:151], v[92:95], v[40:43]
	v_mfma_f32_16x16x32_bf16 v[36:39], v[156:159], v[176:179], v[36:39]
	v_mfma_f32_16x16x32_bf16 v[32:35], v[148:151], v[176:179], v[32:35]
	v_mfma_f32_16x16x32_bf16 v[28:31], v[156:159], v[184:187], v[28:31]
	v_mfma_f32_16x16x32_bf16 v[24:27], v[148:151], v[184:187], v[24:27]
	v_mfma_f32_16x16x32_bf16 v[20:23], v[156:159], v[192:195], v[20:23]
	v_mfma_f32_16x16x32_bf16 v[16:19], v[148:151], v[192:195], v[16:19]
	v_mfma_f32_16x16x32_bf16 v[4:7], v[196:199], v[172:175], v[4:7]
	v_mfma_f32_16x16x32_bf16 v[0:3], v[142:145], v[172:175], v[0:3]
	v_mfma_f32_16x16x32_bf16 v[12:15], v[196:199], v[68:71], v[12:15]
	v_mfma_f32_16x16x32_bf16 v[8:11], v[142:145], v[68:71], v[8:11]
	v_mfma_f32_16x16x32_bf16 v[64:67], v[196:199], v[180:183], v[64:67]
	v_mfma_f32_16x16x32_bf16 v[68:71], v[142:145], v[180:183], v[72:75]
	v_mfma_f32_16x16x32_bf16 v[72:75], v[196:199], v[188:191], v[76:79]
	v_mfma_f32_16x16x32_bf16 v[76:79], v[142:145], v[188:191], v[84:87]
	v_mfma_f32_16x16x32_bf16 v[4:7], v[200:203], v[176:179], v[4:7]
	v_mfma_f32_16x16x32_bf16 v[0:3], v[204:207], v[176:179], v[0:3]
	v_mfma_f32_16x16x32_bf16 v[142:145], v[200:203], v[92:95], v[12:15]
	v_mfma_f32_16x16x32_bf16 v[146:149], v[204:207], v[92:95], v[8:11]
	v_mfma_f32_16x16x32_bf16 v[150:153], v[200:203], v[184:187], v[64:67]
	v_mfma_f32_16x16x32_bf16 v[154:157], v[204:207], v[184:187], v[68:71]
	v_mfma_f32_16x16x32_bf16 v[158:161], v[200:203], v[192:195], v[72:75]
	v_mfma_f32_16x16x32_bf16 v[172:175], v[204:207], v[192:195], v[76:79]
	s_barrier
	ds_read_b128 v[8:11], v137
	ds_read_b128 v[12:15], v138
	ds_read_b128 v[176:179], v139
	ds_read_b128 v[138:141], v140
	ds_read_b128 v[64:67], v129 offset:32768
	ds_read_b128 v[72:75], v129 offset:33792
	ds_read_b128 v[180:183], v132 offset:32768
	ds_read_b128 v[184:187], v132 offset:33792
	ds_read_b128 v[188:191], v131 offset:32768
	ds_read_b128 v[192:195], v131 offset:33792
	ds_read_b128 v[196:199], v130 offset:32768
	ds_read_b128 v[200:203], v130 offset:33792
	s_waitcnt vmcnt(2)
	s_barrier
	s_waitcnt lgkmcnt(7)
	v_mfma_f32_16x16x32_bf16 v[68:71], v[8:11], v[64:67], v[124:127]
	v_mfma_f32_16x16x32_bf16 v[76:79], v[176:179], v[64:67], v[120:123]
	s_waitcnt lgkmcnt(5)
	v_mfma_f32_16x16x32_bf16 v[84:87], v[8:11], v[180:183], v[116:119]
	v_mfma_f32_16x16x32_bf16 v[92:95], v[176:179], v[180:183], v[112:115]
	s_waitcnt lgkmcnt(3)
	v_mfma_f32_16x16x32_bf16 v[112:115], v[8:11], v[188:191], v[108:111]
	v_mfma_f32_16x16x32_bf16 v[104:107], v[176:179], v[188:191], v[104:107]
	s_waitcnt lgkmcnt(1)
	v_mfma_f32_16x16x32_bf16 v[120:123], v[8:11], v[196:199], v[100:103]
	v_mfma_f32_16x16x32_bf16 v[96:99], v[176:179], v[196:199], v[96:99]
	v_mfma_f32_16x16x32_bf16 v[124:127], v[12:15], v[72:75], v[68:71]
	v_mfma_f32_16x16x32_bf16 v[116:119], v[138:141], v[72:75], v[76:79]
	v_mfma_f32_16x16x32_bf16 v[108:111], v[12:15], v[184:187], v[84:87]
	v_mfma_f32_16x16x32_bf16 v[100:103], v[138:141], v[184:187], v[92:95]
	v_mfma_f32_16x16x32_bf16 v[92:95], v[12:15], v[192:195], v[112:115]
	v_mfma_f32_16x16x32_bf16 v[84:87], v[138:141], v[192:195], v[104:107]
	s_waitcnt lgkmcnt(0)
	v_mfma_f32_16x16x32_bf16 v[76:79], v[12:15], v[200:203], v[120:123]
	v_mfma_f32_16x16x32_bf16 v[68:71], v[138:141], v[200:203], v[96:99]
	s_barrier
; #define LDA(dst, b, h) _Pragma("unroll") for (int m = 0; m < 4; ++m) _Pragma("unroll") for (int k = 0; k < 2; ++k) \
;     dst[m][k] = *reinterpret_cast<const bf16x8*>(SA(b, h) + lds_byte(wr * 64 + m * 16 + fr, k * 32 + fq * 8))
; #define LDB(dst, b, h) _Pragma("unroll") for (int n = 0; n < 2; ++n) _Pragma("unroll") for (int k = 0; k < 2; ++k) \
;     dst[n][k] = *reinterpret_cast<const bf16x8*>(SB(b, h) + lds_byte(wc * 32 + n * 16 + fr, k * 32 + fq * 8))
; #define WAIT_V(n) asm volatile("s_waitcnt vmcnt(" #n ")" ::: "memory")
; #define WAIT_L(n) asm volatile("s_waitcnt lgkmcnt(" #n ")" ::: "memory")
; #define BAR __builtin_amdgcn_s_barrier()
;     ...
;     { LDB(B0, 1, 0); LDA(At, 1, 0); WAIT_V(2); BAR; WAIT_L(0); MMA(0, 0, At, B0); BAR;
;       LDB(B1, 1, 1); WAIT_V(0); BAR; WAIT_L(0); MMA(0, 1, At, B1); BAR;
;       LDA(At, 1, 1); BAR; WAIT_L(0); MMA(1, 0, At, B0); MMA(1, 1, At, B1); BAR; }
;     if (wr == 0) BAR;
	ds_read_b128 v[204:207], v133
	ds_read_b128 v[208:211], v134
	ds_read_b128 v[212:215], v135
	ds_read_b128 v[134:137], v136
	s_waitcnt vmcnt(0)
	s_barrier
	s_waitcnt lgkmcnt(1)
	v_mfma_f32_16x16x32_bf16 v[96:99], v[204:207], v[64:67], v[164:167]
	v_mfma_f32_16x16x32_bf16 v[64:67], v[212:215], v[64:67], v[88:91]
	v_mfma_f32_16x16x32_bf16 v[80:83], v[204:207], v[180:183], v[80:83]
	v_mfma_f32_16x16x32_bf16 v[88:91], v[212:215], v[180:183], v[168:171]
	v_mfma_f32_16x16x32_bf16 v[60:63], v[204:207], v[188:191], v[60:63]
	v_mfma_f32_16x16x32_bf16 v[56:59], v[212:215], v[188:191], v[56:59]
	v_mfma_f32_16x16x32_bf16 v[52:55], v[204:207], v[196:199], v[52:55]
	v_mfma_f32_16x16x32_bf16 v[48:51], v[212:215], v[196:199], v[48:51]
	s_waitcnt lgkmcnt(0)
	v_mfma_f32_16x16x32_bf16 v[120:123], v[208:211], v[72:75], v[96:99]
	v_mfma_f32_16x16x32_bf16 v[112:115], v[134:137], v[72:75], v[64:67]
	v_mfma_f32_16x16x32_bf16 v[104:107], v[208:211], v[184:187], v[80:83]
	v_mfma_f32_16x16x32_bf16 v[96:99], v[134:137], v[184:187], v[88:91]
	v_mfma_f32_16x16x32_bf16 v[88:91], v[208:211], v[192:195], v[60:63]
	v_mfma_f32_16x16x32_bf16 v[80:83], v[134:137], v[192:195], v[56:59]
	v_mfma_f32_16x16x32_bf16 v[72:75], v[208:211], v[200:203], v[52:55]
	v_mfma_f32_16x16x32_bf16 v[64:67], v[134:137], v[200:203], v[48:51]
	s_barrier
	s_nop 0
	ds_read_b128 v[48:51], v129 offset:49152
	ds_read_b128 v[162:165], v129 offset:50176
	ds_read_b128 v[52:55], v132 offset:49152
	ds_read_b128 v[166:169], v132 offset:50176
	ds_read_b128 v[180:183], v131 offset:49152
	ds_read_b128 v[184:187], v131 offset:50176
	ds_read_b128 v[188:191], v130 offset:49152
	ds_read_b128 v[130:133], v130 offset:50176
	s_barrier
	s_waitcnt lgkmcnt(0)
	v_mfma_f32_16x16x32_bf16 v[44:47], v[8:11], v[48:51], v[44:47]
	v_mfma_f32_16x16x32_bf16 v[40:43], v[176:179], v[48:51], v[40:43]
	v_mfma_f32_16x16x32_bf16 v[36:39], v[8:11], v[52:55], v[36:39]
	v_mfma_f32_16x16x32_bf16 v[32:35], v[176:179], v[52:55], v[32:35]
	v_mfma_f32_16x16x32_bf16 v[28:31], v[8:11], v[180:183], v[28:31]
	v_mfma_f32_16x16x32_bf16 v[24:27], v[176:179], v[180:183], v[24:27]
	v_mfma_f32_16x16x32_bf16 v[8:11], v[8:11], v[188:191], v[20:23]
	v_mfma_f32_16x16x32_bf16 v[16:19], v[176:179], v[188:191], v[16:19]
	v_mfma_f32_16x16x32_bf16 v[60:63], v[12:15], v[162:165], v[44:47]
	v_mfma_f32_16x16x32_bf16 v[56:59], v[138:141], v[162:165], v[40:43]
	v_mfma_f32_16x16x32_bf16 v[44:47], v[12:15], v[166:169], v[36:39]
	v_mfma_f32_16x16x32_bf16 v[40:43], v[138:141], v[166:169], v[32:35]
	v_mfma_f32_16x16x32_bf16 v[28:31], v[12:15], v[184:187], v[28:31]
	v_mfma_f32_16x16x32_bf16 v[24:27], v[138:141], v[184:187], v[24:27]
	v_mfma_f32_16x16x32_bf16 v[12:15], v[12:15], v[130:133], v[8:11]
	v_mfma_f32_16x16x32_bf16 v[8:11], v[138:141], v[130:133], v[16:19]
	v_mfma_f32_16x16x32_bf16 v[16:19], v[204:207], v[48:51], v[142:145]
	v_mfma_f32_16x16x32_bf16 v[20:23], v[212:215], v[48:51], v[146:149]
	v_mfma_f32_16x16x32_bf16 v[4:7], v[204:207], v[52:55], v[4:7]
	v_mfma_f32_16x16x32_bf16 v[0:3], v[212:215], v[52:55], v[0:3]
	v_mfma_f32_16x16x32_bf16 v[138:141], v[204:207], v[180:183], v[150:153]
	v_mfma_f32_16x16x32_bf16 v[142:145], v[212:215], v[180:183], v[154:157]
	v_mfma_f32_16x16x32_bf16 v[146:149], v[204:207], v[188:191], v[158:161]
	v_mfma_f32_16x16x32_bf16 v[150:153], v[212:215], v[188:191], v[172:175]
	v_mfma_f32_16x16x32_bf16 v[52:55], v[208:211], v[162:165], v[16:19]
	v_mfma_f32_16x16x32_bf16 v[48:51], v[134:137], v[162:165], v[20:23]
	v_mfma_f32_16x16x32_bf16 v[36:39], v[208:211], v[166:169], v[4:7]
	v_mfma_f32_16x16x32_bf16 v[32:35], v[134:137], v[166:169], v[0:3]
	v_mfma_f32_16x16x32_bf16 v[20:23], v[208:211], v[184:187], v[138:141]
	v_mfma_f32_16x16x32_bf16 v[16:19], v[134:137], v[184:187], v[142:145]
	v_mfma_f32_16x16x32_bf16 v[4:7], v[208:211], v[130:133], v[146:149]
	v_mfma_f32_16x16x32_bf16 v[0:3], v[134:137], v[130:133], v[150:153]
	v_cmp_gt_u32_e32 vcc, s46, v128
	s_barrier
	s_and_saveexec_b64 s[6:7], vcc
	s_cbranch_execz .LBB0_294
	s_barrier

; #define STAGE(P, RS, SOFF, OFF, kt) do { const int _so = (SOFF) + (kt) * (BK * 2); \
;     _Pragma("unroll") for (int _i = 0; _i < 2; ++_i) { \
;       __builtin_amdgcn_raw_ptr_buffer_load_lds(RS, (__attribute__((address_space(3))) void*)((P) + wave * 1024 + _i * 8192), 16, OFF[_i], _so, 0, 0); } } while (0)
; #define LDA(dst, b, h) _Pragma("unroll") for (int m = 0; m < 4; ++m) _Pragma("unroll") for (int k = 0; k < 2; ++k) \
;     dst[m][k] = *reinterpret_cast<const bf16x8*>(SA(b, h) + lds_byte(wr * 64 + m * 16 + fr, k * 32 + fq * 8))
; #define LDB(dst, b, h) _Pragma("unroll") for (int n = 0; n < 2; ++n) _Pragma("unroll") for (int k = 0; k < 2; ++k) \
;     dst[n][k] = *reinterpret_cast<const bf16x8*>(SB(b, h) + lds_byte(wc * 32 + n * 16 + fr, k * 32 + fq * 8))
; #define WAIT_V(n) asm volatile("s_waitcnt vmcnt(" #n ")" ::: "memory")
; #define WAIT_L(n) asm volatile("s_waitcnt lgkmcnt(" #n ")" ::: "memory")
; #define BAR __builtin_amdgcn_s_barrier()
; #define SCHED __builtin_amdgcn_sched_barrier(0)
;     ...
;     const int tid = opaque_tid(wave);
;     const int wid = tid >> 6, lane = tid & 63, wr = wid >> 2, wc = wid & 3, fr = lane & 15, fq = lane >> 4;
;     int offA[2], offB[2];
;     _Pragma("unroll") for (int i = 0; i < 2; ++i) {
;       int r, c; stage_rc(tid * 16 + i * 8192, r, c);
;       offA[i] = (r * lda + c) * 2; offB[i] = (r * ldb + c) * 2;
;     }
;     const int brow = pm * BM;
;     f32x4 acc[2][2][4][2];
;     _Pragma("unroll") for (int a = 0; a < 2; ++a) _Pragma("unroll") for (int b = 0; b < 2; ++b) _Pragma("unroll") for (int m = 0; m < 4; ++m) _Pragma("unroll") for (int n = 0; n < 2; ++n)
;       acc[a][b][m][n] = f32x4{0.f, 0.f, 0.f, 0.f};
;     bf16x8 At[4][2], B0[2][2], B1[2][2];
;     if (wr == 1) BAR;
;     if (first_tile) { WAIT_V(0); }
;     else if constexpr (mode == MODE_RESID_LN) { WAIT_V(0); }
;     else if constexpr (mode == MODE_SWIGLU) { WAIT_V(6); }
;     else if constexpr (mode == MODE_V) { WAIT_V(24); }
;     else { WAIT_V(12); }
;     first_tile = false;
;     BAR;
;     BAR;
;     for (int t = 0; t < nt - 2; t += 2) {
;       LDB(B0, 0, 0); SCHED; LDA(At, 0, 0); STAGE(SA(1, 1), rsA, sA1, offA, t + 1);
;       WAIT_L(8); BAR; WAIT_L(0); MMA(0, 0, At, B0); BAR; SCHED;
;       LDB(B1, 0, 1); STAGE(SB(0, 0), rsB, sB0, offB, t + 2);
.LBB0_353:
	v_bfe_i32 v4, v130, 27, 1
	v_lshlrev_b32_e32 v2, 4, v130
	v_lshrrev_b32_e32 v4, 22, v4
	v_add_u32_e32 v4, v2, v4
	v_and_b32_e32 v4, 0xfffffc00, v4
	v_sub_u32_e32 v4, v2, v4
	v_lshrrev_b32_e32 v5, 4, v4
	v_bitop3_b32 v4, v5, v4, 32 bitop3:0x6c
	v_ashrrev_i32_e32 v3, 31, v130
	v_ashrrev_i32_e32 v6, 31, v4
	v_lshrrev_b32_e32 v3, 26, v3
	v_lshrrev_b32_e32 v6, 26, v6
	v_add_u32_e32 v3, v130, v3
	v_add_u32_e32 v6, v4, v6
	v_ashrrev_i32_e32 v3, 6, v3
	v_lshrrev_b32_e32 v7, 6, v6
	v_and_b32_e32 v6, 0xc0, v6
	v_lshlrev_b32_e32 v5, 3, v3
	v_lshlrev_b32_e32 v3, 5, v3
	v_sub_u32_e32 v4, v4, v6
	v_and_b32_e32 v5, 0xffff0, v5
	v_and_b32_e32 v3, 32, v3
	v_ashrrev_i16_sdwa v4, v128, sext(v4) dst_sel:DWORD dst_unused:UNUSED_PAD src0_sel:DWORD src1_sel:BYTE_0
	v_add_u32_sdwa v3, v3, sext(v4) dst_sel:DWORD dst_unused:UNUSED_PAD src0_sel:DWORD src1_sel:WORD_0
	v_add_lshl_u32 v4, v7, v5, 12
	v_add_u32_e32 v2, 0x2000, v2
	v_lshl_add_u32 v143, v3, 1, v4
	v_ashrrev_i32_e32 v3, 31, v2
	v_lshrrev_b32_e32 v3, 22, v3
	v_add_u32_e32 v3, v2, v3
	v_ashrrev_i32_e32 v3, 10, v3
	v_mul_i32_i24_e32 v4, 0x400, v3
	v_sub_u32_e32 v2, v2, v4
	v_lshrrev_b32_e32 v4, 4, v2
	v_bitop3_b32 v2, v4, v2, 32 bitop3:0x6c
	v_ashrrev_i32_e32 v5, 31, v2
	v_lshrrev_b32_e32 v5, 26, v5
	v_add_u32_e32 v5, v2, v5
	v_lshrrev_b32_e32 v6, 6, v5
	v_and_b32_e32 v5, 0xc0, v5
	v_lshlrev_b32_e32 v4, 3, v3
	v_lshlrev_b32_e32 v3, 5, v3
	v_sub_u32_e32 v2, v2, v5
	v_and_b32_e32 v4, 0xffff0, v4
	v_and_b32_e32 v3, 32, v3
	v_ashrrev_i16_sdwa v2, v128, sext(v2) dst_sel:DWORD dst_unused:UNUSED_PAD src0_sel:DWORD src1_sel:BYTE_0
	v_add_u32_sdwa v2, v3, sext(v2) dst_sel:DWORD dst_unused:UNUSED_PAD src0_sel:DWORD src1_sel:WORD_0
	v_add_lshl_u32 v3, v6, v4, 12
	v_lshl_add_u32 v144, v2, 1, v3
	v_and_b32_e32 v3, 15, v0
	v_lshlrev_b32_e32 v5, 2, v0
	v_and_b32_e32 v2, 48, v0
	v_lshlrev_b32_e32 v3, 6, v3
	v_and_b32_e32 v5, 32, v5
	v_lshlrev_b32_e32 v0, 6, v0
	v_or_b32_e32 v4, v3, v2
	v_bitop3_b32 v3, v3, v5, v2 bitop3:0x36
	v_lshlrev_b32_e32 v6, 6, v130
	v_lshlrev_b32_e32 v1, 13, v1
	v_and_or_b32 v0, v0, s34, v2
	v_and_or_b32 v3, v6, s33, v3
	v_bitop3_b32 v0, v1, v0, v5 bitop3:0xf6
	v_or_b32_e32 v6, 0x400, v3
	v_or_b32_e32 v7, 0x800, v3
	v_or_b32_e32 v8, 0xc00, v3
	v_or_b32_e32 v134, 0x800, v0
	v_or_b32_e32 v133, 0x1000, v0
	v_or_b32_e32 v132, 0x1800, v0
	v_mov_b32_e32 v0, 0
	v_bitop3_b32 v131, v4, v1, v5 bitop3:0xde
	s_mov_b32 s16, -2
	s_mov_b32 s17, 0
	v_or_b32_e32 v149, 0x10000, v3
	v_or_b32_e32 v150, 0x10000, v6
	v_or_b32_e32 v151, 0x10000, v7
	v_or_b32_e32 v152, 0x10000, v8
	v_or_b32_e32 v145, 0x14000, v3
	v_or_b32_e32 v146, 0x14000, v6
	v_or_b32_e32 v147, 0x14000, v7
	v_or_b32_e32 v148, 0x14000, v8
	v_or_b32_e32 v139, 0x18000, v3
	v_or_b32_e32 v140, 0x18000, v6
	v_or_b32_e32 v141, 0x18000, v7
	v_or_b32_e32 v142, 0x18000, v8
	v_or_b32_e32 v135, 0x1c000, v3
	v_or_b32_e32 v136, 0x1c000, v6
	v_or_b32_e32 v137, 0x1c000, v7
	v_or_b32_e32 v138, 0x1c000, v8
	s_barrier
	s_barrier
	ds_read_b128 v[154:157], v149
	ds_read_b128 v[158:161], v150
	ds_read_b128 v[162:165], v151
	ds_read_b128 v[166:169], v152
	s_add_i32 s43, s37, s17
	s_add_i32 s10, s43, 0x80
	s_mov_b32 m0, s30
	ds_read_b128 v[170:173], v131
	ds_read_b128 v[174:177], v131 offset:1024
	ds_read_b128 v[178:181], v134
	ds_read_b128 v[182:185], v134 offset:1024
	ds_read_b128 v[186:189], v133
	ds_read_b128 v[190:193], v133 offset:1024
	ds_read_b128 v[194:197], v132
	ds_read_b128 v[198:201], v132 offset:1024
	buffer_load_dwordx4 v143, s[4:7], s10 offen lds
	s_mov_b32 m0, s31
	s_nop 0
	buffer_load_dwordx4 v144, s[4:7], s10 offen lds
	s_waitcnt lgkmcnt(8)
	s_barrier
	s_waitcnt lgkmcnt(0)
	v_mfma_f32_16x16x32_bf16 v[124:127], v[154:157], v[170:173], 0
	v_mfma_f32_16x16x32_bf16 v[124:127], v[158:161], v[174:177], v[124:127]
	v_mfma_f32_16x16x32_bf16 v[120:123], v[166:169], v[174:177], 0
	v_mfma_f32_16x16x32_bf16 v[120:123], v[162:165], v[170:173], v[120:123]
	v_mfma_f32_16x16x32_bf16 v[112:115], v[162:165], v[178:181], 0
	v_mfma_f32_16x16x32_bf16 v[112:115], v[166:169], v[182:185], v[112:115]
	v_mfma_f32_16x16x32_bf16 v[116:119], v[158:161], v[182:185], 0
	v_mfma_f32_16x16x32_bf16 v[116:119], v[154:157], v[178:181], v[116:119]
	v_mfma_f32_16x16x32_bf16 v[108:111], v[154:157], v[186:189], 0
	v_mfma_f32_16x16x32_bf16 v[108:111], v[158:161], v[190:193], v[108:111]
	v_mfma_f32_16x16x32_bf16 v[104:107], v[166:169], v[190:193], 0
	v_mfma_f32_16x16x32_bf16 v[104:107], v[162:165], v[186:189], v[104:107]
	v_mfma_f32_16x16x32_bf16 v[96:99], v[162:165], v[194:197], 0
	v_mfma_f32_16x16x32_bf16 v[96:99], v[166:169], v[198:201], v[96:99]
	v_mfma_f32_16x16x32_bf16 v[100:103], v[158:161], v[198:201], 0
	v_mfma_f32_16x16x32_bf16 v[100:103], v[154:157], v[194:197], v[100:103]
	s_barrier
	s_add_i32 s44, s39, s17
	s_add_i32 s45, s44, 0x100
	s_mov_b32 s10, s6
	s_mov_b32 s11, s7
	s_mov_b32 m0, s1
	ds_read_b128 v[202:205], v145
	ds_read_b128 v[206:209], v146
	ds_read_b128 v[210:213], v147
	ds_read_b128 v[214:217], v148
	buffer_load_dwordx4 v143, s[8:11], s45 offen lds
	s_mov_b32 m0, s3
	s_nop 0
	buffer_load_dwordx4 v144, s[8:11], s45 offen lds
	s_barrier
; #define STAGE(P, RS, SOFF, OFF, kt) do { const int _so = (SOFF) + (kt) * (BK * 2); \
;     _Pragma("unroll") for (int _i = 0; _i < 2; ++_i) { \
;       __builtin_amdgcn_raw_ptr_buffer_load_lds(RS, (__attribute__((address_space(3))) void*)((P) + wave * 1024 + _i * 8192), 16, OFF[_i], _so, 0, 0); } } while (0)
; #define LDA(dst, b, h) _Pragma("unroll") for (int m = 0; m < 4; ++m) _Pragma("unroll") for (int k = 0; k < 2; ++k) \
;     dst[m][k] = *reinterpret_cast<const bf16x8*>(SA(b, h) + lds_byte(wr * 64 + m * 16 + fr, k * 32 + fq * 8))
; #define LDB(dst, b, h) _Pragma("unroll") for (int n = 0; n < 2; ++n) _Pragma("unroll") for (int k = 0; k < 2; ++k) \
;     dst[n][k] = *reinterpret_cast<const bf16x8*>(SB(b, h) + lds_byte(wc * 32 + n * 16 + fr, k * 32 + fq * 8))
; #define WAIT_V(n) asm volatile("s_waitcnt vmcnt(" #n ")" ::: "memory")
; #define WAIT_L(n) asm volatile("s_waitcnt lgkmcnt(" #n ")" ::: "memory")
; #define BAR __builtin_amdgcn_s_barrier()
; #define SCHED __builtin_amdgcn_sched_barrier(0)
;     ...
;       LDB(B1, 0, 1); STAGE(SB(0, 0), rsB, sB0, offB, t + 2);
;       BAR; WAIT_L(0); MMA(0, 1, At, B1); BAR;
;       LDA(At, 0, 1); STAGE(SA(0, 0), rsA, sA0, offA, t + 2);
;       BAR; WAIT_L(0); MMA(1, 0, At, B0); BAR; SCHED;
;       STAGE(SB(0, 1), rsB, sB1, offB, t + 2);
;       WAIT_V(6); BAR; MMA(1, 1, At, B1); BAR;
;       LDB(B0, 1, 0); SCHED; LDA(At, 1, 0); STAGE(SA(0, 1), rsA, sA1, offA, t + 2);
;       WAIT_L(8); BAR; WAIT_L(0); MMA(0, 0, At, B0); BAR; SCHED;
	s_waitcnt lgkmcnt(2)
	v_mfma_f32_16x16x32_bf16 v[92:95], v[202:205], v[170:173], 0
	v_mfma_f32_16x16x32_bf16 v[92:95], v[206:209], v[174:177], v[92:95]
	s_waitcnt lgkmcnt(0)
	v_mfma_f32_16x16x32_bf16 v[88:91], v[214:217], v[174:177], 0
	v_mfma_f32_16x16x32_bf16 v[88:91], v[210:213], v[170:173], v[88:91]
	v_mfma_f32_16x16x32_bf16 v[80:83], v[210:213], v[178:181], 0
	v_mfma_f32_16x16x32_bf16 v[80:83], v[214:217], v[182:185], v[80:83]
	v_mfma_f32_16x16x32_bf16 v[84:87], v[206:209], v[182:185], 0
	v_mfma_f32_16x16x32_bf16 v[84:87], v[202:205], v[178:181], v[84:87]
	v_mfma_f32_16x16x32_bf16 v[76:79], v[202:205], v[186:189], 0
	v_mfma_f32_16x16x32_bf16 v[76:79], v[206:209], v[190:193], v[76:79]
	v_mfma_f32_16x16x32_bf16 v[72:75], v[214:217], v[190:193], 0
	v_mfma_f32_16x16x32_bf16 v[72:75], v[210:213], v[186:189], v[72:75]
	v_mfma_f32_16x16x32_bf16 v[64:67], v[210:213], v[194:197], 0
	v_mfma_f32_16x16x32_bf16 v[64:67], v[214:217], v[198:201], v[64:67]
	v_mfma_f32_16x16x32_bf16 v[68:71], v[206:209], v[198:201], 0
	v_mfma_f32_16x16x32_bf16 v[68:71], v[202:205], v[194:197], v[68:71]
	s_barrier
	s_add_i32 s45, s38, s17
	s_add_i32 s46, s45, 0x100
	s_mov_b32 m0, s0
	ds_read_b128 v[170:173], v131 offset:16384
	ds_read_b128 v[174:177], v131 offset:17408
	ds_read_b128 v[178:181], v134 offset:16384
	ds_read_b128 v[182:185], v134 offset:17408
	ds_read_b128 v[186:189], v133 offset:16384
	ds_read_b128 v[190:193], v133 offset:17408
	ds_read_b128 v[194:197], v132 offset:16384
	ds_read_b128 v[198:201], v132 offset:17408
	buffer_load_dwordx4 v143, s[4:7], s46 offen lds
	s_mov_b32 m0, s18
	s_nop 0
	buffer_load_dwordx4 v144, s[4:7], s46 offen lds
	s_barrier
	s_waitcnt lgkmcnt(6)
	v_mfma_f32_16x16x32_bf16 v[60:63], v[154:157], v[170:173], 0
	v_mfma_f32_16x16x32_bf16 v[60:63], v[158:161], v[174:177], v[60:63]
	v_mfma_f32_16x16x32_bf16 v[56:59], v[166:169], v[174:177], 0
	v_mfma_f32_16x16x32_bf16 v[56:59], v[162:165], v[170:173], v[56:59]
	s_waitcnt lgkmcnt(4)
	v_mfma_f32_16x16x32_bf16 v[48:51], v[162:165], v[178:181], 0
	v_mfma_f32_16x16x32_bf16 v[48:51], v[166:169], v[182:185], v[48:51]
	v_mfma_f32_16x16x32_bf16 v[52:55], v[158:161], v[182:185], 0
	v_mfma_f32_16x16x32_bf16 v[52:55], v[154:157], v[178:181], v[52:55]
	s_waitcnt lgkmcnt(2)
	v_mfma_f32_16x16x32_bf16 v[44:47], v[154:157], v[186:189], 0
	v_mfma_f32_16x16x32_bf16 v[44:47], v[158:161], v[190:193], v[44:47]
	v_mfma_f32_16x16x32_bf16 v[40:43], v[166:169], v[190:193], 0
	v_mfma_f32_16x16x32_bf16 v[40:43], v[162:165], v[186:189], v[40:43]
	s_waitcnt lgkmcnt(0)
	v_mfma_f32_16x16x32_bf16 v[32:35], v[162:165], v[194:197], 0
	v_mfma_f32_16x16x32_bf16 v[32:35], v[166:169], v[198:201], v[32:35]
	v_mfma_f32_16x16x32_bf16 v[36:39], v[158:161], v[198:201], 0
	v_mfma_f32_16x16x32_bf16 v[36:39], v[154:157], v[194:197], v[36:39]
	s_barrier
	s_add_i32 s46, s40, s17
	s_add_i32 s47, s46, 0x100
	s_mov_b32 m0, s19
	s_nop 0
	buffer_load_dwordx4 v143, s[8:11], s47 offen lds
	s_mov_b32 m0, s20
	s_nop 0
	buffer_load_dwordx4 v144, s[8:11], s47 offen lds
	s_waitcnt vmcnt(6)
	s_barrier
	v_mfma_f32_16x16x32_bf16 v[28:31], v[202:205], v[170:173], 0
	v_mfma_f32_16x16x32_bf16 v[28:31], v[206:209], v[174:177], v[28:31]
	v_mfma_f32_16x16x32_bf16 v[24:27], v[214:217], v[174:177], 0
	v_mfma_f32_16x16x32_bf16 v[24:27], v[210:213], v[170:173], v[24:27]
	v_mfma_f32_16x16x32_bf16 v[16:19], v[210:213], v[178:181], 0
	v_mfma_f32_16x16x32_bf16 v[16:19], v[214:217], v[182:185], v[16:19]
	v_mfma_f32_16x16x32_bf16 v[20:23], v[206:209], v[182:185], 0
	v_mfma_f32_16x16x32_bf16 v[20:23], v[202:205], v[178:181], v[20:23]
	v_mfma_f32_16x16x32_bf16 v[12:15], v[202:205], v[186:189], 0
	v_mfma_f32_16x16x32_bf16 v[12:15], v[206:209], v[190:193], v[12:15]
	v_mfma_f32_16x16x32_bf16 v[8:11], v[214:217], v[190:193], 0
	v_mfma_f32_16x16x32_bf16 v[8:11], v[210:213], v[186:189], v[8:11]
	v_mfma_f32_16x16x32_bf16 v[0:3], v[210:213], v[194:197], 0
	v_mfma_f32_16x16x32_bf16 v[0:3], v[214:217], v[198:201], v[0:3]
	v_mfma_f32_16x16x32_bf16 v[4:7], v[206:209], v[198:201], 0
	v_mfma_f32_16x16x32_bf16 v[4:7], v[202:205], v[194:197], v[4:7]
	s_barrier
	ds_read_b128 v[154:157], v139
	ds_read_b128 v[158:161], v140
	ds_read_b128 v[162:165], v141
	ds_read_b128 v[166:169], v142
	s_addk_i32 s43, 0x100
	s_mov_b32 m0, s21
	ds_read_b128 v[170:173], v131 offset:32768
	ds_read_b128 v[174:177], v131 offset:33792
	ds_read_b128 v[178:181], v134 offset:32768
	ds_read_b128 v[182:185], v134 offset:33792
	ds_read_b128 v[186:189], v133 offset:32768
	ds_read_b128 v[190:193], v133 offset:33792
	ds_read_b128 v[194:197], v132 offset:32768
	ds_read_b128 v[198:201], v132 offset:33792
	buffer_load_dwordx4 v143, s[4:7], s43 offen lds
	s_mov_b32 m0, s22
	s_nop 0
	buffer_load_dwordx4 v144, s[4:7], s43 offen lds
	s_waitcnt lgkmcnt(8)
	s_barrier
; #define STAGE(P, RS, SOFF, OFF, kt) do { const int _so = (SOFF) + (kt) * (BK * 2); \
;     _Pragma("unroll") for (int _i = 0; _i < 2; ++_i) { \
;       __builtin_amdgcn_raw_ptr_buffer_load_lds(RS, (__attribute__((address_space(3))) void*)((P) + wave * 1024 + _i * 8192), 16, OFF[_i], _so, 0, 0); } } while (0)
; #define LDA(dst, b, h) _Pragma("unroll") for (int m = 0; m < 4; ++m) _Pragma("unroll") for (int k = 0; k < 2; ++k) \
;     dst[m][k] = *reinterpret_cast<const bf16x8*>(SA(b, h) + lds_byte(wr * 64 + m * 16 + fr, k * 32 + fq * 8))
; #define LDB(dst, b, h) _Pragma("unroll") for (int n = 0; n < 2; ++n) _Pragma("unroll") for (int k = 0; k < 2; ++k) \
;     dst[n][k] = *reinterpret_cast<const bf16x8*>(SB(b, h) + lds_byte(wc * 32 + n * 16 + fr, k * 32 + fq * 8))
; #define WAIT_V(n) asm volatile("s_waitcnt vmcnt(" #n ")" ::: "memory")
; #define WAIT_L(n) asm volatile("s_waitcnt lgkmcnt(" #n ")" ::: "memory")
; #define BAR __builtin_amdgcn_s_barrier()
; #define SCHED __builtin_amdgcn_sched_barrier(0)
;     ...
;       WAIT_L(8); BAR; WAIT_L(0); MMA(0, 0, At, B0); BAR; SCHED;
;       LDB(B1, 1, 1); STAGE(SB(1, 0), rsB, sB0, offB, t + 3);
;       BAR; WAIT_L(0); MMA(0, 1, At, B1); BAR;
;       LDA(At, 1, 1); STAGE(SA(1, 0), rsA, sA0, offA, t + 3);
;       BAR; WAIT_L(0); MMA(1, 0, At, B0); BAR; SCHED;
;       STAGE(SB(1, 1), rsB, sB1, offB, t + 3);
;       WAIT_V(6); BAR; MMA(1, 1, At, B1); BAR;
	s_waitcnt lgkmcnt(6)
	v_mfma_f32_16x16x32_bf16 v[124:127], v[154:157], v[170:173], v[124:127]
	v_mfma_f32_16x16x32_bf16 v[124:127], v[158:161], v[174:177], v[124:127]
	v_mfma_f32_16x16x32_bf16 v[120:123], v[166:169], v[174:177], v[120:123]
	v_mfma_f32_16x16x32_bf16 v[120:123], v[162:165], v[170:173], v[120:123]
	s_waitcnt lgkmcnt(4)
	v_mfma_f32_16x16x32_bf16 v[112:115], v[162:165], v[178:181], v[112:115]
	v_mfma_f32_16x16x32_bf16 v[112:115], v[166:169], v[182:185], v[112:115]
	v_mfma_f32_16x16x32_bf16 v[116:119], v[158:161], v[182:185], v[116:119]
	v_mfma_f32_16x16x32_bf16 v[116:119], v[154:157], v[178:181], v[116:119]
	s_waitcnt lgkmcnt(2)
	v_mfma_f32_16x16x32_bf16 v[108:111], v[154:157], v[186:189], v[108:111]
	v_mfma_f32_16x16x32_bf16 v[108:111], v[158:161], v[190:193], v[108:111]
	v_mfma_f32_16x16x32_bf16 v[104:107], v[166:169], v[190:193], v[104:107]
	v_mfma_f32_16x16x32_bf16 v[104:107], v[162:165], v[186:189], v[104:107]
	s_waitcnt lgkmcnt(0)
	v_mfma_f32_16x16x32_bf16 v[96:99], v[162:165], v[194:197], v[96:99]
	v_mfma_f32_16x16x32_bf16 v[96:99], v[166:169], v[198:201], v[96:99]
	v_mfma_f32_16x16x32_bf16 v[100:103], v[158:161], v[198:201], v[100:103]
	v_mfma_f32_16x16x32_bf16 v[100:103], v[154:157], v[194:197], v[100:103]
	s_barrier
	s_addk_i32 s44, 0x180
	s_mov_b32 m0, s23
	ds_read_b128 v[202:205], v135
	ds_read_b128 v[206:209], v136
	ds_read_b128 v[210:213], v137
	ds_read_b128 v[214:217], v138
	buffer_load_dwordx4 v143, s[8:11], s44 offen lds
	s_mov_b32 m0, s24
	s_nop 0
	buffer_load_dwordx4 v144, s[8:11], s44 offen lds
	s_barrier
	s_waitcnt lgkmcnt(2)
	v_mfma_f32_16x16x32_bf16 v[92:95], v[202:205], v[170:173], v[92:95]
	v_mfma_f32_16x16x32_bf16 v[92:95], v[206:209], v[174:177], v[92:95]
	s_waitcnt lgkmcnt(0)
	v_mfma_f32_16x16x32_bf16 v[88:91], v[214:217], v[174:177], v[88:91]
	v_mfma_f32_16x16x32_bf16 v[88:91], v[210:213], v[170:173], v[88:91]
	v_mfma_f32_16x16x32_bf16 v[80:83], v[210:213], v[178:181], v[80:83]
	v_mfma_f32_16x16x32_bf16 v[80:83], v[214:217], v[182:185], v[80:83]
	v_mfma_f32_16x16x32_bf16 v[84:87], v[206:209], v[182:185], v[84:87]
	v_mfma_f32_16x16x32_bf16 v[84:87], v[202:205], v[178:181], v[84:87]
	v_mfma_f32_16x16x32_bf16 v[76:79], v[202:205], v[186:189], v[76:79]
	v_mfma_f32_16x16x32_bf16 v[76:79], v[206:209], v[190:193], v[76:79]
	v_mfma_f32_16x16x32_bf16 v[72:75], v[214:217], v[190:193], v[72:75]
	v_mfma_f32_16x16x32_bf16 v[72:75], v[210:213], v[186:189], v[72:75]
	v_mfma_f32_16x16x32_bf16 v[64:67], v[210:213], v[194:197], v[64:67]
	v_mfma_f32_16x16x32_bf16 v[64:67], v[214:217], v[198:201], v[64:67]
	v_mfma_f32_16x16x32_bf16 v[68:71], v[206:209], v[198:201], v[68:71]
	v_mfma_f32_16x16x32_bf16 v[68:71], v[202:205], v[194:197], v[68:71]
	s_barrier
	s_addk_i32 s45, 0x180
	s_mov_b32 m0, s25
	ds_read_b128 v[170:173], v131 offset:49152
	ds_read_b128 v[174:177], v131 offset:50176
	ds_read_b128 v[178:181], v134 offset:49152
	ds_read_b128 v[182:185], v134 offset:50176
	ds_read_b128 v[186:189], v133 offset:49152
	ds_read_b128 v[190:193], v133 offset:50176
	ds_read_b128 v[194:197], v132 offset:49152
	ds_read_b128 v[198:201], v132 offset:50176
	buffer_load_dwordx4 v143, s[4:7], s45 offen lds
	s_mov_b32 m0, s26
	s_nop 0
	buffer_load_dwordx4 v144, s[4:7], s45 offen lds
	s_barrier
	s_waitcnt lgkmcnt(6)
	v_mfma_f32_16x16x32_bf16 v[60:63], v[154:157], v[170:173], v[60:63]
	v_mfma_f32_16x16x32_bf16 v[60:63], v[158:161], v[174:177], v[60:63]
	v_mfma_f32_16x16x32_bf16 v[56:59], v[166:169], v[174:177], v[56:59]
	v_mfma_f32_16x16x32_bf16 v[56:59], v[162:165], v[170:173], v[56:59]
	s_waitcnt lgkmcnt(4)
	v_mfma_f32_16x16x32_bf16 v[48:51], v[162:165], v[178:181], v[48:51]
	v_mfma_f32_16x16x32_bf16 v[48:51], v[166:169], v[182:185], v[48:51]
	v_mfma_f32_16x16x32_bf16 v[52:55], v[158:161], v[182:185], v[52:55]
	v_mfma_f32_16x16x32_bf16 v[52:55], v[154:157], v[178:181], v[52:55]
	s_waitcnt lgkmcnt(2)
	v_mfma_f32_16x16x32_bf16 v[44:47], v[154:157], v[186:189], v[44:47]
	v_mfma_f32_16x16x32_bf16 v[44:47], v[158:161], v[190:193], v[44:47]
	v_mfma_f32_16x16x32_bf16 v[40:43], v[166:169], v[190:193], v[40:43]
	v_mfma_f32_16x16x32_bf16 v[40:43], v[162:165], v[186:189], v[40:43]
	s_waitcnt lgkmcnt(0)
	v_mfma_f32_16x16x32_bf16 v[32:35], v[162:165], v[194:197], v[32:35]
	v_mfma_f32_16x16x32_bf16 v[32:35], v[166:169], v[198:201], v[32:35]
	v_mfma_f32_16x16x32_bf16 v[36:39], v[158:161], v[198:201], v[36:39]
	v_mfma_f32_16x16x32_bf16 v[36:39], v[154:157], v[194:197], v[36:39]
	s_barrier
	s_addk_i32 s46, 0x180
	s_mov_b32 m0, s27
	s_nop 0
	buffer_load_dwordx4 v143, s[8:11], s46 offen lds
	s_mov_b32 m0, s28
	s_nop 0
	buffer_load_dwordx4 v144, s[8:11], s46 offen lds
	s_add_i32 s16, s16, 2
	s_addk_i32 s17, 0x100
	s_cmp_gt_u32 s16, 27
	s_cbranch_scc0 .LBB0_354
	s_branch .Lmy_post_354

; #define STAGE(P, RS, SOFF, OFF, kt) do { const int _so = (SOFF) + (kt) * (BK * 2); \
;     _Pragma("unroll") for (int _i = 0; _i < 2; ++_i) { \
;       __builtin_amdgcn_raw_ptr_buffer_load_lds(RS, (__attribute__((address_space(3))) void*)((P) + wave * 1024 + _i * 8192), 16, OFF[_i], _so, 0, 0); } } while (0)
; #define LDA(dst, b, h) _Pragma("unroll") for (int m = 0; m < 4; ++m) _Pragma("unroll") for (int k = 0; k < 2; ++k) \
;     dst[m][k] = *reinterpret_cast<const bf16x8*>(SA(b, h) + lds_byte(wr * 64 + m * 16 + fr, k * 32 + fq * 8))
; #define LDB(dst, b, h) _Pragma("unroll") for (int n = 0; n < 2; ++n) _Pragma("unroll") for (int k = 0; k < 2; ++k) \
;     dst[n][k] = *reinterpret_cast<const bf16x8*>(SB(b, h) + lds_byte(wc * 32 + n * 16 + fr, k * 32 + fq * 8))
; #define WAIT_V(n) asm volatile("s_waitcnt vmcnt(" #n ")" ::: "memory")
; #define WAIT_L(n) asm volatile("s_waitcnt lgkmcnt(" #n ")" ::: "memory")
; #define BAR __builtin_amdgcn_s_barrier()
; #define SCHED __builtin_amdgcn_sched_barrier(0)
;     ...
;       LDB(B0, 0, 0); SCHED; LDA(At, 0, 0); STAGE(SA(1, 1), rsA, sA1, offA, t + 1);
;       WAIT_L(8); BAR; WAIT_L(0); MMA(0, 0, At, B0); BAR; SCHED;
;       LDB(B1, 0, 1); STAGE(SB(0, 0), rsB, sB0, offB, t + 2);
;       BAR; WAIT_L(0); MMA(0, 1, At, B1); BAR;
;       LDA(At, 0, 1); STAGE(SA(0, 0), rsA, sA0, offA, t + 2);
;       BAR; WAIT_L(0); MMA(1, 0, At, B0); BAR; SCHED;
;       STAGE(SB(0, 1), rsB, sB1, offB, t + 2);
;       WAIT_V(6); BAR; MMA(1, 1, At, B1); BAR;
.Lmy_rot_354:
	ds_read_b128 v[154:157], v149
	ds_read_b128 v[158:161], v150
	ds_read_b128 v[162:165], v151
	ds_read_b128 v[166:169], v152
	s_add_i32 s43, s37, s17
	s_add_i32 s10, s43, 0x80
	s_mov_b32 m0, s30
	ds_read_b128 v[170:173], v131
	ds_read_b128 v[174:177], v131 offset:1024
	ds_read_b128 v[178:181], v134
	ds_read_b128 v[182:185], v134 offset:1024
	ds_read_b128 v[186:189], v133
	ds_read_b128 v[190:193], v133 offset:1024
	ds_read_b128 v[194:197], v132
	ds_read_b128 v[198:201], v132 offset:1024
	buffer_load_dwordx4 v143, s[4:7], s10 offen lds
	s_mov_b32 m0, s31
	s_nop 0
	buffer_load_dwordx4 v144, s[4:7], s10 offen lds
	s_waitcnt lgkmcnt(8)
	s_barrier
	s_waitcnt lgkmcnt(0)
	v_mfma_f32_16x16x32_bf16 v[124:127], v[154:157], v[170:173], v[124:127]
	v_mfma_f32_16x16x32_bf16 v[124:127], v[158:161], v[174:177], v[124:127]
	v_mfma_f32_16x16x32_bf16 v[120:123], v[166:169], v[174:177], v[120:123]
	v_mfma_f32_16x16x32_bf16 v[120:123], v[162:165], v[170:173], v[120:123]
	v_mfma_f32_16x16x32_bf16 v[112:115], v[162:165], v[178:181], v[112:115]
	v_mfma_f32_16x16x32_bf16 v[112:115], v[166:169], v[182:185], v[112:115]
	v_mfma_f32_16x16x32_bf16 v[116:119], v[158:161], v[182:185], v[116:119]
	v_mfma_f32_16x16x32_bf16 v[116:119], v[154:157], v[178:181], v[116:119]
	v_mfma_f32_16x16x32_bf16 v[108:111], v[154:157], v[186:189], v[108:111]
	v_mfma_f32_16x16x32_bf16 v[108:111], v[158:161], v[190:193], v[108:111]
	v_mfma_f32_16x16x32_bf16 v[104:107], v[166:169], v[190:193], v[104:107]
	v_mfma_f32_16x16x32_bf16 v[104:107], v[162:165], v[186:189], v[104:107]
	v_mfma_f32_16x16x32_bf16 v[96:99], v[162:165], v[194:197], v[96:99]
	v_mfma_f32_16x16x32_bf16 v[96:99], v[166:169], v[198:201], v[96:99]
	v_mfma_f32_16x16x32_bf16 v[100:103], v[158:161], v[198:201], v[100:103]
	v_mfma_f32_16x16x32_bf16 v[100:103], v[154:157], v[194:197], v[100:103]
	s_barrier
	s_add_i32 s44, s39, s17
	s_add_i32 s45, s44, 0x100
	s_mov_b32 s10, s6
	s_mov_b32 s11, s7
	s_mov_b32 m0, s1
	ds_read_b128 v[202:205], v145
	ds_read_b128 v[206:209], v146
	ds_read_b128 v[210:213], v147
	ds_read_b128 v[214:217], v148
	buffer_load_dwordx4 v143, s[8:11], s45 offen lds
	s_mov_b32 m0, s3
	s_nop 0
	buffer_load_dwordx4 v144, s[8:11], s45 offen lds
	s_barrier
	s_waitcnt lgkmcnt(2)
	v_mfma_f32_16x16x32_bf16 v[92:95], v[202:205], v[170:173], v[92:95]
	v_mfma_f32_16x16x32_bf16 v[92:95], v[206:209], v[174:177], v[92:95]
	s_waitcnt lgkmcnt(0)
	v_mfma_f32_16x16x32_bf16 v[88:91], v[214:217], v[174:177], v[88:91]
	v_mfma_f32_16x16x32_bf16 v[88:91], v[210:213], v[170:173], v[88:91]
	v_mfma_f32_16x16x32_bf16 v[80:83], v[210:213], v[178:181], v[80:83]
	v_mfma_f32_16x16x32_bf16 v[80:83], v[214:217], v[182:185], v[80:83]
	v_mfma_f32_16x16x32_bf16 v[84:87], v[206:209], v[182:185], v[84:87]
	v_mfma_f32_16x16x32_bf16 v[84:87], v[202:205], v[178:181], v[84:87]
	v_mfma_f32_16x16x32_bf16 v[76:79], v[202:205], v[186:189], v[76:79]
	v_mfma_f32_16x16x32_bf16 v[76:79], v[206:209], v[190:193], v[76:79]
	v_mfma_f32_16x16x32_bf16 v[72:75], v[214:217], v[190:193], v[72:75]
	v_mfma_f32_16x16x32_bf16 v[72:75], v[210:213], v[186:189], v[72:75]
	v_mfma_f32_16x16x32_bf16 v[64:67], v[210:213], v[194:197], v[64:67]
	v_mfma_f32_16x16x32_bf16 v[64:67], v[214:217], v[198:201], v[64:67]
	v_mfma_f32_16x16x32_bf16 v[68:71], v[206:209], v[198:201], v[68:71]
	v_mfma_f32_16x16x32_bf16 v[68:71], v[202:205], v[194:197], v[68:71]
	s_barrier
	s_add_i32 s45, s38, s17
	s_add_i32 s46, s45, 0x100
	s_mov_b32 m0, s0
	ds_read_b128 v[170:173], v131 offset:16384
	ds_read_b128 v[174:177], v131 offset:17408
	ds_read_b128 v[178:181], v134 offset:16384
	ds_read_b128 v[182:185], v134 offset:17408
	ds_read_b128 v[186:189], v133 offset:16384
	ds_read_b128 v[190:193], v133 offset:17408
	ds_read_b128 v[194:197], v132 offset:16384
	ds_read_b128 v[198:201], v132 offset:17408
	buffer_load_dwordx4 v143, s[4:7], s46 offen lds
	s_mov_b32 m0, s18
	s_nop 0
	buffer_load_dwordx4 v144, s[4:7], s46 offen lds
	s_barrier
	s_waitcnt lgkmcnt(6)
	v_mfma_f32_16x16x32_bf16 v[60:63], v[154:157], v[170:173], v[60:63]
	v_mfma_f32_16x16x32_bf16 v[60:63], v[158:161], v[174:177], v[60:63]
	v_mfma_f32_16x16x32_bf16 v[56:59], v[166:169], v[174:177], v[56:59]
	v_mfma_f32_16x16x32_bf16 v[56:59], v[162:165], v[170:173], v[56:59]
	s_waitcnt lgkmcnt(4)
	v_mfma_f32_16x16x32_bf16 v[48:51], v[162:165], v[178:181], v[48:51]
	v_mfma_f32_16x16x32_bf16 v[48:51], v[166:169], v[182:185], v[48:51]
	v_mfma_f32_16x16x32_bf16 v[52:55], v[158:161], v[182:185], v[52:55]
	v_mfma_f32_16x16x32_bf16 v[52:55], v[154:157], v[178:181], v[52:55]
	s_waitcnt lgkmcnt(2)
	v_mfma_f32_16x16x32_bf16 v[44:47], v[154:157], v[186:189], v[44:47]
	v_mfma_f32_16x16x32_bf16 v[44:47], v[158:161], v[190:193], v[44:47]
	v_mfma_f32_16x16x32_bf16 v[40:43], v[166:169], v[190:193], v[40:43]
	v_mfma_f32_16x16x32_bf16 v[40:43], v[162:165], v[186:189], v[40:43]
	s_waitcnt lgkmcnt(0)
	v_mfma_f32_16x16x32_bf16 v[32:35], v[162:165], v[194:197], v[32:35]
	v_mfma_f32_16x16x32_bf16 v[32:35], v[166:169], v[198:201], v[32:35]
	v_mfma_f32_16x16x32_bf16 v[36:39], v[158:161], v[198:201], v[36:39]
	v_mfma_f32_16x16x32_bf16 v[36:39], v[154:157], v[194:197], v[36:39]
	s_barrier
	s_add_i32 s46, s40, s17
	s_add_i32 s47, s46, 0x100
	s_mov_b32 m0, s19
	s_nop 0
	buffer_load_dwordx4 v143, s[8:11], s47 offen lds
	s_mov_b32 m0, s20
	s_nop 0
	buffer_load_dwordx4 v144, s[8:11], s47 offen lds
	s_waitcnt vmcnt(6)
	s_barrier
; #define STAGE(P, RS, SOFF, OFF, kt) do { const int _so = (SOFF) + (kt) * (BK * 2); \
;     _Pragma("unroll") for (int _i = 0; _i < 2; ++_i) { \
;       __builtin_amdgcn_raw_ptr_buffer_load_lds(RS, (__attribute__((address_space(3))) void*)((P) + wave * 1024 + _i * 8192), 16, OFF[_i], _so, 0, 0); } } while (0)
; #define LDA(dst, b, h) _Pragma("unroll") for (int m = 0; m < 4; ++m) _Pragma("unroll") for (int k = 0; k < 2; ++k) \
;     dst[m][k] = *reinterpret_cast<const bf16x8*>(SA(b, h) + lds_byte(wr * 64 + m * 16 + fr, k * 32 + fq * 8))
; #define LDB(dst, b, h) _Pragma("unroll") for (int n = 0; n < 2; ++n) _Pragma("unroll") for (int k = 0; k < 2; ++k) \
;     dst[n][k] = *reinterpret_cast<const bf16x8*>(SB(b, h) + lds_byte(wc * 32 + n * 16 + fr, k * 32 + fq * 8))
; #define WAIT_V(n) asm volatile("s_waitcnt vmcnt(" #n ")" ::: "memory")
; #define WAIT_L(n) asm volatile("s_waitcnt lgkmcnt(" #n ")" ::: "memory")
; #define BAR __builtin_amdgcn_s_barrier()
; #define SCHED __builtin_amdgcn_sched_barrier(0)
;     ...
;       WAIT_V(6); BAR; MMA(1, 1, At, B1); BAR;
;       LDB(B0, 1, 0); SCHED; LDA(At, 1, 0); STAGE(SA(0, 1), rsA, sA1, offA, t + 2);
;       WAIT_L(8); BAR; WAIT_L(0); MMA(0, 0, At, B0); BAR; SCHED;
;       LDB(B1, 1, 1); STAGE(SB(1, 0), rsB, sB0, offB, t + 3);
;       BAR; WAIT_L(0); MMA(0, 1, At, B1); BAR;
;       LDA(At, 1, 1); STAGE(SA(1, 0), rsA, sA0, offA, t + 3);
;       BAR; WAIT_L(0); MMA(1, 0, At, B0); BAR; SCHED;
;       STAGE(SB(1, 1), rsB, sB1, offB, t + 3);
;       WAIT_V(6); BAR; MMA(1, 1, At, B1); BAR;
	v_mfma_f32_16x16x32_bf16 v[28:31], v[202:205], v[170:173], v[28:31]
	v_mfma_f32_16x16x32_bf16 v[28:31], v[206:209], v[174:177], v[28:31]
	v_mfma_f32_16x16x32_bf16 v[24:27], v[214:217], v[174:177], v[24:27]
	v_mfma_f32_16x16x32_bf16 v[24:27], v[210:213], v[170:173], v[24:27]
	v_mfma_f32_16x16x32_bf16 v[16:19], v[210:213], v[178:181], v[16:19]
	v_mfma_f32_16x16x32_bf16 v[16:19], v[214:217], v[182:185], v[16:19]
	v_mfma_f32_16x16x32_bf16 v[20:23], v[206:209], v[182:185], v[20:23]
	v_mfma_f32_16x16x32_bf16 v[20:23], v[202:205], v[178:181], v[20:23]
	v_mfma_f32_16x16x32_bf16 v[12:15], v[202:205], v[186:189], v[12:15]
	v_mfma_f32_16x16x32_bf16 v[12:15], v[206:209], v[190:193], v[12:15]
	v_mfma_f32_16x16x32_bf16 v[8:11], v[214:217], v[190:193], v[8:11]
	v_mfma_f32_16x16x32_bf16 v[8:11], v[210:213], v[186:189], v[8:11]
	v_mfma_f32_16x16x32_bf16 v[0:3], v[210:213], v[194:197], v[0:3]
	v_mfma_f32_16x16x32_bf16 v[0:3], v[214:217], v[198:201], v[0:3]
	v_mfma_f32_16x16x32_bf16 v[4:7], v[206:209], v[198:201], v[4:7]
	v_mfma_f32_16x16x32_bf16 v[4:7], v[202:205], v[194:197], v[4:7]
	s_barrier
	ds_read_b128 v[154:157], v139
	ds_read_b128 v[158:161], v140
	ds_read_b128 v[162:165], v141
	ds_read_b128 v[166:169], v142
	s_addk_i32 s43, 0x100
	s_mov_b32 m0, s21
	ds_read_b128 v[170:173], v131 offset:32768
	ds_read_b128 v[174:177], v131 offset:33792
	ds_read_b128 v[178:181], v134 offset:32768
	ds_read_b128 v[182:185], v134 offset:33792
	ds_read_b128 v[186:189], v133 offset:32768
	ds_read_b128 v[190:193], v133 offset:33792
	ds_read_b128 v[194:197], v132 offset:32768
	ds_read_b128 v[198:201], v132 offset:33792
	buffer_load_dwordx4 v143, s[4:7], s43 offen lds
	s_mov_b32 m0, s22
	s_nop 0
	buffer_load_dwordx4 v144, s[4:7], s43 offen lds
	s_waitcnt lgkmcnt(8)
	s_barrier
	s_waitcnt lgkmcnt(6)
	v_mfma_f32_16x16x32_bf16 v[124:127], v[154:157], v[170:173], v[124:127]
	v_mfma_f32_16x16x32_bf16 v[124:127], v[158:161], v[174:177], v[124:127]
	v_mfma_f32_16x16x32_bf16 v[120:123], v[166:169], v[174:177], v[120:123]
	v_mfma_f32_16x16x32_bf16 v[120:123], v[162:165], v[170:173], v[120:123]
	s_waitcnt lgkmcnt(4)
	v_mfma_f32_16x16x32_bf16 v[112:115], v[162:165], v[178:181], v[112:115]
	v_mfma_f32_16x16x32_bf16 v[112:115], v[166:169], v[182:185], v[112:115]
	v_mfma_f32_16x16x32_bf16 v[116:119], v[158:161], v[182:185], v[116:119]
	v_mfma_f32_16x16x32_bf16 v[116:119], v[154:157], v[178:181], v[116:119]
	s_waitcnt lgkmcnt(2)
	v_mfma_f32_16x16x32_bf16 v[108:111], v[154:157], v[186:189], v[108:111]
	v_mfma_f32_16x16x32_bf16 v[108:111], v[158:161], v[190:193], v[108:111]
	v_mfma_f32_16x16x32_bf16 v[104:107], v[166:169], v[190:193], v[104:107]
	v_mfma_f32_16x16x32_bf16 v[104:107], v[162:165], v[186:189], v[104:107]
	s_waitcnt lgkmcnt(0)
	v_mfma_f32_16x16x32_bf16 v[96:99], v[162:165], v[194:197], v[96:99]
	v_mfma_f32_16x16x32_bf16 v[96:99], v[166:169], v[198:201], v[96:99]
	v_mfma_f32_16x16x32_bf16 v[100:103], v[158:161], v[198:201], v[100:103]
	v_mfma_f32_16x16x32_bf16 v[100:103], v[154:157], v[194:197], v[100:103]
	s_barrier
	s_addk_i32 s44, 0x180
	s_mov_b32 m0, s23
	ds_read_b128 v[202:205], v135
	ds_read_b128 v[206:209], v136
	ds_read_b128 v[210:213], v137
	ds_read_b128 v[214:217], v138
	buffer_load_dwordx4 v143, s[8:11], s44 offen lds
	s_mov_b32 m0, s24
	s_nop 0
	buffer_load_dwordx4 v144, s[8:11], s44 offen lds
	s_barrier
	s_waitcnt lgkmcnt(2)
	v_mfma_f32_16x16x32_bf16 v[92:95], v[202:205], v[170:173], v[92:95]
	v_mfma_f32_16x16x32_bf16 v[92:95], v[206:209], v[174:177], v[92:95]
	s_waitcnt lgkmcnt(0)
	v_mfma_f32_16x16x32_bf16 v[88:91], v[214:217], v[174:177], v[88:91]
	v_mfma_f32_16x16x32_bf16 v[88:91], v[210:213], v[170:173], v[88:91]
	v_mfma_f32_16x16x32_bf16 v[80:83], v[210:213], v[178:181], v[80:83]
	v_mfma_f32_16x16x32_bf16 v[80:83], v[214:217], v[182:185], v[80:83]
	v_mfma_f32_16x16x32_bf16 v[84:87], v[206:209], v[182:185], v[84:87]
	v_mfma_f32_16x16x32_bf16 v[84:87], v[202:205], v[178:181], v[84:87]
	v_mfma_f32_16x16x32_bf16 v[76:79], v[202:205], v[186:189], v[76:79]
	v_mfma_f32_16x16x32_bf16 v[76:79], v[206:209], v[190:193], v[76:79]
	v_mfma_f32_16x16x32_bf16 v[72:75], v[214:217], v[190:193], v[72:75]
	v_mfma_f32_16x16x32_bf16 v[72:75], v[210:213], v[186:189], v[72:75]
	v_mfma_f32_16x16x32_bf16 v[64:67], v[210:213], v[194:197], v[64:67]
	v_mfma_f32_16x16x32_bf16 v[64:67], v[214:217], v[198:201], v[64:67]
	v_mfma_f32_16x16x32_bf16 v[68:71], v[206:209], v[198:201], v[68:71]
	v_mfma_f32_16x16x32_bf16 v[68:71], v[202:205], v[194:197], v[68:71]
	s_barrier
	s_addk_i32 s45, 0x180
	s_mov_b32 m0, s25
	ds_read_b128 v[170:173], v131 offset:49152
	ds_read_b128 v[174:177], v131 offset:50176
	ds_read_b128 v[178:181], v134 offset:49152
	ds_read_b128 v[182:185], v134 offset:50176
	ds_read_b128 v[186:189], v133 offset:49152
	ds_read_b128 v[190:193], v133 offset:50176
	ds_read_b128 v[194:197], v132 offset:49152
	ds_read_b128 v[198:201], v132 offset:50176
	buffer_load_dwordx4 v143, s[4:7], s45 offen lds
	s_mov_b32 m0, s26
	s_nop 0
	buffer_load_dwordx4 v144, s[4:7], s45 offen lds
	s_barrier
	s_waitcnt lgkmcnt(6)
	v_mfma_f32_16x16x32_bf16 v[60:63], v[154:157], v[170:173], v[60:63]
	v_mfma_f32_16x16x32_bf16 v[60:63], v[158:161], v[174:177], v[60:63]
	v_mfma_f32_16x16x32_bf16 v[56:59], v[166:169], v[174:177], v[56:59]
	v_mfma_f32_16x16x32_bf16 v[56:59], v[162:165], v[170:173], v[56:59]
	s_waitcnt lgkmcnt(4)
	v_mfma_f32_16x16x32_bf16 v[48:51], v[162:165], v[178:181], v[48:51]
	v_mfma_f32_16x16x32_bf16 v[48:51], v[166:169], v[182:185], v[48:51]
	v_mfma_f32_16x16x32_bf16 v[52:55], v[158:161], v[182:185], v[52:55]
	v_mfma_f32_16x16x32_bf16 v[52:55], v[154:157], v[178:181], v[52:55]
	s_waitcnt lgkmcnt(2)
	v_mfma_f32_16x16x32_bf16 v[44:47], v[154:157], v[186:189], v[44:47]
	v_mfma_f32_16x16x32_bf16 v[44:47], v[158:161], v[190:193], v[44:47]
	v_mfma_f32_16x16x32_bf16 v[40:43], v[166:169], v[190:193], v[40:43]
	v_mfma_f32_16x16x32_bf16 v[40:43], v[162:165], v[186:189], v[40:43]
	s_waitcnt lgkmcnt(0)
	v_mfma_f32_16x16x32_bf16 v[32:35], v[162:165], v[194:197], v[32:35]
	v_mfma_f32_16x16x32_bf16 v[32:35], v[166:169], v[198:201], v[32:35]
	v_mfma_f32_16x16x32_bf16 v[36:39], v[158:161], v[198:201], v[36:39]
	v_mfma_f32_16x16x32_bf16 v[36:39], v[154:157], v[194:197], v[36:39]
	s_barrier
	s_addk_i32 s46, 0x180
	s_mov_b32 m0, s27
	s_nop 0
	buffer_load_dwordx4 v143, s[8:11], s46 offen lds
	s_mov_b32 m0, s28
	s_nop 0
	buffer_load_dwordx4 v144, s[8:11], s46 offen lds
	s_add_i32 s16, s16, 2
	s_addk_i32 s17, 0x100
	s_cmp_gt_u32 s16, 27
	s_cbranch_scc0 .LBB0_354

; #define STAGE(P, RS, SOFF, OFF, kt) do { const int _so = (SOFF) + (kt) * (BK * 2); \
;     _Pragma("unroll") for (int _i = 0; _i < 2; ++_i) { \
;       __builtin_amdgcn_raw_ptr_buffer_load_lds(RS, (__attribute__((address_space(3))) void*)((P) + wave * 1024 + _i * 8192), 16, OFF[_i], _so, 0, 0); } } while (0)
; #define LDA(dst, b, h) _Pragma("unroll") for (int m = 0; m < 4; ++m) _Pragma("unroll") for (int k = 0; k < 2; ++k) \
;     dst[m][k] = *reinterpret_cast<const bf16x8*>(SA(b, h) + lds_byte(wr * 64 + m * 16 + fr, k * 32 + fq * 8))
; #define LDB(dst, b, h) _Pragma("unroll") for (int n = 0; n < 2; ++n) _Pragma("unroll") for (int k = 0; k < 2; ++k) \
;     dst[n][k] = *reinterpret_cast<const bf16x8*>(SB(b, h) + lds_byte(wc * 32 + n * 16 + fr, k * 32 + fq * 8))
; #define WAIT_V(n) asm volatile("s_waitcnt vmcnt(" #n ")" ::: "memory")
; #define WAIT_L(n) asm volatile("s_waitcnt lgkmcnt(" #n ")" ::: "memory")
; #define BAR __builtin_amdgcn_s_barrier()
; #define SCHED __builtin_amdgcn_sched_barrier(0)
;     ...
;     const int tid = opaque_tid(wave);
;     const int wid = tid >> 6, lane = tid & 63, wr = wid >> 2, wc = wid & 3, fr = lane & 15, fq = lane >> 4;
;     int offA[2], offB[2];
;     _Pragma("unroll") for (int i = 0; i < 2; ++i) {
;       int r, c; stage_rc(tid * 16 + i * 8192, r, c);
;       offA[i] = (r * lda + c) * 2; offB[i] = (r * ldb + c) * 2;
;     }
;     const int brow = pm * BM;
;     f32x4 acc[2][2][4][2];
;     _Pragma("unroll") for (int a = 0; a < 2; ++a) _Pragma("unroll") for (int b = 0; b < 2; ++b) _Pragma("unroll") for (int m = 0; m < 4; ++m) _Pragma("unroll") for (int n = 0; n < 2; ++n)
;       acc[a][b][m][n] = f32x4{0.f, 0.f, 0.f, 0.f};
;     bf16x8 At[4][2], B0[2][2], B1[2][2];
;     if (wr == 1) BAR;
;     if (first_tile) { WAIT_V(0); }
;     else if constexpr (mode == MODE_RESID_LN) { WAIT_V(0); }
;     else if constexpr (mode == MODE_SWIGLU) { WAIT_V(6); }
;     else if constexpr (mode == MODE_V) { WAIT_V(24); }
;     else { WAIT_V(12); }
;     first_tile = false;
;     BAR;
;     BAR;
;     for (int t = 0; t < nt - 2; t += 2) {
;       LDB(B0, 0, 0); SCHED; LDA(At, 0, 0); STAGE(SA(1, 1), rsA, sA1, offA, t + 1);
;       WAIT_L(8); BAR; WAIT_L(0); MMA(0, 0, At, B0); BAR; SCHED;
;       LDB(B1, 0, 1); STAGE(SB(0, 0), rsB, sB0, offB, t + 2);
.LBB0_391:
	v_bfe_i32 v4, v128, 27, 1
	v_lshlrev_b32_e32 v2, 4, v128
	v_lshrrev_b32_e32 v4, 22, v4
	v_add_u32_e32 v4, v2, v4
	v_and_b32_e32 v4, 0xfffffc00, v4
	v_sub_u32_e32 v4, v2, v4
	v_lshrrev_b32_e32 v5, 4, v4
	v_bitop3_b32 v4, v5, v4, 32 bitop3:0x6c
	v_ashrrev_i32_e32 v3, 31, v128
	v_ashrrev_i32_e32 v6, 31, v4
	v_lshrrev_b32_e32 v3, 26, v3
	v_lshrrev_b32_e32 v6, 26, v6
	v_add_u32_e32 v3, v128, v3
	v_add_u32_e32 v6, v4, v6
	v_ashrrev_i32_e32 v3, 6, v3
	v_lshrrev_b32_e32 v7, 6, v6
	v_and_b32_e32 v6, 0xc0, v6
	v_lshlrev_b32_e32 v5, 3, v3
	v_lshlrev_b32_e32 v3, 5, v3
	v_sub_u32_e32 v4, v4, v6
	v_and_b32_e32 v5, 0x7fff0, v5
	v_and_b32_e32 v3, 32, v3
	v_ashrrev_i16_sdwa v4, v216, sext(v4) dst_sel:DWORD dst_unused:UNUSED_PAD src0_sel:DWORD src1_sel:BYTE_0
	v_add_u32_sdwa v3, v3, sext(v4) dst_sel:DWORD dst_unused:UNUSED_PAD src0_sel:DWORD src1_sel:WORD_0
	v_add_lshl_u32 v4, v7, v5, 13
	v_add_u32_e32 v2, 0x2000, v2
	v_lshl_add_u32 v141, v3, 1, v4
	v_ashrrev_i32_e32 v3, 31, v2
	v_lshrrev_b32_e32 v3, 22, v3
	v_add_u32_e32 v3, v2, v3
	v_ashrrev_i32_e32 v3, 10, v3
	v_mul_i32_i24_e32 v4, 0x400, v3
	v_sub_u32_e32 v2, v2, v4
	v_lshrrev_b32_e32 v4, 4, v2
	v_bitop3_b32 v2, v4, v2, 32 bitop3:0x6c
	v_ashrrev_i32_e32 v5, 31, v2
	v_lshrrev_b32_e32 v5, 26, v5
	v_add_u32_e32 v5, v2, v5
	v_lshrrev_b32_e32 v6, 6, v5
	v_and_b32_e32 v5, 0xc0, v5
	v_lshlrev_b32_e32 v4, 3, v3
	v_lshlrev_b32_e32 v3, 5, v3
	v_sub_u32_e32 v2, v2, v5
	v_and_b32_e32 v4, 0x7fff0, v4
	v_and_b32_e32 v3, 32, v3
	v_ashrrev_i16_sdwa v2, v216, sext(v2) dst_sel:DWORD dst_unused:UNUSED_PAD src0_sel:DWORD src1_sel:BYTE_0
	v_add_u32_sdwa v2, v3, sext(v2) dst_sel:DWORD dst_unused:UNUSED_PAD src0_sel:DWORD src1_sel:WORD_0
	v_add_lshl_u32 v3, v6, v4, 13
	v_lshl_add_u32 v142, v2, 1, v3
	v_and_b32_e32 v3, 15, v0
	v_lshlrev_b32_e32 v5, 2, v0
	v_and_b32_e32 v2, 48, v0
	v_lshlrev_b32_e32 v3, 6, v3
	v_and_b32_e32 v5, 32, v5
	v_or_b32_e32 v4, v3, v2
	v_bitop3_b32 v3, v3, v5, v2 bitop3:0x36
	v_lshlrev_b32_e32 v6, 6, v128
	s_movk_i32 s1, 0x3000
	v_and_or_b32 v3, v6, s1, v3
	v_lshlrev_b32_e32 v0, 6, v0
	s_movk_i32 s1, 0x3c0
	v_lshlrev_b32_e32 v1, 13, v1
	v_and_or_b32 v0, v0, s1, v2
	v_bitop3_b32 v0, v1, v0, v5 bitop3:0xf6
	v_or_b32_e32 v6, 0x400, v3
	v_or_b32_e32 v7, 0x800, v3
	v_or_b32_e32 v8, 0xc00, v3
	v_or_b32_e32 v132, 0x800, v0
	v_or_b32_e32 v131, 0x1000, v0
	v_or_b32_e32 v130, 0x1800, v0
	v_mov_b32_e32 v0, 0
	v_bitop3_b32 v129, v4, v1, v5 bitop3:0xde
	s_mov_b32 s1, -2
	s_mov_b32 s3, 0
	v_or_b32_e32 v147, 0x10000, v3
	v_or_b32_e32 v148, 0x10000, v6
	v_or_b32_e32 v149, 0x10000, v7
	v_or_b32_e32 v150, 0x10000, v8
	v_or_b32_e32 v143, 0x14000, v3
	v_or_b32_e32 v144, 0x14000, v6
	v_or_b32_e32 v145, 0x14000, v7
	v_or_b32_e32 v146, 0x14000, v8
	v_or_b32_e32 v137, 0x18000, v3
	v_or_b32_e32 v138, 0x18000, v6
	v_or_b32_e32 v139, 0x18000, v7
	v_or_b32_e32 v140, 0x18000, v8
	v_or_b32_e32 v133, 0x1c000, v3
	v_or_b32_e32 v134, 0x1c000, v6
	v_or_b32_e32 v135, 0x1c000, v7
	v_or_b32_e32 v136, 0x1c000, v8
	s_barrier
	s_barrier
	ds_read_b128 v[152:155], v147
	ds_read_b128 v[156:159], v148
	ds_read_b128 v[160:163], v149
	ds_read_b128 v[164:167], v150
	s_add_i32 s5, s86, s3
	s_add_i32 s6, s5, 0x80
	s_mov_b32 m0, s36
	ds_read_b128 v[168:171], v129
	ds_read_b128 v[172:175], v129 offset:1024
	ds_read_b128 v[176:179], v132
	ds_read_b128 v[180:183], v132 offset:1024
	ds_read_b128 v[184:187], v131
	ds_read_b128 v[188:191], v131 offset:1024
	ds_read_b128 v[192:195], v130
	ds_read_b128 v[196:199], v130 offset:1024
	buffer_load_dwordx4 v141, s[8:11], s6 offen lds
	s_mov_b32 m0, s59
	s_nop 0
	buffer_load_dwordx4 v142, s[8:11], s6 offen lds
	s_waitcnt lgkmcnt(8)
	s_barrier
	s_waitcnt lgkmcnt(0)
	v_mfma_f32_16x16x32_bf16 v[124:127], v[152:155], v[168:171], 0
	v_mfma_f32_16x16x32_bf16 v[124:127], v[156:159], v[172:175], v[124:127]
	v_mfma_f32_16x16x32_bf16 v[120:123], v[164:167], v[172:175], 0
	v_mfma_f32_16x16x32_bf16 v[120:123], v[160:163], v[168:171], v[120:123]
	v_mfma_f32_16x16x32_bf16 v[112:115], v[160:163], v[176:179], 0
	v_mfma_f32_16x16x32_bf16 v[112:115], v[164:167], v[180:183], v[112:115]
	v_mfma_f32_16x16x32_bf16 v[116:119], v[156:159], v[180:183], 0
	v_mfma_f32_16x16x32_bf16 v[116:119], v[152:155], v[176:179], v[116:119]
	v_mfma_f32_16x16x32_bf16 v[108:111], v[152:155], v[184:187], 0
	v_mfma_f32_16x16x32_bf16 v[108:111], v[156:159], v[188:191], v[108:111]
	v_mfma_f32_16x16x32_bf16 v[104:107], v[164:167], v[188:191], 0
	v_mfma_f32_16x16x32_bf16 v[104:107], v[160:163], v[184:187], v[104:107]
	v_mfma_f32_16x16x32_bf16 v[96:99], v[160:163], v[192:195], 0
	v_mfma_f32_16x16x32_bf16 v[96:99], v[164:167], v[196:199], v[96:99]
	v_mfma_f32_16x16x32_bf16 v[100:103], v[156:159], v[196:199], 0
	v_mfma_f32_16x16x32_bf16 v[100:103], v[152:155], v[192:195], v[100:103]
	s_barrier
	s_add_i32 s6, s92, s3
	s_add_i32 s7, s6, 0x100
	s_mov_b32 s14, s10
	s_mov_b32 s15, s11
	s_mov_b32 m0, s37
	ds_read_b128 v[200:203], v143
	ds_read_b128 v[204:207], v144
	ds_read_b128 v[208:211], v145
	ds_read_b128 v[212:215], v146
	buffer_load_dwordx4 v141, s[12:15], s7 offen lds
	s_mov_b32 m0, s48
	s_nop 0
	buffer_load_dwordx4 v142, s[12:15], s7 offen lds
	s_barrier
; #define STAGE(P, RS, SOFF, OFF, kt) do { const int _so = (SOFF) + (kt) * (BK * 2); \
;     _Pragma("unroll") for (int _i = 0; _i < 2; ++_i) { \
;       __builtin_amdgcn_raw_ptr_buffer_load_lds(RS, (__attribute__((address_space(3))) void*)((P) + wave * 1024 + _i * 8192), 16, OFF[_i], _so, 0, 0); } } while (0)
; #define LDA(dst, b, h) _Pragma("unroll") for (int m = 0; m < 4; ++m) _Pragma("unroll") for (int k = 0; k < 2; ++k) \
;     dst[m][k] = *reinterpret_cast<const bf16x8*>(SA(b, h) + lds_byte(wr * 64 + m * 16 + fr, k * 32 + fq * 8))
; #define LDB(dst, b, h) _Pragma("unroll") for (int n = 0; n < 2; ++n) _Pragma("unroll") for (int k = 0; k < 2; ++k) \
;     dst[n][k] = *reinterpret_cast<const bf16x8*>(SB(b, h) + lds_byte(wc * 32 + n * 16 + fr, k * 32 + fq * 8))
; #define WAIT_V(n) asm volatile("s_waitcnt vmcnt(" #n ")" ::: "memory")
; #define WAIT_L(n) asm volatile("s_waitcnt lgkmcnt(" #n ")" ::: "memory")
; #define BAR __builtin_amdgcn_s_barrier()
; #define SCHED __builtin_amdgcn_sched_barrier(0)
;     ...
;       LDB(B1, 0, 1); STAGE(SB(0, 0), rsB, sB0, offB, t + 2);
;       BAR; WAIT_L(0); MMA(0, 1, At, B1); BAR;
;       LDA(At, 0, 1); STAGE(SA(0, 0), rsA, sA0, offA, t + 2);
;       BAR; WAIT_L(0); MMA(1, 0, At, B0); BAR; SCHED;
;       STAGE(SB(0, 1), rsB, sB1, offB, t + 2);
;       WAIT_V(6); BAR; MMA(1, 1, At, B1); BAR;
;       LDB(B0, 1, 0); SCHED; LDA(At, 1, 0); STAGE(SA(0, 1), rsA, sA1, offA, t + 2);
;       WAIT_L(8); BAR; WAIT_L(0); MMA(0, 0, At, B0); BAR; SCHED;
	s_waitcnt lgkmcnt(2)
	v_mfma_f32_16x16x32_bf16 v[92:95], v[200:203], v[168:171], 0
	v_mfma_f32_16x16x32_bf16 v[92:95], v[204:207], v[172:175], v[92:95]
	s_waitcnt lgkmcnt(0)
	v_mfma_f32_16x16x32_bf16 v[88:91], v[212:215], v[172:175], 0
	v_mfma_f32_16x16x32_bf16 v[88:91], v[208:211], v[168:171], v[88:91]
	v_mfma_f32_16x16x32_bf16 v[68:71], v[208:211], v[176:179], 0
	v_mfma_f32_16x16x32_bf16 v[68:71], v[212:215], v[180:183], v[68:71]
	v_mfma_f32_16x16x32_bf16 v[80:83], v[204:207], v[180:183], 0
	v_mfma_f32_16x16x32_bf16 v[80:83], v[200:203], v[176:179], v[80:83]
	v_mfma_f32_16x16x32_bf16 v[60:63], v[200:203], v[184:187], 0
	v_mfma_f32_16x16x32_bf16 v[60:63], v[204:207], v[188:191], v[60:63]
	v_mfma_f32_16x16x32_bf16 v[56:59], v[212:215], v[188:191], 0
	v_mfma_f32_16x16x32_bf16 v[56:59], v[208:211], v[184:187], v[56:59]
	v_mfma_f32_16x16x32_bf16 v[48:51], v[208:211], v[192:195], 0
	v_mfma_f32_16x16x32_bf16 v[48:51], v[212:215], v[196:199], v[48:51]
	v_mfma_f32_16x16x32_bf16 v[52:55], v[204:207], v[196:199], 0
	v_mfma_f32_16x16x32_bf16 v[52:55], v[200:203], v[192:195], v[52:55]
	s_barrier
	s_add_i32 s7, s87, s3
	s_add_i32 s22, s7, 0x100
	s_mov_b32 m0, s35
	ds_read_b128 v[168:171], v129 offset:16384
	ds_read_b128 v[172:175], v129 offset:17408
	ds_read_b128 v[176:179], v132 offset:16384
	ds_read_b128 v[180:183], v132 offset:17408
	ds_read_b128 v[184:187], v131 offset:16384
	ds_read_b128 v[188:191], v131 offset:17408
	ds_read_b128 v[192:195], v130 offset:16384
	ds_read_b128 v[196:199], v130 offset:17408
	buffer_load_dwordx4 v141, s[8:11], s22 offen lds
	s_mov_b32 m0, s49
	s_nop 0
	buffer_load_dwordx4 v142, s[8:11], s22 offen lds
	s_barrier
	s_waitcnt lgkmcnt(6)
	v_mfma_f32_16x16x32_bf16 v[44:47], v[152:155], v[168:171], 0
	v_mfma_f32_16x16x32_bf16 v[44:47], v[156:159], v[172:175], v[44:47]
	v_mfma_f32_16x16x32_bf16 v[40:43], v[164:167], v[172:175], 0
	v_mfma_f32_16x16x32_bf16 v[40:43], v[160:163], v[168:171], v[40:43]
	s_waitcnt lgkmcnt(4)
	v_mfma_f32_16x16x32_bf16 v[32:35], v[160:163], v[176:179], 0
	v_mfma_f32_16x16x32_bf16 v[32:35], v[164:167], v[180:183], v[32:35]
	v_mfma_f32_16x16x32_bf16 v[36:39], v[156:159], v[180:183], 0
	v_mfma_f32_16x16x32_bf16 v[36:39], v[152:155], v[176:179], v[36:39]
	s_waitcnt lgkmcnt(2)
	v_mfma_f32_16x16x32_bf16 v[28:31], v[152:155], v[184:187], 0
	v_mfma_f32_16x16x32_bf16 v[28:31], v[156:159], v[188:191], v[28:31]
	v_mfma_f32_16x16x32_bf16 v[24:27], v[164:167], v[188:191], 0
	v_mfma_f32_16x16x32_bf16 v[24:27], v[160:163], v[184:187], v[24:27]
	s_waitcnt lgkmcnt(0)
	v_mfma_f32_16x16x32_bf16 v[16:19], v[160:163], v[192:195], 0
	v_mfma_f32_16x16x32_bf16 v[16:19], v[164:167], v[196:199], v[16:19]
	v_mfma_f32_16x16x32_bf16 v[20:23], v[156:159], v[196:199], 0
	v_mfma_f32_16x16x32_bf16 v[20:23], v[152:155], v[192:195], v[20:23]
	s_barrier
	s_add_i32 s22, s93, s3
	s_add_i32 s23, s22, 0x100
	s_mov_b32 m0, s38
	s_nop 0
	buffer_load_dwordx4 v141, s[12:15], s23 offen lds
	s_mov_b32 m0, s54
	s_nop 0
	buffer_load_dwordx4 v142, s[12:15], s23 offen lds
	s_waitcnt vmcnt(6)
	s_barrier
	v_mfma_f32_16x16x32_bf16 v[12:15], v[200:203], v[168:171], 0
	v_mfma_f32_16x16x32_bf16 v[12:15], v[204:207], v[172:175], v[12:15]
	v_mfma_f32_16x16x32_bf16 v[8:11], v[212:215], v[172:175], 0
	v_mfma_f32_16x16x32_bf16 v[8:11], v[208:211], v[168:171], v[8:11]
	v_mfma_f32_16x16x32_bf16 v[0:3], v[208:211], v[176:179], 0
	v_mfma_f32_16x16x32_bf16 v[0:3], v[212:215], v[180:183], v[0:3]
	v_mfma_f32_16x16x32_bf16 v[4:7], v[204:207], v[180:183], 0
	v_mfma_f32_16x16x32_bf16 v[4:7], v[200:203], v[176:179], v[4:7]
	v_mfma_f32_16x16x32_bf16 v[64:67], v[200:203], v[184:187], 0
	v_mfma_f32_16x16x32_bf16 v[64:67], v[204:207], v[188:191], v[64:67]
	v_mfma_f32_16x16x32_bf16 v[72:75], v[212:215], v[188:191], 0
	v_mfma_f32_16x16x32_bf16 v[72:75], v[208:211], v[184:187], v[72:75]
	v_mfma_f32_16x16x32_bf16 v[84:87], v[208:211], v[192:195], 0
	v_mfma_f32_16x16x32_bf16 v[84:87], v[212:215], v[196:199], v[84:87]
	v_mfma_f32_16x16x32_bf16 v[76:79], v[204:207], v[196:199], 0
	v_mfma_f32_16x16x32_bf16 v[76:79], v[200:203], v[192:195], v[76:79]
	s_barrier
	ds_read_b128 v[152:155], v137
	ds_read_b128 v[156:159], v138
	ds_read_b128 v[160:163], v139
	ds_read_b128 v[164:167], v140
	s_addk_i32 s5, 0x100
	s_mov_b32 m0, s39
	ds_read_b128 v[168:171], v129 offset:32768
	ds_read_b128 v[172:175], v129 offset:33792
	ds_read_b128 v[176:179], v132 offset:32768
	ds_read_b128 v[180:183], v132 offset:33792
	ds_read_b128 v[184:187], v131 offset:32768
	ds_read_b128 v[188:191], v131 offset:33792
	ds_read_b128 v[192:195], v130 offset:32768
	ds_read_b128 v[196:199], v130 offset:33792
	buffer_load_dwordx4 v141, s[8:11], s5 offen lds
	s_mov_b32 m0, s55
	s_nop 0
	buffer_load_dwordx4 v142, s[8:11], s5 offen lds
	s_waitcnt lgkmcnt(8)
	s_barrier
; #define STAGE(P, RS, SOFF, OFF, kt) do { const int _so = (SOFF) + (kt) * (BK * 2); \
;     _Pragma("unroll") for (int _i = 0; _i < 2; ++_i) { \
;       __builtin_amdgcn_raw_ptr_buffer_load_lds(RS, (__attribute__((address_space(3))) void*)((P) + wave * 1024 + _i * 8192), 16, OFF[_i], _so, 0, 0); } } while (0)
; #define LDA(dst, b, h) _Pragma("unroll") for (int m = 0; m < 4; ++m) _Pragma("unroll") for (int k = 0; k < 2; ++k) \
;     dst[m][k] = *reinterpret_cast<const bf16x8*>(SA(b, h) + lds_byte(wr * 64 + m * 16 + fr, k * 32 + fq * 8))
; #define LDB(dst, b, h) _Pragma("unroll") for (int n = 0; n < 2; ++n) _Pragma("unroll") for (int k = 0; k < 2; ++k) \
;     dst[n][k] = *reinterpret_cast<const bf16x8*>(SB(b, h) + lds_byte(wc * 32 + n * 16 + fr, k * 32 + fq * 8))
; #define WAIT_V(n) asm volatile("s_waitcnt vmcnt(" #n ")" ::: "memory")
; #define WAIT_L(n) asm volatile("s_waitcnt lgkmcnt(" #n ")" ::: "memory")
; #define BAR __builtin_amdgcn_s_barrier()
; #define SCHED __builtin_amdgcn_sched_barrier(0)
;     ...
;       WAIT_L(8); BAR; WAIT_L(0); MMA(0, 0, At, B0); BAR; SCHED;
;       LDB(B1, 1, 1); STAGE(SB(1, 0), rsB, sB0, offB, t + 3);
;       BAR; WAIT_L(0); MMA(0, 1, At, B1); BAR;
;       LDA(At, 1, 1); STAGE(SA(1, 0), rsA, sA0, offA, t + 3);
;       BAR; WAIT_L(0); MMA(1, 0, At, B0); BAR; SCHED;
;       STAGE(SB(1, 1), rsB, sB1, offB, t + 3);
;       WAIT_V(6); BAR; MMA(1, 1, At, B1); BAR;
	s_waitcnt lgkmcnt(6)
	v_mfma_f32_16x16x32_bf16 v[124:127], v[152:155], v[168:171], v[124:127]
	v_mfma_f32_16x16x32_bf16 v[124:127], v[156:159], v[172:175], v[124:127]
	v_mfma_f32_16x16x32_bf16 v[120:123], v[164:167], v[172:175], v[120:123]
	v_mfma_f32_16x16x32_bf16 v[120:123], v[160:163], v[168:171], v[120:123]
	s_waitcnt lgkmcnt(4)
	v_mfma_f32_16x16x32_bf16 v[112:115], v[160:163], v[176:179], v[112:115]
	v_mfma_f32_16x16x32_bf16 v[112:115], v[164:167], v[180:183], v[112:115]
	v_mfma_f32_16x16x32_bf16 v[116:119], v[156:159], v[180:183], v[116:119]
	v_mfma_f32_16x16x32_bf16 v[116:119], v[152:155], v[176:179], v[116:119]
	s_waitcnt lgkmcnt(2)
	v_mfma_f32_16x16x32_bf16 v[108:111], v[152:155], v[184:187], v[108:111]
	v_mfma_f32_16x16x32_bf16 v[108:111], v[156:159], v[188:191], v[108:111]
	v_mfma_f32_16x16x32_bf16 v[104:107], v[164:167], v[188:191], v[104:107]
	v_mfma_f32_16x16x32_bf16 v[104:107], v[160:163], v[184:187], v[104:107]
	s_waitcnt lgkmcnt(0)
	v_mfma_f32_16x16x32_bf16 v[96:99], v[160:163], v[192:195], v[96:99]
	v_mfma_f32_16x16x32_bf16 v[96:99], v[164:167], v[196:199], v[96:99]
	v_mfma_f32_16x16x32_bf16 v[100:103], v[156:159], v[196:199], v[100:103]
	v_mfma_f32_16x16x32_bf16 v[100:103], v[152:155], v[192:195], v[100:103]
	s_barrier
	s_addk_i32 s6, 0x180
	s_mov_b32 m0, s42
	ds_read_b128 v[200:203], v133
	ds_read_b128 v[204:207], v134
	ds_read_b128 v[208:211], v135
	ds_read_b128 v[212:215], v136
	buffer_load_dwordx4 v141, s[12:15], s6 offen lds
	s_mov_b32 m0, s56
	s_nop 0
	buffer_load_dwordx4 v142, s[12:15], s6 offen lds
	s_barrier
	s_waitcnt lgkmcnt(2)
	v_mfma_f32_16x16x32_bf16 v[92:95], v[200:203], v[168:171], v[92:95]
	v_mfma_f32_16x16x32_bf16 v[92:95], v[204:207], v[172:175], v[92:95]
	s_waitcnt lgkmcnt(0)
	v_mfma_f32_16x16x32_bf16 v[88:91], v[212:215], v[172:175], v[88:91]
	v_mfma_f32_16x16x32_bf16 v[88:91], v[208:211], v[168:171], v[88:91]
	v_mfma_f32_16x16x32_bf16 v[68:71], v[208:211], v[176:179], v[68:71]
	v_mfma_f32_16x16x32_bf16 v[68:71], v[212:215], v[180:183], v[68:71]
	v_mfma_f32_16x16x32_bf16 v[80:83], v[204:207], v[180:183], v[80:83]
	v_mfma_f32_16x16x32_bf16 v[80:83], v[200:203], v[176:179], v[80:83]
	v_mfma_f32_16x16x32_bf16 v[60:63], v[200:203], v[184:187], v[60:63]
	v_mfma_f32_16x16x32_bf16 v[60:63], v[204:207], v[188:191], v[60:63]
	v_mfma_f32_16x16x32_bf16 v[56:59], v[212:215], v[188:191], v[56:59]
	v_mfma_f32_16x16x32_bf16 v[56:59], v[208:211], v[184:187], v[56:59]
	v_mfma_f32_16x16x32_bf16 v[48:51], v[208:211], v[192:195], v[48:51]
	v_mfma_f32_16x16x32_bf16 v[48:51], v[212:215], v[196:199], v[48:51]
	v_mfma_f32_16x16x32_bf16 v[52:55], v[204:207], v[196:199], v[52:55]
	v_mfma_f32_16x16x32_bf16 v[52:55], v[200:203], v[192:195], v[52:55]
	s_barrier
	s_addk_i32 s7, 0x180
	s_mov_b32 m0, s43
	ds_read_b128 v[168:171], v129 offset:49152
	ds_read_b128 v[172:175], v129 offset:50176
	ds_read_b128 v[176:179], v132 offset:49152
	ds_read_b128 v[180:183], v132 offset:50176
	ds_read_b128 v[184:187], v131 offset:49152
	ds_read_b128 v[188:191], v131 offset:50176
	ds_read_b128 v[192:195], v130 offset:49152
	ds_read_b128 v[196:199], v130 offset:50176
	buffer_load_dwordx4 v141, s[8:11], s7 offen lds
	s_mov_b32 m0, s57
	s_nop 0
	buffer_load_dwordx4 v142, s[8:11], s7 offen lds
	s_barrier
	s_waitcnt lgkmcnt(6)
	v_mfma_f32_16x16x32_bf16 v[44:47], v[152:155], v[168:171], v[44:47]
	v_mfma_f32_16x16x32_bf16 v[44:47], v[156:159], v[172:175], v[44:47]
	v_mfma_f32_16x16x32_bf16 v[40:43], v[164:167], v[172:175], v[40:43]
	v_mfma_f32_16x16x32_bf16 v[40:43], v[160:163], v[168:171], v[40:43]
	s_waitcnt lgkmcnt(4)
	v_mfma_f32_16x16x32_bf16 v[32:35], v[160:163], v[176:179], v[32:35]
	v_mfma_f32_16x16x32_bf16 v[32:35], v[164:167], v[180:183], v[32:35]
	v_mfma_f32_16x16x32_bf16 v[36:39], v[156:159], v[180:183], v[36:39]
	v_mfma_f32_16x16x32_bf16 v[36:39], v[152:155], v[176:179], v[36:39]
	s_waitcnt lgkmcnt(2)
	v_mfma_f32_16x16x32_bf16 v[28:31], v[152:155], v[184:187], v[28:31]
	v_mfma_f32_16x16x32_bf16 v[28:31], v[156:159], v[188:191], v[28:31]
	v_mfma_f32_16x16x32_bf16 v[24:27], v[164:167], v[188:191], v[24:27]
	v_mfma_f32_16x16x32_bf16 v[24:27], v[160:163], v[184:187], v[24:27]
	s_waitcnt lgkmcnt(0)
	v_mfma_f32_16x16x32_bf16 v[16:19], v[160:163], v[192:195], v[16:19]
	v_mfma_f32_16x16x32_bf16 v[16:19], v[164:167], v[196:199], v[16:19]
	v_mfma_f32_16x16x32_bf16 v[20:23], v[156:159], v[196:199], v[20:23]
	v_mfma_f32_16x16x32_bf16 v[20:23], v[152:155], v[192:195], v[20:23]
	s_barrier
	s_addk_i32 s22, 0x180
	s_mov_b32 m0, s44
	s_nop 0
	buffer_load_dwordx4 v141, s[12:15], s22 offen lds
	s_mov_b32 m0, s58
	s_nop 0
	buffer_load_dwordx4 v142, s[12:15], s22 offen lds
	s_add_i32 s1, s1, 2
	s_addk_i32 s3, 0x100
	s_cmp_gt_u32 s1, 59
	s_cbranch_scc0 .LBB0_392
	s_branch .Lmy_post_392

; #define STAGE(P, RS, SOFF, OFF, kt) do { const int _so = (SOFF) + (kt) * (BK * 2); \
;     _Pragma("unroll") for (int _i = 0; _i < 2; ++_i) { \
;       __builtin_amdgcn_raw_ptr_buffer_load_lds(RS, (__attribute__((address_space(3))) void*)((P) + wave * 1024 + _i * 8192), 16, OFF[_i], _so, 0, 0); } } while (0)
; #define LDA(dst, b, h) _Pragma("unroll") for (int m = 0; m < 4; ++m) _Pragma("unroll") for (int k = 0; k < 2; ++k) \
;     dst[m][k] = *reinterpret_cast<const bf16x8*>(SA(b, h) + lds_byte(wr * 64 + m * 16 + fr, k * 32 + fq * 8))
; #define LDB(dst, b, h) _Pragma("unroll") for (int n = 0; n < 2; ++n) _Pragma("unroll") for (int k = 0; k < 2; ++k) \
;     dst[n][k] = *reinterpret_cast<const bf16x8*>(SB(b, h) + lds_byte(wc * 32 + n * 16 + fr, k * 32 + fq * 8))
; #define WAIT_V(n) asm volatile("s_waitcnt vmcnt(" #n ")" ::: "memory")
; #define WAIT_L(n) asm volatile("s_waitcnt lgkmcnt(" #n ")" ::: "memory")
; #define BAR __builtin_amdgcn_s_barrier()
; #define SCHED __builtin_amdgcn_sched_barrier(0)
;     ...
;       LDB(B0, 0, 0); SCHED; LDA(At, 0, 0); STAGE(SA(1, 1), rsA, sA1, offA, t + 1);
;       WAIT_L(8); BAR; WAIT_L(0); MMA(0, 0, At, B0); BAR; SCHED;
;       LDB(B1, 0, 1); STAGE(SB(0, 0), rsB, sB0, offB, t + 2);
;       BAR; WAIT_L(0); MMA(0, 1, At, B1); BAR;
;       LDA(At, 0, 1); STAGE(SA(0, 0), rsA, sA0, offA, t + 2);
;       BAR; WAIT_L(0); MMA(1, 0, At, B0); BAR; SCHED;
;       STAGE(SB(0, 1), rsB, sB1, offB, t + 2);
;       WAIT_V(6); BAR; MMA(1, 1, At, B1); BAR;
.Lmy_rot_392:
	ds_read_b128 v[152:155], v147
	ds_read_b128 v[156:159], v148
	ds_read_b128 v[160:163], v149
	ds_read_b128 v[164:167], v150
	s_add_i32 s5, s86, s3
	s_add_i32 s6, s5, 0x80
	s_mov_b32 m0, s36
	ds_read_b128 v[168:171], v129
	ds_read_b128 v[172:175], v129 offset:1024
	ds_read_b128 v[176:179], v132
	ds_read_b128 v[180:183], v132 offset:1024
	ds_read_b128 v[184:187], v131
	ds_read_b128 v[188:191], v131 offset:1024
	ds_read_b128 v[192:195], v130
	ds_read_b128 v[196:199], v130 offset:1024
	buffer_load_dwordx4 v141, s[8:11], s6 offen lds
	s_mov_b32 m0, s59
	s_nop 0
	buffer_load_dwordx4 v142, s[8:11], s6 offen lds
	s_waitcnt lgkmcnt(8)
	s_barrier
	s_waitcnt lgkmcnt(0)
	v_mfma_f32_16x16x32_bf16 v[124:127], v[152:155], v[168:171], v[124:127]
	v_mfma_f32_16x16x32_bf16 v[124:127], v[156:159], v[172:175], v[124:127]
	v_mfma_f32_16x16x32_bf16 v[120:123], v[164:167], v[172:175], v[120:123]
	v_mfma_f32_16x16x32_bf16 v[120:123], v[160:163], v[168:171], v[120:123]
	v_mfma_f32_16x16x32_bf16 v[112:115], v[160:163], v[176:179], v[112:115]
	v_mfma_f32_16x16x32_bf16 v[112:115], v[164:167], v[180:183], v[112:115]
	v_mfma_f32_16x16x32_bf16 v[116:119], v[156:159], v[180:183], v[116:119]
	v_mfma_f32_16x16x32_bf16 v[116:119], v[152:155], v[176:179], v[116:119]
	v_mfma_f32_16x16x32_bf16 v[108:111], v[152:155], v[184:187], v[108:111]
	v_mfma_f32_16x16x32_bf16 v[108:111], v[156:159], v[188:191], v[108:111]
	v_mfma_f32_16x16x32_bf16 v[104:107], v[164:167], v[188:191], v[104:107]
	v_mfma_f32_16x16x32_bf16 v[104:107], v[160:163], v[184:187], v[104:107]
	v_mfma_f32_16x16x32_bf16 v[96:99], v[160:163], v[192:195], v[96:99]
	v_mfma_f32_16x16x32_bf16 v[96:99], v[164:167], v[196:199], v[96:99]
	v_mfma_f32_16x16x32_bf16 v[100:103], v[156:159], v[196:199], v[100:103]
	v_mfma_f32_16x16x32_bf16 v[100:103], v[152:155], v[192:195], v[100:103]
	s_barrier
	s_add_i32 s6, s92, s3
	s_add_i32 s7, s6, 0x100
	s_mov_b32 s14, s10
	s_mov_b32 s15, s11
	s_mov_b32 m0, s37
	ds_read_b128 v[200:203], v143
	ds_read_b128 v[204:207], v144
	ds_read_b128 v[208:211], v145
	ds_read_b128 v[212:215], v146
	buffer_load_dwordx4 v141, s[12:15], s7 offen lds
	s_mov_b32 m0, s48
	s_nop 0
	buffer_load_dwordx4 v142, s[12:15], s7 offen lds
	s_barrier
	s_waitcnt lgkmcnt(2)
	v_mfma_f32_16x16x32_bf16 v[92:95], v[200:203], v[168:171], v[92:95]
	v_mfma_f32_16x16x32_bf16 v[92:95], v[204:207], v[172:175], v[92:95]
	s_waitcnt lgkmcnt(0)
	v_mfma_f32_16x16x32_bf16 v[88:91], v[212:215], v[172:175], v[88:91]
	v_mfma_f32_16x16x32_bf16 v[88:91], v[208:211], v[168:171], v[88:91]
	v_mfma_f32_16x16x32_bf16 v[68:71], v[208:211], v[176:179], v[68:71]
	v_mfma_f32_16x16x32_bf16 v[68:71], v[212:215], v[180:183], v[68:71]
	v_mfma_f32_16x16x32_bf16 v[80:83], v[204:207], v[180:183], v[80:83]
	v_mfma_f32_16x16x32_bf16 v[80:83], v[200:203], v[176:179], v[80:83]
	v_mfma_f32_16x16x32_bf16 v[60:63], v[200:203], v[184:187], v[60:63]
	v_mfma_f32_16x16x32_bf16 v[60:63], v[204:207], v[188:191], v[60:63]
	v_mfma_f32_16x16x32_bf16 v[56:59], v[212:215], v[188:191], v[56:59]
	v_mfma_f32_16x16x32_bf16 v[56:59], v[208:211], v[184:187], v[56:59]
	v_mfma_f32_16x16x32_bf16 v[48:51], v[208:211], v[192:195], v[48:51]
	v_mfma_f32_16x16x32_bf16 v[48:51], v[212:215], v[196:199], v[48:51]
	v_mfma_f32_16x16x32_bf16 v[52:55], v[204:207], v[196:199], v[52:55]
	v_mfma_f32_16x16x32_bf16 v[52:55], v[200:203], v[192:195], v[52:55]
	s_barrier
	s_add_i32 s7, s87, s3
	s_add_i32 s22, s7, 0x100
	s_mov_b32 m0, s35
	ds_read_b128 v[168:171], v129 offset:16384
	ds_read_b128 v[172:175], v129 offset:17408
	ds_read_b128 v[176:179], v132 offset:16384
	ds_read_b128 v[180:183], v132 offset:17408
	ds_read_b128 v[184:187], v131 offset:16384
	ds_read_b128 v[188:191], v131 offset:17408
	ds_read_b128 v[192:195], v130 offset:16384
	ds_read_b128 v[196:199], v130 offset:17408
	buffer_load_dwordx4 v141, s[8:11], s22 offen lds
	s_mov_b32 m0, s49
	s_nop 0
	buffer_load_dwordx4 v142, s[8:11], s22 offen lds
	s_barrier
	s_waitcnt lgkmcnt(6)
	v_mfma_f32_16x16x32_bf16 v[44:47], v[152:155], v[168:171], v[44:47]
	v_mfma_f32_16x16x32_bf16 v[44:47], v[156:159], v[172:175], v[44:47]
	v_mfma_f32_16x16x32_bf16 v[40:43], v[164:167], v[172:175], v[40:43]
	v_mfma_f32_16x16x32_bf16 v[40:43], v[160:163], v[168:171], v[40:43]
	s_waitcnt lgkmcnt(4)
	v_mfma_f32_16x16x32_bf16 v[32:35], v[160:163], v[176:179], v[32:35]
	v_mfma_f32_16x16x32_bf16 v[32:35], v[164:167], v[180:183], v[32:35]
	v_mfma_f32_16x16x32_bf16 v[36:39], v[156:159], v[180:183], v[36:39]
	v_mfma_f32_16x16x32_bf16 v[36:39], v[152:155], v[176:179], v[36:39]
	s_waitcnt lgkmcnt(2)
	v_mfma_f32_16x16x32_bf16 v[28:31], v[152:155], v[184:187], v[28:31]
	v_mfma_f32_16x16x32_bf16 v[28:31], v[156:159], v[188:191], v[28:31]
	v_mfma_f32_16x16x32_bf16 v[24:27], v[164:167], v[188:191], v[24:27]
	v_mfma_f32_16x16x32_bf16 v[24:27], v[160:163], v[184:187], v[24:27]
	s_waitcnt lgkmcnt(0)
	v_mfma_f32_16x16x32_bf16 v[16:19], v[160:163], v[192:195], v[16:19]
	v_mfma_f32_16x16x32_bf16 v[16:19], v[164:167], v[196:199], v[16:19]
	v_mfma_f32_16x16x32_bf16 v[20:23], v[156:159], v[196:199], v[20:23]
	v_mfma_f32_16x16x32_bf16 v[20:23], v[152:155], v[192:195], v[20:23]
	s_barrier
	s_add_i32 s22, s93, s3
	s_add_i32 s23, s22, 0x100
	s_mov_b32 m0, s38
	s_nop 0
	buffer_load_dwordx4 v141, s[12:15], s23 offen lds
	s_mov_b32 m0, s54
	s_nop 0
	buffer_load_dwordx4 v142, s[12:15], s23 offen lds
	s_waitcnt vmcnt(6)
	s_barrier
; #define STAGE(P, RS, SOFF, OFF, kt) do { const int _so = (SOFF) + (kt) * (BK * 2); \
;     _Pragma("unroll") for (int _i = 0; _i < 2; ++_i) { \
;       __builtin_amdgcn_raw_ptr_buffer_load_lds(RS, (__attribute__((address_space(3))) void*)((P) + wave * 1024 + _i * 8192), 16, OFF[_i], _so, 0, 0); } } while (0)
; #define LDA(dst, b, h) _Pragma("unroll") for (int m = 0; m < 4; ++m) _Pragma("unroll") for (int k = 0; k < 2; ++k) \
;     dst[m][k] = *reinterpret_cast<const bf16x8*>(SA(b, h) + lds_byte(wr * 64 + m * 16 + fr, k * 32 + fq * 8))
; #define LDB(dst, b, h) _Pragma("unroll") for (int n = 0; n < 2; ++n) _Pragma("unroll") for (int k = 0; k < 2; ++k) \
;     dst[n][k] = *reinterpret_cast<const bf16x8*>(SB(b, h) + lds_byte(wc * 32 + n * 16 + fr, k * 32 + fq * 8))
; #define WAIT_V(n) asm volatile("s_waitcnt vmcnt(" #n ")" ::: "memory")
; #define WAIT_L(n) asm volatile("s_waitcnt lgkmcnt(" #n ")" ::: "memory")
; #define BAR __builtin_amdgcn_s_barrier()
; #define SCHED __builtin_amdgcn_sched_barrier(0)
;     ...
;       WAIT_V(6); BAR; MMA(1, 1, At, B1); BAR;
;       LDB(B0, 1, 0); SCHED; LDA(At, 1, 0); STAGE(SA(0, 1), rsA, sA1, offA, t + 2);
;       WAIT_L(8); BAR; WAIT_L(0); MMA(0, 0, At, B0); BAR; SCHED;
;       LDB(B1, 1, 1); STAGE(SB(1, 0), rsB, sB0, offB, t + 3);
;       BAR; WAIT_L(0); MMA(0, 1, At, B1); BAR;
;       LDA(At, 1, 1); STAGE(SA(1, 0), rsA, sA0, offA, t + 3);
;       BAR; WAIT_L(0); MMA(1, 0, At, B0); BAR; SCHED;
;       STAGE(SB(1, 1), rsB, sB1, offB, t + 3);
;       WAIT_V(6); BAR; MMA(1, 1, At, B1); BAR;
	v_mfma_f32_16x16x32_bf16 v[12:15], v[200:203], v[168:171], v[12:15]
	v_mfma_f32_16x16x32_bf16 v[12:15], v[204:207], v[172:175], v[12:15]
	v_mfma_f32_16x16x32_bf16 v[8:11], v[212:215], v[172:175], v[8:11]
	v_mfma_f32_16x16x32_bf16 v[8:11], v[208:211], v[168:171], v[8:11]
	v_mfma_f32_16x16x32_bf16 v[0:3], v[208:211], v[176:179], v[0:3]
	v_mfma_f32_16x16x32_bf16 v[0:3], v[212:215], v[180:183], v[0:3]
	v_mfma_f32_16x16x32_bf16 v[4:7], v[204:207], v[180:183], v[4:7]
	v_mfma_f32_16x16x32_bf16 v[4:7], v[200:203], v[176:179], v[4:7]
	v_mfma_f32_16x16x32_bf16 v[64:67], v[200:203], v[184:187], v[64:67]
	v_mfma_f32_16x16x32_bf16 v[64:67], v[204:207], v[188:191], v[64:67]
	v_mfma_f32_16x16x32_bf16 v[72:75], v[212:215], v[188:191], v[72:75]
	v_mfma_f32_16x16x32_bf16 v[72:75], v[208:211], v[184:187], v[72:75]
	v_mfma_f32_16x16x32_bf16 v[84:87], v[208:211], v[192:195], v[84:87]
	v_mfma_f32_16x16x32_bf16 v[84:87], v[212:215], v[196:199], v[84:87]
	v_mfma_f32_16x16x32_bf16 v[76:79], v[204:207], v[196:199], v[76:79]
	v_mfma_f32_16x16x32_bf16 v[76:79], v[200:203], v[192:195], v[76:79]
	s_barrier
	ds_read_b128 v[152:155], v137
	ds_read_b128 v[156:159], v138
	ds_read_b128 v[160:163], v139
	ds_read_b128 v[164:167], v140
	s_addk_i32 s5, 0x100
	s_mov_b32 m0, s39
	ds_read_b128 v[168:171], v129 offset:32768
	ds_read_b128 v[172:175], v129 offset:33792
	ds_read_b128 v[176:179], v132 offset:32768
	ds_read_b128 v[180:183], v132 offset:33792
	ds_read_b128 v[184:187], v131 offset:32768
	ds_read_b128 v[188:191], v131 offset:33792
	ds_read_b128 v[192:195], v130 offset:32768
	ds_read_b128 v[196:199], v130 offset:33792
	buffer_load_dwordx4 v141, s[8:11], s5 offen lds
	s_mov_b32 m0, s55
	s_nop 0
	buffer_load_dwordx4 v142, s[8:11], s5 offen lds
	s_waitcnt lgkmcnt(8)
	s_barrier
	s_waitcnt lgkmcnt(6)
	v_mfma_f32_16x16x32_bf16 v[124:127], v[152:155], v[168:171], v[124:127]
	v_mfma_f32_16x16x32_bf16 v[124:127], v[156:159], v[172:175], v[124:127]
	v_mfma_f32_16x16x32_bf16 v[120:123], v[164:167], v[172:175], v[120:123]
	v_mfma_f32_16x16x32_bf16 v[120:123], v[160:163], v[168:171], v[120:123]
	s_waitcnt lgkmcnt(4)
	v_mfma_f32_16x16x32_bf16 v[112:115], v[160:163], v[176:179], v[112:115]
	v_mfma_f32_16x16x32_bf16 v[112:115], v[164:167], v[180:183], v[112:115]
	v_mfma_f32_16x16x32_bf16 v[116:119], v[156:159], v[180:183], v[116:119]
	v_mfma_f32_16x16x32_bf16 v[116:119], v[152:155], v[176:179], v[116:119]
	s_waitcnt lgkmcnt(2)
	v_mfma_f32_16x16x32_bf16 v[108:111], v[152:155], v[184:187], v[108:111]
	v_mfma_f32_16x16x32_bf16 v[108:111], v[156:159], v[188:191], v[108:111]
	v_mfma_f32_16x16x32_bf16 v[104:107], v[164:167], v[188:191], v[104:107]
	v_mfma_f32_16x16x32_bf16 v[104:107], v[160:163], v[184:187], v[104:107]
	s_waitcnt lgkmcnt(0)
	v_mfma_f32_16x16x32_bf16 v[96:99], v[160:163], v[192:195], v[96:99]
	v_mfma_f32_16x16x32_bf16 v[96:99], v[164:167], v[196:199], v[96:99]
	v_mfma_f32_16x16x32_bf16 v[100:103], v[156:159], v[196:199], v[100:103]
	v_mfma_f32_16x16x32_bf16 v[100:103], v[152:155], v[192:195], v[100:103]
	s_barrier
	s_addk_i32 s6, 0x180
	s_mov_b32 m0, s42
	ds_read_b128 v[200:203], v133
	ds_read_b128 v[204:207], v134
	ds_read_b128 v[208:211], v135
	ds_read_b128 v[212:215], v136
	buffer_load_dwordx4 v141, s[12:15], s6 offen lds
	s_mov_b32 m0, s56
	s_nop 0
	buffer_load_dwordx4 v142, s[12:15], s6 offen lds
	s_barrier
	s_waitcnt lgkmcnt(2)
	v_mfma_f32_16x16x32_bf16 v[92:95], v[200:203], v[168:171], v[92:95]
	v_mfma_f32_16x16x32_bf16 v[92:95], v[204:207], v[172:175], v[92:95]
	s_waitcnt lgkmcnt(0)
	v_mfma_f32_16x16x32_bf16 v[88:91], v[212:215], v[172:175], v[88:91]
	v_mfma_f32_16x16x32_bf16 v[88:91], v[208:211], v[168:171], v[88:91]
	v_mfma_f32_16x16x32_bf16 v[68:71], v[208:211], v[176:179], v[68:71]
	v_mfma_f32_16x16x32_bf16 v[68:71], v[212:215], v[180:183], v[68:71]
	v_mfma_f32_16x16x32_bf16 v[80:83], v[204:207], v[180:183], v[80:83]
	v_mfma_f32_16x16x32_bf16 v[80:83], v[200:203], v[176:179], v[80:83]
	v_mfma_f32_16x16x32_bf16 v[60:63], v[200:203], v[184:187], v[60:63]
	v_mfma_f32_16x16x32_bf16 v[60:63], v[204:207], v[188:191], v[60:63]
	v_mfma_f32_16x16x32_bf16 v[56:59], v[212:215], v[188:191], v[56:59]
	v_mfma_f32_16x16x32_bf16 v[56:59], v[208:211], v[184:187], v[56:59]
	v_mfma_f32_16x16x32_bf16 v[48:51], v[208:211], v[192:195], v[48:51]
	v_mfma_f32_16x16x32_bf16 v[48:51], v[212:215], v[196:199], v[48:51]
	v_mfma_f32_16x16x32_bf16 v[52:55], v[204:207], v[196:199], v[52:55]
	v_mfma_f32_16x16x32_bf16 v[52:55], v[200:203], v[192:195], v[52:55]
	s_barrier
	s_addk_i32 s7, 0x180
	s_mov_b32 m0, s43
	ds_read_b128 v[168:171], v129 offset:49152
	ds_read_b128 v[172:175], v129 offset:50176
	ds_read_b128 v[176:179], v132 offset:49152
	ds_read_b128 v[180:183], v132 offset:50176
	ds_read_b128 v[184:187], v131 offset:49152
	ds_read_b128 v[188:191], v131 offset:50176
	ds_read_b128 v[192:195], v130 offset:49152
	ds_read_b128 v[196:199], v130 offset:50176
	buffer_load_dwordx4 v141, s[8:11], s7 offen lds
	s_mov_b32 m0, s57
	s_nop 0
	buffer_load_dwordx4 v142, s[8:11], s7 offen lds
	s_barrier
	s_waitcnt lgkmcnt(6)
	v_mfma_f32_16x16x32_bf16 v[44:47], v[152:155], v[168:171], v[44:47]
	v_mfma_f32_16x16x32_bf16 v[44:47], v[156:159], v[172:175], v[44:47]
	v_mfma_f32_16x16x32_bf16 v[40:43], v[164:167], v[172:175], v[40:43]
	v_mfma_f32_16x16x32_bf16 v[40:43], v[160:163], v[168:171], v[40:43]
	s_waitcnt lgkmcnt(4)
	v_mfma_f32_16x16x32_bf16 v[32:35], v[160:163], v[176:179], v[32:35]
	v_mfma_f32_16x16x32_bf16 v[32:35], v[164:167], v[180:183], v[32:35]
	v_mfma_f32_16x16x32_bf16 v[36:39], v[156:159], v[180:183], v[36:39]
	v_mfma_f32_16x16x32_bf16 v[36:39], v[152:155], v[176:179], v[36:39]
	s_waitcnt lgkmcnt(2)
	v_mfma_f32_16x16x32_bf16 v[28:31], v[152:155], v[184:187], v[28:31]
	v_mfma_f32_16x16x32_bf16 v[28:31], v[156:159], v[188:191], v[28:31]
	v_mfma_f32_16x16x32_bf16 v[24:27], v[164:167], v[188:191], v[24:27]
	v_mfma_f32_16x16x32_bf16 v[24:27], v[160:163], v[184:187], v[24:27]
	s_waitcnt lgkmcnt(0)
	v_mfma_f32_16x16x32_bf16 v[16:19], v[160:163], v[192:195], v[16:19]
	v_mfma_f32_16x16x32_bf16 v[16:19], v[164:167], v[196:199], v[16:19]
	v_mfma_f32_16x16x32_bf16 v[20:23], v[156:159], v[196:199], v[20:23]
	v_mfma_f32_16x16x32_bf16 v[20:23], v[152:155], v[192:195], v[20:23]
	s_barrier
	s_addk_i32 s22, 0x180
	s_mov_b32 m0, s44
	s_nop 0
	buffer_load_dwordx4 v141, s[12:15], s22 offen lds
	s_mov_b32 m0, s58
	s_nop 0
	buffer_load_dwordx4 v142, s[12:15], s22 offen lds
	s_add_i32 s1, s1, 2
	s_addk_i32 s3, 0x100
	s_cmp_gt_u32 s1, 59
	s_cbranch_scc0 .LBB0_392
; #define STAGE(P, RS, SOFF, OFF, kt) do { const int _so = (SOFF) + (kt) * (BK * 2); \
;     _Pragma("unroll") for (int _i = 0; _i < 2; ++_i) { \
;       __builtin_amdgcn_raw_ptr_buffer_load_lds(RS, (__attribute__((address_space(3))) void*)((P) + wave * 1024 + _i * 8192), 16, OFF[_i], _so, 0, 0); } } while (0)
; #define LDA(dst, b, h) _Pragma("unroll") for (int m = 0; m < 4; ++m) _Pragma("unroll") for (int k = 0; k < 2; ++k) \
;     dst[m][k] = *reinterpret_cast<const bf16x8*>(SA(b, h) + lds_byte(wr * 64 + m * 16 + fr, k * 32 + fq * 8))
; #define LDB(dst, b, h) _Pragma("unroll") for (int n = 0; n < 2; ++n) _Pragma("unroll") for (int k = 0; k < 2; ++k) \
;     dst[n][k] = *reinterpret_cast<const bf16x8*>(SB(b, h) + lds_byte(wc * 32 + n * 16 + fr, k * 32 + fq * 8))
; #define WAIT_V(n) asm volatile("s_waitcnt vmcnt(" #n ")" ::: "memory")
; #define WAIT_L(n) asm volatile("s_waitcnt lgkmcnt(" #n ")" ::: "memory")
; #define BAR __builtin_amdgcn_s_barrier()
;     ...
;       WAIT_V(6); BAR; MMA(1, 1, At, B1); BAR;
;     }
;     { LDB(B0, 0, 0); LDA(At, 0, 0); STAGE(SA(1, 1), rsA, sA1, offA, nt - 1);
;       BAR; WAIT_L(0); MMA(0, 0, At, B0); BAR;
;       LDB(B1, 0, 1); BAR; WAIT_L(0); MMA(0, 1, At, B1); BAR;
;       LDA(At, 0, 1); WAIT_V(4); BAR; WAIT_L(0); MMA(1, 0, At, B0); MMA(1, 1, At, B1); BAR; }
.Lmy_post_392:
	s_waitcnt vmcnt(6)
	s_barrier
	v_mfma_f32_16x16x32_bf16 v[12:15], v[200:203], v[168:171], v[12:15]
	v_mfma_f32_16x16x32_bf16 v[12:15], v[204:207], v[172:175], v[12:15]
	v_mfma_f32_16x16x32_bf16 v[8:11], v[212:215], v[172:175], v[8:11]
	v_mfma_f32_16x16x32_bf16 v[8:11], v[208:211], v[168:171], v[8:11]
	v_mfma_f32_16x16x32_bf16 v[0:3], v[208:211], v[176:179], v[0:3]
	v_mfma_f32_16x16x32_bf16 v[0:3], v[212:215], v[180:183], v[0:3]
	v_mfma_f32_16x16x32_bf16 v[4:7], v[204:207], v[180:183], v[4:7]
	v_mfma_f32_16x16x32_bf16 v[4:7], v[200:203], v[176:179], v[4:7]
	v_mfma_f32_16x16x32_bf16 v[64:67], v[200:203], v[184:187], v[64:67]
	v_mfma_f32_16x16x32_bf16 v[64:67], v[204:207], v[188:191], v[64:67]
	v_mfma_f32_16x16x32_bf16 v[72:75], v[212:215], v[188:191], v[72:75]
	v_mfma_f32_16x16x32_bf16 v[72:75], v[208:211], v[184:187], v[72:75]
	v_mfma_f32_16x16x32_bf16 v[84:87], v[208:211], v[192:195], v[84:87]
	v_mfma_f32_16x16x32_bf16 v[84:87], v[212:215], v[196:199], v[84:87]
	v_mfma_f32_16x16x32_bf16 v[76:79], v[204:207], v[196:199], v[76:79]
	v_mfma_f32_16x16x32_bf16 v[76:79], v[200:203], v[192:195], v[76:79]
	s_barrier
	s_add_i32 s1, s86, 0x1f80
	s_mov_b32 m0, s36
	ds_read_b128 v[152:155], v147
	ds_read_b128 v[156:159], v148
	ds_read_b128 v[160:163], v149
	ds_read_b128 v[148:151], v150
	ds_read_b128 v[164:167], v129
	ds_read_b128 v[168:171], v129 offset:1024
	ds_read_b128 v[172:175], v132
	ds_read_b128 v[176:179], v132 offset:1024
	ds_read_b128 v[180:183], v131
	ds_read_b128 v[184:187], v131 offset:1024
	ds_read_b128 v[188:191], v130
	ds_read_b128 v[192:195], v130 offset:1024
	buffer_load_dwordx4 v141, s[8:11], s1 offen lds
	s_mov_b32 m0, s59
	s_nop 0
	buffer_load_dwordx4 v142, s[8:11], s1 offen lds
	s_barrier
	s_waitcnt lgkmcnt(6)
	v_mfma_f32_16x16x32_bf16 v[124:127], v[152:155], v[164:167], v[124:127]
	v_mfma_f32_16x16x32_bf16 v[124:127], v[156:159], v[168:171], v[124:127]
	v_mfma_f32_16x16x32_bf16 v[120:123], v[148:151], v[168:171], v[120:123]
	v_mfma_f32_16x16x32_bf16 v[120:123], v[160:163], v[164:167], v[120:123]
	s_waitcnt lgkmcnt(4)
	v_mfma_f32_16x16x32_bf16 v[112:115], v[160:163], v[172:175], v[112:115]
	v_mfma_f32_16x16x32_bf16 v[112:115], v[148:151], v[176:179], v[112:115]
	v_mfma_f32_16x16x32_bf16 v[116:119], v[156:159], v[176:179], v[116:119]
	v_mfma_f32_16x16x32_bf16 v[116:119], v[152:155], v[172:175], v[116:119]
	s_waitcnt lgkmcnt(2)
	v_mfma_f32_16x16x32_bf16 v[108:111], v[152:155], v[180:183], v[108:111]
	v_mfma_f32_16x16x32_bf16 v[108:111], v[156:159], v[184:187], v[108:111]
	v_mfma_f32_16x16x32_bf16 v[104:107], v[148:151], v[184:187], v[104:107]
	v_mfma_f32_16x16x32_bf16 v[104:107], v[160:163], v[180:183], v[104:107]
	s_waitcnt lgkmcnt(0)
	v_mfma_f32_16x16x32_bf16 v[96:99], v[160:163], v[188:191], v[96:99]
	v_mfma_f32_16x16x32_bf16 v[96:99], v[148:151], v[192:195], v[96:99]
	v_mfma_f32_16x16x32_bf16 v[100:103], v[156:159], v[192:195], v[100:103]
	v_mfma_f32_16x16x32_bf16 v[100:103], v[152:155], v[188:191], v[100:103]
	s_barrier
	ds_read_b128 v[196:199], v143
	ds_read_b128 v[200:203], v144
	ds_read_b128 v[142:145], v145
	ds_read_b128 v[204:207], v146
	s_barrier
	s_waitcnt lgkmcnt(1)
	v_mfma_f32_16x16x32_bf16 v[80:83], v[196:199], v[172:175], v[80:83]
	v_mfma_f32_16x16x32_bf16 v[68:71], v[142:145], v[172:175], v[68:71]
	v_mfma_f32_16x16x32_bf16 v[60:63], v[196:199], v[180:183], v[60:63]
	v_mfma_f32_16x16x32_bf16 v[56:59], v[142:145], v[180:183], v[56:59]
	v_mfma_f32_16x16x32_bf16 v[52:55], v[196:199], v[188:191], v[52:55]
	v_mfma_f32_16x16x32_bf16 v[48:51], v[142:145], v[188:191], v[48:51]
	v_mfma_f32_16x16x32_bf16 v[92:95], v[196:199], v[164:167], v[92:95]
	v_mfma_f32_16x16x32_bf16 v[88:91], v[142:145], v[164:167], v[88:91]
	s_waitcnt lgkmcnt(0)
	v_mfma_f32_16x16x32_bf16 v[80:83], v[200:203], v[176:179], v[80:83]
	v_mfma_f32_16x16x32_bf16 v[68:71], v[204:207], v[176:179], v[68:71]
	v_mfma_f32_16x16x32_bf16 v[60:63], v[200:203], v[184:187], v[60:63]
	v_mfma_f32_16x16x32_bf16 v[56:59], v[204:207], v[184:187], v[56:59]
	v_mfma_f32_16x16x32_bf16 v[52:55], v[200:203], v[192:195], v[52:55]
	v_mfma_f32_16x16x32_bf16 v[48:51], v[204:207], v[192:195], v[48:51]
	v_mfma_f32_16x16x32_bf16 v[164:167], v[200:203], v[168:171], v[92:95]
	v_mfma_f32_16x16x32_bf16 v[168:171], v[204:207], v[168:171], v[88:91]
	s_barrier
	s_nop 0
	ds_read_b128 v[88:91], v129 offset:16384
	ds_read_b128 v[92:95], v129 offset:17408
	ds_read_b128 v[172:175], v132 offset:16384
	ds_read_b128 v[176:179], v132 offset:17408
	ds_read_b128 v[180:183], v131 offset:16384
	ds_read_b128 v[184:187], v131 offset:17408
	ds_read_b128 v[188:191], v130 offset:16384
	ds_read_b128 v[192:195], v130 offset:17408
	s_waitcnt vmcnt(4)
	s_barrier
; #define LDA(dst, b, h) _Pragma("unroll") for (int m = 0; m < 4; ++m) _Pragma("unroll") for (int k = 0; k < 2; ++k) \
;     dst[m][k] = *reinterpret_cast<const bf16x8*>(SA(b, h) + lds_byte(wr * 64 + m * 16 + fr, k * 32 + fq * 8))
; #define LDB(dst, b, h) _Pragma("unroll") for (int n = 0; n < 2; ++n) _Pragma("unroll") for (int k = 0; k < 2; ++k) \
;     dst[n][k] = *reinterpret_cast<const bf16x8*>(SB(b, h) + lds_byte(wc * 32 + n * 16 + fr, k * 32 + fq * 8))
; #define WAIT_V(n) asm volatile("s_waitcnt vmcnt(" #n ")" ::: "memory")
; #define WAIT_L(n) asm volatile("s_waitcnt lgkmcnt(" #n ")" ::: "memory")
; #define BAR __builtin_amdgcn_s_barrier()
;     ...
;       LDA(At, 0, 1); WAIT_V(4); BAR; WAIT_L(0); MMA(1, 0, At, B0); MMA(1, 1, At, B1); BAR; }
;     { LDB(B0, 1, 0); LDA(At, 1, 0); WAIT_V(2); BAR; WAIT_L(0); MMA(0, 0, At, B0); BAR;
	s_waitcnt lgkmcnt(0)
	v_mfma_f32_16x16x32_bf16 v[44:47], v[152:155], v[88:91], v[44:47]
	v_mfma_f32_16x16x32_bf16 v[40:43], v[160:163], v[88:91], v[40:43]
	v_mfma_f32_16x16x32_bf16 v[36:39], v[152:155], v[172:175], v[36:39]
	v_mfma_f32_16x16x32_bf16 v[32:35], v[160:163], v[172:175], v[32:35]
	v_mfma_f32_16x16x32_bf16 v[28:31], v[152:155], v[180:183], v[28:31]
	v_mfma_f32_16x16x32_bf16 v[24:27], v[160:163], v[180:183], v[24:27]
	v_mfma_f32_16x16x32_bf16 v[20:23], v[152:155], v[188:191], v[20:23]
	v_mfma_f32_16x16x32_bf16 v[16:19], v[160:163], v[188:191], v[16:19]
	v_mfma_f32_16x16x32_bf16 v[44:47], v[156:159], v[92:95], v[44:47]
	v_mfma_f32_16x16x32_bf16 v[40:43], v[148:151], v[92:95], v[40:43]
	v_mfma_f32_16x16x32_bf16 v[36:39], v[156:159], v[176:179], v[36:39]
	v_mfma_f32_16x16x32_bf16 v[32:35], v[148:151], v[176:179], v[32:35]
	v_mfma_f32_16x16x32_bf16 v[28:31], v[156:159], v[184:187], v[28:31]
	v_mfma_f32_16x16x32_bf16 v[24:27], v[148:151], v[184:187], v[24:27]
	v_mfma_f32_16x16x32_bf16 v[20:23], v[156:159], v[192:195], v[20:23]
	v_mfma_f32_16x16x32_bf16 v[16:19], v[148:151], v[192:195], v[16:19]
	v_mfma_f32_16x16x32_bf16 v[4:7], v[196:199], v[172:175], v[4:7]
	v_mfma_f32_16x16x32_bf16 v[0:3], v[142:145], v[172:175], v[0:3]
	v_mfma_f32_16x16x32_bf16 v[12:15], v[196:199], v[88:91], v[12:15]
	v_mfma_f32_16x16x32_bf16 v[8:11], v[142:145], v[88:91], v[8:11]
	v_mfma_f32_16x16x32_bf16 v[64:67], v[196:199], v[180:183], v[64:67]
	v_mfma_f32_16x16x32_bf16 v[72:75], v[142:145], v[180:183], v[72:75]
	v_mfma_f32_16x16x32_bf16 v[76:79], v[196:199], v[188:191], v[76:79]
	v_mfma_f32_16x16x32_bf16 v[84:87], v[142:145], v[188:191], v[84:87]
	v_mfma_f32_16x16x32_bf16 v[4:7], v[200:203], v[176:179], v[4:7]
	v_mfma_f32_16x16x32_bf16 v[0:3], v[204:207], v[176:179], v[0:3]
	v_mfma_f32_16x16x32_bf16 v[142:145], v[200:203], v[92:95], v[12:15]
	v_mfma_f32_16x16x32_bf16 v[146:149], v[204:207], v[92:95], v[8:11]
	v_mfma_f32_16x16x32_bf16 v[150:153], v[200:203], v[184:187], v[64:67]
	v_mfma_f32_16x16x32_bf16 v[154:157], v[204:207], v[184:187], v[72:75]
	v_mfma_f32_16x16x32_bf16 v[158:161], v[200:203], v[192:195], v[76:79]
	v_mfma_f32_16x16x32_bf16 v[172:175], v[204:207], v[192:195], v[84:87]
	s_barrier
	ds_read_b128 v[8:11], v137
	ds_read_b128 v[12:15], v138
	ds_read_b128 v[176:179], v139
	ds_read_b128 v[138:141], v140
	ds_read_b128 v[64:67], v129 offset:32768
	ds_read_b128 v[84:87], v129 offset:33792
	ds_read_b128 v[180:183], v132 offset:32768
	ds_read_b128 v[184:187], v132 offset:33792
	ds_read_b128 v[188:191], v131 offset:32768
	ds_read_b128 v[192:195], v131 offset:33792
	ds_read_b128 v[196:199], v130 offset:32768
	ds_read_b128 v[200:203], v130 offset:33792
	s_waitcnt vmcnt(2)
	s_barrier
	s_waitcnt lgkmcnt(7)
	v_mfma_f32_16x16x32_bf16 v[72:75], v[8:11], v[64:67], v[124:127]
	v_mfma_f32_16x16x32_bf16 v[76:79], v[176:179], v[64:67], v[120:123]
	s_waitcnt lgkmcnt(5)
	v_mfma_f32_16x16x32_bf16 v[88:91], v[8:11], v[180:183], v[116:119]
	v_mfma_f32_16x16x32_bf16 v[92:95], v[176:179], v[180:183], v[112:115]
	s_waitcnt lgkmcnt(3)
	v_mfma_f32_16x16x32_bf16 v[112:115], v[8:11], v[188:191], v[108:111]
	v_mfma_f32_16x16x32_bf16 v[120:123], v[176:179], v[188:191], v[104:107]
	s_waitcnt lgkmcnt(1)
	v_mfma_f32_16x16x32_bf16 v[100:103], v[8:11], v[196:199], v[100:103]
	v_mfma_f32_16x16x32_bf16 v[96:99], v[176:179], v[196:199], v[96:99]
	v_mfma_f32_16x16x32_bf16 v[124:127], v[12:15], v[84:87], v[72:75]
	v_mfma_f32_16x16x32_bf16 v[116:119], v[138:141], v[84:87], v[76:79]
	v_mfma_f32_16x16x32_bf16 v[108:111], v[12:15], v[184:187], v[88:91]
	v_mfma_f32_16x16x32_bf16 v[104:107], v[138:141], v[184:187], v[92:95]
	v_mfma_f32_16x16x32_bf16 v[92:95], v[12:15], v[192:195], v[112:115]
	v_mfma_f32_16x16x32_bf16 v[88:91], v[138:141], v[192:195], v[120:123]
	s_waitcnt lgkmcnt(0)
	v_mfma_f32_16x16x32_bf16 v[76:79], v[12:15], v[200:203], v[100:103]
	v_mfma_f32_16x16x32_bf16 v[72:75], v[138:141], v[200:203], v[96:99]
	s_barrier
; #define LDA(dst, b, h) _Pragma("unroll") for (int m = 0; m < 4; ++m) _Pragma("unroll") for (int k = 0; k < 2; ++k) \
;     dst[m][k] = *reinterpret_cast<const bf16x8*>(SA(b, h) + lds_byte(wr * 64 + m * 16 + fr, k * 32 + fq * 8))
; #define LDB(dst, b, h) _Pragma("unroll") for (int n = 0; n < 2; ++n) _Pragma("unroll") for (int k = 0; k < 2; ++k) \
;     dst[n][k] = *reinterpret_cast<const bf16x8*>(SB(b, h) + lds_byte(wc * 32 + n * 16 + fr, k * 32 + fq * 8))
; #define WAIT_V(n) asm volatile("s_waitcnt vmcnt(" #n ")" ::: "memory")
; #define WAIT_L(n) asm volatile("s_waitcnt lgkmcnt(" #n ")" ::: "memory")
; #define BAR __builtin_amdgcn_s_barrier()
;     ...
;       LDB(B1, 1, 1); WAIT_V(0); BAR; WAIT_L(0); MMA(0, 1, At, B1); BAR;
;       LDA(At, 1, 1); BAR; WAIT_L(0); MMA(1, 0, At, B0); MMA(1, 1, At, B1); BAR; }
;     if (wr == 0) BAR;
	ds_read_b128 v[204:207], v133
	ds_read_b128 v[208:211], v134
	ds_read_b128 v[212:215], v135
	ds_read_b128 v[134:137], v136
	s_waitcnt vmcnt(0)
	s_barrier
	s_waitcnt lgkmcnt(1)
	v_mfma_f32_16x16x32_bf16 v[96:99], v[204:207], v[64:67], v[164:167]
	v_mfma_f32_16x16x32_bf16 v[64:67], v[212:215], v[64:67], v[168:171]
	v_mfma_f32_16x16x32_bf16 v[80:83], v[204:207], v[180:183], v[80:83]
	v_mfma_f32_16x16x32_bf16 v[68:71], v[212:215], v[180:183], v[68:71]
	v_mfma_f32_16x16x32_bf16 v[60:63], v[204:207], v[188:191], v[60:63]
	v_mfma_f32_16x16x32_bf16 v[56:59], v[212:215], v[188:191], v[56:59]
	v_mfma_f32_16x16x32_bf16 v[52:55], v[204:207], v[196:199], v[52:55]
	v_mfma_f32_16x16x32_bf16 v[48:51], v[212:215], v[196:199], v[48:51]
	s_waitcnt lgkmcnt(0)
	v_mfma_f32_16x16x32_bf16 v[120:123], v[208:211], v[84:87], v[96:99]
	v_mfma_f32_16x16x32_bf16 v[112:115], v[134:137], v[84:87], v[64:67]
	v_mfma_f32_16x16x32_bf16 v[100:103], v[208:211], v[184:187], v[80:83]
	v_mfma_f32_16x16x32_bf16 v[96:99], v[134:137], v[184:187], v[68:71]
	v_mfma_f32_16x16x32_bf16 v[84:87], v[208:211], v[192:195], v[60:63]
	v_mfma_f32_16x16x32_bf16 v[80:83], v[134:137], v[192:195], v[56:59]
	v_mfma_f32_16x16x32_bf16 v[68:71], v[208:211], v[200:203], v[52:55]
	v_mfma_f32_16x16x32_bf16 v[64:67], v[134:137], v[200:203], v[48:51]
	s_barrier
	s_nop 0
	ds_read_b128 v[48:51], v129 offset:49152
	ds_read_b128 v[162:165], v129 offset:50176
	ds_read_b128 v[52:55], v132 offset:49152
	ds_read_b128 v[166:169], v132 offset:50176
	ds_read_b128 v[180:183], v131 offset:49152
	ds_read_b128 v[184:187], v131 offset:50176
	ds_read_b128 v[188:191], v130 offset:49152
	ds_read_b128 v[130:133], v130 offset:50176
	s_barrier
	s_waitcnt lgkmcnt(0)
	v_mfma_f32_16x16x32_bf16 v[44:47], v[8:11], v[48:51], v[44:47]
	v_mfma_f32_16x16x32_bf16 v[40:43], v[176:179], v[48:51], v[40:43]
	v_mfma_f32_16x16x32_bf16 v[36:39], v[8:11], v[52:55], v[36:39]
	v_mfma_f32_16x16x32_bf16 v[32:35], v[176:179], v[52:55], v[32:35]
	v_mfma_f32_16x16x32_bf16 v[28:31], v[8:11], v[180:183], v[28:31]
	v_mfma_f32_16x16x32_bf16 v[24:27], v[176:179], v[180:183], v[24:27]
	v_mfma_f32_16x16x32_bf16 v[8:11], v[8:11], v[188:191], v[20:23]
	v_mfma_f32_16x16x32_bf16 v[16:19], v[176:179], v[188:191], v[16:19]
	v_mfma_f32_16x16x32_bf16 v[60:63], v[12:15], v[162:165], v[44:47]
	v_mfma_f32_16x16x32_bf16 v[56:59], v[138:141], v[162:165], v[40:43]
	v_mfma_f32_16x16x32_bf16 v[44:47], v[12:15], v[166:169], v[36:39]
	v_mfma_f32_16x16x32_bf16 v[40:43], v[138:141], v[166:169], v[32:35]
	v_mfma_f32_16x16x32_bf16 v[28:31], v[12:15], v[184:187], v[28:31]
	v_mfma_f32_16x16x32_bf16 v[24:27], v[138:141], v[184:187], v[24:27]
	v_mfma_f32_16x16x32_bf16 v[12:15], v[12:15], v[130:133], v[8:11]
	v_mfma_f32_16x16x32_bf16 v[8:11], v[138:141], v[130:133], v[16:19]
	v_mfma_f32_16x16x32_bf16 v[16:19], v[204:207], v[48:51], v[142:145]
	v_mfma_f32_16x16x32_bf16 v[20:23], v[212:215], v[48:51], v[146:149]
	v_mfma_f32_16x16x32_bf16 v[4:7], v[204:207], v[52:55], v[4:7]
	v_mfma_f32_16x16x32_bf16 v[0:3], v[212:215], v[52:55], v[0:3]
	v_mfma_f32_16x16x32_bf16 v[138:141], v[204:207], v[180:183], v[150:153]
	v_mfma_f32_16x16x32_bf16 v[142:145], v[212:215], v[180:183], v[154:157]
	v_mfma_f32_16x16x32_bf16 v[146:149], v[204:207], v[188:191], v[158:161]
	v_mfma_f32_16x16x32_bf16 v[150:153], v[212:215], v[188:191], v[172:175]
	v_mfma_f32_16x16x32_bf16 v[52:55], v[208:211], v[162:165], v[16:19]
	v_mfma_f32_16x16x32_bf16 v[48:51], v[134:137], v[162:165], v[20:23]
	v_mfma_f32_16x16x32_bf16 v[36:39], v[208:211], v[166:169], v[4:7]
	v_mfma_f32_16x16x32_bf16 v[32:35], v[134:137], v[166:169], v[0:3]
	v_mfma_f32_16x16x32_bf16 v[20:23], v[208:211], v[184:187], v[138:141]
	v_mfma_f32_16x16x32_bf16 v[16:19], v[134:137], v[184:187], v[142:145]
	v_mfma_f32_16x16x32_bf16 v[4:7], v[208:211], v[130:133], v[146:149]
	v_mfma_f32_16x16x32_bf16 v[0:3], v[134:137], v[130:133], v[150:153]
	v_cmp_gt_u32_e32 vcc, s40, v128
	s_barrier
	s_and_saveexec_b64 s[6:7], vcc
	s_cbranch_execz .LBB0_395
	s_barrier

; #define STAGE(P, RS, SOFF, OFF, kt) do { const int _so = (SOFF) + (kt) * (BK * 2); \
;     _Pragma("unroll") for (int _i = 0; _i < 2; ++_i) { \
;       __builtin_amdgcn_raw_ptr_buffer_load_lds(RS, (__attribute__((address_space(3))) void*)((P) + wave * 1024 + _i * 8192), 16, OFF[_i], _so, 0, 0); } } while (0)
; #define LDA(dst, b, h) _Pragma("unroll") for (int m = 0; m < 4; ++m) _Pragma("unroll") for (int k = 0; k < 2; ++k) \
;     dst[m][k] = *reinterpret_cast<const bf16x8*>(SA(b, h) + lds_byte(wr * 64 + m * 16 + fr, k * 32 + fq * 8))
; #define LDB(dst, b, h) _Pragma("unroll") for (int n = 0; n < 2; ++n) _Pragma("unroll") for (int k = 0; k < 2; ++k) \
;     dst[n][k] = *reinterpret_cast<const bf16x8*>(SB(b, h) + lds_byte(wc * 32 + n * 16 + fr, k * 32 + fq * 8))
; #define WAIT_V(n) asm volatile("s_waitcnt vmcnt(" #n ")" ::: "memory")
; #define WAIT_L(n) asm volatile("s_waitcnt lgkmcnt(" #n ")" ::: "memory")
; #define BAR __builtin_amdgcn_s_barrier()
; #define SCHED __builtin_amdgcn_sched_barrier(0)
;     ...
;     const int tid = opaque_tid(wave);
;     const int wid = tid >> 6, lane = tid & 63, wr = wid >> 2, wc = wid & 3, fr = lane & 15, fq = lane >> 4;
;     int offA[2], offB[2];
;     _Pragma("unroll") for (int i = 0; i < 2; ++i) {
;       int r, c; stage_rc(tid * 16 + i * 8192, r, c);
;       offA[i] = (r * lda + c) * 2; offB[i] = (r * ldb + c) * 2;
;     }
;     const int brow = pm * BM;
;     f32x4 acc[2][2][4][2];
;     _Pragma("unroll") for (int a = 0; a < 2; ++a) _Pragma("unroll") for (int b = 0; b < 2; ++b) _Pragma("unroll") for (int m = 0; m < 4; ++m) _Pragma("unroll") for (int n = 0; n < 2; ++n)
;       acc[a][b][m][n] = f32x4{0.f, 0.f, 0.f, 0.f};
;     bf16x8 At[4][2], B0[2][2], B1[2][2];
;     if (wr == 1) BAR;
;     if (first_tile) { WAIT_V(0); }
;     else if constexpr (mode == MODE_RESID_LN) { WAIT_V(0); }
;     else if constexpr (mode == MODE_SWIGLU) { WAIT_V(6); }
;     else if constexpr (mode == MODE_V) { WAIT_V(24); }
;     else { WAIT_V(12); }
;     first_tile = false;
;     BAR;
;     BAR;
;     for (int t = 0; t < nt - 2; t += 2) {
;       LDB(B0, 0, 0); SCHED; LDA(At, 0, 0); STAGE(SA(1, 1), rsA, sA1, offA, t + 1);
;       WAIT_L(8); BAR; WAIT_L(0); MMA(0, 0, At, B0); BAR; SCHED;
.LBB0_493:
	v_bfe_i32 v4, v128, 27, 1
	v_lshlrev_b32_e32 v2, 4, v128
	v_lshrrev_b32_e32 v4, 22, v4
	v_add_u32_e32 v4, v2, v4
	v_and_b32_e32 v4, 0xfffffc00, v4
	v_sub_u32_e32 v4, v2, v4
	v_lshrrev_b32_e32 v5, 4, v4
	v_bitop3_b32 v4, v5, v4, 32 bitop3:0x6c
	v_ashrrev_i32_e32 v3, 31, v128
	v_ashrrev_i32_e32 v6, 31, v4
	v_lshrrev_b32_e32 v3, 26, v3
	v_lshrrev_b32_e32 v6, 26, v6
	v_add_u32_e32 v3, v128, v3
	v_add_u32_e32 v6, v4, v6
	v_ashrrev_i32_e32 v3, 6, v3
	v_lshrrev_b32_e32 v7, 6, v6
	v_and_b32_e32 v6, 0xc0, v6
	v_lshlrev_b32_e32 v5, 3, v3
	v_lshlrev_b32_e32 v3, 5, v3
	v_sub_u32_e32 v4, v4, v6
	v_and_b32_e32 v5, 0x7fff0, v5
	v_and_b32_e32 v3, 32, v3
	v_ashrrev_i16_sdwa v4, v216, sext(v4) dst_sel:DWORD dst_unused:UNUSED_PAD src0_sel:DWORD src1_sel:BYTE_0
	v_add_u32_sdwa v3, v3, sext(v4) dst_sel:DWORD dst_unused:UNUSED_PAD src0_sel:DWORD src1_sel:WORD_0
	v_add_lshl_u32 v4, v7, v5, 13
	v_add_u32_e32 v2, 0x2000, v2
	v_lshl_add_u32 v141, v3, 1, v4
	v_ashrrev_i32_e32 v3, 31, v2
	v_lshrrev_b32_e32 v3, 22, v3
	v_add_u32_e32 v3, v2, v3
	v_ashrrev_i32_e32 v3, 10, v3
	v_mul_i32_i24_e32 v4, 0x400, v3
	v_sub_u32_e32 v2, v2, v4
	v_lshrrev_b32_e32 v4, 4, v2
	v_bitop3_b32 v2, v4, v2, 32 bitop3:0x6c
	v_ashrrev_i32_e32 v5, 31, v2
	v_lshrrev_b32_e32 v5, 26, v5
	v_add_u32_e32 v5, v2, v5
	v_lshrrev_b32_e32 v6, 6, v5
	v_and_b32_e32 v5, 0xc0, v5
	v_lshlrev_b32_e32 v4, 3, v3
	v_lshlrev_b32_e32 v3, 5, v3
	v_sub_u32_e32 v2, v2, v5
	v_and_b32_e32 v4, 0x7fff0, v4
	v_and_b32_e32 v3, 32, v3
	v_ashrrev_i16_sdwa v2, v216, sext(v2) dst_sel:DWORD dst_unused:UNUSED_PAD src0_sel:DWORD src1_sel:BYTE_0
	v_add_u32_sdwa v2, v3, sext(v2) dst_sel:DWORD dst_unused:UNUSED_PAD src0_sel:DWORD src1_sel:WORD_0
	v_add_lshl_u32 v3, v6, v4, 13
	v_lshl_add_u32 v142, v2, 1, v3
	v_and_b32_e32 v3, 15, v0
	v_lshlrev_b32_e32 v5, 2, v0
	v_and_b32_e32 v2, 48, v0
	v_lshlrev_b32_e32 v3, 6, v3
	v_and_b32_e32 v5, 32, v5
	v_or_b32_e32 v4, v3, v2
	v_bitop3_b32 v3, v3, v5, v2 bitop3:0x36
	v_lshlrev_b32_e32 v6, 6, v128
	s_movk_i32 s1, 0x3000
	v_and_or_b32 v3, v6, s1, v3
	v_lshlrev_b32_e32 v0, 6, v0
	s_movk_i32 s1, 0x3c0
	v_lshlrev_b32_e32 v1, 13, v1
	v_and_or_b32 v0, v0, s1, v2
	v_bitop3_b32 v0, v1, v0, v5 bitop3:0xf6
	v_or_b32_e32 v6, 0x400, v3
	v_or_b32_e32 v7, 0x800, v3
	v_or_b32_e32 v8, 0xc00, v3
	v_or_b32_e32 v132, 0x800, v0
	v_or_b32_e32 v131, 0x1000, v0
	v_or_b32_e32 v130, 0x1800, v0
	v_mov_b32_e32 v0, 0
	v_bitop3_b32 v129, v4, v1, v5 bitop3:0xde
	s_mov_b32 s1, -2
	s_mov_b32 s3, 0
	v_or_b32_e32 v147, 0x10000, v3
	v_or_b32_e32 v148, 0x10000, v6
	v_or_b32_e32 v149, 0x10000, v7
	v_or_b32_e32 v150, 0x10000, v8
	v_or_b32_e32 v143, 0x14000, v3
	v_or_b32_e32 v144, 0x14000, v6
	v_or_b32_e32 v145, 0x14000, v7
	v_or_b32_e32 v146, 0x14000, v8
	v_or_b32_e32 v137, 0x18000, v3
	v_or_b32_e32 v138, 0x18000, v6
	v_or_b32_e32 v139, 0x18000, v7
	v_or_b32_e32 v140, 0x18000, v8
	v_or_b32_e32 v133, 0x1c000, v3
	v_or_b32_e32 v134, 0x1c000, v6
	v_or_b32_e32 v135, 0x1c000, v7
	v_or_b32_e32 v136, 0x1c000, v8
	s_barrier
	s_barrier
	ds_read_b128 v[152:155], v147
	ds_read_b128 v[156:159], v148
	ds_read_b128 v[160:163], v149
	ds_read_b128 v[164:167], v150
	s_add_i32 s5, s82, s3
	s_add_i32 s6, s5, 0x80
	s_mov_b32 m0, s36
	ds_read_b128 v[168:171], v129
	ds_read_b128 v[172:175], v129 offset:1024
	ds_read_b128 v[176:179], v132
	ds_read_b128 v[180:183], v132 offset:1024
	ds_read_b128 v[184:187], v131
	ds_read_b128 v[188:191], v131 offset:1024
	ds_read_b128 v[192:195], v130
	ds_read_b128 v[196:199], v130 offset:1024
	buffer_load_dwordx4 v141, s[8:11], s6 offen lds
	s_mov_b32 m0, s59
	s_nop 0
	buffer_load_dwordx4 v142, s[8:11], s6 offen lds
	s_waitcnt lgkmcnt(8)
	s_barrier
	s_waitcnt lgkmcnt(0)
	v_mfma_f32_16x16x32_bf16 v[124:127], v[152:155], v[168:171], 0
	v_mfma_f32_16x16x32_bf16 v[124:127], v[156:159], v[172:175], v[124:127]
	v_mfma_f32_16x16x32_bf16 v[120:123], v[164:167], v[172:175], 0
	v_mfma_f32_16x16x32_bf16 v[120:123], v[160:163], v[168:171], v[120:123]
	v_mfma_f32_16x16x32_bf16 v[112:115], v[160:163], v[176:179], 0
	v_mfma_f32_16x16x32_bf16 v[112:115], v[164:167], v[180:183], v[112:115]
	v_mfma_f32_16x16x32_bf16 v[116:119], v[156:159], v[180:183], 0
	v_mfma_f32_16x16x32_bf16 v[116:119], v[152:155], v[176:179], v[116:119]
	v_mfma_f32_16x16x32_bf16 v[108:111], v[152:155], v[184:187], 0
	v_mfma_f32_16x16x32_bf16 v[108:111], v[156:159], v[188:191], v[108:111]
	v_mfma_f32_16x16x32_bf16 v[104:107], v[164:167], v[188:191], 0
	v_mfma_f32_16x16x32_bf16 v[104:107], v[160:163], v[184:187], v[104:107]
	v_mfma_f32_16x16x32_bf16 v[96:99], v[160:163], v[192:195], 0
	v_mfma_f32_16x16x32_bf16 v[96:99], v[164:167], v[196:199], v[96:99]
	v_mfma_f32_16x16x32_bf16 v[100:103], v[156:159], v[196:199], 0
	v_mfma_f32_16x16x32_bf16 v[100:103], v[152:155], v[192:195], v[100:103]
	s_barrier
	s_add_i32 s6, s84, s3
	s_add_i32 s7, s6, 0x100
	s_mov_b32 s14, s10
	s_mov_b32 s15, s11
	s_mov_b32 m0, s37
	ds_read_b128 v[200:203], v143
	ds_read_b128 v[204:207], v144
	ds_read_b128 v[208:211], v145
	ds_read_b128 v[212:215], v146
	buffer_load_dwordx4 v141, s[12:15], s7 offen lds
	s_mov_b32 m0, s70
	s_nop 0
	buffer_load_dwordx4 v142, s[12:15], s7 offen lds
	s_barrier
; #define STAGE(P, RS, SOFF, OFF, kt) do { const int _so = (SOFF) + (kt) * (BK * 2); \
;     _Pragma("unroll") for (int _i = 0; _i < 2; ++_i) { \
;       __builtin_amdgcn_raw_ptr_buffer_load_lds(RS, (__attribute__((address_space(3))) void*)((P) + wave * 1024 + _i * 8192), 16, OFF[_i], _so, 0, 0); } } while (0)
; #define LDA(dst, b, h) _Pragma("unroll") for (int m = 0; m < 4; ++m) _Pragma("unroll") for (int k = 0; k < 2; ++k) \
;     dst[m][k] = *reinterpret_cast<const bf16x8*>(SA(b, h) + lds_byte(wr * 64 + m * 16 + fr, k * 32 + fq * 8))
; #define LDB(dst, b, h) _Pragma("unroll") for (int n = 0; n < 2; ++n) _Pragma("unroll") for (int k = 0; k < 2; ++k) \
;     dst[n][k] = *reinterpret_cast<const bf16x8*>(SB(b, h) + lds_byte(wc * 32 + n * 16 + fr, k * 32 + fq * 8))
; #define WAIT_V(n) asm volatile("s_waitcnt vmcnt(" #n ")" ::: "memory")
; #define WAIT_L(n) asm volatile("s_waitcnt lgkmcnt(" #n ")" ::: "memory")
; #define BAR __builtin_amdgcn_s_barrier()
; #define SCHED __builtin_amdgcn_sched_barrier(0)
;     ...
;       WAIT_L(8); BAR; WAIT_L(0); MMA(0, 0, At, B0); BAR; SCHED;
;       LDB(B1, 0, 1); STAGE(SB(0, 0), rsB, sB0, offB, t + 2);
;       BAR; WAIT_L(0); MMA(0, 1, At, B1); BAR;
;       LDA(At, 0, 1); STAGE(SA(0, 0), rsA, sA0, offA, t + 2);
;       BAR; WAIT_L(0); MMA(1, 0, At, B0); BAR; SCHED;
;       STAGE(SB(0, 1), rsB, sB1, offB, t + 2);
;       WAIT_V(6); BAR; MMA(1, 1, At, B1); BAR;
;       LDB(B0, 1, 0); SCHED; LDA(At, 1, 0); STAGE(SA(0, 1), rsA, sA1, offA, t + 2);
	s_waitcnt lgkmcnt(2)
	v_mfma_f32_16x16x32_bf16 v[92:95], v[200:203], v[168:171], 0
	v_mfma_f32_16x16x32_bf16 v[92:95], v[204:207], v[172:175], v[92:95]
	s_waitcnt lgkmcnt(0)
	v_mfma_f32_16x16x32_bf16 v[88:91], v[212:215], v[172:175], 0
	v_mfma_f32_16x16x32_bf16 v[88:91], v[208:211], v[168:171], v[88:91]
	v_mfma_f32_16x16x32_bf16 v[68:71], v[208:211], v[176:179], 0
	v_mfma_f32_16x16x32_bf16 v[68:71], v[212:215], v[180:183], v[68:71]
	v_mfma_f32_16x16x32_bf16 v[80:83], v[204:207], v[180:183], 0
	v_mfma_f32_16x16x32_bf16 v[80:83], v[200:203], v[176:179], v[80:83]
	v_mfma_f32_16x16x32_bf16 v[60:63], v[200:203], v[184:187], 0
	v_mfma_f32_16x16x32_bf16 v[60:63], v[204:207], v[188:191], v[60:63]
	v_mfma_f32_16x16x32_bf16 v[56:59], v[212:215], v[188:191], 0
	v_mfma_f32_16x16x32_bf16 v[56:59], v[208:211], v[184:187], v[56:59]
	v_mfma_f32_16x16x32_bf16 v[48:51], v[208:211], v[192:195], 0
	v_mfma_f32_16x16x32_bf16 v[48:51], v[212:215], v[196:199], v[48:51]
	v_mfma_f32_16x16x32_bf16 v[52:55], v[204:207], v[196:199], 0
	v_mfma_f32_16x16x32_bf16 v[52:55], v[200:203], v[192:195], v[52:55]
	s_barrier
	s_add_i32 s7, s83, s3
	s_add_i32 s22, s7, 0x100
	s_mov_b32 m0, s35
	ds_read_b128 v[168:171], v129 offset:16384
	ds_read_b128 v[172:175], v129 offset:17408
	ds_read_b128 v[176:179], v132 offset:16384
	ds_read_b128 v[180:183], v132 offset:17408
	ds_read_b128 v[184:187], v131 offset:16384
	ds_read_b128 v[188:191], v131 offset:17408
	ds_read_b128 v[192:195], v130 offset:16384
	ds_read_b128 v[196:199], v130 offset:17408
	buffer_load_dwordx4 v141, s[8:11], s22 offen lds
	s_mov_b32 m0, s95
	s_nop 0
	buffer_load_dwordx4 v142, s[8:11], s22 offen lds
	s_barrier
	s_waitcnt lgkmcnt(6)
	v_mfma_f32_16x16x32_bf16 v[44:47], v[152:155], v[168:171], 0
	v_mfma_f32_16x16x32_bf16 v[44:47], v[156:159], v[172:175], v[44:47]
	v_mfma_f32_16x16x32_bf16 v[40:43], v[164:167], v[172:175], 0
	v_mfma_f32_16x16x32_bf16 v[40:43], v[160:163], v[168:171], v[40:43]
	s_waitcnt lgkmcnt(4)
	v_mfma_f32_16x16x32_bf16 v[32:35], v[160:163], v[176:179], 0
	v_mfma_f32_16x16x32_bf16 v[32:35], v[164:167], v[180:183], v[32:35]
	v_mfma_f32_16x16x32_bf16 v[36:39], v[156:159], v[180:183], 0
	v_mfma_f32_16x16x32_bf16 v[36:39], v[152:155], v[176:179], v[36:39]
	s_waitcnt lgkmcnt(2)
	v_mfma_f32_16x16x32_bf16 v[28:31], v[152:155], v[184:187], 0
	v_mfma_f32_16x16x32_bf16 v[28:31], v[156:159], v[188:191], v[28:31]
	v_mfma_f32_16x16x32_bf16 v[24:27], v[164:167], v[188:191], 0
	v_mfma_f32_16x16x32_bf16 v[24:27], v[160:163], v[184:187], v[24:27]
	s_waitcnt lgkmcnt(0)
	v_mfma_f32_16x16x32_bf16 v[16:19], v[160:163], v[192:195], 0
	v_mfma_f32_16x16x32_bf16 v[16:19], v[164:167], v[196:199], v[16:19]
	v_mfma_f32_16x16x32_bf16 v[20:23], v[156:159], v[196:199], 0
	v_mfma_f32_16x16x32_bf16 v[20:23], v[152:155], v[192:195], v[20:23]
	s_barrier
	s_add_i32 s22, s85, s3
	s_add_i32 s23, s22, 0x100
	s_mov_b32 m0, s38
	s_nop 0
	buffer_load_dwordx4 v141, s[12:15], s23 offen lds
	s_mov_b32 m0, s71
	s_nop 0
	buffer_load_dwordx4 v142, s[12:15], s23 offen lds
	s_waitcnt vmcnt(6)
	s_barrier
	v_mfma_f32_16x16x32_bf16 v[12:15], v[200:203], v[168:171], 0
	v_mfma_f32_16x16x32_bf16 v[12:15], v[204:207], v[172:175], v[12:15]
	v_mfma_f32_16x16x32_bf16 v[8:11], v[212:215], v[172:175], 0
	v_mfma_f32_16x16x32_bf16 v[8:11], v[208:211], v[168:171], v[8:11]
	v_mfma_f32_16x16x32_bf16 v[0:3], v[208:211], v[176:179], 0
	v_mfma_f32_16x16x32_bf16 v[0:3], v[212:215], v[180:183], v[0:3]
	v_mfma_f32_16x16x32_bf16 v[4:7], v[204:207], v[180:183], 0
	v_mfma_f32_16x16x32_bf16 v[4:7], v[200:203], v[176:179], v[4:7]
	v_mfma_f32_16x16x32_bf16 v[64:67], v[200:203], v[184:187], 0
	v_mfma_f32_16x16x32_bf16 v[64:67], v[204:207], v[188:191], v[64:67]
	v_mfma_f32_16x16x32_bf16 v[72:75], v[212:215], v[188:191], 0
	v_mfma_f32_16x16x32_bf16 v[72:75], v[208:211], v[184:187], v[72:75]
	v_mfma_f32_16x16x32_bf16 v[84:87], v[208:211], v[192:195], 0
	v_mfma_f32_16x16x32_bf16 v[84:87], v[212:215], v[196:199], v[84:87]
	v_mfma_f32_16x16x32_bf16 v[76:79], v[204:207], v[196:199], 0
	v_mfma_f32_16x16x32_bf16 v[76:79], v[200:203], v[192:195], v[76:79]
	s_barrier
	ds_read_b128 v[152:155], v137
	ds_read_b128 v[156:159], v138
	ds_read_b128 v[160:163], v139
	ds_read_b128 v[164:167], v140
	s_addk_i32 s5, 0x100
	s_mov_b32 m0, s39
	ds_read_b128 v[168:171], v129 offset:32768
	ds_read_b128 v[172:175], v129 offset:33792
	ds_read_b128 v[176:179], v132 offset:32768
	ds_read_b128 v[180:183], v132 offset:33792
	ds_read_b128 v[184:187], v131 offset:32768
	ds_read_b128 v[188:191], v131 offset:33792
	ds_read_b128 v[192:195], v130 offset:32768
	ds_read_b128 v[196:199], v130 offset:33792
	buffer_load_dwordx4 v141, s[8:11], s5 offen lds
	s_mov_b32 m0, s97
	s_nop 0
	buffer_load_dwordx4 v142, s[8:11], s5 offen lds
	s_waitcnt lgkmcnt(8)
	s_barrier
; #define STAGE(P, RS, SOFF, OFF, kt) do { const int _so = (SOFF) + (kt) * (BK * 2); \
;     _Pragma("unroll") for (int _i = 0; _i < 2; ++_i) { \
;       __builtin_amdgcn_raw_ptr_buffer_load_lds(RS, (__attribute__((address_space(3))) void*)((P) + wave * 1024 + _i * 8192), 16, OFF[_i], _so, 0, 0); } } while (0)
; #define LDA(dst, b, h) _Pragma("unroll") for (int m = 0; m < 4; ++m) _Pragma("unroll") for (int k = 0; k < 2; ++k) \
;     dst[m][k] = *reinterpret_cast<const bf16x8*>(SA(b, h) + lds_byte(wr * 64 + m * 16 + fr, k * 32 + fq * 8))
; #define LDB(dst, b, h) _Pragma("unroll") for (int n = 0; n < 2; ++n) _Pragma("unroll") for (int k = 0; k < 2; ++k) \
;     dst[n][k] = *reinterpret_cast<const bf16x8*>(SB(b, h) + lds_byte(wc * 32 + n * 16 + fr, k * 32 + fq * 8))
; #define WAIT_L(n) asm volatile("s_waitcnt lgkmcnt(" #n ")" ::: "memory")
; #define BAR __builtin_amdgcn_s_barrier()
; #define SCHED __builtin_amdgcn_sched_barrier(0)
;     ...
;       WAIT_L(8); BAR; WAIT_L(0); MMA(0, 0, At, B0); BAR; SCHED;
;       LDB(B1, 1, 1); STAGE(SB(1, 0), rsB, sB0, offB, t + 3);
;       BAR; WAIT_L(0); MMA(0, 1, At, B1); BAR;
;       LDA(At, 1, 1); STAGE(SA(1, 0), rsA, sA0, offA, t + 3);
;       BAR; WAIT_L(0); MMA(1, 0, At, B0); BAR; SCHED;
;       STAGE(SB(1, 1), rsB, sB1, offB, t + 3);
	s_waitcnt lgkmcnt(6)
	v_mfma_f32_16x16x32_bf16 v[124:127], v[152:155], v[168:171], v[124:127]
	v_mfma_f32_16x16x32_bf16 v[124:127], v[156:159], v[172:175], v[124:127]
	v_mfma_f32_16x16x32_bf16 v[120:123], v[164:167], v[172:175], v[120:123]
	v_mfma_f32_16x16x32_bf16 v[120:123], v[160:163], v[168:171], v[120:123]
	s_waitcnt lgkmcnt(4)
	v_mfma_f32_16x16x32_bf16 v[112:115], v[160:163], v[176:179], v[112:115]
	v_mfma_f32_16x16x32_bf16 v[112:115], v[164:167], v[180:183], v[112:115]
	v_mfma_f32_16x16x32_bf16 v[116:119], v[156:159], v[180:183], v[116:119]
	v_mfma_f32_16x16x32_bf16 v[116:119], v[152:155], v[176:179], v[116:119]
	s_waitcnt lgkmcnt(2)
	v_mfma_f32_16x16x32_bf16 v[108:111], v[152:155], v[184:187], v[108:111]
	v_mfma_f32_16x16x32_bf16 v[108:111], v[156:159], v[188:191], v[108:111]
	v_mfma_f32_16x16x32_bf16 v[104:107], v[164:167], v[188:191], v[104:107]
	v_mfma_f32_16x16x32_bf16 v[104:107], v[160:163], v[184:187], v[104:107]
	s_waitcnt lgkmcnt(0)
	v_mfma_f32_16x16x32_bf16 v[96:99], v[160:163], v[192:195], v[96:99]
	v_mfma_f32_16x16x32_bf16 v[96:99], v[164:167], v[196:199], v[96:99]
	v_mfma_f32_16x16x32_bf16 v[100:103], v[156:159], v[196:199], v[100:103]
	v_mfma_f32_16x16x32_bf16 v[100:103], v[152:155], v[192:195], v[100:103]
	s_barrier
	s_addk_i32 s6, 0x180
	s_mov_b32 m0, s92
	ds_read_b128 v[200:203], v133
	ds_read_b128 v[204:207], v134
	ds_read_b128 v[208:211], v135
	ds_read_b128 v[212:215], v136
	buffer_load_dwordx4 v141, s[12:15], s6 offen lds
	s_mov_b32 m0, s56
	s_nop 0
	buffer_load_dwordx4 v142, s[12:15], s6 offen lds
	s_barrier
	s_waitcnt lgkmcnt(2)
	v_mfma_f32_16x16x32_bf16 v[92:95], v[200:203], v[168:171], v[92:95]
	v_mfma_f32_16x16x32_bf16 v[92:95], v[204:207], v[172:175], v[92:95]
	s_waitcnt lgkmcnt(0)
	v_mfma_f32_16x16x32_bf16 v[88:91], v[212:215], v[172:175], v[88:91]
	v_mfma_f32_16x16x32_bf16 v[88:91], v[208:211], v[168:171], v[88:91]
	v_mfma_f32_16x16x32_bf16 v[68:71], v[208:211], v[176:179], v[68:71]
	v_mfma_f32_16x16x32_bf16 v[68:71], v[212:215], v[180:183], v[68:71]
	v_mfma_f32_16x16x32_bf16 v[80:83], v[204:207], v[180:183], v[80:83]
	v_mfma_f32_16x16x32_bf16 v[80:83], v[200:203], v[176:179], v[80:83]
	v_mfma_f32_16x16x32_bf16 v[60:63], v[200:203], v[184:187], v[60:63]
	v_mfma_f32_16x16x32_bf16 v[60:63], v[204:207], v[188:191], v[60:63]
	v_mfma_f32_16x16x32_bf16 v[56:59], v[212:215], v[188:191], v[56:59]
	v_mfma_f32_16x16x32_bf16 v[56:59], v[208:211], v[184:187], v[56:59]
	v_mfma_f32_16x16x32_bf16 v[48:51], v[208:211], v[192:195], v[48:51]
	v_mfma_f32_16x16x32_bf16 v[48:51], v[212:215], v[196:199], v[48:51]
	v_mfma_f32_16x16x32_bf16 v[52:55], v[204:207], v[196:199], v[52:55]
	v_mfma_f32_16x16x32_bf16 v[52:55], v[200:203], v[192:195], v[52:55]
	s_barrier
	s_addk_i32 s7, 0x180
	s_mov_b32 m0, s93
	ds_read_b128 v[168:171], v129 offset:49152
	ds_read_b128 v[172:175], v129 offset:50176
	ds_read_b128 v[176:179], v132 offset:49152
	ds_read_b128 v[180:183], v132 offset:50176
	ds_read_b128 v[184:187], v131 offset:49152
	ds_read_b128 v[188:191], v131 offset:50176
	ds_read_b128 v[192:195], v130 offset:49152
	ds_read_b128 v[196:199], v130 offset:50176
	buffer_load_dwordx4 v141, s[8:11], s7 offen lds
	s_mov_b32 m0, s57
	s_nop 0
	buffer_load_dwordx4 v142, s[8:11], s7 offen lds
	s_barrier
	s_waitcnt lgkmcnt(6)
	v_mfma_f32_16x16x32_bf16 v[44:47], v[152:155], v[168:171], v[44:47]
	v_mfma_f32_16x16x32_bf16 v[44:47], v[156:159], v[172:175], v[44:47]
	v_mfma_f32_16x16x32_bf16 v[40:43], v[164:167], v[172:175], v[40:43]
	v_mfma_f32_16x16x32_bf16 v[40:43], v[160:163], v[168:171], v[40:43]
	s_waitcnt lgkmcnt(4)
	v_mfma_f32_16x16x32_bf16 v[32:35], v[160:163], v[176:179], v[32:35]
	v_mfma_f32_16x16x32_bf16 v[32:35], v[164:167], v[180:183], v[32:35]
	v_mfma_f32_16x16x32_bf16 v[36:39], v[156:159], v[180:183], v[36:39]
	v_mfma_f32_16x16x32_bf16 v[36:39], v[152:155], v[176:179], v[36:39]
	s_waitcnt lgkmcnt(2)
	v_mfma_f32_16x16x32_bf16 v[28:31], v[152:155], v[184:187], v[28:31]
	v_mfma_f32_16x16x32_bf16 v[28:31], v[156:159], v[188:191], v[28:31]
	v_mfma_f32_16x16x32_bf16 v[24:27], v[164:167], v[188:191], v[24:27]
	v_mfma_f32_16x16x32_bf16 v[24:27], v[160:163], v[184:187], v[24:27]
	s_waitcnt lgkmcnt(0)
	v_mfma_f32_16x16x32_bf16 v[16:19], v[160:163], v[192:195], v[16:19]
	v_mfma_f32_16x16x32_bf16 v[16:19], v[164:167], v[196:199], v[16:19]
	v_mfma_f32_16x16x32_bf16 v[20:23], v[156:159], v[196:199], v[20:23]
	v_mfma_f32_16x16x32_bf16 v[20:23], v[152:155], v[192:195], v[20:23]
	s_barrier
	s_addk_i32 s22, 0x180
	s_mov_b32 m0, s94
	s_nop 0
	buffer_load_dwordx4 v141, s[12:15], s22 offen lds
	s_mov_b32 m0, s58
	s_nop 0
	buffer_load_dwordx4 v142, s[12:15], s22 offen lds
	s_add_i32 s1, s1, 2
	s_addk_i32 s3, 0x100
	s_cmp_gt_u32 s1, 59
	s_cbranch_scc0 .LBB0_494
	s_branch .Lmy_post_494

; #define STAGE(P, RS, SOFF, OFF, kt) do { const int _so = (SOFF) + (kt) * (BK * 2); \
;     _Pragma("unroll") for (int _i = 0; _i < 2; ++_i) { \
;       __builtin_amdgcn_raw_ptr_buffer_load_lds(RS, (__attribute__((address_space(3))) void*)((P) + wave * 1024 + _i * 8192), 16, OFF[_i], _so, 0, 0); } } while (0)
; #define LDA(dst, b, h) _Pragma("unroll") for (int m = 0; m < 4; ++m) _Pragma("unroll") for (int k = 0; k < 2; ++k) \
;     dst[m][k] = *reinterpret_cast<const bf16x8*>(SA(b, h) + lds_byte(wr * 64 + m * 16 + fr, k * 32 + fq * 8))
; #define LDB(dst, b, h) _Pragma("unroll") for (int n = 0; n < 2; ++n) _Pragma("unroll") for (int k = 0; k < 2; ++k) \
;     dst[n][k] = *reinterpret_cast<const bf16x8*>(SB(b, h) + lds_byte(wc * 32 + n * 16 + fr, k * 32 + fq * 8))
; #define WAIT_V(n) asm volatile("s_waitcnt vmcnt(" #n ")" ::: "memory")
; #define WAIT_L(n) asm volatile("s_waitcnt lgkmcnt(" #n ")" ::: "memory")
; #define BAR __builtin_amdgcn_s_barrier()
; #define SCHED __builtin_amdgcn_sched_barrier(0)
;     ...
;       LDB(B0, 0, 0); SCHED; LDA(At, 0, 0); STAGE(SA(1, 1), rsA, sA1, offA, t + 1);
;       WAIT_L(8); BAR; WAIT_L(0); MMA(0, 0, At, B0); BAR; SCHED;
;       LDB(B1, 0, 1); STAGE(SB(0, 0), rsB, sB0, offB, t + 2);
;       BAR; WAIT_L(0); MMA(0, 1, At, B1); BAR;
;       LDA(At, 0, 1); STAGE(SA(0, 0), rsA, sA0, offA, t + 2);
;       BAR; WAIT_L(0); MMA(1, 0, At, B0); BAR; SCHED;
;       STAGE(SB(0, 1), rsB, sB1, offB, t + 2);
;       WAIT_V(6); BAR; MMA(1, 1, At, B1); BAR;
.Lmy_rot_494:
	ds_read_b128 v[152:155], v147
	ds_read_b128 v[156:159], v148
	ds_read_b128 v[160:163], v149
	ds_read_b128 v[164:167], v150
	s_add_i32 s5, s82, s3
	s_add_i32 s6, s5, 0x80
	s_mov_b32 m0, s36
	ds_read_b128 v[168:171], v129
	ds_read_b128 v[172:175], v129 offset:1024
	ds_read_b128 v[176:179], v132
	ds_read_b128 v[180:183], v132 offset:1024
	ds_read_b128 v[184:187], v131
	ds_read_b128 v[188:191], v131 offset:1024
	ds_read_b128 v[192:195], v130
	ds_read_b128 v[196:199], v130 offset:1024
	buffer_load_dwordx4 v141, s[8:11], s6 offen lds
	s_mov_b32 m0, s59
	s_nop 0
	buffer_load_dwordx4 v142, s[8:11], s6 offen lds
	s_waitcnt lgkmcnt(8)
	s_barrier
	s_waitcnt lgkmcnt(0)
	v_mfma_f32_16x16x32_bf16 v[124:127], v[152:155], v[168:171], v[124:127]
	v_mfma_f32_16x16x32_bf16 v[124:127], v[156:159], v[172:175], v[124:127]
	v_mfma_f32_16x16x32_bf16 v[120:123], v[164:167], v[172:175], v[120:123]
	v_mfma_f32_16x16x32_bf16 v[120:123], v[160:163], v[168:171], v[120:123]
	v_mfma_f32_16x16x32_bf16 v[112:115], v[160:163], v[176:179], v[112:115]
	v_mfma_f32_16x16x32_bf16 v[112:115], v[164:167], v[180:183], v[112:115]
	v_mfma_f32_16x16x32_bf16 v[116:119], v[156:159], v[180:183], v[116:119]
	v_mfma_f32_16x16x32_bf16 v[116:119], v[152:155], v[176:179], v[116:119]
	v_mfma_f32_16x16x32_bf16 v[108:111], v[152:155], v[184:187], v[108:111]
	v_mfma_f32_16x16x32_bf16 v[108:111], v[156:159], v[188:191], v[108:111]
	v_mfma_f32_16x16x32_bf16 v[104:107], v[164:167], v[188:191], v[104:107]
	v_mfma_f32_16x16x32_bf16 v[104:107], v[160:163], v[184:187], v[104:107]
	v_mfma_f32_16x16x32_bf16 v[96:99], v[160:163], v[192:195], v[96:99]
	v_mfma_f32_16x16x32_bf16 v[96:99], v[164:167], v[196:199], v[96:99]
	v_mfma_f32_16x16x32_bf16 v[100:103], v[156:159], v[196:199], v[100:103]
	v_mfma_f32_16x16x32_bf16 v[100:103], v[152:155], v[192:195], v[100:103]
	s_barrier
	s_add_i32 s6, s84, s3
	s_add_i32 s7, s6, 0x100
	s_mov_b32 s14, s10
	s_mov_b32 s15, s11
	s_mov_b32 m0, s37
	ds_read_b128 v[200:203], v143
	ds_read_b128 v[204:207], v144
	ds_read_b128 v[208:211], v145
	ds_read_b128 v[212:215], v146
	buffer_load_dwordx4 v141, s[12:15], s7 offen lds
	s_mov_b32 m0, s70
	s_nop 0
	buffer_load_dwordx4 v142, s[12:15], s7 offen lds
	s_barrier
	s_waitcnt lgkmcnt(2)
	v_mfma_f32_16x16x32_bf16 v[92:95], v[200:203], v[168:171], v[92:95]
	v_mfma_f32_16x16x32_bf16 v[92:95], v[204:207], v[172:175], v[92:95]
	s_waitcnt lgkmcnt(0)
	v_mfma_f32_16x16x32_bf16 v[88:91], v[212:215], v[172:175], v[88:91]
	v_mfma_f32_16x16x32_bf16 v[88:91], v[208:211], v[168:171], v[88:91]
	v_mfma_f32_16x16x32_bf16 v[68:71], v[208:211], v[176:179], v[68:71]
	v_mfma_f32_16x16x32_bf16 v[68:71], v[212:215], v[180:183], v[68:71]
	v_mfma_f32_16x16x32_bf16 v[80:83], v[204:207], v[180:183], v[80:83]
	v_mfma_f32_16x16x32_bf16 v[80:83], v[200:203], v[176:179], v[80:83]
	v_mfma_f32_16x16x32_bf16 v[60:63], v[200:203], v[184:187], v[60:63]
	v_mfma_f32_16x16x32_bf16 v[60:63], v[204:207], v[188:191], v[60:63]
	v_mfma_f32_16x16x32_bf16 v[56:59], v[212:215], v[188:191], v[56:59]
	v_mfma_f32_16x16x32_bf16 v[56:59], v[208:211], v[184:187], v[56:59]
	v_mfma_f32_16x16x32_bf16 v[48:51], v[208:211], v[192:195], v[48:51]
	v_mfma_f32_16x16x32_bf16 v[48:51], v[212:215], v[196:199], v[48:51]
	v_mfma_f32_16x16x32_bf16 v[52:55], v[204:207], v[196:199], v[52:55]
	v_mfma_f32_16x16x32_bf16 v[52:55], v[200:203], v[192:195], v[52:55]
	s_barrier
	s_add_i32 s7, s83, s3
	s_add_i32 s22, s7, 0x100
	s_mov_b32 m0, s35
	ds_read_b128 v[168:171], v129 offset:16384
	ds_read_b128 v[172:175], v129 offset:17408
	ds_read_b128 v[176:179], v132 offset:16384
	ds_read_b128 v[180:183], v132 offset:17408
	ds_read_b128 v[184:187], v131 offset:16384
	ds_read_b128 v[188:191], v131 offset:17408
	ds_read_b128 v[192:195], v130 offset:16384
	ds_read_b128 v[196:199], v130 offset:17408
	buffer_load_dwordx4 v141, s[8:11], s22 offen lds
	s_mov_b32 m0, s95
	s_nop 0
	buffer_load_dwordx4 v142, s[8:11], s22 offen lds
	s_barrier
	s_waitcnt lgkmcnt(6)
	v_mfma_f32_16x16x32_bf16 v[44:47], v[152:155], v[168:171], v[44:47]
	v_mfma_f32_16x16x32_bf16 v[44:47], v[156:159], v[172:175], v[44:47]
	v_mfma_f32_16x16x32_bf16 v[40:43], v[164:167], v[172:175], v[40:43]
	v_mfma_f32_16x16x32_bf16 v[40:43], v[160:163], v[168:171], v[40:43]
	s_waitcnt lgkmcnt(4)
	v_mfma_f32_16x16x32_bf16 v[32:35], v[160:163], v[176:179], v[32:35]
	v_mfma_f32_16x16x32_bf16 v[32:35], v[164:167], v[180:183], v[32:35]
	v_mfma_f32_16x16x32_bf16 v[36:39], v[156:159], v[180:183], v[36:39]
	v_mfma_f32_16x16x32_bf16 v[36:39], v[152:155], v[176:179], v[36:39]
	s_waitcnt lgkmcnt(2)
	v_mfma_f32_16x16x32_bf16 v[28:31], v[152:155], v[184:187], v[28:31]
	v_mfma_f32_16x16x32_bf16 v[28:31], v[156:159], v[188:191], v[28:31]
	v_mfma_f32_16x16x32_bf16 v[24:27], v[164:167], v[188:191], v[24:27]
	v_mfma_f32_16x16x32_bf16 v[24:27], v[160:163], v[184:187], v[24:27]
	s_waitcnt lgkmcnt(0)
	v_mfma_f32_16x16x32_bf16 v[16:19], v[160:163], v[192:195], v[16:19]
	v_mfma_f32_16x16x32_bf16 v[16:19], v[164:167], v[196:199], v[16:19]
	v_mfma_f32_16x16x32_bf16 v[20:23], v[156:159], v[196:199], v[20:23]
	v_mfma_f32_16x16x32_bf16 v[20:23], v[152:155], v[192:195], v[20:23]
	s_barrier
	s_add_i32 s22, s85, s3
	s_add_i32 s23, s22, 0x100
	s_mov_b32 m0, s38
	s_nop 0
	buffer_load_dwordx4 v141, s[12:15], s23 offen lds
	s_mov_b32 m0, s71
	s_nop 0
	buffer_load_dwordx4 v142, s[12:15], s23 offen lds
	s_waitcnt vmcnt(6)
	s_barrier
; #define STAGE(P, RS, SOFF, OFF, kt) do { const int _so = (SOFF) + (kt) * (BK * 2); \
;     _Pragma("unroll") for (int _i = 0; _i < 2; ++_i) { \
;       __builtin_amdgcn_raw_ptr_buffer_load_lds(RS, (__attribute__((address_space(3))) void*)((P) + wave * 1024 + _i * 8192), 16, OFF[_i], _so, 0, 0); } } while (0)
; #define LDA(dst, b, h) _Pragma("unroll") for (int m = 0; m < 4; ++m) _Pragma("unroll") for (int k = 0; k < 2; ++k) \
;     dst[m][k] = *reinterpret_cast<const bf16x8*>(SA(b, h) + lds_byte(wr * 64 + m * 16 + fr, k * 32 + fq * 8))
; #define LDB(dst, b, h) _Pragma("unroll") for (int n = 0; n < 2; ++n) _Pragma("unroll") for (int k = 0; k < 2; ++k) \
;     dst[n][k] = *reinterpret_cast<const bf16x8*>(SB(b, h) + lds_byte(wc * 32 + n * 16 + fr, k * 32 + fq * 8))
; #define WAIT_V(n) asm volatile("s_waitcnt vmcnt(" #n ")" ::: "memory")
; #define WAIT_L(n) asm volatile("s_waitcnt lgkmcnt(" #n ")" ::: "memory")
; #define BAR __builtin_amdgcn_s_barrier()
; #define SCHED __builtin_amdgcn_sched_barrier(0)
;     ...
;       WAIT_V(6); BAR; MMA(1, 1, At, B1); BAR;
;       LDB(B0, 1, 0); SCHED; LDA(At, 1, 0); STAGE(SA(0, 1), rsA, sA1, offA, t + 2);
;       WAIT_L(8); BAR; WAIT_L(0); MMA(0, 0, At, B0); BAR; SCHED;
;       LDB(B1, 1, 1); STAGE(SB(1, 0), rsB, sB0, offB, t + 3);
;       BAR; WAIT_L(0); MMA(0, 1, At, B1); BAR;
;       LDA(At, 1, 1); STAGE(SA(1, 0), rsA, sA0, offA, t + 3);
;       BAR; WAIT_L(0); MMA(1, 0, At, B0); BAR; SCHED;
;       STAGE(SB(1, 1), rsB, sB1, offB, t + 3);
	v_mfma_f32_16x16x32_bf16 v[12:15], v[200:203], v[168:171], v[12:15]
	v_mfma_f32_16x16x32_bf16 v[12:15], v[204:207], v[172:175], v[12:15]
	v_mfma_f32_16x16x32_bf16 v[8:11], v[212:215], v[172:175], v[8:11]
	v_mfma_f32_16x16x32_bf16 v[8:11], v[208:211], v[168:171], v[8:11]
	v_mfma_f32_16x16x32_bf16 v[0:3], v[208:211], v[176:179], v[0:3]
	v_mfma_f32_16x16x32_bf16 v[0:3], v[212:215], v[180:183], v[0:3]
	v_mfma_f32_16x16x32_bf16 v[4:7], v[204:207], v[180:183], v[4:7]
	v_mfma_f32_16x16x32_bf16 v[4:7], v[200:203], v[176:179], v[4:7]
	v_mfma_f32_16x16x32_bf16 v[64:67], v[200:203], v[184:187], v[64:67]
	v_mfma_f32_16x16x32_bf16 v[64:67], v[204:207], v[188:191], v[64:67]
	v_mfma_f32_16x16x32_bf16 v[72:75], v[212:215], v[188:191], v[72:75]
	v_mfma_f32_16x16x32_bf16 v[72:75], v[208:211], v[184:187], v[72:75]
	v_mfma_f32_16x16x32_bf16 v[84:87], v[208:211], v[192:195], v[84:87]
	v_mfma_f32_16x16x32_bf16 v[84:87], v[212:215], v[196:199], v[84:87]
	v_mfma_f32_16x16x32_bf16 v[76:79], v[204:207], v[196:199], v[76:79]
	v_mfma_f32_16x16x32_bf16 v[76:79], v[200:203], v[192:195], v[76:79]
	s_barrier
	ds_read_b128 v[152:155], v137
	ds_read_b128 v[156:159], v138
	ds_read_b128 v[160:163], v139
	ds_read_b128 v[164:167], v140
	s_addk_i32 s5, 0x100
	s_mov_b32 m0, s39
	ds_read_b128 v[168:171], v129 offset:32768
	ds_read_b128 v[172:175], v129 offset:33792
	ds_read_b128 v[176:179], v132 offset:32768
	ds_read_b128 v[180:183], v132 offset:33792
	ds_read_b128 v[184:187], v131 offset:32768
	ds_read_b128 v[188:191], v131 offset:33792
	ds_read_b128 v[192:195], v130 offset:32768
	ds_read_b128 v[196:199], v130 offset:33792
	buffer_load_dwordx4 v141, s[8:11], s5 offen lds
	s_mov_b32 m0, s97
	s_nop 0
	buffer_load_dwordx4 v142, s[8:11], s5 offen lds
	s_waitcnt lgkmcnt(8)
	s_barrier
	s_waitcnt lgkmcnt(6)
	v_mfma_f32_16x16x32_bf16 v[124:127], v[152:155], v[168:171], v[124:127]
	v_mfma_f32_16x16x32_bf16 v[124:127], v[156:159], v[172:175], v[124:127]
	v_mfma_f32_16x16x32_bf16 v[120:123], v[164:167], v[172:175], v[120:123]
	v_mfma_f32_16x16x32_bf16 v[120:123], v[160:163], v[168:171], v[120:123]
	s_waitcnt lgkmcnt(4)
	v_mfma_f32_16x16x32_bf16 v[112:115], v[160:163], v[176:179], v[112:115]
	v_mfma_f32_16x16x32_bf16 v[112:115], v[164:167], v[180:183], v[112:115]
	v_mfma_f32_16x16x32_bf16 v[116:119], v[156:159], v[180:183], v[116:119]
	v_mfma_f32_16x16x32_bf16 v[116:119], v[152:155], v[176:179], v[116:119]
	s_waitcnt lgkmcnt(2)
	v_mfma_f32_16x16x32_bf16 v[108:111], v[152:155], v[184:187], v[108:111]
	v_mfma_f32_16x16x32_bf16 v[108:111], v[156:159], v[188:191], v[108:111]
	v_mfma_f32_16x16x32_bf16 v[104:107], v[164:167], v[188:191], v[104:107]
	v_mfma_f32_16x16x32_bf16 v[104:107], v[160:163], v[184:187], v[104:107]
	s_waitcnt lgkmcnt(0)
	v_mfma_f32_16x16x32_bf16 v[96:99], v[160:163], v[192:195], v[96:99]
	v_mfma_f32_16x16x32_bf16 v[96:99], v[164:167], v[196:199], v[96:99]
	v_mfma_f32_16x16x32_bf16 v[100:103], v[156:159], v[196:199], v[100:103]
	v_mfma_f32_16x16x32_bf16 v[100:103], v[152:155], v[192:195], v[100:103]
	s_barrier
	s_addk_i32 s6, 0x180
	s_mov_b32 m0, s92
	ds_read_b128 v[200:203], v133
	ds_read_b128 v[204:207], v134
	ds_read_b128 v[208:211], v135
	ds_read_b128 v[212:215], v136
	buffer_load_dwordx4 v141, s[12:15], s6 offen lds
	s_mov_b32 m0, s56
	s_nop 0
	buffer_load_dwordx4 v142, s[12:15], s6 offen lds
	s_barrier
	s_waitcnt lgkmcnt(2)
	v_mfma_f32_16x16x32_bf16 v[92:95], v[200:203], v[168:171], v[92:95]
	v_mfma_f32_16x16x32_bf16 v[92:95], v[204:207], v[172:175], v[92:95]
	s_waitcnt lgkmcnt(0)
	v_mfma_f32_16x16x32_bf16 v[88:91], v[212:215], v[172:175], v[88:91]
	v_mfma_f32_16x16x32_bf16 v[88:91], v[208:211], v[168:171], v[88:91]
	v_mfma_f32_16x16x32_bf16 v[68:71], v[208:211], v[176:179], v[68:71]
	v_mfma_f32_16x16x32_bf16 v[68:71], v[212:215], v[180:183], v[68:71]
	v_mfma_f32_16x16x32_bf16 v[80:83], v[204:207], v[180:183], v[80:83]
	v_mfma_f32_16x16x32_bf16 v[80:83], v[200:203], v[176:179], v[80:83]
	v_mfma_f32_16x16x32_bf16 v[60:63], v[200:203], v[184:187], v[60:63]
	v_mfma_f32_16x16x32_bf16 v[60:63], v[204:207], v[188:191], v[60:63]
	v_mfma_f32_16x16x32_bf16 v[56:59], v[212:215], v[188:191], v[56:59]
	v_mfma_f32_16x16x32_bf16 v[56:59], v[208:211], v[184:187], v[56:59]
	v_mfma_f32_16x16x32_bf16 v[48:51], v[208:211], v[192:195], v[48:51]
	v_mfma_f32_16x16x32_bf16 v[48:51], v[212:215], v[196:199], v[48:51]
	v_mfma_f32_16x16x32_bf16 v[52:55], v[204:207], v[196:199], v[52:55]
	v_mfma_f32_16x16x32_bf16 v[52:55], v[200:203], v[192:195], v[52:55]
	s_barrier
	s_addk_i32 s7, 0x180
	s_mov_b32 m0, s93
	ds_read_b128 v[168:171], v129 offset:49152
	ds_read_b128 v[172:175], v129 offset:50176
	ds_read_b128 v[176:179], v132 offset:49152
	ds_read_b128 v[180:183], v132 offset:50176
	ds_read_b128 v[184:187], v131 offset:49152
	ds_read_b128 v[188:191], v131 offset:50176
	ds_read_b128 v[192:195], v130 offset:49152
	ds_read_b128 v[196:199], v130 offset:50176
	buffer_load_dwordx4 v141, s[8:11], s7 offen lds
	s_mov_b32 m0, s57
	s_nop 0
	buffer_load_dwordx4 v142, s[8:11], s7 offen lds
	s_barrier
	s_waitcnt lgkmcnt(6)
	v_mfma_f32_16x16x32_bf16 v[44:47], v[152:155], v[168:171], v[44:47]
	v_mfma_f32_16x16x32_bf16 v[44:47], v[156:159], v[172:175], v[44:47]
	v_mfma_f32_16x16x32_bf16 v[40:43], v[164:167], v[172:175], v[40:43]
	v_mfma_f32_16x16x32_bf16 v[40:43], v[160:163], v[168:171], v[40:43]
	s_waitcnt lgkmcnt(4)
	v_mfma_f32_16x16x32_bf16 v[32:35], v[160:163], v[176:179], v[32:35]
	v_mfma_f32_16x16x32_bf16 v[32:35], v[164:167], v[180:183], v[32:35]
	v_mfma_f32_16x16x32_bf16 v[36:39], v[156:159], v[180:183], v[36:39]
	v_mfma_f32_16x16x32_bf16 v[36:39], v[152:155], v[176:179], v[36:39]
	s_waitcnt lgkmcnt(2)
	v_mfma_f32_16x16x32_bf16 v[28:31], v[152:155], v[184:187], v[28:31]
	v_mfma_f32_16x16x32_bf16 v[28:31], v[156:159], v[188:191], v[28:31]
	v_mfma_f32_16x16x32_bf16 v[24:27], v[164:167], v[188:191], v[24:27]
	v_mfma_f32_16x16x32_bf16 v[24:27], v[160:163], v[184:187], v[24:27]
	s_waitcnt lgkmcnt(0)
	v_mfma_f32_16x16x32_bf16 v[16:19], v[160:163], v[192:195], v[16:19]
	v_mfma_f32_16x16x32_bf16 v[16:19], v[164:167], v[196:199], v[16:19]
	v_mfma_f32_16x16x32_bf16 v[20:23], v[156:159], v[196:199], v[20:23]
	v_mfma_f32_16x16x32_bf16 v[20:23], v[152:155], v[192:195], v[20:23]
	s_barrier
	s_addk_i32 s22, 0x180
	s_mov_b32 m0, s94
	s_nop 0
	buffer_load_dwordx4 v141, s[12:15], s22 offen lds
	s_mov_b32 m0, s58
	s_nop 0
	buffer_load_dwordx4 v142, s[12:15], s22 offen lds
	s_add_i32 s1, s1, 2
	s_addk_i32 s3, 0x100
	s_cmp_gt_u32 s1, 59
	s_cbranch_scc0 .LBB0_494
; #define STAGE(P, RS, SOFF, OFF, kt) do { const int _so = (SOFF) + (kt) * (BK * 2); \
;     _Pragma("unroll") for (int _i = 0; _i < 2; ++_i) { \
;       __builtin_amdgcn_raw_ptr_buffer_load_lds(RS, (__attribute__((address_space(3))) void*)((P) + wave * 1024 + _i * 8192), 16, OFF[_i], _so, 0, 0); } } while (0)
; #define LDA(dst, b, h) _Pragma("unroll") for (int m = 0; m < 4; ++m) _Pragma("unroll") for (int k = 0; k < 2; ++k) \
;     dst[m][k] = *reinterpret_cast<const bf16x8*>(SA(b, h) + lds_byte(wr * 64 + m * 16 + fr, k * 32 + fq * 8))
; #define LDB(dst, b, h) _Pragma("unroll") for (int n = 0; n < 2; ++n) _Pragma("unroll") for (int k = 0; k < 2; ++k) \
;     dst[n][k] = *reinterpret_cast<const bf16x8*>(SB(b, h) + lds_byte(wc * 32 + n * 16 + fr, k * 32 + fq * 8))
; #define WAIT_V(n) asm volatile("s_waitcnt vmcnt(" #n ")" ::: "memory")
; #define WAIT_L(n) asm volatile("s_waitcnt lgkmcnt(" #n ")" ::: "memory")
; #define BAR __builtin_amdgcn_s_barrier()
;     ...
;       WAIT_V(6); BAR; MMA(1, 1, At, B1); BAR;
;     }
;     { LDB(B0, 0, 0); LDA(At, 0, 0); STAGE(SA(1, 1), rsA, sA1, offA, nt - 1);
;       BAR; WAIT_L(0); MMA(0, 0, At, B0); BAR;
;       LDB(B1, 0, 1); BAR; WAIT_L(0); MMA(0, 1, At, B1); BAR;
;       LDA(At, 0, 1); WAIT_V(4); BAR; WAIT_L(0); MMA(1, 0, At, B0); MMA(1, 1, At, B1); BAR; }
.Lmy_post_494:
	s_waitcnt vmcnt(6)
	s_barrier
	v_mfma_f32_16x16x32_bf16 v[12:15], v[200:203], v[168:171], v[12:15]
	v_mfma_f32_16x16x32_bf16 v[12:15], v[204:207], v[172:175], v[12:15]
	v_mfma_f32_16x16x32_bf16 v[8:11], v[212:215], v[172:175], v[8:11]
	v_mfma_f32_16x16x32_bf16 v[8:11], v[208:211], v[168:171], v[8:11]
	v_mfma_f32_16x16x32_bf16 v[0:3], v[208:211], v[176:179], v[0:3]
	v_mfma_f32_16x16x32_bf16 v[0:3], v[212:215], v[180:183], v[0:3]
	v_mfma_f32_16x16x32_bf16 v[4:7], v[204:207], v[180:183], v[4:7]
	v_mfma_f32_16x16x32_bf16 v[4:7], v[200:203], v[176:179], v[4:7]
	v_mfma_f32_16x16x32_bf16 v[64:67], v[200:203], v[184:187], v[64:67]
	v_mfma_f32_16x16x32_bf16 v[64:67], v[204:207], v[188:191], v[64:67]
	v_mfma_f32_16x16x32_bf16 v[72:75], v[212:215], v[188:191], v[72:75]
	v_mfma_f32_16x16x32_bf16 v[72:75], v[208:211], v[184:187], v[72:75]
	v_mfma_f32_16x16x32_bf16 v[84:87], v[208:211], v[192:195], v[84:87]
	v_mfma_f32_16x16x32_bf16 v[84:87], v[212:215], v[196:199], v[84:87]
	v_mfma_f32_16x16x32_bf16 v[76:79], v[204:207], v[196:199], v[76:79]
	v_mfma_f32_16x16x32_bf16 v[76:79], v[200:203], v[192:195], v[76:79]
	s_barrier
	s_add_i32 s1, s82, 0x1f80
	s_mov_b32 m0, s36
	ds_read_b128 v[152:155], v147
	ds_read_b128 v[156:159], v148
	ds_read_b128 v[160:163], v149
	ds_read_b128 v[148:151], v150
	ds_read_b128 v[164:167], v129
	ds_read_b128 v[168:171], v129 offset:1024
	ds_read_b128 v[172:175], v132
	ds_read_b128 v[176:179], v132 offset:1024
	ds_read_b128 v[180:183], v131
	ds_read_b128 v[184:187], v131 offset:1024
	ds_read_b128 v[188:191], v130
	ds_read_b128 v[192:195], v130 offset:1024
	buffer_load_dwordx4 v141, s[8:11], s1 offen lds
	s_mov_b32 m0, s59
	s_nop 0
	buffer_load_dwordx4 v142, s[8:11], s1 offen lds
	s_barrier
	s_waitcnt lgkmcnt(6)
	v_mfma_f32_16x16x32_bf16 v[124:127], v[152:155], v[164:167], v[124:127]
	v_mfma_f32_16x16x32_bf16 v[124:127], v[156:159], v[168:171], v[124:127]
	v_mfma_f32_16x16x32_bf16 v[120:123], v[148:151], v[168:171], v[120:123]
	v_mfma_f32_16x16x32_bf16 v[120:123], v[160:163], v[164:167], v[120:123]
	s_waitcnt lgkmcnt(4)
	v_mfma_f32_16x16x32_bf16 v[112:115], v[160:163], v[172:175], v[112:115]
	v_mfma_f32_16x16x32_bf16 v[112:115], v[148:151], v[176:179], v[112:115]
	v_mfma_f32_16x16x32_bf16 v[116:119], v[156:159], v[176:179], v[116:119]
	v_mfma_f32_16x16x32_bf16 v[116:119], v[152:155], v[172:175], v[116:119]
	s_waitcnt lgkmcnt(2)
	v_mfma_f32_16x16x32_bf16 v[108:111], v[152:155], v[180:183], v[108:111]
	v_mfma_f32_16x16x32_bf16 v[108:111], v[156:159], v[184:187], v[108:111]
	v_mfma_f32_16x16x32_bf16 v[104:107], v[148:151], v[184:187], v[104:107]
	v_mfma_f32_16x16x32_bf16 v[104:107], v[160:163], v[180:183], v[104:107]
	s_waitcnt lgkmcnt(0)
	v_mfma_f32_16x16x32_bf16 v[96:99], v[160:163], v[188:191], v[96:99]
	v_mfma_f32_16x16x32_bf16 v[96:99], v[148:151], v[192:195], v[96:99]
	v_mfma_f32_16x16x32_bf16 v[100:103], v[156:159], v[192:195], v[100:103]
	v_mfma_f32_16x16x32_bf16 v[100:103], v[152:155], v[188:191], v[100:103]
	s_barrier
	ds_read_b128 v[196:199], v143
	ds_read_b128 v[200:203], v144
	ds_read_b128 v[142:145], v145
	ds_read_b128 v[204:207], v146
	s_barrier
	s_waitcnt lgkmcnt(1)
	v_mfma_f32_16x16x32_bf16 v[80:83], v[196:199], v[172:175], v[80:83]
	v_mfma_f32_16x16x32_bf16 v[68:71], v[142:145], v[172:175], v[68:71]
	v_mfma_f32_16x16x32_bf16 v[60:63], v[196:199], v[180:183], v[60:63]
	v_mfma_f32_16x16x32_bf16 v[56:59], v[142:145], v[180:183], v[56:59]
	v_mfma_f32_16x16x32_bf16 v[52:55], v[196:199], v[188:191], v[52:55]
	v_mfma_f32_16x16x32_bf16 v[48:51], v[142:145], v[188:191], v[48:51]
	v_mfma_f32_16x16x32_bf16 v[92:95], v[196:199], v[164:167], v[92:95]
	v_mfma_f32_16x16x32_bf16 v[88:91], v[142:145], v[164:167], v[88:91]
	s_waitcnt lgkmcnt(0)
	v_mfma_f32_16x16x32_bf16 v[80:83], v[200:203], v[176:179], v[80:83]
	v_mfma_f32_16x16x32_bf16 v[68:71], v[204:207], v[176:179], v[68:71]
	v_mfma_f32_16x16x32_bf16 v[60:63], v[200:203], v[184:187], v[60:63]
	v_mfma_f32_16x16x32_bf16 v[56:59], v[204:207], v[184:187], v[56:59]
	v_mfma_f32_16x16x32_bf16 v[52:55], v[200:203], v[192:195], v[52:55]
	v_mfma_f32_16x16x32_bf16 v[48:51], v[204:207], v[192:195], v[48:51]
	v_mfma_f32_16x16x32_bf16 v[164:167], v[200:203], v[168:171], v[92:95]
	v_mfma_f32_16x16x32_bf16 v[168:171], v[204:207], v[168:171], v[88:91]
	s_barrier
	s_nop 0
	ds_read_b128 v[88:91], v129 offset:16384
	ds_read_b128 v[92:95], v129 offset:17408
	ds_read_b128 v[172:175], v132 offset:16384
	ds_read_b128 v[176:179], v132 offset:17408
	ds_read_b128 v[180:183], v131 offset:16384
	ds_read_b128 v[184:187], v131 offset:17408
	ds_read_b128 v[188:191], v130 offset:16384
	ds_read_b128 v[192:195], v130 offset:17408
	s_waitcnt vmcnt(4)
	s_barrier
; #define LDA(dst, b, h) _Pragma("unroll") for (int m = 0; m < 4; ++m) _Pragma("unroll") for (int k = 0; k < 2; ++k) \
;     dst[m][k] = *reinterpret_cast<const bf16x8*>(SA(b, h) + lds_byte(wr * 64 + m * 16 + fr, k * 32 + fq * 8))
; #define LDB(dst, b, h) _Pragma("unroll") for (int n = 0; n < 2; ++n) _Pragma("unroll") for (int k = 0; k < 2; ++k) \
;     dst[n][k] = *reinterpret_cast<const bf16x8*>(SB(b, h) + lds_byte(wc * 32 + n * 16 + fr, k * 32 + fq * 8))
; #define WAIT_V(n) asm volatile("s_waitcnt vmcnt(" #n ")" ::: "memory")
; #define WAIT_L(n) asm volatile("s_waitcnt lgkmcnt(" #n ")" ::: "memory")
; #define BAR __builtin_amdgcn_s_barrier()
;     ...
;       LDA(At, 0, 1); WAIT_V(4); BAR; WAIT_L(0); MMA(1, 0, At, B0); MMA(1, 1, At, B1); BAR; }
;     { LDB(B0, 1, 0); LDA(At, 1, 0); WAIT_V(2); BAR; WAIT_L(0); MMA(0, 0, At, B0); BAR;
	s_waitcnt lgkmcnt(0)
	v_mfma_f32_16x16x32_bf16 v[44:47], v[152:155], v[88:91], v[44:47]
	v_mfma_f32_16x16x32_bf16 v[40:43], v[160:163], v[88:91], v[40:43]
	v_mfma_f32_16x16x32_bf16 v[36:39], v[152:155], v[172:175], v[36:39]
	v_mfma_f32_16x16x32_bf16 v[32:35], v[160:163], v[172:175], v[32:35]
	v_mfma_f32_16x16x32_bf16 v[28:31], v[152:155], v[180:183], v[28:31]
	v_mfma_f32_16x16x32_bf16 v[24:27], v[160:163], v[180:183], v[24:27]
	v_mfma_f32_16x16x32_bf16 v[20:23], v[152:155], v[188:191], v[20:23]
	v_mfma_f32_16x16x32_bf16 v[16:19], v[160:163], v[188:191], v[16:19]
	v_mfma_f32_16x16x32_bf16 v[44:47], v[156:159], v[92:95], v[44:47]
	v_mfma_f32_16x16x32_bf16 v[40:43], v[148:151], v[92:95], v[40:43]
	v_mfma_f32_16x16x32_bf16 v[36:39], v[156:159], v[176:179], v[36:39]
	v_mfma_f32_16x16x32_bf16 v[32:35], v[148:151], v[176:179], v[32:35]
	v_mfma_f32_16x16x32_bf16 v[28:31], v[156:159], v[184:187], v[28:31]
	v_mfma_f32_16x16x32_bf16 v[24:27], v[148:151], v[184:187], v[24:27]
	v_mfma_f32_16x16x32_bf16 v[20:23], v[156:159], v[192:195], v[20:23]
	v_mfma_f32_16x16x32_bf16 v[16:19], v[148:151], v[192:195], v[16:19]
	v_mfma_f32_16x16x32_bf16 v[4:7], v[196:199], v[172:175], v[4:7]
	v_mfma_f32_16x16x32_bf16 v[0:3], v[142:145], v[172:175], v[0:3]
	v_mfma_f32_16x16x32_bf16 v[12:15], v[196:199], v[88:91], v[12:15]
	v_mfma_f32_16x16x32_bf16 v[8:11], v[142:145], v[88:91], v[8:11]
	v_mfma_f32_16x16x32_bf16 v[64:67], v[196:199], v[180:183], v[64:67]
	v_mfma_f32_16x16x32_bf16 v[72:75], v[142:145], v[180:183], v[72:75]
	v_mfma_f32_16x16x32_bf16 v[76:79], v[196:199], v[188:191], v[76:79]
	v_mfma_f32_16x16x32_bf16 v[84:87], v[142:145], v[188:191], v[84:87]
	v_mfma_f32_16x16x32_bf16 v[4:7], v[200:203], v[176:179], v[4:7]
	v_mfma_f32_16x16x32_bf16 v[0:3], v[204:207], v[176:179], v[0:3]
	v_mfma_f32_16x16x32_bf16 v[142:145], v[200:203], v[92:95], v[12:15]
	v_mfma_f32_16x16x32_bf16 v[146:149], v[204:207], v[92:95], v[8:11]
	v_mfma_f32_16x16x32_bf16 v[150:153], v[200:203], v[184:187], v[64:67]
	v_mfma_f32_16x16x32_bf16 v[154:157], v[204:207], v[184:187], v[72:75]
	v_mfma_f32_16x16x32_bf16 v[158:161], v[200:203], v[192:195], v[76:79]
	v_mfma_f32_16x16x32_bf16 v[172:175], v[204:207], v[192:195], v[84:87]
	s_barrier
	ds_read_b128 v[8:11], v137
	ds_read_b128 v[12:15], v138
	ds_read_b128 v[176:179], v139
	ds_read_b128 v[138:141], v140
	ds_read_b128 v[64:67], v129 offset:32768
	ds_read_b128 v[84:87], v129 offset:33792
	ds_read_b128 v[180:183], v132 offset:32768
	ds_read_b128 v[184:187], v132 offset:33792
	ds_read_b128 v[188:191], v131 offset:32768
	ds_read_b128 v[192:195], v131 offset:33792
	ds_read_b128 v[196:199], v130 offset:32768
	ds_read_b128 v[200:203], v130 offset:33792
	s_waitcnt vmcnt(2)
	s_barrier
	s_waitcnt lgkmcnt(7)
	v_mfma_f32_16x16x32_bf16 v[72:75], v[8:11], v[64:67], v[124:127]
	v_mfma_f32_16x16x32_bf16 v[76:79], v[176:179], v[64:67], v[120:123]
	s_waitcnt lgkmcnt(5)
	v_mfma_f32_16x16x32_bf16 v[88:91], v[8:11], v[180:183], v[116:119]
	v_mfma_f32_16x16x32_bf16 v[92:95], v[176:179], v[180:183], v[112:115]
	s_waitcnt lgkmcnt(3)
	v_mfma_f32_16x16x32_bf16 v[112:115], v[8:11], v[188:191], v[108:111]
	v_mfma_f32_16x16x32_bf16 v[120:123], v[176:179], v[188:191], v[104:107]
	s_waitcnt lgkmcnt(1)
	v_mfma_f32_16x16x32_bf16 v[100:103], v[8:11], v[196:199], v[100:103]
	v_mfma_f32_16x16x32_bf16 v[96:99], v[176:179], v[196:199], v[96:99]
	v_mfma_f32_16x16x32_bf16 v[124:127], v[12:15], v[84:87], v[72:75]
	v_mfma_f32_16x16x32_bf16 v[116:119], v[138:141], v[84:87], v[76:79]
	v_mfma_f32_16x16x32_bf16 v[108:111], v[12:15], v[184:187], v[88:91]
	v_mfma_f32_16x16x32_bf16 v[104:107], v[138:141], v[184:187], v[92:95]
	v_mfma_f32_16x16x32_bf16 v[92:95], v[12:15], v[192:195], v[112:115]
	v_mfma_f32_16x16x32_bf16 v[88:91], v[138:141], v[192:195], v[120:123]
	s_waitcnt lgkmcnt(0)
	v_mfma_f32_16x16x32_bf16 v[76:79], v[12:15], v[200:203], v[100:103]
	v_mfma_f32_16x16x32_bf16 v[72:75], v[138:141], v[200:203], v[96:99]
	s_barrier
; #define LDA(dst, b, h) _Pragma("unroll") for (int m = 0; m < 4; ++m) _Pragma("unroll") for (int k = 0; k < 2; ++k) \
;     dst[m][k] = *reinterpret_cast<const bf16x8*>(SA(b, h) + lds_byte(wr * 64 + m * 16 + fr, k * 32 + fq * 8))
; #define LDB(dst, b, h) _Pragma("unroll") for (int n = 0; n < 2; ++n) _Pragma("unroll") for (int k = 0; k < 2; ++k) \
;     dst[n][k] = *reinterpret_cast<const bf16x8*>(SB(b, h) + lds_byte(wc * 32 + n * 16 + fr, k * 32 + fq * 8))
; #define WAIT_V(n) asm volatile("s_waitcnt vmcnt(" #n ")" ::: "memory")
; #define WAIT_L(n) asm volatile("s_waitcnt lgkmcnt(" #n ")" ::: "memory")
; #define BAR __builtin_amdgcn_s_barrier()
;     ...
;       LDB(B1, 1, 1); WAIT_V(0); BAR; WAIT_L(0); MMA(0, 1, At, B1); BAR;
;       LDA(At, 1, 1); BAR; WAIT_L(0); MMA(1, 0, At, B0); MMA(1, 1, At, B1); BAR; }
;     if (wr == 0) BAR;
	ds_read_b128 v[204:207], v133
	ds_read_b128 v[208:211], v134
	ds_read_b128 v[212:215], v135
	ds_read_b128 v[134:137], v136
	s_waitcnt vmcnt(0)
	s_barrier
	s_waitcnt lgkmcnt(1)
	v_mfma_f32_16x16x32_bf16 v[96:99], v[204:207], v[64:67], v[164:167]
	v_mfma_f32_16x16x32_bf16 v[64:67], v[212:215], v[64:67], v[168:171]
	v_mfma_f32_16x16x32_bf16 v[80:83], v[204:207], v[180:183], v[80:83]
	v_mfma_f32_16x16x32_bf16 v[68:71], v[212:215], v[180:183], v[68:71]
	v_mfma_f32_16x16x32_bf16 v[60:63], v[204:207], v[188:191], v[60:63]
	v_mfma_f32_16x16x32_bf16 v[56:59], v[212:215], v[188:191], v[56:59]
	v_mfma_f32_16x16x32_bf16 v[52:55], v[204:207], v[196:199], v[52:55]
	v_mfma_f32_16x16x32_bf16 v[48:51], v[212:215], v[196:199], v[48:51]
	s_waitcnt lgkmcnt(0)
	v_mfma_f32_16x16x32_bf16 v[120:123], v[208:211], v[84:87], v[96:99]
	v_mfma_f32_16x16x32_bf16 v[112:115], v[134:137], v[84:87], v[64:67]
	v_mfma_f32_16x16x32_bf16 v[100:103], v[208:211], v[184:187], v[80:83]
	v_mfma_f32_16x16x32_bf16 v[96:99], v[134:137], v[184:187], v[68:71]
	v_mfma_f32_16x16x32_bf16 v[84:87], v[208:211], v[192:195], v[60:63]
	v_mfma_f32_16x16x32_bf16 v[80:83], v[134:137], v[192:195], v[56:59]
	v_mfma_f32_16x16x32_bf16 v[68:71], v[208:211], v[200:203], v[52:55]
	v_mfma_f32_16x16x32_bf16 v[64:67], v[134:137], v[200:203], v[48:51]
	s_barrier
	s_nop 0
	ds_read_b128 v[48:51], v129 offset:49152
	ds_read_b128 v[162:165], v129 offset:50176
	ds_read_b128 v[52:55], v132 offset:49152
	ds_read_b128 v[166:169], v132 offset:50176
	ds_read_b128 v[180:183], v131 offset:49152
	ds_read_b128 v[184:187], v131 offset:50176
	ds_read_b128 v[188:191], v130 offset:49152
	ds_read_b128 v[130:133], v130 offset:50176
	s_barrier
	s_waitcnt lgkmcnt(0)
	v_mfma_f32_16x16x32_bf16 v[44:47], v[8:11], v[48:51], v[44:47]
	v_mfma_f32_16x16x32_bf16 v[40:43], v[176:179], v[48:51], v[40:43]
	v_mfma_f32_16x16x32_bf16 v[36:39], v[8:11], v[52:55], v[36:39]
	v_mfma_f32_16x16x32_bf16 v[32:35], v[176:179], v[52:55], v[32:35]
	v_mfma_f32_16x16x32_bf16 v[28:31], v[8:11], v[180:183], v[28:31]
	v_mfma_f32_16x16x32_bf16 v[24:27], v[176:179], v[180:183], v[24:27]
	v_mfma_f32_16x16x32_bf16 v[8:11], v[8:11], v[188:191], v[20:23]
	v_mfma_f32_16x16x32_bf16 v[16:19], v[176:179], v[188:191], v[16:19]
	v_mfma_f32_16x16x32_bf16 v[60:63], v[12:15], v[162:165], v[44:47]
	v_mfma_f32_16x16x32_bf16 v[56:59], v[138:141], v[162:165], v[40:43]
	v_mfma_f32_16x16x32_bf16 v[44:47], v[12:15], v[166:169], v[36:39]
	v_mfma_f32_16x16x32_bf16 v[40:43], v[138:141], v[166:169], v[32:35]
	v_mfma_f32_16x16x32_bf16 v[28:31], v[12:15], v[184:187], v[28:31]
	v_mfma_f32_16x16x32_bf16 v[24:27], v[138:141], v[184:187], v[24:27]
	v_mfma_f32_16x16x32_bf16 v[12:15], v[12:15], v[130:133], v[8:11]
	v_mfma_f32_16x16x32_bf16 v[8:11], v[138:141], v[130:133], v[16:19]
	v_mfma_f32_16x16x32_bf16 v[16:19], v[204:207], v[48:51], v[142:145]
	v_mfma_f32_16x16x32_bf16 v[20:23], v[212:215], v[48:51], v[146:149]
	v_mfma_f32_16x16x32_bf16 v[4:7], v[204:207], v[52:55], v[4:7]
	v_mfma_f32_16x16x32_bf16 v[0:3], v[212:215], v[52:55], v[0:3]
	v_mfma_f32_16x16x32_bf16 v[138:141], v[204:207], v[180:183], v[150:153]
	v_mfma_f32_16x16x32_bf16 v[142:145], v[212:215], v[180:183], v[154:157]
	v_mfma_f32_16x16x32_bf16 v[146:149], v[204:207], v[188:191], v[158:161]
	v_mfma_f32_16x16x32_bf16 v[150:153], v[212:215], v[188:191], v[172:175]
	v_mfma_f32_16x16x32_bf16 v[52:55], v[208:211], v[162:165], v[16:19]
	v_mfma_f32_16x16x32_bf16 v[48:51], v[134:137], v[162:165], v[20:23]
	v_mfma_f32_16x16x32_bf16 v[36:39], v[208:211], v[166:169], v[4:7]
	v_mfma_f32_16x16x32_bf16 v[32:35], v[134:137], v[166:169], v[0:3]
	v_mfma_f32_16x16x32_bf16 v[20:23], v[208:211], v[184:187], v[138:141]
	v_mfma_f32_16x16x32_bf16 v[16:19], v[134:137], v[184:187], v[142:145]
	v_mfma_f32_16x16x32_bf16 v[4:7], v[208:211], v[130:133], v[146:149]
	v_mfma_f32_16x16x32_bf16 v[0:3], v[134:137], v[130:133], v[150:153]
	v_cmp_gt_u32_e32 vcc, s76, v128
	s_barrier
	s_and_saveexec_b64 s[6:7], vcc
	s_cbranch_execz .LBB0_497
	s_barrier

; #define STAGE(P, RS, SOFF, OFF, kt) do { const int _so = (SOFF) + (kt) * (BK * 2); \
;     _Pragma("unroll") for (int _i = 0; _i < 2; ++_i) { \
;       __builtin_amdgcn_raw_ptr_buffer_load_lds(RS, (__attribute__((address_space(3))) void*)((P) + wave * 1024 + _i * 8192), 16, OFF[_i], _so, 0, 0); } } while (0)
; #define LDA(dst, b, h) _Pragma("unroll") for (int m = 0; m < 4; ++m) _Pragma("unroll") for (int k = 0; k < 2; ++k) \
;     dst[m][k] = *reinterpret_cast<const bf16x8*>(SA(b, h) + lds_byte(wr * 64 + m * 16 + fr, k * 32 + fq * 8))
; #define LDB(dst, b, h) _Pragma("unroll") for (int n = 0; n < 2; ++n) _Pragma("unroll") for (int k = 0; k < 2; ++k) \
;     dst[n][k] = *reinterpret_cast<const bf16x8*>(SB(b, h) + lds_byte(wc * 32 + n * 16 + fr, k * 32 + fq * 8))
; #define WAIT_V(n) asm volatile("s_waitcnt vmcnt(" #n ")" ::: "memory")
; #define WAIT_L(n) asm volatile("s_waitcnt lgkmcnt(" #n ")" ::: "memory")
; #define BAR __builtin_amdgcn_s_barrier()
;     ...
;       WAIT_V(6); BAR; MMA(1, 1, At, B1); BAR;
;     }
;     { LDB(B0, 0, 0); LDA(At, 0, 0); STAGE(SA(1, 1), rsA, sA1, offA, nt - 1);
;       BAR; WAIT_L(0); MMA(0, 0, At, B0); BAR;
;       LDB(B1, 0, 1); BAR; WAIT_L(0); MMA(0, 1, At, B1); BAR;
;       LDA(At, 0, 1); WAIT_V(4); BAR; WAIT_L(0); MMA(1, 0, At, B0); MMA(1, 1, At, B1); BAR; }
.Lmy_post_556:
	s_waitcnt vmcnt(6)
	s_barrier
	v_mfma_f32_16x16x32_bf16 v[28:31], v[202:205], v[170:173], v[28:31]
	v_mfma_f32_16x16x32_bf16 v[28:31], v[206:209], v[174:177], v[28:31]
	v_mfma_f32_16x16x32_bf16 v[24:27], v[214:217], v[174:177], v[24:27]
	v_mfma_f32_16x16x32_bf16 v[24:27], v[210:213], v[170:173], v[24:27]
	v_mfma_f32_16x16x32_bf16 v[16:19], v[210:213], v[178:181], v[16:19]
	v_mfma_f32_16x16x32_bf16 v[16:19], v[214:217], v[182:185], v[16:19]
	v_mfma_f32_16x16x32_bf16 v[20:23], v[206:209], v[182:185], v[20:23]
	v_mfma_f32_16x16x32_bf16 v[20:23], v[202:205], v[178:181], v[20:23]
	v_mfma_f32_16x16x32_bf16 v[12:15], v[202:205], v[186:189], v[12:15]
	v_mfma_f32_16x16x32_bf16 v[12:15], v[206:209], v[190:193], v[12:15]
	v_mfma_f32_16x16x32_bf16 v[8:11], v[214:217], v[190:193], v[8:11]
	v_mfma_f32_16x16x32_bf16 v[8:11], v[210:213], v[186:189], v[8:11]
	v_mfma_f32_16x16x32_bf16 v[0:3], v[210:213], v[194:197], v[0:3]
	v_mfma_f32_16x16x32_bf16 v[0:3], v[214:217], v[198:201], v[0:3]
	v_mfma_f32_16x16x32_bf16 v[4:7], v[206:209], v[198:201], v[4:7]
	v_mfma_f32_16x16x32_bf16 v[4:7], v[202:205], v[194:197], v[4:7]
	s_barrier
	s_add_i32 s10, s37, 0xf80
	s_mov_b32 m0, s30
	ds_read_b128 v[154:157], v149
	ds_read_b128 v[158:161], v150
	ds_read_b128 v[162:165], v151
	ds_read_b128 v[150:153], v152
	ds_read_b128 v[166:169], v131
	ds_read_b128 v[170:173], v131 offset:1024
	ds_read_b128 v[174:177], v134
	ds_read_b128 v[178:181], v134 offset:1024
	ds_read_b128 v[182:185], v133
	ds_read_b128 v[186:189], v133 offset:1024
	ds_read_b128 v[190:193], v132
	ds_read_b128 v[194:197], v132 offset:1024
	buffer_load_dwordx4 v143, s[4:7], s10 offen lds
	s_mov_b32 m0, s31
	s_nop 0
	buffer_load_dwordx4 v144, s[4:7], s10 offen lds
	s_barrier
	s_waitcnt lgkmcnt(6)
	v_mfma_f32_16x16x32_bf16 v[124:127], v[154:157], v[166:169], v[124:127]
	v_mfma_f32_16x16x32_bf16 v[124:127], v[158:161], v[170:173], v[124:127]
	v_mfma_f32_16x16x32_bf16 v[120:123], v[150:153], v[170:173], v[120:123]
	v_mfma_f32_16x16x32_bf16 v[120:123], v[162:165], v[166:169], v[120:123]
	s_waitcnt lgkmcnt(4)
	v_mfma_f32_16x16x32_bf16 v[112:115], v[162:165], v[174:177], v[112:115]
	v_mfma_f32_16x16x32_bf16 v[112:115], v[150:153], v[178:181], v[112:115]
	v_mfma_f32_16x16x32_bf16 v[116:119], v[158:161], v[178:181], v[116:119]
	v_mfma_f32_16x16x32_bf16 v[116:119], v[154:157], v[174:177], v[116:119]
	s_waitcnt lgkmcnt(2)
	v_mfma_f32_16x16x32_bf16 v[108:111], v[154:157], v[182:185], v[108:111]
	v_mfma_f32_16x16x32_bf16 v[108:111], v[158:161], v[186:189], v[108:111]
	v_mfma_f32_16x16x32_bf16 v[104:107], v[150:153], v[186:189], v[104:107]
	v_mfma_f32_16x16x32_bf16 v[104:107], v[162:165], v[182:185], v[104:107]
	s_waitcnt lgkmcnt(0)
	v_mfma_f32_16x16x32_bf16 v[96:99], v[162:165], v[190:193], v[96:99]
	v_mfma_f32_16x16x32_bf16 v[96:99], v[150:153], v[194:197], v[96:99]
	v_mfma_f32_16x16x32_bf16 v[100:103], v[158:161], v[194:197], v[100:103]
	v_mfma_f32_16x16x32_bf16 v[100:103], v[154:157], v[190:193], v[100:103]
	s_barrier
	ds_read_b128 v[198:201], v145
	ds_read_b128 v[202:205], v146
	ds_read_b128 v[144:147], v147
	ds_read_b128 v[206:209], v148
	s_barrier
	s_waitcnt lgkmcnt(2)
	v_mfma_f32_16x16x32_bf16 v[92:95], v[198:201], v[166:169], v[92:95]
	v_mfma_f32_16x16x32_bf16 v[92:95], v[202:205], v[170:173], v[92:95]
	s_waitcnt lgkmcnt(0)
	v_mfma_f32_16x16x32_bf16 v[88:91], v[206:209], v[170:173], v[88:91]
	v_mfma_f32_16x16x32_bf16 v[88:91], v[144:147], v[166:169], v[88:91]
	v_mfma_f32_16x16x32_bf16 v[80:83], v[144:147], v[174:177], v[80:83]
	v_mfma_f32_16x16x32_bf16 v[80:83], v[206:209], v[178:181], v[80:83]
	v_mfma_f32_16x16x32_bf16 v[84:87], v[202:205], v[178:181], v[84:87]
	v_mfma_f32_16x16x32_bf16 v[84:87], v[198:201], v[174:177], v[84:87]
	v_mfma_f32_16x16x32_bf16 v[76:79], v[198:201], v[182:185], v[76:79]
	v_mfma_f32_16x16x32_bf16 v[76:79], v[202:205], v[186:189], v[76:79]
	v_mfma_f32_16x16x32_bf16 v[72:75], v[206:209], v[186:189], v[72:75]
	v_mfma_f32_16x16x32_bf16 v[72:75], v[144:147], v[182:185], v[72:75]
	v_mfma_f32_16x16x32_bf16 v[64:67], v[144:147], v[190:193], v[64:67]
	v_mfma_f32_16x16x32_bf16 v[64:67], v[206:209], v[194:197], v[64:67]
	v_mfma_f32_16x16x32_bf16 v[68:71], v[202:205], v[194:197], v[68:71]
	v_mfma_f32_16x16x32_bf16 v[68:71], v[198:201], v[190:193], v[68:71]
	s_barrier
	ds_read_b128 v[166:169], v131 offset:16384
	ds_read_b128 v[170:173], v131 offset:17408
	ds_read_b128 v[174:177], v134 offset:16384
	ds_read_b128 v[178:181], v134 offset:17408
	ds_read_b128 v[182:185], v133 offset:16384
	ds_read_b128 v[186:189], v133 offset:17408
	ds_read_b128 v[190:193], v132 offset:16384
	ds_read_b128 v[194:197], v132 offset:17408
	s_waitcnt vmcnt(4)
	s_barrier
; #define LDA(dst, b, h) _Pragma("unroll") for (int m = 0; m < 4; ++m) _Pragma("unroll") for (int k = 0; k < 2; ++k) \
;     dst[m][k] = *reinterpret_cast<const bf16x8*>(SA(b, h) + lds_byte(wr * 64 + m * 16 + fr, k * 32 + fq * 8))
; #define LDB(dst, b, h) _Pragma("unroll") for (int n = 0; n < 2; ++n) _Pragma("unroll") for (int k = 0; k < 2; ++k) \
;     dst[n][k] = *reinterpret_cast<const bf16x8*>(SB(b, h) + lds_byte(wc * 32 + n * 16 + fr, k * 32 + fq * 8))
; #define WAIT_V(n) asm volatile("s_waitcnt vmcnt(" #n ")" ::: "memory")
; #define WAIT_L(n) asm volatile("s_waitcnt lgkmcnt(" #n ")" ::: "memory")
; #define BAR __builtin_amdgcn_s_barrier()
;     ...
;       LDA(At, 0, 1); WAIT_V(4); BAR; WAIT_L(0); MMA(1, 0, At, B0); MMA(1, 1, At, B1); BAR; }
;     { LDB(B0, 1, 0); LDA(At, 1, 0); WAIT_V(2); BAR; WAIT_L(0); MMA(0, 0, At, B0); BAR;
	s_waitcnt lgkmcnt(0)
	v_mfma_f32_16x16x32_bf16 v[60:63], v[154:157], v[166:169], v[60:63]
	v_mfma_f32_16x16x32_bf16 v[60:63], v[158:161], v[170:173], v[60:63]
	v_mfma_f32_16x16x32_bf16 v[56:59], v[150:153], v[170:173], v[56:59]
	v_mfma_f32_16x16x32_bf16 v[56:59], v[162:165], v[166:169], v[56:59]
	v_mfma_f32_16x16x32_bf16 v[48:51], v[162:165], v[174:177], v[48:51]
	v_mfma_f32_16x16x32_bf16 v[48:51], v[150:153], v[178:181], v[48:51]
	v_mfma_f32_16x16x32_bf16 v[52:55], v[158:161], v[178:181], v[52:55]
	v_mfma_f32_16x16x32_bf16 v[52:55], v[154:157], v[174:177], v[52:55]
	v_mfma_f32_16x16x32_bf16 v[44:47], v[154:157], v[182:185], v[44:47]
	v_mfma_f32_16x16x32_bf16 v[44:47], v[158:161], v[186:189], v[44:47]
	v_mfma_f32_16x16x32_bf16 v[40:43], v[150:153], v[186:189], v[40:43]
	v_mfma_f32_16x16x32_bf16 v[40:43], v[162:165], v[182:185], v[40:43]
	v_mfma_f32_16x16x32_bf16 v[32:35], v[162:165], v[190:193], v[32:35]
	v_mfma_f32_16x16x32_bf16 v[32:35], v[150:153], v[194:197], v[32:35]
	v_mfma_f32_16x16x32_bf16 v[36:39], v[158:161], v[194:197], v[36:39]
	v_mfma_f32_16x16x32_bf16 v[36:39], v[154:157], v[190:193], v[36:39]
	v_mfma_f32_16x16x32_bf16 v[4:7], v[198:201], v[190:193], v[4:7]
	v_mfma_f32_16x16x32_bf16 v[4:7], v[202:205], v[194:197], v[4:7]
	v_mfma_f32_16x16x32_bf16 v[28:31], v[202:205], v[170:173], v[28:31]
	v_mfma_f32_16x16x32_bf16 v[28:31], v[198:201], v[166:169], v[28:31]
	v_mfma_f32_16x16x32_bf16 v[24:27], v[144:147], v[166:169], v[24:27]
	v_mfma_f32_16x16x32_bf16 v[24:27], v[206:209], v[170:173], v[24:27]
	v_mfma_f32_16x16x32_bf16 v[16:19], v[206:209], v[178:181], v[16:19]
	v_mfma_f32_16x16x32_bf16 v[16:19], v[144:147], v[174:177], v[16:19]
	v_mfma_f32_16x16x32_bf16 v[20:23], v[198:201], v[174:177], v[20:23]
	v_mfma_f32_16x16x32_bf16 v[20:23], v[202:205], v[178:181], v[20:23]
	v_mfma_f32_16x16x32_bf16 v[12:15], v[202:205], v[186:189], v[12:15]
	v_mfma_f32_16x16x32_bf16 v[12:15], v[198:201], v[182:185], v[12:15]
	v_mfma_f32_16x16x32_bf16 v[8:11], v[144:147], v[182:185], v[8:11]
	v_mfma_f32_16x16x32_bf16 v[8:11], v[206:209], v[186:189], v[8:11]
	v_mfma_f32_16x16x32_bf16 v[0:3], v[206:209], v[194:197], v[0:3]
	v_mfma_f32_16x16x32_bf16 v[0:3], v[144:147], v[190:193], v[0:3]
	s_barrier
	ds_read_b128 v[144:147], v139
	ds_read_b128 v[148:151], v140
	ds_read_b128 v[152:155], v141
	ds_read_b128 v[140:143], v142
	ds_read_b128 v[156:159], v131 offset:32768
	ds_read_b128 v[160:163], v131 offset:33792
	ds_read_b128 v[164:167], v134 offset:32768
	ds_read_b128 v[168:171], v134 offset:33792
	ds_read_b128 v[172:175], v133 offset:32768
	ds_read_b128 v[176:179], v133 offset:33792
	ds_read_b128 v[180:183], v132 offset:32768
	ds_read_b128 v[184:187], v132 offset:33792
	s_waitcnt vmcnt(2)
	s_barrier
	s_waitcnt lgkmcnt(6)
	v_mfma_f32_16x16x32_bf16 v[124:127], v[144:147], v[156:159], v[124:127]
	v_mfma_f32_16x16x32_bf16 v[124:127], v[148:151], v[160:163], v[124:127]
	v_mfma_f32_16x16x32_bf16 v[120:123], v[140:143], v[160:163], v[120:123]
	v_mfma_f32_16x16x32_bf16 v[120:123], v[152:155], v[156:159], v[120:123]
	s_waitcnt lgkmcnt(4)
	v_mfma_f32_16x16x32_bf16 v[112:115], v[152:155], v[164:167], v[112:115]
	v_mfma_f32_16x16x32_bf16 v[112:115], v[140:143], v[168:171], v[112:115]
	v_mfma_f32_16x16x32_bf16 v[116:119], v[148:151], v[168:171], v[116:119]
	v_mfma_f32_16x16x32_bf16 v[116:119], v[144:147], v[164:167], v[116:119]
	s_waitcnt lgkmcnt(2)
	v_mfma_f32_16x16x32_bf16 v[108:111], v[144:147], v[172:175], v[108:111]
	v_mfma_f32_16x16x32_bf16 v[108:111], v[148:151], v[176:179], v[108:111]
	v_mfma_f32_16x16x32_bf16 v[104:107], v[140:143], v[176:179], v[104:107]
	v_mfma_f32_16x16x32_bf16 v[104:107], v[152:155], v[172:175], v[104:107]
	s_waitcnt lgkmcnt(0)
	v_mfma_f32_16x16x32_bf16 v[96:99], v[152:155], v[180:183], v[96:99]
	v_mfma_f32_16x16x32_bf16 v[96:99], v[140:143], v[184:187], v[96:99]
	v_mfma_f32_16x16x32_bf16 v[100:103], v[148:151], v[184:187], v[100:103]
	v_mfma_f32_16x16x32_bf16 v[100:103], v[144:147], v[180:183], v[100:103]
	s_barrier
; #define LDA(dst, b, h) _Pragma("unroll") for (int m = 0; m < 4; ++m) _Pragma("unroll") for (int k = 0; k < 2; ++k) \
;     dst[m][k] = *reinterpret_cast<const bf16x8*>(SA(b, h) + lds_byte(wr * 64 + m * 16 + fr, k * 32 + fq * 8))
; #define LDB(dst, b, h) _Pragma("unroll") for (int n = 0; n < 2; ++n) _Pragma("unroll") for (int k = 0; k < 2; ++k) \
;     dst[n][k] = *reinterpret_cast<const bf16x8*>(SB(b, h) + lds_byte(wc * 32 + n * 16 + fr, k * 32 + fq * 8))
; #define WAIT_V(n) asm volatile("s_waitcnt vmcnt(" #n ")" ::: "memory")
; #define WAIT_L(n) asm volatile("s_waitcnt lgkmcnt(" #n ")" ::: "memory")
; #define BAR __builtin_amdgcn_s_barrier()
;     ...
;       LDB(B1, 1, 1); WAIT_V(0); BAR; WAIT_L(0); MMA(0, 1, At, B1); BAR;
;       LDA(At, 1, 1); BAR; WAIT_L(0); MMA(1, 0, At, B0); MMA(1, 1, At, B1); BAR; }
;     if (wr == 0) BAR;
	ds_read_b128 v[188:191], v135
	ds_read_b128 v[192:195], v136
	ds_read_b128 v[196:199], v137
	ds_read_b128 v[136:139], v138
	s_waitcnt vmcnt(0)
	s_barrier
	s_waitcnt lgkmcnt(2)
	v_mfma_f32_16x16x32_bf16 v[92:95], v[188:191], v[156:159], v[92:95]
	v_mfma_f32_16x16x32_bf16 v[92:95], v[192:195], v[160:163], v[92:95]
	s_waitcnt lgkmcnt(0)
	v_mfma_f32_16x16x32_bf16 v[88:91], v[136:139], v[160:163], v[88:91]
	v_mfma_f32_16x16x32_bf16 v[88:91], v[196:199], v[156:159], v[88:91]
	v_mfma_f32_16x16x32_bf16 v[80:83], v[196:199], v[164:167], v[80:83]
	v_mfma_f32_16x16x32_bf16 v[80:83], v[136:139], v[168:171], v[80:83]
	v_mfma_f32_16x16x32_bf16 v[84:87], v[192:195], v[168:171], v[84:87]
	v_mfma_f32_16x16x32_bf16 v[84:87], v[188:191], v[164:167], v[84:87]
	v_mfma_f32_16x16x32_bf16 v[76:79], v[188:191], v[172:175], v[76:79]
	v_mfma_f32_16x16x32_bf16 v[76:79], v[192:195], v[176:179], v[76:79]
	v_mfma_f32_16x16x32_bf16 v[72:75], v[136:139], v[176:179], v[72:75]
	v_mfma_f32_16x16x32_bf16 v[72:75], v[196:199], v[172:175], v[72:75]
	v_mfma_f32_16x16x32_bf16 v[64:67], v[196:199], v[180:183], v[64:67]
	v_mfma_f32_16x16x32_bf16 v[64:67], v[136:139], v[184:187], v[64:67]
	v_mfma_f32_16x16x32_bf16 v[68:71], v[192:195], v[184:187], v[68:71]
	v_mfma_f32_16x16x32_bf16 v[68:71], v[188:191], v[180:183], v[68:71]
	s_barrier
	ds_read_b128 v[156:159], v131 offset:49152
	ds_read_b128 v[160:163], v131 offset:50176
	ds_read_b128 v[164:167], v134 offset:49152
	ds_read_b128 v[168:171], v134 offset:50176
	ds_read_b128 v[172:175], v133 offset:49152
	ds_read_b128 v[176:179], v133 offset:50176
	ds_read_b128 v[180:183], v132 offset:49152
	ds_read_b128 v[132:135], v132 offset:50176
	s_barrier
	s_waitcnt lgkmcnt(0)
	v_mfma_f32_16x16x32_bf16 v[60:63], v[144:147], v[156:159], v[60:63]
	v_mfma_f32_16x16x32_bf16 v[60:63], v[148:151], v[160:163], v[60:63]
	v_mfma_f32_16x16x32_bf16 v[56:59], v[140:143], v[160:163], v[56:59]
	v_mfma_f32_16x16x32_bf16 v[56:59], v[152:155], v[156:159], v[56:59]
	v_mfma_f32_16x16x32_bf16 v[48:51], v[152:155], v[164:167], v[48:51]
	v_mfma_f32_16x16x32_bf16 v[48:51], v[140:143], v[168:171], v[48:51]
	v_mfma_f32_16x16x32_bf16 v[52:55], v[148:151], v[168:171], v[52:55]
	v_mfma_f32_16x16x32_bf16 v[52:55], v[144:147], v[164:167], v[52:55]
	v_mfma_f32_16x16x32_bf16 v[44:47], v[144:147], v[172:175], v[44:47]
	v_mfma_f32_16x16x32_bf16 v[44:47], v[148:151], v[176:179], v[44:47]
	v_mfma_f32_16x16x32_bf16 v[40:43], v[140:143], v[176:179], v[40:43]
	v_mfma_f32_16x16x32_bf16 v[40:43], v[152:155], v[172:175], v[40:43]
	v_mfma_f32_16x16x32_bf16 v[32:35], v[152:155], v[180:183], v[32:35]
	v_mfma_f32_16x16x32_bf16 v[32:35], v[140:143], v[132:135], v[32:35]
	v_mfma_f32_16x16x32_bf16 v[36:39], v[148:151], v[132:135], v[36:39]
	v_mfma_f32_16x16x32_bf16 v[36:39], v[144:147], v[180:183], v[36:39]
	v_mfma_f32_16x16x32_bf16 v[4:7], v[188:191], v[180:183], v[4:7]
	v_mfma_f32_16x16x32_bf16 v[4:7], v[192:195], v[132:135], v[4:7]
	v_mfma_f32_16x16x32_bf16 v[28:31], v[192:195], v[160:163], v[28:31]
	v_mfma_f32_16x16x32_bf16 v[28:31], v[188:191], v[156:159], v[28:31]
	v_mfma_f32_16x16x32_bf16 v[24:27], v[196:199], v[156:159], v[24:27]
	v_mfma_f32_16x16x32_bf16 v[24:27], v[136:139], v[160:163], v[24:27]
	v_mfma_f32_16x16x32_bf16 v[16:19], v[136:139], v[168:171], v[16:19]
	v_mfma_f32_16x16x32_bf16 v[16:19], v[196:199], v[164:167], v[16:19]
	v_mfma_f32_16x16x32_bf16 v[20:23], v[188:191], v[164:167], v[20:23]
	v_mfma_f32_16x16x32_bf16 v[20:23], v[192:195], v[168:171], v[20:23]
	v_mfma_f32_16x16x32_bf16 v[12:15], v[192:195], v[176:179], v[12:15]
	v_mfma_f32_16x16x32_bf16 v[12:15], v[188:191], v[172:175], v[12:15]
	v_mfma_f32_16x16x32_bf16 v[8:11], v[196:199], v[172:175], v[8:11]
	v_mfma_f32_16x16x32_bf16 v[8:11], v[136:139], v[176:179], v[8:11]
	v_mfma_f32_16x16x32_bf16 v[0:3], v[136:139], v[132:135], v[0:3]
	v_mfma_f32_16x16x32_bf16 v[0:3], v[196:199], v[180:183], v[0:3]
	v_cmp_gt_u32_e32 vcc, s35, v130
	s_barrier
	s_and_saveexec_b64 s[10:11], vcc
	s_cbranch_execz .LBB0_559
	s_barrier

; #define STAGE(P, RS, SOFF, OFF, kt) do { const int _so = (SOFF) + (kt) * (BK * 2); \
;     _Pragma("unroll") for (int _i = 0; _i < 2; ++_i) { \
;       __builtin_amdgcn_raw_ptr_buffer_load_lds(RS, (__attribute__((address_space(3))) void*)((P) + wave * 1024 + _i * 8192), 16, OFF[_i], _so, 0, 0); } } while (0)
; #define LDA(dst, b, h) _Pragma("unroll") for (int m = 0; m < 4; ++m) _Pragma("unroll") for (int k = 0; k < 2; ++k) \
;     dst[m][k] = *reinterpret_cast<const bf16x8*>(SA(b, h) + lds_byte(wr * 64 + m * 16 + fr, k * 32 + fq * 8))
; #define LDB(dst, b, h) _Pragma("unroll") for (int n = 0; n < 2; ++n) _Pragma("unroll") for (int k = 0; k < 2; ++k) \
;     dst[n][k] = *reinterpret_cast<const bf16x8*>(SB(b, h) + lds_byte(wc * 32 + n * 16 + fr, k * 32 + fq * 8))
; #define WAIT_V(n) asm volatile("s_waitcnt vmcnt(" #n ")" ::: "memory")
; #define WAIT_L(n) asm volatile("s_waitcnt lgkmcnt(" #n ")" ::: "memory")
; #define BAR __builtin_amdgcn_s_barrier()
; #define SCHED __builtin_amdgcn_sched_barrier(0)
;     ...
;     const int tid = opaque_tid(wave);
;     const int wid = tid >> 6, lane = tid & 63, wr = wid >> 2, wc = wid & 3, fr = lane & 15, fq = lane >> 4;
;     int offA[2], offB[2];
;     _Pragma("unroll") for (int i = 0; i < 2; ++i) {
;       int r, c; stage_rc(tid * 16 + i * 8192, r, c);
;       offA[i] = (r * lda + c) * 2; offB[i] = (r * ldb + c) * 2;
;     }
;     const int brow = pm * BM;
;     f32x4 acc[2][2][4][2];
;     _Pragma("unroll") for (int a = 0; a < 2; ++a) _Pragma("unroll") for (int b = 0; b < 2; ++b) _Pragma("unroll") for (int m = 0; m < 4; ++m) _Pragma("unroll") for (int n = 0; n < 2; ++n)
;       acc[a][b][m][n] = f32x4{0.f, 0.f, 0.f, 0.f};
;     bf16x8 At[4][2], B0[2][2], B1[2][2];
;     if (wr == 1) BAR;
;     if (first_tile) { WAIT_V(0); }
;     else if constexpr (mode == MODE_RESID_LN) { WAIT_V(0); }
;     else if constexpr (mode == MODE_SWIGLU) { WAIT_V(6); }
;     else if constexpr (mode == MODE_V) { WAIT_V(24); }
;     else { WAIT_V(12); }
;     first_tile = false;
;     BAR;
;     BAR;
;     for (int t = 0; t < nt - 2; t += 2) {
;       LDB(B0, 0, 0); SCHED; LDA(At, 0, 0); STAGE(SA(1, 1), rsA, sA1, offA, t + 1);
;       WAIT_L(8); BAR; WAIT_L(0); MMA(0, 0, At, B0); BAR; SCHED;
.LBB0_656:
	v_bfe_i32 v4, v128, 27, 1
	v_lshlrev_b32_e32 v2, 4, v128
	v_lshrrev_b32_e32 v4, 22, v4
	v_add_u32_e32 v4, v2, v4
	v_and_b32_e32 v4, 0xfffffc00, v4
	v_sub_u32_e32 v4, v2, v4
	v_lshrrev_b32_e32 v5, 4, v4
	v_bitop3_b32 v4, v5, v4, 32 bitop3:0x6c
	v_ashrrev_i32_e32 v3, 31, v128
	v_ashrrev_i32_e32 v6, 31, v4
	v_lshrrev_b32_e32 v3, 26, v3
	v_lshrrev_b32_e32 v6, 26, v6
	v_add_u32_e32 v3, v128, v3
	v_add_u32_e32 v6, v4, v6
	v_ashrrev_i32_e32 v3, 6, v3
	v_lshrrev_b32_e32 v7, 6, v6
	v_and_b32_e32 v6, 0xc0, v6
	v_lshlrev_b32_e32 v5, 3, v3
	v_lshlrev_b32_e32 v3, 5, v3
	v_sub_u32_e32 v4, v4, v6
	v_and_b32_e32 v5, 0xffff0, v5
	v_and_b32_e32 v3, 32, v3
	v_ashrrev_i16_sdwa v4, v216, sext(v4) dst_sel:DWORD dst_unused:UNUSED_PAD src0_sel:DWORD src1_sel:BYTE_0
	v_add_u32_sdwa v3, v3, sext(v4) dst_sel:DWORD dst_unused:UNUSED_PAD src0_sel:DWORD src1_sel:WORD_0
	v_add_lshl_u32 v4, v7, v5, 12
	v_add_u32_e32 v2, 0x2000, v2
	v_lshl_add_u32 v141, v3, 1, v4
	v_ashrrev_i32_e32 v3, 31, v2
	v_lshrrev_b32_e32 v3, 22, v3
	v_add_u32_e32 v3, v2, v3
	v_ashrrev_i32_e32 v3, 10, v3
	v_mul_i32_i24_e32 v4, 0x400, v3
	v_sub_u32_e32 v2, v2, v4
	v_lshrrev_b32_e32 v4, 4, v2
	v_bitop3_b32 v2, v4, v2, 32 bitop3:0x6c
	v_ashrrev_i32_e32 v5, 31, v2
	v_lshrrev_b32_e32 v5, 26, v5
	v_add_u32_e32 v5, v2, v5
	v_lshrrev_b32_e32 v6, 6, v5
	v_and_b32_e32 v5, 0xc0, v5
	v_lshlrev_b32_e32 v4, 3, v3
	v_lshlrev_b32_e32 v3, 5, v3
	v_sub_u32_e32 v2, v2, v5
	v_and_b32_e32 v4, 0xffff0, v4
	v_and_b32_e32 v3, 32, v3
	v_ashrrev_i16_sdwa v2, v216, sext(v2) dst_sel:DWORD dst_unused:UNUSED_PAD src0_sel:DWORD src1_sel:BYTE_0
	v_add_u32_sdwa v2, v3, sext(v2) dst_sel:DWORD dst_unused:UNUSED_PAD src0_sel:DWORD src1_sel:WORD_0
	v_add_lshl_u32 v3, v6, v4, 12
	v_lshl_add_u32 v142, v2, 1, v3
	v_and_b32_e32 v3, 15, v0
	v_lshlrev_b32_e32 v5, 2, v0
	v_and_b32_e32 v2, 48, v0
	v_lshlrev_b32_e32 v3, 6, v3
	v_and_b32_e32 v5, 32, v5
	v_or_b32_e32 v4, v3, v2
	v_bitop3_b32 v3, v3, v5, v2 bitop3:0x36
	v_lshlrev_b32_e32 v6, 6, v128
	s_movk_i32 s1, 0x3000
	v_and_or_b32 v3, v6, s1, v3
	v_lshlrev_b32_e32 v0, 6, v0
	s_movk_i32 s1, 0x3c0
	v_lshlrev_b32_e32 v1, 13, v1
	v_and_or_b32 v0, v0, s1, v2
	v_bitop3_b32 v0, v1, v0, v5 bitop3:0xf6
	v_or_b32_e32 v6, 0x400, v3
	v_or_b32_e32 v7, 0x800, v3
	v_or_b32_e32 v8, 0xc00, v3
	v_or_b32_e32 v132, 0x800, v0
	v_or_b32_e32 v131, 0x1000, v0
	v_or_b32_e32 v130, 0x1800, v0
	v_mov_b32_e32 v0, 0
	v_bitop3_b32 v129, v4, v1, v5 bitop3:0xde
	s_mov_b32 s1, -2
	s_mov_b32 s3, 0
	v_or_b32_e32 v147, 0x10000, v3
	v_or_b32_e32 v148, 0x10000, v6
	v_or_b32_e32 v149, 0x10000, v7
	v_or_b32_e32 v150, 0x10000, v8
	v_or_b32_e32 v143, 0x14000, v3
	v_or_b32_e32 v144, 0x14000, v6
	v_or_b32_e32 v145, 0x14000, v7
	v_or_b32_e32 v146, 0x14000, v8
	v_or_b32_e32 v137, 0x18000, v3
	v_or_b32_e32 v138, 0x18000, v6
	v_or_b32_e32 v139, 0x18000, v7
	v_or_b32_e32 v140, 0x18000, v8
	v_or_b32_e32 v133, 0x1c000, v3
	v_or_b32_e32 v134, 0x1c000, v6
	v_or_b32_e32 v135, 0x1c000, v7
	v_or_b32_e32 v136, 0x1c000, v8
	s_barrier
	s_barrier
	ds_read_b128 v[152:155], v147
	ds_read_b128 v[156:159], v148
	ds_read_b128 v[160:163], v149
	ds_read_b128 v[164:167], v150
	s_add_i32 s5, s81, s3
	s_add_i32 s6, s5, 0x80
	s_mov_b32 m0, s39
	ds_read_b128 v[168:171], v129
	ds_read_b128 v[172:175], v129 offset:1024
	ds_read_b128 v[176:179], v132
	ds_read_b128 v[180:183], v132 offset:1024
	ds_read_b128 v[184:187], v131
	ds_read_b128 v[188:191], v131 offset:1024
	ds_read_b128 v[192:195], v130
	ds_read_b128 v[196:199], v130 offset:1024
	buffer_load_dwordx4 v141, s[8:11], s6 offen lds
	s_mov_b32 m0, s58
	s_nop 0
	buffer_load_dwordx4 v142, s[8:11], s6 offen lds
	s_waitcnt lgkmcnt(8)
	s_barrier
	s_waitcnt lgkmcnt(0)
	v_mfma_f32_16x16x32_bf16 v[124:127], v[152:155], v[168:171], 0
	v_mfma_f32_16x16x32_bf16 v[124:127], v[156:159], v[172:175], v[124:127]
	v_mfma_f32_16x16x32_bf16 v[120:123], v[164:167], v[172:175], 0
	v_mfma_f32_16x16x32_bf16 v[120:123], v[160:163], v[168:171], v[120:123]
	v_mfma_f32_16x16x32_bf16 v[112:115], v[160:163], v[176:179], 0
	v_mfma_f32_16x16x32_bf16 v[112:115], v[164:167], v[180:183], v[112:115]
	v_mfma_f32_16x16x32_bf16 v[116:119], v[156:159], v[180:183], 0
	v_mfma_f32_16x16x32_bf16 v[116:119], v[152:155], v[176:179], v[116:119]
	v_mfma_f32_16x16x32_bf16 v[108:111], v[152:155], v[184:187], 0
	v_mfma_f32_16x16x32_bf16 v[108:111], v[156:159], v[188:191], v[108:111]
	v_mfma_f32_16x16x32_bf16 v[104:107], v[164:167], v[188:191], 0
	v_mfma_f32_16x16x32_bf16 v[104:107], v[160:163], v[184:187], v[104:107]
	v_mfma_f32_16x16x32_bf16 v[96:99], v[160:163], v[192:195], 0
	v_mfma_f32_16x16x32_bf16 v[96:99], v[164:167], v[196:199], v[96:99]
	v_mfma_f32_16x16x32_bf16 v[100:103], v[156:159], v[196:199], 0
	v_mfma_f32_16x16x32_bf16 v[100:103], v[152:155], v[192:195], v[100:103]
	s_barrier
	s_add_i32 s6, s83, s3
	s_add_i32 s7, s6, 0x100
	s_mov_b32 s14, s10
	s_mov_b32 s15, s11
	s_mov_b32 m0, s85
	ds_read_b128 v[200:203], v143
	ds_read_b128 v[204:207], v144
	ds_read_b128 v[208:211], v145
	ds_read_b128 v[212:215], v146
	buffer_load_dwordx4 v141, s[12:15], s7 offen lds
	s_mov_b32 m0, s75
	s_nop 0
	buffer_load_dwordx4 v142, s[12:15], s7 offen lds
	s_barrier
; #define STAGE(P, RS, SOFF, OFF, kt) do { const int _so = (SOFF) + (kt) * (BK * 2); \
;     _Pragma("unroll") for (int _i = 0; _i < 2; ++_i) { \
;       __builtin_amdgcn_raw_ptr_buffer_load_lds(RS, (__attribute__((address_space(3))) void*)((P) + wave * 1024 + _i * 8192), 16, OFF[_i], _so, 0, 0); } } while (0)
; #define LDA(dst, b, h) _Pragma("unroll") for (int m = 0; m < 4; ++m) _Pragma("unroll") for (int k = 0; k < 2; ++k) \
;     dst[m][k] = *reinterpret_cast<const bf16x8*>(SA(b, h) + lds_byte(wr * 64 + m * 16 + fr, k * 32 + fq * 8))
; #define LDB(dst, b, h) _Pragma("unroll") for (int n = 0; n < 2; ++n) _Pragma("unroll") for (int k = 0; k < 2; ++k) \
;     dst[n][k] = *reinterpret_cast<const bf16x8*>(SB(b, h) + lds_byte(wc * 32 + n * 16 + fr, k * 32 + fq * 8))
; #define WAIT_V(n) asm volatile("s_waitcnt vmcnt(" #n ")" ::: "memory")
; #define WAIT_L(n) asm volatile("s_waitcnt lgkmcnt(" #n ")" ::: "memory")
; #define BAR __builtin_amdgcn_s_barrier()
; #define SCHED __builtin_amdgcn_sched_barrier(0)
;     ...
;       WAIT_L(8); BAR; WAIT_L(0); MMA(0, 0, At, B0); BAR; SCHED;
;       LDB(B1, 0, 1); STAGE(SB(0, 0), rsB, sB0, offB, t + 2);
;       BAR; WAIT_L(0); MMA(0, 1, At, B1); BAR;
;       LDA(At, 0, 1); STAGE(SA(0, 0), rsA, sA0, offA, t + 2);
;       BAR; WAIT_L(0); MMA(1, 0, At, B0); BAR; SCHED;
;       STAGE(SB(0, 1), rsB, sB1, offB, t + 2);
;       WAIT_V(6); BAR; MMA(1, 1, At, B1); BAR;
;       LDB(B0, 1, 0); SCHED; LDA(At, 1, 0); STAGE(SA(0, 1), rsA, sA1, offA, t + 2);
	s_waitcnt lgkmcnt(2)
	v_mfma_f32_16x16x32_bf16 v[92:95], v[200:203], v[168:171], 0
	v_mfma_f32_16x16x32_bf16 v[92:95], v[204:207], v[172:175], v[92:95]
	s_waitcnt lgkmcnt(0)
	v_mfma_f32_16x16x32_bf16 v[88:91], v[212:215], v[172:175], 0
	v_mfma_f32_16x16x32_bf16 v[88:91], v[208:211], v[168:171], v[88:91]
	v_mfma_f32_16x16x32_bf16 v[68:71], v[208:211], v[176:179], 0
	v_mfma_f32_16x16x32_bf16 v[68:71], v[212:215], v[180:183], v[68:71]
	v_mfma_f32_16x16x32_bf16 v[80:83], v[204:207], v[180:183], 0
	v_mfma_f32_16x16x32_bf16 v[80:83], v[200:203], v[176:179], v[80:83]
	v_mfma_f32_16x16x32_bf16 v[60:63], v[200:203], v[184:187], 0
	v_mfma_f32_16x16x32_bf16 v[60:63], v[204:207], v[188:191], v[60:63]
	v_mfma_f32_16x16x32_bf16 v[56:59], v[212:215], v[188:191], 0
	v_mfma_f32_16x16x32_bf16 v[56:59], v[208:211], v[184:187], v[56:59]
	v_mfma_f32_16x16x32_bf16 v[48:51], v[208:211], v[192:195], 0
	v_mfma_f32_16x16x32_bf16 v[48:51], v[212:215], v[196:199], v[48:51]
	v_mfma_f32_16x16x32_bf16 v[52:55], v[204:207], v[196:199], 0
	v_mfma_f32_16x16x32_bf16 v[52:55], v[200:203], v[192:195], v[52:55]
	s_barrier
	s_add_i32 s7, s82, s3
	s_add_i32 s22, s7, 0x100
	s_mov_b32 m0, s38
	ds_read_b128 v[168:171], v129 offset:16384
	ds_read_b128 v[172:175], v129 offset:17408
	ds_read_b128 v[176:179], v132 offset:16384
	ds_read_b128 v[180:183], v132 offset:17408
	ds_read_b128 v[184:187], v131 offset:16384
	ds_read_b128 v[188:191], v131 offset:17408
	ds_read_b128 v[192:195], v130 offset:16384
	ds_read_b128 v[196:199], v130 offset:17408
	buffer_load_dwordx4 v141, s[8:11], s22 offen lds
	s_mov_b32 m0, s95
	s_nop 0
	buffer_load_dwordx4 v142, s[8:11], s22 offen lds
	s_barrier
	s_waitcnt lgkmcnt(6)
	v_mfma_f32_16x16x32_bf16 v[44:47], v[152:155], v[168:171], 0
	v_mfma_f32_16x16x32_bf16 v[44:47], v[156:159], v[172:175], v[44:47]
	v_mfma_f32_16x16x32_bf16 v[40:43], v[164:167], v[172:175], 0
	v_mfma_f32_16x16x32_bf16 v[40:43], v[160:163], v[168:171], v[40:43]
	s_waitcnt lgkmcnt(4)
	v_mfma_f32_16x16x32_bf16 v[32:35], v[160:163], v[176:179], 0
	v_mfma_f32_16x16x32_bf16 v[32:35], v[164:167], v[180:183], v[32:35]
	v_mfma_f32_16x16x32_bf16 v[36:39], v[156:159], v[180:183], 0
	v_mfma_f32_16x16x32_bf16 v[36:39], v[152:155], v[176:179], v[36:39]
	s_waitcnt lgkmcnt(2)
	v_mfma_f32_16x16x32_bf16 v[28:31], v[152:155], v[184:187], 0
	v_mfma_f32_16x16x32_bf16 v[28:31], v[156:159], v[188:191], v[28:31]
	v_mfma_f32_16x16x32_bf16 v[24:27], v[164:167], v[188:191], 0
	v_mfma_f32_16x16x32_bf16 v[24:27], v[160:163], v[184:187], v[24:27]
	s_waitcnt lgkmcnt(0)
	v_mfma_f32_16x16x32_bf16 v[16:19], v[160:163], v[192:195], 0
	v_mfma_f32_16x16x32_bf16 v[16:19], v[164:167], v[196:199], v[16:19]
	v_mfma_f32_16x16x32_bf16 v[20:23], v[156:159], v[196:199], 0
	v_mfma_f32_16x16x32_bf16 v[20:23], v[152:155], v[192:195], v[20:23]
	s_barrier
	s_add_i32 s22, s84, s3
	s_add_i32 s23, s22, 0x100
	s_mov_b32 m0, s86
	s_nop 0
	buffer_load_dwordx4 v141, s[12:15], s23 offen lds
	s_mov_b32 m0, s28
	s_nop 0
	buffer_load_dwordx4 v142, s[12:15], s23 offen lds
	s_waitcnt vmcnt(6)
	s_barrier
	v_mfma_f32_16x16x32_bf16 v[12:15], v[200:203], v[168:171], 0
	v_mfma_f32_16x16x32_bf16 v[12:15], v[204:207], v[172:175], v[12:15]
	v_mfma_f32_16x16x32_bf16 v[8:11], v[212:215], v[172:175], 0
	v_mfma_f32_16x16x32_bf16 v[8:11], v[208:211], v[168:171], v[8:11]
	v_mfma_f32_16x16x32_bf16 v[0:3], v[208:211], v[176:179], 0
	v_mfma_f32_16x16x32_bf16 v[0:3], v[212:215], v[180:183], v[0:3]
	v_mfma_f32_16x16x32_bf16 v[4:7], v[204:207], v[180:183], 0
	v_mfma_f32_16x16x32_bf16 v[4:7], v[200:203], v[176:179], v[4:7]
	v_mfma_f32_16x16x32_bf16 v[64:67], v[200:203], v[184:187], 0
	v_mfma_f32_16x16x32_bf16 v[64:67], v[204:207], v[188:191], v[64:67]
	v_mfma_f32_16x16x32_bf16 v[72:75], v[212:215], v[188:191], 0
	v_mfma_f32_16x16x32_bf16 v[72:75], v[208:211], v[184:187], v[72:75]
	v_mfma_f32_16x16x32_bf16 v[84:87], v[208:211], v[192:195], 0
	v_mfma_f32_16x16x32_bf16 v[84:87], v[212:215], v[196:199], v[84:87]
	v_mfma_f32_16x16x32_bf16 v[76:79], v[204:207], v[196:199], 0
	v_mfma_f32_16x16x32_bf16 v[76:79], v[200:203], v[192:195], v[76:79]
	s_barrier
	ds_read_b128 v[152:155], v137
	ds_read_b128 v[156:159], v138
	ds_read_b128 v[160:163], v139
	ds_read_b128 v[164:167], v140
	s_addk_i32 s5, 0x100
	s_mov_b32 m0, s87
	ds_read_b128 v[168:171], v129 offset:32768
	ds_read_b128 v[172:175], v129 offset:33792
	ds_read_b128 v[176:179], v132 offset:32768
	ds_read_b128 v[180:183], v132 offset:33792
	ds_read_b128 v[184:187], v131 offset:32768
	ds_read_b128 v[188:191], v131 offset:33792
	ds_read_b128 v[192:195], v130 offset:32768
	ds_read_b128 v[196:199], v130 offset:33792
	buffer_load_dwordx4 v141, s[8:11], s5 offen lds
	s_mov_b32 m0, s97
	s_nop 0
	buffer_load_dwordx4 v142, s[8:11], s5 offen lds
	s_waitcnt lgkmcnt(8)
	s_barrier
; #define STAGE(P, RS, SOFF, OFF, kt) do { const int _so = (SOFF) + (kt) * (BK * 2); \
;     _Pragma("unroll") for (int _i = 0; _i < 2; ++_i) { \
;       __builtin_amdgcn_raw_ptr_buffer_load_lds(RS, (__attribute__((address_space(3))) void*)((P) + wave * 1024 + _i * 8192), 16, OFF[_i], _so, 0, 0); } } while (0)
; #define LDA(dst, b, h) _Pragma("unroll") for (int m = 0; m < 4; ++m) _Pragma("unroll") for (int k = 0; k < 2; ++k) \
;     dst[m][k] = *reinterpret_cast<const bf16x8*>(SA(b, h) + lds_byte(wr * 64 + m * 16 + fr, k * 32 + fq * 8))
; #define LDB(dst, b, h) _Pragma("unroll") for (int n = 0; n < 2; ++n) _Pragma("unroll") for (int k = 0; k < 2; ++k) \
;     dst[n][k] = *reinterpret_cast<const bf16x8*>(SB(b, h) + lds_byte(wc * 32 + n * 16 + fr, k * 32 + fq * 8))
; #define WAIT_L(n) asm volatile("s_waitcnt lgkmcnt(" #n ")" ::: "memory")
; #define BAR __builtin_amdgcn_s_barrier()
; #define SCHED __builtin_amdgcn_sched_barrier(0)
;     ...
;       WAIT_L(8); BAR; WAIT_L(0); MMA(0, 0, At, B0); BAR; SCHED;
;       LDB(B1, 1, 1); STAGE(SB(1, 0), rsB, sB0, offB, t + 3);
;       BAR; WAIT_L(0); MMA(0, 1, At, B1); BAR;
;       LDA(At, 1, 1); STAGE(SA(1, 0), rsA, sA0, offA, t + 3);
;       BAR; WAIT_L(0); MMA(1, 0, At, B0); BAR; SCHED;
;       STAGE(SB(1, 1), rsB, sB1, offB, t + 3);
	s_waitcnt lgkmcnt(6)
	v_mfma_f32_16x16x32_bf16 v[124:127], v[152:155], v[168:171], v[124:127]
	v_mfma_f32_16x16x32_bf16 v[124:127], v[156:159], v[172:175], v[124:127]
	v_mfma_f32_16x16x32_bf16 v[120:123], v[164:167], v[172:175], v[120:123]
	v_mfma_f32_16x16x32_bf16 v[120:123], v[160:163], v[168:171], v[120:123]
	s_waitcnt lgkmcnt(4)
	v_mfma_f32_16x16x32_bf16 v[112:115], v[160:163], v[176:179], v[112:115]
	v_mfma_f32_16x16x32_bf16 v[112:115], v[164:167], v[180:183], v[112:115]
	v_mfma_f32_16x16x32_bf16 v[116:119], v[156:159], v[180:183], v[116:119]
	v_mfma_f32_16x16x32_bf16 v[116:119], v[152:155], v[176:179], v[116:119]
	s_waitcnt lgkmcnt(2)
	v_mfma_f32_16x16x32_bf16 v[108:111], v[152:155], v[184:187], v[108:111]
	v_mfma_f32_16x16x32_bf16 v[108:111], v[156:159], v[188:191], v[108:111]
	v_mfma_f32_16x16x32_bf16 v[104:107], v[164:167], v[188:191], v[104:107]
	v_mfma_f32_16x16x32_bf16 v[104:107], v[160:163], v[184:187], v[104:107]
	s_waitcnt lgkmcnt(0)
	v_mfma_f32_16x16x32_bf16 v[96:99], v[160:163], v[192:195], v[96:99]
	v_mfma_f32_16x16x32_bf16 v[96:99], v[164:167], v[196:199], v[96:99]
	v_mfma_f32_16x16x32_bf16 v[100:103], v[156:159], v[196:199], v[100:103]
	v_mfma_f32_16x16x32_bf16 v[100:103], v[152:155], v[192:195], v[100:103]
	s_barrier
	s_addk_i32 s6, 0x180
	s_mov_b32 m0, s92
	ds_read_b128 v[200:203], v133
	ds_read_b128 v[204:207], v134
	ds_read_b128 v[208:211], v135
	ds_read_b128 v[212:215], v136
	buffer_load_dwordx4 v141, s[12:15], s6 offen lds
	s_mov_b32 m0, s29
	s_nop 0
	buffer_load_dwordx4 v142, s[12:15], s6 offen lds
	s_barrier
	s_waitcnt lgkmcnt(2)
	v_mfma_f32_16x16x32_bf16 v[92:95], v[200:203], v[168:171], v[92:95]
	v_mfma_f32_16x16x32_bf16 v[92:95], v[204:207], v[172:175], v[92:95]
	s_waitcnt lgkmcnt(0)
	v_mfma_f32_16x16x32_bf16 v[88:91], v[212:215], v[172:175], v[88:91]
	v_mfma_f32_16x16x32_bf16 v[88:91], v[208:211], v[168:171], v[88:91]
	v_mfma_f32_16x16x32_bf16 v[68:71], v[208:211], v[176:179], v[68:71]
	v_mfma_f32_16x16x32_bf16 v[68:71], v[212:215], v[180:183], v[68:71]
	v_mfma_f32_16x16x32_bf16 v[80:83], v[204:207], v[180:183], v[80:83]
	v_mfma_f32_16x16x32_bf16 v[80:83], v[200:203], v[176:179], v[80:83]
	v_mfma_f32_16x16x32_bf16 v[60:63], v[200:203], v[184:187], v[60:63]
	v_mfma_f32_16x16x32_bf16 v[60:63], v[204:207], v[188:191], v[60:63]
	v_mfma_f32_16x16x32_bf16 v[56:59], v[212:215], v[188:191], v[56:59]
	v_mfma_f32_16x16x32_bf16 v[56:59], v[208:211], v[184:187], v[56:59]
	v_mfma_f32_16x16x32_bf16 v[48:51], v[208:211], v[192:195], v[48:51]
	v_mfma_f32_16x16x32_bf16 v[48:51], v[212:215], v[196:199], v[48:51]
	v_mfma_f32_16x16x32_bf16 v[52:55], v[204:207], v[196:199], v[52:55]
	v_mfma_f32_16x16x32_bf16 v[52:55], v[200:203], v[192:195], v[52:55]
	s_barrier
	s_addk_i32 s7, 0x180
	s_mov_b32 m0, s93
	ds_read_b128 v[168:171], v129 offset:49152
	ds_read_b128 v[172:175], v129 offset:50176
	ds_read_b128 v[176:179], v132 offset:49152
	ds_read_b128 v[180:183], v132 offset:50176
	ds_read_b128 v[184:187], v131 offset:49152
	ds_read_b128 v[188:191], v131 offset:50176
	ds_read_b128 v[192:195], v130 offset:49152
	ds_read_b128 v[196:199], v130 offset:50176
	buffer_load_dwordx4 v141, s[8:11], s7 offen lds
	s_mov_b32 m0, s56
	s_nop 0
	buffer_load_dwordx4 v142, s[8:11], s7 offen lds
	s_barrier
	s_waitcnt lgkmcnt(6)
	v_mfma_f32_16x16x32_bf16 v[44:47], v[152:155], v[168:171], v[44:47]
	v_mfma_f32_16x16x32_bf16 v[44:47], v[156:159], v[172:175], v[44:47]
	v_mfma_f32_16x16x32_bf16 v[40:43], v[164:167], v[172:175], v[40:43]
	v_mfma_f32_16x16x32_bf16 v[40:43], v[160:163], v[168:171], v[40:43]
	s_waitcnt lgkmcnt(4)
	v_mfma_f32_16x16x32_bf16 v[32:35], v[160:163], v[176:179], v[32:35]
	v_mfma_f32_16x16x32_bf16 v[32:35], v[164:167], v[180:183], v[32:35]
	v_mfma_f32_16x16x32_bf16 v[36:39], v[156:159], v[180:183], v[36:39]
	v_mfma_f32_16x16x32_bf16 v[36:39], v[152:155], v[176:179], v[36:39]
	s_waitcnt lgkmcnt(2)
	v_mfma_f32_16x16x32_bf16 v[28:31], v[152:155], v[184:187], v[28:31]
	v_mfma_f32_16x16x32_bf16 v[28:31], v[156:159], v[188:191], v[28:31]
	v_mfma_f32_16x16x32_bf16 v[24:27], v[164:167], v[188:191], v[24:27]
	v_mfma_f32_16x16x32_bf16 v[24:27], v[160:163], v[184:187], v[24:27]
	s_waitcnt lgkmcnt(0)
	v_mfma_f32_16x16x32_bf16 v[16:19], v[160:163], v[192:195], v[16:19]
	v_mfma_f32_16x16x32_bf16 v[16:19], v[164:167], v[196:199], v[16:19]
	v_mfma_f32_16x16x32_bf16 v[20:23], v[156:159], v[196:199], v[20:23]
	v_mfma_f32_16x16x32_bf16 v[20:23], v[152:155], v[192:195], v[20:23]
	s_barrier
	s_addk_i32 s22, 0x180
	s_mov_b32 m0, s94
	s_nop 0
	buffer_load_dwordx4 v141, s[12:15], s22 offen lds
	s_mov_b32 m0, s57
	s_nop 0
	buffer_load_dwordx4 v142, s[12:15], s22 offen lds
	s_add_i32 s1, s1, 2
	s_addk_i32 s3, 0x100
	s_cmp_gt_u32 s1, 27
	s_cbranch_scc0 .LBB0_657
	s_branch .Lmy_post_657

; #define STAGE(P, RS, SOFF, OFF, kt) do { const int _so = (SOFF) + (kt) * (BK * 2); \
;     _Pragma("unroll") for (int _i = 0; _i < 2; ++_i) { \
;       __builtin_amdgcn_raw_ptr_buffer_load_lds(RS, (__attribute__((address_space(3))) void*)((P) + wave * 1024 + _i * 8192), 16, OFF[_i], _so, 0, 0); } } while (0)
; #define LDA(dst, b, h) _Pragma("unroll") for (int m = 0; m < 4; ++m) _Pragma("unroll") for (int k = 0; k < 2; ++k) \
;     dst[m][k] = *reinterpret_cast<const bf16x8*>(SA(b, h) + lds_byte(wr * 64 + m * 16 + fr, k * 32 + fq * 8))
; #define LDB(dst, b, h) _Pragma("unroll") for (int n = 0; n < 2; ++n) _Pragma("unroll") for (int k = 0; k < 2; ++k) \
;     dst[n][k] = *reinterpret_cast<const bf16x8*>(SB(b, h) + lds_byte(wc * 32 + n * 16 + fr, k * 32 + fq * 8))
; #define WAIT_V(n) asm volatile("s_waitcnt vmcnt(" #n ")" ::: "memory")
; #define WAIT_L(n) asm volatile("s_waitcnt lgkmcnt(" #n ")" ::: "memory")
; #define BAR __builtin_amdgcn_s_barrier()
; #define SCHED __builtin_amdgcn_sched_barrier(0)
;     ...
;       LDB(B0, 0, 0); SCHED; LDA(At, 0, 0); STAGE(SA(1, 1), rsA, sA1, offA, t + 1);
;       WAIT_L(8); BAR; WAIT_L(0); MMA(0, 0, At, B0); BAR; SCHED;
;       LDB(B1, 0, 1); STAGE(SB(0, 0), rsB, sB0, offB, t + 2);
;       BAR; WAIT_L(0); MMA(0, 1, At, B1); BAR;
;       LDA(At, 0, 1); STAGE(SA(0, 0), rsA, sA0, offA, t + 2);
;       BAR; WAIT_L(0); MMA(1, 0, At, B0); BAR; SCHED;
;       STAGE(SB(0, 1), rsB, sB1, offB, t + 2);
;       WAIT_V(6); BAR; MMA(1, 1, At, B1); BAR;
.Lmy_rot_657:
	ds_read_b128 v[152:155], v147
	ds_read_b128 v[156:159], v148
	ds_read_b128 v[160:163], v149
	ds_read_b128 v[164:167], v150
	s_add_i32 s5, s81, s3
	s_add_i32 s6, s5, 0x80
	s_mov_b32 m0, s39
	ds_read_b128 v[168:171], v129
	ds_read_b128 v[172:175], v129 offset:1024
	ds_read_b128 v[176:179], v132
	ds_read_b128 v[180:183], v132 offset:1024
	ds_read_b128 v[184:187], v131
	ds_read_b128 v[188:191], v131 offset:1024
	ds_read_b128 v[192:195], v130
	ds_read_b128 v[196:199], v130 offset:1024
	buffer_load_dwordx4 v141, s[8:11], s6 offen lds
	s_mov_b32 m0, s58
	s_nop 0
	buffer_load_dwordx4 v142, s[8:11], s6 offen lds
	s_waitcnt lgkmcnt(8)
	s_barrier
	s_waitcnt lgkmcnt(0)
	v_mfma_f32_16x16x32_bf16 v[124:127], v[152:155], v[168:171], v[124:127]
	v_mfma_f32_16x16x32_bf16 v[124:127], v[156:159], v[172:175], v[124:127]
	v_mfma_f32_16x16x32_bf16 v[120:123], v[164:167], v[172:175], v[120:123]
	v_mfma_f32_16x16x32_bf16 v[120:123], v[160:163], v[168:171], v[120:123]
	v_mfma_f32_16x16x32_bf16 v[112:115], v[160:163], v[176:179], v[112:115]
	v_mfma_f32_16x16x32_bf16 v[112:115], v[164:167], v[180:183], v[112:115]
	v_mfma_f32_16x16x32_bf16 v[116:119], v[156:159], v[180:183], v[116:119]
	v_mfma_f32_16x16x32_bf16 v[116:119], v[152:155], v[176:179], v[116:119]
	v_mfma_f32_16x16x32_bf16 v[108:111], v[152:155], v[184:187], v[108:111]
	v_mfma_f32_16x16x32_bf16 v[108:111], v[156:159], v[188:191], v[108:111]
	v_mfma_f32_16x16x32_bf16 v[104:107], v[164:167], v[188:191], v[104:107]
	v_mfma_f32_16x16x32_bf16 v[104:107], v[160:163], v[184:187], v[104:107]
	v_mfma_f32_16x16x32_bf16 v[96:99], v[160:163], v[192:195], v[96:99]
	v_mfma_f32_16x16x32_bf16 v[96:99], v[164:167], v[196:199], v[96:99]
	v_mfma_f32_16x16x32_bf16 v[100:103], v[156:159], v[196:199], v[100:103]
	v_mfma_f32_16x16x32_bf16 v[100:103], v[152:155], v[192:195], v[100:103]
	s_barrier
	s_add_i32 s6, s83, s3
	s_add_i32 s7, s6, 0x100
	s_mov_b32 s14, s10
	s_mov_b32 s15, s11
	s_mov_b32 m0, s85
	ds_read_b128 v[200:203], v143
	ds_read_b128 v[204:207], v144
	ds_read_b128 v[208:211], v145
	ds_read_b128 v[212:215], v146
	buffer_load_dwordx4 v141, s[12:15], s7 offen lds
	s_mov_b32 m0, s75
	s_nop 0
	buffer_load_dwordx4 v142, s[12:15], s7 offen lds
	s_barrier
	s_waitcnt lgkmcnt(2)
	v_mfma_f32_16x16x32_bf16 v[92:95], v[200:203], v[168:171], v[92:95]
	v_mfma_f32_16x16x32_bf16 v[92:95], v[204:207], v[172:175], v[92:95]
	s_waitcnt lgkmcnt(0)
	v_mfma_f32_16x16x32_bf16 v[88:91], v[212:215], v[172:175], v[88:91]
	v_mfma_f32_16x16x32_bf16 v[88:91], v[208:211], v[168:171], v[88:91]
	v_mfma_f32_16x16x32_bf16 v[68:71], v[208:211], v[176:179], v[68:71]
	v_mfma_f32_16x16x32_bf16 v[68:71], v[212:215], v[180:183], v[68:71]
	v_mfma_f32_16x16x32_bf16 v[80:83], v[204:207], v[180:183], v[80:83]
	v_mfma_f32_16x16x32_bf16 v[80:83], v[200:203], v[176:179], v[80:83]
	v_mfma_f32_16x16x32_bf16 v[60:63], v[200:203], v[184:187], v[60:63]
	v_mfma_f32_16x16x32_bf16 v[60:63], v[204:207], v[188:191], v[60:63]
	v_mfma_f32_16x16x32_bf16 v[56:59], v[212:215], v[188:191], v[56:59]
	v_mfma_f32_16x16x32_bf16 v[56:59], v[208:211], v[184:187], v[56:59]
	v_mfma_f32_16x16x32_bf16 v[48:51], v[208:211], v[192:195], v[48:51]
	v_mfma_f32_16x16x32_bf16 v[48:51], v[212:215], v[196:199], v[48:51]
	v_mfma_f32_16x16x32_bf16 v[52:55], v[204:207], v[196:199], v[52:55]
	v_mfma_f32_16x16x32_bf16 v[52:55], v[200:203], v[192:195], v[52:55]
	s_barrier
	s_add_i32 s7, s82, s3
	s_add_i32 s22, s7, 0x100
	s_mov_b32 m0, s38
	ds_read_b128 v[168:171], v129 offset:16384
	ds_read_b128 v[172:175], v129 offset:17408
	ds_read_b128 v[176:179], v132 offset:16384
	ds_read_b128 v[180:183], v132 offset:17408
	ds_read_b128 v[184:187], v131 offset:16384
	ds_read_b128 v[188:191], v131 offset:17408
	ds_read_b128 v[192:195], v130 offset:16384
	ds_read_b128 v[196:199], v130 offset:17408
	buffer_load_dwordx4 v141, s[8:11], s22 offen lds
	s_mov_b32 m0, s95
	s_nop 0
	buffer_load_dwordx4 v142, s[8:11], s22 offen lds
	s_barrier
	s_waitcnt lgkmcnt(6)
	v_mfma_f32_16x16x32_bf16 v[44:47], v[152:155], v[168:171], v[44:47]
	v_mfma_f32_16x16x32_bf16 v[44:47], v[156:159], v[172:175], v[44:47]
	v_mfma_f32_16x16x32_bf16 v[40:43], v[164:167], v[172:175], v[40:43]
	v_mfma_f32_16x16x32_bf16 v[40:43], v[160:163], v[168:171], v[40:43]
	s_waitcnt lgkmcnt(4)
	v_mfma_f32_16x16x32_bf16 v[32:35], v[160:163], v[176:179], v[32:35]
	v_mfma_f32_16x16x32_bf16 v[32:35], v[164:167], v[180:183], v[32:35]
	v_mfma_f32_16x16x32_bf16 v[36:39], v[156:159], v[180:183], v[36:39]
	v_mfma_f32_16x16x32_bf16 v[36:39], v[152:155], v[176:179], v[36:39]
	s_waitcnt lgkmcnt(2)
	v_mfma_f32_16x16x32_bf16 v[28:31], v[152:155], v[184:187], v[28:31]
	v_mfma_f32_16x16x32_bf16 v[28:31], v[156:159], v[188:191], v[28:31]
	v_mfma_f32_16x16x32_bf16 v[24:27], v[164:167], v[188:191], v[24:27]
	v_mfma_f32_16x16x32_bf16 v[24:27], v[160:163], v[184:187], v[24:27]
	s_waitcnt lgkmcnt(0)
	v_mfma_f32_16x16x32_bf16 v[16:19], v[160:163], v[192:195], v[16:19]
	v_mfma_f32_16x16x32_bf16 v[16:19], v[164:167], v[196:199], v[16:19]
	v_mfma_f32_16x16x32_bf16 v[20:23], v[156:159], v[196:199], v[20:23]
	v_mfma_f32_16x16x32_bf16 v[20:23], v[152:155], v[192:195], v[20:23]
	s_barrier
	s_add_i32 s22, s84, s3
	s_add_i32 s23, s22, 0x100
	s_mov_b32 m0, s86
	s_nop 0
	buffer_load_dwordx4 v141, s[12:15], s23 offen lds
	s_mov_b32 m0, s28
	s_nop 0
	buffer_load_dwordx4 v142, s[12:15], s23 offen lds
	s_waitcnt vmcnt(6)
	s_barrier
; #define STAGE(P, RS, SOFF, OFF, kt) do { const int _so = (SOFF) + (kt) * (BK * 2); \
;     _Pragma("unroll") for (int _i = 0; _i < 2; ++_i) { \
;       __builtin_amdgcn_raw_ptr_buffer_load_lds(RS, (__attribute__((address_space(3))) void*)((P) + wave * 1024 + _i * 8192), 16, OFF[_i], _so, 0, 0); } } while (0)
; #define LDA(dst, b, h) _Pragma("unroll") for (int m = 0; m < 4; ++m) _Pragma("unroll") for (int k = 0; k < 2; ++k) \
;     dst[m][k] = *reinterpret_cast<const bf16x8*>(SA(b, h) + lds_byte(wr * 64 + m * 16 + fr, k * 32 + fq * 8))
; #define LDB(dst, b, h) _Pragma("unroll") for (int n = 0; n < 2; ++n) _Pragma("unroll") for (int k = 0; k < 2; ++k) \
;     dst[n][k] = *reinterpret_cast<const bf16x8*>(SB(b, h) + lds_byte(wc * 32 + n * 16 + fr, k * 32 + fq * 8))
; #define WAIT_V(n) asm volatile("s_waitcnt vmcnt(" #n ")" ::: "memory")
; #define WAIT_L(n) asm volatile("s_waitcnt lgkmcnt(" #n ")" ::: "memory")
; #define BAR __builtin_amdgcn_s_barrier()
; #define SCHED __builtin_amdgcn_sched_barrier(0)
;     ...
;       WAIT_V(6); BAR; MMA(1, 1, At, B1); BAR;
;       LDB(B0, 1, 0); SCHED; LDA(At, 1, 0); STAGE(SA(0, 1), rsA, sA1, offA, t + 2);
;       WAIT_L(8); BAR; WAIT_L(0); MMA(0, 0, At, B0); BAR; SCHED;
;       LDB(B1, 1, 1); STAGE(SB(1, 0), rsB, sB0, offB, t + 3);
;       BAR; WAIT_L(0); MMA(0, 1, At, B1); BAR;
;       LDA(At, 1, 1); STAGE(SA(1, 0), rsA, sA0, offA, t + 3);
;       BAR; WAIT_L(0); MMA(1, 0, At, B0); BAR; SCHED;
;       STAGE(SB(1, 1), rsB, sB1, offB, t + 3);
	v_mfma_f32_16x16x32_bf16 v[12:15], v[200:203], v[168:171], v[12:15]
	v_mfma_f32_16x16x32_bf16 v[12:15], v[204:207], v[172:175], v[12:15]
	v_mfma_f32_16x16x32_bf16 v[8:11], v[212:215], v[172:175], v[8:11]
	v_mfma_f32_16x16x32_bf16 v[8:11], v[208:211], v[168:171], v[8:11]
	v_mfma_f32_16x16x32_bf16 v[0:3], v[208:211], v[176:179], v[0:3]
	v_mfma_f32_16x16x32_bf16 v[0:3], v[212:215], v[180:183], v[0:3]
	v_mfma_f32_16x16x32_bf16 v[4:7], v[204:207], v[180:183], v[4:7]
	v_mfma_f32_16x16x32_bf16 v[4:7], v[200:203], v[176:179], v[4:7]
	v_mfma_f32_16x16x32_bf16 v[64:67], v[200:203], v[184:187], v[64:67]
	v_mfma_f32_16x16x32_bf16 v[64:67], v[204:207], v[188:191], v[64:67]
	v_mfma_f32_16x16x32_bf16 v[72:75], v[212:215], v[188:191], v[72:75]
	v_mfma_f32_16x16x32_bf16 v[72:75], v[208:211], v[184:187], v[72:75]
	v_mfma_f32_16x16x32_bf16 v[84:87], v[208:211], v[192:195], v[84:87]
	v_mfma_f32_16x16x32_bf16 v[84:87], v[212:215], v[196:199], v[84:87]
	v_mfma_f32_16x16x32_bf16 v[76:79], v[204:207], v[196:199], v[76:79]
	v_mfma_f32_16x16x32_bf16 v[76:79], v[200:203], v[192:195], v[76:79]
	s_barrier
	ds_read_b128 v[152:155], v137
	ds_read_b128 v[156:159], v138
	ds_read_b128 v[160:163], v139
	ds_read_b128 v[164:167], v140
	s_addk_i32 s5, 0x100
	s_mov_b32 m0, s87
	ds_read_b128 v[168:171], v129 offset:32768
	ds_read_b128 v[172:175], v129 offset:33792
	ds_read_b128 v[176:179], v132 offset:32768
	ds_read_b128 v[180:183], v132 offset:33792
	ds_read_b128 v[184:187], v131 offset:32768
	ds_read_b128 v[188:191], v131 offset:33792
	ds_read_b128 v[192:195], v130 offset:32768
	ds_read_b128 v[196:199], v130 offset:33792
	buffer_load_dwordx4 v141, s[8:11], s5 offen lds
	s_mov_b32 m0, s97
	s_nop 0
	buffer_load_dwordx4 v142, s[8:11], s5 offen lds
	s_waitcnt lgkmcnt(8)
	s_barrier
	s_waitcnt lgkmcnt(6)
	v_mfma_f32_16x16x32_bf16 v[124:127], v[152:155], v[168:171], v[124:127]
	v_mfma_f32_16x16x32_bf16 v[124:127], v[156:159], v[172:175], v[124:127]
	v_mfma_f32_16x16x32_bf16 v[120:123], v[164:167], v[172:175], v[120:123]
	v_mfma_f32_16x16x32_bf16 v[120:123], v[160:163], v[168:171], v[120:123]
	s_waitcnt lgkmcnt(4)
	v_mfma_f32_16x16x32_bf16 v[112:115], v[160:163], v[176:179], v[112:115]
	v_mfma_f32_16x16x32_bf16 v[112:115], v[164:167], v[180:183], v[112:115]
	v_mfma_f32_16x16x32_bf16 v[116:119], v[156:159], v[180:183], v[116:119]
	v_mfma_f32_16x16x32_bf16 v[116:119], v[152:155], v[176:179], v[116:119]
	s_waitcnt lgkmcnt(2)
	v_mfma_f32_16x16x32_bf16 v[108:111], v[152:155], v[184:187], v[108:111]
	v_mfma_f32_16x16x32_bf16 v[108:111], v[156:159], v[188:191], v[108:111]
	v_mfma_f32_16x16x32_bf16 v[104:107], v[164:167], v[188:191], v[104:107]
	v_mfma_f32_16x16x32_bf16 v[104:107], v[160:163], v[184:187], v[104:107]
	s_waitcnt lgkmcnt(0)
	v_mfma_f32_16x16x32_bf16 v[96:99], v[160:163], v[192:195], v[96:99]
	v_mfma_f32_16x16x32_bf16 v[96:99], v[164:167], v[196:199], v[96:99]
	v_mfma_f32_16x16x32_bf16 v[100:103], v[156:159], v[196:199], v[100:103]
	v_mfma_f32_16x16x32_bf16 v[100:103], v[152:155], v[192:195], v[100:103]
	s_barrier
	s_addk_i32 s6, 0x180
	s_mov_b32 m0, s92
	ds_read_b128 v[200:203], v133
	ds_read_b128 v[204:207], v134
	ds_read_b128 v[208:211], v135
	ds_read_b128 v[212:215], v136
	buffer_load_dwordx4 v141, s[12:15], s6 offen lds
	s_mov_b32 m0, s29
	s_nop 0
	buffer_load_dwordx4 v142, s[12:15], s6 offen lds
	s_barrier
	s_waitcnt lgkmcnt(2)
	v_mfma_f32_16x16x32_bf16 v[92:95], v[200:203], v[168:171], v[92:95]
	v_mfma_f32_16x16x32_bf16 v[92:95], v[204:207], v[172:175], v[92:95]
	s_waitcnt lgkmcnt(0)
	v_mfma_f32_16x16x32_bf16 v[88:91], v[212:215], v[172:175], v[88:91]
	v_mfma_f32_16x16x32_bf16 v[88:91], v[208:211], v[168:171], v[88:91]
	v_mfma_f32_16x16x32_bf16 v[68:71], v[208:211], v[176:179], v[68:71]
	v_mfma_f32_16x16x32_bf16 v[68:71], v[212:215], v[180:183], v[68:71]
	v_mfma_f32_16x16x32_bf16 v[80:83], v[204:207], v[180:183], v[80:83]
	v_mfma_f32_16x16x32_bf16 v[80:83], v[200:203], v[176:179], v[80:83]
	v_mfma_f32_16x16x32_bf16 v[60:63], v[200:203], v[184:187], v[60:63]
	v_mfma_f32_16x16x32_bf16 v[60:63], v[204:207], v[188:191], v[60:63]
	v_mfma_f32_16x16x32_bf16 v[56:59], v[212:215], v[188:191], v[56:59]
	v_mfma_f32_16x16x32_bf16 v[56:59], v[208:211], v[184:187], v[56:59]
	v_mfma_f32_16x16x32_bf16 v[48:51], v[208:211], v[192:195], v[48:51]
	v_mfma_f32_16x16x32_bf16 v[48:51], v[212:215], v[196:199], v[48:51]
	v_mfma_f32_16x16x32_bf16 v[52:55], v[204:207], v[196:199], v[52:55]
	v_mfma_f32_16x16x32_bf16 v[52:55], v[200:203], v[192:195], v[52:55]
	s_barrier
	s_addk_i32 s7, 0x180
	s_mov_b32 m0, s93
	ds_read_b128 v[168:171], v129 offset:49152
	ds_read_b128 v[172:175], v129 offset:50176
	ds_read_b128 v[176:179], v132 offset:49152
	ds_read_b128 v[180:183], v132 offset:50176
	ds_read_b128 v[184:187], v131 offset:49152
	ds_read_b128 v[188:191], v131 offset:50176
	ds_read_b128 v[192:195], v130 offset:49152
	ds_read_b128 v[196:199], v130 offset:50176
	buffer_load_dwordx4 v141, s[8:11], s7 offen lds
	s_mov_b32 m0, s56
	s_nop 0
	buffer_load_dwordx4 v142, s[8:11], s7 offen lds
	s_barrier
	s_waitcnt lgkmcnt(6)
	v_mfma_f32_16x16x32_bf16 v[44:47], v[152:155], v[168:171], v[44:47]
	v_mfma_f32_16x16x32_bf16 v[44:47], v[156:159], v[172:175], v[44:47]
	v_mfma_f32_16x16x32_bf16 v[40:43], v[164:167], v[172:175], v[40:43]
	v_mfma_f32_16x16x32_bf16 v[40:43], v[160:163], v[168:171], v[40:43]
	s_waitcnt lgkmcnt(4)
	v_mfma_f32_16x16x32_bf16 v[32:35], v[160:163], v[176:179], v[32:35]
	v_mfma_f32_16x16x32_bf16 v[32:35], v[164:167], v[180:183], v[32:35]
	v_mfma_f32_16x16x32_bf16 v[36:39], v[156:159], v[180:183], v[36:39]
	v_mfma_f32_16x16x32_bf16 v[36:39], v[152:155], v[176:179], v[36:39]
	s_waitcnt lgkmcnt(2)
	v_mfma_f32_16x16x32_bf16 v[28:31], v[152:155], v[184:187], v[28:31]
	v_mfma_f32_16x16x32_bf16 v[28:31], v[156:159], v[188:191], v[28:31]
	v_mfma_f32_16x16x32_bf16 v[24:27], v[164:167], v[188:191], v[24:27]
	v_mfma_f32_16x16x32_bf16 v[24:27], v[160:163], v[184:187], v[24:27]
	s_waitcnt lgkmcnt(0)
	v_mfma_f32_16x16x32_bf16 v[16:19], v[160:163], v[192:195], v[16:19]
	v_mfma_f32_16x16x32_bf16 v[16:19], v[164:167], v[196:199], v[16:19]
	v_mfma_f32_16x16x32_bf16 v[20:23], v[156:159], v[196:199], v[20:23]
	v_mfma_f32_16x16x32_bf16 v[20:23], v[152:155], v[192:195], v[20:23]
	s_barrier
	s_addk_i32 s22, 0x180
	s_mov_b32 m0, s94
	s_nop 0
	buffer_load_dwordx4 v141, s[12:15], s22 offen lds
	s_mov_b32 m0, s57
	s_nop 0
	buffer_load_dwordx4 v142, s[12:15], s22 offen lds
	s_add_i32 s1, s1, 2
	s_addk_i32 s3, 0x100
	s_cmp_gt_u32 s1, 27
	s_cbranch_scc0 .LBB0_657
; #define STAGE(P, RS, SOFF, OFF, kt) do { const int _so = (SOFF) + (kt) * (BK * 2); \
;     _Pragma("unroll") for (int _i = 0; _i < 2; ++_i) { \
;       __builtin_amdgcn_raw_ptr_buffer_load_lds(RS, (__attribute__((address_space(3))) void*)((P) + wave * 1024 + _i * 8192), 16, OFF[_i], _so, 0, 0); } } while (0)
; #define LDA(dst, b, h) _Pragma("unroll") for (int m = 0; m < 4; ++m) _Pragma("unroll") for (int k = 0; k < 2; ++k) \
;     dst[m][k] = *reinterpret_cast<const bf16x8*>(SA(b, h) + lds_byte(wr * 64 + m * 16 + fr, k * 32 + fq * 8))
; #define LDB(dst, b, h) _Pragma("unroll") for (int n = 0; n < 2; ++n) _Pragma("unroll") for (int k = 0; k < 2; ++k) \
;     dst[n][k] = *reinterpret_cast<const bf16x8*>(SB(b, h) + lds_byte(wc * 32 + n * 16 + fr, k * 32 + fq * 8))
; #define WAIT_V(n) asm volatile("s_waitcnt vmcnt(" #n ")" ::: "memory")
; #define WAIT_L(n) asm volatile("s_waitcnt lgkmcnt(" #n ")" ::: "memory")
; #define BAR __builtin_amdgcn_s_barrier()
;     ...
;       WAIT_V(6); BAR; MMA(1, 1, At, B1); BAR;
;     }
;     { LDB(B0, 0, 0); LDA(At, 0, 0); STAGE(SA(1, 1), rsA, sA1, offA, nt - 1);
;       BAR; WAIT_L(0); MMA(0, 0, At, B0); BAR;
;       LDB(B1, 0, 1); BAR; WAIT_L(0); MMA(0, 1, At, B1); BAR;
;       LDA(At, 0, 1); WAIT_V(4); BAR; WAIT_L(0); MMA(1, 0, At, B0); MMA(1, 1, At, B1); BAR; }
.Lmy_post_657:
	s_waitcnt vmcnt(6)
	s_barrier
	v_mfma_f32_16x16x32_bf16 v[12:15], v[200:203], v[168:171], v[12:15]
	v_mfma_f32_16x16x32_bf16 v[12:15], v[204:207], v[172:175], v[12:15]
	v_mfma_f32_16x16x32_bf16 v[8:11], v[212:215], v[172:175], v[8:11]
	v_mfma_f32_16x16x32_bf16 v[8:11], v[208:211], v[168:171], v[8:11]
	v_mfma_f32_16x16x32_bf16 v[0:3], v[208:211], v[176:179], v[0:3]
	v_mfma_f32_16x16x32_bf16 v[0:3], v[212:215], v[180:183], v[0:3]
	v_mfma_f32_16x16x32_bf16 v[4:7], v[204:207], v[180:183], v[4:7]
	v_mfma_f32_16x16x32_bf16 v[4:7], v[200:203], v[176:179], v[4:7]
	v_mfma_f32_16x16x32_bf16 v[64:67], v[200:203], v[184:187], v[64:67]
	v_mfma_f32_16x16x32_bf16 v[64:67], v[204:207], v[188:191], v[64:67]
	v_mfma_f32_16x16x32_bf16 v[72:75], v[212:215], v[188:191], v[72:75]
	v_mfma_f32_16x16x32_bf16 v[72:75], v[208:211], v[184:187], v[72:75]
	v_mfma_f32_16x16x32_bf16 v[84:87], v[208:211], v[192:195], v[84:87]
	v_mfma_f32_16x16x32_bf16 v[84:87], v[212:215], v[196:199], v[84:87]
	v_mfma_f32_16x16x32_bf16 v[76:79], v[204:207], v[196:199], v[76:79]
	v_mfma_f32_16x16x32_bf16 v[76:79], v[200:203], v[192:195], v[76:79]
	s_barrier
	s_add_i32 s1, s81, 0xf80
	s_mov_b32 m0, s39
	ds_read_b128 v[152:155], v147
	ds_read_b128 v[156:159], v148
	ds_read_b128 v[160:163], v149
	ds_read_b128 v[148:151], v150
	ds_read_b128 v[164:167], v129
	ds_read_b128 v[168:171], v129 offset:1024
	ds_read_b128 v[172:175], v132
	ds_read_b128 v[176:179], v132 offset:1024
	ds_read_b128 v[180:183], v131
	ds_read_b128 v[184:187], v131 offset:1024
	ds_read_b128 v[188:191], v130
	ds_read_b128 v[192:195], v130 offset:1024
	buffer_load_dwordx4 v141, s[8:11], s1 offen lds
	s_mov_b32 m0, s58
	s_nop 0
	buffer_load_dwordx4 v142, s[8:11], s1 offen lds
	s_barrier
	s_waitcnt lgkmcnt(6)
	v_mfma_f32_16x16x32_bf16 v[124:127], v[152:155], v[164:167], v[124:127]
	v_mfma_f32_16x16x32_bf16 v[124:127], v[156:159], v[168:171], v[124:127]
	v_mfma_f32_16x16x32_bf16 v[120:123], v[148:151], v[168:171], v[120:123]
	v_mfma_f32_16x16x32_bf16 v[120:123], v[160:163], v[164:167], v[120:123]
	s_waitcnt lgkmcnt(4)
	v_mfma_f32_16x16x32_bf16 v[112:115], v[160:163], v[172:175], v[112:115]
	v_mfma_f32_16x16x32_bf16 v[112:115], v[148:151], v[176:179], v[112:115]
	v_mfma_f32_16x16x32_bf16 v[116:119], v[156:159], v[176:179], v[116:119]
	v_mfma_f32_16x16x32_bf16 v[116:119], v[152:155], v[172:175], v[116:119]
	s_waitcnt lgkmcnt(2)
	v_mfma_f32_16x16x32_bf16 v[108:111], v[152:155], v[180:183], v[108:111]
	v_mfma_f32_16x16x32_bf16 v[108:111], v[156:159], v[184:187], v[108:111]
	v_mfma_f32_16x16x32_bf16 v[104:107], v[148:151], v[184:187], v[104:107]
	v_mfma_f32_16x16x32_bf16 v[104:107], v[160:163], v[180:183], v[104:107]
	s_waitcnt lgkmcnt(0)
	v_mfma_f32_16x16x32_bf16 v[96:99], v[160:163], v[188:191], v[96:99]
	v_mfma_f32_16x16x32_bf16 v[96:99], v[148:151], v[192:195], v[96:99]
	v_mfma_f32_16x16x32_bf16 v[100:103], v[156:159], v[192:195], v[100:103]
	v_mfma_f32_16x16x32_bf16 v[100:103], v[152:155], v[188:191], v[100:103]
	s_barrier
	ds_read_b128 v[196:199], v143
	ds_read_b128 v[200:203], v144
	ds_read_b128 v[142:145], v145
	ds_read_b128 v[204:207], v146
	s_barrier
	s_waitcnt lgkmcnt(1)
	v_mfma_f32_16x16x32_bf16 v[88:91], v[142:145], v[164:167], v[88:91]
	v_mfma_f32_16x16x32_bf16 v[80:83], v[196:199], v[172:175], v[80:83]
	v_mfma_f32_16x16x32_bf16 v[60:63], v[196:199], v[180:183], v[60:63]
	v_mfma_f32_16x16x32_bf16 v[56:59], v[142:145], v[180:183], v[56:59]
	v_mfma_f32_16x16x32_bf16 v[52:55], v[196:199], v[188:191], v[52:55]
	v_mfma_f32_16x16x32_bf16 v[48:51], v[142:145], v[188:191], v[48:51]
	v_mfma_f32_16x16x32_bf16 v[92:95], v[196:199], v[164:167], v[92:95]
	v_mfma_f32_16x16x32_bf16 v[68:71], v[142:145], v[172:175], v[68:71]
	s_waitcnt lgkmcnt(0)
	v_mfma_f32_16x16x32_bf16 v[88:91], v[204:207], v[168:171], v[88:91]
	v_mfma_f32_16x16x32_bf16 v[80:83], v[200:203], v[176:179], v[80:83]
	v_mfma_f32_16x16x32_bf16 v[60:63], v[200:203], v[184:187], v[60:63]
	v_mfma_f32_16x16x32_bf16 v[56:59], v[204:207], v[184:187], v[56:59]
	v_mfma_f32_16x16x32_bf16 v[52:55], v[200:203], v[192:195], v[52:55]
	v_mfma_f32_16x16x32_bf16 v[48:51], v[204:207], v[192:195], v[48:51]
	v_mfma_f32_16x16x32_bf16 v[164:167], v[200:203], v[168:171], v[92:95]
	v_mfma_f32_16x16x32_bf16 v[168:171], v[204:207], v[176:179], v[68:71]
	s_barrier
	s_nop 0
	ds_read_b128 v[68:71], v129 offset:16384
	ds_read_b128 v[92:95], v129 offset:17408
	ds_read_b128 v[172:175], v132 offset:16384
	ds_read_b128 v[176:179], v132 offset:17408
	ds_read_b128 v[180:183], v131 offset:16384
	ds_read_b128 v[184:187], v131 offset:17408
	ds_read_b128 v[188:191], v130 offset:16384
	ds_read_b128 v[192:195], v130 offset:17408
	s_waitcnt vmcnt(4)
	s_barrier
; #define LDA(dst, b, h) _Pragma("unroll") for (int m = 0; m < 4; ++m) _Pragma("unroll") for (int k = 0; k < 2; ++k) \
;     dst[m][k] = *reinterpret_cast<const bf16x8*>(SA(b, h) + lds_byte(wr * 64 + m * 16 + fr, k * 32 + fq * 8))
; #define LDB(dst, b, h) _Pragma("unroll") for (int n = 0; n < 2; ++n) _Pragma("unroll") for (int k = 0; k < 2; ++k) \
;     dst[n][k] = *reinterpret_cast<const bf16x8*>(SB(b, h) + lds_byte(wc * 32 + n * 16 + fr, k * 32 + fq * 8))
; #define WAIT_V(n) asm volatile("s_waitcnt vmcnt(" #n ")" ::: "memory")
; #define WAIT_L(n) asm volatile("s_waitcnt lgkmcnt(" #n ")" ::: "memory")
; #define BAR __builtin_amdgcn_s_barrier()
;     ...
;       LDA(At, 0, 1); WAIT_V(4); BAR; WAIT_L(0); MMA(1, 0, At, B0); MMA(1, 1, At, B1); BAR; }
;     { LDB(B0, 1, 0); LDA(At, 1, 0); WAIT_V(2); BAR; WAIT_L(0); MMA(0, 0, At, B0); BAR;
	s_waitcnt lgkmcnt(0)
	v_mfma_f32_16x16x32_bf16 v[44:47], v[152:155], v[68:71], v[44:47]
	v_mfma_f32_16x16x32_bf16 v[40:43], v[160:163], v[68:71], v[40:43]
	v_mfma_f32_16x16x32_bf16 v[36:39], v[152:155], v[172:175], v[36:39]
	v_mfma_f32_16x16x32_bf16 v[32:35], v[160:163], v[172:175], v[32:35]
	v_mfma_f32_16x16x32_bf16 v[28:31], v[152:155], v[180:183], v[28:31]
	v_mfma_f32_16x16x32_bf16 v[24:27], v[160:163], v[180:183], v[24:27]
	v_mfma_f32_16x16x32_bf16 v[20:23], v[152:155], v[188:191], v[20:23]
	v_mfma_f32_16x16x32_bf16 v[16:19], v[160:163], v[188:191], v[16:19]
	v_mfma_f32_16x16x32_bf16 v[44:47], v[156:159], v[92:95], v[44:47]
	v_mfma_f32_16x16x32_bf16 v[40:43], v[148:151], v[92:95], v[40:43]
	v_mfma_f32_16x16x32_bf16 v[36:39], v[156:159], v[176:179], v[36:39]
	v_mfma_f32_16x16x32_bf16 v[32:35], v[148:151], v[176:179], v[32:35]
	v_mfma_f32_16x16x32_bf16 v[28:31], v[156:159], v[184:187], v[28:31]
	v_mfma_f32_16x16x32_bf16 v[24:27], v[148:151], v[184:187], v[24:27]
	v_mfma_f32_16x16x32_bf16 v[20:23], v[156:159], v[192:195], v[20:23]
	v_mfma_f32_16x16x32_bf16 v[16:19], v[148:151], v[192:195], v[16:19]
	v_mfma_f32_16x16x32_bf16 v[4:7], v[196:199], v[172:175], v[4:7]
	v_mfma_f32_16x16x32_bf16 v[0:3], v[142:145], v[172:175], v[0:3]
	v_mfma_f32_16x16x32_bf16 v[12:15], v[196:199], v[68:71], v[12:15]
	v_mfma_f32_16x16x32_bf16 v[8:11], v[142:145], v[68:71], v[8:11]
	v_mfma_f32_16x16x32_bf16 v[64:67], v[196:199], v[180:183], v[64:67]
	v_mfma_f32_16x16x32_bf16 v[68:71], v[142:145], v[180:183], v[72:75]
	v_mfma_f32_16x16x32_bf16 v[72:75], v[196:199], v[188:191], v[76:79]
	v_mfma_f32_16x16x32_bf16 v[76:79], v[142:145], v[188:191], v[84:87]
	v_mfma_f32_16x16x32_bf16 v[4:7], v[200:203], v[176:179], v[4:7]
	v_mfma_f32_16x16x32_bf16 v[0:3], v[204:207], v[176:179], v[0:3]
	v_mfma_f32_16x16x32_bf16 v[142:145], v[200:203], v[92:95], v[12:15]
	v_mfma_f32_16x16x32_bf16 v[146:149], v[204:207], v[92:95], v[8:11]
	v_mfma_f32_16x16x32_bf16 v[150:153], v[200:203], v[184:187], v[64:67]
	v_mfma_f32_16x16x32_bf16 v[154:157], v[204:207], v[184:187], v[68:71]
	v_mfma_f32_16x16x32_bf16 v[158:161], v[200:203], v[192:195], v[72:75]
	v_mfma_f32_16x16x32_bf16 v[172:175], v[204:207], v[192:195], v[76:79]
	s_barrier
	ds_read_b128 v[8:11], v137
	ds_read_b128 v[12:15], v138
	ds_read_b128 v[176:179], v139
	ds_read_b128 v[138:141], v140
	ds_read_b128 v[64:67], v129 offset:32768
	ds_read_b128 v[72:75], v129 offset:33792
	ds_read_b128 v[180:183], v132 offset:32768
	ds_read_b128 v[184:187], v132 offset:33792
	ds_read_b128 v[188:191], v131 offset:32768
	ds_read_b128 v[192:195], v131 offset:33792
	ds_read_b128 v[196:199], v130 offset:32768
	ds_read_b128 v[200:203], v130 offset:33792
	s_waitcnt vmcnt(2)
	s_barrier
	s_waitcnt lgkmcnt(7)
	v_mfma_f32_16x16x32_bf16 v[68:71], v[8:11], v[64:67], v[124:127]
	v_mfma_f32_16x16x32_bf16 v[76:79], v[176:179], v[64:67], v[120:123]
	s_waitcnt lgkmcnt(5)
	v_mfma_f32_16x16x32_bf16 v[84:87], v[8:11], v[180:183], v[116:119]
	v_mfma_f32_16x16x32_bf16 v[92:95], v[176:179], v[180:183], v[112:115]
	s_waitcnt lgkmcnt(3)
	v_mfma_f32_16x16x32_bf16 v[112:115], v[8:11], v[188:191], v[108:111]
	v_mfma_f32_16x16x32_bf16 v[104:107], v[176:179], v[188:191], v[104:107]
	s_waitcnt lgkmcnt(1)
	v_mfma_f32_16x16x32_bf16 v[120:123], v[8:11], v[196:199], v[100:103]
	v_mfma_f32_16x16x32_bf16 v[96:99], v[176:179], v[196:199], v[96:99]
	v_mfma_f32_16x16x32_bf16 v[124:127], v[12:15], v[72:75], v[68:71]
	v_mfma_f32_16x16x32_bf16 v[116:119], v[138:141], v[72:75], v[76:79]
	v_mfma_f32_16x16x32_bf16 v[108:111], v[12:15], v[184:187], v[84:87]
	v_mfma_f32_16x16x32_bf16 v[100:103], v[138:141], v[184:187], v[92:95]
	v_mfma_f32_16x16x32_bf16 v[92:95], v[12:15], v[192:195], v[112:115]
	v_mfma_f32_16x16x32_bf16 v[84:87], v[138:141], v[192:195], v[104:107]
	s_waitcnt lgkmcnt(0)
	v_mfma_f32_16x16x32_bf16 v[76:79], v[12:15], v[200:203], v[120:123]
	v_mfma_f32_16x16x32_bf16 v[68:71], v[138:141], v[200:203], v[96:99]
	s_barrier
; #define LDA(dst, b, h) _Pragma("unroll") for (int m = 0; m < 4; ++m) _Pragma("unroll") for (int k = 0; k < 2; ++k) \
;     dst[m][k] = *reinterpret_cast<const bf16x8*>(SA(b, h) + lds_byte(wr * 64 + m * 16 + fr, k * 32 + fq * 8))
; #define LDB(dst, b, h) _Pragma("unroll") for (int n = 0; n < 2; ++n) _Pragma("unroll") for (int k = 0; k < 2; ++k) \
;     dst[n][k] = *reinterpret_cast<const bf16x8*>(SB(b, h) + lds_byte(wc * 32 + n * 16 + fr, k * 32 + fq * 8))
; #define WAIT_V(n) asm volatile("s_waitcnt vmcnt(" #n ")" ::: "memory")
; #define WAIT_L(n) asm volatile("s_waitcnt lgkmcnt(" #n ")" ::: "memory")
; #define BAR __builtin_amdgcn_s_barrier()
;     ...
;       LDB(B1, 1, 1); WAIT_V(0); BAR; WAIT_L(0); MMA(0, 1, At, B1); BAR;
;       LDA(At, 1, 1); BAR; WAIT_L(0); MMA(1, 0, At, B0); MMA(1, 1, At, B1); BAR; }
;     if (wr == 0) BAR;
	ds_read_b128 v[204:207], v133
	ds_read_b128 v[208:211], v134
	ds_read_b128 v[212:215], v135
	ds_read_b128 v[134:137], v136
	s_waitcnt vmcnt(0)
	s_barrier
	s_waitcnt lgkmcnt(1)
	v_mfma_f32_16x16x32_bf16 v[96:99], v[204:207], v[64:67], v[164:167]
	v_mfma_f32_16x16x32_bf16 v[64:67], v[212:215], v[64:67], v[88:91]
	v_mfma_f32_16x16x32_bf16 v[80:83], v[204:207], v[180:183], v[80:83]
	v_mfma_f32_16x16x32_bf16 v[88:91], v[212:215], v[180:183], v[168:171]
	v_mfma_f32_16x16x32_bf16 v[60:63], v[204:207], v[188:191], v[60:63]
	v_mfma_f32_16x16x32_bf16 v[56:59], v[212:215], v[188:191], v[56:59]
	v_mfma_f32_16x16x32_bf16 v[52:55], v[204:207], v[196:199], v[52:55]
	v_mfma_f32_16x16x32_bf16 v[48:51], v[212:215], v[196:199], v[48:51]
	s_waitcnt lgkmcnt(0)
	v_mfma_f32_16x16x32_bf16 v[120:123], v[208:211], v[72:75], v[96:99]
	v_mfma_f32_16x16x32_bf16 v[112:115], v[134:137], v[72:75], v[64:67]
	v_mfma_f32_16x16x32_bf16 v[104:107], v[208:211], v[184:187], v[80:83]
	v_mfma_f32_16x16x32_bf16 v[96:99], v[134:137], v[184:187], v[88:91]
	v_mfma_f32_16x16x32_bf16 v[88:91], v[208:211], v[192:195], v[60:63]
	v_mfma_f32_16x16x32_bf16 v[80:83], v[134:137], v[192:195], v[56:59]
	v_mfma_f32_16x16x32_bf16 v[72:75], v[208:211], v[200:203], v[52:55]
	v_mfma_f32_16x16x32_bf16 v[64:67], v[134:137], v[200:203], v[48:51]
	s_barrier
	s_nop 0
	ds_read_b128 v[48:51], v129 offset:49152
	ds_read_b128 v[162:165], v129 offset:50176
	ds_read_b128 v[52:55], v132 offset:49152
	ds_read_b128 v[166:169], v132 offset:50176
	ds_read_b128 v[180:183], v131 offset:49152
	ds_read_b128 v[184:187], v131 offset:50176
	ds_read_b128 v[188:191], v130 offset:49152
	ds_read_b128 v[130:133], v130 offset:50176
	s_barrier
	s_waitcnt lgkmcnt(0)
	v_mfma_f32_16x16x32_bf16 v[44:47], v[8:11], v[48:51], v[44:47]
	v_mfma_f32_16x16x32_bf16 v[40:43], v[176:179], v[48:51], v[40:43]
	v_mfma_f32_16x16x32_bf16 v[36:39], v[8:11], v[52:55], v[36:39]
	v_mfma_f32_16x16x32_bf16 v[32:35], v[176:179], v[52:55], v[32:35]
	v_mfma_f32_16x16x32_bf16 v[28:31], v[8:11], v[180:183], v[28:31]
	v_mfma_f32_16x16x32_bf16 v[24:27], v[176:179], v[180:183], v[24:27]
	v_mfma_f32_16x16x32_bf16 v[8:11], v[8:11], v[188:191], v[20:23]
	v_mfma_f32_16x16x32_bf16 v[16:19], v[176:179], v[188:191], v[16:19]
	v_mfma_f32_16x16x32_bf16 v[60:63], v[12:15], v[162:165], v[44:47]
	v_mfma_f32_16x16x32_bf16 v[56:59], v[138:141], v[162:165], v[40:43]
	v_mfma_f32_16x16x32_bf16 v[44:47], v[12:15], v[166:169], v[36:39]
	v_mfma_f32_16x16x32_bf16 v[40:43], v[138:141], v[166:169], v[32:35]
	v_mfma_f32_16x16x32_bf16 v[28:31], v[12:15], v[184:187], v[28:31]
	v_mfma_f32_16x16x32_bf16 v[24:27], v[138:141], v[184:187], v[24:27]
	v_mfma_f32_16x16x32_bf16 v[12:15], v[12:15], v[130:133], v[8:11]
	v_mfma_f32_16x16x32_bf16 v[8:11], v[138:141], v[130:133], v[16:19]
	v_mfma_f32_16x16x32_bf16 v[16:19], v[204:207], v[48:51], v[142:145]
	v_mfma_f32_16x16x32_bf16 v[20:23], v[212:215], v[48:51], v[146:149]
	v_mfma_f32_16x16x32_bf16 v[4:7], v[204:207], v[52:55], v[4:7]
	v_mfma_f32_16x16x32_bf16 v[0:3], v[212:215], v[52:55], v[0:3]
	v_mfma_f32_16x16x32_bf16 v[138:141], v[204:207], v[180:183], v[150:153]
	v_mfma_f32_16x16x32_bf16 v[142:145], v[212:215], v[180:183], v[154:157]
	v_mfma_f32_16x16x32_bf16 v[146:149], v[204:207], v[188:191], v[158:161]
	v_mfma_f32_16x16x32_bf16 v[150:153], v[212:215], v[188:191], v[172:175]
	v_mfma_f32_16x16x32_bf16 v[52:55], v[208:211], v[162:165], v[16:19]
	v_mfma_f32_16x16x32_bf16 v[48:51], v[134:137], v[162:165], v[20:23]
	v_mfma_f32_16x16x32_bf16 v[36:39], v[208:211], v[166:169], v[4:7]
	v_mfma_f32_16x16x32_bf16 v[32:35], v[134:137], v[166:169], v[0:3]
	v_mfma_f32_16x16x32_bf16 v[20:23], v[208:211], v[184:187], v[138:141]
	v_mfma_f32_16x16x32_bf16 v[16:19], v[134:137], v[184:187], v[142:145]
	v_mfma_f32_16x16x32_bf16 v[4:7], v[208:211], v[130:133], v[146:149]
	v_mfma_f32_16x16x32_bf16 v[0:3], v[134:137], v[130:133], v[150:153]
	v_cmp_gt_u32_e32 vcc, s73, v128
	s_barrier
	s_and_saveexec_b64 s[6:7], vcc
	s_cbranch_execz .LBB0_660
	s_barrier

; #define STAGE(P, RS, SOFF, OFF, kt) do { const int _so = (SOFF) + (kt) * (BK * 2); \
;     _Pragma("unroll") for (int _i = 0; _i < 2; ++_i) { \
;       __builtin_amdgcn_raw_ptr_buffer_load_lds(RS, (__attribute__((address_space(3))) void*)((P) + wave * 1024 + _i * 8192), 16, OFF[_i], _so, 0, 0); } } while (0)
; #define LDA(dst, b, h) _Pragma("unroll") for (int m = 0; m < 4; ++m) _Pragma("unroll") for (int k = 0; k < 2; ++k) \
;     dst[m][k] = *reinterpret_cast<const bf16x8*>(SA(b, h) + lds_byte(wr * 64 + m * 16 + fr, k * 32 + fq * 8))
; #define LDB(dst, b, h) _Pragma("unroll") for (int n = 0; n < 2; ++n) _Pragma("unroll") for (int k = 0; k < 2; ++k) \
;     dst[n][k] = *reinterpret_cast<const bf16x8*>(SB(b, h) + lds_byte(wc * 32 + n * 16 + fr, k * 32 + fq * 8))
; #define WAIT_V(n) asm volatile("s_waitcnt vmcnt(" #n ")" ::: "memory")
; #define WAIT_L(n) asm volatile("s_waitcnt lgkmcnt(" #n ")" ::: "memory")
; #define BAR __builtin_amdgcn_s_barrier()
; #define SCHED __builtin_amdgcn_sched_barrier(0)
;     ...
;     const int tid = opaque_tid(wave);
;     const int wid = tid >> 6, lane = tid & 63, wr = wid >> 2, wc = wid & 3, fr = lane & 15, fq = lane >> 4;
;     int offA[2], offB[2];
;     _Pragma("unroll") for (int i = 0; i < 2; ++i) {
;       int r, c; stage_rc(tid * 16 + i * 8192, r, c);
;       offA[i] = (r * lda + c) * 2; offB[i] = (r * ldb + c) * 2;
;     }
;     const int brow = pm * BM;
;     f32x4 acc[2][2][4][2];
;     _Pragma("unroll") for (int a = 0; a < 2; ++a) _Pragma("unroll") for (int b = 0; b < 2; ++b) _Pragma("unroll") for (int m = 0; m < 4; ++m) _Pragma("unroll") for (int n = 0; n < 2; ++n)
;       acc[a][b][m][n] = f32x4{0.f, 0.f, 0.f, 0.f};
;     bf16x8 At[4][2], B0[2][2], B1[2][2];
;     if (wr == 1) BAR;
;     if (first_tile) { WAIT_V(0); }
;     else if constexpr (mode == MODE_RESID_LN) { WAIT_V(0); }
;     else if constexpr (mode == MODE_SWIGLU) { WAIT_V(6); }
;     else if constexpr (mode == MODE_V) { WAIT_V(24); }
;     else { WAIT_V(12); }
;     first_tile = false;
;     BAR;
;     BAR;
;     for (int t = 0; t < nt - 2; t += 2) {
;       LDB(B0, 0, 0); SCHED; LDA(At, 0, 0); STAGE(SA(1, 1), rsA, sA1, offA, t + 1);
;       WAIT_L(8); BAR; WAIT_L(0); MMA(0, 0, At, B0); BAR; SCHED;
.LBB0_756:
	v_bfe_i32 v4, v128, 27, 1
	v_lshlrev_b32_e32 v2, 4, v128
	v_lshrrev_b32_e32 v4, 22, v4
	v_add_u32_e32 v4, v2, v4
	v_and_b32_e32 v4, 0xfffffc00, v4
	v_sub_u32_e32 v4, v2, v4
	v_lshrrev_b32_e32 v5, 4, v4
	v_bitop3_b32 v4, v5, v4, 32 bitop3:0x6c
	v_ashrrev_i32_e32 v3, 31, v128
	v_ashrrev_i32_e32 v6, 31, v4
	v_lshrrev_b32_e32 v3, 26, v3
	v_lshrrev_b32_e32 v6, 26, v6
	v_add_u32_e32 v3, v128, v3
	v_add_u32_e32 v6, v4, v6
	v_ashrrev_i32_e32 v3, 6, v3
	v_lshrrev_b32_e32 v7, 6, v6
	v_and_b32_e32 v6, 0xc0, v6
	v_lshlrev_b32_e32 v5, 3, v3
	v_lshlrev_b32_e32 v3, 5, v3
	v_sub_u32_e32 v4, v4, v6
	v_and_b32_e32 v5, 0x7fff0, v5
	v_and_b32_e32 v3, 32, v3
	v_ashrrev_i16_sdwa v4, v216, sext(v4) dst_sel:DWORD dst_unused:UNUSED_PAD src0_sel:DWORD src1_sel:BYTE_0
	v_add_u32_sdwa v3, v3, sext(v4) dst_sel:DWORD dst_unused:UNUSED_PAD src0_sel:DWORD src1_sel:WORD_0
	v_add_lshl_u32 v4, v7, v5, 13
	v_add_u32_e32 v2, 0x2000, v2
	v_lshl_add_u32 v141, v3, 1, v4
	v_ashrrev_i32_e32 v3, 31, v2
	v_lshrrev_b32_e32 v3, 22, v3
	v_add_u32_e32 v3, v2, v3
	v_ashrrev_i32_e32 v3, 10, v3
	v_mul_i32_i24_e32 v4, 0x400, v3
	v_sub_u32_e32 v2, v2, v4
	v_lshrrev_b32_e32 v4, 4, v2
	v_bitop3_b32 v2, v4, v2, 32 bitop3:0x6c
	v_ashrrev_i32_e32 v5, 31, v2
	v_lshrrev_b32_e32 v5, 26, v5
	v_add_u32_e32 v5, v2, v5
	v_lshrrev_b32_e32 v6, 6, v5
	v_and_b32_e32 v5, 0xc0, v5
	v_lshlrev_b32_e32 v4, 3, v3
	v_lshlrev_b32_e32 v3, 5, v3
	v_sub_u32_e32 v2, v2, v5
	v_and_b32_e32 v4, 0x7fff0, v4
	v_and_b32_e32 v3, 32, v3
	v_ashrrev_i16_sdwa v2, v216, sext(v2) dst_sel:DWORD dst_unused:UNUSED_PAD src0_sel:DWORD src1_sel:BYTE_0
	v_add_u32_sdwa v2, v3, sext(v2) dst_sel:DWORD dst_unused:UNUSED_PAD src0_sel:DWORD src1_sel:WORD_0
	v_add_lshl_u32 v3, v6, v4, 13
	v_lshl_add_u32 v142, v2, 1, v3
	v_and_b32_e32 v3, 15, v0
	v_lshlrev_b32_e32 v5, 2, v0
	v_and_b32_e32 v2, 48, v0
	v_lshlrev_b32_e32 v3, 6, v3
	v_and_b32_e32 v5, 32, v5
	v_lshlrev_b32_e32 v0, 6, v0
	v_or_b32_e32 v4, v3, v2
	v_bitop3_b32 v3, v3, v5, v2 bitop3:0x36
	v_lshlrev_b32_e32 v6, 6, v128
	v_lshlrev_b32_e32 v1, 13, v1
	v_and_or_b32 v0, v0, s72, v2
	v_and_or_b32 v3, v6, s71, v3
	v_bitop3_b32 v0, v1, v0, v5 bitop3:0xf6
	v_or_b32_e32 v6, 0x400, v3
	v_or_b32_e32 v7, 0x800, v3
	v_or_b32_e32 v8, 0xc00, v3
	v_or_b32_e32 v132, 0x800, v0
	v_or_b32_e32 v131, 0x1000, v0
	v_or_b32_e32 v130, 0x1800, v0
	v_mov_b32_e32 v0, 0
	v_bitop3_b32 v129, v4, v1, v5 bitop3:0xde
	s_mov_b32 s4, -2
	s_mov_b32 s5, 0
	v_or_b32_e32 v147, 0x10000, v3
	v_or_b32_e32 v148, 0x10000, v6
	v_or_b32_e32 v149, 0x10000, v7
	v_or_b32_e32 v150, 0x10000, v8
	v_or_b32_e32 v143, 0x14000, v3
	v_or_b32_e32 v144, 0x14000, v6
	v_or_b32_e32 v145, 0x14000, v7
	v_or_b32_e32 v146, 0x14000, v8
	v_or_b32_e32 v137, 0x18000, v3
	v_or_b32_e32 v138, 0x18000, v6
	v_or_b32_e32 v139, 0x18000, v7
	v_or_b32_e32 v140, 0x18000, v8
	v_or_b32_e32 v133, 0x1c000, v3
	v_or_b32_e32 v134, 0x1c000, v6
	v_or_b32_e32 v135, 0x1c000, v7
	v_or_b32_e32 v136, 0x1c000, v8
	s_barrier
	s_barrier
	ds_read_b128 v[152:155], v147
	ds_read_b128 v[156:159], v148
	ds_read_b128 v[160:163], v149
	ds_read_b128 v[164:167], v150
	s_add_i32 s6, s85, s5
	s_add_i32 s7, s6, 0x80
	s_mov_b32 m0, s39
	ds_read_b128 v[168:171], v129
	ds_read_b128 v[172:175], v129 offset:1024
	ds_read_b128 v[176:179], v132
	ds_read_b128 v[180:183], v132 offset:1024
	ds_read_b128 v[184:187], v131
	ds_read_b128 v[188:191], v131 offset:1024
	ds_read_b128 v[192:195], v130
	ds_read_b128 v[196:199], v130 offset:1024
	buffer_load_dwordx4 v141, s[8:11], s7 offen lds
	s_mov_b32 m0, s56
	s_nop 0
	buffer_load_dwordx4 v142, s[8:11], s7 offen lds
	s_waitcnt lgkmcnt(8)
	s_barrier
	s_waitcnt lgkmcnt(0)
	v_mfma_f32_16x16x32_bf16 v[124:127], v[152:155], v[168:171], 0
	v_mfma_f32_16x16x32_bf16 v[124:127], v[156:159], v[172:175], v[124:127]
	v_mfma_f32_16x16x32_bf16 v[120:123], v[164:167], v[172:175], 0
	v_mfma_f32_16x16x32_bf16 v[120:123], v[160:163], v[168:171], v[120:123]
	v_mfma_f32_16x16x32_bf16 v[112:115], v[160:163], v[176:179], 0
	v_mfma_f32_16x16x32_bf16 v[112:115], v[164:167], v[180:183], v[112:115]
	v_mfma_f32_16x16x32_bf16 v[116:119], v[156:159], v[180:183], 0
	v_mfma_f32_16x16x32_bf16 v[116:119], v[152:155], v[176:179], v[116:119]
	v_mfma_f32_16x16x32_bf16 v[108:111], v[152:155], v[184:187], 0
	v_mfma_f32_16x16x32_bf16 v[108:111], v[156:159], v[188:191], v[108:111]
	v_mfma_f32_16x16x32_bf16 v[104:107], v[164:167], v[188:191], 0
	v_mfma_f32_16x16x32_bf16 v[104:107], v[160:163], v[184:187], v[104:107]
	v_mfma_f32_16x16x32_bf16 v[96:99], v[160:163], v[192:195], 0
	v_mfma_f32_16x16x32_bf16 v[96:99], v[164:167], v[196:199], v[96:99]
	v_mfma_f32_16x16x32_bf16 v[100:103], v[156:159], v[196:199], 0
	v_mfma_f32_16x16x32_bf16 v[100:103], v[152:155], v[192:195], v[100:103]
	s_barrier
	s_add_i32 s7, s87, s5
	s_add_i32 s23, s7, 0x100
	s_mov_b32 s14, s10
	s_mov_b32 s15, s11
	s_mov_b32 m0, s42
	ds_read_b128 v[200:203], v143
	ds_read_b128 v[204:207], v144
	ds_read_b128 v[208:211], v145
	ds_read_b128 v[212:215], v146
	buffer_load_dwordx4 v141, s[12:15], s23 offen lds
	s_mov_b32 m0, s49
	s_nop 0
	buffer_load_dwordx4 v142, s[12:15], s23 offen lds
	s_barrier
; #define STAGE(P, RS, SOFF, OFF, kt) do { const int _so = (SOFF) + (kt) * (BK * 2); \
;     _Pragma("unroll") for (int _i = 0; _i < 2; ++_i) { \
;       __builtin_amdgcn_raw_ptr_buffer_load_lds(RS, (__attribute__((address_space(3))) void*)((P) + wave * 1024 + _i * 8192), 16, OFF[_i], _so, 0, 0); } } while (0)
; #define LDA(dst, b, h) _Pragma("unroll") for (int m = 0; m < 4; ++m) _Pragma("unroll") for (int k = 0; k < 2; ++k) \
;     dst[m][k] = *reinterpret_cast<const bf16x8*>(SA(b, h) + lds_byte(wr * 64 + m * 16 + fr, k * 32 + fq * 8))
; #define LDB(dst, b, h) _Pragma("unroll") for (int n = 0; n < 2; ++n) _Pragma("unroll") for (int k = 0; k < 2; ++k) \
;     dst[n][k] = *reinterpret_cast<const bf16x8*>(SB(b, h) + lds_byte(wc * 32 + n * 16 + fr, k * 32 + fq * 8))
; #define WAIT_V(n) asm volatile("s_waitcnt vmcnt(" #n ")" ::: "memory")
; #define WAIT_L(n) asm volatile("s_waitcnt lgkmcnt(" #n ")" ::: "memory")
; #define BAR __builtin_amdgcn_s_barrier()
; #define SCHED __builtin_amdgcn_sched_barrier(0)
;     ...
;       WAIT_L(8); BAR; WAIT_L(0); MMA(0, 0, At, B0); BAR; SCHED;
;       LDB(B1, 0, 1); STAGE(SB(0, 0), rsB, sB0, offB, t + 2);
;       BAR; WAIT_L(0); MMA(0, 1, At, B1); BAR;
;       LDA(At, 0, 1); STAGE(SA(0, 0), rsA, sA0, offA, t + 2);
;       BAR; WAIT_L(0); MMA(1, 0, At, B0); BAR; SCHED;
;       STAGE(SB(0, 1), rsB, sB1, offB, t + 2);
;       WAIT_V(6); BAR; MMA(1, 1, At, B1); BAR;
;       LDB(B0, 1, 0); SCHED; LDA(At, 1, 0); STAGE(SA(0, 1), rsA, sA1, offA, t + 2);
	s_waitcnt lgkmcnt(2)
	v_mfma_f32_16x16x32_bf16 v[92:95], v[200:203], v[168:171], 0
	v_mfma_f32_16x16x32_bf16 v[92:95], v[204:207], v[172:175], v[92:95]
	s_waitcnt lgkmcnt(0)
	v_mfma_f32_16x16x32_bf16 v[88:91], v[212:215], v[172:175], 0
	v_mfma_f32_16x16x32_bf16 v[88:91], v[208:211], v[168:171], v[88:91]
	v_mfma_f32_16x16x32_bf16 v[68:71], v[208:211], v[176:179], 0
	v_mfma_f32_16x16x32_bf16 v[68:71], v[212:215], v[180:183], v[68:71]
	v_mfma_f32_16x16x32_bf16 v[80:83], v[204:207], v[180:183], 0
	v_mfma_f32_16x16x32_bf16 v[80:83], v[200:203], v[176:179], v[80:83]
	v_mfma_f32_16x16x32_bf16 v[60:63], v[200:203], v[184:187], 0
	v_mfma_f32_16x16x32_bf16 v[60:63], v[204:207], v[188:191], v[60:63]
	v_mfma_f32_16x16x32_bf16 v[56:59], v[212:215], v[188:191], 0
	v_mfma_f32_16x16x32_bf16 v[56:59], v[208:211], v[184:187], v[56:59]
	v_mfma_f32_16x16x32_bf16 v[48:51], v[208:211], v[192:195], 0
	v_mfma_f32_16x16x32_bf16 v[48:51], v[212:215], v[196:199], v[48:51]
	v_mfma_f32_16x16x32_bf16 v[52:55], v[204:207], v[196:199], 0
	v_mfma_f32_16x16x32_bf16 v[52:55], v[200:203], v[192:195], v[52:55]
	s_barrier
	s_add_i32 s23, s86, s5
	s_add_i32 s26, s23, 0x100
	s_mov_b32 m0, s33
	ds_read_b128 v[168:171], v129 offset:16384
	ds_read_b128 v[172:175], v129 offset:17408
	ds_read_b128 v[176:179], v132 offset:16384
	ds_read_b128 v[180:183], v132 offset:17408
	ds_read_b128 v[184:187], v131 offset:16384
	ds_read_b128 v[188:191], v131 offset:17408
	ds_read_b128 v[192:195], v130 offset:16384
	ds_read_b128 v[196:199], v130 offset:17408
	buffer_load_dwordx4 v141, s[8:11], s26 offen lds
	s_mov_b32 m0, s50
	s_nop 0
	buffer_load_dwordx4 v142, s[8:11], s26 offen lds
	s_barrier
	s_waitcnt lgkmcnt(6)
	v_mfma_f32_16x16x32_bf16 v[44:47], v[152:155], v[168:171], 0
	v_mfma_f32_16x16x32_bf16 v[44:47], v[156:159], v[172:175], v[44:47]
	v_mfma_f32_16x16x32_bf16 v[40:43], v[164:167], v[172:175], 0
	v_mfma_f32_16x16x32_bf16 v[40:43], v[160:163], v[168:171], v[40:43]
	s_waitcnt lgkmcnt(4)
	v_mfma_f32_16x16x32_bf16 v[32:35], v[160:163], v[176:179], 0
	v_mfma_f32_16x16x32_bf16 v[32:35], v[164:167], v[180:183], v[32:35]
	v_mfma_f32_16x16x32_bf16 v[36:39], v[156:159], v[180:183], 0
	v_mfma_f32_16x16x32_bf16 v[36:39], v[152:155], v[176:179], v[36:39]
	s_waitcnt lgkmcnt(2)
	v_mfma_f32_16x16x32_bf16 v[28:31], v[152:155], v[184:187], 0
	v_mfma_f32_16x16x32_bf16 v[28:31], v[156:159], v[188:191], v[28:31]
	v_mfma_f32_16x16x32_bf16 v[24:27], v[164:167], v[188:191], 0
	v_mfma_f32_16x16x32_bf16 v[24:27], v[160:163], v[184:187], v[24:27]
	s_waitcnt lgkmcnt(0)
	v_mfma_f32_16x16x32_bf16 v[16:19], v[160:163], v[192:195], 0
	v_mfma_f32_16x16x32_bf16 v[16:19], v[164:167], v[196:199], v[16:19]
	v_mfma_f32_16x16x32_bf16 v[20:23], v[156:159], v[196:199], 0
	v_mfma_f32_16x16x32_bf16 v[20:23], v[152:155], v[192:195], v[20:23]
	s_barrier
	s_add_i32 s26, s90, s5
	s_add_i32 s27, s26, 0x100
	s_mov_b32 m0, s43
	s_nop 0
	buffer_load_dwordx4 v141, s[12:15], s27 offen lds
	s_mov_b32 m0, s51
	s_nop 0
	buffer_load_dwordx4 v142, s[12:15], s27 offen lds
	s_waitcnt vmcnt(6)
	s_barrier
	v_mfma_f32_16x16x32_bf16 v[12:15], v[200:203], v[168:171], 0
	v_mfma_f32_16x16x32_bf16 v[12:15], v[204:207], v[172:175], v[12:15]
	v_mfma_f32_16x16x32_bf16 v[8:11], v[212:215], v[172:175], 0
	v_mfma_f32_16x16x32_bf16 v[8:11], v[208:211], v[168:171], v[8:11]
	v_mfma_f32_16x16x32_bf16 v[0:3], v[208:211], v[176:179], 0
	v_mfma_f32_16x16x32_bf16 v[0:3], v[212:215], v[180:183], v[0:3]
	v_mfma_f32_16x16x32_bf16 v[4:7], v[204:207], v[180:183], 0
	v_mfma_f32_16x16x32_bf16 v[4:7], v[200:203], v[176:179], v[4:7]
	v_mfma_f32_16x16x32_bf16 v[64:67], v[200:203], v[184:187], 0
	v_mfma_f32_16x16x32_bf16 v[64:67], v[204:207], v[188:191], v[64:67]
	v_mfma_f32_16x16x32_bf16 v[72:75], v[212:215], v[188:191], 0
	v_mfma_f32_16x16x32_bf16 v[72:75], v[208:211], v[184:187], v[72:75]
	v_mfma_f32_16x16x32_bf16 v[84:87], v[208:211], v[192:195], 0
	v_mfma_f32_16x16x32_bf16 v[84:87], v[212:215], v[196:199], v[84:87]
	v_mfma_f32_16x16x32_bf16 v[76:79], v[204:207], v[196:199], 0
	v_mfma_f32_16x16x32_bf16 v[76:79], v[200:203], v[192:195], v[76:79]
	s_barrier
	ds_read_b128 v[152:155], v137
	ds_read_b128 v[156:159], v138
	ds_read_b128 v[160:163], v139
	ds_read_b128 v[164:167], v140
	s_addk_i32 s6, 0x100
	s_mov_b32 m0, s44
	ds_read_b128 v[168:171], v129 offset:32768
	ds_read_b128 v[172:175], v129 offset:33792
	ds_read_b128 v[176:179], v132 offset:32768
	ds_read_b128 v[180:183], v132 offset:33792
	ds_read_b128 v[184:187], v131 offset:32768
	ds_read_b128 v[188:191], v131 offset:33792
	ds_read_b128 v[192:195], v130 offset:32768
	ds_read_b128 v[196:199], v130 offset:33792
	buffer_load_dwordx4 v141, s[8:11], s6 offen lds
	s_mov_b32 m0, s52
	s_nop 0
	buffer_load_dwordx4 v142, s[8:11], s6 offen lds
	s_waitcnt lgkmcnt(8)
	s_barrier
; #define STAGE(P, RS, SOFF, OFF, kt) do { const int _so = (SOFF) + (kt) * (BK * 2); \
;     _Pragma("unroll") for (int _i = 0; _i < 2; ++_i) { \
;       __builtin_amdgcn_raw_ptr_buffer_load_lds(RS, (__attribute__((address_space(3))) void*)((P) + wave * 1024 + _i * 8192), 16, OFF[_i], _so, 0, 0); } } while (0)
; #define LDA(dst, b, h) _Pragma("unroll") for (int m = 0; m < 4; ++m) _Pragma("unroll") for (int k = 0; k < 2; ++k) \
;     dst[m][k] = *reinterpret_cast<const bf16x8*>(SA(b, h) + lds_byte(wr * 64 + m * 16 + fr, k * 32 + fq * 8))
; #define LDB(dst, b, h) _Pragma("unroll") for (int n = 0; n < 2; ++n) _Pragma("unroll") for (int k = 0; k < 2; ++k) \
;     dst[n][k] = *reinterpret_cast<const bf16x8*>(SB(b, h) + lds_byte(wc * 32 + n * 16 + fr, k * 32 + fq * 8))
; #define WAIT_L(n) asm volatile("s_waitcnt lgkmcnt(" #n ")" ::: "memory")
; #define BAR __builtin_amdgcn_s_barrier()
; #define SCHED __builtin_amdgcn_sched_barrier(0)
;     ...
;       WAIT_L(8); BAR; WAIT_L(0); MMA(0, 0, At, B0); BAR; SCHED;
;       LDB(B1, 1, 1); STAGE(SB(1, 0), rsB, sB0, offB, t + 3);
;       BAR; WAIT_L(0); MMA(0, 1, At, B1); BAR;
;       LDA(At, 1, 1); STAGE(SA(1, 0), rsA, sA0, offA, t + 3);
;       BAR; WAIT_L(0); MMA(1, 0, At, B0); BAR; SCHED;
;       STAGE(SB(1, 1), rsB, sB1, offB, t + 3);
	s_waitcnt lgkmcnt(6)
	v_mfma_f32_16x16x32_bf16 v[124:127], v[152:155], v[168:171], v[124:127]
	v_mfma_f32_16x16x32_bf16 v[124:127], v[156:159], v[172:175], v[124:127]
	v_mfma_f32_16x16x32_bf16 v[120:123], v[164:167], v[172:175], v[120:123]
	v_mfma_f32_16x16x32_bf16 v[120:123], v[160:163], v[168:171], v[120:123]
	s_waitcnt lgkmcnt(4)
	v_mfma_f32_16x16x32_bf16 v[112:115], v[160:163], v[176:179], v[112:115]
	v_mfma_f32_16x16x32_bf16 v[112:115], v[164:167], v[180:183], v[112:115]
	v_mfma_f32_16x16x32_bf16 v[116:119], v[156:159], v[180:183], v[116:119]
	v_mfma_f32_16x16x32_bf16 v[116:119], v[152:155], v[176:179], v[116:119]
	s_waitcnt lgkmcnt(2)
	v_mfma_f32_16x16x32_bf16 v[108:111], v[152:155], v[184:187], v[108:111]
	v_mfma_f32_16x16x32_bf16 v[108:111], v[156:159], v[188:191], v[108:111]
	v_mfma_f32_16x16x32_bf16 v[104:107], v[164:167], v[188:191], v[104:107]
	v_mfma_f32_16x16x32_bf16 v[104:107], v[160:163], v[184:187], v[104:107]
	s_waitcnt lgkmcnt(0)
	v_mfma_f32_16x16x32_bf16 v[96:99], v[160:163], v[192:195], v[96:99]
	v_mfma_f32_16x16x32_bf16 v[96:99], v[164:167], v[196:199], v[96:99]
	v_mfma_f32_16x16x32_bf16 v[100:103], v[156:159], v[196:199], v[100:103]
	v_mfma_f32_16x16x32_bf16 v[100:103], v[152:155], v[192:195], v[100:103]
	s_barrier
	s_addk_i32 s7, 0x180
	s_mov_b32 m0, s45
	ds_read_b128 v[200:203], v133
	ds_read_b128 v[204:207], v134
	ds_read_b128 v[208:211], v135
	ds_read_b128 v[212:215], v136
	buffer_load_dwordx4 v141, s[12:15], s7 offen lds
	s_mov_b32 m0, s53
	s_nop 0
	buffer_load_dwordx4 v142, s[12:15], s7 offen lds
	s_barrier
	s_waitcnt lgkmcnt(2)
	v_mfma_f32_16x16x32_bf16 v[92:95], v[200:203], v[168:171], v[92:95]
	v_mfma_f32_16x16x32_bf16 v[92:95], v[204:207], v[172:175], v[92:95]
	s_waitcnt lgkmcnt(0)
	v_mfma_f32_16x16x32_bf16 v[88:91], v[212:215], v[172:175], v[88:91]
	v_mfma_f32_16x16x32_bf16 v[88:91], v[208:211], v[168:171], v[88:91]
	v_mfma_f32_16x16x32_bf16 v[68:71], v[208:211], v[176:179], v[68:71]
	v_mfma_f32_16x16x32_bf16 v[68:71], v[212:215], v[180:183], v[68:71]
	v_mfma_f32_16x16x32_bf16 v[80:83], v[204:207], v[180:183], v[80:83]
	v_mfma_f32_16x16x32_bf16 v[80:83], v[200:203], v[176:179], v[80:83]
	v_mfma_f32_16x16x32_bf16 v[60:63], v[200:203], v[184:187], v[60:63]
	v_mfma_f32_16x16x32_bf16 v[60:63], v[204:207], v[188:191], v[60:63]
	v_mfma_f32_16x16x32_bf16 v[56:59], v[212:215], v[188:191], v[56:59]
	v_mfma_f32_16x16x32_bf16 v[56:59], v[208:211], v[184:187], v[56:59]
	v_mfma_f32_16x16x32_bf16 v[48:51], v[208:211], v[192:195], v[48:51]
	v_mfma_f32_16x16x32_bf16 v[48:51], v[212:215], v[196:199], v[48:51]
	v_mfma_f32_16x16x32_bf16 v[52:55], v[204:207], v[196:199], v[52:55]
	v_mfma_f32_16x16x32_bf16 v[52:55], v[200:203], v[192:195], v[52:55]
	s_barrier
	s_addk_i32 s23, 0x180
	s_mov_b32 m0, s46
	ds_read_b128 v[168:171], v129 offset:49152
	ds_read_b128 v[172:175], v129 offset:50176
	ds_read_b128 v[176:179], v132 offset:49152
	ds_read_b128 v[180:183], v132 offset:50176
	ds_read_b128 v[184:187], v131 offset:49152
	ds_read_b128 v[188:191], v131 offset:50176
	ds_read_b128 v[192:195], v130 offset:49152
	ds_read_b128 v[196:199], v130 offset:50176
	buffer_load_dwordx4 v141, s[8:11], s23 offen lds
	s_mov_b32 m0, s54
	s_nop 0
	buffer_load_dwordx4 v142, s[8:11], s23 offen lds
	s_barrier
	s_waitcnt lgkmcnt(6)
	v_mfma_f32_16x16x32_bf16 v[44:47], v[152:155], v[168:171], v[44:47]
	v_mfma_f32_16x16x32_bf16 v[44:47], v[156:159], v[172:175], v[44:47]
	v_mfma_f32_16x16x32_bf16 v[40:43], v[164:167], v[172:175], v[40:43]
	v_mfma_f32_16x16x32_bf16 v[40:43], v[160:163], v[168:171], v[40:43]
	s_waitcnt lgkmcnt(4)
	v_mfma_f32_16x16x32_bf16 v[32:35], v[160:163], v[176:179], v[32:35]
	v_mfma_f32_16x16x32_bf16 v[32:35], v[164:167], v[180:183], v[32:35]
	v_mfma_f32_16x16x32_bf16 v[36:39], v[156:159], v[180:183], v[36:39]
	v_mfma_f32_16x16x32_bf16 v[36:39], v[152:155], v[176:179], v[36:39]
	s_waitcnt lgkmcnt(2)
	v_mfma_f32_16x16x32_bf16 v[28:31], v[152:155], v[184:187], v[28:31]
	v_mfma_f32_16x16x32_bf16 v[28:31], v[156:159], v[188:191], v[28:31]
	v_mfma_f32_16x16x32_bf16 v[24:27], v[164:167], v[188:191], v[24:27]
	v_mfma_f32_16x16x32_bf16 v[24:27], v[160:163], v[184:187], v[24:27]
	s_waitcnt lgkmcnt(0)
	v_mfma_f32_16x16x32_bf16 v[16:19], v[160:163], v[192:195], v[16:19]
	v_mfma_f32_16x16x32_bf16 v[16:19], v[164:167], v[196:199], v[16:19]
	v_mfma_f32_16x16x32_bf16 v[20:23], v[156:159], v[196:199], v[20:23]
	v_mfma_f32_16x16x32_bf16 v[20:23], v[152:155], v[192:195], v[20:23]
	s_barrier
	s_addk_i32 s26, 0x180
	s_mov_b32 m0, s47
	s_nop 0
	buffer_load_dwordx4 v141, s[12:15], s26 offen lds
	s_mov_b32 m0, s55
	s_nop 0
	buffer_load_dwordx4 v142, s[12:15], s26 offen lds
	s_add_i32 s4, s4, 2
	s_addk_i32 s5, 0x100
	s_cmp_gt_u32 s4, 59
	s_cbranch_scc0 .LBB0_757
	s_branch .Lmy_post_757

; #define STAGE(P, RS, SOFF, OFF, kt) do { const int _so = (SOFF) + (kt) * (BK * 2); \
;     _Pragma("unroll") for (int _i = 0; _i < 2; ++_i) { \
;       __builtin_amdgcn_raw_ptr_buffer_load_lds(RS, (__attribute__((address_space(3))) void*)((P) + wave * 1024 + _i * 8192), 16, OFF[_i], _so, 0, 0); } } while (0)
; #define LDA(dst, b, h) _Pragma("unroll") for (int m = 0; m < 4; ++m) _Pragma("unroll") for (int k = 0; k < 2; ++k) \
;     dst[m][k] = *reinterpret_cast<const bf16x8*>(SA(b, h) + lds_byte(wr * 64 + m * 16 + fr, k * 32 + fq * 8))
; #define LDB(dst, b, h) _Pragma("unroll") for (int n = 0; n < 2; ++n) _Pragma("unroll") for (int k = 0; k < 2; ++k) \
;     dst[n][k] = *reinterpret_cast<const bf16x8*>(SB(b, h) + lds_byte(wc * 32 + n * 16 + fr, k * 32 + fq * 8))
; #define WAIT_V(n) asm volatile("s_waitcnt vmcnt(" #n ")" ::: "memory")
; #define WAIT_L(n) asm volatile("s_waitcnt lgkmcnt(" #n ")" ::: "memory")
; #define BAR __builtin_amdgcn_s_barrier()
; #define SCHED __builtin_amdgcn_sched_barrier(0)
;     ...
;       LDB(B0, 0, 0); SCHED; LDA(At, 0, 0); STAGE(SA(1, 1), rsA, sA1, offA, t + 1);
;       WAIT_L(8); BAR; WAIT_L(0); MMA(0, 0, At, B0); BAR; SCHED;
;       LDB(B1, 0, 1); STAGE(SB(0, 0), rsB, sB0, offB, t + 2);
;       BAR; WAIT_L(0); MMA(0, 1, At, B1); BAR;
;       LDA(At, 0, 1); STAGE(SA(0, 0), rsA, sA0, offA, t + 2);
;       BAR; WAIT_L(0); MMA(1, 0, At, B0); BAR; SCHED;
;       STAGE(SB(0, 1), rsB, sB1, offB, t + 2);
;       WAIT_V(6); BAR; MMA(1, 1, At, B1); BAR;
.Lmy_rot_757:
	ds_read_b128 v[152:155], v147
	ds_read_b128 v[156:159], v148
	ds_read_b128 v[160:163], v149
	ds_read_b128 v[164:167], v150
	s_add_i32 s6, s85, s5
	s_add_i32 s7, s6, 0x80
	s_mov_b32 m0, s39
	ds_read_b128 v[168:171], v129
	ds_read_b128 v[172:175], v129 offset:1024
	ds_read_b128 v[176:179], v132
	ds_read_b128 v[180:183], v132 offset:1024
	ds_read_b128 v[184:187], v131
	ds_read_b128 v[188:191], v131 offset:1024
	ds_read_b128 v[192:195], v130
	ds_read_b128 v[196:199], v130 offset:1024
	buffer_load_dwordx4 v141, s[8:11], s7 offen lds
	s_mov_b32 m0, s56
	s_nop 0
	buffer_load_dwordx4 v142, s[8:11], s7 offen lds
	s_waitcnt lgkmcnt(8)
	s_barrier
	s_waitcnt lgkmcnt(0)
	v_mfma_f32_16x16x32_bf16 v[124:127], v[152:155], v[168:171], v[124:127]
	v_mfma_f32_16x16x32_bf16 v[124:127], v[156:159], v[172:175], v[124:127]
	v_mfma_f32_16x16x32_bf16 v[120:123], v[164:167], v[172:175], v[120:123]
	v_mfma_f32_16x16x32_bf16 v[120:123], v[160:163], v[168:171], v[120:123]
	v_mfma_f32_16x16x32_bf16 v[112:115], v[160:163], v[176:179], v[112:115]
	v_mfma_f32_16x16x32_bf16 v[112:115], v[164:167], v[180:183], v[112:115]
	v_mfma_f32_16x16x32_bf16 v[116:119], v[156:159], v[180:183], v[116:119]
	v_mfma_f32_16x16x32_bf16 v[116:119], v[152:155], v[176:179], v[116:119]
	v_mfma_f32_16x16x32_bf16 v[108:111], v[152:155], v[184:187], v[108:111]
	v_mfma_f32_16x16x32_bf16 v[108:111], v[156:159], v[188:191], v[108:111]
	v_mfma_f32_16x16x32_bf16 v[104:107], v[164:167], v[188:191], v[104:107]
	v_mfma_f32_16x16x32_bf16 v[104:107], v[160:163], v[184:187], v[104:107]
	v_mfma_f32_16x16x32_bf16 v[96:99], v[160:163], v[192:195], v[96:99]
	v_mfma_f32_16x16x32_bf16 v[96:99], v[164:167], v[196:199], v[96:99]
	v_mfma_f32_16x16x32_bf16 v[100:103], v[156:159], v[196:199], v[100:103]
	v_mfma_f32_16x16x32_bf16 v[100:103], v[152:155], v[192:195], v[100:103]
	s_barrier
	s_add_i32 s7, s87, s5
	s_add_i32 s23, s7, 0x100
	s_mov_b32 s14, s10
	s_mov_b32 s15, s11
	s_mov_b32 m0, s42
	ds_read_b128 v[200:203], v143
	ds_read_b128 v[204:207], v144
	ds_read_b128 v[208:211], v145
	ds_read_b128 v[212:215], v146
	buffer_load_dwordx4 v141, s[12:15], s23 offen lds
	s_mov_b32 m0, s49
	s_nop 0
	buffer_load_dwordx4 v142, s[12:15], s23 offen lds
	s_barrier
	s_waitcnt lgkmcnt(2)
	v_mfma_f32_16x16x32_bf16 v[92:95], v[200:203], v[168:171], v[92:95]
	v_mfma_f32_16x16x32_bf16 v[92:95], v[204:207], v[172:175], v[92:95]
	s_waitcnt lgkmcnt(0)
	v_mfma_f32_16x16x32_bf16 v[88:91], v[212:215], v[172:175], v[88:91]
	v_mfma_f32_16x16x32_bf16 v[88:91], v[208:211], v[168:171], v[88:91]
	v_mfma_f32_16x16x32_bf16 v[68:71], v[208:211], v[176:179], v[68:71]
	v_mfma_f32_16x16x32_bf16 v[68:71], v[212:215], v[180:183], v[68:71]
	v_mfma_f32_16x16x32_bf16 v[80:83], v[204:207], v[180:183], v[80:83]
	v_mfma_f32_16x16x32_bf16 v[80:83], v[200:203], v[176:179], v[80:83]
	v_mfma_f32_16x16x32_bf16 v[60:63], v[200:203], v[184:187], v[60:63]
	v_mfma_f32_16x16x32_bf16 v[60:63], v[204:207], v[188:191], v[60:63]
	v_mfma_f32_16x16x32_bf16 v[56:59], v[212:215], v[188:191], v[56:59]
	v_mfma_f32_16x16x32_bf16 v[56:59], v[208:211], v[184:187], v[56:59]
	v_mfma_f32_16x16x32_bf16 v[48:51], v[208:211], v[192:195], v[48:51]
	v_mfma_f32_16x16x32_bf16 v[48:51], v[212:215], v[196:199], v[48:51]
	v_mfma_f32_16x16x32_bf16 v[52:55], v[204:207], v[196:199], v[52:55]
	v_mfma_f32_16x16x32_bf16 v[52:55], v[200:203], v[192:195], v[52:55]
	s_barrier
	s_add_i32 s23, s86, s5
	s_add_i32 s26, s23, 0x100
	s_mov_b32 m0, s33
	ds_read_b128 v[168:171], v129 offset:16384
	ds_read_b128 v[172:175], v129 offset:17408
	ds_read_b128 v[176:179], v132 offset:16384
	ds_read_b128 v[180:183], v132 offset:17408
	ds_read_b128 v[184:187], v131 offset:16384
	ds_read_b128 v[188:191], v131 offset:17408
	ds_read_b128 v[192:195], v130 offset:16384
	ds_read_b128 v[196:199], v130 offset:17408
	buffer_load_dwordx4 v141, s[8:11], s26 offen lds
	s_mov_b32 m0, s50
	s_nop 0
	buffer_load_dwordx4 v142, s[8:11], s26 offen lds
	s_barrier
	s_waitcnt lgkmcnt(6)
	v_mfma_f32_16x16x32_bf16 v[44:47], v[152:155], v[168:171], v[44:47]
	v_mfma_f32_16x16x32_bf16 v[44:47], v[156:159], v[172:175], v[44:47]
	v_mfma_f32_16x16x32_bf16 v[40:43], v[164:167], v[172:175], v[40:43]
	v_mfma_f32_16x16x32_bf16 v[40:43], v[160:163], v[168:171], v[40:43]
	s_waitcnt lgkmcnt(4)
	v_mfma_f32_16x16x32_bf16 v[32:35], v[160:163], v[176:179], v[32:35]
	v_mfma_f32_16x16x32_bf16 v[32:35], v[164:167], v[180:183], v[32:35]
	v_mfma_f32_16x16x32_bf16 v[36:39], v[156:159], v[180:183], v[36:39]
	v_mfma_f32_16x16x32_bf16 v[36:39], v[152:155], v[176:179], v[36:39]
	s_waitcnt lgkmcnt(2)
	v_mfma_f32_16x16x32_bf16 v[28:31], v[152:155], v[184:187], v[28:31]
	v_mfma_f32_16x16x32_bf16 v[28:31], v[156:159], v[188:191], v[28:31]
	v_mfma_f32_16x16x32_bf16 v[24:27], v[164:167], v[188:191], v[24:27]
	v_mfma_f32_16x16x32_bf16 v[24:27], v[160:163], v[184:187], v[24:27]
	s_waitcnt lgkmcnt(0)
	v_mfma_f32_16x16x32_bf16 v[16:19], v[160:163], v[192:195], v[16:19]
	v_mfma_f32_16x16x32_bf16 v[16:19], v[164:167], v[196:199], v[16:19]
	v_mfma_f32_16x16x32_bf16 v[20:23], v[156:159], v[196:199], v[20:23]
	v_mfma_f32_16x16x32_bf16 v[20:23], v[152:155], v[192:195], v[20:23]
	s_barrier
	s_add_i32 s26, s90, s5
	s_add_i32 s27, s26, 0x100
	s_mov_b32 m0, s43
	s_nop 0
	buffer_load_dwordx4 v141, s[12:15], s27 offen lds
	s_mov_b32 m0, s51
	s_nop 0
	buffer_load_dwordx4 v142, s[12:15], s27 offen lds
	s_waitcnt vmcnt(6)
	s_barrier
; #define STAGE(P, RS, SOFF, OFF, kt) do { const int _so = (SOFF) + (kt) * (BK * 2); \
;     _Pragma("unroll") for (int _i = 0; _i < 2; ++_i) { \
;       __builtin_amdgcn_raw_ptr_buffer_load_lds(RS, (__attribute__((address_space(3))) void*)((P) + wave * 1024 + _i * 8192), 16, OFF[_i], _so, 0, 0); } } while (0)
; #define LDA(dst, b, h) _Pragma("unroll") for (int m = 0; m < 4; ++m) _Pragma("unroll") for (int k = 0; k < 2; ++k) \
;     dst[m][k] = *reinterpret_cast<const bf16x8*>(SA(b, h) + lds_byte(wr * 64 + m * 16 + fr, k * 32 + fq * 8))
; #define LDB(dst, b, h) _Pragma("unroll") for (int n = 0; n < 2; ++n) _Pragma("unroll") for (int k = 0; k < 2; ++k) \
;     dst[n][k] = *reinterpret_cast<const bf16x8*>(SB(b, h) + lds_byte(wc * 32 + n * 16 + fr, k * 32 + fq * 8))
; #define WAIT_V(n) asm volatile("s_waitcnt vmcnt(" #n ")" ::: "memory")
; #define WAIT_L(n) asm volatile("s_waitcnt lgkmcnt(" #n ")" ::: "memory")
; #define BAR __builtin_amdgcn_s_barrier()
; #define SCHED __builtin_amdgcn_sched_barrier(0)
;     ...
;     for (int t = 0; t < nt - 2; t += 2) {
;       LDB(B0, 0, 0); SCHED; LDA(At, 0, 0); STAGE(SA(1, 1), rsA, sA1, offA, t + 1);
;       WAIT_L(8); BAR; WAIT_L(0); MMA(0, 0, At, B0); BAR; SCHED;
;       LDB(B1, 0, 1); STAGE(SB(0, 0), rsB, sB0, offB, t + 2);
;       BAR; WAIT_L(0); MMA(0, 1, At, B1); BAR;
;       LDA(At, 0, 1); STAGE(SA(0, 0), rsA, sA0, offA, t + 2);
;       BAR; WAIT_L(0); MMA(1, 0, At, B0); BAR; SCHED;
;       STAGE(SB(0, 1), rsB, sB1, offB, t + 2);
;       WAIT_V(6); BAR; MMA(1, 1, At, B1); BAR;
;       LDB(B0, 1, 0); SCHED; LDA(At, 1, 0); STAGE(SA(0, 1), rsA, sA1, offA, t + 2);
;       WAIT_L(8); BAR; WAIT_L(0); MMA(0, 0, At, B0); BAR; SCHED;
;       LDB(B1, 1, 1); STAGE(SB(1, 0), rsB, sB0, offB, t + 3);
;       BAR; WAIT_L(0); MMA(0, 1, At, B1); BAR;
;       LDA(At, 1, 1); STAGE(SA(1, 0), rsA, sA0, offA, t + 3);
;       BAR; WAIT_L(0); MMA(1, 0, At, B0); BAR; SCHED;
;       STAGE(SB(1, 1), rsB, sB1, offB, t + 3);
;       WAIT_V(6); BAR; MMA(1, 1, At, B1); BAR;
;     }
	v_mfma_f32_16x16x32_bf16 v[12:15], v[200:203], v[168:171], v[12:15]
	v_mfma_f32_16x16x32_bf16 v[12:15], v[204:207], v[172:175], v[12:15]
	v_mfma_f32_16x16x32_bf16 v[8:11], v[212:215], v[172:175], v[8:11]
	v_mfma_f32_16x16x32_bf16 v[8:11], v[208:211], v[168:171], v[8:11]
	v_mfma_f32_16x16x32_bf16 v[0:3], v[208:211], v[176:179], v[0:3]
	v_mfma_f32_16x16x32_bf16 v[0:3], v[212:215], v[180:183], v[0:3]
	v_mfma_f32_16x16x32_bf16 v[4:7], v[204:207], v[180:183], v[4:7]
	v_mfma_f32_16x16x32_bf16 v[4:7], v[200:203], v[176:179], v[4:7]
	v_mfma_f32_16x16x32_bf16 v[64:67], v[200:203], v[184:187], v[64:67]
	v_mfma_f32_16x16x32_bf16 v[64:67], v[204:207], v[188:191], v[64:67]
	v_mfma_f32_16x16x32_bf16 v[72:75], v[212:215], v[188:191], v[72:75]
	v_mfma_f32_16x16x32_bf16 v[72:75], v[208:211], v[184:187], v[72:75]
	v_mfma_f32_16x16x32_bf16 v[84:87], v[208:211], v[192:195], v[84:87]
	v_mfma_f32_16x16x32_bf16 v[84:87], v[212:215], v[196:199], v[84:87]
	v_mfma_f32_16x16x32_bf16 v[76:79], v[204:207], v[196:199], v[76:79]
	v_mfma_f32_16x16x32_bf16 v[76:79], v[200:203], v[192:195], v[76:79]
	s_barrier
	ds_read_b128 v[152:155], v137
	ds_read_b128 v[156:159], v138
	ds_read_b128 v[160:163], v139
	ds_read_b128 v[164:167], v140
	s_addk_i32 s6, 0x100
	s_mov_b32 m0, s44
	ds_read_b128 v[168:171], v129 offset:32768
	ds_read_b128 v[172:175], v129 offset:33792
	ds_read_b128 v[176:179], v132 offset:32768
	ds_read_b128 v[180:183], v132 offset:33792
	ds_read_b128 v[184:187], v131 offset:32768
	ds_read_b128 v[188:191], v131 offset:33792
	ds_read_b128 v[192:195], v130 offset:32768
	ds_read_b128 v[196:199], v130 offset:33792
	buffer_load_dwordx4 v141, s[8:11], s6 offen lds
	s_mov_b32 m0, s52
	s_nop 0
	buffer_load_dwordx4 v142, s[8:11], s6 offen lds
	s_waitcnt lgkmcnt(8)
	s_barrier
	s_waitcnt lgkmcnt(6)
	v_mfma_f32_16x16x32_bf16 v[124:127], v[152:155], v[168:171], v[124:127]
	v_mfma_f32_16x16x32_bf16 v[124:127], v[156:159], v[172:175], v[124:127]
	v_mfma_f32_16x16x32_bf16 v[120:123], v[164:167], v[172:175], v[120:123]
	v_mfma_f32_16x16x32_bf16 v[120:123], v[160:163], v[168:171], v[120:123]
	s_waitcnt lgkmcnt(4)
	v_mfma_f32_16x16x32_bf16 v[112:115], v[160:163], v[176:179], v[112:115]
	v_mfma_f32_16x16x32_bf16 v[112:115], v[164:167], v[180:183], v[112:115]
	v_mfma_f32_16x16x32_bf16 v[116:119], v[156:159], v[180:183], v[116:119]
	v_mfma_f32_16x16x32_bf16 v[116:119], v[152:155], v[176:179], v[116:119]
	s_waitcnt lgkmcnt(2)
	v_mfma_f32_16x16x32_bf16 v[108:111], v[152:155], v[184:187], v[108:111]
	v_mfma_f32_16x16x32_bf16 v[108:111], v[156:159], v[188:191], v[108:111]
	v_mfma_f32_16x16x32_bf16 v[104:107], v[164:167], v[188:191], v[104:107]
	v_mfma_f32_16x16x32_bf16 v[104:107], v[160:163], v[184:187], v[104:107]
	s_waitcnt lgkmcnt(0)
	v_mfma_f32_16x16x32_bf16 v[96:99], v[160:163], v[192:195], v[96:99]
	v_mfma_f32_16x16x32_bf16 v[96:99], v[164:167], v[196:199], v[96:99]
	v_mfma_f32_16x16x32_bf16 v[100:103], v[156:159], v[196:199], v[100:103]
	v_mfma_f32_16x16x32_bf16 v[100:103], v[152:155], v[192:195], v[100:103]
	s_barrier
	s_addk_i32 s7, 0x180
	s_mov_b32 m0, s45
	ds_read_b128 v[200:203], v133
	ds_read_b128 v[204:207], v134
	ds_read_b128 v[208:211], v135
	ds_read_b128 v[212:215], v136
	buffer_load_dwordx4 v141, s[12:15], s7 offen lds
	s_mov_b32 m0, s53
	s_nop 0
	buffer_load_dwordx4 v142, s[12:15], s7 offen lds
	s_barrier
	s_waitcnt lgkmcnt(2)
	v_mfma_f32_16x16x32_bf16 v[92:95], v[200:203], v[168:171], v[92:95]
	v_mfma_f32_16x16x32_bf16 v[92:95], v[204:207], v[172:175], v[92:95]
	s_waitcnt lgkmcnt(0)
	v_mfma_f32_16x16x32_bf16 v[88:91], v[212:215], v[172:175], v[88:91]
	v_mfma_f32_16x16x32_bf16 v[88:91], v[208:211], v[168:171], v[88:91]
	v_mfma_f32_16x16x32_bf16 v[68:71], v[208:211], v[176:179], v[68:71]
	v_mfma_f32_16x16x32_bf16 v[68:71], v[212:215], v[180:183], v[68:71]
	v_mfma_f32_16x16x32_bf16 v[80:83], v[204:207], v[180:183], v[80:83]
	v_mfma_f32_16x16x32_bf16 v[80:83], v[200:203], v[176:179], v[80:83]
	v_mfma_f32_16x16x32_bf16 v[60:63], v[200:203], v[184:187], v[60:63]
	v_mfma_f32_16x16x32_bf16 v[60:63], v[204:207], v[188:191], v[60:63]
	v_mfma_f32_16x16x32_bf16 v[56:59], v[212:215], v[188:191], v[56:59]
	v_mfma_f32_16x16x32_bf16 v[56:59], v[208:211], v[184:187], v[56:59]
	v_mfma_f32_16x16x32_bf16 v[48:51], v[208:211], v[192:195], v[48:51]
	v_mfma_f32_16x16x32_bf16 v[48:51], v[212:215], v[196:199], v[48:51]
	v_mfma_f32_16x16x32_bf16 v[52:55], v[204:207], v[196:199], v[52:55]
	v_mfma_f32_16x16x32_bf16 v[52:55], v[200:203], v[192:195], v[52:55]
	s_barrier
	s_addk_i32 s23, 0x180
	s_mov_b32 m0, s46
	ds_read_b128 v[168:171], v129 offset:49152
	ds_read_b128 v[172:175], v129 offset:50176
	ds_read_b128 v[176:179], v132 offset:49152
	ds_read_b128 v[180:183], v132 offset:50176
	ds_read_b128 v[184:187], v131 offset:49152
	ds_read_b128 v[188:191], v131 offset:50176
	ds_read_b128 v[192:195], v130 offset:49152
	ds_read_b128 v[196:199], v130 offset:50176
	buffer_load_dwordx4 v141, s[8:11], s23 offen lds
	s_mov_b32 m0, s54
	s_nop 0
	buffer_load_dwordx4 v142, s[8:11], s23 offen lds
	s_barrier
	s_waitcnt lgkmcnt(6)
	v_mfma_f32_16x16x32_bf16 v[44:47], v[152:155], v[168:171], v[44:47]
	v_mfma_f32_16x16x32_bf16 v[44:47], v[156:159], v[172:175], v[44:47]
	v_mfma_f32_16x16x32_bf16 v[40:43], v[164:167], v[172:175], v[40:43]
	v_mfma_f32_16x16x32_bf16 v[40:43], v[160:163], v[168:171], v[40:43]
	s_waitcnt lgkmcnt(4)
	v_mfma_f32_16x16x32_bf16 v[32:35], v[160:163], v[176:179], v[32:35]
	v_mfma_f32_16x16x32_bf16 v[32:35], v[164:167], v[180:183], v[32:35]
	v_mfma_f32_16x16x32_bf16 v[36:39], v[156:159], v[180:183], v[36:39]
	v_mfma_f32_16x16x32_bf16 v[36:39], v[152:155], v[176:179], v[36:39]
	s_waitcnt lgkmcnt(2)
	v_mfma_f32_16x16x32_bf16 v[28:31], v[152:155], v[184:187], v[28:31]
	v_mfma_f32_16x16x32_bf16 v[28:31], v[156:159], v[188:191], v[28:31]
	v_mfma_f32_16x16x32_bf16 v[24:27], v[164:167], v[188:191], v[24:27]
	v_mfma_f32_16x16x32_bf16 v[24:27], v[160:163], v[184:187], v[24:27]
	s_waitcnt lgkmcnt(0)
	v_mfma_f32_16x16x32_bf16 v[16:19], v[160:163], v[192:195], v[16:19]
	v_mfma_f32_16x16x32_bf16 v[16:19], v[164:167], v[196:199], v[16:19]
	v_mfma_f32_16x16x32_bf16 v[20:23], v[156:159], v[196:199], v[20:23]
	v_mfma_f32_16x16x32_bf16 v[20:23], v[152:155], v[192:195], v[20:23]
	s_barrier
	s_addk_i32 s26, 0x180
	s_mov_b32 m0, s47
	s_nop 0
	buffer_load_dwordx4 v141, s[12:15], s26 offen lds
	s_mov_b32 m0, s55
	s_nop 0
	buffer_load_dwordx4 v142, s[12:15], s26 offen lds
	s_add_i32 s4, s4, 2
	s_addk_i32 s5, 0x100
	s_cmp_gt_u32 s4, 59
	s_cbranch_scc0 .LBB0_757
; #define STAGE(P, RS, SOFF, OFF, kt) do { const int _so = (SOFF) + (kt) * (BK * 2); \
;     _Pragma("unroll") for (int _i = 0; _i < 2; ++_i) { \
;       __builtin_amdgcn_raw_ptr_buffer_load_lds(RS, (__attribute__((address_space(3))) void*)((P) + wave * 1024 + _i * 8192), 16, OFF[_i], _so, 0, 0); } } while (0)
; #define LDA(dst, b, h) _Pragma("unroll") for (int m = 0; m < 4; ++m) _Pragma("unroll") for (int k = 0; k < 2; ++k) \
;     dst[m][k] = *reinterpret_cast<const bf16x8*>(SA(b, h) + lds_byte(wr * 64 + m * 16 + fr, k * 32 + fq * 8))
; #define LDB(dst, b, h) _Pragma("unroll") for (int n = 0; n < 2; ++n) _Pragma("unroll") for (int k = 0; k < 2; ++k) \
;     dst[n][k] = *reinterpret_cast<const bf16x8*>(SB(b, h) + lds_byte(wc * 32 + n * 16 + fr, k * 32 + fq * 8))
; #define WAIT_V(n) asm volatile("s_waitcnt vmcnt(" #n ")" ::: "memory")
; #define WAIT_L(n) asm volatile("s_waitcnt lgkmcnt(" #n ")" ::: "memory")
; #define BAR __builtin_amdgcn_s_barrier()
; #define SCHED __builtin_amdgcn_sched_barrier(0)
;     ...
;       WAIT_V(6); BAR; MMA(1, 1, At, B1); BAR;
;       LDB(B0, 1, 0); SCHED; LDA(At, 1, 0); STAGE(SA(0, 1), rsA, sA1, offA, t + 2);
;       WAIT_L(8); BAR; WAIT_L(0); MMA(0, 0, At, B0); BAR; SCHED;
;       LDB(B1, 1, 1); STAGE(SB(1, 0), rsB, sB0, offB, t + 3);
;       BAR; WAIT_L(0); MMA(0, 1, At, B1); BAR;
;       LDA(At, 1, 1); STAGE(SA(1, 0), rsA, sA0, offA, t + 3);
;       BAR; WAIT_L(0); MMA(1, 0, At, B0); BAR; SCHED;
;       STAGE(SB(1, 1), rsB, sB1, offB, t + 3);
;       WAIT_V(6); BAR; MMA(1, 1, At, B1); BAR;
;     }
;     { LDB(B0, 0, 0); LDA(At, 0, 0); STAGE(SA(1, 1), rsA, sA1, offA, nt - 1);
;       BAR; WAIT_L(0); MMA(0, 0, At, B0); BAR;
;       LDB(B1, 0, 1); BAR; WAIT_L(0); MMA(0, 1, At, B1); BAR;
;       LDA(At, 0, 1); WAIT_V(4); BAR; WAIT_L(0); MMA(1, 0, At, B0); MMA(1, 1, At, B1); BAR; }
.Lmy_post_757:
	s_waitcnt vmcnt(6)
	s_barrier
	v_mfma_f32_16x16x32_bf16 v[12:15], v[200:203], v[168:171], v[12:15]
	v_mfma_f32_16x16x32_bf16 v[12:15], v[204:207], v[172:175], v[12:15]
	v_mfma_f32_16x16x32_bf16 v[8:11], v[212:215], v[172:175], v[8:11]
	v_mfma_f32_16x16x32_bf16 v[8:11], v[208:211], v[168:171], v[8:11]
	v_mfma_f32_16x16x32_bf16 v[0:3], v[208:211], v[176:179], v[0:3]
	v_mfma_f32_16x16x32_bf16 v[0:3], v[212:215], v[180:183], v[0:3]
	v_mfma_f32_16x16x32_bf16 v[4:7], v[204:207], v[180:183], v[4:7]
	v_mfma_f32_16x16x32_bf16 v[4:7], v[200:203], v[176:179], v[4:7]
	v_mfma_f32_16x16x32_bf16 v[64:67], v[200:203], v[184:187], v[64:67]
	v_mfma_f32_16x16x32_bf16 v[64:67], v[204:207], v[188:191], v[64:67]
	v_mfma_f32_16x16x32_bf16 v[72:75], v[212:215], v[188:191], v[72:75]
	v_mfma_f32_16x16x32_bf16 v[72:75], v[208:211], v[184:187], v[72:75]
	v_mfma_f32_16x16x32_bf16 v[84:87], v[208:211], v[192:195], v[84:87]
	v_mfma_f32_16x16x32_bf16 v[84:87], v[212:215], v[196:199], v[84:87]
	v_mfma_f32_16x16x32_bf16 v[76:79], v[204:207], v[196:199], v[76:79]
	v_mfma_f32_16x16x32_bf16 v[76:79], v[200:203], v[192:195], v[76:79]
	s_barrier
	s_add_i32 s4, s85, 0x1f80
	s_mov_b32 m0, s39
	ds_read_b128 v[152:155], v147
	ds_read_b128 v[156:159], v148
	ds_read_b128 v[160:163], v149
	ds_read_b128 v[148:151], v150
	ds_read_b128 v[164:167], v129
	ds_read_b128 v[168:171], v129 offset:1024
	ds_read_b128 v[172:175], v132
	ds_read_b128 v[176:179], v132 offset:1024
	ds_read_b128 v[180:183], v131
	ds_read_b128 v[184:187], v131 offset:1024
	ds_read_b128 v[188:191], v130
	ds_read_b128 v[192:195], v130 offset:1024
	buffer_load_dwordx4 v141, s[8:11], s4 offen lds
	s_mov_b32 m0, s56
	s_nop 0
	buffer_load_dwordx4 v142, s[8:11], s4 offen lds
	s_barrier
	s_waitcnt lgkmcnt(6)
	v_mfma_f32_16x16x32_bf16 v[124:127], v[152:155], v[164:167], v[124:127]
	v_mfma_f32_16x16x32_bf16 v[124:127], v[156:159], v[168:171], v[124:127]
	v_mfma_f32_16x16x32_bf16 v[120:123], v[148:151], v[168:171], v[120:123]
	v_mfma_f32_16x16x32_bf16 v[120:123], v[160:163], v[164:167], v[120:123]
	s_waitcnt lgkmcnt(4)
	v_mfma_f32_16x16x32_bf16 v[112:115], v[160:163], v[172:175], v[112:115]
	v_mfma_f32_16x16x32_bf16 v[112:115], v[148:151], v[176:179], v[112:115]
	v_mfma_f32_16x16x32_bf16 v[116:119], v[156:159], v[176:179], v[116:119]
	v_mfma_f32_16x16x32_bf16 v[116:119], v[152:155], v[172:175], v[116:119]
	s_waitcnt lgkmcnt(2)
	v_mfma_f32_16x16x32_bf16 v[108:111], v[152:155], v[180:183], v[108:111]
	v_mfma_f32_16x16x32_bf16 v[108:111], v[156:159], v[184:187], v[108:111]
	v_mfma_f32_16x16x32_bf16 v[104:107], v[148:151], v[184:187], v[104:107]
	v_mfma_f32_16x16x32_bf16 v[104:107], v[160:163], v[180:183], v[104:107]
	s_waitcnt lgkmcnt(0)
	v_mfma_f32_16x16x32_bf16 v[96:99], v[160:163], v[188:191], v[96:99]
	v_mfma_f32_16x16x32_bf16 v[96:99], v[148:151], v[192:195], v[96:99]
	v_mfma_f32_16x16x32_bf16 v[100:103], v[156:159], v[192:195], v[100:103]
	v_mfma_f32_16x16x32_bf16 v[100:103], v[152:155], v[188:191], v[100:103]
	s_barrier
	ds_read_b128 v[196:199], v143
	ds_read_b128 v[200:203], v144
	ds_read_b128 v[142:145], v145
	ds_read_b128 v[204:207], v146
	s_barrier
	s_waitcnt lgkmcnt(1)
	v_mfma_f32_16x16x32_bf16 v[88:91], v[142:145], v[164:167], v[88:91]
	v_mfma_f32_16x16x32_bf16 v[80:83], v[196:199], v[172:175], v[80:83]
	v_mfma_f32_16x16x32_bf16 v[60:63], v[196:199], v[180:183], v[60:63]
	v_mfma_f32_16x16x32_bf16 v[56:59], v[142:145], v[180:183], v[56:59]
	v_mfma_f32_16x16x32_bf16 v[52:55], v[196:199], v[188:191], v[52:55]
	v_mfma_f32_16x16x32_bf16 v[48:51], v[142:145], v[188:191], v[48:51]
	v_mfma_f32_16x16x32_bf16 v[92:95], v[196:199], v[164:167], v[92:95]
	v_mfma_f32_16x16x32_bf16 v[68:71], v[142:145], v[172:175], v[68:71]
	s_waitcnt lgkmcnt(0)
	v_mfma_f32_16x16x32_bf16 v[88:91], v[204:207], v[168:171], v[88:91]
	v_mfma_f32_16x16x32_bf16 v[80:83], v[200:203], v[176:179], v[80:83]
	v_mfma_f32_16x16x32_bf16 v[60:63], v[200:203], v[184:187], v[60:63]
	v_mfma_f32_16x16x32_bf16 v[56:59], v[204:207], v[184:187], v[56:59]
	v_mfma_f32_16x16x32_bf16 v[52:55], v[200:203], v[192:195], v[52:55]
	v_mfma_f32_16x16x32_bf16 v[48:51], v[204:207], v[192:195], v[48:51]
	v_mfma_f32_16x16x32_bf16 v[164:167], v[200:203], v[168:171], v[92:95]
	v_mfma_f32_16x16x32_bf16 v[168:171], v[204:207], v[176:179], v[68:71]
	s_barrier
	s_nop 0
	ds_read_b128 v[68:71], v129 offset:16384
	ds_read_b128 v[92:95], v129 offset:17408
	ds_read_b128 v[172:175], v132 offset:16384
	ds_read_b128 v[176:179], v132 offset:17408
	ds_read_b128 v[180:183], v131 offset:16384
	ds_read_b128 v[184:187], v131 offset:17408
	ds_read_b128 v[188:191], v130 offset:16384
	ds_read_b128 v[192:195], v130 offset:17408
	s_waitcnt vmcnt(4)
	s_barrier
; #define LDA(dst, b, h) _Pragma("unroll") for (int m = 0; m < 4; ++m) _Pragma("unroll") for (int k = 0; k < 2; ++k) \
;     dst[m][k] = *reinterpret_cast<const bf16x8*>(SA(b, h) + lds_byte(wr * 64 + m * 16 + fr, k * 32 + fq * 8))
; #define LDB(dst, b, h) _Pragma("unroll") for (int n = 0; n < 2; ++n) _Pragma("unroll") for (int k = 0; k < 2; ++k) \
;     dst[n][k] = *reinterpret_cast<const bf16x8*>(SB(b, h) + lds_byte(wc * 32 + n * 16 + fr, k * 32 + fq * 8))
; #define WAIT_V(n) asm volatile("s_waitcnt vmcnt(" #n ")" ::: "memory")
; #define WAIT_L(n) asm volatile("s_waitcnt lgkmcnt(" #n ")" ::: "memory")
; #define BAR __builtin_amdgcn_s_barrier()
;     ...
;       LDA(At, 0, 1); WAIT_V(4); BAR; WAIT_L(0); MMA(1, 0, At, B0); MMA(1, 1, At, B1); BAR; }
;     { LDB(B0, 1, 0); LDA(At, 1, 0); WAIT_V(2); BAR; WAIT_L(0); MMA(0, 0, At, B0); BAR;
;       LDB(B1, 1, 1); WAIT_V(0); BAR; WAIT_L(0); MMA(0, 1, At, B1); BAR;
	s_waitcnt lgkmcnt(0)
	v_mfma_f32_16x16x32_bf16 v[44:47], v[152:155], v[68:71], v[44:47]
	v_mfma_f32_16x16x32_bf16 v[40:43], v[160:163], v[68:71], v[40:43]
	v_mfma_f32_16x16x32_bf16 v[36:39], v[152:155], v[172:175], v[36:39]
	v_mfma_f32_16x16x32_bf16 v[32:35], v[160:163], v[172:175], v[32:35]
	v_mfma_f32_16x16x32_bf16 v[28:31], v[152:155], v[180:183], v[28:31]
	v_mfma_f32_16x16x32_bf16 v[24:27], v[160:163], v[180:183], v[24:27]
	v_mfma_f32_16x16x32_bf16 v[20:23], v[152:155], v[188:191], v[20:23]
	v_mfma_f32_16x16x32_bf16 v[16:19], v[160:163], v[188:191], v[16:19]
	v_mfma_f32_16x16x32_bf16 v[44:47], v[156:159], v[92:95], v[44:47]
	v_mfma_f32_16x16x32_bf16 v[40:43], v[148:151], v[92:95], v[40:43]
	v_mfma_f32_16x16x32_bf16 v[36:39], v[156:159], v[176:179], v[36:39]
	v_mfma_f32_16x16x32_bf16 v[32:35], v[148:151], v[176:179], v[32:35]
	v_mfma_f32_16x16x32_bf16 v[28:31], v[156:159], v[184:187], v[28:31]
	v_mfma_f32_16x16x32_bf16 v[24:27], v[148:151], v[184:187], v[24:27]
	v_mfma_f32_16x16x32_bf16 v[20:23], v[156:159], v[192:195], v[20:23]
	v_mfma_f32_16x16x32_bf16 v[16:19], v[148:151], v[192:195], v[16:19]
	v_mfma_f32_16x16x32_bf16 v[4:7], v[196:199], v[172:175], v[4:7]
	v_mfma_f32_16x16x32_bf16 v[0:3], v[142:145], v[172:175], v[0:3]
	v_mfma_f32_16x16x32_bf16 v[12:15], v[196:199], v[68:71], v[12:15]
	v_mfma_f32_16x16x32_bf16 v[8:11], v[142:145], v[68:71], v[8:11]
	v_mfma_f32_16x16x32_bf16 v[64:67], v[196:199], v[180:183], v[64:67]
	v_mfma_f32_16x16x32_bf16 v[68:71], v[142:145], v[180:183], v[72:75]
	v_mfma_f32_16x16x32_bf16 v[72:75], v[196:199], v[188:191], v[76:79]
	v_mfma_f32_16x16x32_bf16 v[76:79], v[142:145], v[188:191], v[84:87]
	v_mfma_f32_16x16x32_bf16 v[4:7], v[200:203], v[176:179], v[4:7]
	v_mfma_f32_16x16x32_bf16 v[0:3], v[204:207], v[176:179], v[0:3]
	v_mfma_f32_16x16x32_bf16 v[142:145], v[200:203], v[92:95], v[12:15]
	v_mfma_f32_16x16x32_bf16 v[146:149], v[204:207], v[92:95], v[8:11]
	v_mfma_f32_16x16x32_bf16 v[150:153], v[200:203], v[184:187], v[64:67]
	v_mfma_f32_16x16x32_bf16 v[154:157], v[204:207], v[184:187], v[68:71]
	v_mfma_f32_16x16x32_bf16 v[158:161], v[200:203], v[192:195], v[72:75]
	v_mfma_f32_16x16x32_bf16 v[172:175], v[204:207], v[192:195], v[76:79]
	s_barrier
	ds_read_b128 v[8:11], v137
	ds_read_b128 v[12:15], v138
	ds_read_b128 v[176:179], v139
	ds_read_b128 v[138:141], v140
	ds_read_b128 v[64:67], v129 offset:32768
	ds_read_b128 v[72:75], v129 offset:33792
	ds_read_b128 v[180:183], v132 offset:32768
	ds_read_b128 v[184:187], v132 offset:33792
	ds_read_b128 v[188:191], v131 offset:32768
	ds_read_b128 v[192:195], v131 offset:33792
	ds_read_b128 v[196:199], v130 offset:32768
	ds_read_b128 v[200:203], v130 offset:33792
	s_waitcnt vmcnt(2)
	s_barrier
	s_waitcnt lgkmcnt(7)
	v_mfma_f32_16x16x32_bf16 v[68:71], v[8:11], v[64:67], v[124:127]
	v_mfma_f32_16x16x32_bf16 v[76:79], v[176:179], v[64:67], v[120:123]
	s_waitcnt lgkmcnt(5)
	v_mfma_f32_16x16x32_bf16 v[84:87], v[8:11], v[180:183], v[116:119]
	v_mfma_f32_16x16x32_bf16 v[92:95], v[176:179], v[180:183], v[112:115]
	s_waitcnt lgkmcnt(3)
	v_mfma_f32_16x16x32_bf16 v[112:115], v[8:11], v[188:191], v[108:111]
	v_mfma_f32_16x16x32_bf16 v[104:107], v[176:179], v[188:191], v[104:107]
	s_waitcnt lgkmcnt(1)
	v_mfma_f32_16x16x32_bf16 v[120:123], v[8:11], v[196:199], v[100:103]
	v_mfma_f32_16x16x32_bf16 v[96:99], v[176:179], v[196:199], v[96:99]
	v_mfma_f32_16x16x32_bf16 v[124:127], v[12:15], v[72:75], v[68:71]
	v_mfma_f32_16x16x32_bf16 v[116:119], v[138:141], v[72:75], v[76:79]
	v_mfma_f32_16x16x32_bf16 v[108:111], v[12:15], v[184:187], v[84:87]
	v_mfma_f32_16x16x32_bf16 v[100:103], v[138:141], v[184:187], v[92:95]
	v_mfma_f32_16x16x32_bf16 v[92:95], v[12:15], v[192:195], v[112:115]
	v_mfma_f32_16x16x32_bf16 v[84:87], v[138:141], v[192:195], v[104:107]
	s_waitcnt lgkmcnt(0)
	v_mfma_f32_16x16x32_bf16 v[76:79], v[12:15], v[200:203], v[120:123]
	v_mfma_f32_16x16x32_bf16 v[68:71], v[138:141], v[200:203], v[96:99]
	s_barrier
; #define LDA(dst, b, h) _Pragma("unroll") for (int m = 0; m < 4; ++m) _Pragma("unroll") for (int k = 0; k < 2; ++k) \
;     dst[m][k] = *reinterpret_cast<const bf16x8*>(SA(b, h) + lds_byte(wr * 64 + m * 16 + fr, k * 32 + fq * 8))
; #define LDB(dst, b, h) _Pragma("unroll") for (int n = 0; n < 2; ++n) _Pragma("unroll") for (int k = 0; k < 2; ++k) \
;     dst[n][k] = *reinterpret_cast<const bf16x8*>(SB(b, h) + lds_byte(wc * 32 + n * 16 + fr, k * 32 + fq * 8))
; #define WAIT_V(n) asm volatile("s_waitcnt vmcnt(" #n ")" ::: "memory")
; #define WAIT_L(n) asm volatile("s_waitcnt lgkmcnt(" #n ")" ::: "memory")
; #define BAR __builtin_amdgcn_s_barrier()
;     ...
;       LDB(B1, 1, 1); WAIT_V(0); BAR; WAIT_L(0); MMA(0, 1, At, B1); BAR;
;       LDA(At, 1, 1); BAR; WAIT_L(0); MMA(1, 0, At, B0); MMA(1, 1, At, B1); BAR; }
;     if (wr == 0) BAR;
	ds_read_b128 v[204:207], v133
	ds_read_b128 v[208:211], v134
	ds_read_b128 v[212:215], v135
	ds_read_b128 v[134:137], v136
	s_waitcnt vmcnt(0)
	s_barrier
	s_waitcnt lgkmcnt(1)
	v_mfma_f32_16x16x32_bf16 v[96:99], v[204:207], v[64:67], v[164:167]
	v_mfma_f32_16x16x32_bf16 v[64:67], v[212:215], v[64:67], v[88:91]
	v_mfma_f32_16x16x32_bf16 v[80:83], v[204:207], v[180:183], v[80:83]
	v_mfma_f32_16x16x32_bf16 v[88:91], v[212:215], v[180:183], v[168:171]
	v_mfma_f32_16x16x32_bf16 v[60:63], v[204:207], v[188:191], v[60:63]
	v_mfma_f32_16x16x32_bf16 v[56:59], v[212:215], v[188:191], v[56:59]
	v_mfma_f32_16x16x32_bf16 v[52:55], v[204:207], v[196:199], v[52:55]
	v_mfma_f32_16x16x32_bf16 v[48:51], v[212:215], v[196:199], v[48:51]
	s_waitcnt lgkmcnt(0)
	v_mfma_f32_16x16x32_bf16 v[120:123], v[208:211], v[72:75], v[96:99]
	v_mfma_f32_16x16x32_bf16 v[112:115], v[134:137], v[72:75], v[64:67]
	v_mfma_f32_16x16x32_bf16 v[104:107], v[208:211], v[184:187], v[80:83]
	v_mfma_f32_16x16x32_bf16 v[96:99], v[134:137], v[184:187], v[88:91]
	v_mfma_f32_16x16x32_bf16 v[88:91], v[208:211], v[192:195], v[60:63]
	v_mfma_f32_16x16x32_bf16 v[80:83], v[134:137], v[192:195], v[56:59]
	v_mfma_f32_16x16x32_bf16 v[72:75], v[208:211], v[200:203], v[52:55]
	v_mfma_f32_16x16x32_bf16 v[64:67], v[134:137], v[200:203], v[48:51]
	s_barrier
	s_nop 0
	ds_read_b128 v[48:51], v129 offset:49152
	ds_read_b128 v[162:165], v129 offset:50176
	ds_read_b128 v[52:55], v132 offset:49152
	ds_read_b128 v[166:169], v132 offset:50176
	ds_read_b128 v[180:183], v131 offset:49152
	ds_read_b128 v[184:187], v131 offset:50176
	ds_read_b128 v[188:191], v130 offset:49152
	ds_read_b128 v[130:133], v130 offset:50176
	s_barrier
	s_waitcnt lgkmcnt(0)
	v_mfma_f32_16x16x32_bf16 v[44:47], v[8:11], v[48:51], v[44:47]
	v_mfma_f32_16x16x32_bf16 v[40:43], v[176:179], v[48:51], v[40:43]
	v_mfma_f32_16x16x32_bf16 v[36:39], v[8:11], v[52:55], v[36:39]
	v_mfma_f32_16x16x32_bf16 v[32:35], v[176:179], v[52:55], v[32:35]
	v_mfma_f32_16x16x32_bf16 v[28:31], v[8:11], v[180:183], v[28:31]
	v_mfma_f32_16x16x32_bf16 v[24:27], v[176:179], v[180:183], v[24:27]
	v_mfma_f32_16x16x32_bf16 v[8:11], v[8:11], v[188:191], v[20:23]
	v_mfma_f32_16x16x32_bf16 v[16:19], v[176:179], v[188:191], v[16:19]
	v_mfma_f32_16x16x32_bf16 v[60:63], v[12:15], v[162:165], v[44:47]
	v_mfma_f32_16x16x32_bf16 v[56:59], v[138:141], v[162:165], v[40:43]
	v_mfma_f32_16x16x32_bf16 v[44:47], v[12:15], v[166:169], v[36:39]
	v_mfma_f32_16x16x32_bf16 v[40:43], v[138:141], v[166:169], v[32:35]
	v_mfma_f32_16x16x32_bf16 v[28:31], v[12:15], v[184:187], v[28:31]
	v_mfma_f32_16x16x32_bf16 v[24:27], v[138:141], v[184:187], v[24:27]
	v_mfma_f32_16x16x32_bf16 v[12:15], v[12:15], v[130:133], v[8:11]
	v_mfma_f32_16x16x32_bf16 v[8:11], v[138:141], v[130:133], v[16:19]
	v_mfma_f32_16x16x32_bf16 v[16:19], v[204:207], v[48:51], v[142:145]
	v_mfma_f32_16x16x32_bf16 v[20:23], v[212:215], v[48:51], v[146:149]
	v_mfma_f32_16x16x32_bf16 v[4:7], v[204:207], v[52:55], v[4:7]
	v_mfma_f32_16x16x32_bf16 v[0:3], v[212:215], v[52:55], v[0:3]
	v_mfma_f32_16x16x32_bf16 v[138:141], v[204:207], v[180:183], v[150:153]
	v_mfma_f32_16x16x32_bf16 v[142:145], v[212:215], v[180:183], v[154:157]
	v_mfma_f32_16x16x32_bf16 v[146:149], v[204:207], v[188:191], v[158:161]
	v_mfma_f32_16x16x32_bf16 v[150:153], v[212:215], v[188:191], v[172:175]
	v_mfma_f32_16x16x32_bf16 v[52:55], v[208:211], v[162:165], v[16:19]
	v_mfma_f32_16x16x32_bf16 v[48:51], v[134:137], v[162:165], v[20:23]
	v_mfma_f32_16x16x32_bf16 v[36:39], v[208:211], v[166:169], v[4:7]
	v_mfma_f32_16x16x32_bf16 v[32:35], v[134:137], v[166:169], v[0:3]
	v_mfma_f32_16x16x32_bf16 v[20:23], v[208:211], v[184:187], v[138:141]
	v_mfma_f32_16x16x32_bf16 v[16:19], v[134:137], v[184:187], v[142:145]
	v_mfma_f32_16x16x32_bf16 v[4:7], v[208:211], v[130:133], v[146:149]
	v_mfma_f32_16x16x32_bf16 v[0:3], v[134:137], v[130:133], v[150:153]
	v_cmp_gt_u32_e32 vcc, s74, v128
	s_barrier
	s_and_saveexec_b64 s[4:5], vcc
	s_cbranch_execz .LBB0_760
	s_barrier
